# hand-written LDS-DMA 3-stage GEMM engine replaces the 8 big GEMM phase bodies; LDS XOR-swizzle pitch 64; tile order swap so CU-mate blocks share A
# speedup vs baseline: 1.0660x; 1.0660x over previous
; #define LWRITE(S, buf) do { bf16_t* sA_ = sbase + (buf) * BUF; bf16_t* sB_ = sA_ + 256 * PITCH; \
;     _Pragma("unroll") for (int i_ = 0; i_ < 4; ++i_) *(u32x4*)(sA_ + (sr + i_ * 64) * PITCH + scv * 8) = ra[S][i_]; \
;     _Pragma("unroll") for (int i_ = 0; i_ < 2; ++i_) *(u32x4*)(sB_ + (sr + i_ * 64) * PITCH + scv * 8) = rb[S][i_]; } while (0)
; template <class Epi>
; DI void gemm_tile(char* smem, const bf16_t* __restrict__ A0, int lda0, int ksplit, const bf16_t* __restrict__ A1, int lda1,
;                   const bf16_t* __restrict__ Bt, int K, int row0, int col0, const Epi& epi, int tid) {
;   constexpr int BK = 32, PITCH = 40, BUF = (256 + 128) * PITCH;
;   bf16_t* sbase = (bf16_t*)smem;
;   const int lane = tid & 63, wid = tid >> 6, wr = wid >> 1, wc = wid & 1, fr = lane & 15, fq = lane >> 4;
;   f32x4 acc[8][4];
; #pragma unroll
;   for (int m = 0; m < 8; ++m)
; #pragma unroll
;     for (int n = 0; n < 4; ++n) acc[m][n] = (f32x4){0.f, 0.f, 0.f, 0.f};
;   u32x4 ra[2][4], rb[2][2];
;   const int nk = K / BK;
;   const int sr = tid >> 2, scv = tid & 3;
;     ...
;   __syncthreads();
;   {
;     const int last = nk - 1;
;     GLOAD(0, 0);
;     __builtin_amdgcn_sched_barrier(0);
;     GLOAD(1, 1);
;     __builtin_amdgcn_sched_barrier(0);
;     LWRITE(0, 0);
;     __builtin_amdgcn_sched_barrier(0);
;     GLOAD(0, (2 < last ? 2 : last));
;     __builtin_amdgcn_sched_barrier(0);
;     __syncthreads();
; template <class Epi>
; DI void gemm_phase(char* smem, const bf16_t* A0, int lda0, int ksplit, const bf16_t* A1, int lda1, const bf16_t* Bt, int K, int nN, const Epi& epi, int tid) {
;     ...
;     const int x = blockIdx.x & 7, l = blockIdx.x >> 3, L = G >> 3, per = 8 * nN, tot = 2 * per;
;     for (int q = l; q < tot; q += L) { const int rgl = q / per, rem = q % per, ct = rem >> 3, rt = (x * 2 + rgl) * 8 + (rem & 7);
;       gemm_tile(smem, A0, lda0, ksplit, A1, lda1, Bt, K, rt * 256, ct * 128, epi, tid); }
.LBB0_60:
	s_load_dwordx4 s[52:55], s[74:75], 0x160
	s_load_dwordx8 s[0:7], s[74:75], 0x140
	s_load_dwordx16 s[36:51], s[74:75], 0x80
	s_cmp_gt_i32 s94, 1
	v_mbcnt_lo_u32_b32 v194, -1, 0
	s_waitcnt lgkmcnt(0)
	v_writelane_b32 v253, s0, 48
	s_nop 1
	v_writelane_b32 v253, s1, 49
	v_writelane_b32 v253, s2, 50
	v_writelane_b32 v253, s3, 51
	v_writelane_b32 v253, s4, 52
	v_writelane_b32 v253, s5, 53
	v_writelane_b32 v253, s6, 54
	v_writelane_b32 v253, s7, 55
	s_cselect_b64 s[0:1], -1, 0
	s_cmp_lt_i32 s95, 2
	s_cselect_b64 s[2:3], -1, 0
	s_or_b64 s[0:1], s[0:1], s[2:3]
	s_and_b64 vcc, exec, s[0:1]
	s_cbranch_vccnz .LBB0_344
	s_load_dword s26, s[74:75], 0x180
	s_add_u32 s0, s92, 0x3800000
	s_addc_u32 s1, s93, 0
	s_and_b32 s28, s72, 0xffffffc0
	v_mbcnt_hi_u32_b32 v195, -1, v194
	s_waitcnt lgkmcnt(0)
	s_and_b32 s27, s26, 7
	s_cmp_lg_u32 s27, 0
	v_add_u32_e32 v196, s28, v195
	v_mbcnt_lo_u32_b32 v240, -1, 0
	v_mbcnt_hi_u32_b32 v240, -1, v240
	s_lshr_b32 s23, s72, 6
	s_lshl_b32 s100, s23, 10
	v_and_b32_e32 v241, 15, v240
	v_lshrrev_b32_e32 v242, 4, v240
	v_bfe_u32 v243, v240, 3, 1
	v_mul_u32_u24_e32 v243, 3, v243
	v_xor_b32_e32 v243, v242, v243
	v_lshlrev_b32_e32 v243, 4, v243
	v_lshl_add_u32 v243, v241, 6, v243
	s_lshr_b32 s22, s23, 1
	s_lshl_b32 s22, s22, 13
	v_add_u32_e32 v230, s22, v243
	s_and_b32 s22, s23, 1
	s_lshl_b32 s22, s22, 12
	s_add_u32 s22, s22, 16384
	v_add_u32_e32 v231, s22, v243
	s_lshr_b32 s22, s23, 1
	s_lshl_b32 s22, s22, 7
	v_add_u32_e32 v244, s22, v241
	s_and_b32 s22, s23, 1
	s_lshl_b32 s22, s22, 6
	v_lshl_add_u32 v245, v242, 2, s22
	s_movk_i32 s22, 3584
	v_mul_lo_u32 v246, v244, s22
	v_lshl_add_u32 v234, v245, 1, v246
	s_movk_i32 s22, 5184
	v_mul_lo_u32 v246, v244, s22
	v_lshl_add_u32 v235, v245, 1, v246
	v_lshrrev_b32_e32 v241, 2, v240
	s_lshl_b32 s22, s23, 4
	v_add_u32_e32 v241, s22, v241
	v_bfe_u32 v242, v240, 5, 1
	v_mul_u32_u24_e32 v242, 3, v242
	v_and_b32_e32 v243, 3, v240
	v_xor_b32_e32 v243, v243, v242
	v_lshlrev_b32_e32 v243, 4, v243
	s_mov_b32 s22, 2048
	v_mad_u32_u24 v224, v241, s22, v243
	v_add_u32_e32 v225, 0x20000, v224
	v_add_u32_e32 v226, 0x40000, v224
	v_add_u32_e32 v227, 0x60000, v224
	s_mov_b32 s22, 2048
	v_mad_u32_u24 v228, v241, s22, v243
	v_add_u32_e32 v229, 0x20000, v228
	s_lshr_b32 s29, s96, 3
	s_and_b32 s101, s96, 7
	s_lshl_b32 s101, s101, 1
	s_waitcnt lgkmcnt(0)
.Lg1_tile:
	s_cmpk_ge_u32 s29, 560
	s_cbranch_scc1 .Lg1_done
	s_cmpk_ge_u32 s29, 280
	s_cselect_b32 s23, 1, 0
	s_cselect_b32 s22, 280, 0
	s_sub_u32 s22, s29, s22
	s_add_u32 s23, s23, s101
	s_lshl_b32 s23, s23, 3
	s_and_b32 s25, s22, 7
	s_add_u32 s25, s25, s23
	s_lshl_b32 s25, s25, 8
	s_lshr_b32 s24, s22, 3
	s_lshl_b32 s24, s24, 7
	s_mul_i32 s23, s25, 2048
	s_add_u32 s23, s23, 0x3800000
	s_add_u32 s0, s92, s23
	s_addc_u32 s1, s93, 0
	s_mul_i32 s23, s24, 2048
	s_add_u32 s23, s23, 0x0
	s_add_u32 s2, s92, s23
	s_addc_u32 s3, s93, 0
	s_mov_b32 s99, 0
	s_mov_b32 s30, 0
	s_add_u32 s22, s30, s100
	s_add_u32 m0, s22, 0
	s_nop 0
	global_load_lds_dwordx4 v224, s[0:1]
	s_add_u32 m0, s22, 4096
	s_nop 0
	global_load_lds_dwordx4 v225, s[0:1]
	s_add_u32 m0, s22, 8192
	s_nop 0
	global_load_lds_dwordx4 v226, s[0:1]
	s_add_u32 m0, s22, 12288
	s_nop 0
	global_load_lds_dwordx4 v227, s[0:1]
	s_add_u32 m0, s22, 16384
	s_nop 0
	global_load_lds_dwordx4 v228, s[2:3]
	s_add_u32 m0, s22, 20480
	s_nop 0
	global_load_lds_dwordx4 v229, s[2:3]
	s_add_u32 s0, s0, 64
	s_addc_u32 s1, s1, 0
	s_add_u32 s2, s2, 64
	s_addc_u32 s3, s3, 0
	s_add_u32 s99, s99, 1
	s_add_u32 s30, s30, 24576
	s_cmp_eq_u32 s30, 73728
	s_cselect_b32 s30, 0, s30
	s_add_u32 s22, s30, s100
	s_add_u32 m0, s22, 0
	s_nop 0
	global_load_lds_dwordx4 v224, s[0:1]
	s_add_u32 m0, s22, 4096
	s_nop 0
	global_load_lds_dwordx4 v225, s[0:1]
	s_add_u32 m0, s22, 8192
	s_nop 0
	global_load_lds_dwordx4 v226, s[0:1]
	s_add_u32 m0, s22, 12288
	s_nop 0
	global_load_lds_dwordx4 v227, s[0:1]
	s_add_u32 m0, s22, 16384
	s_nop 0
	global_load_lds_dwordx4 v228, s[2:3]
	s_add_u32 m0, s22, 20480
	s_nop 0
	global_load_lds_dwordx4 v229, s[2:3]
	s_add_u32 s0, s0, 64
	s_addc_u32 s1, s1, 0
	s_add_u32 s2, s2, 64
	s_addc_u32 s3, s3, 0
	s_add_u32 s99, s99, 1
	s_add_u32 s30, s30, 24576
	s_cmp_eq_u32 s30, 73728
	s_cselect_b32 s30, 0, s30
	s_add_u32 s22, s30, s100
	s_add_u32 m0, s22, 0
	s_nop 0
	global_load_lds_dwordx4 v224, s[0:1]
	s_add_u32 m0, s22, 4096
	s_nop 0
	global_load_lds_dwordx4 v225, s[0:1]
	s_add_u32 m0, s22, 8192
	s_nop 0
	global_load_lds_dwordx4 v226, s[0:1]
	s_add_u32 m0, s22, 12288
	s_nop 0
	global_load_lds_dwordx4 v227, s[0:1]
	s_add_u32 m0, s22, 16384
	s_nop 0
	global_load_lds_dwordx4 v228, s[2:3]
	s_add_u32 m0, s22, 20480
	s_nop 0
	global_load_lds_dwordx4 v229, s[2:3]
	s_add_u32 s0, s0, 64
	s_addc_u32 s1, s1, 0
	s_add_u32 s2, s2, 64
	s_addc_u32 s3, s3, 0
	s_add_u32 s99, s99, 1
	s_add_u32 s30, s30, 24576
	s_cmp_eq_u32 s30, 73728
	s_cselect_b32 s30, 0, s30
	v_mov_b32_e32 v0, 0
	v_mov_b32_e32 v1, 0
	v_mov_b32_e32 v2, 0
	v_mov_b32_e32 v3, 0
	v_mov_b32_e32 v4, 0
	v_mov_b32_e32 v5, 0
	v_mov_b32_e32 v6, 0
	v_mov_b32_e32 v7, 0
	v_mov_b32_e32 v8, 0
	v_mov_b32_e32 v9, 0
	v_mov_b32_e32 v10, 0
	v_mov_b32_e32 v11, 0
	v_mov_b32_e32 v12, 0
	v_mov_b32_e32 v13, 0
	v_mov_b32_e32 v14, 0
	v_mov_b32_e32 v15, 0
	v_mov_b32_e32 v16, 0
	v_mov_b32_e32 v17, 0
	v_mov_b32_e32 v18, 0
	v_mov_b32_e32 v19, 0
	v_mov_b32_e32 v20, 0
	v_mov_b32_e32 v21, 0
	v_mov_b32_e32 v22, 0
	v_mov_b32_e32 v23, 0
	v_mov_b32_e32 v24, 0
	v_mov_b32_e32 v25, 0
	v_mov_b32_e32 v26, 0
	v_mov_b32_e32 v27, 0
	v_mov_b32_e32 v28, 0
	v_mov_b32_e32 v29, 0
	v_mov_b32_e32 v30, 0
	v_mov_b32_e32 v31, 0
	v_mov_b32_e32 v32, 0
	v_mov_b32_e32 v33, 0
	v_mov_b32_e32 v34, 0
	v_mov_b32_e32 v35, 0
; #define LWRITE(S, buf) do { bf16_t* sA_ = sbase + (buf) * BUF; bf16_t* sB_ = sA_ + 256 * PITCH; \
;     _Pragma("unroll") for (int i_ = 0; i_ < 4; ++i_) *(u32x4*)(sA_ + (sr + i_ * 64) * PITCH + scv * 8) = ra[S][i_]; \
;     _Pragma("unroll") for (int i_ = 0; i_ < 2; ++i_) *(u32x4*)(sB_ + (sr + i_ * 64) * PITCH + scv * 8) = rb[S][i_]; } while (0)
; template <class Epi>
; DI void gemm_tile(char* smem, const bf16_t* __restrict__ A0, int lda0, int ksplit, const bf16_t* __restrict__ A1, int lda1,
;                   const bf16_t* __restrict__ Bt, int K, int row0, int col0, const Epi& epi, int tid) {
;     ...
;   __syncthreads();
;   {
;     const int last = nk - 1;
;     GLOAD(0, 0);
;     __builtin_amdgcn_sched_barrier(0);
;     GLOAD(1, 1);
;     __builtin_amdgcn_sched_barrier(0);
;     LWRITE(0, 0);
;     __builtin_amdgcn_sched_barrier(0);
;     GLOAD(0, (2 < last ? 2 : last));
;     __builtin_amdgcn_sched_barrier(0);
;     __syncthreads();
;     for (int kt = 0; kt < nk; kt += 2) {
;       LWRITE(1, 1);
;       __builtin_amdgcn_sched_barrier(0);
;       GLOAD(1, (kt + 3 < last ? kt + 3 : last));
;       __builtin_amdgcn_sched_barrier(0);
;       COMPUTE(0);
;       __syncthreads();
;       LWRITE(0, 0);
;       __builtin_amdgcn_sched_barrier(0);
;       GLOAD(0, (kt + 4 < last ? kt + 4 : last));
;       __builtin_amdgcn_sched_barrier(0);
;       COMPUTE(1);
	v_mov_b32_e32 v36, 0
	v_mov_b32_e32 v37, 0
	v_mov_b32_e32 v38, 0
	v_mov_b32_e32 v39, 0
	v_mov_b32_e32 v40, 0
	v_mov_b32_e32 v41, 0
	v_mov_b32_e32 v42, 0
	v_mov_b32_e32 v43, 0
	v_mov_b32_e32 v44, 0
	v_mov_b32_e32 v45, 0
	v_mov_b32_e32 v46, 0
	v_mov_b32_e32 v47, 0
	v_mov_b32_e32 v48, 0
	v_mov_b32_e32 v49, 0
	v_mov_b32_e32 v50, 0
	v_mov_b32_e32 v51, 0
	v_mov_b32_e32 v52, 0
	v_mov_b32_e32 v53, 0
	v_mov_b32_e32 v54, 0
	v_mov_b32_e32 v55, 0
	v_mov_b32_e32 v56, 0
	v_mov_b32_e32 v57, 0
	v_mov_b32_e32 v58, 0
	v_mov_b32_e32 v59, 0
	v_mov_b32_e32 v60, 0
	v_mov_b32_e32 v61, 0
	v_mov_b32_e32 v62, 0
	v_mov_b32_e32 v63, 0
	v_mov_b32_e32 v64, 0
	v_mov_b32_e32 v65, 0
	v_mov_b32_e32 v66, 0
	v_mov_b32_e32 v67, 0
	v_mov_b32_e32 v68, 0
	v_mov_b32_e32 v69, 0
	v_mov_b32_e32 v70, 0
	v_mov_b32_e32 v71, 0
	v_mov_b32_e32 v72, 0
	v_mov_b32_e32 v73, 0
	v_mov_b32_e32 v74, 0
	v_mov_b32_e32 v75, 0
	v_mov_b32_e32 v76, 0
	v_mov_b32_e32 v77, 0
	v_mov_b32_e32 v78, 0
	v_mov_b32_e32 v79, 0
	v_mov_b32_e32 v80, 0
	v_mov_b32_e32 v81, 0
	v_mov_b32_e32 v82, 0
	v_mov_b32_e32 v83, 0
	v_mov_b32_e32 v84, 0
	v_mov_b32_e32 v85, 0
	v_mov_b32_e32 v86, 0
	v_mov_b32_e32 v87, 0
	v_mov_b32_e32 v88, 0
	v_mov_b32_e32 v89, 0
	v_mov_b32_e32 v90, 0
	v_mov_b32_e32 v91, 0
	v_mov_b32_e32 v92, 0
	v_mov_b32_e32 v93, 0
	v_mov_b32_e32 v94, 0
	v_mov_b32_e32 v95, 0
	v_mov_b32_e32 v96, 0
	v_mov_b32_e32 v97, 0
	v_mov_b32_e32 v98, 0
	v_mov_b32_e32 v99, 0
	v_mov_b32_e32 v100, 0
	v_mov_b32_e32 v101, 0
	v_mov_b32_e32 v102, 0
	v_mov_b32_e32 v103, 0
	v_mov_b32_e32 v104, 0
	v_mov_b32_e32 v105, 0
	v_mov_b32_e32 v106, 0
	v_mov_b32_e32 v107, 0
	v_mov_b32_e32 v108, 0
	v_mov_b32_e32 v109, 0
	v_mov_b32_e32 v110, 0
	v_mov_b32_e32 v111, 0
	v_mov_b32_e32 v112, 0
	v_mov_b32_e32 v113, 0
	v_mov_b32_e32 v114, 0
	v_mov_b32_e32 v115, 0
	v_mov_b32_e32 v116, 0
	v_mov_b32_e32 v117, 0
	v_mov_b32_e32 v118, 0
	v_mov_b32_e32 v119, 0
	v_mov_b32_e32 v120, 0
	v_mov_b32_e32 v121, 0
	v_mov_b32_e32 v122, 0
	v_mov_b32_e32 v123, 0
	v_mov_b32_e32 v124, 0
	v_mov_b32_e32 v125, 0
	v_mov_b32_e32 v126, 0
	v_mov_b32_e32 v127, 0
	s_mov_b32 s98, 0
	s_mov_b32 s31, 24576
	s_waitcnt vmcnt(12)
	s_barrier
	ds_read_b128 v[128:131], v231 offset:0
	ds_read_b128 v[132:135], v231 offset:1024
	ds_read_b128 v[136:139], v231 offset:2048
	ds_read_b128 v[140:143], v231 offset:3072
	ds_read_b128 v[144:147], v230 offset:0
	ds_read_b128 v[148:151], v230 offset:1024
	ds_read_b128 v[152:155], v230 offset:2048
	ds_read_b128 v[156:159], v230 offset:3072
	ds_read_b128 v[160:163], v230 offset:4096
	ds_read_b128 v[164:167], v230 offset:5120
	ds_read_b128 v[168:171], v230 offset:6144
	ds_read_b128 v[172:175], v230 offset:7168
.Lg1_kloop:
	s_waitcnt vmcnt(6)
	s_waitcnt lgkmcnt(0)
	s_barrier
	v_add_u32_e32 v232, s31, v230
	v_add_u32_e32 v233, s31, v231
	s_add_u32 s22, s30, s100
	v_mfma_f32_16x16x32_bf16 v[0:3], v[128:131], v[144:147], v[0:3]
	v_mfma_f32_16x16x32_bf16 v[4:7], v[132:135], v[144:147], v[4:7]
	v_mfma_f32_16x16x32_bf16 v[8:11], v[136:139], v[144:147], v[8:11]
	v_mfma_f32_16x16x32_bf16 v[12:15], v[140:143], v[144:147], v[12:15]
	ds_read_b128 v[176:179], v233 offset:0
	ds_read_b128 v[180:183], v233 offset:1024
	s_add_u32 m0, s22, 0
	s_nop 0
	global_load_lds_dwordx4 v224, s[0:1]
	v_mfma_f32_16x16x32_bf16 v[16:19], v[128:131], v[148:151], v[16:19]
	v_mfma_f32_16x16x32_bf16 v[20:23], v[132:135], v[148:151], v[20:23]
	v_mfma_f32_16x16x32_bf16 v[24:27], v[136:139], v[148:151], v[24:27]
	v_mfma_f32_16x16x32_bf16 v[28:31], v[140:143], v[148:151], v[28:31]
	ds_read_b128 v[184:187], v233 offset:2048
	ds_read_b128 v[188:191], v233 offset:3072
	s_add_u32 m0, s22, 4096
	s_nop 0
	global_load_lds_dwordx4 v225, s[0:1]
	v_mfma_f32_16x16x32_bf16 v[32:35], v[128:131], v[152:155], v[32:35]
	v_mfma_f32_16x16x32_bf16 v[36:39], v[132:135], v[152:155], v[36:39]
	v_mfma_f32_16x16x32_bf16 v[40:43], v[136:139], v[152:155], v[40:43]
	v_mfma_f32_16x16x32_bf16 v[44:47], v[140:143], v[152:155], v[44:47]
	ds_read_b128 v[192:195], v232 offset:0
	ds_read_b128 v[196:199], v232 offset:1024
	s_add_u32 m0, s22, 8192
	s_nop 0
	global_load_lds_dwordx4 v226, s[0:1]
	v_mfma_f32_16x16x32_bf16 v[48:51], v[128:131], v[156:159], v[48:51]
	v_mfma_f32_16x16x32_bf16 v[52:55], v[132:135], v[156:159], v[52:55]
	v_mfma_f32_16x16x32_bf16 v[56:59], v[136:139], v[156:159], v[56:59]
	v_mfma_f32_16x16x32_bf16 v[60:63], v[140:143], v[156:159], v[60:63]
	ds_read_b128 v[200:203], v232 offset:2048
	ds_read_b128 v[204:207], v232 offset:3072
	s_add_u32 m0, s22, 12288
	s_nop 0
	global_load_lds_dwordx4 v227, s[0:1]
	v_mfma_f32_16x16x32_bf16 v[64:67], v[128:131], v[160:163], v[64:67]
	v_mfma_f32_16x16x32_bf16 v[68:71], v[132:135], v[160:163], v[68:71]
	v_mfma_f32_16x16x32_bf16 v[72:75], v[136:139], v[160:163], v[72:75]
	v_mfma_f32_16x16x32_bf16 v[76:79], v[140:143], v[160:163], v[76:79]
	ds_read_b128 v[208:211], v232 offset:4096
	s_add_u32 m0, s22, 16384
	s_nop 0
	global_load_lds_dwordx4 v228, s[2:3]
	v_mfma_f32_16x16x32_bf16 v[80:83], v[128:131], v[164:167], v[80:83]
	v_mfma_f32_16x16x32_bf16 v[84:87], v[132:135], v[164:167], v[84:87]
	v_mfma_f32_16x16x32_bf16 v[88:91], v[136:139], v[164:167], v[88:91]
	v_mfma_f32_16x16x32_bf16 v[92:95], v[140:143], v[164:167], v[92:95]
	ds_read_b128 v[212:215], v232 offset:5120
	s_add_u32 m0, s22, 20480
	s_nop 0
	global_load_lds_dwordx4 v229, s[2:3]
	v_mfma_f32_16x16x32_bf16 v[96:99], v[128:131], v[168:171], v[96:99]
	v_mfma_f32_16x16x32_bf16 v[100:103], v[132:135], v[168:171], v[100:103]
	v_mfma_f32_16x16x32_bf16 v[104:107], v[136:139], v[168:171], v[104:107]
	v_mfma_f32_16x16x32_bf16 v[108:111], v[140:143], v[168:171], v[108:111]
	ds_read_b128 v[216:219], v232 offset:6144
	s_add_u32 s0, s0, 64
	s_addc_u32 s1, s1, 0
	s_add_u32 s2, s2, 64
	s_addc_u32 s3, s3, 0
	s_add_u32 s99, s99, 1
	s_add_u32 s30, s30, 24576
	s_cmp_eq_u32 s30, 73728
	s_cselect_b32 s30, 0, s30
	s_add_u32 s31, s31, 24576
	s_cmp_eq_u32 s31, 73728
	s_cselect_b32 s31, 0, s31
	v_mfma_f32_16x16x32_bf16 v[112:115], v[128:131], v[172:175], v[112:115]
	v_mfma_f32_16x16x32_bf16 v[116:119], v[132:135], v[172:175], v[116:119]
	v_mfma_f32_16x16x32_bf16 v[120:123], v[136:139], v[172:175], v[120:123]
	v_mfma_f32_16x16x32_bf16 v[124:127], v[140:143], v[172:175], v[124:127]
	ds_read_b128 v[220:223], v232 offset:7168
	s_waitcnt vmcnt(6)
	s_waitcnt lgkmcnt(0)
	s_barrier
; #define LWRITE(S, buf) do { bf16_t* sA_ = sbase + (buf) * BUF; bf16_t* sB_ = sA_ + 256 * PITCH; \
;     _Pragma("unroll") for (int i_ = 0; i_ < 4; ++i_) *(u32x4*)(sA_ + (sr + i_ * 64) * PITCH + scv * 8) = ra[S][i_]; \
;     _Pragma("unroll") for (int i_ = 0; i_ < 2; ++i_) *(u32x4*)(sB_ + (sr + i_ * 64) * PITCH + scv * 8) = rb[S][i_]; } while (0)
; template <class Epi>
; DI void gemm_tile(char* smem, const bf16_t* __restrict__ A0, int lda0, int ksplit, const bf16_t* __restrict__ A1, int lda1,
;                   const bf16_t* __restrict__ Bt, int K, int row0, int col0, const Epi& epi, int tid) {
;     ...
;   __syncthreads();
;   {
;     const int last = nk - 1;
;     GLOAD(0, 0);
;     __builtin_amdgcn_sched_barrier(0);
;     GLOAD(1, 1);
;     __builtin_amdgcn_sched_barrier(0);
;     LWRITE(0, 0);
;     __builtin_amdgcn_sched_barrier(0);
;     GLOAD(0, (2 < last ? 2 : last));
;     __builtin_amdgcn_sched_barrier(0);
;     __syncthreads();
;     for (int kt = 0; kt < nk; kt += 2) {
;       LWRITE(1, 1);
;       __builtin_amdgcn_sched_barrier(0);
;       GLOAD(1, (kt + 3 < last ? kt + 3 : last));
;       __builtin_amdgcn_sched_barrier(0);
;       COMPUTE(0);
;       __syncthreads();
;       LWRITE(0, 0);
;       __builtin_amdgcn_sched_barrier(0);
;       GLOAD(0, (kt + 4 < last ? kt + 4 : last));
;       __builtin_amdgcn_sched_barrier(0);
;       COMPUTE(1);
	v_add_u32_e32 v232, s31, v230
	v_add_u32_e32 v233, s31, v231
	s_add_u32 s22, s30, s100
	v_mfma_f32_16x16x32_bf16 v[0:3], v[176:179], v[192:195], v[0:3]
	v_mfma_f32_16x16x32_bf16 v[4:7], v[180:183], v[192:195], v[4:7]
	v_mfma_f32_16x16x32_bf16 v[8:11], v[184:187], v[192:195], v[8:11]
	v_mfma_f32_16x16x32_bf16 v[12:15], v[188:191], v[192:195], v[12:15]
	ds_read_b128 v[128:131], v233 offset:0
	ds_read_b128 v[132:135], v233 offset:1024
	s_add_u32 m0, s22, 0
	s_nop 0
	global_load_lds_dwordx4 v224, s[0:1]
	v_mfma_f32_16x16x32_bf16 v[16:19], v[176:179], v[196:199], v[16:19]
	v_mfma_f32_16x16x32_bf16 v[20:23], v[180:183], v[196:199], v[20:23]
	v_mfma_f32_16x16x32_bf16 v[24:27], v[184:187], v[196:199], v[24:27]
	v_mfma_f32_16x16x32_bf16 v[28:31], v[188:191], v[196:199], v[28:31]
	ds_read_b128 v[136:139], v233 offset:2048
	ds_read_b128 v[140:143], v233 offset:3072
	s_add_u32 m0, s22, 4096
	s_nop 0
	global_load_lds_dwordx4 v225, s[0:1]
	v_mfma_f32_16x16x32_bf16 v[32:35], v[176:179], v[200:203], v[32:35]
	v_mfma_f32_16x16x32_bf16 v[36:39], v[180:183], v[200:203], v[36:39]
	v_mfma_f32_16x16x32_bf16 v[40:43], v[184:187], v[200:203], v[40:43]
	v_mfma_f32_16x16x32_bf16 v[44:47], v[188:191], v[200:203], v[44:47]
	ds_read_b128 v[144:147], v232 offset:0
	ds_read_b128 v[148:151], v232 offset:1024
	s_add_u32 m0, s22, 8192
	s_nop 0
	global_load_lds_dwordx4 v226, s[0:1]
	v_mfma_f32_16x16x32_bf16 v[48:51], v[176:179], v[204:207], v[48:51]
	v_mfma_f32_16x16x32_bf16 v[52:55], v[180:183], v[204:207], v[52:55]
	v_mfma_f32_16x16x32_bf16 v[56:59], v[184:187], v[204:207], v[56:59]
	v_mfma_f32_16x16x32_bf16 v[60:63], v[188:191], v[204:207], v[60:63]
	ds_read_b128 v[152:155], v232 offset:2048
	ds_read_b128 v[156:159], v232 offset:3072
	s_add_u32 m0, s22, 12288
	s_nop 0
	global_load_lds_dwordx4 v227, s[0:1]
	v_mfma_f32_16x16x32_bf16 v[64:67], v[176:179], v[208:211], v[64:67]
	v_mfma_f32_16x16x32_bf16 v[68:71], v[180:183], v[208:211], v[68:71]
	v_mfma_f32_16x16x32_bf16 v[72:75], v[184:187], v[208:211], v[72:75]
	v_mfma_f32_16x16x32_bf16 v[76:79], v[188:191], v[208:211], v[76:79]
	ds_read_b128 v[160:163], v232 offset:4096
	s_add_u32 m0, s22, 16384
	s_nop 0
	global_load_lds_dwordx4 v228, s[2:3]
	v_mfma_f32_16x16x32_bf16 v[80:83], v[176:179], v[212:215], v[80:83]
	v_mfma_f32_16x16x32_bf16 v[84:87], v[180:183], v[212:215], v[84:87]
	v_mfma_f32_16x16x32_bf16 v[88:91], v[184:187], v[212:215], v[88:91]
	v_mfma_f32_16x16x32_bf16 v[92:95], v[188:191], v[212:215], v[92:95]
	ds_read_b128 v[164:167], v232 offset:5120
	s_add_u32 m0, s22, 20480
	s_nop 0
	global_load_lds_dwordx4 v229, s[2:3]
	v_mfma_f32_16x16x32_bf16 v[96:99], v[176:179], v[216:219], v[96:99]
	v_mfma_f32_16x16x32_bf16 v[100:103], v[180:183], v[216:219], v[100:103]
	v_mfma_f32_16x16x32_bf16 v[104:107], v[184:187], v[216:219], v[104:107]
	v_mfma_f32_16x16x32_bf16 v[108:111], v[188:191], v[216:219], v[108:111]
	ds_read_b128 v[168:171], v232 offset:6144
	s_add_u32 s0, s0, 64
	s_addc_u32 s1, s1, 0
	s_add_u32 s2, s2, 64
	s_addc_u32 s3, s3, 0
	s_add_u32 s99, s99, 1
	s_add_u32 s30, s30, 24576
	s_cmp_eq_u32 s30, 73728
	s_cselect_b32 s30, 0, s30
	s_add_u32 s31, s31, 24576
	s_cmp_eq_u32 s31, 73728
	s_cselect_b32 s31, 0, s31
	v_mfma_f32_16x16x32_bf16 v[112:115], v[176:179], v[220:223], v[112:115]
	v_mfma_f32_16x16x32_bf16 v[116:119], v[180:183], v[220:223], v[116:119]
	v_mfma_f32_16x16x32_bf16 v[120:123], v[184:187], v[220:223], v[120:123]
	v_mfma_f32_16x16x32_bf16 v[124:127], v[188:191], v[220:223], v[124:127]
	ds_read_b128 v[172:175], v232 offset:7168
	s_add_u32 s98, s98, 2
	s_cmp_lt_u32 s98, 28
	s_cbranch_scc1 .Lg1_kloop
	s_waitcnt vmcnt(6)
	s_waitcnt lgkmcnt(0)
	s_barrier
	v_add_u32_e32 v232, s31, v230
	v_add_u32_e32 v233, s31, v231
	s_add_u32 s22, s30, s100
	v_mfma_f32_16x16x32_bf16 v[0:3], v[128:131], v[144:147], v[0:3]
	v_mfma_f32_16x16x32_bf16 v[4:7], v[132:135], v[144:147], v[4:7]
	v_mfma_f32_16x16x32_bf16 v[8:11], v[136:139], v[144:147], v[8:11]
	v_mfma_f32_16x16x32_bf16 v[12:15], v[140:143], v[144:147], v[12:15]
	ds_read_b128 v[176:179], v233 offset:0
	ds_read_b128 v[180:183], v233 offset:1024
	s_add_u32 m0, s22, 0
	s_nop 0
	global_load_lds_dwordx4 v224, s[0:1]
	v_mfma_f32_16x16x32_bf16 v[16:19], v[128:131], v[148:151], v[16:19]
	v_mfma_f32_16x16x32_bf16 v[20:23], v[132:135], v[148:151], v[20:23]
	v_mfma_f32_16x16x32_bf16 v[24:27], v[136:139], v[148:151], v[24:27]
	v_mfma_f32_16x16x32_bf16 v[28:31], v[140:143], v[148:151], v[28:31]
	ds_read_b128 v[184:187], v233 offset:2048
	ds_read_b128 v[188:191], v233 offset:3072
	s_add_u32 m0, s22, 4096
	s_nop 0
	global_load_lds_dwordx4 v225, s[0:1]
	v_mfma_f32_16x16x32_bf16 v[32:35], v[128:131], v[152:155], v[32:35]
	v_mfma_f32_16x16x32_bf16 v[36:39], v[132:135], v[152:155], v[36:39]
	v_mfma_f32_16x16x32_bf16 v[40:43], v[136:139], v[152:155], v[40:43]
	v_mfma_f32_16x16x32_bf16 v[44:47], v[140:143], v[152:155], v[44:47]
	ds_read_b128 v[192:195], v232 offset:0
	ds_read_b128 v[196:199], v232 offset:1024
	s_add_u32 m0, s22, 8192
	s_nop 0
	global_load_lds_dwordx4 v226, s[0:1]
	v_mfma_f32_16x16x32_bf16 v[48:51], v[128:131], v[156:159], v[48:51]
	v_mfma_f32_16x16x32_bf16 v[52:55], v[132:135], v[156:159], v[52:55]
	v_mfma_f32_16x16x32_bf16 v[56:59], v[136:139], v[156:159], v[56:59]
	v_mfma_f32_16x16x32_bf16 v[60:63], v[140:143], v[156:159], v[60:63]
	ds_read_b128 v[200:203], v232 offset:2048
	ds_read_b128 v[204:207], v232 offset:3072
	s_add_u32 m0, s22, 12288
	s_nop 0
	global_load_lds_dwordx4 v227, s[0:1]
	v_mfma_f32_16x16x32_bf16 v[64:67], v[128:131], v[160:163], v[64:67]
	v_mfma_f32_16x16x32_bf16 v[68:71], v[132:135], v[160:163], v[68:71]
	v_mfma_f32_16x16x32_bf16 v[72:75], v[136:139], v[160:163], v[72:75]
; #define LWRITE(S, buf) do { bf16_t* sA_ = sbase + (buf) * BUF; bf16_t* sB_ = sA_ + 256 * PITCH; \
;     _Pragma("unroll") for (int i_ = 0; i_ < 4; ++i_) *(u32x4*)(sA_ + (sr + i_ * 64) * PITCH + scv * 8) = ra[S][i_]; \
;     _Pragma("unroll") for (int i_ = 0; i_ < 2; ++i_) *(u32x4*)(sB_ + (sr + i_ * 64) * PITCH + scv * 8) = rb[S][i_]; } while (0)
; template <class Epi>
; DI void gemm_tile(char* smem, const bf16_t* __restrict__ A0, int lda0, int ksplit, const bf16_t* __restrict__ A1, int lda1,
;                   const bf16_t* __restrict__ Bt, int K, int row0, int col0, const Epi& epi, int tid) {
;     ...
;   __syncthreads();
;   {
;     const int last = nk - 1;
;     GLOAD(0, 0);
;     __builtin_amdgcn_sched_barrier(0);
;     GLOAD(1, 1);
;     __builtin_amdgcn_sched_barrier(0);
;     LWRITE(0, 0);
;     __builtin_amdgcn_sched_barrier(0);
;     GLOAD(0, (2 < last ? 2 : last));
;     __builtin_amdgcn_sched_barrier(0);
;     __syncthreads();
;     for (int kt = 0; kt < nk; kt += 2) {
;       LWRITE(1, 1);
;       __builtin_amdgcn_sched_barrier(0);
;       GLOAD(1, (kt + 3 < last ? kt + 3 : last));
;       __builtin_amdgcn_sched_barrier(0);
;       COMPUTE(0);
;       __syncthreads();
;       LWRITE(0, 0);
;       __builtin_amdgcn_sched_barrier(0);
;       GLOAD(0, (kt + 4 < last ? kt + 4 : last));
;       __builtin_amdgcn_sched_barrier(0);
;       COMPUTE(1);
;       __syncthreads();
;     }
	v_mfma_f32_16x16x32_bf16 v[76:79], v[140:143], v[160:163], v[76:79]
	ds_read_b128 v[208:211], v232 offset:4096
	s_add_u32 m0, s22, 16384
	s_nop 0
	global_load_lds_dwordx4 v228, s[2:3]
	v_mfma_f32_16x16x32_bf16 v[80:83], v[128:131], v[164:167], v[80:83]
	v_mfma_f32_16x16x32_bf16 v[84:87], v[132:135], v[164:167], v[84:87]
	v_mfma_f32_16x16x32_bf16 v[88:91], v[136:139], v[164:167], v[88:91]
	v_mfma_f32_16x16x32_bf16 v[92:95], v[140:143], v[164:167], v[92:95]
	ds_read_b128 v[212:215], v232 offset:5120
	s_add_u32 m0, s22, 20480
	s_nop 0
	global_load_lds_dwordx4 v229, s[2:3]
	v_mfma_f32_16x16x32_bf16 v[96:99], v[128:131], v[168:171], v[96:99]
	v_mfma_f32_16x16x32_bf16 v[100:103], v[132:135], v[168:171], v[100:103]
	v_mfma_f32_16x16x32_bf16 v[104:107], v[136:139], v[168:171], v[104:107]
	v_mfma_f32_16x16x32_bf16 v[108:111], v[140:143], v[168:171], v[108:111]
	ds_read_b128 v[216:219], v232 offset:6144
	s_add_u32 s0, s0, 64
	s_addc_u32 s1, s1, 0
	s_add_u32 s2, s2, 64
	s_addc_u32 s3, s3, 0
	s_add_u32 s99, s99, 1
	s_add_u32 s30, s30, 24576
	s_cmp_eq_u32 s30, 73728
	s_cselect_b32 s30, 0, s30
	s_add_u32 s31, s31, 24576
	s_cmp_eq_u32 s31, 73728
	s_cselect_b32 s31, 0, s31
	v_mfma_f32_16x16x32_bf16 v[112:115], v[128:131], v[172:175], v[112:115]
	v_mfma_f32_16x16x32_bf16 v[116:119], v[132:135], v[172:175], v[116:119]
	v_mfma_f32_16x16x32_bf16 v[120:123], v[136:139], v[172:175], v[120:123]
	v_mfma_f32_16x16x32_bf16 v[124:127], v[140:143], v[172:175], v[124:127]
	ds_read_b128 v[220:223], v232 offset:7168
	s_waitcnt vmcnt(6)
	s_waitcnt lgkmcnt(0)
	s_barrier
	v_add_u32_e32 v232, s31, v230
	v_add_u32_e32 v233, s31, v231
	v_mfma_f32_16x16x32_bf16 v[0:3], v[176:179], v[192:195], v[0:3]
	v_mfma_f32_16x16x32_bf16 v[4:7], v[180:183], v[192:195], v[4:7]
	v_mfma_f32_16x16x32_bf16 v[8:11], v[184:187], v[192:195], v[8:11]
	v_mfma_f32_16x16x32_bf16 v[12:15], v[188:191], v[192:195], v[12:15]
	ds_read_b128 v[128:131], v233 offset:0
	ds_read_b128 v[132:135], v233 offset:1024
	v_mfma_f32_16x16x32_bf16 v[16:19], v[176:179], v[196:199], v[16:19]
	v_mfma_f32_16x16x32_bf16 v[20:23], v[180:183], v[196:199], v[20:23]
	v_mfma_f32_16x16x32_bf16 v[24:27], v[184:187], v[196:199], v[24:27]
	v_mfma_f32_16x16x32_bf16 v[28:31], v[188:191], v[196:199], v[28:31]
	ds_read_b128 v[136:139], v233 offset:2048
	ds_read_b128 v[140:143], v233 offset:3072
	v_mfma_f32_16x16x32_bf16 v[32:35], v[176:179], v[200:203], v[32:35]
	v_mfma_f32_16x16x32_bf16 v[36:39], v[180:183], v[200:203], v[36:39]
	v_mfma_f32_16x16x32_bf16 v[40:43], v[184:187], v[200:203], v[40:43]
	v_mfma_f32_16x16x32_bf16 v[44:47], v[188:191], v[200:203], v[44:47]
	ds_read_b128 v[144:147], v232 offset:0
	ds_read_b128 v[148:151], v232 offset:1024
	v_mfma_f32_16x16x32_bf16 v[48:51], v[176:179], v[204:207], v[48:51]
	v_mfma_f32_16x16x32_bf16 v[52:55], v[180:183], v[204:207], v[52:55]
	v_mfma_f32_16x16x32_bf16 v[56:59], v[184:187], v[204:207], v[56:59]
	v_mfma_f32_16x16x32_bf16 v[60:63], v[188:191], v[204:207], v[60:63]
	ds_read_b128 v[152:155], v232 offset:2048
	ds_read_b128 v[156:159], v232 offset:3072
	v_mfma_f32_16x16x32_bf16 v[64:67], v[176:179], v[208:211], v[64:67]
	v_mfma_f32_16x16x32_bf16 v[68:71], v[180:183], v[208:211], v[68:71]
	v_mfma_f32_16x16x32_bf16 v[72:75], v[184:187], v[208:211], v[72:75]
	v_mfma_f32_16x16x32_bf16 v[76:79], v[188:191], v[208:211], v[76:79]
	ds_read_b128 v[160:163], v232 offset:4096
	v_mfma_f32_16x16x32_bf16 v[80:83], v[176:179], v[212:215], v[80:83]
	v_mfma_f32_16x16x32_bf16 v[84:87], v[180:183], v[212:215], v[84:87]
	v_mfma_f32_16x16x32_bf16 v[88:91], v[184:187], v[212:215], v[88:91]
	v_mfma_f32_16x16x32_bf16 v[92:95], v[188:191], v[212:215], v[92:95]
	ds_read_b128 v[164:167], v232 offset:5120
	v_mfma_f32_16x16x32_bf16 v[96:99], v[176:179], v[216:219], v[96:99]
	v_mfma_f32_16x16x32_bf16 v[100:103], v[180:183], v[216:219], v[100:103]
	v_mfma_f32_16x16x32_bf16 v[104:107], v[184:187], v[216:219], v[104:107]
	v_mfma_f32_16x16x32_bf16 v[108:111], v[188:191], v[216:219], v[108:111]
	ds_read_b128 v[168:171], v232 offset:6144
	s_add_u32 s31, s31, 24576
	s_cmp_eq_u32 s31, 73728
	s_cselect_b32 s31, 0, s31
	v_mfma_f32_16x16x32_bf16 v[112:115], v[176:179], v[220:223], v[112:115]
	v_mfma_f32_16x16x32_bf16 v[116:119], v[180:183], v[220:223], v[116:119]
	v_mfma_f32_16x16x32_bf16 v[120:123], v[184:187], v[220:223], v[120:123]
	v_mfma_f32_16x16x32_bf16 v[124:127], v[188:191], v[220:223], v[124:127]
	ds_read_b128 v[172:175], v232 offset:7168
	s_waitcnt vmcnt(0)
	s_waitcnt lgkmcnt(0)
	s_barrier
; #define LWRITE(S, buf) do { bf16_t* sA_ = sbase + (buf) * BUF; bf16_t* sB_ = sA_ + 256 * PITCH; \
;     _Pragma("unroll") for (int i_ = 0; i_ < 4; ++i_) *(u32x4*)(sA_ + (sr + i_ * 64) * PITCH + scv * 8) = ra[S][i_]; \
;     _Pragma("unroll") for (int i_ = 0; i_ < 2; ++i_) *(u32x4*)(sB_ + (sr + i_ * 64) * PITCH + scv * 8) = rb[S][i_]; } while (0)
; template <class Epi>
; DI void gemm_tile(char* smem, const bf16_t* __restrict__ A0, int lda0, int ksplit, const bf16_t* __restrict__ A1, int lda1,
;                   const bf16_t* __restrict__ Bt, int K, int row0, int col0, const Epi& epi, int tid) {
;     ...
;   __syncthreads();
;   {
;     const int last = nk - 1;
;     GLOAD(0, 0);
;     __builtin_amdgcn_sched_barrier(0);
;     GLOAD(1, 1);
;     __builtin_amdgcn_sched_barrier(0);
;     LWRITE(0, 0);
;     __builtin_amdgcn_sched_barrier(0);
;     GLOAD(0, (2 < last ? 2 : last));
;     __builtin_amdgcn_sched_barrier(0);
;     __syncthreads();
;     for (int kt = 0; kt < nk; kt += 2) {
;       LWRITE(1, 1);
;       __builtin_amdgcn_sched_barrier(0);
;       GLOAD(1, (kt + 3 < last ? kt + 3 : last));
;       __builtin_amdgcn_sched_barrier(0);
;       COMPUTE(0);
;       __syncthreads();
;       LWRITE(0, 0);
;       __builtin_amdgcn_sched_barrier(0);
;       GLOAD(0, (kt + 4 < last ? kt + 4 : last));
;       __builtin_amdgcn_sched_barrier(0);
;       COMPUTE(1);
;       __syncthreads();
;     }
	v_add_u32_e32 v232, s31, v230
	v_add_u32_e32 v233, s31, v231
	v_mfma_f32_16x16x32_bf16 v[0:3], v[128:131], v[144:147], v[0:3]
	v_mfma_f32_16x16x32_bf16 v[4:7], v[132:135], v[144:147], v[4:7]
	v_mfma_f32_16x16x32_bf16 v[8:11], v[136:139], v[144:147], v[8:11]
	v_mfma_f32_16x16x32_bf16 v[12:15], v[140:143], v[144:147], v[12:15]
	ds_read_b128 v[176:179], v233 offset:0
	ds_read_b128 v[180:183], v233 offset:1024
	v_mfma_f32_16x16x32_bf16 v[16:19], v[128:131], v[148:151], v[16:19]
	v_mfma_f32_16x16x32_bf16 v[20:23], v[132:135], v[148:151], v[20:23]
	v_mfma_f32_16x16x32_bf16 v[24:27], v[136:139], v[148:151], v[24:27]
	v_mfma_f32_16x16x32_bf16 v[28:31], v[140:143], v[148:151], v[28:31]
	ds_read_b128 v[184:187], v233 offset:2048
	ds_read_b128 v[188:191], v233 offset:3072
	v_mfma_f32_16x16x32_bf16 v[32:35], v[128:131], v[152:155], v[32:35]
	v_mfma_f32_16x16x32_bf16 v[36:39], v[132:135], v[152:155], v[36:39]
	v_mfma_f32_16x16x32_bf16 v[40:43], v[136:139], v[152:155], v[40:43]
	v_mfma_f32_16x16x32_bf16 v[44:47], v[140:143], v[152:155], v[44:47]
	ds_read_b128 v[192:195], v232 offset:0
	ds_read_b128 v[196:199], v232 offset:1024
	v_mfma_f32_16x16x32_bf16 v[48:51], v[128:131], v[156:159], v[48:51]
	v_mfma_f32_16x16x32_bf16 v[52:55], v[132:135], v[156:159], v[52:55]
	v_mfma_f32_16x16x32_bf16 v[56:59], v[136:139], v[156:159], v[56:59]
	v_mfma_f32_16x16x32_bf16 v[60:63], v[140:143], v[156:159], v[60:63]
	ds_read_b128 v[200:203], v232 offset:2048
	ds_read_b128 v[204:207], v232 offset:3072
	v_mfma_f32_16x16x32_bf16 v[64:67], v[128:131], v[160:163], v[64:67]
	v_mfma_f32_16x16x32_bf16 v[68:71], v[132:135], v[160:163], v[68:71]
	v_mfma_f32_16x16x32_bf16 v[72:75], v[136:139], v[160:163], v[72:75]
	v_mfma_f32_16x16x32_bf16 v[76:79], v[140:143], v[160:163], v[76:79]
	ds_read_b128 v[208:211], v232 offset:4096
	v_mfma_f32_16x16x32_bf16 v[80:83], v[128:131], v[164:167], v[80:83]
	v_mfma_f32_16x16x32_bf16 v[84:87], v[132:135], v[164:167], v[84:87]
	v_mfma_f32_16x16x32_bf16 v[88:91], v[136:139], v[164:167], v[88:91]
	v_mfma_f32_16x16x32_bf16 v[92:95], v[140:143], v[164:167], v[92:95]
	ds_read_b128 v[212:215], v232 offset:5120
	v_mfma_f32_16x16x32_bf16 v[96:99], v[128:131], v[168:171], v[96:99]
	v_mfma_f32_16x16x32_bf16 v[100:103], v[132:135], v[168:171], v[100:103]
	v_mfma_f32_16x16x32_bf16 v[104:107], v[136:139], v[168:171], v[104:107]
	v_mfma_f32_16x16x32_bf16 v[108:111], v[140:143], v[168:171], v[108:111]
	ds_read_b128 v[216:219], v232 offset:6144
	s_add_u32 s31, s31, 24576
	s_cmp_eq_u32 s31, 73728
	s_cselect_b32 s31, 0, s31
	v_mfma_f32_16x16x32_bf16 v[112:115], v[128:131], v[172:175], v[112:115]
	v_mfma_f32_16x16x32_bf16 v[116:119], v[132:135], v[172:175], v[116:119]
	v_mfma_f32_16x16x32_bf16 v[120:123], v[136:139], v[172:175], v[120:123]
	v_mfma_f32_16x16x32_bf16 v[124:127], v[140:143], v[172:175], v[124:127]
	ds_read_b128 v[220:223], v232 offset:7168
	s_waitcnt lgkmcnt(0)
	s_barrier
	v_mfma_f32_16x16x32_bf16 v[0:3], v[176:179], v[192:195], v[0:3]
	v_mfma_f32_16x16x32_bf16 v[4:7], v[180:183], v[192:195], v[4:7]
	v_mfma_f32_16x16x32_bf16 v[8:11], v[184:187], v[192:195], v[8:11]
	v_mfma_f32_16x16x32_bf16 v[12:15], v[188:191], v[192:195], v[12:15]
	v_mfma_f32_16x16x32_bf16 v[16:19], v[176:179], v[196:199], v[16:19]
	v_mfma_f32_16x16x32_bf16 v[20:23], v[180:183], v[196:199], v[20:23]
	v_mfma_f32_16x16x32_bf16 v[24:27], v[184:187], v[196:199], v[24:27]
	v_mfma_f32_16x16x32_bf16 v[28:31], v[188:191], v[196:199], v[28:31]
	v_mfma_f32_16x16x32_bf16 v[32:35], v[176:179], v[200:203], v[32:35]
	v_mfma_f32_16x16x32_bf16 v[36:39], v[180:183], v[200:203], v[36:39]
	v_mfma_f32_16x16x32_bf16 v[40:43], v[184:187], v[200:203], v[40:43]
	v_mfma_f32_16x16x32_bf16 v[44:47], v[188:191], v[200:203], v[44:47]
	v_mfma_f32_16x16x32_bf16 v[48:51], v[176:179], v[204:207], v[48:51]
	v_mfma_f32_16x16x32_bf16 v[52:55], v[180:183], v[204:207], v[52:55]
	v_mfma_f32_16x16x32_bf16 v[56:59], v[184:187], v[204:207], v[56:59]
	v_mfma_f32_16x16x32_bf16 v[60:63], v[188:191], v[204:207], v[60:63]
	v_mfma_f32_16x16x32_bf16 v[64:67], v[176:179], v[208:211], v[64:67]
	v_mfma_f32_16x16x32_bf16 v[68:71], v[180:183], v[208:211], v[68:71]
	v_mfma_f32_16x16x32_bf16 v[72:75], v[184:187], v[208:211], v[72:75]
	v_mfma_f32_16x16x32_bf16 v[76:79], v[188:191], v[208:211], v[76:79]
	v_mfma_f32_16x16x32_bf16 v[80:83], v[176:179], v[212:215], v[80:83]
	v_mfma_f32_16x16x32_bf16 v[84:87], v[180:183], v[212:215], v[84:87]
	v_mfma_f32_16x16x32_bf16 v[88:91], v[184:187], v[212:215], v[88:91]
	v_mfma_f32_16x16x32_bf16 v[92:95], v[188:191], v[212:215], v[92:95]
	v_mfma_f32_16x16x32_bf16 v[96:99], v[176:179], v[216:219], v[96:99]
	v_mfma_f32_16x16x32_bf16 v[100:103], v[180:183], v[216:219], v[100:103]
	v_mfma_f32_16x16x32_bf16 v[104:107], v[184:187], v[216:219], v[104:107]
	v_mfma_f32_16x16x32_bf16 v[108:111], v[188:191], v[216:219], v[108:111]
	v_mfma_f32_16x16x32_bf16 v[112:115], v[176:179], v[220:223], v[112:115]
	v_mfma_f32_16x16x32_bf16 v[116:119], v[180:183], v[220:223], v[116:119]
	v_mfma_f32_16x16x32_bf16 v[120:123], v[184:187], v[220:223], v[120:123]
	v_mfma_f32_16x16x32_bf16 v[124:127], v[188:191], v[220:223], v[124:127]
	s_branch .Lg1_epi
; DI unsigned pack2(float lo, float hi) { const f32x2c v = {lo, hi}; return __builtin_bit_cast(unsigned, __builtin_convertvector(v, bf16x2c)); }
; template <class Epi>
; DI void gemm_tile(char* smem, const bf16_t* __restrict__ A0, int lda0, int ksplit, const bf16_t* __restrict__ A1, int lda1,
;                   const bf16_t* __restrict__ Bt, int K, int row0, int col0, const Epi& epi, int tid) {
;     ...
;   for (int m = 0; m < 8; ++m)
; #pragma unroll
;     for (int n = 0; n < 4; ++n) epi(row0 + wr * 128 + m * 16 + fr, col0 + wc * 64 + n * 16 + fq * 4, acc[m][n]);
; }
; DI void st_bf16x4(bf16_t* o, f32x4 v) { u32x2 q; q.x = pack2(v[0], v[1]); q.y = pack2(v[2], v[3]); *(u32x2*)o = q; }
;   DI void operator()(int row, int col, f32x4 v) const {
;     if (col < n0) st_bf16x4(o0 + (size_t)row * ld0 + col, v);
;     else { const int c = col - n0; if (c < n1) st_bf16x4(o1 + (size_t)row * ld1 + c, v); }
;   }
.Lg1_epi:
	s_nop 7
	s_nop 7
	s_cmpk_ge_u32 s24, 1792
	s_cbranch_scc1 .Lg1_eo1
	s_mul_i32 s23, s25, 3584
	s_lshl_b32 s22, s24, 1
	s_add_u32 s23, s23, s22
	s_add_u32 s23, s23, 0x7800000
	s_add_u32 s4, s92, s23
	s_addc_u32 s5, s93, 0
	v_cvt_pk_bf16_f32 v128, v0, v1
	v_cvt_pk_bf16_f32 v129, v2, v3
	global_store_dwordx2 v234, v[128:129], s[4:5] offset:0
	v_cvt_pk_bf16_f32 v130, v4, v5
	v_cvt_pk_bf16_f32 v131, v6, v7
	global_store_dwordx2 v234, v[130:131], s[4:5] offset:32
	v_cvt_pk_bf16_f32 v132, v8, v9
	v_cvt_pk_bf16_f32 v133, v10, v11
	global_store_dwordx2 v234, v[132:133], s[4:5] offset:64
	v_cvt_pk_bf16_f32 v134, v12, v13
	v_cvt_pk_bf16_f32 v135, v14, v15
	global_store_dwordx2 v234, v[134:135], s[4:5] offset:96
	s_add_u32 s4, s4, 0xe000
	s_addc_u32 s5, s5, 0
	v_cvt_pk_bf16_f32 v136, v16, v17
	v_cvt_pk_bf16_f32 v137, v18, v19
	global_store_dwordx2 v234, v[136:137], s[4:5] offset:0
	v_cvt_pk_bf16_f32 v138, v20, v21
	v_cvt_pk_bf16_f32 v139, v22, v23
	global_store_dwordx2 v234, v[138:139], s[4:5] offset:32
	v_cvt_pk_bf16_f32 v140, v24, v25
	v_cvt_pk_bf16_f32 v141, v26, v27
	global_store_dwordx2 v234, v[140:141], s[4:5] offset:64
	v_cvt_pk_bf16_f32 v142, v28, v29
	v_cvt_pk_bf16_f32 v143, v30, v31
	global_store_dwordx2 v234, v[142:143], s[4:5] offset:96
	s_add_u32 s4, s4, 0xe000
	s_addc_u32 s5, s5, 0
	v_cvt_pk_bf16_f32 v144, v32, v33
	v_cvt_pk_bf16_f32 v145, v34, v35
	global_store_dwordx2 v234, v[144:145], s[4:5] offset:0
	v_cvt_pk_bf16_f32 v146, v36, v37
	v_cvt_pk_bf16_f32 v147, v38, v39
	global_store_dwordx2 v234, v[146:147], s[4:5] offset:32
	v_cvt_pk_bf16_f32 v148, v40, v41
	v_cvt_pk_bf16_f32 v149, v42, v43
	global_store_dwordx2 v234, v[148:149], s[4:5] offset:64
	v_cvt_pk_bf16_f32 v150, v44, v45
	v_cvt_pk_bf16_f32 v151, v46, v47
	global_store_dwordx2 v234, v[150:151], s[4:5] offset:96
	s_add_u32 s4, s4, 0xe000
	s_addc_u32 s5, s5, 0
	v_cvt_pk_bf16_f32 v152, v48, v49
	v_cvt_pk_bf16_f32 v153, v50, v51
	global_store_dwordx2 v234, v[152:153], s[4:5] offset:0
	v_cvt_pk_bf16_f32 v154, v52, v53
	v_cvt_pk_bf16_f32 v155, v54, v55
	global_store_dwordx2 v234, v[154:155], s[4:5] offset:32
	v_cvt_pk_bf16_f32 v156, v56, v57
	v_cvt_pk_bf16_f32 v157, v58, v59
	global_store_dwordx2 v234, v[156:157], s[4:5] offset:64
	v_cvt_pk_bf16_f32 v158, v60, v61
	v_cvt_pk_bf16_f32 v159, v62, v63
	global_store_dwordx2 v234, v[158:159], s[4:5] offset:96
	s_add_u32 s4, s4, 0xe000
	s_addc_u32 s5, s5, 0
	v_cvt_pk_bf16_f32 v128, v64, v65
	v_cvt_pk_bf16_f32 v129, v66, v67
	global_store_dwordx2 v234, v[128:129], s[4:5] offset:0
	v_cvt_pk_bf16_f32 v130, v68, v69
	v_cvt_pk_bf16_f32 v131, v70, v71
	global_store_dwordx2 v234, v[130:131], s[4:5] offset:32
	v_cvt_pk_bf16_f32 v132, v72, v73
	v_cvt_pk_bf16_f32 v133, v74, v75
	global_store_dwordx2 v234, v[132:133], s[4:5] offset:64
	v_cvt_pk_bf16_f32 v134, v76, v77
	v_cvt_pk_bf16_f32 v135, v78, v79
	global_store_dwordx2 v234, v[134:135], s[4:5] offset:96
	s_add_u32 s4, s4, 0xe000
	s_addc_u32 s5, s5, 0
	v_cvt_pk_bf16_f32 v136, v80, v81
	v_cvt_pk_bf16_f32 v137, v82, v83
	global_store_dwordx2 v234, v[136:137], s[4:5] offset:0
	v_cvt_pk_bf16_f32 v138, v84, v85
	v_cvt_pk_bf16_f32 v139, v86, v87
	global_store_dwordx2 v234, v[138:139], s[4:5] offset:32
	v_cvt_pk_bf16_f32 v140, v88, v89
	v_cvt_pk_bf16_f32 v141, v90, v91
	global_store_dwordx2 v234, v[140:141], s[4:5] offset:64
	v_cvt_pk_bf16_f32 v142, v92, v93
	v_cvt_pk_bf16_f32 v143, v94, v95
	global_store_dwordx2 v234, v[142:143], s[4:5] offset:96
	s_add_u32 s4, s4, 0xe000
	s_addc_u32 s5, s5, 0
	v_cvt_pk_bf16_f32 v144, v96, v97
	v_cvt_pk_bf16_f32 v145, v98, v99
	global_store_dwordx2 v234, v[144:145], s[4:5] offset:0
	v_cvt_pk_bf16_f32 v146, v100, v101
	v_cvt_pk_bf16_f32 v147, v102, v103
	global_store_dwordx2 v234, v[146:147], s[4:5] offset:32
	v_cvt_pk_bf16_f32 v148, v104, v105
	v_cvt_pk_bf16_f32 v149, v106, v107
	global_store_dwordx2 v234, v[148:149], s[4:5] offset:64
	v_cvt_pk_bf16_f32 v150, v108, v109
	v_cvt_pk_bf16_f32 v151, v110, v111
	global_store_dwordx2 v234, v[150:151], s[4:5] offset:96
	s_add_u32 s4, s4, 0xe000
	s_addc_u32 s5, s5, 0
	v_cvt_pk_bf16_f32 v152, v112, v113
	v_cvt_pk_bf16_f32 v153, v114, v115
	global_store_dwordx2 v234, v[152:153], s[4:5] offset:0
	v_cvt_pk_bf16_f32 v154, v116, v117
	v_cvt_pk_bf16_f32 v155, v118, v119
	global_store_dwordx2 v234, v[154:155], s[4:5] offset:32
	v_cvt_pk_bf16_f32 v156, v120, v121
	v_cvt_pk_bf16_f32 v157, v122, v123
	global_store_dwordx2 v234, v[156:157], s[4:5] offset:64
	v_cvt_pk_bf16_f32 v158, v124, v125
	v_cvt_pk_bf16_f32 v159, v126, v127
	global_store_dwordx2 v234, v[158:159], s[4:5] offset:96
	s_branch .Lg1_enext
.Lg1_eo1:
	s_mul_i32 s23, s25, 5184
	s_sub_u32 s22, s24, 1792
	s_lshl_b32 s22, s22, 1
	s_add_u32 s23, s23, s22
	s_add_u32 s23, s23, 0xe800000
	s_add_u32 s4, s92, s23
	s_addc_u32 s5, s93, 0
	s_sub_u32 s22, s24, 1792
	s_sub_u32 s22, 2592, s22
	s_lshr_b32 s23, s100, 4
	s_and_b32 s23, s23, 64
	s_sub_u32 s22, s22, s23
	v_cvt_pk_bf16_f32 v128, v0, v1
	v_cvt_pk_bf16_f32 v129, v2, v3
	s_cmp_gt_i32 s22, 0
	s_cbranch_scc0 .Lg1_ps0
	global_store_dwordx2 v235, v[128:129], s[4:5] offset:0
.Lg1_ps0:
	v_cvt_pk_bf16_f32 v130, v4, v5
	v_cvt_pk_bf16_f32 v131, v6, v7
	s_cmp_gt_i32 s22, 16
	s_cbranch_scc0 .Lg1_ps1
	global_store_dwordx2 v235, v[130:131], s[4:5] offset:32
.Lg1_ps1:
	v_cvt_pk_bf16_f32 v132, v8, v9
	v_cvt_pk_bf16_f32 v133, v10, v11
	s_cmp_gt_i32 s22, 32
	s_cbranch_scc0 .Lg1_ps2
	global_store_dwordx2 v235, v[132:133], s[4:5] offset:64
.Lg1_ps2:
	v_cvt_pk_bf16_f32 v134, v12, v13
	v_cvt_pk_bf16_f32 v135, v14, v15
	s_cmp_gt_i32 s22, 48
	s_cbranch_scc0 .Lg1_ps3
	global_store_dwordx2 v235, v[134:135], s[4:5] offset:96
; DI unsigned pack2(float lo, float hi) { const f32x2c v = {lo, hi}; return __builtin_bit_cast(unsigned, __builtin_convertvector(v, bf16x2c)); }
; template <class Epi>
; DI void gemm_tile(char* smem, const bf16_t* __restrict__ A0, int lda0, int ksplit, const bf16_t* __restrict__ A1, int lda1,
;                   const bf16_t* __restrict__ Bt, int K, int row0, int col0, const Epi& epi, int tid) {
;     ...
;   for (int m = 0; m < 8; ++m)
; #pragma unroll
;     for (int n = 0; n < 4; ++n) epi(row0 + wr * 128 + m * 16 + fr, col0 + wc * 64 + n * 16 + fq * 4, acc[m][n]);
; }
; DI void st_bf16x4(bf16_t* o, f32x4 v) { u32x2 q; q.x = pack2(v[0], v[1]); q.y = pack2(v[2], v[3]); *(u32x2*)o = q; }
;   DI void operator()(int row, int col, f32x4 v) const {
;     if (col < n0) st_bf16x4(o0 + (size_t)row * ld0 + col, v);
;     else { const int c = col - n0; if (c < n1) st_bf16x4(o1 + (size_t)row * ld1 + c, v); }
;   }
; template <class Epi>
; DI void gemm_phase(char* smem, const bf16_t* A0, int lda0, int ksplit, const bf16_t* A1, int lda1, const bf16_t* Bt, int K, int nN, const Epi& epi, int tid) {
;     ...
;     for (int q = l; q < tot; q += L) { const int rgl = q / per, rem = q % per, ct = rem >> 3, rt = (x * 2 + rgl) * 8 + (rem & 7);
.Lg1_ps3:
	s_add_u32 s4, s4, 0x14400
	s_addc_u32 s5, s5, 0
	v_cvt_pk_bf16_f32 v136, v16, v17
	v_cvt_pk_bf16_f32 v137, v18, v19
	s_cmp_gt_i32 s22, 0
	s_cbranch_scc0 .Lg1_ps4
	global_store_dwordx2 v235, v[136:137], s[4:5] offset:0
.Lg1_ps4:
	v_cvt_pk_bf16_f32 v138, v20, v21
	v_cvt_pk_bf16_f32 v139, v22, v23
	s_cmp_gt_i32 s22, 16
	s_cbranch_scc0 .Lg1_ps5
	global_store_dwordx2 v235, v[138:139], s[4:5] offset:32
.Lg1_ps5:
	v_cvt_pk_bf16_f32 v140, v24, v25
	v_cvt_pk_bf16_f32 v141, v26, v27
	s_cmp_gt_i32 s22, 32
	s_cbranch_scc0 .Lg1_ps6
	global_store_dwordx2 v235, v[140:141], s[4:5] offset:64
.Lg1_ps6:
	v_cvt_pk_bf16_f32 v142, v28, v29
	v_cvt_pk_bf16_f32 v143, v30, v31
	s_cmp_gt_i32 s22, 48
	s_cbranch_scc0 .Lg1_ps7
	global_store_dwordx2 v235, v[142:143], s[4:5] offset:96
.Lg1_ps7:
	s_add_u32 s4, s4, 0x14400
	s_addc_u32 s5, s5, 0
	v_cvt_pk_bf16_f32 v144, v32, v33
	v_cvt_pk_bf16_f32 v145, v34, v35
	s_cmp_gt_i32 s22, 0
	s_cbranch_scc0 .Lg1_ps8
	global_store_dwordx2 v235, v[144:145], s[4:5] offset:0
.Lg1_ps8:
	v_cvt_pk_bf16_f32 v146, v36, v37
	v_cvt_pk_bf16_f32 v147, v38, v39
	s_cmp_gt_i32 s22, 16
	s_cbranch_scc0 .Lg1_ps9
	global_store_dwordx2 v235, v[146:147], s[4:5] offset:32
.Lg1_ps9:
	v_cvt_pk_bf16_f32 v148, v40, v41
	v_cvt_pk_bf16_f32 v149, v42, v43
	s_cmp_gt_i32 s22, 32
	s_cbranch_scc0 .Lg1_ps10
	global_store_dwordx2 v235, v[148:149], s[4:5] offset:64
.Lg1_ps10:
	v_cvt_pk_bf16_f32 v150, v44, v45
	v_cvt_pk_bf16_f32 v151, v46, v47
	s_cmp_gt_i32 s22, 48
	s_cbranch_scc0 .Lg1_ps11
	global_store_dwordx2 v235, v[150:151], s[4:5] offset:96
.Lg1_ps11:
	s_add_u32 s4, s4, 0x14400
	s_addc_u32 s5, s5, 0
	v_cvt_pk_bf16_f32 v152, v48, v49
	v_cvt_pk_bf16_f32 v153, v50, v51
	s_cmp_gt_i32 s22, 0
	s_cbranch_scc0 .Lg1_ps12
	global_store_dwordx2 v235, v[152:153], s[4:5] offset:0
.Lg1_ps12:
	v_cvt_pk_bf16_f32 v154, v52, v53
	v_cvt_pk_bf16_f32 v155, v54, v55
	s_cmp_gt_i32 s22, 16
	s_cbranch_scc0 .Lg1_ps13
	global_store_dwordx2 v235, v[154:155], s[4:5] offset:32
.Lg1_ps13:
	v_cvt_pk_bf16_f32 v156, v56, v57
	v_cvt_pk_bf16_f32 v157, v58, v59
	s_cmp_gt_i32 s22, 32
	s_cbranch_scc0 .Lg1_ps14
	global_store_dwordx2 v235, v[156:157], s[4:5] offset:64
.Lg1_ps14:
	v_cvt_pk_bf16_f32 v158, v60, v61
	v_cvt_pk_bf16_f32 v159, v62, v63
	s_cmp_gt_i32 s22, 48
	s_cbranch_scc0 .Lg1_ps15
	global_store_dwordx2 v235, v[158:159], s[4:5] offset:96
.Lg1_ps15:
	s_add_u32 s4, s4, 0x14400
	s_addc_u32 s5, s5, 0
	v_cvt_pk_bf16_f32 v128, v64, v65
	v_cvt_pk_bf16_f32 v129, v66, v67
	s_cmp_gt_i32 s22, 0
	s_cbranch_scc0 .Lg1_ps16
	global_store_dwordx2 v235, v[128:129], s[4:5] offset:0
.Lg1_ps16:
	v_cvt_pk_bf16_f32 v130, v68, v69
	v_cvt_pk_bf16_f32 v131, v70, v71
	s_cmp_gt_i32 s22, 16
	s_cbranch_scc0 .Lg1_ps17
	global_store_dwordx2 v235, v[130:131], s[4:5] offset:32
.Lg1_ps17:
	v_cvt_pk_bf16_f32 v132, v72, v73
	v_cvt_pk_bf16_f32 v133, v74, v75
	s_cmp_gt_i32 s22, 32
	s_cbranch_scc0 .Lg1_ps18
	global_store_dwordx2 v235, v[132:133], s[4:5] offset:64
.Lg1_ps18:
	v_cvt_pk_bf16_f32 v134, v76, v77
	v_cvt_pk_bf16_f32 v135, v78, v79
	s_cmp_gt_i32 s22, 48
	s_cbranch_scc0 .Lg1_ps19
	global_store_dwordx2 v235, v[134:135], s[4:5] offset:96
.Lg1_ps19:
	s_add_u32 s4, s4, 0x14400
	s_addc_u32 s5, s5, 0
	v_cvt_pk_bf16_f32 v136, v80, v81
	v_cvt_pk_bf16_f32 v137, v82, v83
	s_cmp_gt_i32 s22, 0
	s_cbranch_scc0 .Lg1_ps20
	global_store_dwordx2 v235, v[136:137], s[4:5] offset:0
.Lg1_ps20:
	v_cvt_pk_bf16_f32 v138, v84, v85
	v_cvt_pk_bf16_f32 v139, v86, v87
	s_cmp_gt_i32 s22, 16
	s_cbranch_scc0 .Lg1_ps21
	global_store_dwordx2 v235, v[138:139], s[4:5] offset:32
.Lg1_ps21:
	v_cvt_pk_bf16_f32 v140, v88, v89
	v_cvt_pk_bf16_f32 v141, v90, v91
	s_cmp_gt_i32 s22, 32
	s_cbranch_scc0 .Lg1_ps22
	global_store_dwordx2 v235, v[140:141], s[4:5] offset:64
.Lg1_ps22:
	v_cvt_pk_bf16_f32 v142, v92, v93
	v_cvt_pk_bf16_f32 v143, v94, v95
	s_cmp_gt_i32 s22, 48
	s_cbranch_scc0 .Lg1_ps23
	global_store_dwordx2 v235, v[142:143], s[4:5] offset:96
.Lg1_ps23:
	s_add_u32 s4, s4, 0x14400
	s_addc_u32 s5, s5, 0
	v_cvt_pk_bf16_f32 v144, v96, v97
	v_cvt_pk_bf16_f32 v145, v98, v99
	s_cmp_gt_i32 s22, 0
	s_cbranch_scc0 .Lg1_ps24
	global_store_dwordx2 v235, v[144:145], s[4:5] offset:0
.Lg1_ps24:
	v_cvt_pk_bf16_f32 v146, v100, v101
	v_cvt_pk_bf16_f32 v147, v102, v103
	s_cmp_gt_i32 s22, 16
	s_cbranch_scc0 .Lg1_ps25
	global_store_dwordx2 v235, v[146:147], s[4:5] offset:32
.Lg1_ps25:
	v_cvt_pk_bf16_f32 v148, v104, v105
	v_cvt_pk_bf16_f32 v149, v106, v107
	s_cmp_gt_i32 s22, 32
	s_cbranch_scc0 .Lg1_ps26
	global_store_dwordx2 v235, v[148:149], s[4:5] offset:64
.Lg1_ps26:
	v_cvt_pk_bf16_f32 v150, v108, v109
	v_cvt_pk_bf16_f32 v151, v110, v111
	s_cmp_gt_i32 s22, 48
	s_cbranch_scc0 .Lg1_ps27
	global_store_dwordx2 v235, v[150:151], s[4:5] offset:96
.Lg1_ps27:
	s_add_u32 s4, s4, 0x14400
	s_addc_u32 s5, s5, 0
	v_cvt_pk_bf16_f32 v152, v112, v113
	v_cvt_pk_bf16_f32 v153, v114, v115
	s_cmp_gt_i32 s22, 0
	s_cbranch_scc0 .Lg1_ps28
	global_store_dwordx2 v235, v[152:153], s[4:5] offset:0
.Lg1_ps28:
	v_cvt_pk_bf16_f32 v154, v116, v117
	v_cvt_pk_bf16_f32 v155, v118, v119
	s_cmp_gt_i32 s22, 16
	s_cbranch_scc0 .Lg1_ps29
	global_store_dwordx2 v235, v[154:155], s[4:5] offset:32
.Lg1_ps29:
	v_cvt_pk_bf16_f32 v156, v120, v121
	v_cvt_pk_bf16_f32 v157, v122, v123
	s_cmp_gt_i32 s22, 32
	s_cbranch_scc0 .Lg1_ps30
	global_store_dwordx2 v235, v[156:157], s[4:5] offset:64
.Lg1_ps30:
	v_cvt_pk_bf16_f32 v158, v124, v125
	v_cvt_pk_bf16_f32 v159, v126, v127
	s_cmp_gt_i32 s22, 48
	s_cbranch_scc0 .Lg1_ps31
	global_store_dwordx2 v235, v[158:159], s[4:5] offset:96
.Lg1_ps31:
.Lg1_enext:
	s_add_u32 s29, s29, 64
	s_branch .Lg1_tile
.Lg1_done:
	v_mbcnt_lo_u32_b32 v194, -1, 0
	v_mbcnt_hi_u32_b32 v195, -1, v194

; #define LWRITE(S, buf) do { bf16_t* sA_ = sbase + (buf) * BUF; bf16_t* sB_ = sA_ + 256 * PITCH; \
;     _Pragma("unroll") for (int i_ = 0; i_ < 4; ++i_) *(u32x4*)(sA_ + (sr + i_ * 64) * PITCH + scv * 8) = ra[S][i_]; \
;     _Pragma("unroll") for (int i_ = 0; i_ < 2; ++i_) *(u32x4*)(sB_ + (sr + i_ * 64) * PITCH + scv * 8) = rb[S][i_]; } while (0)
; template <class Epi>
; DI void gemm_tile(char* smem, const bf16_t* __restrict__ A0, int lda0, int ksplit, const bf16_t* __restrict__ A1, int lda1,
;                   const bf16_t* __restrict__ Bt, int K, int row0, int col0, const Epi& epi, int tid) {
;     ...
;   u32x4 ra[2][4], rb[2][2];
;   const int nk = K / BK;
;   const int sr = tid >> 2, scv = tid & 3;
;     ...
;   __syncthreads();
;   {
;     const int last = nk - 1;
;     GLOAD(0, 0);
;     __builtin_amdgcn_sched_barrier(0);
;     GLOAD(1, 1);
;     __builtin_amdgcn_sched_barrier(0);
;     LWRITE(0, 0);
;     __builtin_amdgcn_sched_barrier(0);
;     GLOAD(0, (2 < last ? 2 : last));
;     __builtin_amdgcn_sched_barrier(0);
;     __syncthreads();
;     for (int kt = 0; kt < nk; kt += 2) {
;       LWRITE(1, 1);
;       __builtin_amdgcn_sched_barrier(0);
;       GLOAD(1, (kt + 3 < last ? kt + 3 : last));
;       __builtin_amdgcn_sched_barrier(0);
;       COMPUTE(0);
;       __syncthreads();
; template <class Epi>
; DI void gemm_phase(char* smem, const bf16_t* A0, int lda0, int ksplit, const bf16_t* A1, int lda1, const bf16_t* Bt, int K, int nN, const Epi& epi, int tid) {
;     ...
;     for (int u = blockIdx.x; u < ntiles; u += G) { const int rt = u / nN, ct = u % nN; gemm_tile(smem, A0, lda0, ksplit, A1, lda1, Bt, K, rt * 256, ct * 128, epi, tid); }
.LBB0_549:
	s_cmp_gt_i32 s94, 3
	s_cselect_b64 s[0:1], -1, 0
	s_cmp_lt_i32 s95, 4
	s_cselect_b64 s[2:3], -1, 0
	s_or_b64 s[0:1], s[0:1], s[2:3]
	s_and_b64 vcc, exec, s[0:1]
	s_cbranch_vccnz .LBB0_600
	s_and_b32 s14, s72, 0xffffffc0
	s_add_u32 s4, s92, 0x1ea00000
	s_load_dword s12, s[74:75], 0x180
	s_addc_u32 s5, s93, 0
	s_add_u32 s0, s92, 0x7800000
	s_addc_u32 s1, s93, 0
	s_add_u32 s6, s92, 0x34a0000
	s_addc_u32 s7, s93, 0
	s_waitcnt lgkmcnt(0)
	s_and_b32 s13, s12, 7
	s_cmp_lg_u32 s13, 0
	s_waitcnt vmcnt(7)
	v_mbcnt_hi_u32_b32 v136, -1, v194
	s_cselect_b64 s[2:3], -1, 0
	v_add_u32_e32 v137, s14, v136
	s_and_b64 vcc, exec, s[2:3]
	s_cbranch_vccz .LBB0_555
	s_load_dwordx16 s[56:71], s[74:75], 0x40
	s_cmpk_gt_i32 s96, 0x1ff
	s_cbranch_scc1 .LBB0_554
	v_and_b32_e32 v0, 3, v136
	v_lshlrev_b32_e32 v0, 4, v0
	v_mov_b32_e32 v1, 0
	v_ashrrev_i32_e32 v122, 2, v137
	v_lshl_add_u64 v[112:113], s[4:5], 0, v[0:1]
	v_lshl_add_u64 v[114:115], s[6:7], 0, v[0:1]
	v_bfe_u32 v1, v136, 4, 2
	s_movk_i32 s8, 0x40
	v_and_b32_e32 v3, 0x4f, v137
	v_and_b32_e32 v123, 0xffffff8f, v137
	v_or_b32_e32 v6, 0x70, v137
	v_add_u32_e32 v0, 0, v0
	v_mul_lo_u32 v2, v122, s8
	v_lshl_add_u32 v4, v1, 4, 0
	v_mul_u32_u24_e32 v3, 0x40, v3
	v_mul_lo_u32 v5, v123, s8
	v_mul_lo_u32 v6, v6, s8
	v_lshlrev_b32_e32 v1, 2, v1
	v_and_or_b32 v124, v137, 64, v1
	s_lshl_b32 s11, s96, 7
	s_lshl_b32 s15, s12, 7
	s_mov_b64 s[8:9], 0x18000
	s_mov_b32 s16, 0x18000
	v_add_u32_e32 v125, v0, v2
	v_add_u32_e32 v126, v4, v3
	v_add_u32_e32 v127, v4, v5
	v_add_u32_e32 v128, v4, v6
	v_mbcnt_lo_u32_b32 v2, -1, 0
	v_mbcnt_hi_u32_b32 v2, -1, v2
	v_bfe_u32 v3, v2, 3, 1
	v_bfe_u32 v2, v2, 5, 1
	v_mul_u32_u24_e32 v3, 48, v3
	v_mul_u32_u24_e32 v2, 48, v2
	v_xor_b32_e32 v125, v125, v2
	v_xor_b32_e32 v126, v126, v3
	v_xor_b32_e32 v127, v127, v3
	v_xor_b32_e32 v128, v128, v3
	s_mov_b32 s10, 0x3f1b4598
	s_mov_b32 s17, s96
.LBB0_553:
	s_ashr_i32 s18, s17, 31
	s_lshr_b32 s18, s18, 30
	s_add_i32 s18, s17, s18
	s_ashr_i32 s19, s18, 2
	s_lshl_b32 s18, s19, 8
	v_add_u32_e32 v0, s18, v122
	v_ashrrev_i32_e32 v1, 31, v0
	v_lshlrev_b64 v[0:1], 9, v[0:1]
	v_lshl_add_u64 v[24:25], v[112:113], 0, v[0:1]
	s_mov_b32 s20, 0x8000
	s_lshl_b32 s19, s19, 9
	v_add_co_u32_e32 v4, vcc, s20, v24
	s_sub_i32 s19, s11, s19
	s_nop 0
	v_addc_co_u32_e32 v5, vcc, 0, v25, vcc
	s_mov_b32 s20, 0x10000
	v_add_u32_e32 v16, s19, v122
	v_add_co_u32_e32 v8, vcc, s20, v24
	v_ashrrev_i32_e32 v17, 31, v16
	s_nop 0
	v_addc_co_u32_e32 v9, vcc, 0, v25, vcc
	v_lshlrev_b64 v[18:19], 7, v[16:17]
	v_add_u32_e32 v16, 64, v16
	v_add_co_u32_e32 v12, vcc, s16, v24
	v_ashrrev_i32_e32 v17, 31, v16
	s_nop 0
	v_addc_co_u32_e32 v13, vcc, 0, v25, vcc
	v_lshl_add_u64 v[40:41], v[114:115], 0, v[18:19]
	v_lshlrev_b64 v[16:17], 7, v[16:17]
	s_waitcnt lgkmcnt(0)
	s_barrier
	global_load_dwordx4 v[0:3], v[24:25], off
	s_nop 0
	global_load_dwordx4 v[4:7], v[4:5], off
	s_nop 0
	global_load_dwordx4 v[8:11], v[8:9], off
	s_nop 0
	global_load_dwordx4 v[12:15], v[12:13], off
	v_lshl_add_u64 v[44:45], v[114:115], 0, v[16:17]
	global_load_dwordx4 v[16:19], v[40:41], off
	global_load_dwordx4 v[20:23], v[44:45], off
	s_mov_b64 s[20:21], 0x8000
	v_lshl_add_u64 v[28:29], v[24:25], 0, s[20:21]
	s_mov_b64 s[20:21], 0x10000
	v_lshl_add_u64 v[32:33], v[24:25], 0, s[20:21]
	v_lshl_add_u64 v[36:37], v[24:25], 0, s[8:9]
	global_load_dwordx4 v[24:27], v[24:25], off offset:64
	s_nop 0
	global_load_dwordx4 v[28:31], v[28:29], off offset:64
	s_nop 0
	global_load_dwordx4 v[32:35], v[32:33], off offset:64
	s_nop 0
	global_load_dwordx4 v[36:39], v[36:37], off offset:64
	s_nop 0
	global_load_dwordx4 v[40:43], v[40:41], off offset:64
	s_nop 0
	global_load_dwordx4 v[44:47], v[44:45], off offset:64
	s_waitcnt vmcnt(11)
	ds_write_b128 v125, v[0:3]
	s_waitcnt vmcnt(10)
	ds_write_b128 v125, v[4:7] offset:4096
	s_waitcnt vmcnt(9)
	ds_write_b128 v125, v[8:11] offset:8192
	s_waitcnt vmcnt(8)
	ds_write_b128 v125, v[12:15] offset:12288
	s_waitcnt vmcnt(7)
	ds_write_b128 v125, v[16:19] offset:16384
	s_waitcnt vmcnt(6)
	ds_write_b128 v125, v[20:23] offset:20480
	s_waitcnt lgkmcnt(0)
	s_barrier
	s_waitcnt vmcnt(5)
	ds_write_b128 v125, v[24:27] offset:24576
	s_waitcnt vmcnt(4)
	ds_write_b128 v125, v[28:31] offset:28672
	s_waitcnt vmcnt(3)
	ds_write_b128 v125, v[32:35] offset:32768
	s_waitcnt vmcnt(2)
	ds_write_b128 v125, v[36:39] offset:36864
	s_waitcnt vmcnt(1)
	ds_write_b128 v125, v[40:43] offset:40960
	s_waitcnt vmcnt(0)
	ds_write_b128 v125, v[44:47] offset:45056
	ds_read_b128 v[0:3], v126 offset:16384
	ds_read_b128 v[4:7], v126 offset:17408
	ds_read_b128 v[8:11], v126 offset:18432
	ds_read_b128 v[12:15], v126 offset:19456
	ds_read_b128 v[16:19], v127
	ds_read_b128 v[20:23], v127 offset:1024
	ds_read_b128 v[48:51], v127 offset:2048
	ds_read_b128 v[52:55], v127 offset:3072
	ds_read_b128 v[56:59], v127 offset:4096
	ds_read_b128 v[60:63], v127 offset:5120
	ds_read_b128 v[64:67], v127 offset:6144
	ds_read_b128 v[68:71], v128
	s_setprio 1
	s_waitcnt lgkmcnt(7)
	v_mfma_f32_16x16x32_bf16 v[72:75], v[0:3], v[16:19], 0
	v_mfma_f32_16x16x32_bf16 v[76:79], v[4:7], v[16:19], 0
	v_mfma_f32_16x16x32_bf16 v[80:83], v[8:11], v[16:19], 0
	v_mfma_f32_16x16x32_bf16 v[16:19], v[12:15], v[16:19], 0
	s_waitcnt lgkmcnt(6)
	v_mfma_f32_16x16x32_bf16 v[84:87], v[0:3], v[20:23], 0
	v_mfma_f32_16x16x32_bf16 v[88:91], v[4:7], v[20:23], 0
	v_mfma_f32_16x16x32_bf16 v[92:95], v[8:11], v[20:23], 0
	v_mfma_f32_16x16x32_bf16 v[20:23], v[12:15], v[20:23], 0
	s_waitcnt lgkmcnt(5)
	v_mfma_f32_16x16x32_bf16 v[116:119], v[0:3], v[48:51], 0
	v_mfma_f32_16x16x32_bf16 v[130:133], v[4:7], v[48:51], 0
	v_mfma_f32_16x16x32_bf16 v[138:141], v[8:11], v[48:51], 0
	v_mfma_f32_16x16x32_bf16 v[48:51], v[12:15], v[48:51], 0
	s_waitcnt lgkmcnt(4)
	v_mfma_f32_16x16x32_bf16 v[142:145], v[0:3], v[52:55], 0
	v_mfma_f32_16x16x32_bf16 v[146:149], v[4:7], v[52:55], 0
	v_mfma_f32_16x16x32_bf16 v[150:153], v[8:11], v[52:55], 0
	v_mfma_f32_16x16x32_bf16 v[52:55], v[12:15], v[52:55], 0
	s_waitcnt lgkmcnt(3)
	v_mfma_f32_16x16x32_bf16 v[154:157], v[0:3], v[56:59], 0
	v_mfma_f32_16x16x32_bf16 v[158:161], v[4:7], v[56:59], 0
	v_mfma_f32_16x16x32_bf16 v[162:165], v[8:11], v[56:59], 0
	v_mfma_f32_16x16x32_bf16 v[166:169], v[12:15], v[56:59], 0
	s_waitcnt lgkmcnt(2)
	v_mfma_f32_16x16x32_bf16 v[170:173], v[0:3], v[60:63], 0
	v_mfma_f32_16x16x32_bf16 v[174:177], v[4:7], v[60:63], 0
	v_mfma_f32_16x16x32_bf16 v[178:181], v[8:11], v[60:63], 0
	v_mfma_f32_16x16x32_bf16 v[182:185], v[12:15], v[60:63], 0
	s_waitcnt lgkmcnt(1)
	v_mfma_f32_16x16x32_bf16 v[186:189], v[0:3], v[64:67], 0
	v_mfma_f32_16x16x32_bf16 v[190:193], v[4:7], v[64:67], 0
	v_mfma_f32_16x16x32_bf16 v[196:199], v[8:11], v[64:67], 0
	v_mfma_f32_16x16x32_bf16 v[200:203], v[12:15], v[64:67], 0
	s_waitcnt lgkmcnt(0)
	v_mfma_f32_16x16x32_bf16 v[0:3], v[0:3], v[68:71], 0
	v_mfma_f32_16x16x32_bf16 v[4:7], v[4:7], v[68:71], 0
	v_mfma_f32_16x16x32_bf16 v[204:207], v[8:11], v[68:71], 0
	v_mfma_f32_16x16x32_bf16 v[208:211], v[12:15], v[68:71], 0
	s_setprio 0
	s_barrier
; DI unsigned pack2(float lo, float hi) { const f32x2c v = {lo, hi}; return __builtin_bit_cast(unsigned, __builtin_convertvector(v, bf16x2c)); }
; #define LWRITE(S, buf) do { bf16_t* sA_ = sbase + (buf) * BUF; bf16_t* sB_ = sA_ + 256 * PITCH; \
;     _Pragma("unroll") for (int i_ = 0; i_ < 4; ++i_) *(u32x4*)(sA_ + (sr + i_ * 64) * PITCH + scv * 8) = ra[S][i_]; \
;     _Pragma("unroll") for (int i_ = 0; i_ < 2; ++i_) *(u32x4*)(sB_ + (sr + i_ * 64) * PITCH + scv * 8) = rb[S][i_]; } while (0)
; template <class Epi>
; DI void gemm_tile(char* smem, const bf16_t* __restrict__ A0, int lda0, int ksplit, const bf16_t* __restrict__ A1, int lda1,
;                   const bf16_t* __restrict__ Bt, int K, int row0, int col0, const Epi& epi, int tid) {
;     ...
;       COMPUTE(0);
;       __syncthreads();
;       LWRITE(0, 0);
;       __builtin_amdgcn_sched_barrier(0);
;       GLOAD(0, (kt + 4 < last ? kt + 4 : last));
;       __builtin_amdgcn_sched_barrier(0);
;       COMPUTE(1);
;       __syncthreads();
;     }
;   }
;     ...
; #pragma unroll
;   for (int m = 0; m < 8; ++m)
; #pragma unroll
;     for (int n = 0; n < 4; ++n) epi(row0 + wr * 128 + m * 16 + fr, col0 + wc * 64 + n * 16 + fq * 4, acc[m][n]);
; }
; DI void st_bf16x4(bf16_t* o, f32x4 v) { u32x2 q; q.x = pack2(v[0], v[1]); q.y = pack2(v[2], v[3]); *(u32x2*)o = q; }
;   DI void operator()(int row, int col, f32x4 v) const {
;     if (col < n0) st_bf16x4(o0 + (size_t)row * ld0 + col, v);
;     else { const int c = col - n0; if (c < n1) st_bf16x4(o1 + (size_t)row * ld1 + c, v); }
;   }
	ds_write_b128 v125, v[24:27]
	ds_write_b128 v125, v[28:31] offset:4096
	ds_write_b128 v125, v[32:35] offset:8192
	ds_write_b128 v125, v[36:39] offset:12288
	ds_write_b128 v125, v[40:43] offset:16384
	ds_write_b128 v125, v[44:47] offset:20480
	ds_read_b128 v[8:11], v126 offset:40960
	ds_read_b128 v[212:215], v126 offset:41984
	ds_read_b128 v[216:219], v126 offset:43008
	ds_read_b128 v[220:223], v126 offset:44032
	ds_read_b128 v[12:15], v127 offset:26624
	ds_read_b128 v[24:27], v127 offset:27648
	ds_read_b128 v[28:31], v127 offset:28672
	ds_read_b128 v[32:35], v127 offset:29696
	ds_read_b128 v[36:39], v127 offset:24576
	ds_read_b128 v[224:227], v127 offset:30720
	ds_read_b128 v[40:43], v127 offset:25600
	ds_read_b128 v[228:231], v128 offset:24576
	s_setprio 1
	s_waitcnt lgkmcnt(3)
	v_mfma_f32_16x16x32_bf16 v[232:235], v[8:11], v[36:39], v[72:75]
	v_mfma_f32_16x16x32_bf16 v[236:239], v[212:215], v[36:39], v[76:79]
	v_mfma_f32_16x16x32_bf16 v[240:243], v[216:219], v[36:39], v[80:83]
	v_mfma_f32_16x16x32_bf16 v[244:247], v[220:223], v[36:39], v[16:19]
	s_waitcnt lgkmcnt(1)
	v_mfma_f32_16x16x32_bf16 v[108:111], v[8:11], v[40:43], v[84:87]
	v_mfma_f32_16x16x32_bf16 v[104:107], v[212:215], v[40:43], v[88:91]
	v_mfma_f32_16x16x32_bf16 v[100:103], v[216:219], v[40:43], v[92:95]
	v_mfma_f32_16x16x32_bf16 v[96:99], v[220:223], v[40:43], v[20:23]
	v_mfma_f32_16x16x32_bf16 v[92:95], v[8:11], v[12:15], v[116:119]
	v_mfma_f32_16x16x32_bf16 v[88:91], v[212:215], v[12:15], v[130:133]
	v_mfma_f32_16x16x32_bf16 v[84:87], v[216:219], v[12:15], v[138:141]
	v_mfma_f32_16x16x32_bf16 v[80:83], v[220:223], v[12:15], v[48:51]
	v_mfma_f32_16x16x32_bf16 v[76:79], v[8:11], v[24:27], v[142:145]
	v_mfma_f32_16x16x32_bf16 v[72:75], v[212:215], v[24:27], v[146:149]
	v_mfma_f32_16x16x32_bf16 v[68:71], v[216:219], v[24:27], v[150:153]
	v_mfma_f32_16x16x32_bf16 v[64:67], v[220:223], v[24:27], v[52:55]
	v_mfma_f32_16x16x32_bf16 v[60:63], v[8:11], v[28:31], v[154:157]
	v_mfma_f32_16x16x32_bf16 v[56:59], v[212:215], v[28:31], v[158:161]
	v_mfma_f32_16x16x32_bf16 v[52:55], v[216:219], v[28:31], v[162:165]
	v_mfma_f32_16x16x32_bf16 v[48:51], v[220:223], v[28:31], v[166:169]
	v_mfma_f32_16x16x32_bf16 v[44:47], v[8:11], v[32:35], v[170:173]
	v_mfma_f32_16x16x32_bf16 v[40:43], v[212:215], v[32:35], v[174:177]
	v_mfma_f32_16x16x32_bf16 v[36:39], v[216:219], v[32:35], v[178:181]
	v_mfma_f32_16x16x32_bf16 v[32:35], v[220:223], v[32:35], v[182:185]
	v_mfma_f32_16x16x32_bf16 v[28:31], v[8:11], v[224:227], v[186:189]
	v_mfma_f32_16x16x32_bf16 v[24:27], v[212:215], v[224:227], v[190:193]
	v_mfma_f32_16x16x32_bf16 v[20:23], v[216:219], v[224:227], v[196:199]
	v_mfma_f32_16x16x32_bf16 v[16:19], v[220:223], v[224:227], v[200:203]
	s_waitcnt lgkmcnt(0)
	v_mfma_f32_16x16x32_bf16 v[12:15], v[8:11], v[228:231], v[0:3]
	v_mfma_f32_16x16x32_bf16 v[8:11], v[212:215], v[228:231], v[4:7]
	v_mfma_f32_16x16x32_bf16 v[4:7], v[216:219], v[228:231], v[204:207]
	v_mfma_f32_16x16x32_bf16 v[0:3], v[220:223], v[228:231], v[208:211]
	s_setprio 0
	v_add_u32_e32 v118, s19, v124
	v_ashrrev_i32_e32 v119, 31, v118
	v_lshl_add_u64 v[116:117], v[118:119], 2, s[58:59]
	s_barrier
	global_load_dwordx4 v[130:133], v[116:117], off
	v_add_u32_e32 v120, s18, v123
	v_ashrrev_i32_e32 v121, 31, v120
	v_lshlrev_b64 v[134:135], 10, v[120:121]
	v_lshlrev_b64 v[118:119], 1, v[118:119]
	v_lshl_add_u64 v[134:135], s[0:1], 0, v[134:135]
	v_lshl_add_u64 v[134:135], v[134:135], 0, v[118:119]
	s_add_i32 s17, s17, s12
	s_waitcnt vmcnt(0)
	v_add_f32_e32 v121, v232, v130
	v_add_f32_e32 v129, v233, v131
	v_add_f32_e32 v130, v234, v132
	v_add_f32_e32 v131, v235, v133
	v_mul_f32_e32 v121, 0xbfb8aa3b, v121
	v_mul_f32_e32 v129, 0xbfb8aa3b, v129
	v_mul_f32_e32 v130, 0xbfb8aa3b, v130
	v_mul_f32_e32 v131, 0xbfb8aa3b, v131
	v_exp_f32_e32 v121, v121
	v_exp_f32_e32 v129, v129
	v_exp_f32_e32 v130, v130
	v_exp_f32_e32 v131, v131
	v_add_f32_e32 v121, 1.0, v121
	v_add_f32_e32 v129, 1.0, v129
	v_add_f32_e32 v132, 1.0, v130
	v_add_f32_e32 v131, 1.0, v131
	v_rcp_f32_e32 v130, v121
	v_rcp_f32_e32 v132, v132
	v_rcp_f32_e32 v133, v131
	v_rcp_f32_e32 v131, v129
	v_pk_mul_f32 v[132:133], v[132:133], s[10:11] op_sel_hi:[1,0]
	v_pk_mul_f32 v[130:131], v[130:131], s[10:11] op_sel_hi:[1,0]
	s_nop 0
	v_cvt_pk_bf16_f32 v130, v130, v131
	v_cvt_pk_bf16_f32 v131, v132, v133
	global_store_dwordx2 v[134:135], v[130:131], off
	global_load_dwordx4 v[130:133], v[116:117], off offset:64
	s_waitcnt vmcnt(0)
	v_add_f32_e32 v121, v236, v130
	v_add_f32_e32 v129, v237, v131
	v_add_f32_e32 v130, v238, v132
	v_add_f32_e32 v131, v239, v133
	v_mul_f32_e32 v121, 0xbfb8aa3b, v121
	v_mul_f32_e32 v129, 0xbfb8aa3b, v129
	v_mul_f32_e32 v130, 0xbfb8aa3b, v130
	v_mul_f32_e32 v131, 0xbfb8aa3b, v131
	v_exp_f32_e32 v121, v121
	v_exp_f32_e32 v129, v129
	v_exp_f32_e32 v130, v130
	v_exp_f32_e32 v131, v131
	v_add_f32_e32 v121, 1.0, v121
	v_add_f32_e32 v129, 1.0, v129
	v_add_f32_e32 v132, 1.0, v130
	v_add_f32_e32 v131, 1.0, v131
	v_rcp_f32_e32 v130, v121
	v_rcp_f32_e32 v132, v132
	v_rcp_f32_e32 v133, v131
	v_rcp_f32_e32 v131, v129
	v_pk_mul_f32 v[132:133], v[132:133], s[10:11] op_sel_hi:[1,0]
	v_pk_mul_f32 v[130:131], v[130:131], s[10:11] op_sel_hi:[1,0]
	s_nop 0
	v_cvt_pk_bf16_f32 v130, v130, v131
	v_cvt_pk_bf16_f32 v131, v132, v133
	global_store_dwordx2 v[134:135], v[130:131], off offset:32
	global_load_dwordx4 v[130:133], v[116:117], off offset:128
	s_waitcnt vmcnt(0)
; template <class Epi>
; DI void gemm_tile(char* smem, const bf16_t* __restrict__ A0, int lda0, int ksplit, const bf16_t* __restrict__ A1, int lda1,
;                   const bf16_t* __restrict__ Bt, int K, int row0, int col0, const Epi& epi, int tid) {
;     ...
;   for (int m = 0; m < 8; ++m)
; #pragma unroll
;     for (int n = 0; n < 4; ++n) epi(row0 + wr * 128 + m * 16 + fr, col0 + wc * 64 + n * 16 + fq * 4, acc[m][n]);
	v_add_f32_e32 v121, v240, v130
	v_add_f32_e32 v129, v241, v131
	v_add_f32_e32 v130, v242, v132
	v_add_f32_e32 v131, v243, v133
	v_mul_f32_e32 v121, 0xbfb8aa3b, v121
	v_mul_f32_e32 v129, 0xbfb8aa3b, v129
	v_mul_f32_e32 v130, 0xbfb8aa3b, v130
	v_mul_f32_e32 v131, 0xbfb8aa3b, v131
	v_exp_f32_e32 v121, v121
	v_exp_f32_e32 v129, v129
	v_exp_f32_e32 v130, v130
	v_exp_f32_e32 v131, v131
	v_add_f32_e32 v121, 1.0, v121
	v_add_f32_e32 v129, 1.0, v129
	v_add_f32_e32 v132, 1.0, v130
	v_add_f32_e32 v131, 1.0, v131
	v_rcp_f32_e32 v130, v121
	v_rcp_f32_e32 v132, v132
	v_rcp_f32_e32 v133, v131
	v_rcp_f32_e32 v131, v129
	v_pk_mul_f32 v[132:133], v[132:133], s[10:11] op_sel_hi:[1,0]
	v_pk_mul_f32 v[130:131], v[130:131], s[10:11] op_sel_hi:[1,0]
	s_nop 0
	v_cvt_pk_bf16_f32 v130, v130, v131
	v_cvt_pk_bf16_f32 v131, v132, v133
	global_store_dwordx2 v[134:135], v[130:131], off offset:64
	global_load_dwordx4 v[130:133], v[116:117], off offset:192
	s_waitcnt vmcnt(0)
	v_add_f32_e32 v121, v244, v130
	v_add_f32_e32 v129, v245, v131
	v_add_f32_e32 v130, v246, v132
	v_add_f32_e32 v131, v247, v133
	v_mul_f32_e32 v121, 0xbfb8aa3b, v121
	v_mul_f32_e32 v129, 0xbfb8aa3b, v129
	v_mul_f32_e32 v130, 0xbfb8aa3b, v130
	v_mul_f32_e32 v131, 0xbfb8aa3b, v131
	v_exp_f32_e32 v121, v121
	v_exp_f32_e32 v129, v129
	v_exp_f32_e32 v130, v130
	v_exp_f32_e32 v131, v131
	v_add_f32_e32 v121, 1.0, v121
	v_add_f32_e32 v129, 1.0, v129
	v_add_f32_e32 v132, 1.0, v130
	v_add_f32_e32 v131, 1.0, v131
	v_rcp_f32_e32 v130, v121
	v_rcp_f32_e32 v132, v132
	v_rcp_f32_e32 v133, v131
	v_rcp_f32_e32 v131, v129
	v_pk_mul_f32 v[132:133], v[132:133], s[10:11] op_sel_hi:[1,0]
	v_pk_mul_f32 v[130:131], v[130:131], s[10:11] op_sel_hi:[1,0]
	s_nop 0
	v_cvt_pk_bf16_f32 v130, v130, v131
	v_cvt_pk_bf16_f32 v131, v132, v133
	global_store_dwordx2 v[134:135], v[130:131], off offset:96
	global_load_dwordx4 v[130:133], v[116:117], off
	v_or_b32_e32 v134, 16, v120
	v_ashrrev_i32_e32 v135, 31, v134
	v_lshlrev_b64 v[134:135], 10, v[134:135]
	s_waitcnt vmcnt(0)
	v_add_f32_e32 v108, v108, v130
	v_add_f32_e32 v109, v109, v131
	v_add_f32_e32 v110, v110, v132
	v_add_f32_e32 v111, v111, v133
	v_mul_f32_e32 v108, 0xbfb8aa3b, v108
	v_mul_f32_e32 v109, 0xbfb8aa3b, v109
	v_mul_f32_e32 v110, 0xbfb8aa3b, v110
	v_mul_f32_e32 v111, 0xbfb8aa3b, v111
	v_exp_f32_e32 v108, v108
	v_exp_f32_e32 v109, v109
	v_exp_f32_e32 v110, v110
	v_exp_f32_e32 v111, v111
	v_add_f32_e32 v108, 1.0, v108
	v_add_f32_e32 v109, 1.0, v109
	v_add_f32_e32 v110, 1.0, v110
	v_add_f32_e32 v111, 1.0, v111
	v_rcp_f32_e32 v108, v108
	v_rcp_f32_e32 v110, v110
	v_rcp_f32_e32 v111, v111
	v_rcp_f32_e32 v109, v109
	v_lshl_add_u64 v[130:131], s[0:1], 0, v[134:135]
	v_lshl_add_u64 v[130:131], v[130:131], 0, v[118:119]
	v_pk_mul_f32 v[110:111], v[110:111], s[10:11] op_sel_hi:[1,0]
	v_pk_mul_f32 v[108:109], v[108:109], s[10:11] op_sel_hi:[1,0]
	s_nop 0
	v_cvt_pk_bf16_f32 v108, v108, v109
	v_cvt_pk_bf16_f32 v109, v110, v111
	global_store_dwordx2 v[130:131], v[108:109], off
	global_load_dwordx4 v[108:111], v[116:117], off offset:64
	s_waitcnt vmcnt(0)
	v_add_f32_e32 v104, v104, v108
	v_add_f32_e32 v105, v105, v109
	v_add_f32_e32 v106, v106, v110
	v_add_f32_e32 v107, v107, v111
	v_mul_f32_e32 v104, 0xbfb8aa3b, v104
	v_mul_f32_e32 v105, 0xbfb8aa3b, v105
	v_mul_f32_e32 v106, 0xbfb8aa3b, v106
	v_mul_f32_e32 v107, 0xbfb8aa3b, v107
	v_exp_f32_e32 v104, v104
	v_exp_f32_e32 v105, v105
	v_exp_f32_e32 v106, v106
	v_exp_f32_e32 v107, v107
	v_add_f32_e32 v104, 1.0, v104
	v_add_f32_e32 v105, 1.0, v105
	v_add_f32_e32 v106, 1.0, v106
	v_add_f32_e32 v107, 1.0, v107
	v_rcp_f32_e32 v104, v104
	v_rcp_f32_e32 v106, v106
	v_rcp_f32_e32 v107, v107
	v_rcp_f32_e32 v105, v105
	v_pk_mul_f32 v[106:107], v[106:107], s[10:11] op_sel_hi:[1,0]
	v_pk_mul_f32 v[104:105], v[104:105], s[10:11] op_sel_hi:[1,0]
	s_nop 0
	v_cvt_pk_bf16_f32 v104, v104, v105
	v_cvt_pk_bf16_f32 v105, v106, v107
	global_store_dwordx2 v[130:131], v[104:105], off offset:32
	global_load_dwordx4 v[104:107], v[116:117], off offset:128
	s_waitcnt vmcnt(0)
	v_add_f32_e32 v100, v100, v104
	v_add_f32_e32 v101, v101, v105
	v_add_f32_e32 v102, v102, v106
	v_add_f32_e32 v103, v103, v107
	v_mul_f32_e32 v100, 0xbfb8aa3b, v100
	v_mul_f32_e32 v101, 0xbfb8aa3b, v101
	v_mul_f32_e32 v102, 0xbfb8aa3b, v102
	v_mul_f32_e32 v103, 0xbfb8aa3b, v103
	v_exp_f32_e32 v100, v100
	v_exp_f32_e32 v101, v101
	v_exp_f32_e32 v102, v102
	v_exp_f32_e32 v103, v103
	v_add_f32_e32 v100, 1.0, v100
	v_add_f32_e32 v101, 1.0, v101
	v_add_f32_e32 v102, 1.0, v102
	v_add_f32_e32 v103, 1.0, v103
	v_rcp_f32_e32 v100, v100
	v_rcp_f32_e32 v102, v102
	v_rcp_f32_e32 v103, v103
	v_rcp_f32_e32 v101, v101
	v_pk_mul_f32 v[102:103], v[102:103], s[10:11] op_sel_hi:[1,0]
	v_pk_mul_f32 v[100:101], v[100:101], s[10:11] op_sel_hi:[1,0]
	s_nop 0
	v_cvt_pk_bf16_f32 v100, v100, v101
	v_cvt_pk_bf16_f32 v101, v102, v103
	global_store_dwordx2 v[130:131], v[100:101], off offset:64
	global_load_dwordx4 v[100:103], v[116:117], off offset:192
	s_waitcnt vmcnt(0)
	v_add_f32_e32 v96, v96, v100
	v_add_f32_e32 v97, v97, v101
	v_add_f32_e32 v98, v98, v102
	v_add_f32_e32 v99, v99, v103
	v_mul_f32_e32 v96, 0xbfb8aa3b, v96
	v_mul_f32_e32 v97, 0xbfb8aa3b, v97
	v_mul_f32_e32 v98, 0xbfb8aa3b, v98
	v_mul_f32_e32 v99, 0xbfb8aa3b, v99
	v_exp_f32_e32 v96, v96
	v_exp_f32_e32 v97, v97
	v_exp_f32_e32 v98, v98
	v_exp_f32_e32 v99, v99
	v_add_f32_e32 v96, 1.0, v96
	v_add_f32_e32 v97, 1.0, v97
	v_add_f32_e32 v98, 1.0, v98
	v_add_f32_e32 v99, 1.0, v99
	v_rcp_f32_e32 v96, v96
	v_rcp_f32_e32 v98, v98
	v_rcp_f32_e32 v99, v99
	v_rcp_f32_e32 v97, v97
	v_or_b32_e32 v100, 32, v120
	v_ashrrev_i32_e32 v101, 31, v100
	v_pk_mul_f32 v[98:99], v[98:99], s[10:11] op_sel_hi:[1,0]
	v_pk_mul_f32 v[96:97], v[96:97], s[10:11] op_sel_hi:[1,0]
	v_lshlrev_b64 v[100:101], 10, v[100:101]
	v_cvt_pk_bf16_f32 v96, v96, v97
	v_cvt_pk_bf16_f32 v97, v98, v99
	global_store_dwordx2 v[130:131], v[96:97], off offset:96
	global_load_dwordx4 v[96:99], v[116:117], off
	s_waitcnt vmcnt(0)
; template <class Epi>
; DI void gemm_tile(char* smem, const bf16_t* __restrict__ A0, int lda0, int ksplit, const bf16_t* __restrict__ A1, int lda1,
;                   const bf16_t* __restrict__ Bt, int K, int row0, int col0, const Epi& epi, int tid) {
;     ...
;   for (int m = 0; m < 8; ++m)
; #pragma unroll
;     for (int n = 0; n < 4; ++n) epi(row0 + wr * 128 + m * 16 + fr, col0 + wc * 64 + n * 16 + fq * 4, acc[m][n]);
	v_add_f32_e32 v92, v92, v96
	v_add_f32_e32 v93, v93, v97
	v_add_f32_e32 v94, v94, v98
	v_add_f32_e32 v95, v95, v99
	v_mul_f32_e32 v92, 0xbfb8aa3b, v92
	v_mul_f32_e32 v93, 0xbfb8aa3b, v93
	v_mul_f32_e32 v94, 0xbfb8aa3b, v94
	v_mul_f32_e32 v95, 0xbfb8aa3b, v95
	v_exp_f32_e32 v92, v92
	v_exp_f32_e32 v93, v93
	v_exp_f32_e32 v94, v94
	v_exp_f32_e32 v95, v95
	v_add_f32_e32 v92, 1.0, v92
	v_add_f32_e32 v93, 1.0, v93
	v_add_f32_e32 v94, 1.0, v94
	v_add_f32_e32 v95, 1.0, v95
	v_rcp_f32_e32 v92, v92
	v_rcp_f32_e32 v94, v94
	v_rcp_f32_e32 v95, v95
	v_rcp_f32_e32 v93, v93
	v_lshl_add_u64 v[96:97], s[0:1], 0, v[100:101]
	v_lshl_add_u64 v[96:97], v[96:97], 0, v[118:119]
	v_pk_mul_f32 v[94:95], v[94:95], s[10:11] op_sel_hi:[1,0]
	v_pk_mul_f32 v[92:93], v[92:93], s[10:11] op_sel_hi:[1,0]
	s_nop 0
	v_cvt_pk_bf16_f32 v92, v92, v93
	v_cvt_pk_bf16_f32 v93, v94, v95
	global_store_dwordx2 v[96:97], v[92:93], off
	global_load_dwordx4 v[92:95], v[116:117], off offset:64
	s_waitcnt vmcnt(0)
	v_add_f32_e32 v88, v88, v92
	v_add_f32_e32 v89, v89, v93
	v_add_f32_e32 v90, v90, v94
	v_add_f32_e32 v91, v91, v95
	v_mul_f32_e32 v88, 0xbfb8aa3b, v88
	v_mul_f32_e32 v89, 0xbfb8aa3b, v89
	v_mul_f32_e32 v90, 0xbfb8aa3b, v90
	v_mul_f32_e32 v91, 0xbfb8aa3b, v91
	v_exp_f32_e32 v88, v88
	v_exp_f32_e32 v89, v89
	v_exp_f32_e32 v90, v90
	v_exp_f32_e32 v91, v91
	v_add_f32_e32 v88, 1.0, v88
	v_add_f32_e32 v89, 1.0, v89
	v_add_f32_e32 v90, 1.0, v90
	v_add_f32_e32 v91, 1.0, v91
	v_rcp_f32_e32 v88, v88
	v_rcp_f32_e32 v90, v90
	v_rcp_f32_e32 v91, v91
	v_rcp_f32_e32 v89, v89
	v_pk_mul_f32 v[90:91], v[90:91], s[10:11] op_sel_hi:[1,0]
	v_pk_mul_f32 v[88:89], v[88:89], s[10:11] op_sel_hi:[1,0]
	s_nop 0
	v_cvt_pk_bf16_f32 v88, v88, v89
	v_cvt_pk_bf16_f32 v89, v90, v91
	global_store_dwordx2 v[96:97], v[88:89], off offset:32
	global_load_dwordx4 v[88:91], v[116:117], off offset:128
	s_waitcnt vmcnt(0)
	v_add_f32_e32 v84, v84, v88
	v_add_f32_e32 v85, v85, v89
	v_add_f32_e32 v86, v86, v90
	v_add_f32_e32 v87, v87, v91
	v_mul_f32_e32 v84, 0xbfb8aa3b, v84
	v_mul_f32_e32 v85, 0xbfb8aa3b, v85
	v_mul_f32_e32 v86, 0xbfb8aa3b, v86
	v_mul_f32_e32 v87, 0xbfb8aa3b, v87
	v_exp_f32_e32 v84, v84
	v_exp_f32_e32 v85, v85
	v_exp_f32_e32 v86, v86
	v_exp_f32_e32 v87, v87
	v_add_f32_e32 v84, 1.0, v84
	v_add_f32_e32 v85, 1.0, v85
	v_add_f32_e32 v86, 1.0, v86
	v_add_f32_e32 v87, 1.0, v87
	v_rcp_f32_e32 v84, v84
	v_rcp_f32_e32 v86, v86
	v_rcp_f32_e32 v87, v87
	v_rcp_f32_e32 v85, v85
	v_pk_mul_f32 v[86:87], v[86:87], s[10:11] op_sel_hi:[1,0]
	v_pk_mul_f32 v[84:85], v[84:85], s[10:11] op_sel_hi:[1,0]
	s_nop 0
	v_cvt_pk_bf16_f32 v84, v84, v85
	v_cvt_pk_bf16_f32 v85, v86, v87
	global_store_dwordx2 v[96:97], v[84:85], off offset:64
	global_load_dwordx4 v[84:87], v[116:117], off offset:192
	s_waitcnt vmcnt(0)
	v_add_f32_e32 v80, v80, v84
	v_add_f32_e32 v81, v81, v85
	v_add_f32_e32 v82, v82, v86
	v_add_f32_e32 v83, v83, v87
	v_mul_f32_e32 v80, 0xbfb8aa3b, v80
	v_mul_f32_e32 v81, 0xbfb8aa3b, v81
	v_mul_f32_e32 v82, 0xbfb8aa3b, v82
	v_mul_f32_e32 v83, 0xbfb8aa3b, v83
	v_exp_f32_e32 v80, v80
	v_exp_f32_e32 v81, v81
	v_exp_f32_e32 v82, v82
	v_exp_f32_e32 v83, v83
	v_add_f32_e32 v80, 1.0, v80
	v_add_f32_e32 v81, 1.0, v81
	v_add_f32_e32 v82, 1.0, v82
	v_add_f32_e32 v83, 1.0, v83
	v_rcp_f32_e32 v80, v80
	v_rcp_f32_e32 v82, v82
	v_rcp_f32_e32 v83, v83
	v_rcp_f32_e32 v81, v81
	v_or_b32_e32 v84, 48, v120
	v_ashrrev_i32_e32 v85, 31, v84
	v_pk_mul_f32 v[82:83], v[82:83], s[10:11] op_sel_hi:[1,0]
	v_pk_mul_f32 v[80:81], v[80:81], s[10:11] op_sel_hi:[1,0]
	v_lshlrev_b64 v[84:85], 10, v[84:85]
	v_cvt_pk_bf16_f32 v80, v80, v81
	v_cvt_pk_bf16_f32 v81, v82, v83
	global_store_dwordx2 v[96:97], v[80:81], off offset:96
	global_load_dwordx4 v[80:83], v[116:117], off
	s_waitcnt vmcnt(0)
	v_add_f32_e32 v76, v76, v80
	v_add_f32_e32 v77, v77, v81
	v_add_f32_e32 v78, v78, v82
	v_add_f32_e32 v79, v79, v83
	v_mul_f32_e32 v76, 0xbfb8aa3b, v76
	v_mul_f32_e32 v77, 0xbfb8aa3b, v77
	v_mul_f32_e32 v78, 0xbfb8aa3b, v78
	v_mul_f32_e32 v79, 0xbfb8aa3b, v79
	v_exp_f32_e32 v76, v76
	v_exp_f32_e32 v77, v77
	v_exp_f32_e32 v78, v78
	v_exp_f32_e32 v79, v79
	v_add_f32_e32 v76, 1.0, v76
	v_add_f32_e32 v77, 1.0, v77
	v_add_f32_e32 v78, 1.0, v78
	v_add_f32_e32 v79, 1.0, v79
	v_rcp_f32_e32 v76, v76
	v_rcp_f32_e32 v78, v78
	v_rcp_f32_e32 v79, v79
	v_rcp_f32_e32 v77, v77
	v_lshl_add_u64 v[80:81], s[0:1], 0, v[84:85]
	v_lshl_add_u64 v[80:81], v[80:81], 0, v[118:119]
	v_pk_mul_f32 v[78:79], v[78:79], s[10:11] op_sel_hi:[1,0]
	v_pk_mul_f32 v[76:77], v[76:77], s[10:11] op_sel_hi:[1,0]
	s_nop 0
	v_cvt_pk_bf16_f32 v76, v76, v77
	v_cvt_pk_bf16_f32 v77, v78, v79
	global_store_dwordx2 v[80:81], v[76:77], off
	global_load_dwordx4 v[76:79], v[116:117], off offset:64
	s_waitcnt vmcnt(0)
	v_add_f32_e32 v72, v72, v76
	v_add_f32_e32 v73, v73, v77
	v_add_f32_e32 v74, v74, v78
	v_add_f32_e32 v75, v75, v79
	v_mul_f32_e32 v72, 0xbfb8aa3b, v72
	v_mul_f32_e32 v73, 0xbfb8aa3b, v73
	v_mul_f32_e32 v74, 0xbfb8aa3b, v74
	v_mul_f32_e32 v75, 0xbfb8aa3b, v75
	v_exp_f32_e32 v72, v72
	v_exp_f32_e32 v73, v73
	v_exp_f32_e32 v74, v74
	v_exp_f32_e32 v75, v75
	v_add_f32_e32 v72, 1.0, v72
	v_add_f32_e32 v73, 1.0, v73
	v_add_f32_e32 v74, 1.0, v74
	v_add_f32_e32 v75, 1.0, v75
	v_rcp_f32_e32 v72, v72
	v_rcp_f32_e32 v74, v74
	v_rcp_f32_e32 v75, v75
	v_rcp_f32_e32 v73, v73
	v_pk_mul_f32 v[74:75], v[74:75], s[10:11] op_sel_hi:[1,0]
	v_pk_mul_f32 v[72:73], v[72:73], s[10:11] op_sel_hi:[1,0]
	s_nop 0
	v_cvt_pk_bf16_f32 v72, v72, v73
	v_cvt_pk_bf16_f32 v73, v74, v75
	global_store_dwordx2 v[80:81], v[72:73], off offset:32
	global_load_dwordx4 v[72:75], v[116:117], off offset:128
	s_waitcnt vmcnt(0)
; template <class Epi>
; DI void gemm_tile(char* smem, const bf16_t* __restrict__ A0, int lda0, int ksplit, const bf16_t* __restrict__ A1, int lda1,
;                   const bf16_t* __restrict__ Bt, int K, int row0, int col0, const Epi& epi, int tid) {
;     ...
;   for (int m = 0; m < 8; ++m)
; #pragma unroll
;     for (int n = 0; n < 4; ++n) epi(row0 + wr * 128 + m * 16 + fr, col0 + wc * 64 + n * 16 + fq * 4, acc[m][n]);
	v_add_f32_e32 v68, v68, v72
	v_add_f32_e32 v69, v69, v73
	v_add_f32_e32 v70, v70, v74
	v_add_f32_e32 v71, v71, v75
	v_mul_f32_e32 v68, 0xbfb8aa3b, v68
	v_mul_f32_e32 v69, 0xbfb8aa3b, v69
	v_mul_f32_e32 v70, 0xbfb8aa3b, v70
	v_mul_f32_e32 v71, 0xbfb8aa3b, v71
	v_exp_f32_e32 v68, v68
	v_exp_f32_e32 v69, v69
	v_exp_f32_e32 v70, v70
	v_exp_f32_e32 v71, v71
	v_add_f32_e32 v68, 1.0, v68
	v_add_f32_e32 v69, 1.0, v69
	v_add_f32_e32 v70, 1.0, v70
	v_add_f32_e32 v71, 1.0, v71
	v_rcp_f32_e32 v68, v68
	v_rcp_f32_e32 v70, v70
	v_rcp_f32_e32 v71, v71
	v_rcp_f32_e32 v69, v69
	v_pk_mul_f32 v[70:71], v[70:71], s[10:11] op_sel_hi:[1,0]
	v_pk_mul_f32 v[68:69], v[68:69], s[10:11] op_sel_hi:[1,0]
	s_nop 0
	v_cvt_pk_bf16_f32 v68, v68, v69
	v_cvt_pk_bf16_f32 v69, v70, v71
	global_store_dwordx2 v[80:81], v[68:69], off offset:64
	global_load_dwordx4 v[68:71], v[116:117], off offset:192
	s_waitcnt vmcnt(0)
	v_add_f32_e32 v64, v64, v68
	v_add_f32_e32 v65, v65, v69
	v_add_f32_e32 v66, v66, v70
	v_add_f32_e32 v67, v67, v71
	v_mul_f32_e32 v64, 0xbfb8aa3b, v64
	v_mul_f32_e32 v65, 0xbfb8aa3b, v65
	v_mul_f32_e32 v66, 0xbfb8aa3b, v66
	v_mul_f32_e32 v67, 0xbfb8aa3b, v67
	v_exp_f32_e32 v64, v64
	v_exp_f32_e32 v65, v65
	v_exp_f32_e32 v66, v66
	v_exp_f32_e32 v67, v67
	v_add_f32_e32 v64, 1.0, v64
	v_add_f32_e32 v65, 1.0, v65
	v_add_f32_e32 v66, 1.0, v66
	v_add_f32_e32 v67, 1.0, v67
	v_rcp_f32_e32 v64, v64
	v_rcp_f32_e32 v66, v66
	v_rcp_f32_e32 v67, v67
	v_rcp_f32_e32 v65, v65
	v_or_b32_e32 v68, 64, v120
	v_ashrrev_i32_e32 v69, 31, v68
	v_pk_mul_f32 v[66:67], v[66:67], s[10:11] op_sel_hi:[1,0]
	v_pk_mul_f32 v[64:65], v[64:65], s[10:11] op_sel_hi:[1,0]
	v_lshlrev_b64 v[68:69], 10, v[68:69]
	v_cvt_pk_bf16_f32 v64, v64, v65
	v_cvt_pk_bf16_f32 v65, v66, v67
	global_store_dwordx2 v[80:81], v[64:65], off offset:96
	global_load_dwordx4 v[64:67], v[116:117], off
	s_waitcnt vmcnt(0)
	v_add_f32_e32 v60, v60, v64
	v_add_f32_e32 v61, v61, v65
	v_add_f32_e32 v62, v62, v66
	v_add_f32_e32 v63, v63, v67
	v_mul_f32_e32 v60, 0xbfb8aa3b, v60
	v_mul_f32_e32 v61, 0xbfb8aa3b, v61
	v_mul_f32_e32 v62, 0xbfb8aa3b, v62
	v_mul_f32_e32 v63, 0xbfb8aa3b, v63
	v_exp_f32_e32 v60, v60
	v_exp_f32_e32 v61, v61
	v_exp_f32_e32 v62, v62
	v_exp_f32_e32 v63, v63
	v_add_f32_e32 v60, 1.0, v60
	v_add_f32_e32 v61, 1.0, v61
	v_add_f32_e32 v62, 1.0, v62
	v_add_f32_e32 v63, 1.0, v63
	v_rcp_f32_e32 v60, v60
	v_rcp_f32_e32 v62, v62
	v_rcp_f32_e32 v63, v63
	v_rcp_f32_e32 v61, v61
	v_lshl_add_u64 v[64:65], s[0:1], 0, v[68:69]
	v_lshl_add_u64 v[64:65], v[64:65], 0, v[118:119]
	v_pk_mul_f32 v[62:63], v[62:63], s[10:11] op_sel_hi:[1,0]
	v_pk_mul_f32 v[60:61], v[60:61], s[10:11] op_sel_hi:[1,0]
	s_nop 0
	v_cvt_pk_bf16_f32 v60, v60, v61
	v_cvt_pk_bf16_f32 v61, v62, v63
	global_store_dwordx2 v[64:65], v[60:61], off
	global_load_dwordx4 v[60:63], v[116:117], off offset:64
	s_waitcnt vmcnt(0)
	v_add_f32_e32 v56, v56, v60
	v_add_f32_e32 v57, v57, v61
	v_add_f32_e32 v58, v58, v62
	v_add_f32_e32 v59, v59, v63
	v_mul_f32_e32 v56, 0xbfb8aa3b, v56
	v_mul_f32_e32 v57, 0xbfb8aa3b, v57
	v_mul_f32_e32 v58, 0xbfb8aa3b, v58
	v_mul_f32_e32 v59, 0xbfb8aa3b, v59
	v_exp_f32_e32 v56, v56
	v_exp_f32_e32 v57, v57
	v_exp_f32_e32 v58, v58
	v_exp_f32_e32 v59, v59
	v_add_f32_e32 v56, 1.0, v56
	v_add_f32_e32 v57, 1.0, v57
	v_add_f32_e32 v58, 1.0, v58
	v_add_f32_e32 v59, 1.0, v59
	v_rcp_f32_e32 v56, v56
	v_rcp_f32_e32 v58, v58
	v_rcp_f32_e32 v59, v59
	v_rcp_f32_e32 v57, v57
	v_pk_mul_f32 v[58:59], v[58:59], s[10:11] op_sel_hi:[1,0]
	v_pk_mul_f32 v[56:57], v[56:57], s[10:11] op_sel_hi:[1,0]
	s_nop 0
	v_cvt_pk_bf16_f32 v56, v56, v57
	v_cvt_pk_bf16_f32 v57, v58, v59
	global_store_dwordx2 v[64:65], v[56:57], off offset:32
	global_load_dwordx4 v[56:59], v[116:117], off offset:128
	s_waitcnt vmcnt(0)
	v_add_f32_e32 v52, v52, v56
	v_add_f32_e32 v53, v53, v57
	v_add_f32_e32 v54, v54, v58
	v_add_f32_e32 v55, v55, v59
	v_mul_f32_e32 v52, 0xbfb8aa3b, v52
	v_mul_f32_e32 v53, 0xbfb8aa3b, v53
	v_mul_f32_e32 v54, 0xbfb8aa3b, v54
	v_mul_f32_e32 v55, 0xbfb8aa3b, v55
	v_exp_f32_e32 v52, v52
	v_exp_f32_e32 v53, v53
	v_exp_f32_e32 v54, v54
	v_exp_f32_e32 v55, v55
	v_add_f32_e32 v52, 1.0, v52
	v_add_f32_e32 v53, 1.0, v53
	v_add_f32_e32 v54, 1.0, v54
	v_add_f32_e32 v55, 1.0, v55
	v_rcp_f32_e32 v52, v52
	v_rcp_f32_e32 v54, v54
	v_rcp_f32_e32 v55, v55
	v_rcp_f32_e32 v53, v53
	v_pk_mul_f32 v[54:55], v[54:55], s[10:11] op_sel_hi:[1,0]
	v_pk_mul_f32 v[52:53], v[52:53], s[10:11] op_sel_hi:[1,0]
	s_nop 0
	v_cvt_pk_bf16_f32 v52, v52, v53
	v_cvt_pk_bf16_f32 v53, v54, v55
	global_store_dwordx2 v[64:65], v[52:53], off offset:64
	global_load_dwordx4 v[52:55], v[116:117], off offset:192
	s_waitcnt vmcnt(0)
	v_add_f32_e32 v48, v48, v52
	v_add_f32_e32 v49, v49, v53
	v_add_f32_e32 v50, v50, v54
	v_add_f32_e32 v51, v51, v55
	v_mul_f32_e32 v48, 0xbfb8aa3b, v48
	v_mul_f32_e32 v49, 0xbfb8aa3b, v49
	v_mul_f32_e32 v50, 0xbfb8aa3b, v50
	v_mul_f32_e32 v51, 0xbfb8aa3b, v51
	v_exp_f32_e32 v48, v48
	v_exp_f32_e32 v49, v49
	v_exp_f32_e32 v50, v50
	v_exp_f32_e32 v51, v51
	v_add_f32_e32 v48, 1.0, v48
	v_add_f32_e32 v49, 1.0, v49
	v_add_f32_e32 v50, 1.0, v50
	v_add_f32_e32 v51, 1.0, v51
	v_rcp_f32_e32 v48, v48
	v_rcp_f32_e32 v50, v50
	v_rcp_f32_e32 v51, v51
	v_rcp_f32_e32 v49, v49
	v_or_b32_e32 v52, 0x50, v120
	v_ashrrev_i32_e32 v53, 31, v52
	v_pk_mul_f32 v[50:51], v[50:51], s[10:11] op_sel_hi:[1,0]
	v_pk_mul_f32 v[48:49], v[48:49], s[10:11] op_sel_hi:[1,0]
	v_lshlrev_b64 v[52:53], 10, v[52:53]
	v_cvt_pk_bf16_f32 v48, v48, v49
	v_cvt_pk_bf16_f32 v49, v50, v51
	global_store_dwordx2 v[64:65], v[48:49], off offset:96
	global_load_dwordx4 v[48:51], v[116:117], off
	s_waitcnt vmcnt(0)
; template <class Epi>
; DI void gemm_tile(char* smem, const bf16_t* __restrict__ A0, int lda0, int ksplit, const bf16_t* __restrict__ A1, int lda1,
;                   const bf16_t* __restrict__ Bt, int K, int row0, int col0, const Epi& epi, int tid) {
;     ...
;   for (int m = 0; m < 8; ++m)
; #pragma unroll
;     for (int n = 0; n < 4; ++n) epi(row0 + wr * 128 + m * 16 + fr, col0 + wc * 64 + n * 16 + fq * 4, acc[m][n]);
	v_add_f32_e32 v44, v44, v48
	v_add_f32_e32 v45, v45, v49
	v_add_f32_e32 v46, v46, v50
	v_add_f32_e32 v47, v47, v51
	v_mul_f32_e32 v44, 0xbfb8aa3b, v44
	v_mul_f32_e32 v45, 0xbfb8aa3b, v45
	v_mul_f32_e32 v46, 0xbfb8aa3b, v46
	v_mul_f32_e32 v47, 0xbfb8aa3b, v47
	v_exp_f32_e32 v44, v44
	v_exp_f32_e32 v45, v45
	v_exp_f32_e32 v46, v46
	v_exp_f32_e32 v47, v47
	v_add_f32_e32 v44, 1.0, v44
	v_add_f32_e32 v45, 1.0, v45
	v_add_f32_e32 v46, 1.0, v46
	v_add_f32_e32 v47, 1.0, v47
	v_rcp_f32_e32 v44, v44
	v_rcp_f32_e32 v46, v46
	v_rcp_f32_e32 v47, v47
	v_rcp_f32_e32 v45, v45
	v_lshl_add_u64 v[48:49], s[0:1], 0, v[52:53]
	v_lshl_add_u64 v[48:49], v[48:49], 0, v[118:119]
	v_pk_mul_f32 v[46:47], v[46:47], s[10:11] op_sel_hi:[1,0]
	v_pk_mul_f32 v[44:45], v[44:45], s[10:11] op_sel_hi:[1,0]
	s_nop 0
	v_cvt_pk_bf16_f32 v44, v44, v45
	v_cvt_pk_bf16_f32 v45, v46, v47
	global_store_dwordx2 v[48:49], v[44:45], off
	global_load_dwordx4 v[44:47], v[116:117], off offset:64
	s_waitcnt vmcnt(0)
	v_add_f32_e32 v40, v40, v44
	v_add_f32_e32 v41, v41, v45
	v_add_f32_e32 v42, v42, v46
	v_add_f32_e32 v43, v43, v47
	v_mul_f32_e32 v40, 0xbfb8aa3b, v40
	v_mul_f32_e32 v41, 0xbfb8aa3b, v41
	v_mul_f32_e32 v42, 0xbfb8aa3b, v42
	v_mul_f32_e32 v43, 0xbfb8aa3b, v43
	v_exp_f32_e32 v40, v40
	v_exp_f32_e32 v41, v41
	v_exp_f32_e32 v42, v42
	v_exp_f32_e32 v43, v43
	v_add_f32_e32 v40, 1.0, v40
	v_add_f32_e32 v41, 1.0, v41
	v_add_f32_e32 v42, 1.0, v42
	v_add_f32_e32 v43, 1.0, v43
	v_rcp_f32_e32 v40, v40
	v_rcp_f32_e32 v42, v42
	v_rcp_f32_e32 v43, v43
	v_rcp_f32_e32 v41, v41
	v_pk_mul_f32 v[42:43], v[42:43], s[10:11] op_sel_hi:[1,0]
	v_pk_mul_f32 v[40:41], v[40:41], s[10:11] op_sel_hi:[1,0]
	s_nop 0
	v_cvt_pk_bf16_f32 v40, v40, v41
	v_cvt_pk_bf16_f32 v41, v42, v43
	global_store_dwordx2 v[48:49], v[40:41], off offset:32
	global_load_dwordx4 v[40:43], v[116:117], off offset:128
	s_waitcnt vmcnt(0)
	v_add_f32_e32 v36, v36, v40
	v_add_f32_e32 v37, v37, v41
	v_add_f32_e32 v38, v38, v42
	v_add_f32_e32 v39, v39, v43
	v_mul_f32_e32 v36, 0xbfb8aa3b, v36
	v_mul_f32_e32 v37, 0xbfb8aa3b, v37
	v_mul_f32_e32 v38, 0xbfb8aa3b, v38
	v_mul_f32_e32 v39, 0xbfb8aa3b, v39
	v_exp_f32_e32 v36, v36
	v_exp_f32_e32 v37, v37
	v_exp_f32_e32 v38, v38
	v_exp_f32_e32 v39, v39
	v_add_f32_e32 v36, 1.0, v36
	v_add_f32_e32 v37, 1.0, v37
	v_add_f32_e32 v38, 1.0, v38
	v_add_f32_e32 v39, 1.0, v39
	v_rcp_f32_e32 v36, v36
	v_rcp_f32_e32 v38, v38
	v_rcp_f32_e32 v39, v39
	v_rcp_f32_e32 v37, v37
	v_pk_mul_f32 v[38:39], v[38:39], s[10:11] op_sel_hi:[1,0]
	v_pk_mul_f32 v[36:37], v[36:37], s[10:11] op_sel_hi:[1,0]
	s_nop 0
	v_cvt_pk_bf16_f32 v36, v36, v37
	v_cvt_pk_bf16_f32 v37, v38, v39
	global_store_dwordx2 v[48:49], v[36:37], off offset:64
	global_load_dwordx4 v[36:39], v[116:117], off offset:192
	s_waitcnt vmcnt(0)
	v_add_f32_e32 v32, v32, v36
	v_add_f32_e32 v33, v33, v37
	v_add_f32_e32 v34, v34, v38
	v_add_f32_e32 v35, v35, v39
	v_mul_f32_e32 v32, 0xbfb8aa3b, v32
	v_mul_f32_e32 v33, 0xbfb8aa3b, v33
	v_mul_f32_e32 v34, 0xbfb8aa3b, v34
	v_mul_f32_e32 v35, 0xbfb8aa3b, v35
	v_exp_f32_e32 v32, v32
	v_exp_f32_e32 v33, v33
	v_exp_f32_e32 v34, v34
	v_exp_f32_e32 v35, v35
	v_add_f32_e32 v32, 1.0, v32
	v_add_f32_e32 v33, 1.0, v33
	v_add_f32_e32 v34, 1.0, v34
	v_add_f32_e32 v35, 1.0, v35
	v_rcp_f32_e32 v32, v32
	v_rcp_f32_e32 v34, v34
	v_rcp_f32_e32 v35, v35
	v_rcp_f32_e32 v33, v33
	v_or_b32_e32 v36, 0x60, v120
	v_ashrrev_i32_e32 v37, 31, v36
	v_pk_mul_f32 v[34:35], v[34:35], s[10:11] op_sel_hi:[1,0]
	v_pk_mul_f32 v[32:33], v[32:33], s[10:11] op_sel_hi:[1,0]
	v_lshlrev_b64 v[36:37], 10, v[36:37]
	v_cvt_pk_bf16_f32 v32, v32, v33
	v_cvt_pk_bf16_f32 v33, v34, v35
	global_store_dwordx2 v[48:49], v[32:33], off offset:96
	global_load_dwordx4 v[32:35], v[116:117], off
	s_waitcnt vmcnt(0)
	v_add_f32_e32 v28, v28, v32
	v_add_f32_e32 v29, v29, v33
	v_add_f32_e32 v30, v30, v34
	v_add_f32_e32 v31, v31, v35
	v_mul_f32_e32 v28, 0xbfb8aa3b, v28
	v_mul_f32_e32 v29, 0xbfb8aa3b, v29
	v_mul_f32_e32 v30, 0xbfb8aa3b, v30
	v_mul_f32_e32 v31, 0xbfb8aa3b, v31
	v_exp_f32_e32 v28, v28
	v_exp_f32_e32 v29, v29
	v_exp_f32_e32 v30, v30
	v_exp_f32_e32 v31, v31
	v_add_f32_e32 v28, 1.0, v28
	v_add_f32_e32 v29, 1.0, v29
	v_add_f32_e32 v30, 1.0, v30
	v_add_f32_e32 v31, 1.0, v31
	v_rcp_f32_e32 v28, v28
	v_rcp_f32_e32 v30, v30
	v_rcp_f32_e32 v31, v31
	v_rcp_f32_e32 v29, v29
	v_lshl_add_u64 v[32:33], s[0:1], 0, v[36:37]
	v_lshl_add_u64 v[32:33], v[32:33], 0, v[118:119]
	v_pk_mul_f32 v[30:31], v[30:31], s[10:11] op_sel_hi:[1,0]
	v_pk_mul_f32 v[28:29], v[28:29], s[10:11] op_sel_hi:[1,0]
	s_nop 0
	v_cvt_pk_bf16_f32 v28, v28, v29
	v_cvt_pk_bf16_f32 v29, v30, v31
	global_store_dwordx2 v[32:33], v[28:29], off
	global_load_dwordx4 v[28:31], v[116:117], off offset:64
	s_waitcnt vmcnt(0)
	v_add_f32_e32 v24, v24, v28
	v_add_f32_e32 v25, v25, v29
	v_add_f32_e32 v26, v26, v30
	v_add_f32_e32 v27, v27, v31
	v_mul_f32_e32 v24, 0xbfb8aa3b, v24
	v_mul_f32_e32 v25, 0xbfb8aa3b, v25
	v_mul_f32_e32 v26, 0xbfb8aa3b, v26
	v_mul_f32_e32 v27, 0xbfb8aa3b, v27
	v_exp_f32_e32 v24, v24
	v_exp_f32_e32 v25, v25
	v_exp_f32_e32 v26, v26
	v_exp_f32_e32 v27, v27
	v_add_f32_e32 v24, 1.0, v24
	v_add_f32_e32 v25, 1.0, v25
	v_add_f32_e32 v26, 1.0, v26
	v_add_f32_e32 v27, 1.0, v27
	v_rcp_f32_e32 v24, v24
	v_rcp_f32_e32 v26, v26
	v_rcp_f32_e32 v27, v27
	v_rcp_f32_e32 v25, v25
	v_pk_mul_f32 v[26:27], v[26:27], s[10:11] op_sel_hi:[1,0]
	v_pk_mul_f32 v[24:25], v[24:25], s[10:11] op_sel_hi:[1,0]
	s_nop 0
	v_cvt_pk_bf16_f32 v24, v24, v25
	v_cvt_pk_bf16_f32 v25, v26, v27
	global_store_dwordx2 v[32:33], v[24:25], off offset:32
	global_load_dwordx4 v[24:27], v[116:117], off offset:128
	s_waitcnt vmcnt(0)
; template <class Epi>
; DI void gemm_tile(char* smem, const bf16_t* __restrict__ A0, int lda0, int ksplit, const bf16_t* __restrict__ A1, int lda1,
;                   const bf16_t* __restrict__ Bt, int K, int row0, int col0, const Epi& epi, int tid) {
;     ...
;   for (int m = 0; m < 8; ++m)
; #pragma unroll
;     for (int n = 0; n < 4; ++n) epi(row0 + wr * 128 + m * 16 + fr, col0 + wc * 64 + n * 16 + fq * 4, acc[m][n]);
	v_add_f32_e32 v20, v20, v24
	v_add_f32_e32 v21, v21, v25
	v_add_f32_e32 v22, v22, v26
	v_add_f32_e32 v23, v23, v27
	v_mul_f32_e32 v20, 0xbfb8aa3b, v20
	v_mul_f32_e32 v21, 0xbfb8aa3b, v21
	v_mul_f32_e32 v22, 0xbfb8aa3b, v22
	v_mul_f32_e32 v23, 0xbfb8aa3b, v23
	v_exp_f32_e32 v20, v20
	v_exp_f32_e32 v21, v21
	v_exp_f32_e32 v22, v22
	v_exp_f32_e32 v23, v23
	v_add_f32_e32 v20, 1.0, v20
	v_add_f32_e32 v21, 1.0, v21
	v_add_f32_e32 v22, 1.0, v22
	v_add_f32_e32 v23, 1.0, v23
	v_rcp_f32_e32 v20, v20
	v_rcp_f32_e32 v22, v22
	v_rcp_f32_e32 v23, v23
	v_rcp_f32_e32 v21, v21
	v_pk_mul_f32 v[22:23], v[22:23], s[10:11] op_sel_hi:[1,0]
	v_pk_mul_f32 v[20:21], v[20:21], s[10:11] op_sel_hi:[1,0]
	s_nop 0
	v_cvt_pk_bf16_f32 v20, v20, v21
	v_cvt_pk_bf16_f32 v21, v22, v23
	global_store_dwordx2 v[32:33], v[20:21], off offset:64
	global_load_dwordx4 v[20:23], v[116:117], off offset:192
	s_waitcnt vmcnt(0)
	v_add_f32_e32 v16, v16, v20
	v_add_f32_e32 v17, v17, v21
	v_add_f32_e32 v18, v18, v22
	v_add_f32_e32 v19, v19, v23
	v_mul_f32_e32 v16, 0xbfb8aa3b, v16
	v_mul_f32_e32 v17, 0xbfb8aa3b, v17
	v_mul_f32_e32 v18, 0xbfb8aa3b, v18
	v_mul_f32_e32 v19, 0xbfb8aa3b, v19
	v_exp_f32_e32 v16, v16
	v_exp_f32_e32 v17, v17
	v_exp_f32_e32 v18, v18
	v_exp_f32_e32 v19, v19
	v_add_f32_e32 v16, 1.0, v16
	v_add_f32_e32 v17, 1.0, v17
	v_add_f32_e32 v18, 1.0, v18
	v_add_f32_e32 v19, 1.0, v19
	v_rcp_f32_e32 v16, v16
	v_rcp_f32_e32 v18, v18
	v_rcp_f32_e32 v19, v19
	v_rcp_f32_e32 v17, v17
	v_or_b32_e32 v20, 0x70, v120
	v_ashrrev_i32_e32 v21, 31, v20
	v_pk_mul_f32 v[18:19], v[18:19], s[10:11] op_sel_hi:[1,0]
	v_pk_mul_f32 v[16:17], v[16:17], s[10:11] op_sel_hi:[1,0]
	v_lshlrev_b64 v[20:21], 10, v[20:21]
	v_cvt_pk_bf16_f32 v16, v16, v17
	v_cvt_pk_bf16_f32 v17, v18, v19
	global_store_dwordx2 v[32:33], v[16:17], off offset:96
	global_load_dwordx4 v[16:19], v[116:117], off
	s_waitcnt vmcnt(0)
	v_add_f32_e32 v12, v12, v16
	v_add_f32_e32 v13, v13, v17
	v_add_f32_e32 v14, v14, v18
	v_add_f32_e32 v15, v15, v19
	v_mul_f32_e32 v12, 0xbfb8aa3b, v12
	v_mul_f32_e32 v13, 0xbfb8aa3b, v13
	v_mul_f32_e32 v14, 0xbfb8aa3b, v14
	v_mul_f32_e32 v15, 0xbfb8aa3b, v15
	v_exp_f32_e32 v12, v12
	v_exp_f32_e32 v13, v13
	v_exp_f32_e32 v14, v14
	v_exp_f32_e32 v15, v15
	v_add_f32_e32 v12, 1.0, v12
	v_add_f32_e32 v13, 1.0, v13
	v_add_f32_e32 v14, 1.0, v14
	v_add_f32_e32 v15, 1.0, v15
	v_rcp_f32_e32 v12, v12
	v_rcp_f32_e32 v14, v14
	v_rcp_f32_e32 v15, v15
	v_rcp_f32_e32 v13, v13
	v_lshl_add_u64 v[16:17], s[0:1], 0, v[20:21]
	v_lshl_add_u64 v[16:17], v[16:17], 0, v[118:119]
	v_pk_mul_f32 v[14:15], v[14:15], s[10:11] op_sel_hi:[1,0]
	v_pk_mul_f32 v[12:13], v[12:13], s[10:11] op_sel_hi:[1,0]
	s_nop 0
	v_cvt_pk_bf16_f32 v12, v12, v13
	v_cvt_pk_bf16_f32 v13, v14, v15
	global_store_dwordx2 v[16:17], v[12:13], off
	global_load_dwordx4 v[12:15], v[116:117], off offset:64
	s_waitcnt vmcnt(0)
	v_add_f32_e32 v8, v8, v12
	v_add_f32_e32 v9, v9, v13
	v_add_f32_e32 v10, v10, v14
	v_add_f32_e32 v11, v11, v15
	v_mul_f32_e32 v8, 0xbfb8aa3b, v8
	v_mul_f32_e32 v9, 0xbfb8aa3b, v9
	v_mul_f32_e32 v10, 0xbfb8aa3b, v10
	v_mul_f32_e32 v11, 0xbfb8aa3b, v11
	v_exp_f32_e32 v8, v8
	v_exp_f32_e32 v9, v9
	v_exp_f32_e32 v10, v10
	v_exp_f32_e32 v11, v11
	v_add_f32_e32 v8, 1.0, v8
	v_add_f32_e32 v9, 1.0, v9
	v_add_f32_e32 v10, 1.0, v10
	v_add_f32_e32 v11, 1.0, v11
	v_rcp_f32_e32 v8, v8
	v_rcp_f32_e32 v10, v10
	v_rcp_f32_e32 v11, v11
	v_rcp_f32_e32 v9, v9
	v_pk_mul_f32 v[10:11], v[10:11], s[10:11] op_sel_hi:[1,0]
	v_pk_mul_f32 v[8:9], v[8:9], s[10:11] op_sel_hi:[1,0]
	s_nop 0
	v_cvt_pk_bf16_f32 v8, v8, v9
	v_cvt_pk_bf16_f32 v9, v10, v11
	global_store_dwordx2 v[16:17], v[8:9], off offset:32
	global_load_dwordx4 v[8:11], v[116:117], off offset:128
	s_waitcnt vmcnt(0)
	v_add_f32_e32 v4, v4, v8
	v_add_f32_e32 v5, v5, v9
	v_add_f32_e32 v6, v6, v10
	v_add_f32_e32 v7, v7, v11
	v_mul_f32_e32 v4, 0xbfb8aa3b, v4
	v_mul_f32_e32 v5, 0xbfb8aa3b, v5
	v_mul_f32_e32 v6, 0xbfb8aa3b, v6
	v_mul_f32_e32 v7, 0xbfb8aa3b, v7
	v_exp_f32_e32 v4, v4
	v_exp_f32_e32 v5, v5
	v_exp_f32_e32 v6, v6
	v_exp_f32_e32 v7, v7
	v_add_f32_e32 v4, 1.0, v4
	v_add_f32_e32 v5, 1.0, v5
	v_add_f32_e32 v6, 1.0, v6
	v_add_f32_e32 v7, 1.0, v7
	v_rcp_f32_e32 v4, v4
	v_rcp_f32_e32 v6, v6
	v_rcp_f32_e32 v7, v7
	v_rcp_f32_e32 v5, v5
	v_pk_mul_f32 v[6:7], v[6:7], s[10:11] op_sel_hi:[1,0]
	v_pk_mul_f32 v[4:5], v[4:5], s[10:11] op_sel_hi:[1,0]
	s_add_i32 s11, s11, s15
	v_cvt_pk_bf16_f32 v4, v4, v5
	v_cvt_pk_bf16_f32 v5, v6, v7
	global_store_dwordx2 v[16:17], v[4:5], off offset:64
	global_load_dwordx4 v[4:7], v[116:117], off offset:192
	s_cmpk_lt_i32 s17, 0x200
	s_waitcnt vmcnt(0)
	v_add_f32_e32 v0, v0, v4
	v_add_f32_e32 v1, v1, v5
	v_add_f32_e32 v2, v2, v6
	v_add_f32_e32 v3, v3, v7
	v_mul_f32_e32 v0, 0xbfb8aa3b, v0
	v_mul_f32_e32 v1, 0xbfb8aa3b, v1
	v_mul_f32_e32 v2, 0xbfb8aa3b, v2
	v_mul_f32_e32 v3, 0xbfb8aa3b, v3
	v_exp_f32_e32 v0, v0
	v_exp_f32_e32 v1, v1
	v_exp_f32_e32 v2, v2
	v_exp_f32_e32 v3, v3
	v_add_f32_e32 v0, 1.0, v0
	v_add_f32_e32 v1, 1.0, v1
	v_add_f32_e32 v2, 1.0, v2
	v_add_f32_e32 v3, 1.0, v3
	v_rcp_f32_e32 v0, v0
	v_rcp_f32_e32 v2, v2
	v_rcp_f32_e32 v3, v3
	v_rcp_f32_e32 v1, v1
	v_pk_mul_f32 v[2:3], v[2:3], s[10:11] op_sel_hi:[1,0]
	v_pk_mul_f32 v[0:1], v[0:1], s[10:11] op_sel_hi:[1,0]
	s_nop 0
	v_cvt_pk_bf16_f32 v0, v0, v1
	v_cvt_pk_bf16_f32 v1, v2, v3
	global_store_dwordx2 v[16:17], v[0:1], off offset:96
	s_cbranch_scc1 .LBB0_553

; #define LWRITE(S, buf) do { bf16_t* sA_ = sbase + (buf) * BUF; bf16_t* sB_ = sA_ + 256 * PITCH; \
;     _Pragma("unroll") for (int i_ = 0; i_ < 4; ++i_) *(u32x4*)(sA_ + (sr + i_ * 64) * PITCH + scv * 8) = ra[S][i_]; \
;     _Pragma("unroll") for (int i_ = 0; i_ < 2; ++i_) *(u32x4*)(sB_ + (sr + i_ * 64) * PITCH + scv * 8) = rb[S][i_]; } while (0)
; template <class Epi>
; DI void gemm_tile(char* smem, const bf16_t* __restrict__ A0, int lda0, int ksplit, const bf16_t* __restrict__ A1, int lda1,
;                   const bf16_t* __restrict__ Bt, int K, int row0, int col0, const Epi& epi, int tid) {
;     ...
;   u32x4 ra[2][4], rb[2][2];
;   const int nk = K / BK;
;   const int sr = tid >> 2, scv = tid & 3;
;     ...
;   __syncthreads();
;   {
;     const int last = nk - 1;
;     GLOAD(0, 0);
;     __builtin_amdgcn_sched_barrier(0);
;     GLOAD(1, 1);
;     __builtin_amdgcn_sched_barrier(0);
;     LWRITE(0, 0);
;     __builtin_amdgcn_sched_barrier(0);
;     GLOAD(0, (2 < last ? 2 : last));
;     __builtin_amdgcn_sched_barrier(0);
;     __syncthreads();
;     for (int kt = 0; kt < nk; kt += 2) {
;       LWRITE(1, 1);
;       __builtin_amdgcn_sched_barrier(0);
;       GLOAD(1, (kt + 3 < last ? kt + 3 : last));
;       __builtin_amdgcn_sched_barrier(0);
;       COMPUTE(0);
;       __syncthreads();
; template <class Epi>
; DI void gemm_phase(char* smem, const bf16_t* A0, int lda0, int ksplit, const bf16_t* A1, int lda1, const bf16_t* Bt, int K, int nN, const Epi& epi, int tid) {
;     ...
;     const int x = blockIdx.x & 7, l = blockIdx.x >> 3, L = G >> 3, per = 8 * nN, tot = 2 * per;
;     for (int q = l; q < tot; q += L) { const int rgl = q / per, rem = q % per, ct = rem >> 3, rt = (x * 2 + rgl) * 8 + (rem & 7);
;       gemm_tile(smem, A0, lda0, ksplit, A1, lda1, Bt, K, rt * 256, ct * 128, epi, tid); }
.LBB0_556:
	s_cmpk_gt_u32 s96, 0x1ff
	s_cbranch_scc1 .LBB0_559
	v_and_b32_e32 v0, 3, v136
	v_lshlrev_b32_e32 v0, 4, v0
	v_mov_b32_e32 v1, 0
	v_ashrrev_i32_e32 v122, 2, v137
	v_lshl_add_u64 v[112:113], s[4:5], 0, v[0:1]
	v_lshl_add_u64 v[114:115], s[6:7], 0, v[0:1]
	v_bfe_u32 v1, v136, 4, 2
	s_movk_i32 s6, 0x40
	v_and_b32_e32 v4, 0x4f, v137
	v_and_b32_e32 v123, 0xffffff8f, v137
	v_or_b32_e32 v7, 0x70, v137
	s_ashr_i32 s8, s12, 3
	s_lshr_b32 s9, s96, 3
	s_lshl_b32 s10, s96, 1
	v_add_u32_e32 v0, 0, v0
	v_mul_lo_u32 v2, v122, s6
	v_and_b32_e32 v3, 64, v137
	v_lshl_add_u32 v5, v1, 4, 0
	v_mul_u32_u24_e32 v4, 0x40, v4
	v_mul_lo_u32 v6, v123, s6
	v_mul_lo_u32 v7, v7, s6
	s_and_b32 s10, s10, 14
	v_lshl_or_b32 v124, v1, 2, v3
	s_lshl_b32 s7, s9, 8
	s_lshl_b32 s11, s8, 8
	s_lshl_b32 s15, s9, 4
	s_lshl_b32 s16, s8, 4
	s_movk_i32 s17, 0x2000
	v_add_u32_e32 v125, v0, v2
	v_add_u32_e32 v126, v5, v4
	v_add_u32_e32 v127, v5, v6
	v_add_u32_e32 v128, v5, v7
	v_mbcnt_lo_u32_b32 v2, -1, 0
	v_mbcnt_hi_u32_b32 v2, -1, v2
	v_bfe_u32 v4, v2, 3, 1
	v_bfe_u32 v2, v2, 5, 1
	v_mul_u32_u24_e32 v4, 48, v4
	v_mul_u32_u24_e32 v2, 48, v2
	v_xor_b32_e32 v125, v125, v2
	v_xor_b32_e32 v126, v126, v4
	v_xor_b32_e32 v127, v127, v4
	v_xor_b32_e32 v128, v128, v4
	s_mov_b32 s6, 0x3f1b4598
.LBB0_558:
	s_ashr_i32 s18, s9, 31
	s_lshr_b32 s18, s18, 27
	s_add_i32 s18, s9, s18
	s_ashr_i32 s19, s18, 5
	s_add_i32 s18, s19, s10
	s_lshl_b32 s18, s18, 11
	s_and_b32 s20, s7, 0x700
	s_or_b32 s18, s18, s20
	v_add_u32_e32 v0, s18, v122
	v_ashrrev_i32_e32 v1, 31, v0
	v_lshlrev_b64 v[0:1], 9, v[0:1]
	s_lshl_b32 s19, s19, 9
	v_lshl_add_u64 v[24:25], v[112:113], 0, v[0:1]
	s_mov_b32 s20, 0x8000
	s_sub_i32 s19, s15, s19
	v_add_co_u32_e32 v4, vcc, s20, v24
	s_and_b32 s19, s19, 0xffffff80
	s_nop 0
	v_addc_co_u32_e32 v5, vcc, 0, v25, vcc
	s_mov_b32 s20, 0x10000
	v_add_co_u32_e32 v8, vcc, s20, v24
	v_add_u32_e32 v16, s19, v122
	s_nop 0
	v_addc_co_u32_e32 v9, vcc, 0, v25, vcc
	s_mov_b32 s20, 0x18000
	v_ashrrev_i32_e32 v17, 31, v16
	v_add_co_u32_e32 v12, vcc, s20, v24
	v_lshlrev_b64 v[16:17], 7, v[16:17]
	s_nop 0
	v_addc_co_u32_e32 v13, vcc, 0, v25, vcc
	v_lshl_add_u64 v[40:41], v[114:115], 0, v[16:17]
	v_add_co_u32_e32 v20, vcc, s17, v40
	s_waitcnt lgkmcnt(0)
	s_nop 0
	v_addc_co_u32_e32 v21, vcc, 0, v41, vcc
	s_barrier
	global_load_dwordx4 v[0:3], v[24:25], off
	s_nop 0
	global_load_dwordx4 v[4:7], v[4:5], off
	s_nop 0
	global_load_dwordx4 v[8:11], v[8:9], off
	s_nop 0
	global_load_dwordx4 v[12:15], v[12:13], off
	s_nop 0
	global_load_dwordx4 v[16:19], v[40:41], off
	s_nop 0
	global_load_dwordx4 v[20:23], v[20:21], off
	s_mov_b64 s[20:21], 0x8000
	v_lshl_add_u64 v[28:29], v[24:25], 0, s[20:21]
	s_mov_b64 s[20:21], 0x10000
	v_lshl_add_u64 v[32:33], v[24:25], 0, s[20:21]
	s_mov_b64 s[20:21], 0x18000
	v_lshl_add_u64 v[36:37], v[24:25], 0, s[20:21]
	s_mov_b64 s[20:21], 0x2000
	v_lshl_add_u64 v[44:45], v[40:41], 0, s[20:21]
	global_load_dwordx4 v[24:27], v[24:25], off offset:64
	s_nop 0
	global_load_dwordx4 v[28:31], v[28:29], off offset:64
	s_nop 0
	global_load_dwordx4 v[32:35], v[32:33], off offset:64
	s_nop 0
	global_load_dwordx4 v[36:39], v[36:37], off offset:64
	s_nop 0
	global_load_dwordx4 v[40:43], v[40:41], off offset:64
	s_nop 0
	global_load_dwordx4 v[44:47], v[44:45], off offset:64
	s_waitcnt vmcnt(11)
	ds_write_b128 v125, v[0:3]
	s_waitcnt vmcnt(10)
	ds_write_b128 v125, v[4:7] offset:4096
	s_waitcnt vmcnt(9)
	ds_write_b128 v125, v[8:11] offset:8192
	s_waitcnt vmcnt(8)
	ds_write_b128 v125, v[12:15] offset:12288
	s_waitcnt vmcnt(7)
	ds_write_b128 v125, v[16:19] offset:16384
	s_waitcnt vmcnt(6)
	ds_write_b128 v125, v[20:23] offset:20480
	s_waitcnt lgkmcnt(0)
	s_barrier
	s_waitcnt vmcnt(5)
	ds_write_b128 v125, v[24:27] offset:24576
	s_waitcnt vmcnt(4)
	ds_write_b128 v125, v[28:31] offset:28672
	s_waitcnt vmcnt(3)
	ds_write_b128 v125, v[32:35] offset:32768
	s_waitcnt vmcnt(2)
	ds_write_b128 v125, v[36:39] offset:36864
	s_waitcnt vmcnt(1)
	ds_write_b128 v125, v[40:43] offset:40960
	s_waitcnt vmcnt(0)
	ds_write_b128 v125, v[44:47] offset:45056
	ds_read_b128 v[0:3], v126 offset:16384
	ds_read_b128 v[4:7], v126 offset:17408
	ds_read_b128 v[8:11], v126 offset:18432
	ds_read_b128 v[12:15], v126 offset:19456
	ds_read_b128 v[16:19], v127
	ds_read_b128 v[20:23], v127 offset:1024
	ds_read_b128 v[48:51], v127 offset:2048
	ds_read_b128 v[52:55], v127 offset:3072
	ds_read_b128 v[56:59], v127 offset:4096
	ds_read_b128 v[60:63], v127 offset:5120
	ds_read_b128 v[64:67], v127 offset:6144
	ds_read_b128 v[68:71], v128
	s_setprio 1
	s_waitcnt lgkmcnt(7)
	v_mfma_f32_16x16x32_bf16 v[72:75], v[0:3], v[16:19], 0
	v_mfma_f32_16x16x32_bf16 v[76:79], v[4:7], v[16:19], 0
	v_mfma_f32_16x16x32_bf16 v[80:83], v[8:11], v[16:19], 0
	v_mfma_f32_16x16x32_bf16 v[16:19], v[12:15], v[16:19], 0
	s_waitcnt lgkmcnt(6)
	v_mfma_f32_16x16x32_bf16 v[84:87], v[0:3], v[20:23], 0
	v_mfma_f32_16x16x32_bf16 v[88:91], v[4:7], v[20:23], 0
	v_mfma_f32_16x16x32_bf16 v[92:95], v[8:11], v[20:23], 0
	v_mfma_f32_16x16x32_bf16 v[20:23], v[12:15], v[20:23], 0
	s_waitcnt lgkmcnt(5)
	v_mfma_f32_16x16x32_bf16 v[116:119], v[0:3], v[48:51], 0
	v_mfma_f32_16x16x32_bf16 v[130:133], v[4:7], v[48:51], 0
	v_mfma_f32_16x16x32_bf16 v[138:141], v[8:11], v[48:51], 0
	v_mfma_f32_16x16x32_bf16 v[48:51], v[12:15], v[48:51], 0
	s_waitcnt lgkmcnt(4)
	v_mfma_f32_16x16x32_bf16 v[142:145], v[0:3], v[52:55], 0
	v_mfma_f32_16x16x32_bf16 v[146:149], v[4:7], v[52:55], 0
	v_mfma_f32_16x16x32_bf16 v[150:153], v[8:11], v[52:55], 0
	v_mfma_f32_16x16x32_bf16 v[52:55], v[12:15], v[52:55], 0
	s_waitcnt lgkmcnt(3)
	v_mfma_f32_16x16x32_bf16 v[154:157], v[0:3], v[56:59], 0
	v_mfma_f32_16x16x32_bf16 v[158:161], v[4:7], v[56:59], 0
	v_mfma_f32_16x16x32_bf16 v[162:165], v[8:11], v[56:59], 0
	v_mfma_f32_16x16x32_bf16 v[166:169], v[12:15], v[56:59], 0
	s_waitcnt lgkmcnt(2)
	v_mfma_f32_16x16x32_bf16 v[170:173], v[0:3], v[60:63], 0
	v_mfma_f32_16x16x32_bf16 v[174:177], v[4:7], v[60:63], 0
	v_mfma_f32_16x16x32_bf16 v[178:181], v[8:11], v[60:63], 0
	v_mfma_f32_16x16x32_bf16 v[182:185], v[12:15], v[60:63], 0
	s_waitcnt lgkmcnt(1)
	v_mfma_f32_16x16x32_bf16 v[186:189], v[0:3], v[64:67], 0
	v_mfma_f32_16x16x32_bf16 v[190:193], v[4:7], v[64:67], 0
	v_mfma_f32_16x16x32_bf16 v[196:199], v[8:11], v[64:67], 0
	v_mfma_f32_16x16x32_bf16 v[200:203], v[12:15], v[64:67], 0
	s_waitcnt lgkmcnt(0)
	v_mfma_f32_16x16x32_bf16 v[0:3], v[0:3], v[68:71], 0
	v_mfma_f32_16x16x32_bf16 v[4:7], v[4:7], v[68:71], 0
	v_mfma_f32_16x16x32_bf16 v[204:207], v[8:11], v[68:71], 0
	v_mfma_f32_16x16x32_bf16 v[208:211], v[12:15], v[68:71], 0
	s_setprio 0
	s_barrier
; DI unsigned pack2(float lo, float hi) { const f32x2c v = {lo, hi}; return __builtin_bit_cast(unsigned, __builtin_convertvector(v, bf16x2c)); }
; #define LWRITE(S, buf) do { bf16_t* sA_ = sbase + (buf) * BUF; bf16_t* sB_ = sA_ + 256 * PITCH; \
;     _Pragma("unroll") for (int i_ = 0; i_ < 4; ++i_) *(u32x4*)(sA_ + (sr + i_ * 64) * PITCH + scv * 8) = ra[S][i_]; \
;     _Pragma("unroll") for (int i_ = 0; i_ < 2; ++i_) *(u32x4*)(sB_ + (sr + i_ * 64) * PITCH + scv * 8) = rb[S][i_]; } while (0)
; template <class Epi>
; DI void gemm_tile(char* smem, const bf16_t* __restrict__ A0, int lda0, int ksplit, const bf16_t* __restrict__ A1, int lda1,
;                   const bf16_t* __restrict__ Bt, int K, int row0, int col0, const Epi& epi, int tid) {
;     ...
;       COMPUTE(0);
;       __syncthreads();
;       LWRITE(0, 0);
;       __builtin_amdgcn_sched_barrier(0);
;       GLOAD(0, (kt + 4 < last ? kt + 4 : last));
;       __builtin_amdgcn_sched_barrier(0);
;       COMPUTE(1);
;       __syncthreads();
;     }
;   }
;     ...
; #pragma unroll
;   for (int m = 0; m < 8; ++m)
; #pragma unroll
;     for (int n = 0; n < 4; ++n) epi(row0 + wr * 128 + m * 16 + fr, col0 + wc * 64 + n * 16 + fq * 4, acc[m][n]);
; }
; DI void st_bf16x4(bf16_t* o, f32x4 v) { u32x2 q; q.x = pack2(v[0], v[1]); q.y = pack2(v[2], v[3]); *(u32x2*)o = q; }
;   DI void operator()(int row, int col, f32x4 v) const {
;     if (col < n0) st_bf16x4(o0 + (size_t)row * ld0 + col, v);
;     else { const int c = col - n0; if (c < n1) st_bf16x4(o1 + (size_t)row * ld1 + c, v); }
;   }
	ds_write_b128 v125, v[24:27]
	ds_write_b128 v125, v[28:31] offset:4096
	ds_write_b128 v125, v[32:35] offset:8192
	ds_write_b128 v125, v[36:39] offset:12288
	ds_write_b128 v125, v[40:43] offset:16384
	ds_write_b128 v125, v[44:47] offset:20480
	ds_read_b128 v[8:11], v126 offset:40960
	ds_read_b128 v[212:215], v126 offset:41984
	ds_read_b128 v[216:219], v126 offset:43008
	ds_read_b128 v[220:223], v126 offset:44032
	ds_read_b128 v[12:15], v127 offset:26624
	ds_read_b128 v[24:27], v127 offset:27648
	ds_read_b128 v[28:31], v127 offset:28672
	ds_read_b128 v[32:35], v127 offset:29696
	ds_read_b128 v[36:39], v127 offset:24576
	ds_read_b128 v[224:227], v127 offset:30720
	ds_read_b128 v[40:43], v127 offset:25600
	ds_read_b128 v[228:231], v128 offset:24576
	s_setprio 1
	s_waitcnt lgkmcnt(3)
	v_mfma_f32_16x16x32_bf16 v[232:235], v[8:11], v[36:39], v[72:75]
	v_mfma_f32_16x16x32_bf16 v[236:239], v[212:215], v[36:39], v[76:79]
	v_mfma_f32_16x16x32_bf16 v[240:243], v[216:219], v[36:39], v[80:83]
	v_mfma_f32_16x16x32_bf16 v[244:247], v[220:223], v[36:39], v[16:19]
	s_waitcnt lgkmcnt(1)
	v_mfma_f32_16x16x32_bf16 v[108:111], v[8:11], v[40:43], v[84:87]
	v_mfma_f32_16x16x32_bf16 v[104:107], v[212:215], v[40:43], v[88:91]
	v_mfma_f32_16x16x32_bf16 v[100:103], v[216:219], v[40:43], v[92:95]
	v_mfma_f32_16x16x32_bf16 v[96:99], v[220:223], v[40:43], v[20:23]
	v_mfma_f32_16x16x32_bf16 v[92:95], v[8:11], v[12:15], v[116:119]
	v_mfma_f32_16x16x32_bf16 v[88:91], v[212:215], v[12:15], v[130:133]
	v_mfma_f32_16x16x32_bf16 v[84:87], v[216:219], v[12:15], v[138:141]
	v_mfma_f32_16x16x32_bf16 v[80:83], v[220:223], v[12:15], v[48:51]
	v_mfma_f32_16x16x32_bf16 v[76:79], v[8:11], v[24:27], v[142:145]
	v_mfma_f32_16x16x32_bf16 v[72:75], v[212:215], v[24:27], v[146:149]
	v_mfma_f32_16x16x32_bf16 v[68:71], v[216:219], v[24:27], v[150:153]
	v_mfma_f32_16x16x32_bf16 v[64:67], v[220:223], v[24:27], v[52:55]
	v_mfma_f32_16x16x32_bf16 v[60:63], v[8:11], v[28:31], v[154:157]
	v_mfma_f32_16x16x32_bf16 v[56:59], v[212:215], v[28:31], v[158:161]
	v_mfma_f32_16x16x32_bf16 v[52:55], v[216:219], v[28:31], v[162:165]
	v_mfma_f32_16x16x32_bf16 v[48:51], v[220:223], v[28:31], v[166:169]
	v_mfma_f32_16x16x32_bf16 v[44:47], v[8:11], v[32:35], v[170:173]
	v_mfma_f32_16x16x32_bf16 v[40:43], v[212:215], v[32:35], v[174:177]
	v_mfma_f32_16x16x32_bf16 v[36:39], v[216:219], v[32:35], v[178:181]
	v_mfma_f32_16x16x32_bf16 v[32:35], v[220:223], v[32:35], v[182:185]
	v_mfma_f32_16x16x32_bf16 v[28:31], v[8:11], v[224:227], v[186:189]
	v_mfma_f32_16x16x32_bf16 v[24:27], v[212:215], v[224:227], v[190:193]
	v_mfma_f32_16x16x32_bf16 v[20:23], v[216:219], v[224:227], v[196:199]
	v_mfma_f32_16x16x32_bf16 v[16:19], v[220:223], v[224:227], v[200:203]
	s_waitcnt lgkmcnt(0)
	v_mfma_f32_16x16x32_bf16 v[12:15], v[8:11], v[228:231], v[0:3]
	v_mfma_f32_16x16x32_bf16 v[8:11], v[212:215], v[228:231], v[4:7]
	v_mfma_f32_16x16x32_bf16 v[4:7], v[216:219], v[228:231], v[204:207]
	v_mfma_f32_16x16x32_bf16 v[0:3], v[220:223], v[228:231], v[208:211]
	s_setprio 0
	v_or_b32_e32 v118, s19, v124
	v_ashrrev_i32_e32 v119, 31, v118
	v_lshl_add_u64 v[116:117], v[118:119], 2, s[58:59]
	s_barrier
	global_load_dwordx4 v[130:133], v[116:117], off
	v_add_u32_e32 v120, s18, v123
	v_ashrrev_i32_e32 v121, 31, v120
	v_lshlrev_b64 v[134:135], 10, v[120:121]
	v_lshlrev_b64 v[118:119], 1, v[118:119]
	v_lshl_add_u64 v[134:135], s[0:1], 0, v[134:135]
	v_lshl_add_u64 v[134:135], v[134:135], 0, v[118:119]
	s_add_i32 s9, s9, s8
	s_add_i32 s15, s15, s16
	s_waitcnt vmcnt(0)
	v_add_f32_e32 v121, v232, v130
	v_add_f32_e32 v129, v233, v131
	v_add_f32_e32 v130, v234, v132
	v_add_f32_e32 v131, v235, v133
	v_mul_f32_e32 v121, 0xbfb8aa3b, v121
	v_mul_f32_e32 v129, 0xbfb8aa3b, v129
	v_mul_f32_e32 v130, 0xbfb8aa3b, v130
	v_mul_f32_e32 v131, 0xbfb8aa3b, v131
	v_exp_f32_e32 v121, v121
	v_exp_f32_e32 v129, v129
	v_exp_f32_e32 v130, v130
	v_exp_f32_e32 v131, v131
	v_add_f32_e32 v121, 1.0, v121
	v_add_f32_e32 v129, 1.0, v129
	v_add_f32_e32 v132, 1.0, v130
	v_add_f32_e32 v131, 1.0, v131
	v_rcp_f32_e32 v130, v121
	v_rcp_f32_e32 v132, v132
	v_rcp_f32_e32 v133, v131
	v_rcp_f32_e32 v131, v129
	v_pk_mul_f32 v[132:133], v[132:133], s[6:7] op_sel_hi:[1,0]
	v_pk_mul_f32 v[130:131], v[130:131], s[6:7] op_sel_hi:[1,0]
	s_nop 0
	v_cvt_pk_bf16_f32 v130, v130, v131
	v_cvt_pk_bf16_f32 v131, v132, v133
	global_store_dwordx2 v[134:135], v[130:131], off
	global_load_dwordx4 v[130:133], v[116:117], off offset:64
	s_waitcnt vmcnt(0)
	v_add_f32_e32 v121, v236, v130
	v_add_f32_e32 v129, v237, v131
	v_add_f32_e32 v130, v238, v132
	v_add_f32_e32 v131, v239, v133
	v_mul_f32_e32 v121, 0xbfb8aa3b, v121
	v_mul_f32_e32 v129, 0xbfb8aa3b, v129
	v_mul_f32_e32 v130, 0xbfb8aa3b, v130
	v_mul_f32_e32 v131, 0xbfb8aa3b, v131
	v_exp_f32_e32 v121, v121
	v_exp_f32_e32 v129, v129
	v_exp_f32_e32 v130, v130
	v_exp_f32_e32 v131, v131
	v_add_f32_e32 v121, 1.0, v121
	v_add_f32_e32 v129, 1.0, v129
	v_add_f32_e32 v132, 1.0, v130
	v_add_f32_e32 v131, 1.0, v131
	v_rcp_f32_e32 v130, v121
	v_rcp_f32_e32 v132, v132
	v_rcp_f32_e32 v133, v131
	v_rcp_f32_e32 v131, v129
	v_pk_mul_f32 v[132:133], v[132:133], s[6:7] op_sel_hi:[1,0]
	v_pk_mul_f32 v[130:131], v[130:131], s[6:7] op_sel_hi:[1,0]
	s_nop 0
	v_cvt_pk_bf16_f32 v130, v130, v131
	v_cvt_pk_bf16_f32 v131, v132, v133
	global_store_dwordx2 v[134:135], v[130:131], off offset:32
	global_load_dwordx4 v[130:133], v[116:117], off offset:128
	s_waitcnt vmcnt(0)
; template <class Epi>
; DI void gemm_tile(char* smem, const bf16_t* __restrict__ A0, int lda0, int ksplit, const bf16_t* __restrict__ A1, int lda1,
;                   const bf16_t* __restrict__ Bt, int K, int row0, int col0, const Epi& epi, int tid) {
;     ...
;   for (int m = 0; m < 8; ++m)
; #pragma unroll
;     for (int n = 0; n < 4; ++n) epi(row0 + wr * 128 + m * 16 + fr, col0 + wc * 64 + n * 16 + fq * 4, acc[m][n]);
	v_add_f32_e32 v121, v240, v130
	v_add_f32_e32 v129, v241, v131
	v_add_f32_e32 v130, v242, v132
	v_add_f32_e32 v131, v243, v133
	v_mul_f32_e32 v121, 0xbfb8aa3b, v121
	v_mul_f32_e32 v129, 0xbfb8aa3b, v129
	v_mul_f32_e32 v130, 0xbfb8aa3b, v130
	v_mul_f32_e32 v131, 0xbfb8aa3b, v131
	v_exp_f32_e32 v121, v121
	v_exp_f32_e32 v129, v129
	v_exp_f32_e32 v130, v130
	v_exp_f32_e32 v131, v131
	v_add_f32_e32 v121, 1.0, v121
	v_add_f32_e32 v129, 1.0, v129
	v_add_f32_e32 v132, 1.0, v130
	v_add_f32_e32 v131, 1.0, v131
	v_rcp_f32_e32 v130, v121
	v_rcp_f32_e32 v132, v132
	v_rcp_f32_e32 v133, v131
	v_rcp_f32_e32 v131, v129
	v_pk_mul_f32 v[132:133], v[132:133], s[6:7] op_sel_hi:[1,0]
	v_pk_mul_f32 v[130:131], v[130:131], s[6:7] op_sel_hi:[1,0]
	s_nop 0
	v_cvt_pk_bf16_f32 v130, v130, v131
	v_cvt_pk_bf16_f32 v131, v132, v133
	global_store_dwordx2 v[134:135], v[130:131], off offset:64
	global_load_dwordx4 v[130:133], v[116:117], off offset:192
	s_waitcnt vmcnt(0)
	v_add_f32_e32 v121, v244, v130
	v_add_f32_e32 v129, v245, v131
	v_add_f32_e32 v130, v246, v132
	v_add_f32_e32 v131, v247, v133
	v_mul_f32_e32 v121, 0xbfb8aa3b, v121
	v_mul_f32_e32 v129, 0xbfb8aa3b, v129
	v_mul_f32_e32 v130, 0xbfb8aa3b, v130
	v_mul_f32_e32 v131, 0xbfb8aa3b, v131
	v_exp_f32_e32 v121, v121
	v_exp_f32_e32 v129, v129
	v_exp_f32_e32 v130, v130
	v_exp_f32_e32 v131, v131
	v_add_f32_e32 v121, 1.0, v121
	v_add_f32_e32 v129, 1.0, v129
	v_add_f32_e32 v132, 1.0, v130
	v_add_f32_e32 v131, 1.0, v131
	v_rcp_f32_e32 v130, v121
	v_rcp_f32_e32 v132, v132
	v_rcp_f32_e32 v133, v131
	v_rcp_f32_e32 v131, v129
	v_pk_mul_f32 v[132:133], v[132:133], s[6:7] op_sel_hi:[1,0]
	v_pk_mul_f32 v[130:131], v[130:131], s[6:7] op_sel_hi:[1,0]
	s_nop 0
	v_cvt_pk_bf16_f32 v130, v130, v131
	v_cvt_pk_bf16_f32 v131, v132, v133
	global_store_dwordx2 v[134:135], v[130:131], off offset:96
	global_load_dwordx4 v[130:133], v[116:117], off
	v_or_b32_e32 v134, 16, v120
	v_ashrrev_i32_e32 v135, 31, v134
	v_lshlrev_b64 v[134:135], 10, v[134:135]
	s_waitcnt vmcnt(0)
	v_add_f32_e32 v108, v108, v130
	v_add_f32_e32 v109, v109, v131
	v_add_f32_e32 v110, v110, v132
	v_add_f32_e32 v111, v111, v133
	v_mul_f32_e32 v108, 0xbfb8aa3b, v108
	v_mul_f32_e32 v109, 0xbfb8aa3b, v109
	v_mul_f32_e32 v110, 0xbfb8aa3b, v110
	v_mul_f32_e32 v111, 0xbfb8aa3b, v111
	v_exp_f32_e32 v108, v108
	v_exp_f32_e32 v109, v109
	v_exp_f32_e32 v110, v110
	v_exp_f32_e32 v111, v111
	v_add_f32_e32 v108, 1.0, v108
	v_add_f32_e32 v109, 1.0, v109
	v_add_f32_e32 v110, 1.0, v110
	v_add_f32_e32 v111, 1.0, v111
	v_rcp_f32_e32 v108, v108
	v_rcp_f32_e32 v110, v110
	v_rcp_f32_e32 v111, v111
	v_rcp_f32_e32 v109, v109
	v_lshl_add_u64 v[130:131], s[0:1], 0, v[134:135]
	v_lshl_add_u64 v[130:131], v[130:131], 0, v[118:119]
	v_pk_mul_f32 v[110:111], v[110:111], s[6:7] op_sel_hi:[1,0]
	v_pk_mul_f32 v[108:109], v[108:109], s[6:7] op_sel_hi:[1,0]
	s_nop 0
	v_cvt_pk_bf16_f32 v108, v108, v109
	v_cvt_pk_bf16_f32 v109, v110, v111
	global_store_dwordx2 v[130:131], v[108:109], off
	global_load_dwordx4 v[108:111], v[116:117], off offset:64
	s_waitcnt vmcnt(0)
	v_add_f32_e32 v104, v104, v108
	v_add_f32_e32 v105, v105, v109
	v_add_f32_e32 v106, v106, v110
	v_add_f32_e32 v107, v107, v111
	v_mul_f32_e32 v104, 0xbfb8aa3b, v104
	v_mul_f32_e32 v105, 0xbfb8aa3b, v105
	v_mul_f32_e32 v106, 0xbfb8aa3b, v106
	v_mul_f32_e32 v107, 0xbfb8aa3b, v107
	v_exp_f32_e32 v104, v104
	v_exp_f32_e32 v105, v105
	v_exp_f32_e32 v106, v106
	v_exp_f32_e32 v107, v107
	v_add_f32_e32 v104, 1.0, v104
	v_add_f32_e32 v105, 1.0, v105
	v_add_f32_e32 v106, 1.0, v106
	v_add_f32_e32 v107, 1.0, v107
	v_rcp_f32_e32 v104, v104
	v_rcp_f32_e32 v106, v106
	v_rcp_f32_e32 v107, v107
	v_rcp_f32_e32 v105, v105
	v_pk_mul_f32 v[106:107], v[106:107], s[6:7] op_sel_hi:[1,0]
	v_pk_mul_f32 v[104:105], v[104:105], s[6:7] op_sel_hi:[1,0]
	s_nop 0
	v_cvt_pk_bf16_f32 v104, v104, v105
	v_cvt_pk_bf16_f32 v105, v106, v107
	global_store_dwordx2 v[130:131], v[104:105], off offset:32
	global_load_dwordx4 v[104:107], v[116:117], off offset:128
	s_waitcnt vmcnt(0)
	v_add_f32_e32 v100, v100, v104
	v_add_f32_e32 v101, v101, v105
	v_add_f32_e32 v102, v102, v106
	v_add_f32_e32 v103, v103, v107
	v_mul_f32_e32 v100, 0xbfb8aa3b, v100
	v_mul_f32_e32 v101, 0xbfb8aa3b, v101
	v_mul_f32_e32 v102, 0xbfb8aa3b, v102
	v_mul_f32_e32 v103, 0xbfb8aa3b, v103
	v_exp_f32_e32 v100, v100
	v_exp_f32_e32 v101, v101
	v_exp_f32_e32 v102, v102
	v_exp_f32_e32 v103, v103
	v_add_f32_e32 v100, 1.0, v100
	v_add_f32_e32 v101, 1.0, v101
	v_add_f32_e32 v102, 1.0, v102
	v_add_f32_e32 v103, 1.0, v103
	v_rcp_f32_e32 v100, v100
	v_rcp_f32_e32 v102, v102
	v_rcp_f32_e32 v103, v103
	v_rcp_f32_e32 v101, v101
	v_pk_mul_f32 v[102:103], v[102:103], s[6:7] op_sel_hi:[1,0]
	v_pk_mul_f32 v[100:101], v[100:101], s[6:7] op_sel_hi:[1,0]
	s_nop 0
	v_cvt_pk_bf16_f32 v100, v100, v101
	v_cvt_pk_bf16_f32 v101, v102, v103
	global_store_dwordx2 v[130:131], v[100:101], off offset:64
	global_load_dwordx4 v[100:103], v[116:117], off offset:192
	s_waitcnt vmcnt(0)
	v_add_f32_e32 v96, v96, v100
	v_add_f32_e32 v97, v97, v101
	v_add_f32_e32 v98, v98, v102
	v_add_f32_e32 v99, v99, v103
	v_mul_f32_e32 v96, 0xbfb8aa3b, v96
	v_mul_f32_e32 v97, 0xbfb8aa3b, v97
	v_mul_f32_e32 v98, 0xbfb8aa3b, v98
	v_mul_f32_e32 v99, 0xbfb8aa3b, v99
	v_exp_f32_e32 v96, v96
	v_exp_f32_e32 v97, v97
	v_exp_f32_e32 v98, v98
	v_exp_f32_e32 v99, v99
	v_add_f32_e32 v96, 1.0, v96
	v_add_f32_e32 v97, 1.0, v97
	v_add_f32_e32 v98, 1.0, v98
	v_add_f32_e32 v99, 1.0, v99
	v_rcp_f32_e32 v96, v96
	v_rcp_f32_e32 v98, v98
	v_rcp_f32_e32 v99, v99
	v_rcp_f32_e32 v97, v97
	v_or_b32_e32 v100, 32, v120
	v_ashrrev_i32_e32 v101, 31, v100
	v_pk_mul_f32 v[98:99], v[98:99], s[6:7] op_sel_hi:[1,0]
	v_pk_mul_f32 v[96:97], v[96:97], s[6:7] op_sel_hi:[1,0]
	v_lshlrev_b64 v[100:101], 10, v[100:101]
	v_cvt_pk_bf16_f32 v96, v96, v97
	v_cvt_pk_bf16_f32 v97, v98, v99
	global_store_dwordx2 v[130:131], v[96:97], off offset:96
	global_load_dwordx4 v[96:99], v[116:117], off
	s_waitcnt vmcnt(0)
; template <class Epi>
; DI void gemm_tile(char* smem, const bf16_t* __restrict__ A0, int lda0, int ksplit, const bf16_t* __restrict__ A1, int lda1,
;                   const bf16_t* __restrict__ Bt, int K, int row0, int col0, const Epi& epi, int tid) {
;     ...
;   for (int m = 0; m < 8; ++m)
; #pragma unroll
;     for (int n = 0; n < 4; ++n) epi(row0 + wr * 128 + m * 16 + fr, col0 + wc * 64 + n * 16 + fq * 4, acc[m][n]);
	v_add_f32_e32 v92, v92, v96
	v_add_f32_e32 v93, v93, v97
	v_add_f32_e32 v94, v94, v98
	v_add_f32_e32 v95, v95, v99
	v_mul_f32_e32 v92, 0xbfb8aa3b, v92
	v_mul_f32_e32 v93, 0xbfb8aa3b, v93
	v_mul_f32_e32 v94, 0xbfb8aa3b, v94
	v_mul_f32_e32 v95, 0xbfb8aa3b, v95
	v_exp_f32_e32 v92, v92
	v_exp_f32_e32 v93, v93
	v_exp_f32_e32 v94, v94
	v_exp_f32_e32 v95, v95
	v_add_f32_e32 v92, 1.0, v92
	v_add_f32_e32 v93, 1.0, v93
	v_add_f32_e32 v94, 1.0, v94
	v_add_f32_e32 v95, 1.0, v95
	v_rcp_f32_e32 v92, v92
	v_rcp_f32_e32 v94, v94
	v_rcp_f32_e32 v95, v95
	v_rcp_f32_e32 v93, v93
	v_lshl_add_u64 v[96:97], s[0:1], 0, v[100:101]
	v_lshl_add_u64 v[96:97], v[96:97], 0, v[118:119]
	v_pk_mul_f32 v[94:95], v[94:95], s[6:7] op_sel_hi:[1,0]
	v_pk_mul_f32 v[92:93], v[92:93], s[6:7] op_sel_hi:[1,0]
	s_nop 0
	v_cvt_pk_bf16_f32 v92, v92, v93
	v_cvt_pk_bf16_f32 v93, v94, v95
	global_store_dwordx2 v[96:97], v[92:93], off
	global_load_dwordx4 v[92:95], v[116:117], off offset:64
	s_waitcnt vmcnt(0)
	v_add_f32_e32 v88, v88, v92
	v_add_f32_e32 v89, v89, v93
	v_add_f32_e32 v90, v90, v94
	v_add_f32_e32 v91, v91, v95
	v_mul_f32_e32 v88, 0xbfb8aa3b, v88
	v_mul_f32_e32 v89, 0xbfb8aa3b, v89
	v_mul_f32_e32 v90, 0xbfb8aa3b, v90
	v_mul_f32_e32 v91, 0xbfb8aa3b, v91
	v_exp_f32_e32 v88, v88
	v_exp_f32_e32 v89, v89
	v_exp_f32_e32 v90, v90
	v_exp_f32_e32 v91, v91
	v_add_f32_e32 v88, 1.0, v88
	v_add_f32_e32 v89, 1.0, v89
	v_add_f32_e32 v90, 1.0, v90
	v_add_f32_e32 v91, 1.0, v91
	v_rcp_f32_e32 v88, v88
	v_rcp_f32_e32 v90, v90
	v_rcp_f32_e32 v91, v91
	v_rcp_f32_e32 v89, v89
	v_pk_mul_f32 v[90:91], v[90:91], s[6:7] op_sel_hi:[1,0]
	v_pk_mul_f32 v[88:89], v[88:89], s[6:7] op_sel_hi:[1,0]
	s_nop 0
	v_cvt_pk_bf16_f32 v88, v88, v89
	v_cvt_pk_bf16_f32 v89, v90, v91
	global_store_dwordx2 v[96:97], v[88:89], off offset:32
	global_load_dwordx4 v[88:91], v[116:117], off offset:128
	s_waitcnt vmcnt(0)
	v_add_f32_e32 v84, v84, v88
	v_add_f32_e32 v85, v85, v89
	v_add_f32_e32 v86, v86, v90
	v_add_f32_e32 v87, v87, v91
	v_mul_f32_e32 v84, 0xbfb8aa3b, v84
	v_mul_f32_e32 v85, 0xbfb8aa3b, v85
	v_mul_f32_e32 v86, 0xbfb8aa3b, v86
	v_mul_f32_e32 v87, 0xbfb8aa3b, v87
	v_exp_f32_e32 v84, v84
	v_exp_f32_e32 v85, v85
	v_exp_f32_e32 v86, v86
	v_exp_f32_e32 v87, v87
	v_add_f32_e32 v84, 1.0, v84
	v_add_f32_e32 v85, 1.0, v85
	v_add_f32_e32 v86, 1.0, v86
	v_add_f32_e32 v87, 1.0, v87
	v_rcp_f32_e32 v84, v84
	v_rcp_f32_e32 v86, v86
	v_rcp_f32_e32 v87, v87
	v_rcp_f32_e32 v85, v85
	v_pk_mul_f32 v[86:87], v[86:87], s[6:7] op_sel_hi:[1,0]
	v_pk_mul_f32 v[84:85], v[84:85], s[6:7] op_sel_hi:[1,0]
	s_nop 0
	v_cvt_pk_bf16_f32 v84, v84, v85
	v_cvt_pk_bf16_f32 v85, v86, v87
	global_store_dwordx2 v[96:97], v[84:85], off offset:64
	global_load_dwordx4 v[84:87], v[116:117], off offset:192
	s_waitcnt vmcnt(0)
	v_add_f32_e32 v80, v80, v84
	v_add_f32_e32 v81, v81, v85
	v_add_f32_e32 v82, v82, v86
	v_add_f32_e32 v83, v83, v87
	v_mul_f32_e32 v80, 0xbfb8aa3b, v80
	v_mul_f32_e32 v81, 0xbfb8aa3b, v81
	v_mul_f32_e32 v82, 0xbfb8aa3b, v82
	v_mul_f32_e32 v83, 0xbfb8aa3b, v83
	v_exp_f32_e32 v80, v80
	v_exp_f32_e32 v81, v81
	v_exp_f32_e32 v82, v82
	v_exp_f32_e32 v83, v83
	v_add_f32_e32 v80, 1.0, v80
	v_add_f32_e32 v81, 1.0, v81
	v_add_f32_e32 v82, 1.0, v82
	v_add_f32_e32 v83, 1.0, v83
	v_rcp_f32_e32 v80, v80
	v_rcp_f32_e32 v82, v82
	v_rcp_f32_e32 v83, v83
	v_rcp_f32_e32 v81, v81
	v_or_b32_e32 v84, 48, v120
	v_ashrrev_i32_e32 v85, 31, v84
	v_pk_mul_f32 v[82:83], v[82:83], s[6:7] op_sel_hi:[1,0]
	v_pk_mul_f32 v[80:81], v[80:81], s[6:7] op_sel_hi:[1,0]
	v_lshlrev_b64 v[84:85], 10, v[84:85]
	v_cvt_pk_bf16_f32 v80, v80, v81
	v_cvt_pk_bf16_f32 v81, v82, v83
	global_store_dwordx2 v[96:97], v[80:81], off offset:96
	global_load_dwordx4 v[80:83], v[116:117], off
	s_waitcnt vmcnt(0)
	v_add_f32_e32 v76, v76, v80
	v_add_f32_e32 v77, v77, v81
	v_add_f32_e32 v78, v78, v82
	v_add_f32_e32 v79, v79, v83
	v_mul_f32_e32 v76, 0xbfb8aa3b, v76
	v_mul_f32_e32 v77, 0xbfb8aa3b, v77
	v_mul_f32_e32 v78, 0xbfb8aa3b, v78
	v_mul_f32_e32 v79, 0xbfb8aa3b, v79
	v_exp_f32_e32 v76, v76
	v_exp_f32_e32 v77, v77
	v_exp_f32_e32 v78, v78
	v_exp_f32_e32 v79, v79
	v_add_f32_e32 v76, 1.0, v76
	v_add_f32_e32 v77, 1.0, v77
	v_add_f32_e32 v78, 1.0, v78
	v_add_f32_e32 v79, 1.0, v79
	v_rcp_f32_e32 v76, v76
	v_rcp_f32_e32 v78, v78
	v_rcp_f32_e32 v79, v79
	v_rcp_f32_e32 v77, v77
	v_lshl_add_u64 v[80:81], s[0:1], 0, v[84:85]
	v_lshl_add_u64 v[80:81], v[80:81], 0, v[118:119]
	v_pk_mul_f32 v[78:79], v[78:79], s[6:7] op_sel_hi:[1,0]
	v_pk_mul_f32 v[76:77], v[76:77], s[6:7] op_sel_hi:[1,0]
	s_nop 0
	v_cvt_pk_bf16_f32 v76, v76, v77
	v_cvt_pk_bf16_f32 v77, v78, v79
	global_store_dwordx2 v[80:81], v[76:77], off
	global_load_dwordx4 v[76:79], v[116:117], off offset:64
	s_waitcnt vmcnt(0)
	v_add_f32_e32 v72, v72, v76
	v_add_f32_e32 v73, v73, v77
	v_add_f32_e32 v74, v74, v78
	v_add_f32_e32 v75, v75, v79
	v_mul_f32_e32 v72, 0xbfb8aa3b, v72
	v_mul_f32_e32 v73, 0xbfb8aa3b, v73
	v_mul_f32_e32 v74, 0xbfb8aa3b, v74
	v_mul_f32_e32 v75, 0xbfb8aa3b, v75
	v_exp_f32_e32 v72, v72
	v_exp_f32_e32 v73, v73
	v_exp_f32_e32 v74, v74
	v_exp_f32_e32 v75, v75
	v_add_f32_e32 v72, 1.0, v72
	v_add_f32_e32 v73, 1.0, v73
	v_add_f32_e32 v74, 1.0, v74
	v_add_f32_e32 v75, 1.0, v75
	v_rcp_f32_e32 v72, v72
	v_rcp_f32_e32 v74, v74
	v_rcp_f32_e32 v75, v75
	v_rcp_f32_e32 v73, v73
	v_pk_mul_f32 v[74:75], v[74:75], s[6:7] op_sel_hi:[1,0]
	v_pk_mul_f32 v[72:73], v[72:73], s[6:7] op_sel_hi:[1,0]
	s_nop 0
	v_cvt_pk_bf16_f32 v72, v72, v73
	v_cvt_pk_bf16_f32 v73, v74, v75
	global_store_dwordx2 v[80:81], v[72:73], off offset:32
	global_load_dwordx4 v[72:75], v[116:117], off offset:128
	s_waitcnt vmcnt(0)
; template <class Epi>
; DI void gemm_tile(char* smem, const bf16_t* __restrict__ A0, int lda0, int ksplit, const bf16_t* __restrict__ A1, int lda1,
;                   const bf16_t* __restrict__ Bt, int K, int row0, int col0, const Epi& epi, int tid) {
;     ...
;   for (int m = 0; m < 8; ++m)
; #pragma unroll
;     for (int n = 0; n < 4; ++n) epi(row0 + wr * 128 + m * 16 + fr, col0 + wc * 64 + n * 16 + fq * 4, acc[m][n]);
	v_add_f32_e32 v68, v68, v72
	v_add_f32_e32 v69, v69, v73
	v_add_f32_e32 v70, v70, v74
	v_add_f32_e32 v71, v71, v75
	v_mul_f32_e32 v68, 0xbfb8aa3b, v68
	v_mul_f32_e32 v69, 0xbfb8aa3b, v69
	v_mul_f32_e32 v70, 0xbfb8aa3b, v70
	v_mul_f32_e32 v71, 0xbfb8aa3b, v71
	v_exp_f32_e32 v68, v68
	v_exp_f32_e32 v69, v69
	v_exp_f32_e32 v70, v70
	v_exp_f32_e32 v71, v71
	v_add_f32_e32 v68, 1.0, v68
	v_add_f32_e32 v69, 1.0, v69
	v_add_f32_e32 v70, 1.0, v70
	v_add_f32_e32 v71, 1.0, v71
	v_rcp_f32_e32 v68, v68
	v_rcp_f32_e32 v70, v70
	v_rcp_f32_e32 v71, v71
	v_rcp_f32_e32 v69, v69
	v_pk_mul_f32 v[70:71], v[70:71], s[6:7] op_sel_hi:[1,0]
	v_pk_mul_f32 v[68:69], v[68:69], s[6:7] op_sel_hi:[1,0]
	s_nop 0
	v_cvt_pk_bf16_f32 v68, v68, v69
	v_cvt_pk_bf16_f32 v69, v70, v71
	global_store_dwordx2 v[80:81], v[68:69], off offset:64
	global_load_dwordx4 v[68:71], v[116:117], off offset:192
	s_waitcnt vmcnt(0)
	v_add_f32_e32 v64, v64, v68
	v_add_f32_e32 v65, v65, v69
	v_add_f32_e32 v66, v66, v70
	v_add_f32_e32 v67, v67, v71
	v_mul_f32_e32 v64, 0xbfb8aa3b, v64
	v_mul_f32_e32 v65, 0xbfb8aa3b, v65
	v_mul_f32_e32 v66, 0xbfb8aa3b, v66
	v_mul_f32_e32 v67, 0xbfb8aa3b, v67
	v_exp_f32_e32 v64, v64
	v_exp_f32_e32 v65, v65
	v_exp_f32_e32 v66, v66
	v_exp_f32_e32 v67, v67
	v_add_f32_e32 v64, 1.0, v64
	v_add_f32_e32 v65, 1.0, v65
	v_add_f32_e32 v66, 1.0, v66
	v_add_f32_e32 v67, 1.0, v67
	v_rcp_f32_e32 v64, v64
	v_rcp_f32_e32 v66, v66
	v_rcp_f32_e32 v67, v67
	v_rcp_f32_e32 v65, v65
	v_or_b32_e32 v68, 64, v120
	v_ashrrev_i32_e32 v69, 31, v68
	v_pk_mul_f32 v[66:67], v[66:67], s[6:7] op_sel_hi:[1,0]
	v_pk_mul_f32 v[64:65], v[64:65], s[6:7] op_sel_hi:[1,0]
	v_lshlrev_b64 v[68:69], 10, v[68:69]
	v_cvt_pk_bf16_f32 v64, v64, v65
	v_cvt_pk_bf16_f32 v65, v66, v67
	global_store_dwordx2 v[80:81], v[64:65], off offset:96
	global_load_dwordx4 v[64:67], v[116:117], off
	s_waitcnt vmcnt(0)
	v_add_f32_e32 v60, v60, v64
	v_add_f32_e32 v61, v61, v65
	v_add_f32_e32 v62, v62, v66
	v_add_f32_e32 v63, v63, v67
	v_mul_f32_e32 v60, 0xbfb8aa3b, v60
	v_mul_f32_e32 v61, 0xbfb8aa3b, v61
	v_mul_f32_e32 v62, 0xbfb8aa3b, v62
	v_mul_f32_e32 v63, 0xbfb8aa3b, v63
	v_exp_f32_e32 v60, v60
	v_exp_f32_e32 v61, v61
	v_exp_f32_e32 v62, v62
	v_exp_f32_e32 v63, v63
	v_add_f32_e32 v60, 1.0, v60
	v_add_f32_e32 v61, 1.0, v61
	v_add_f32_e32 v62, 1.0, v62
	v_add_f32_e32 v63, 1.0, v63
	v_rcp_f32_e32 v60, v60
	v_rcp_f32_e32 v62, v62
	v_rcp_f32_e32 v63, v63
	v_rcp_f32_e32 v61, v61
	v_lshl_add_u64 v[64:65], s[0:1], 0, v[68:69]
	v_lshl_add_u64 v[64:65], v[64:65], 0, v[118:119]
	v_pk_mul_f32 v[62:63], v[62:63], s[6:7] op_sel_hi:[1,0]
	v_pk_mul_f32 v[60:61], v[60:61], s[6:7] op_sel_hi:[1,0]
	s_nop 0
	v_cvt_pk_bf16_f32 v60, v60, v61
	v_cvt_pk_bf16_f32 v61, v62, v63
	global_store_dwordx2 v[64:65], v[60:61], off
	global_load_dwordx4 v[60:63], v[116:117], off offset:64
	s_waitcnt vmcnt(0)
	v_add_f32_e32 v56, v56, v60
	v_add_f32_e32 v57, v57, v61
	v_add_f32_e32 v58, v58, v62
	v_add_f32_e32 v59, v59, v63
	v_mul_f32_e32 v56, 0xbfb8aa3b, v56
	v_mul_f32_e32 v57, 0xbfb8aa3b, v57
	v_mul_f32_e32 v58, 0xbfb8aa3b, v58
	v_mul_f32_e32 v59, 0xbfb8aa3b, v59
	v_exp_f32_e32 v56, v56
	v_exp_f32_e32 v57, v57
	v_exp_f32_e32 v58, v58
	v_exp_f32_e32 v59, v59
	v_add_f32_e32 v56, 1.0, v56
	v_add_f32_e32 v57, 1.0, v57
	v_add_f32_e32 v58, 1.0, v58
	v_add_f32_e32 v59, 1.0, v59
	v_rcp_f32_e32 v56, v56
	v_rcp_f32_e32 v58, v58
	v_rcp_f32_e32 v59, v59
	v_rcp_f32_e32 v57, v57
	v_pk_mul_f32 v[58:59], v[58:59], s[6:7] op_sel_hi:[1,0]
	v_pk_mul_f32 v[56:57], v[56:57], s[6:7] op_sel_hi:[1,0]
	s_nop 0
	v_cvt_pk_bf16_f32 v56, v56, v57
	v_cvt_pk_bf16_f32 v57, v58, v59
	global_store_dwordx2 v[64:65], v[56:57], off offset:32
	global_load_dwordx4 v[56:59], v[116:117], off offset:128
	s_waitcnt vmcnt(0)
	v_add_f32_e32 v52, v52, v56
	v_add_f32_e32 v53, v53, v57
	v_add_f32_e32 v54, v54, v58
	v_add_f32_e32 v55, v55, v59
	v_mul_f32_e32 v52, 0xbfb8aa3b, v52
	v_mul_f32_e32 v53, 0xbfb8aa3b, v53
	v_mul_f32_e32 v54, 0xbfb8aa3b, v54
	v_mul_f32_e32 v55, 0xbfb8aa3b, v55
	v_exp_f32_e32 v52, v52
	v_exp_f32_e32 v53, v53
	v_exp_f32_e32 v54, v54
	v_exp_f32_e32 v55, v55
	v_add_f32_e32 v52, 1.0, v52
	v_add_f32_e32 v53, 1.0, v53
	v_add_f32_e32 v54, 1.0, v54
	v_add_f32_e32 v55, 1.0, v55
	v_rcp_f32_e32 v52, v52
	v_rcp_f32_e32 v54, v54
	v_rcp_f32_e32 v55, v55
	v_rcp_f32_e32 v53, v53
	v_pk_mul_f32 v[54:55], v[54:55], s[6:7] op_sel_hi:[1,0]
	v_pk_mul_f32 v[52:53], v[52:53], s[6:7] op_sel_hi:[1,0]
	s_nop 0
	v_cvt_pk_bf16_f32 v52, v52, v53
	v_cvt_pk_bf16_f32 v53, v54, v55
	global_store_dwordx2 v[64:65], v[52:53], off offset:64
	global_load_dwordx4 v[52:55], v[116:117], off offset:192
	s_waitcnt vmcnt(0)
	v_add_f32_e32 v48, v48, v52
	v_add_f32_e32 v49, v49, v53
	v_add_f32_e32 v50, v50, v54
	v_add_f32_e32 v51, v51, v55
	v_mul_f32_e32 v48, 0xbfb8aa3b, v48
	v_mul_f32_e32 v49, 0xbfb8aa3b, v49
	v_mul_f32_e32 v50, 0xbfb8aa3b, v50
	v_mul_f32_e32 v51, 0xbfb8aa3b, v51
	v_exp_f32_e32 v48, v48
	v_exp_f32_e32 v49, v49
	v_exp_f32_e32 v50, v50
	v_exp_f32_e32 v51, v51
	v_add_f32_e32 v48, 1.0, v48
	v_add_f32_e32 v49, 1.0, v49
	v_add_f32_e32 v50, 1.0, v50
	v_add_f32_e32 v51, 1.0, v51
	v_rcp_f32_e32 v48, v48
	v_rcp_f32_e32 v50, v50
	v_rcp_f32_e32 v51, v51
	v_rcp_f32_e32 v49, v49
	v_or_b32_e32 v52, 0x50, v120
	v_ashrrev_i32_e32 v53, 31, v52
	v_pk_mul_f32 v[50:51], v[50:51], s[6:7] op_sel_hi:[1,0]
	v_pk_mul_f32 v[48:49], v[48:49], s[6:7] op_sel_hi:[1,0]
	v_lshlrev_b64 v[52:53], 10, v[52:53]
	v_cvt_pk_bf16_f32 v48, v48, v49
	v_cvt_pk_bf16_f32 v49, v50, v51
	global_store_dwordx2 v[64:65], v[48:49], off offset:96
	global_load_dwordx4 v[48:51], v[116:117], off
	s_waitcnt vmcnt(0)
; template <class Epi>
; DI void gemm_tile(char* smem, const bf16_t* __restrict__ A0, int lda0, int ksplit, const bf16_t* __restrict__ A1, int lda1,
;                   const bf16_t* __restrict__ Bt, int K, int row0, int col0, const Epi& epi, int tid) {
;     ...
;   for (int m = 0; m < 8; ++m)
; #pragma unroll
;     for (int n = 0; n < 4; ++n) epi(row0 + wr * 128 + m * 16 + fr, col0 + wc * 64 + n * 16 + fq * 4, acc[m][n]);
	v_add_f32_e32 v44, v44, v48
	v_add_f32_e32 v45, v45, v49
	v_add_f32_e32 v46, v46, v50
	v_add_f32_e32 v47, v47, v51
	v_mul_f32_e32 v44, 0xbfb8aa3b, v44
	v_mul_f32_e32 v45, 0xbfb8aa3b, v45
	v_mul_f32_e32 v46, 0xbfb8aa3b, v46
	v_mul_f32_e32 v47, 0xbfb8aa3b, v47
	v_exp_f32_e32 v44, v44
	v_exp_f32_e32 v45, v45
	v_exp_f32_e32 v46, v46
	v_exp_f32_e32 v47, v47
	v_add_f32_e32 v44, 1.0, v44
	v_add_f32_e32 v45, 1.0, v45
	v_add_f32_e32 v46, 1.0, v46
	v_add_f32_e32 v47, 1.0, v47
	v_rcp_f32_e32 v44, v44
	v_rcp_f32_e32 v46, v46
	v_rcp_f32_e32 v47, v47
	v_rcp_f32_e32 v45, v45
	v_lshl_add_u64 v[48:49], s[0:1], 0, v[52:53]
	v_lshl_add_u64 v[48:49], v[48:49], 0, v[118:119]
	v_pk_mul_f32 v[46:47], v[46:47], s[6:7] op_sel_hi:[1,0]
	v_pk_mul_f32 v[44:45], v[44:45], s[6:7] op_sel_hi:[1,0]
	s_nop 0
	v_cvt_pk_bf16_f32 v44, v44, v45
	v_cvt_pk_bf16_f32 v45, v46, v47
	global_store_dwordx2 v[48:49], v[44:45], off
	global_load_dwordx4 v[44:47], v[116:117], off offset:64
	s_waitcnt vmcnt(0)
	v_add_f32_e32 v40, v40, v44
	v_add_f32_e32 v41, v41, v45
	v_add_f32_e32 v42, v42, v46
	v_add_f32_e32 v43, v43, v47
	v_mul_f32_e32 v40, 0xbfb8aa3b, v40
	v_mul_f32_e32 v41, 0xbfb8aa3b, v41
	v_mul_f32_e32 v42, 0xbfb8aa3b, v42
	v_mul_f32_e32 v43, 0xbfb8aa3b, v43
	v_exp_f32_e32 v40, v40
	v_exp_f32_e32 v41, v41
	v_exp_f32_e32 v42, v42
	v_exp_f32_e32 v43, v43
	v_add_f32_e32 v40, 1.0, v40
	v_add_f32_e32 v41, 1.0, v41
	v_add_f32_e32 v42, 1.0, v42
	v_add_f32_e32 v43, 1.0, v43
	v_rcp_f32_e32 v40, v40
	v_rcp_f32_e32 v42, v42
	v_rcp_f32_e32 v43, v43
	v_rcp_f32_e32 v41, v41
	v_pk_mul_f32 v[42:43], v[42:43], s[6:7] op_sel_hi:[1,0]
	v_pk_mul_f32 v[40:41], v[40:41], s[6:7] op_sel_hi:[1,0]
	s_nop 0
	v_cvt_pk_bf16_f32 v40, v40, v41
	v_cvt_pk_bf16_f32 v41, v42, v43
	global_store_dwordx2 v[48:49], v[40:41], off offset:32
	global_load_dwordx4 v[40:43], v[116:117], off offset:128
	s_waitcnt vmcnt(0)
	v_add_f32_e32 v36, v36, v40
	v_add_f32_e32 v37, v37, v41
	v_add_f32_e32 v38, v38, v42
	v_add_f32_e32 v39, v39, v43
	v_mul_f32_e32 v36, 0xbfb8aa3b, v36
	v_mul_f32_e32 v37, 0xbfb8aa3b, v37
	v_mul_f32_e32 v38, 0xbfb8aa3b, v38
	v_mul_f32_e32 v39, 0xbfb8aa3b, v39
	v_exp_f32_e32 v36, v36
	v_exp_f32_e32 v37, v37
	v_exp_f32_e32 v38, v38
	v_exp_f32_e32 v39, v39
	v_add_f32_e32 v36, 1.0, v36
	v_add_f32_e32 v37, 1.0, v37
	v_add_f32_e32 v38, 1.0, v38
	v_add_f32_e32 v39, 1.0, v39
	v_rcp_f32_e32 v36, v36
	v_rcp_f32_e32 v38, v38
	v_rcp_f32_e32 v39, v39
	v_rcp_f32_e32 v37, v37
	v_pk_mul_f32 v[38:39], v[38:39], s[6:7] op_sel_hi:[1,0]
	v_pk_mul_f32 v[36:37], v[36:37], s[6:7] op_sel_hi:[1,0]
	s_nop 0
	v_cvt_pk_bf16_f32 v36, v36, v37
	v_cvt_pk_bf16_f32 v37, v38, v39
	global_store_dwordx2 v[48:49], v[36:37], off offset:64
	global_load_dwordx4 v[36:39], v[116:117], off offset:192
	s_waitcnt vmcnt(0)
	v_add_f32_e32 v32, v32, v36
	v_add_f32_e32 v33, v33, v37
	v_add_f32_e32 v34, v34, v38
	v_add_f32_e32 v35, v35, v39
	v_mul_f32_e32 v32, 0xbfb8aa3b, v32
	v_mul_f32_e32 v33, 0xbfb8aa3b, v33
	v_mul_f32_e32 v34, 0xbfb8aa3b, v34
	v_mul_f32_e32 v35, 0xbfb8aa3b, v35
	v_exp_f32_e32 v32, v32
	v_exp_f32_e32 v33, v33
	v_exp_f32_e32 v34, v34
	v_exp_f32_e32 v35, v35
	v_add_f32_e32 v32, 1.0, v32
	v_add_f32_e32 v33, 1.0, v33
	v_add_f32_e32 v34, 1.0, v34
	v_add_f32_e32 v35, 1.0, v35
	v_rcp_f32_e32 v32, v32
	v_rcp_f32_e32 v34, v34
	v_rcp_f32_e32 v35, v35
	v_rcp_f32_e32 v33, v33
	v_or_b32_e32 v36, 0x60, v120
	v_ashrrev_i32_e32 v37, 31, v36
	v_pk_mul_f32 v[34:35], v[34:35], s[6:7] op_sel_hi:[1,0]
	v_pk_mul_f32 v[32:33], v[32:33], s[6:7] op_sel_hi:[1,0]
	v_lshlrev_b64 v[36:37], 10, v[36:37]
	v_cvt_pk_bf16_f32 v32, v32, v33
	v_cvt_pk_bf16_f32 v33, v34, v35
	global_store_dwordx2 v[48:49], v[32:33], off offset:96
	global_load_dwordx4 v[32:35], v[116:117], off
	s_waitcnt vmcnt(0)
	v_add_f32_e32 v28, v28, v32
	v_add_f32_e32 v29, v29, v33
	v_add_f32_e32 v30, v30, v34
	v_add_f32_e32 v31, v31, v35
	v_mul_f32_e32 v28, 0xbfb8aa3b, v28
	v_mul_f32_e32 v29, 0xbfb8aa3b, v29
	v_mul_f32_e32 v30, 0xbfb8aa3b, v30
	v_mul_f32_e32 v31, 0xbfb8aa3b, v31
	v_exp_f32_e32 v28, v28
	v_exp_f32_e32 v29, v29
	v_exp_f32_e32 v30, v30
	v_exp_f32_e32 v31, v31
	v_add_f32_e32 v28, 1.0, v28
	v_add_f32_e32 v29, 1.0, v29
	v_add_f32_e32 v30, 1.0, v30
	v_add_f32_e32 v31, 1.0, v31
	v_rcp_f32_e32 v28, v28
	v_rcp_f32_e32 v30, v30
	v_rcp_f32_e32 v31, v31
	v_rcp_f32_e32 v29, v29
	v_lshl_add_u64 v[32:33], s[0:1], 0, v[36:37]
	v_lshl_add_u64 v[32:33], v[32:33], 0, v[118:119]
	v_pk_mul_f32 v[30:31], v[30:31], s[6:7] op_sel_hi:[1,0]
	v_pk_mul_f32 v[28:29], v[28:29], s[6:7] op_sel_hi:[1,0]
	s_nop 0
	v_cvt_pk_bf16_f32 v28, v28, v29
	v_cvt_pk_bf16_f32 v29, v30, v31
	global_store_dwordx2 v[32:33], v[28:29], off
	global_load_dwordx4 v[28:31], v[116:117], off offset:64
	s_waitcnt vmcnt(0)
	v_add_f32_e32 v24, v24, v28
	v_add_f32_e32 v25, v25, v29
	v_add_f32_e32 v26, v26, v30
	v_add_f32_e32 v27, v27, v31
	v_mul_f32_e32 v24, 0xbfb8aa3b, v24
	v_mul_f32_e32 v25, 0xbfb8aa3b, v25
	v_mul_f32_e32 v26, 0xbfb8aa3b, v26
	v_mul_f32_e32 v27, 0xbfb8aa3b, v27
	v_exp_f32_e32 v24, v24
	v_exp_f32_e32 v25, v25
	v_exp_f32_e32 v26, v26
	v_exp_f32_e32 v27, v27
	v_add_f32_e32 v24, 1.0, v24
	v_add_f32_e32 v25, 1.0, v25
	v_add_f32_e32 v26, 1.0, v26
	v_add_f32_e32 v27, 1.0, v27
	v_rcp_f32_e32 v24, v24
	v_rcp_f32_e32 v26, v26
	v_rcp_f32_e32 v27, v27
	v_rcp_f32_e32 v25, v25
	v_pk_mul_f32 v[26:27], v[26:27], s[6:7] op_sel_hi:[1,0]
	v_pk_mul_f32 v[24:25], v[24:25], s[6:7] op_sel_hi:[1,0]
	s_nop 0
	v_cvt_pk_bf16_f32 v24, v24, v25
	v_cvt_pk_bf16_f32 v25, v26, v27
	global_store_dwordx2 v[32:33], v[24:25], off offset:32
	global_load_dwordx4 v[24:27], v[116:117], off offset:128
	s_waitcnt vmcnt(0)
; template <class Epi>
; DI void gemm_tile(char* smem, const bf16_t* __restrict__ A0, int lda0, int ksplit, const bf16_t* __restrict__ A1, int lda1,
;                   const bf16_t* __restrict__ Bt, int K, int row0, int col0, const Epi& epi, int tid) {
;     ...
; #pragma unroll
;   for (int m = 0; m < 8; ++m)
; #pragma unroll
;     for (int n = 0; n < 4; ++n) epi(row0 + wr * 128 + m * 16 + fr, col0 + wc * 64 + n * 16 + fq * 4, acc[m][n]);
	v_add_f32_e32 v20, v20, v24
	v_add_f32_e32 v21, v21, v25
	v_add_f32_e32 v22, v22, v26
	v_add_f32_e32 v23, v23, v27
	v_mul_f32_e32 v20, 0xbfb8aa3b, v20
	v_mul_f32_e32 v21, 0xbfb8aa3b, v21
	v_mul_f32_e32 v22, 0xbfb8aa3b, v22
	v_mul_f32_e32 v23, 0xbfb8aa3b, v23
	v_exp_f32_e32 v20, v20
	v_exp_f32_e32 v21, v21
	v_exp_f32_e32 v22, v22
	v_exp_f32_e32 v23, v23
	v_add_f32_e32 v20, 1.0, v20
	v_add_f32_e32 v21, 1.0, v21
	v_add_f32_e32 v22, 1.0, v22
	v_add_f32_e32 v23, 1.0, v23
	v_rcp_f32_e32 v20, v20
	v_rcp_f32_e32 v22, v22
	v_rcp_f32_e32 v23, v23
	v_rcp_f32_e32 v21, v21
	v_pk_mul_f32 v[22:23], v[22:23], s[6:7] op_sel_hi:[1,0]
	v_pk_mul_f32 v[20:21], v[20:21], s[6:7] op_sel_hi:[1,0]
	s_nop 0
	v_cvt_pk_bf16_f32 v20, v20, v21
	v_cvt_pk_bf16_f32 v21, v22, v23
	global_store_dwordx2 v[32:33], v[20:21], off offset:64
	global_load_dwordx4 v[20:23], v[116:117], off offset:192
	s_waitcnt vmcnt(0)
	v_add_f32_e32 v16, v16, v20
	v_add_f32_e32 v17, v17, v21
	v_add_f32_e32 v18, v18, v22
	v_add_f32_e32 v19, v19, v23
	v_mul_f32_e32 v16, 0xbfb8aa3b, v16
	v_mul_f32_e32 v17, 0xbfb8aa3b, v17
	v_mul_f32_e32 v18, 0xbfb8aa3b, v18
	v_mul_f32_e32 v19, 0xbfb8aa3b, v19
	v_exp_f32_e32 v16, v16
	v_exp_f32_e32 v17, v17
	v_exp_f32_e32 v18, v18
	v_exp_f32_e32 v19, v19
	v_add_f32_e32 v16, 1.0, v16
	v_add_f32_e32 v17, 1.0, v17
	v_add_f32_e32 v18, 1.0, v18
	v_add_f32_e32 v19, 1.0, v19
	v_rcp_f32_e32 v16, v16
	v_rcp_f32_e32 v18, v18
	v_rcp_f32_e32 v19, v19
	v_rcp_f32_e32 v17, v17
	v_or_b32_e32 v20, 0x70, v120
	v_ashrrev_i32_e32 v21, 31, v20
	v_pk_mul_f32 v[18:19], v[18:19], s[6:7] op_sel_hi:[1,0]
	v_pk_mul_f32 v[16:17], v[16:17], s[6:7] op_sel_hi:[1,0]
	v_lshlrev_b64 v[20:21], 10, v[20:21]
	v_cvt_pk_bf16_f32 v16, v16, v17
	v_cvt_pk_bf16_f32 v17, v18, v19
	global_store_dwordx2 v[32:33], v[16:17], off offset:96
	global_load_dwordx4 v[16:19], v[116:117], off
	s_waitcnt vmcnt(0)
	v_add_f32_e32 v12, v12, v16
	v_add_f32_e32 v13, v13, v17
	v_add_f32_e32 v14, v14, v18
	v_add_f32_e32 v15, v15, v19
	v_mul_f32_e32 v12, 0xbfb8aa3b, v12
	v_mul_f32_e32 v13, 0xbfb8aa3b, v13
	v_mul_f32_e32 v14, 0xbfb8aa3b, v14
	v_mul_f32_e32 v15, 0xbfb8aa3b, v15
	v_exp_f32_e32 v12, v12
	v_exp_f32_e32 v13, v13
	v_exp_f32_e32 v14, v14
	v_exp_f32_e32 v15, v15
	v_add_f32_e32 v12, 1.0, v12
	v_add_f32_e32 v13, 1.0, v13
	v_add_f32_e32 v14, 1.0, v14
	v_add_f32_e32 v15, 1.0, v15
	v_rcp_f32_e32 v12, v12
	v_rcp_f32_e32 v14, v14
	v_rcp_f32_e32 v15, v15
	v_rcp_f32_e32 v13, v13
	v_lshl_add_u64 v[16:17], s[0:1], 0, v[20:21]
	v_lshl_add_u64 v[16:17], v[16:17], 0, v[118:119]
	v_pk_mul_f32 v[14:15], v[14:15], s[6:7] op_sel_hi:[1,0]
	v_pk_mul_f32 v[12:13], v[12:13], s[6:7] op_sel_hi:[1,0]
	s_nop 0
	v_cvt_pk_bf16_f32 v12, v12, v13
	v_cvt_pk_bf16_f32 v13, v14, v15
	global_store_dwordx2 v[16:17], v[12:13], off
	global_load_dwordx4 v[12:15], v[116:117], off offset:64
	s_waitcnt vmcnt(0)
	v_add_f32_e32 v8, v8, v12
	v_add_f32_e32 v9, v9, v13
	v_add_f32_e32 v10, v10, v14
	v_add_f32_e32 v11, v11, v15
	v_mul_f32_e32 v8, 0xbfb8aa3b, v8
	v_mul_f32_e32 v9, 0xbfb8aa3b, v9
	v_mul_f32_e32 v10, 0xbfb8aa3b, v10
	v_mul_f32_e32 v11, 0xbfb8aa3b, v11
	v_exp_f32_e32 v8, v8
	v_exp_f32_e32 v9, v9
	v_exp_f32_e32 v10, v10
	v_exp_f32_e32 v11, v11
	v_add_f32_e32 v8, 1.0, v8
	v_add_f32_e32 v9, 1.0, v9
	v_add_f32_e32 v10, 1.0, v10
	v_add_f32_e32 v11, 1.0, v11
	v_rcp_f32_e32 v8, v8
	v_rcp_f32_e32 v10, v10
	v_rcp_f32_e32 v11, v11
	v_rcp_f32_e32 v9, v9
	v_pk_mul_f32 v[10:11], v[10:11], s[6:7] op_sel_hi:[1,0]
	v_pk_mul_f32 v[8:9], v[8:9], s[6:7] op_sel_hi:[1,0]
	s_nop 0
	v_cvt_pk_bf16_f32 v8, v8, v9
	v_cvt_pk_bf16_f32 v9, v10, v11
	global_store_dwordx2 v[16:17], v[8:9], off offset:32
	global_load_dwordx4 v[8:11], v[116:117], off offset:128
	s_waitcnt vmcnt(0)
	v_add_f32_e32 v4, v4, v8
	v_add_f32_e32 v5, v5, v9
	v_add_f32_e32 v6, v6, v10
	v_add_f32_e32 v7, v7, v11
	v_mul_f32_e32 v4, 0xbfb8aa3b, v4
	v_mul_f32_e32 v5, 0xbfb8aa3b, v5
	v_mul_f32_e32 v6, 0xbfb8aa3b, v6
	v_mul_f32_e32 v7, 0xbfb8aa3b, v7
	v_exp_f32_e32 v4, v4
	v_exp_f32_e32 v5, v5
	v_exp_f32_e32 v6, v6
	v_exp_f32_e32 v7, v7
	v_add_f32_e32 v4, 1.0, v4
	v_add_f32_e32 v5, 1.0, v5
	v_add_f32_e32 v6, 1.0, v6
	v_add_f32_e32 v7, 1.0, v7
	v_rcp_f32_e32 v4, v4
	v_rcp_f32_e32 v6, v6
	v_rcp_f32_e32 v7, v7
	v_rcp_f32_e32 v5, v5
	v_pk_mul_f32 v[6:7], v[6:7], s[6:7] op_sel_hi:[1,0]
	v_pk_mul_f32 v[4:5], v[4:5], s[6:7] op_sel_hi:[1,0]
	s_add_i32 s7, s7, s11
	v_cvt_pk_bf16_f32 v4, v4, v5
	v_cvt_pk_bf16_f32 v5, v6, v7
	global_store_dwordx2 v[16:17], v[4:5], off offset:64
	global_load_dwordx4 v[4:7], v[116:117], off offset:192
	s_cmp_gt_i32 s9, 63
	s_waitcnt vmcnt(0)
	v_add_f32_e32 v0, v0, v4
	v_add_f32_e32 v1, v1, v5
	v_add_f32_e32 v2, v2, v6
	v_add_f32_e32 v3, v3, v7
	v_mul_f32_e32 v0, 0xbfb8aa3b, v0
	v_mul_f32_e32 v1, 0xbfb8aa3b, v1
	v_mul_f32_e32 v2, 0xbfb8aa3b, v2
	v_mul_f32_e32 v3, 0xbfb8aa3b, v3
	v_exp_f32_e32 v0, v0
	v_exp_f32_e32 v1, v1
	v_exp_f32_e32 v2, v2
	v_exp_f32_e32 v3, v3
	v_add_f32_e32 v0, 1.0, v0
	v_add_f32_e32 v1, 1.0, v1
	v_add_f32_e32 v2, 1.0, v2
	v_add_f32_e32 v3, 1.0, v3
	v_rcp_f32_e32 v0, v0
	v_rcp_f32_e32 v2, v2
	v_rcp_f32_e32 v3, v3
	v_rcp_f32_e32 v1, v1
	v_pk_mul_f32 v[2:3], v[2:3], s[6:7] op_sel_hi:[1,0]
	v_pk_mul_f32 v[0:1], v[0:1], s[6:7] op_sel_hi:[1,0]
	s_nop 0
	v_cvt_pk_bf16_f32 v0, v0, v1
	v_cvt_pk_bf16_f32 v1, v2, v3
	global_store_dwordx2 v[16:17], v[0:1], off offset:96
	s_cbranch_scc0 .LBB0_558
; #define LWRITE(S, buf) do { bf16_t* sA_ = sbase + (buf) * BUF; bf16_t* sB_ = sA_ + 256 * PITCH; \
;     _Pragma("unroll") for (int i_ = 0; i_ < 4; ++i_) *(u32x4*)(sA_ + (sr + i_ * 64) * PITCH + scv * 8) = ra[S][i_]; \
;     _Pragma("unroll") for (int i_ = 0; i_ < 2; ++i_) *(u32x4*)(sB_ + (sr + i_ * 64) * PITCH + scv * 8) = rb[S][i_]; } while (0)
; template <class Epi>
; DI void gemm_tile(char* smem, const bf16_t* __restrict__ A0, int lda0, int ksplit, const bf16_t* __restrict__ A1, int lda1,
;                   const bf16_t* __restrict__ Bt, int K, int row0, int col0, const Epi& epi, int tid) {
;   constexpr int BK = 32, PITCH = 40, BUF = (256 + 128) * PITCH;
;   bf16_t* sbase = (bf16_t*)smem;
;   const int lane = tid & 63, wid = tid >> 6, wr = wid >> 1, wc = wid & 1, fr = lane & 15, fq = lane >> 4;
;   f32x4 acc[8][4];
; #pragma unroll
;   for (int m = 0; m < 8; ++m)
; #pragma unroll
;     for (int n = 0; n < 4; ++n) acc[m][n] = (f32x4){0.f, 0.f, 0.f, 0.f};
;   u32x4 ra[2][4], rb[2][2];
;   const int nk = K / BK;
;   const int sr = tid >> 2, scv = tid & 3;
;     ...
;   __syncthreads();
;   {
;     const int last = nk - 1;
;     GLOAD(0, 0);
;     __builtin_amdgcn_sched_barrier(0);
;     GLOAD(1, 1);
;     __builtin_amdgcn_sched_barrier(0);
;     LWRITE(0, 0);
;     __builtin_amdgcn_sched_barrier(0);
;     GLOAD(0, (2 < last ? 2 : last));
;     __builtin_amdgcn_sched_barrier(0);
;     __syncthreads();
;     for (int kt = 0; kt < nk; kt += 2) {
;       LWRITE(1, 1);
;       __builtin_amdgcn_sched_barrier(0);
;       GLOAD(1, (kt + 3 < last ? kt + 3 : last));
;       __builtin_amdgcn_sched_barrier(0);
;       COMPUTE(0);
;       __syncthreads();
;       LWRITE(0, 0);
;       __builtin_amdgcn_sched_barrier(0);
;       GLOAD(0, (kt + 4 < last ? kt + 4 : last));
;       __builtin_amdgcn_sched_barrier(0);
;       COMPUTE(1);
;       __syncthreads();
;     }
; template <class Epi>
; DI void gemm_phase(char* smem, const bf16_t* A0, int lda0, int ksplit, const bf16_t* A1, int lda1, const bf16_t* Bt, int K, int nN, const Epi& epi, int tid) {
;     ...
;     const int ntiles = (NTOK / 256) * nN;
;     for (int u = blockIdx.x; u < ntiles; u += G) { const int rt = u / nN, ct = u % nN; gemm_tile(smem, A0, lda0, ksplit, A1, lda1, Bt, K, rt * 256, ct * 128, epi, tid); }
.LBB0_559:
	s_add_u32 s0, s92, 0x9800000
	s_addc_u32 s1, s93, 0
	s_add_u32 s6, s92, 0x34b0000
	s_addc_u32 s7, s93, 0
	s_and_b64 vcc, exec, s[2:3]
	s_cbranch_vccz .LBB0_564
	s_waitcnt lgkmcnt(0)
	s_load_dwordx16 s[56:71], s[74:75], 0x40
	s_cmpk_gt_i32 s96, 0x1ff
	s_cbranch_scc1 .LBB0_563
	v_and_b32_e32 v0, 3, v136
	v_lshlrev_b32_e32 v0, 4, v0
	v_mov_b32_e32 v1, 0
	v_ashrrev_i32_e32 v122, 2, v137
	v_lshl_add_u64 v[112:113], s[4:5], 0, v[0:1]
	v_lshl_add_u64 v[114:115], s[6:7], 0, v[0:1]
	v_bfe_u32 v1, v136, 4, 2
	s_movk_i32 s8, 0x40
	v_and_b32_e32 v3, 0x4f, v137
	v_and_b32_e32 v123, 0xffffff8f, v137
	v_or_b32_e32 v6, 0x70, v137
	v_add_u32_e32 v0, 0, v0
	v_mul_lo_u32 v2, v122, s8
	v_lshl_add_u32 v4, v1, 4, 0
	v_mul_u32_u24_e32 v3, 0x40, v3
	v_mul_lo_u32 v5, v123, s8
	v_mul_lo_u32 v6, v6, s8
	v_lshlrev_b32_e32 v1, 2, v1
	v_and_or_b32 v124, v137, 64, v1
	s_lshl_b32 s11, s96, 7
	s_lshl_b32 s15, s12, 7
	s_mov_b64 s[8:9], 0x18000
	s_mov_b32 s16, 0x18000
	v_add_u32_e32 v125, v0, v2
	v_add_u32_e32 v126, v4, v3
	v_add_u32_e32 v127, v4, v5
	v_add_u32_e32 v128, v4, v6
	v_mbcnt_lo_u32_b32 v2, -1, 0
	v_mbcnt_hi_u32_b32 v2, -1, v2
	v_bfe_u32 v3, v2, 3, 1
	v_bfe_u32 v2, v2, 5, 1
	v_mul_u32_u24_e32 v3, 48, v3
	v_mul_u32_u24_e32 v2, 48, v2
	v_xor_b32_e32 v125, v125, v2
	v_xor_b32_e32 v126, v126, v3
	v_xor_b32_e32 v127, v127, v3
	v_xor_b32_e32 v128, v128, v3
	s_mov_b32 s10, 0x3f1b4598
	s_mov_b32 s17, s96
.LBB0_562:
	s_ashr_i32 s18, s17, 31
	s_lshr_b32 s18, s18, 30
	s_add_i32 s18, s17, s18
	s_ashr_i32 s19, s18, 2
	s_lshl_b32 s18, s19, 8
	v_add_u32_e32 v0, s18, v122
	v_ashrrev_i32_e32 v1, 31, v0
	v_lshlrev_b64 v[0:1], 9, v[0:1]
	v_lshl_add_u64 v[24:25], v[112:113], 0, v[0:1]
	s_mov_b32 s20, 0x8000
	s_lshl_b32 s19, s19, 9
	v_add_co_u32_e32 v4, vcc, s20, v24
	s_sub_i32 s19, s11, s19
	s_nop 0
	v_addc_co_u32_e32 v5, vcc, 0, v25, vcc
	s_mov_b32 s20, 0x10000
	v_add_u32_e32 v16, s19, v122
	v_add_co_u32_e32 v8, vcc, s20, v24
	v_ashrrev_i32_e32 v17, 31, v16
	s_nop 0
	v_addc_co_u32_e32 v9, vcc, 0, v25, vcc
	v_lshlrev_b64 v[18:19], 7, v[16:17]
	v_add_u32_e32 v16, 64, v16
	v_add_co_u32_e32 v12, vcc, s16, v24
	v_ashrrev_i32_e32 v17, 31, v16
	s_nop 0
	v_addc_co_u32_e32 v13, vcc, 0, v25, vcc
	v_lshl_add_u64 v[40:41], v[114:115], 0, v[18:19]
	v_lshlrev_b64 v[16:17], 7, v[16:17]
	s_waitcnt lgkmcnt(0)
	s_barrier
	global_load_dwordx4 v[0:3], v[24:25], off
	s_nop 0
	global_load_dwordx4 v[4:7], v[4:5], off
	s_nop 0
	global_load_dwordx4 v[8:11], v[8:9], off
	s_nop 0
	global_load_dwordx4 v[12:15], v[12:13], off
	v_lshl_add_u64 v[44:45], v[114:115], 0, v[16:17]
	global_load_dwordx4 v[16:19], v[40:41], off
	global_load_dwordx4 v[20:23], v[44:45], off
	s_mov_b64 s[20:21], 0x8000
	v_lshl_add_u64 v[28:29], v[24:25], 0, s[20:21]
	s_mov_b64 s[20:21], 0x10000
	v_lshl_add_u64 v[32:33], v[24:25], 0, s[20:21]
	v_lshl_add_u64 v[36:37], v[24:25], 0, s[8:9]
	global_load_dwordx4 v[24:27], v[24:25], off offset:64
	s_nop 0
	global_load_dwordx4 v[28:31], v[28:29], off offset:64
	s_nop 0
	global_load_dwordx4 v[32:35], v[32:33], off offset:64
	s_nop 0
	global_load_dwordx4 v[36:39], v[36:37], off offset:64
	s_nop 0
	global_load_dwordx4 v[40:43], v[40:41], off offset:64
	s_nop 0
	global_load_dwordx4 v[44:47], v[44:45], off offset:64
	s_waitcnt vmcnt(11)
	ds_write_b128 v125, v[0:3]
	s_waitcnt vmcnt(10)
	ds_write_b128 v125, v[4:7] offset:4096
	s_waitcnt vmcnt(9)
	ds_write_b128 v125, v[8:11] offset:8192
	s_waitcnt vmcnt(8)
	ds_write_b128 v125, v[12:15] offset:12288
	s_waitcnt vmcnt(7)
	ds_write_b128 v125, v[16:19] offset:16384
	s_waitcnt vmcnt(6)
	ds_write_b128 v125, v[20:23] offset:20480
	s_waitcnt lgkmcnt(0)
	s_barrier
	s_waitcnt vmcnt(5)
	ds_write_b128 v125, v[24:27] offset:24576
	s_waitcnt vmcnt(4)
	ds_write_b128 v125, v[28:31] offset:28672
	s_waitcnt vmcnt(3)
	ds_write_b128 v125, v[32:35] offset:32768
	s_waitcnt vmcnt(2)
	ds_write_b128 v125, v[36:39] offset:36864
	s_waitcnt vmcnt(1)
	ds_write_b128 v125, v[40:43] offset:40960
	s_waitcnt vmcnt(0)
	ds_write_b128 v125, v[44:47] offset:45056
	ds_read_b128 v[0:3], v126 offset:16384
	ds_read_b128 v[4:7], v126 offset:17408
	ds_read_b128 v[8:11], v126 offset:18432
	ds_read_b128 v[12:15], v126 offset:19456
	ds_read_b128 v[16:19], v127
	ds_read_b128 v[20:23], v127 offset:1024
	ds_read_b128 v[48:51], v127 offset:2048
	ds_read_b128 v[52:55], v127 offset:3072
	ds_read_b128 v[56:59], v127 offset:4096
	ds_read_b128 v[60:63], v127 offset:5120
	ds_read_b128 v[64:67], v127 offset:6144
	ds_read_b128 v[68:71], v128
	s_setprio 1
	s_waitcnt lgkmcnt(7)
	v_mfma_f32_16x16x32_bf16 v[72:75], v[0:3], v[16:19], 0
	v_mfma_f32_16x16x32_bf16 v[76:79], v[4:7], v[16:19], 0
	v_mfma_f32_16x16x32_bf16 v[80:83], v[8:11], v[16:19], 0
	v_mfma_f32_16x16x32_bf16 v[16:19], v[12:15], v[16:19], 0
	s_waitcnt lgkmcnt(6)
	v_mfma_f32_16x16x32_bf16 v[84:87], v[0:3], v[20:23], 0
	v_mfma_f32_16x16x32_bf16 v[88:91], v[4:7], v[20:23], 0
	v_mfma_f32_16x16x32_bf16 v[92:95], v[8:11], v[20:23], 0
	v_mfma_f32_16x16x32_bf16 v[20:23], v[12:15], v[20:23], 0
	s_waitcnt lgkmcnt(5)
	v_mfma_f32_16x16x32_bf16 v[116:119], v[0:3], v[48:51], 0
	v_mfma_f32_16x16x32_bf16 v[130:133], v[4:7], v[48:51], 0
	v_mfma_f32_16x16x32_bf16 v[138:141], v[8:11], v[48:51], 0
	v_mfma_f32_16x16x32_bf16 v[48:51], v[12:15], v[48:51], 0
	s_waitcnt lgkmcnt(4)
	v_mfma_f32_16x16x32_bf16 v[142:145], v[0:3], v[52:55], 0
	v_mfma_f32_16x16x32_bf16 v[146:149], v[4:7], v[52:55], 0
	v_mfma_f32_16x16x32_bf16 v[150:153], v[8:11], v[52:55], 0
	v_mfma_f32_16x16x32_bf16 v[52:55], v[12:15], v[52:55], 0
	s_waitcnt lgkmcnt(3)
	v_mfma_f32_16x16x32_bf16 v[154:157], v[0:3], v[56:59], 0
	v_mfma_f32_16x16x32_bf16 v[158:161], v[4:7], v[56:59], 0
	v_mfma_f32_16x16x32_bf16 v[162:165], v[8:11], v[56:59], 0
	v_mfma_f32_16x16x32_bf16 v[166:169], v[12:15], v[56:59], 0
	s_waitcnt lgkmcnt(2)
	v_mfma_f32_16x16x32_bf16 v[170:173], v[0:3], v[60:63], 0
	v_mfma_f32_16x16x32_bf16 v[174:177], v[4:7], v[60:63], 0
	v_mfma_f32_16x16x32_bf16 v[178:181], v[8:11], v[60:63], 0
	v_mfma_f32_16x16x32_bf16 v[182:185], v[12:15], v[60:63], 0
	s_waitcnt lgkmcnt(1)
	v_mfma_f32_16x16x32_bf16 v[186:189], v[0:3], v[64:67], 0
	v_mfma_f32_16x16x32_bf16 v[190:193], v[4:7], v[64:67], 0
	v_mfma_f32_16x16x32_bf16 v[196:199], v[8:11], v[64:67], 0
	v_mfma_f32_16x16x32_bf16 v[200:203], v[12:15], v[64:67], 0
	s_waitcnt lgkmcnt(0)
	v_mfma_f32_16x16x32_bf16 v[0:3], v[0:3], v[68:71], 0
	v_mfma_f32_16x16x32_bf16 v[4:7], v[4:7], v[68:71], 0
	v_mfma_f32_16x16x32_bf16 v[204:207], v[8:11], v[68:71], 0
	v_mfma_f32_16x16x32_bf16 v[208:211], v[12:15], v[68:71], 0
	s_setprio 0
	s_barrier
; #define LWRITE(S, buf) do { bf16_t* sA_ = sbase + (buf) * BUF; bf16_t* sB_ = sA_ + 256 * PITCH; \
;     _Pragma("unroll") for (int i_ = 0; i_ < 4; ++i_) *(u32x4*)(sA_ + (sr + i_ * 64) * PITCH + scv * 8) = ra[S][i_]; \
;     _Pragma("unroll") for (int i_ = 0; i_ < 2; ++i_) *(u32x4*)(sB_ + (sr + i_ * 64) * PITCH + scv * 8) = rb[S][i_]; } while (0)
; template <class Epi>
; DI void gemm_tile(char* smem, const bf16_t* __restrict__ A0, int lda0, int ksplit, const bf16_t* __restrict__ A1, int lda1,
;                   const bf16_t* __restrict__ Bt, int K, int row0, int col0, const Epi& epi, int tid) {
;     ...
;   __syncthreads();
;   {
;     const int last = nk - 1;
;     GLOAD(0, 0);
;     __builtin_amdgcn_sched_barrier(0);
;     GLOAD(1, 1);
;     __builtin_amdgcn_sched_barrier(0);
;     LWRITE(0, 0);
;     __builtin_amdgcn_sched_barrier(0);
;     GLOAD(0, (2 < last ? 2 : last));
;     __builtin_amdgcn_sched_barrier(0);
;     __syncthreads();
;     for (int kt = 0; kt < nk; kt += 2) {
;       LWRITE(1, 1);
;       __builtin_amdgcn_sched_barrier(0);
;       GLOAD(1, (kt + 3 < last ? kt + 3 : last));
;       __builtin_amdgcn_sched_barrier(0);
;       COMPUTE(0);
;       __syncthreads();
;       LWRITE(0, 0);
;       __builtin_amdgcn_sched_barrier(0);
;       GLOAD(0, (kt + 4 < last ? kt + 4 : last));
;       __builtin_amdgcn_sched_barrier(0);
;       COMPUTE(1);
;       __syncthreads();
	ds_write_b128 v125, v[24:27]
	ds_write_b128 v125, v[28:31] offset:4096
	ds_write_b128 v125, v[32:35] offset:8192
	ds_write_b128 v125, v[36:39] offset:12288
	ds_write_b128 v125, v[40:43] offset:16384
	ds_write_b128 v125, v[44:47] offset:20480
	ds_read_b128 v[8:11], v126 offset:40960
	ds_read_b128 v[212:215], v126 offset:41984
	ds_read_b128 v[216:219], v126 offset:43008
	ds_read_b128 v[220:223], v126 offset:44032
	ds_read_b128 v[12:15], v127 offset:26624
	ds_read_b128 v[24:27], v127 offset:27648
	ds_read_b128 v[28:31], v127 offset:28672
	ds_read_b128 v[32:35], v127 offset:29696
	ds_read_b128 v[36:39], v127 offset:24576
	ds_read_b128 v[224:227], v127 offset:30720
	ds_read_b128 v[40:43], v127 offset:25600
	ds_read_b128 v[228:231], v128 offset:24576
	s_setprio 1
	s_waitcnt lgkmcnt(3)
	v_mfma_f32_16x16x32_bf16 v[232:235], v[8:11], v[36:39], v[72:75]
	v_mfma_f32_16x16x32_bf16 v[236:239], v[212:215], v[36:39], v[76:79]
	v_mfma_f32_16x16x32_bf16 v[240:243], v[216:219], v[36:39], v[80:83]
	v_mfma_f32_16x16x32_bf16 v[244:247], v[220:223], v[36:39], v[16:19]
	s_waitcnt lgkmcnt(1)
	v_mfma_f32_16x16x32_bf16 v[108:111], v[8:11], v[40:43], v[84:87]
	v_mfma_f32_16x16x32_bf16 v[104:107], v[212:215], v[40:43], v[88:91]
	v_mfma_f32_16x16x32_bf16 v[100:103], v[216:219], v[40:43], v[92:95]
	v_mfma_f32_16x16x32_bf16 v[96:99], v[220:223], v[40:43], v[20:23]
	v_mfma_f32_16x16x32_bf16 v[92:95], v[8:11], v[12:15], v[116:119]
	v_mfma_f32_16x16x32_bf16 v[88:91], v[212:215], v[12:15], v[130:133]
	v_mfma_f32_16x16x32_bf16 v[84:87], v[216:219], v[12:15], v[138:141]
	v_mfma_f32_16x16x32_bf16 v[80:83], v[220:223], v[12:15], v[48:51]
	v_mfma_f32_16x16x32_bf16 v[76:79], v[8:11], v[24:27], v[142:145]
	v_mfma_f32_16x16x32_bf16 v[72:75], v[212:215], v[24:27], v[146:149]
	v_mfma_f32_16x16x32_bf16 v[68:71], v[216:219], v[24:27], v[150:153]
	v_mfma_f32_16x16x32_bf16 v[64:67], v[220:223], v[24:27], v[52:55]
	v_mfma_f32_16x16x32_bf16 v[60:63], v[8:11], v[28:31], v[154:157]
	v_mfma_f32_16x16x32_bf16 v[56:59], v[212:215], v[28:31], v[158:161]
	v_mfma_f32_16x16x32_bf16 v[52:55], v[216:219], v[28:31], v[162:165]
	v_mfma_f32_16x16x32_bf16 v[48:51], v[220:223], v[28:31], v[166:169]
	v_mfma_f32_16x16x32_bf16 v[44:47], v[8:11], v[32:35], v[170:173]
	v_mfma_f32_16x16x32_bf16 v[40:43], v[212:215], v[32:35], v[174:177]
	v_mfma_f32_16x16x32_bf16 v[36:39], v[216:219], v[32:35], v[178:181]
	v_mfma_f32_16x16x32_bf16 v[32:35], v[220:223], v[32:35], v[182:185]
	v_mfma_f32_16x16x32_bf16 v[28:31], v[8:11], v[224:227], v[186:189]
	v_mfma_f32_16x16x32_bf16 v[24:27], v[212:215], v[224:227], v[190:193]
	v_mfma_f32_16x16x32_bf16 v[20:23], v[216:219], v[224:227], v[196:199]
	v_mfma_f32_16x16x32_bf16 v[16:19], v[220:223], v[224:227], v[200:203]
	s_waitcnt lgkmcnt(0)
	v_mfma_f32_16x16x32_bf16 v[12:15], v[8:11], v[228:231], v[0:3]
	v_mfma_f32_16x16x32_bf16 v[8:11], v[212:215], v[228:231], v[4:7]
	v_mfma_f32_16x16x32_bf16 v[4:7], v[216:219], v[228:231], v[204:207]
	v_mfma_f32_16x16x32_bf16 v[0:3], v[220:223], v[228:231], v[208:211]
	s_setprio 0
	v_add_u32_e32 v118, s19, v124
	v_ashrrev_i32_e32 v119, 31, v118
	v_lshl_add_u64 v[116:117], v[118:119], 2, s[58:59]
	s_barrier
	global_load_dwordx4 v[130:133], v[116:117], off offset:2048
	v_add_u32_e32 v120, s18, v123
	v_ashrrev_i32_e32 v121, 31, v120
	v_lshlrev_b64 v[134:135], 10, v[120:121]
	v_lshlrev_b64 v[118:119], 1, v[118:119]
	v_lshl_add_u64 v[134:135], s[0:1], 0, v[134:135]
	v_lshl_add_u64 v[134:135], v[134:135], 0, v[118:119]
	s_add_i32 s17, s17, s12
	s_waitcnt vmcnt(0)
	v_add_f32_e32 v121, v232, v130
	v_add_f32_e32 v129, v233, v131
	v_add_f32_e32 v130, v234, v132
	v_add_f32_e32 v131, v235, v133
	v_mul_f32_e32 v121, 0xbfb8aa3b, v121
	v_mul_f32_e32 v129, 0xbfb8aa3b, v129
	v_mul_f32_e32 v130, 0xbfb8aa3b, v130
	v_mul_f32_e32 v131, 0xbfb8aa3b, v131
	v_exp_f32_e32 v121, v121
	v_exp_f32_e32 v129, v129
	v_exp_f32_e32 v130, v130
	v_exp_f32_e32 v131, v131
	v_add_f32_e32 v121, 1.0, v121
	v_add_f32_e32 v129, 1.0, v129
	v_add_f32_e32 v132, 1.0, v130
	v_add_f32_e32 v131, 1.0, v131
	v_rcp_f32_e32 v130, v121
	v_rcp_f32_e32 v132, v132
	v_rcp_f32_e32 v133, v131
	v_rcp_f32_e32 v131, v129
	v_pk_mul_f32 v[132:133], v[132:133], s[10:11] op_sel_hi:[1,0]
	v_pk_mul_f32 v[130:131], v[130:131], s[10:11] op_sel_hi:[1,0]
	s_nop 0
	v_cvt_pk_bf16_f32 v130, v130, v131
	v_cvt_pk_bf16_f32 v131, v132, v133
	global_store_dwordx2 v[134:135], v[130:131], off
	global_load_dwordx4 v[130:133], v[116:117], off offset:2112
	s_waitcnt vmcnt(0)
	v_add_f32_e32 v121, v236, v130
	v_add_f32_e32 v129, v237, v131
	v_add_f32_e32 v130, v238, v132
	v_add_f32_e32 v131, v239, v133
	v_mul_f32_e32 v121, 0xbfb8aa3b, v121
	v_mul_f32_e32 v129, 0xbfb8aa3b, v129
	v_mul_f32_e32 v130, 0xbfb8aa3b, v130
	v_mul_f32_e32 v131, 0xbfb8aa3b, v131
	v_exp_f32_e32 v121, v121
	v_exp_f32_e32 v129, v129
	v_exp_f32_e32 v130, v130
	v_exp_f32_e32 v131, v131
	v_add_f32_e32 v121, 1.0, v121
	v_add_f32_e32 v129, 1.0, v129
	v_add_f32_e32 v132, 1.0, v130
	v_add_f32_e32 v131, 1.0, v131
	v_rcp_f32_e32 v130, v121
	v_rcp_f32_e32 v132, v132
	v_rcp_f32_e32 v133, v131
	v_rcp_f32_e32 v131, v129
	v_pk_mul_f32 v[132:133], v[132:133], s[10:11] op_sel_hi:[1,0]
	v_pk_mul_f32 v[130:131], v[130:131], s[10:11] op_sel_hi:[1,0]
	s_nop 0
	v_cvt_pk_bf16_f32 v130, v130, v131
	v_cvt_pk_bf16_f32 v131, v132, v133
	global_store_dwordx2 v[134:135], v[130:131], off offset:32
	global_load_dwordx4 v[130:133], v[116:117], off offset:2176
	s_waitcnt vmcnt(0)
; template <class Epi>
; DI void gemm_tile(char* smem, const bf16_t* __restrict__ A0, int lda0, int ksplit, const bf16_t* __restrict__ A1, int lda1,
;                   const bf16_t* __restrict__ Bt, int K, int row0, int col0, const Epi& epi, int tid) {
;     ...
; #pragma unroll
;   for (int m = 0; m < 8; ++m)
; #pragma unroll
;     for (int n = 0; n < 4; ++n) epi(row0 + wr * 128 + m * 16 + fr, col0 + wc * 64 + n * 16 + fq * 4, acc[m][n]);
	v_add_f32_e32 v121, v240, v130
	v_add_f32_e32 v129, v241, v131
	v_add_f32_e32 v130, v242, v132
	v_add_f32_e32 v131, v243, v133
	v_mul_f32_e32 v121, 0xbfb8aa3b, v121
	v_mul_f32_e32 v129, 0xbfb8aa3b, v129
	v_mul_f32_e32 v130, 0xbfb8aa3b, v130
	v_mul_f32_e32 v131, 0xbfb8aa3b, v131
	v_exp_f32_e32 v121, v121
	v_exp_f32_e32 v129, v129
	v_exp_f32_e32 v130, v130
	v_exp_f32_e32 v131, v131
	v_add_f32_e32 v121, 1.0, v121
	v_add_f32_e32 v129, 1.0, v129
	v_add_f32_e32 v132, 1.0, v130
	v_add_f32_e32 v131, 1.0, v131
	v_rcp_f32_e32 v130, v121
	v_rcp_f32_e32 v132, v132
	v_rcp_f32_e32 v133, v131
	v_rcp_f32_e32 v131, v129
	v_pk_mul_f32 v[132:133], v[132:133], s[10:11] op_sel_hi:[1,0]
	v_pk_mul_f32 v[130:131], v[130:131], s[10:11] op_sel_hi:[1,0]
	s_nop 0
	v_cvt_pk_bf16_f32 v130, v130, v131
	v_cvt_pk_bf16_f32 v131, v132, v133
	global_store_dwordx2 v[134:135], v[130:131], off offset:64
	global_load_dwordx4 v[130:133], v[116:117], off offset:2240
	s_waitcnt vmcnt(0)
	v_add_f32_e32 v121, v244, v130
	v_add_f32_e32 v129, v245, v131
	v_add_f32_e32 v130, v246, v132
	v_add_f32_e32 v131, v247, v133
	v_mul_f32_e32 v121, 0xbfb8aa3b, v121
	v_mul_f32_e32 v129, 0xbfb8aa3b, v129
	v_mul_f32_e32 v130, 0xbfb8aa3b, v130
	v_mul_f32_e32 v131, 0xbfb8aa3b, v131
	v_exp_f32_e32 v121, v121
	v_exp_f32_e32 v129, v129
	v_exp_f32_e32 v130, v130
	v_exp_f32_e32 v131, v131
	v_add_f32_e32 v121, 1.0, v121
	v_add_f32_e32 v129, 1.0, v129
	v_add_f32_e32 v132, 1.0, v130
	v_add_f32_e32 v131, 1.0, v131
	v_rcp_f32_e32 v130, v121
	v_rcp_f32_e32 v132, v132
	v_rcp_f32_e32 v133, v131
	v_rcp_f32_e32 v131, v129
	v_pk_mul_f32 v[132:133], v[132:133], s[10:11] op_sel_hi:[1,0]
	v_pk_mul_f32 v[130:131], v[130:131], s[10:11] op_sel_hi:[1,0]
	s_nop 0
	v_cvt_pk_bf16_f32 v130, v130, v131
	v_cvt_pk_bf16_f32 v131, v132, v133
	global_store_dwordx2 v[134:135], v[130:131], off offset:96
	global_load_dwordx4 v[130:133], v[116:117], off offset:2048
	v_or_b32_e32 v134, 16, v120
	v_ashrrev_i32_e32 v135, 31, v134
	v_lshlrev_b64 v[134:135], 10, v[134:135]
	s_waitcnt vmcnt(0)
	v_add_f32_e32 v108, v108, v130
	v_add_f32_e32 v109, v109, v131
	v_add_f32_e32 v110, v110, v132
	v_add_f32_e32 v111, v111, v133
	v_mul_f32_e32 v108, 0xbfb8aa3b, v108
	v_mul_f32_e32 v109, 0xbfb8aa3b, v109
	v_mul_f32_e32 v110, 0xbfb8aa3b, v110
	v_mul_f32_e32 v111, 0xbfb8aa3b, v111
	v_exp_f32_e32 v108, v108
	v_exp_f32_e32 v109, v109
	v_exp_f32_e32 v110, v110
	v_exp_f32_e32 v111, v111
	v_add_f32_e32 v108, 1.0, v108
	v_add_f32_e32 v109, 1.0, v109
	v_add_f32_e32 v110, 1.0, v110
	v_add_f32_e32 v111, 1.0, v111
	v_rcp_f32_e32 v108, v108
	v_rcp_f32_e32 v110, v110
	v_rcp_f32_e32 v111, v111
	v_rcp_f32_e32 v109, v109
	v_lshl_add_u64 v[130:131], s[0:1], 0, v[134:135]
	v_lshl_add_u64 v[130:131], v[130:131], 0, v[118:119]
	v_pk_mul_f32 v[110:111], v[110:111], s[10:11] op_sel_hi:[1,0]
	v_pk_mul_f32 v[108:109], v[108:109], s[10:11] op_sel_hi:[1,0]
	s_nop 0
	v_cvt_pk_bf16_f32 v108, v108, v109
	v_cvt_pk_bf16_f32 v109, v110, v111
	global_store_dwordx2 v[130:131], v[108:109], off
	global_load_dwordx4 v[108:111], v[116:117], off offset:2112
	s_waitcnt vmcnt(0)
	v_add_f32_e32 v104, v104, v108
	v_add_f32_e32 v105, v105, v109
	v_add_f32_e32 v106, v106, v110
	v_add_f32_e32 v107, v107, v111
	v_mul_f32_e32 v104, 0xbfb8aa3b, v104
	v_mul_f32_e32 v105, 0xbfb8aa3b, v105
	v_mul_f32_e32 v106, 0xbfb8aa3b, v106
	v_mul_f32_e32 v107, 0xbfb8aa3b, v107
	v_exp_f32_e32 v104, v104
	v_exp_f32_e32 v105, v105
	v_exp_f32_e32 v106, v106
	v_exp_f32_e32 v107, v107
	v_add_f32_e32 v104, 1.0, v104
	v_add_f32_e32 v105, 1.0, v105
	v_add_f32_e32 v106, 1.0, v106
	v_add_f32_e32 v107, 1.0, v107
	v_rcp_f32_e32 v104, v104
	v_rcp_f32_e32 v106, v106
	v_rcp_f32_e32 v107, v107
	v_rcp_f32_e32 v105, v105
	v_pk_mul_f32 v[106:107], v[106:107], s[10:11] op_sel_hi:[1,0]
	v_pk_mul_f32 v[104:105], v[104:105], s[10:11] op_sel_hi:[1,0]
	s_nop 0
	v_cvt_pk_bf16_f32 v104, v104, v105
	v_cvt_pk_bf16_f32 v105, v106, v107
	global_store_dwordx2 v[130:131], v[104:105], off offset:32
	global_load_dwordx4 v[104:107], v[116:117], off offset:2176
	s_waitcnt vmcnt(0)
	v_add_f32_e32 v100, v100, v104
	v_add_f32_e32 v101, v101, v105
	v_add_f32_e32 v102, v102, v106
	v_add_f32_e32 v103, v103, v107
	v_mul_f32_e32 v100, 0xbfb8aa3b, v100
	v_mul_f32_e32 v101, 0xbfb8aa3b, v101
	v_mul_f32_e32 v102, 0xbfb8aa3b, v102
	v_mul_f32_e32 v103, 0xbfb8aa3b, v103
	v_exp_f32_e32 v100, v100
	v_exp_f32_e32 v101, v101
	v_exp_f32_e32 v102, v102
	v_exp_f32_e32 v103, v103
	v_add_f32_e32 v100, 1.0, v100
	v_add_f32_e32 v101, 1.0, v101
	v_add_f32_e32 v102, 1.0, v102
	v_add_f32_e32 v103, 1.0, v103
	v_rcp_f32_e32 v100, v100
	v_rcp_f32_e32 v102, v102
	v_rcp_f32_e32 v103, v103
	v_rcp_f32_e32 v101, v101
	v_pk_mul_f32 v[102:103], v[102:103], s[10:11] op_sel_hi:[1,0]
	v_pk_mul_f32 v[100:101], v[100:101], s[10:11] op_sel_hi:[1,0]
	s_nop 0
	v_cvt_pk_bf16_f32 v100, v100, v101
	v_cvt_pk_bf16_f32 v101, v102, v103
	global_store_dwordx2 v[130:131], v[100:101], off offset:64
	global_load_dwordx4 v[100:103], v[116:117], off offset:2240
	s_waitcnt vmcnt(0)
	v_add_f32_e32 v96, v96, v100
	v_add_f32_e32 v97, v97, v101
	v_add_f32_e32 v98, v98, v102
	v_add_f32_e32 v99, v99, v103
	v_mul_f32_e32 v96, 0xbfb8aa3b, v96
	v_mul_f32_e32 v97, 0xbfb8aa3b, v97
	v_mul_f32_e32 v98, 0xbfb8aa3b, v98
	v_mul_f32_e32 v99, 0xbfb8aa3b, v99
	v_exp_f32_e32 v96, v96
	v_exp_f32_e32 v97, v97
	v_exp_f32_e32 v98, v98
	v_exp_f32_e32 v99, v99
	v_add_f32_e32 v96, 1.0, v96
	v_add_f32_e32 v97, 1.0, v97
	v_add_f32_e32 v98, 1.0, v98
	v_add_f32_e32 v99, 1.0, v99
	v_rcp_f32_e32 v96, v96
	v_rcp_f32_e32 v98, v98
	v_rcp_f32_e32 v99, v99
	v_rcp_f32_e32 v97, v97
	v_or_b32_e32 v100, 32, v120
	v_ashrrev_i32_e32 v101, 31, v100
	v_pk_mul_f32 v[98:99], v[98:99], s[10:11] op_sel_hi:[1,0]
	v_pk_mul_f32 v[96:97], v[96:97], s[10:11] op_sel_hi:[1,0]
	v_lshlrev_b64 v[100:101], 10, v[100:101]
	v_cvt_pk_bf16_f32 v96, v96, v97
	v_cvt_pk_bf16_f32 v97, v98, v99
	global_store_dwordx2 v[130:131], v[96:97], off offset:96
	global_load_dwordx4 v[96:99], v[116:117], off offset:2048
	s_waitcnt vmcnt(0)
; template <class Epi>
; DI void gemm_tile(char* smem, const bf16_t* __restrict__ A0, int lda0, int ksplit, const bf16_t* __restrict__ A1, int lda1,
;                   const bf16_t* __restrict__ Bt, int K, int row0, int col0, const Epi& epi, int tid) {
;     ...
; #pragma unroll
;   for (int m = 0; m < 8; ++m)
; #pragma unroll
;     for (int n = 0; n < 4; ++n) epi(row0 + wr * 128 + m * 16 + fr, col0 + wc * 64 + n * 16 + fq * 4, acc[m][n]);
	v_add_f32_e32 v92, v92, v96
	v_add_f32_e32 v93, v93, v97
	v_add_f32_e32 v94, v94, v98
	v_add_f32_e32 v95, v95, v99
	v_mul_f32_e32 v92, 0xbfb8aa3b, v92
	v_mul_f32_e32 v93, 0xbfb8aa3b, v93
	v_mul_f32_e32 v94, 0xbfb8aa3b, v94
	v_mul_f32_e32 v95, 0xbfb8aa3b, v95
	v_exp_f32_e32 v92, v92
	v_exp_f32_e32 v93, v93
	v_exp_f32_e32 v94, v94
	v_exp_f32_e32 v95, v95
	v_add_f32_e32 v92, 1.0, v92
	v_add_f32_e32 v93, 1.0, v93
	v_add_f32_e32 v94, 1.0, v94
	v_add_f32_e32 v95, 1.0, v95
	v_rcp_f32_e32 v92, v92
	v_rcp_f32_e32 v94, v94
	v_rcp_f32_e32 v95, v95
	v_rcp_f32_e32 v93, v93
	v_lshl_add_u64 v[96:97], s[0:1], 0, v[100:101]
	v_lshl_add_u64 v[96:97], v[96:97], 0, v[118:119]
	v_pk_mul_f32 v[94:95], v[94:95], s[10:11] op_sel_hi:[1,0]
	v_pk_mul_f32 v[92:93], v[92:93], s[10:11] op_sel_hi:[1,0]
	s_nop 0
	v_cvt_pk_bf16_f32 v92, v92, v93
	v_cvt_pk_bf16_f32 v93, v94, v95
	global_store_dwordx2 v[96:97], v[92:93], off
	global_load_dwordx4 v[92:95], v[116:117], off offset:2112
	s_waitcnt vmcnt(0)
	v_add_f32_e32 v88, v88, v92
	v_add_f32_e32 v89, v89, v93
	v_add_f32_e32 v90, v90, v94
	v_add_f32_e32 v91, v91, v95
	v_mul_f32_e32 v88, 0xbfb8aa3b, v88
	v_mul_f32_e32 v89, 0xbfb8aa3b, v89
	v_mul_f32_e32 v90, 0xbfb8aa3b, v90
	v_mul_f32_e32 v91, 0xbfb8aa3b, v91
	v_exp_f32_e32 v88, v88
	v_exp_f32_e32 v89, v89
	v_exp_f32_e32 v90, v90
	v_exp_f32_e32 v91, v91
	v_add_f32_e32 v88, 1.0, v88
	v_add_f32_e32 v89, 1.0, v89
	v_add_f32_e32 v90, 1.0, v90
	v_add_f32_e32 v91, 1.0, v91
	v_rcp_f32_e32 v88, v88
	v_rcp_f32_e32 v90, v90
	v_rcp_f32_e32 v91, v91
	v_rcp_f32_e32 v89, v89
	v_pk_mul_f32 v[90:91], v[90:91], s[10:11] op_sel_hi:[1,0]
	v_pk_mul_f32 v[88:89], v[88:89], s[10:11] op_sel_hi:[1,0]
	s_nop 0
	v_cvt_pk_bf16_f32 v88, v88, v89
	v_cvt_pk_bf16_f32 v89, v90, v91
	global_store_dwordx2 v[96:97], v[88:89], off offset:32
	global_load_dwordx4 v[88:91], v[116:117], off offset:2176
	s_waitcnt vmcnt(0)
	v_add_f32_e32 v84, v84, v88
	v_add_f32_e32 v85, v85, v89
	v_add_f32_e32 v86, v86, v90
	v_add_f32_e32 v87, v87, v91
	v_mul_f32_e32 v84, 0xbfb8aa3b, v84
	v_mul_f32_e32 v85, 0xbfb8aa3b, v85
	v_mul_f32_e32 v86, 0xbfb8aa3b, v86
	v_mul_f32_e32 v87, 0xbfb8aa3b, v87
	v_exp_f32_e32 v84, v84
	v_exp_f32_e32 v85, v85
	v_exp_f32_e32 v86, v86
	v_exp_f32_e32 v87, v87
	v_add_f32_e32 v84, 1.0, v84
	v_add_f32_e32 v85, 1.0, v85
	v_add_f32_e32 v86, 1.0, v86
	v_add_f32_e32 v87, 1.0, v87
	v_rcp_f32_e32 v84, v84
	v_rcp_f32_e32 v86, v86
	v_rcp_f32_e32 v87, v87
	v_rcp_f32_e32 v85, v85
	v_pk_mul_f32 v[86:87], v[86:87], s[10:11] op_sel_hi:[1,0]
	v_pk_mul_f32 v[84:85], v[84:85], s[10:11] op_sel_hi:[1,0]
	s_nop 0
	v_cvt_pk_bf16_f32 v84, v84, v85
	v_cvt_pk_bf16_f32 v85, v86, v87
	global_store_dwordx2 v[96:97], v[84:85], off offset:64
	global_load_dwordx4 v[84:87], v[116:117], off offset:2240
	s_waitcnt vmcnt(0)
	v_add_f32_e32 v80, v80, v84
	v_add_f32_e32 v81, v81, v85
	v_add_f32_e32 v82, v82, v86
	v_add_f32_e32 v83, v83, v87
	v_mul_f32_e32 v80, 0xbfb8aa3b, v80
	v_mul_f32_e32 v81, 0xbfb8aa3b, v81
	v_mul_f32_e32 v82, 0xbfb8aa3b, v82
	v_mul_f32_e32 v83, 0xbfb8aa3b, v83
	v_exp_f32_e32 v80, v80
	v_exp_f32_e32 v81, v81
	v_exp_f32_e32 v82, v82
	v_exp_f32_e32 v83, v83
	v_add_f32_e32 v80, 1.0, v80
	v_add_f32_e32 v81, 1.0, v81
	v_add_f32_e32 v82, 1.0, v82
	v_add_f32_e32 v83, 1.0, v83
	v_rcp_f32_e32 v80, v80
	v_rcp_f32_e32 v82, v82
	v_rcp_f32_e32 v83, v83
	v_rcp_f32_e32 v81, v81
	v_or_b32_e32 v84, 48, v120
	v_ashrrev_i32_e32 v85, 31, v84
	v_pk_mul_f32 v[82:83], v[82:83], s[10:11] op_sel_hi:[1,0]
	v_pk_mul_f32 v[80:81], v[80:81], s[10:11] op_sel_hi:[1,0]
	v_lshlrev_b64 v[84:85], 10, v[84:85]
	v_cvt_pk_bf16_f32 v80, v80, v81
	v_cvt_pk_bf16_f32 v81, v82, v83
	global_store_dwordx2 v[96:97], v[80:81], off offset:96
	global_load_dwordx4 v[80:83], v[116:117], off offset:2048
	s_waitcnt vmcnt(0)
	v_add_f32_e32 v76, v76, v80
	v_add_f32_e32 v77, v77, v81
	v_add_f32_e32 v78, v78, v82
	v_add_f32_e32 v79, v79, v83
	v_mul_f32_e32 v76, 0xbfb8aa3b, v76
	v_mul_f32_e32 v77, 0xbfb8aa3b, v77
	v_mul_f32_e32 v78, 0xbfb8aa3b, v78
	v_mul_f32_e32 v79, 0xbfb8aa3b, v79
	v_exp_f32_e32 v76, v76
	v_exp_f32_e32 v77, v77
	v_exp_f32_e32 v78, v78
	v_exp_f32_e32 v79, v79
	v_add_f32_e32 v76, 1.0, v76
	v_add_f32_e32 v77, 1.0, v77
	v_add_f32_e32 v78, 1.0, v78
	v_add_f32_e32 v79, 1.0, v79
	v_rcp_f32_e32 v76, v76
	v_rcp_f32_e32 v78, v78
	v_rcp_f32_e32 v79, v79
	v_rcp_f32_e32 v77, v77
	v_lshl_add_u64 v[80:81], s[0:1], 0, v[84:85]
	v_lshl_add_u64 v[80:81], v[80:81], 0, v[118:119]
	v_pk_mul_f32 v[78:79], v[78:79], s[10:11] op_sel_hi:[1,0]
	v_pk_mul_f32 v[76:77], v[76:77], s[10:11] op_sel_hi:[1,0]
	s_nop 0
	v_cvt_pk_bf16_f32 v76, v76, v77
	v_cvt_pk_bf16_f32 v77, v78, v79
	global_store_dwordx2 v[80:81], v[76:77], off
	global_load_dwordx4 v[76:79], v[116:117], off offset:2112
	s_waitcnt vmcnt(0)
	v_add_f32_e32 v72, v72, v76
	v_add_f32_e32 v73, v73, v77
	v_add_f32_e32 v74, v74, v78
	v_add_f32_e32 v75, v75, v79
	v_mul_f32_e32 v72, 0xbfb8aa3b, v72
	v_mul_f32_e32 v73, 0xbfb8aa3b, v73
	v_mul_f32_e32 v74, 0xbfb8aa3b, v74
	v_mul_f32_e32 v75, 0xbfb8aa3b, v75
	v_exp_f32_e32 v72, v72
	v_exp_f32_e32 v73, v73
	v_exp_f32_e32 v74, v74
	v_exp_f32_e32 v75, v75
	v_add_f32_e32 v72, 1.0, v72
	v_add_f32_e32 v73, 1.0, v73
	v_add_f32_e32 v74, 1.0, v74
	v_add_f32_e32 v75, 1.0, v75
	v_rcp_f32_e32 v72, v72
	v_rcp_f32_e32 v74, v74
	v_rcp_f32_e32 v75, v75
	v_rcp_f32_e32 v73, v73
	v_pk_mul_f32 v[74:75], v[74:75], s[10:11] op_sel_hi:[1,0]
	v_pk_mul_f32 v[72:73], v[72:73], s[10:11] op_sel_hi:[1,0]
	s_nop 0
	v_cvt_pk_bf16_f32 v72, v72, v73
	v_cvt_pk_bf16_f32 v73, v74, v75
	global_store_dwordx2 v[80:81], v[72:73], off offset:32
	global_load_dwordx4 v[72:75], v[116:117], off offset:2176
	s_waitcnt vmcnt(0)
; template <class Epi>
; DI void gemm_tile(char* smem, const bf16_t* __restrict__ A0, int lda0, int ksplit, const bf16_t* __restrict__ A1, int lda1,
;                   const bf16_t* __restrict__ Bt, int K, int row0, int col0, const Epi& epi, int tid) {
;     ...
; #pragma unroll
;   for (int m = 0; m < 8; ++m)
; #pragma unroll
;     for (int n = 0; n < 4; ++n) epi(row0 + wr * 128 + m * 16 + fr, col0 + wc * 64 + n * 16 + fq * 4, acc[m][n]);
	v_add_f32_e32 v68, v68, v72
	v_add_f32_e32 v69, v69, v73
	v_add_f32_e32 v70, v70, v74
	v_add_f32_e32 v71, v71, v75
	v_mul_f32_e32 v68, 0xbfb8aa3b, v68
	v_mul_f32_e32 v69, 0xbfb8aa3b, v69
	v_mul_f32_e32 v70, 0xbfb8aa3b, v70
	v_mul_f32_e32 v71, 0xbfb8aa3b, v71
	v_exp_f32_e32 v68, v68
	v_exp_f32_e32 v69, v69
	v_exp_f32_e32 v70, v70
	v_exp_f32_e32 v71, v71
	v_add_f32_e32 v68, 1.0, v68
	v_add_f32_e32 v69, 1.0, v69
	v_add_f32_e32 v70, 1.0, v70
	v_add_f32_e32 v71, 1.0, v71
	v_rcp_f32_e32 v68, v68
	v_rcp_f32_e32 v70, v70
	v_rcp_f32_e32 v71, v71
	v_rcp_f32_e32 v69, v69
	v_pk_mul_f32 v[70:71], v[70:71], s[10:11] op_sel_hi:[1,0]
	v_pk_mul_f32 v[68:69], v[68:69], s[10:11] op_sel_hi:[1,0]
	s_nop 0
	v_cvt_pk_bf16_f32 v68, v68, v69
	v_cvt_pk_bf16_f32 v69, v70, v71
	global_store_dwordx2 v[80:81], v[68:69], off offset:64
	global_load_dwordx4 v[68:71], v[116:117], off offset:2240
	s_waitcnt vmcnt(0)
	v_add_f32_e32 v64, v64, v68
	v_add_f32_e32 v65, v65, v69
	v_add_f32_e32 v66, v66, v70
	v_add_f32_e32 v67, v67, v71
	v_mul_f32_e32 v64, 0xbfb8aa3b, v64
	v_mul_f32_e32 v65, 0xbfb8aa3b, v65
	v_mul_f32_e32 v66, 0xbfb8aa3b, v66
	v_mul_f32_e32 v67, 0xbfb8aa3b, v67
	v_exp_f32_e32 v64, v64
	v_exp_f32_e32 v65, v65
	v_exp_f32_e32 v66, v66
	v_exp_f32_e32 v67, v67
	v_add_f32_e32 v64, 1.0, v64
	v_add_f32_e32 v65, 1.0, v65
	v_add_f32_e32 v66, 1.0, v66
	v_add_f32_e32 v67, 1.0, v67
	v_rcp_f32_e32 v64, v64
	v_rcp_f32_e32 v66, v66
	v_rcp_f32_e32 v67, v67
	v_rcp_f32_e32 v65, v65
	v_or_b32_e32 v68, 64, v120
	v_ashrrev_i32_e32 v69, 31, v68
	v_pk_mul_f32 v[66:67], v[66:67], s[10:11] op_sel_hi:[1,0]
	v_pk_mul_f32 v[64:65], v[64:65], s[10:11] op_sel_hi:[1,0]
	v_lshlrev_b64 v[68:69], 10, v[68:69]
	v_cvt_pk_bf16_f32 v64, v64, v65
	v_cvt_pk_bf16_f32 v65, v66, v67
	global_store_dwordx2 v[80:81], v[64:65], off offset:96
	global_load_dwordx4 v[64:67], v[116:117], off offset:2048
	s_waitcnt vmcnt(0)
	v_add_f32_e32 v60, v60, v64
	v_add_f32_e32 v61, v61, v65
	v_add_f32_e32 v62, v62, v66
	v_add_f32_e32 v63, v63, v67
	v_mul_f32_e32 v60, 0xbfb8aa3b, v60
	v_mul_f32_e32 v61, 0xbfb8aa3b, v61
	v_mul_f32_e32 v62, 0xbfb8aa3b, v62
	v_mul_f32_e32 v63, 0xbfb8aa3b, v63
	v_exp_f32_e32 v60, v60
	v_exp_f32_e32 v61, v61
	v_exp_f32_e32 v62, v62
	v_exp_f32_e32 v63, v63
	v_add_f32_e32 v60, 1.0, v60
	v_add_f32_e32 v61, 1.0, v61
	v_add_f32_e32 v62, 1.0, v62
	v_add_f32_e32 v63, 1.0, v63
	v_rcp_f32_e32 v60, v60
	v_rcp_f32_e32 v62, v62
	v_rcp_f32_e32 v63, v63
	v_rcp_f32_e32 v61, v61
	v_lshl_add_u64 v[64:65], s[0:1], 0, v[68:69]
	v_lshl_add_u64 v[64:65], v[64:65], 0, v[118:119]
	v_pk_mul_f32 v[62:63], v[62:63], s[10:11] op_sel_hi:[1,0]
	v_pk_mul_f32 v[60:61], v[60:61], s[10:11] op_sel_hi:[1,0]
	s_nop 0
	v_cvt_pk_bf16_f32 v60, v60, v61
	v_cvt_pk_bf16_f32 v61, v62, v63
	global_store_dwordx2 v[64:65], v[60:61], off
	global_load_dwordx4 v[60:63], v[116:117], off offset:2112
	s_waitcnt vmcnt(0)
	v_add_f32_e32 v56, v56, v60
	v_add_f32_e32 v57, v57, v61
	v_add_f32_e32 v58, v58, v62
	v_add_f32_e32 v59, v59, v63
	v_mul_f32_e32 v56, 0xbfb8aa3b, v56
	v_mul_f32_e32 v57, 0xbfb8aa3b, v57
	v_mul_f32_e32 v58, 0xbfb8aa3b, v58
	v_mul_f32_e32 v59, 0xbfb8aa3b, v59
	v_exp_f32_e32 v56, v56
	v_exp_f32_e32 v57, v57
	v_exp_f32_e32 v58, v58
	v_exp_f32_e32 v59, v59
	v_add_f32_e32 v56, 1.0, v56
	v_add_f32_e32 v57, 1.0, v57
	v_add_f32_e32 v58, 1.0, v58
	v_add_f32_e32 v59, 1.0, v59
	v_rcp_f32_e32 v56, v56
	v_rcp_f32_e32 v58, v58
	v_rcp_f32_e32 v59, v59
	v_rcp_f32_e32 v57, v57
	v_pk_mul_f32 v[58:59], v[58:59], s[10:11] op_sel_hi:[1,0]
	v_pk_mul_f32 v[56:57], v[56:57], s[10:11] op_sel_hi:[1,0]
	s_nop 0
	v_cvt_pk_bf16_f32 v56, v56, v57
	v_cvt_pk_bf16_f32 v57, v58, v59
	global_store_dwordx2 v[64:65], v[56:57], off offset:32
	global_load_dwordx4 v[56:59], v[116:117], off offset:2176
	s_waitcnt vmcnt(0)
	v_add_f32_e32 v52, v52, v56
	v_add_f32_e32 v53, v53, v57
	v_add_f32_e32 v54, v54, v58
	v_add_f32_e32 v55, v55, v59
	v_mul_f32_e32 v52, 0xbfb8aa3b, v52
	v_mul_f32_e32 v53, 0xbfb8aa3b, v53
	v_mul_f32_e32 v54, 0xbfb8aa3b, v54
	v_mul_f32_e32 v55, 0xbfb8aa3b, v55
	v_exp_f32_e32 v52, v52
	v_exp_f32_e32 v53, v53
	v_exp_f32_e32 v54, v54
	v_exp_f32_e32 v55, v55
	v_add_f32_e32 v52, 1.0, v52
	v_add_f32_e32 v53, 1.0, v53
	v_add_f32_e32 v54, 1.0, v54
	v_add_f32_e32 v55, 1.0, v55
	v_rcp_f32_e32 v52, v52
	v_rcp_f32_e32 v54, v54
	v_rcp_f32_e32 v55, v55
	v_rcp_f32_e32 v53, v53
	v_pk_mul_f32 v[54:55], v[54:55], s[10:11] op_sel_hi:[1,0]
	v_pk_mul_f32 v[52:53], v[52:53], s[10:11] op_sel_hi:[1,0]
	s_nop 0
	v_cvt_pk_bf16_f32 v52, v52, v53
	v_cvt_pk_bf16_f32 v53, v54, v55
	global_store_dwordx2 v[64:65], v[52:53], off offset:64
	global_load_dwordx4 v[52:55], v[116:117], off offset:2240
	s_waitcnt vmcnt(0)
	v_add_f32_e32 v48, v48, v52
	v_add_f32_e32 v49, v49, v53
	v_add_f32_e32 v50, v50, v54
	v_add_f32_e32 v51, v51, v55
	v_mul_f32_e32 v48, 0xbfb8aa3b, v48
	v_mul_f32_e32 v49, 0xbfb8aa3b, v49
	v_mul_f32_e32 v50, 0xbfb8aa3b, v50
	v_mul_f32_e32 v51, 0xbfb8aa3b, v51
	v_exp_f32_e32 v48, v48
	v_exp_f32_e32 v49, v49
	v_exp_f32_e32 v50, v50
	v_exp_f32_e32 v51, v51
	v_add_f32_e32 v48, 1.0, v48
	v_add_f32_e32 v49, 1.0, v49
	v_add_f32_e32 v50, 1.0, v50
	v_add_f32_e32 v51, 1.0, v51
	v_rcp_f32_e32 v48, v48
	v_rcp_f32_e32 v50, v50
	v_rcp_f32_e32 v51, v51
	v_rcp_f32_e32 v49, v49
	v_or_b32_e32 v52, 0x50, v120
	v_ashrrev_i32_e32 v53, 31, v52
	v_pk_mul_f32 v[50:51], v[50:51], s[10:11] op_sel_hi:[1,0]
	v_pk_mul_f32 v[48:49], v[48:49], s[10:11] op_sel_hi:[1,0]
	v_lshlrev_b64 v[52:53], 10, v[52:53]
	v_cvt_pk_bf16_f32 v48, v48, v49
	v_cvt_pk_bf16_f32 v49, v50, v51
	global_store_dwordx2 v[64:65], v[48:49], off offset:96
	global_load_dwordx4 v[48:51], v[116:117], off offset:2048
	s_waitcnt vmcnt(0)
; template <class Epi>
; DI void gemm_tile(char* smem, const bf16_t* __restrict__ A0, int lda0, int ksplit, const bf16_t* __restrict__ A1, int lda1,
;                   const bf16_t* __restrict__ Bt, int K, int row0, int col0, const Epi& epi, int tid) {
;     ...
; #pragma unroll
;   for (int m = 0; m < 8; ++m)
; #pragma unroll
;     for (int n = 0; n < 4; ++n) epi(row0 + wr * 128 + m * 16 + fr, col0 + wc * 64 + n * 16 + fq * 4, acc[m][n]);
	v_add_f32_e32 v44, v44, v48
	v_add_f32_e32 v45, v45, v49
	v_add_f32_e32 v46, v46, v50
	v_add_f32_e32 v47, v47, v51
	v_mul_f32_e32 v44, 0xbfb8aa3b, v44
	v_mul_f32_e32 v45, 0xbfb8aa3b, v45
	v_mul_f32_e32 v46, 0xbfb8aa3b, v46
	v_mul_f32_e32 v47, 0xbfb8aa3b, v47
	v_exp_f32_e32 v44, v44
	v_exp_f32_e32 v45, v45
	v_exp_f32_e32 v46, v46
	v_exp_f32_e32 v47, v47
	v_add_f32_e32 v44, 1.0, v44
	v_add_f32_e32 v45, 1.0, v45
	v_add_f32_e32 v46, 1.0, v46
	v_add_f32_e32 v47, 1.0, v47
	v_rcp_f32_e32 v44, v44
	v_rcp_f32_e32 v46, v46
	v_rcp_f32_e32 v47, v47
	v_rcp_f32_e32 v45, v45
	v_lshl_add_u64 v[48:49], s[0:1], 0, v[52:53]
	v_lshl_add_u64 v[48:49], v[48:49], 0, v[118:119]
	v_pk_mul_f32 v[46:47], v[46:47], s[10:11] op_sel_hi:[1,0]
	v_pk_mul_f32 v[44:45], v[44:45], s[10:11] op_sel_hi:[1,0]
	s_nop 0
	v_cvt_pk_bf16_f32 v44, v44, v45
	v_cvt_pk_bf16_f32 v45, v46, v47
	global_store_dwordx2 v[48:49], v[44:45], off
	global_load_dwordx4 v[44:47], v[116:117], off offset:2112
	s_waitcnt vmcnt(0)
	v_add_f32_e32 v40, v40, v44
	v_add_f32_e32 v41, v41, v45
	v_add_f32_e32 v42, v42, v46
	v_add_f32_e32 v43, v43, v47
	v_mul_f32_e32 v40, 0xbfb8aa3b, v40
	v_mul_f32_e32 v41, 0xbfb8aa3b, v41
	v_mul_f32_e32 v42, 0xbfb8aa3b, v42
	v_mul_f32_e32 v43, 0xbfb8aa3b, v43
	v_exp_f32_e32 v40, v40
	v_exp_f32_e32 v41, v41
	v_exp_f32_e32 v42, v42
	v_exp_f32_e32 v43, v43
	v_add_f32_e32 v40, 1.0, v40
	v_add_f32_e32 v41, 1.0, v41
	v_add_f32_e32 v42, 1.0, v42
	v_add_f32_e32 v43, 1.0, v43
	v_rcp_f32_e32 v40, v40
	v_rcp_f32_e32 v42, v42
	v_rcp_f32_e32 v43, v43
	v_rcp_f32_e32 v41, v41
	v_pk_mul_f32 v[42:43], v[42:43], s[10:11] op_sel_hi:[1,0]
	v_pk_mul_f32 v[40:41], v[40:41], s[10:11] op_sel_hi:[1,0]
	s_nop 0
	v_cvt_pk_bf16_f32 v40, v40, v41
	v_cvt_pk_bf16_f32 v41, v42, v43
	global_store_dwordx2 v[48:49], v[40:41], off offset:32
	global_load_dwordx4 v[40:43], v[116:117], off offset:2176
	s_waitcnt vmcnt(0)
	v_add_f32_e32 v36, v36, v40
	v_add_f32_e32 v37, v37, v41
	v_add_f32_e32 v38, v38, v42
	v_add_f32_e32 v39, v39, v43
	v_mul_f32_e32 v36, 0xbfb8aa3b, v36
	v_mul_f32_e32 v37, 0xbfb8aa3b, v37
	v_mul_f32_e32 v38, 0xbfb8aa3b, v38
	v_mul_f32_e32 v39, 0xbfb8aa3b, v39
	v_exp_f32_e32 v36, v36
	v_exp_f32_e32 v37, v37
	v_exp_f32_e32 v38, v38
	v_exp_f32_e32 v39, v39
	v_add_f32_e32 v36, 1.0, v36
	v_add_f32_e32 v37, 1.0, v37
	v_add_f32_e32 v38, 1.0, v38
	v_add_f32_e32 v39, 1.0, v39
	v_rcp_f32_e32 v36, v36
	v_rcp_f32_e32 v38, v38
	v_rcp_f32_e32 v39, v39
	v_rcp_f32_e32 v37, v37
	v_pk_mul_f32 v[38:39], v[38:39], s[10:11] op_sel_hi:[1,0]
	v_pk_mul_f32 v[36:37], v[36:37], s[10:11] op_sel_hi:[1,0]
	s_nop 0
	v_cvt_pk_bf16_f32 v36, v36, v37
	v_cvt_pk_bf16_f32 v37, v38, v39
	global_store_dwordx2 v[48:49], v[36:37], off offset:64
	global_load_dwordx4 v[36:39], v[116:117], off offset:2240
	s_waitcnt vmcnt(0)
	v_add_f32_e32 v32, v32, v36
	v_add_f32_e32 v33, v33, v37
	v_add_f32_e32 v34, v34, v38
	v_add_f32_e32 v35, v35, v39
	v_mul_f32_e32 v32, 0xbfb8aa3b, v32
	v_mul_f32_e32 v33, 0xbfb8aa3b, v33
	v_mul_f32_e32 v34, 0xbfb8aa3b, v34
	v_mul_f32_e32 v35, 0xbfb8aa3b, v35
	v_exp_f32_e32 v32, v32
	v_exp_f32_e32 v33, v33
	v_exp_f32_e32 v34, v34
	v_exp_f32_e32 v35, v35
	v_add_f32_e32 v32, 1.0, v32
	v_add_f32_e32 v33, 1.0, v33
	v_add_f32_e32 v34, 1.0, v34
	v_add_f32_e32 v35, 1.0, v35
	v_rcp_f32_e32 v32, v32
	v_rcp_f32_e32 v34, v34
	v_rcp_f32_e32 v35, v35
	v_rcp_f32_e32 v33, v33
	v_or_b32_e32 v36, 0x60, v120
	v_ashrrev_i32_e32 v37, 31, v36
	v_pk_mul_f32 v[34:35], v[34:35], s[10:11] op_sel_hi:[1,0]
	v_pk_mul_f32 v[32:33], v[32:33], s[10:11] op_sel_hi:[1,0]
	v_lshlrev_b64 v[36:37], 10, v[36:37]
	v_cvt_pk_bf16_f32 v32, v32, v33
	v_cvt_pk_bf16_f32 v33, v34, v35
	global_store_dwordx2 v[48:49], v[32:33], off offset:96
	global_load_dwordx4 v[32:35], v[116:117], off offset:2048
	s_waitcnt vmcnt(0)
	v_add_f32_e32 v28, v28, v32
	v_add_f32_e32 v29, v29, v33
	v_add_f32_e32 v30, v30, v34
	v_add_f32_e32 v31, v31, v35
	v_mul_f32_e32 v28, 0xbfb8aa3b, v28
	v_mul_f32_e32 v29, 0xbfb8aa3b, v29
	v_mul_f32_e32 v30, 0xbfb8aa3b, v30
	v_mul_f32_e32 v31, 0xbfb8aa3b, v31
	v_exp_f32_e32 v28, v28
	v_exp_f32_e32 v29, v29
	v_exp_f32_e32 v30, v30
	v_exp_f32_e32 v31, v31
	v_add_f32_e32 v28, 1.0, v28
	v_add_f32_e32 v29, 1.0, v29
	v_add_f32_e32 v30, 1.0, v30
	v_add_f32_e32 v31, 1.0, v31
	v_rcp_f32_e32 v28, v28
	v_rcp_f32_e32 v30, v30
	v_rcp_f32_e32 v31, v31
	v_rcp_f32_e32 v29, v29
	v_lshl_add_u64 v[32:33], s[0:1], 0, v[36:37]
	v_lshl_add_u64 v[32:33], v[32:33], 0, v[118:119]
	v_pk_mul_f32 v[30:31], v[30:31], s[10:11] op_sel_hi:[1,0]
	v_pk_mul_f32 v[28:29], v[28:29], s[10:11] op_sel_hi:[1,0]
	s_nop 0
	v_cvt_pk_bf16_f32 v28, v28, v29
	v_cvt_pk_bf16_f32 v29, v30, v31
	global_store_dwordx2 v[32:33], v[28:29], off
	global_load_dwordx4 v[28:31], v[116:117], off offset:2112
	s_waitcnt vmcnt(0)
	v_add_f32_e32 v24, v24, v28
	v_add_f32_e32 v25, v25, v29
	v_add_f32_e32 v26, v26, v30
	v_add_f32_e32 v27, v27, v31
	v_mul_f32_e32 v24, 0xbfb8aa3b, v24
	v_mul_f32_e32 v25, 0xbfb8aa3b, v25
	v_mul_f32_e32 v26, 0xbfb8aa3b, v26
	v_mul_f32_e32 v27, 0xbfb8aa3b, v27
	v_exp_f32_e32 v24, v24
	v_exp_f32_e32 v25, v25
	v_exp_f32_e32 v26, v26
	v_exp_f32_e32 v27, v27
	v_add_f32_e32 v24, 1.0, v24
	v_add_f32_e32 v25, 1.0, v25
	v_add_f32_e32 v26, 1.0, v26
	v_add_f32_e32 v27, 1.0, v27
	v_rcp_f32_e32 v24, v24
	v_rcp_f32_e32 v26, v26
	v_rcp_f32_e32 v27, v27
	v_rcp_f32_e32 v25, v25
	v_pk_mul_f32 v[26:27], v[26:27], s[10:11] op_sel_hi:[1,0]
	v_pk_mul_f32 v[24:25], v[24:25], s[10:11] op_sel_hi:[1,0]
	s_nop 0
	v_cvt_pk_bf16_f32 v24, v24, v25
	v_cvt_pk_bf16_f32 v25, v26, v27
	global_store_dwordx2 v[32:33], v[24:25], off offset:32
	global_load_dwordx4 v[24:27], v[116:117], off offset:2176
	s_waitcnt vmcnt(0)
; template <class Epi>
; DI void gemm_tile(char* smem, const bf16_t* __restrict__ A0, int lda0, int ksplit, const bf16_t* __restrict__ A1, int lda1,
;                   const bf16_t* __restrict__ Bt, int K, int row0, int col0, const Epi& epi, int tid) {
;     ...
; #pragma unroll
;   for (int m = 0; m < 8; ++m)
; #pragma unroll
;     for (int n = 0; n < 4; ++n) epi(row0 + wr * 128 + m * 16 + fr, col0 + wc * 64 + n * 16 + fq * 4, acc[m][n]);
; template <class Epi>
; DI void gemm_phase(char* smem, const bf16_t* A0, int lda0, int ksplit, const bf16_t* A1, int lda1, const bf16_t* Bt, int K, int nN, const Epi& epi, int tid) {
;     ...
;     for (int u = blockIdx.x; u < ntiles; u += G) { const int rt = u / nN, ct = u % nN; gemm_tile(smem, A0, lda0, ksplit, A1, lda1, Bt, K, rt * 256, ct * 128, epi, tid); }
	v_add_f32_e32 v20, v20, v24
	v_add_f32_e32 v21, v21, v25
	v_add_f32_e32 v22, v22, v26
	v_add_f32_e32 v23, v23, v27
	v_mul_f32_e32 v20, 0xbfb8aa3b, v20
	v_mul_f32_e32 v21, 0xbfb8aa3b, v21
	v_mul_f32_e32 v22, 0xbfb8aa3b, v22
	v_mul_f32_e32 v23, 0xbfb8aa3b, v23
	v_exp_f32_e32 v20, v20
	v_exp_f32_e32 v21, v21
	v_exp_f32_e32 v22, v22
	v_exp_f32_e32 v23, v23
	v_add_f32_e32 v20, 1.0, v20
	v_add_f32_e32 v21, 1.0, v21
	v_add_f32_e32 v22, 1.0, v22
	v_add_f32_e32 v23, 1.0, v23
	v_rcp_f32_e32 v20, v20
	v_rcp_f32_e32 v22, v22
	v_rcp_f32_e32 v23, v23
	v_rcp_f32_e32 v21, v21
	v_pk_mul_f32 v[22:23], v[22:23], s[10:11] op_sel_hi:[1,0]
	v_pk_mul_f32 v[20:21], v[20:21], s[10:11] op_sel_hi:[1,0]
	s_nop 0
	v_cvt_pk_bf16_f32 v20, v20, v21
	v_cvt_pk_bf16_f32 v21, v22, v23
	global_store_dwordx2 v[32:33], v[20:21], off offset:64
	global_load_dwordx4 v[20:23], v[116:117], off offset:2240
	s_waitcnt vmcnt(0)
	v_add_f32_e32 v16, v16, v20
	v_add_f32_e32 v17, v17, v21
	v_add_f32_e32 v18, v18, v22
	v_add_f32_e32 v19, v19, v23
	v_mul_f32_e32 v16, 0xbfb8aa3b, v16
	v_mul_f32_e32 v17, 0xbfb8aa3b, v17
	v_mul_f32_e32 v18, 0xbfb8aa3b, v18
	v_mul_f32_e32 v19, 0xbfb8aa3b, v19
	v_exp_f32_e32 v16, v16
	v_exp_f32_e32 v17, v17
	v_exp_f32_e32 v18, v18
	v_exp_f32_e32 v19, v19
	v_add_f32_e32 v16, 1.0, v16
	v_add_f32_e32 v17, 1.0, v17
	v_add_f32_e32 v18, 1.0, v18
	v_add_f32_e32 v19, 1.0, v19
	v_rcp_f32_e32 v16, v16
	v_rcp_f32_e32 v18, v18
	v_rcp_f32_e32 v19, v19
	v_rcp_f32_e32 v17, v17
	v_or_b32_e32 v20, 0x70, v120
	v_ashrrev_i32_e32 v21, 31, v20
	v_pk_mul_f32 v[18:19], v[18:19], s[10:11] op_sel_hi:[1,0]
	v_pk_mul_f32 v[16:17], v[16:17], s[10:11] op_sel_hi:[1,0]
	v_lshlrev_b64 v[20:21], 10, v[20:21]
	v_cvt_pk_bf16_f32 v16, v16, v17
	v_cvt_pk_bf16_f32 v17, v18, v19
	global_store_dwordx2 v[32:33], v[16:17], off offset:96
	global_load_dwordx4 v[16:19], v[116:117], off offset:2048
	s_waitcnt vmcnt(0)
	v_add_f32_e32 v12, v12, v16
	v_add_f32_e32 v13, v13, v17
	v_add_f32_e32 v14, v14, v18
	v_add_f32_e32 v15, v15, v19
	v_mul_f32_e32 v12, 0xbfb8aa3b, v12
	v_mul_f32_e32 v13, 0xbfb8aa3b, v13
	v_mul_f32_e32 v14, 0xbfb8aa3b, v14
	v_mul_f32_e32 v15, 0xbfb8aa3b, v15
	v_exp_f32_e32 v12, v12
	v_exp_f32_e32 v13, v13
	v_exp_f32_e32 v14, v14
	v_exp_f32_e32 v15, v15
	v_add_f32_e32 v12, 1.0, v12
	v_add_f32_e32 v13, 1.0, v13
	v_add_f32_e32 v14, 1.0, v14
	v_add_f32_e32 v15, 1.0, v15
	v_rcp_f32_e32 v12, v12
	v_rcp_f32_e32 v14, v14
	v_rcp_f32_e32 v15, v15
	v_rcp_f32_e32 v13, v13
	v_lshl_add_u64 v[16:17], s[0:1], 0, v[20:21]
	v_lshl_add_u64 v[16:17], v[16:17], 0, v[118:119]
	v_pk_mul_f32 v[14:15], v[14:15], s[10:11] op_sel_hi:[1,0]
	v_pk_mul_f32 v[12:13], v[12:13], s[10:11] op_sel_hi:[1,0]
	s_nop 0
	v_cvt_pk_bf16_f32 v12, v12, v13
	v_cvt_pk_bf16_f32 v13, v14, v15
	global_store_dwordx2 v[16:17], v[12:13], off
	global_load_dwordx4 v[12:15], v[116:117], off offset:2112
	s_waitcnt vmcnt(0)
	v_add_f32_e32 v8, v8, v12
	v_add_f32_e32 v9, v9, v13
	v_add_f32_e32 v10, v10, v14
	v_add_f32_e32 v11, v11, v15
	v_mul_f32_e32 v8, 0xbfb8aa3b, v8
	v_mul_f32_e32 v9, 0xbfb8aa3b, v9
	v_mul_f32_e32 v10, 0xbfb8aa3b, v10
	v_mul_f32_e32 v11, 0xbfb8aa3b, v11
	v_exp_f32_e32 v8, v8
	v_exp_f32_e32 v9, v9
	v_exp_f32_e32 v10, v10
	v_exp_f32_e32 v11, v11
	v_add_f32_e32 v8, 1.0, v8
	v_add_f32_e32 v9, 1.0, v9
	v_add_f32_e32 v10, 1.0, v10
	v_add_f32_e32 v11, 1.0, v11
	v_rcp_f32_e32 v8, v8
	v_rcp_f32_e32 v10, v10
	v_rcp_f32_e32 v11, v11
	v_rcp_f32_e32 v9, v9
	v_pk_mul_f32 v[10:11], v[10:11], s[10:11] op_sel_hi:[1,0]
	v_pk_mul_f32 v[8:9], v[8:9], s[10:11] op_sel_hi:[1,0]
	s_nop 0
	v_cvt_pk_bf16_f32 v8, v8, v9
	v_cvt_pk_bf16_f32 v9, v10, v11
	global_store_dwordx2 v[16:17], v[8:9], off offset:32
	global_load_dwordx4 v[8:11], v[116:117], off offset:2176
	s_waitcnt vmcnt(0)
	v_add_f32_e32 v4, v4, v8
	v_add_f32_e32 v5, v5, v9
	v_add_f32_e32 v6, v6, v10
	v_add_f32_e32 v7, v7, v11
	v_mul_f32_e32 v4, 0xbfb8aa3b, v4
	v_mul_f32_e32 v5, 0xbfb8aa3b, v5
	v_mul_f32_e32 v6, 0xbfb8aa3b, v6
	v_mul_f32_e32 v7, 0xbfb8aa3b, v7
	v_exp_f32_e32 v4, v4
	v_exp_f32_e32 v5, v5
	v_exp_f32_e32 v6, v6
	v_exp_f32_e32 v7, v7
	v_add_f32_e32 v4, 1.0, v4
	v_add_f32_e32 v5, 1.0, v5
	v_add_f32_e32 v6, 1.0, v6
	v_add_f32_e32 v7, 1.0, v7
	v_rcp_f32_e32 v4, v4
	v_rcp_f32_e32 v6, v6
	v_rcp_f32_e32 v7, v7
	v_rcp_f32_e32 v5, v5
	v_pk_mul_f32 v[6:7], v[6:7], s[10:11] op_sel_hi:[1,0]
	v_pk_mul_f32 v[4:5], v[4:5], s[10:11] op_sel_hi:[1,0]
	s_add_i32 s11, s11, s15
	v_cvt_pk_bf16_f32 v4, v4, v5
	v_cvt_pk_bf16_f32 v5, v6, v7
	global_store_dwordx2 v[16:17], v[4:5], off offset:64
	global_load_dwordx4 v[4:7], v[116:117], off offset:2240
	s_cmpk_lt_i32 s17, 0x200
	s_waitcnt vmcnt(0)
	v_add_f32_e32 v0, v0, v4
	v_add_f32_e32 v1, v1, v5
	v_add_f32_e32 v2, v2, v6
	v_add_f32_e32 v3, v3, v7
	v_mul_f32_e32 v0, 0xbfb8aa3b, v0
	v_mul_f32_e32 v1, 0xbfb8aa3b, v1
	v_mul_f32_e32 v2, 0xbfb8aa3b, v2
	v_mul_f32_e32 v3, 0xbfb8aa3b, v3
	v_exp_f32_e32 v0, v0
	v_exp_f32_e32 v1, v1
	v_exp_f32_e32 v2, v2
	v_exp_f32_e32 v3, v3
	v_add_f32_e32 v0, 1.0, v0
	v_add_f32_e32 v1, 1.0, v1
	v_add_f32_e32 v2, 1.0, v2
	v_add_f32_e32 v3, 1.0, v3
	v_rcp_f32_e32 v0, v0
	v_rcp_f32_e32 v2, v2
	v_rcp_f32_e32 v3, v3
	v_rcp_f32_e32 v1, v1
	v_pk_mul_f32 v[2:3], v[2:3], s[10:11] op_sel_hi:[1,0]
	v_pk_mul_f32 v[0:1], v[0:1], s[10:11] op_sel_hi:[1,0]
	s_nop 0
	v_cvt_pk_bf16_f32 v0, v0, v1
	v_cvt_pk_bf16_f32 v1, v2, v3
	global_store_dwordx2 v[16:17], v[0:1], off offset:96
	s_cbranch_scc1 .LBB0_562

; #define LWRITE(S, buf) do { bf16_t* sA_ = sbase + (buf) * BUF; bf16_t* sB_ = sA_ + 256 * PITCH; \
;     _Pragma("unroll") for (int i_ = 0; i_ < 4; ++i_) *(u32x4*)(sA_ + (sr + i_ * 64) * PITCH + scv * 8) = ra[S][i_]; \
;     _Pragma("unroll") for (int i_ = 0; i_ < 2; ++i_) *(u32x4*)(sB_ + (sr + i_ * 64) * PITCH + scv * 8) = rb[S][i_]; } while (0)
; template <class Epi>
; DI void gemm_tile(char* smem, const bf16_t* __restrict__ A0, int lda0, int ksplit, const bf16_t* __restrict__ A1, int lda1,
;                   const bf16_t* __restrict__ Bt, int K, int row0, int col0, const Epi& epi, int tid) {
;   constexpr int BK = 32, PITCH = 40, BUF = (256 + 128) * PITCH;
;   bf16_t* sbase = (bf16_t*)smem;
;   const int lane = tid & 63, wid = tid >> 6, wr = wid >> 1, wc = wid & 1, fr = lane & 15, fq = lane >> 4;
;   f32x4 acc[8][4];
; #pragma unroll
;   for (int m = 0; m < 8; ++m)
; #pragma unroll
;     for (int n = 0; n < 4; ++n) acc[m][n] = (f32x4){0.f, 0.f, 0.f, 0.f};
;   u32x4 ra[2][4], rb[2][2];
;   const int nk = K / BK;
;   const int sr = tid >> 2, scv = tid & 3;
;     ...
;   __syncthreads();
;   {
;     const int last = nk - 1;
;     GLOAD(0, 0);
;     __builtin_amdgcn_sched_barrier(0);
;     GLOAD(1, 1);
;     __builtin_amdgcn_sched_barrier(0);
;     LWRITE(0, 0);
;     __builtin_amdgcn_sched_barrier(0);
;     GLOAD(0, (2 < last ? 2 : last));
;     __builtin_amdgcn_sched_barrier(0);
;     __syncthreads();
;     for (int kt = 0; kt < nk; kt += 2) {
;       LWRITE(1, 1);
;       __builtin_amdgcn_sched_barrier(0);
;       GLOAD(1, (kt + 3 < last ? kt + 3 : last));
;       __builtin_amdgcn_sched_barrier(0);
;       COMPUTE(0);
;       __syncthreads();
;       LWRITE(0, 0);
;       __builtin_amdgcn_sched_barrier(0);
;       GLOAD(0, (kt + 4 < last ? kt + 4 : last));
;       __builtin_amdgcn_sched_barrier(0);
;       COMPUTE(1);
;       __syncthreads();
;     }
; template <class Epi>
; DI void gemm_phase(char* smem, const bf16_t* A0, int lda0, int ksplit, const bf16_t* A1, int lda1, const bf16_t* Bt, int K, int nN, const Epi& epi, int tid) {
;     ...
;     const int x = blockIdx.x & 7, l = blockIdx.x >> 3, L = G >> 3, per = 8 * nN, tot = 2 * per;
;     for (int q = l; q < tot; q += L) { const int rgl = q / per, rem = q % per, ct = rem >> 3, rt = (x * 2 + rgl) * 8 + (rem & 7);
;       gemm_tile(smem, A0, lda0, ksplit, A1, lda1, Bt, K, rt * 256, ct * 128, epi, tid); }
.LBB0_564:
.LBB0_565:
	s_cmpk_gt_u32 s96, 0x1ff
	s_cbranch_scc1 .LBB0_568
	v_and_b32_e32 v0, 3, v136
	s_waitcnt lgkmcnt(0)
	s_load_dwordx16 s[56:71], s[74:75], 0x40
	v_lshlrev_b32_e32 v0, 4, v0
	v_mov_b32_e32 v1, 0
	v_ashrrev_i32_e32 v122, 2, v137
	v_lshl_add_u64 v[112:113], s[4:5], 0, v[0:1]
	v_lshl_add_u64 v[114:115], s[6:7], 0, v[0:1]
	v_bfe_u32 v1, v136, 4, 2
	s_movk_i32 s4, 0x40
	v_and_b32_e32 v4, 0x4f, v137
	v_and_b32_e32 v123, 0xffffff8f, v137
	v_or_b32_e32 v7, 0x70, v137
	s_ashr_i32 s8, s12, 3
	s_lshr_b32 s9, s96, 3
	s_lshl_b32 s10, s96, 1
	v_add_u32_e32 v0, 0, v0
	v_mul_lo_u32 v2, v122, s4
	v_and_b32_e32 v3, 64, v137
	v_lshl_add_u32 v5, v1, 4, 0
	v_mul_u32_u24_e32 v4, 0x40, v4
	v_mul_lo_u32 v6, v123, s4
	v_mul_lo_u32 v7, v7, s4
	s_and_b32 s10, s10, 14
	v_lshl_or_b32 v124, v1, 2, v3
	s_lshl_b32 s7, s9, 8
	s_lshl_b32 s11, s8, 8
	s_lshl_b32 s15, s9, 4
	s_lshl_b32 s16, s8, 4
	s_mov_b64 s[4:5], 0x2000
	s_movk_i32 s17, 0x2000
	v_add_u32_e32 v125, v0, v2
	v_add_u32_e32 v126, v5, v4
	v_add_u32_e32 v127, v5, v6
	v_add_u32_e32 v128, v5, v7
	v_mbcnt_lo_u32_b32 v2, -1, 0
	v_mbcnt_hi_u32_b32 v2, -1, v2
	v_bfe_u32 v4, v2, 3, 1
	v_bfe_u32 v2, v2, 5, 1
	v_mul_u32_u24_e32 v4, 48, v4
	v_mul_u32_u24_e32 v2, 48, v2
	v_xor_b32_e32 v125, v125, v2
	v_xor_b32_e32 v126, v126, v4
	v_xor_b32_e32 v127, v127, v4
	v_xor_b32_e32 v128, v128, v4
	s_mov_b32 s6, 0x3f1b4598
.LBB0_567:
	s_ashr_i32 s18, s9, 31
	s_lshr_b32 s18, s18, 27
	s_add_i32 s18, s9, s18
	s_ashr_i32 s19, s18, 5
	s_add_i32 s18, s19, s10
	s_lshl_b32 s18, s18, 11
	s_and_b32 s20, s7, 0x700
	s_or_b32 s18, s18, s20
	v_add_u32_e32 v0, s18, v122
	v_ashrrev_i32_e32 v1, 31, v0
	v_lshlrev_b64 v[0:1], 9, v[0:1]
	s_lshl_b32 s19, s19, 9
	v_lshl_add_u64 v[24:25], v[112:113], 0, v[0:1]
	s_mov_b32 s20, 0x8000
	s_sub_i32 s19, s15, s19
	v_add_co_u32_e32 v4, vcc, s20, v24
	s_and_b32 s19, s19, 0xffffff80
	s_nop 0
	v_addc_co_u32_e32 v5, vcc, 0, v25, vcc
	s_mov_b32 s20, 0x10000
	v_add_co_u32_e32 v8, vcc, s20, v24
	v_add_u32_e32 v16, s19, v122
	s_nop 0
	v_addc_co_u32_e32 v9, vcc, 0, v25, vcc
	s_mov_b32 s20, 0x18000
	v_ashrrev_i32_e32 v17, 31, v16
	v_add_co_u32_e32 v12, vcc, s20, v24
	v_lshlrev_b64 v[16:17], 7, v[16:17]
	s_nop 0
	v_addc_co_u32_e32 v13, vcc, 0, v25, vcc
	v_lshl_add_u64 v[40:41], v[114:115], 0, v[16:17]
	v_add_co_u32_e32 v20, vcc, s17, v40
	s_waitcnt lgkmcnt(0)
	s_nop 0
	v_addc_co_u32_e32 v21, vcc, 0, v41, vcc
	s_barrier
	global_load_dwordx4 v[0:3], v[24:25], off
	s_nop 0
	global_load_dwordx4 v[4:7], v[4:5], off
	s_nop 0
	global_load_dwordx4 v[8:11], v[8:9], off
	s_nop 0
	global_load_dwordx4 v[12:15], v[12:13], off
	s_nop 0
	global_load_dwordx4 v[16:19], v[40:41], off
	s_nop 0
	global_load_dwordx4 v[20:23], v[20:21], off
	s_mov_b64 s[20:21], 0x8000
	v_lshl_add_u64 v[28:29], v[24:25], 0, s[20:21]
	s_mov_b64 s[20:21], 0x10000
	v_lshl_add_u64 v[32:33], v[24:25], 0, s[20:21]
	s_mov_b64 s[20:21], 0x18000
	v_lshl_add_u64 v[36:37], v[24:25], 0, s[20:21]
	v_lshl_add_u64 v[44:45], v[40:41], 0, s[4:5]
	global_load_dwordx4 v[24:27], v[24:25], off offset:64
	s_nop 0
	global_load_dwordx4 v[28:31], v[28:29], off offset:64
	s_nop 0
	global_load_dwordx4 v[32:35], v[32:33], off offset:64
	s_nop 0
	global_load_dwordx4 v[36:39], v[36:37], off offset:64
	s_nop 0
	global_load_dwordx4 v[40:43], v[40:41], off offset:64
	s_nop 0
	global_load_dwordx4 v[44:47], v[44:45], off offset:64
	s_waitcnt vmcnt(11)
	ds_write_b128 v125, v[0:3]
	s_waitcnt vmcnt(10)
	ds_write_b128 v125, v[4:7] offset:4096
	s_waitcnt vmcnt(9)
	ds_write_b128 v125, v[8:11] offset:8192
	s_waitcnt vmcnt(8)
	ds_write_b128 v125, v[12:15] offset:12288
	s_waitcnt vmcnt(7)
	ds_write_b128 v125, v[16:19] offset:16384
	s_waitcnt vmcnt(6)
	ds_write_b128 v125, v[20:23] offset:20480
	s_waitcnt lgkmcnt(0)
	s_barrier
	s_waitcnt vmcnt(5)
	ds_write_b128 v125, v[24:27] offset:24576
	s_waitcnt vmcnt(4)
	ds_write_b128 v125, v[28:31] offset:28672
	s_waitcnt vmcnt(3)
	ds_write_b128 v125, v[32:35] offset:32768
	s_waitcnt vmcnt(2)
	ds_write_b128 v125, v[36:39] offset:36864
	s_waitcnt vmcnt(1)
	ds_write_b128 v125, v[40:43] offset:40960
	s_waitcnt vmcnt(0)
	ds_write_b128 v125, v[44:47] offset:45056
	ds_read_b128 v[0:3], v126 offset:16384
	ds_read_b128 v[4:7], v126 offset:17408
	ds_read_b128 v[8:11], v126 offset:18432
	ds_read_b128 v[12:15], v126 offset:19456
	ds_read_b128 v[16:19], v127
	ds_read_b128 v[20:23], v127 offset:1024
	ds_read_b128 v[48:51], v127 offset:2048
	ds_read_b128 v[52:55], v127 offset:3072
	ds_read_b128 v[56:59], v127 offset:4096
	ds_read_b128 v[60:63], v127 offset:5120
	ds_read_b128 v[64:67], v127 offset:6144
	ds_read_b128 v[68:71], v128
	s_setprio 1
	s_waitcnt lgkmcnt(7)
	v_mfma_f32_16x16x32_bf16 v[72:75], v[0:3], v[16:19], 0
	v_mfma_f32_16x16x32_bf16 v[76:79], v[4:7], v[16:19], 0
	v_mfma_f32_16x16x32_bf16 v[80:83], v[8:11], v[16:19], 0
	v_mfma_f32_16x16x32_bf16 v[16:19], v[12:15], v[16:19], 0
	s_waitcnt lgkmcnt(6)
	v_mfma_f32_16x16x32_bf16 v[84:87], v[0:3], v[20:23], 0
	v_mfma_f32_16x16x32_bf16 v[88:91], v[4:7], v[20:23], 0
	v_mfma_f32_16x16x32_bf16 v[92:95], v[8:11], v[20:23], 0
	v_mfma_f32_16x16x32_bf16 v[20:23], v[12:15], v[20:23], 0
	s_waitcnt lgkmcnt(5)
	v_mfma_f32_16x16x32_bf16 v[116:119], v[0:3], v[48:51], 0
	v_mfma_f32_16x16x32_bf16 v[130:133], v[4:7], v[48:51], 0
	v_mfma_f32_16x16x32_bf16 v[138:141], v[8:11], v[48:51], 0
	v_mfma_f32_16x16x32_bf16 v[48:51], v[12:15], v[48:51], 0
	s_waitcnt lgkmcnt(4)
	v_mfma_f32_16x16x32_bf16 v[142:145], v[0:3], v[52:55], 0
	v_mfma_f32_16x16x32_bf16 v[146:149], v[4:7], v[52:55], 0
	v_mfma_f32_16x16x32_bf16 v[150:153], v[8:11], v[52:55], 0
	v_mfma_f32_16x16x32_bf16 v[52:55], v[12:15], v[52:55], 0
	s_waitcnt lgkmcnt(3)
	v_mfma_f32_16x16x32_bf16 v[154:157], v[0:3], v[56:59], 0
	v_mfma_f32_16x16x32_bf16 v[158:161], v[4:7], v[56:59], 0
	v_mfma_f32_16x16x32_bf16 v[162:165], v[8:11], v[56:59], 0
	v_mfma_f32_16x16x32_bf16 v[166:169], v[12:15], v[56:59], 0
	s_waitcnt lgkmcnt(2)
	v_mfma_f32_16x16x32_bf16 v[170:173], v[0:3], v[60:63], 0
	v_mfma_f32_16x16x32_bf16 v[174:177], v[4:7], v[60:63], 0
	v_mfma_f32_16x16x32_bf16 v[178:181], v[8:11], v[60:63], 0
	v_mfma_f32_16x16x32_bf16 v[182:185], v[12:15], v[60:63], 0
	s_waitcnt lgkmcnt(1)
	v_mfma_f32_16x16x32_bf16 v[186:189], v[0:3], v[64:67], 0
	v_mfma_f32_16x16x32_bf16 v[190:193], v[4:7], v[64:67], 0
	v_mfma_f32_16x16x32_bf16 v[196:199], v[8:11], v[64:67], 0
	v_mfma_f32_16x16x32_bf16 v[200:203], v[12:15], v[64:67], 0
	s_waitcnt lgkmcnt(0)
	v_mfma_f32_16x16x32_bf16 v[0:3], v[0:3], v[68:71], 0
	v_mfma_f32_16x16x32_bf16 v[4:7], v[4:7], v[68:71], 0
	v_mfma_f32_16x16x32_bf16 v[204:207], v[8:11], v[68:71], 0
	v_mfma_f32_16x16x32_bf16 v[208:211], v[12:15], v[68:71], 0
	s_setprio 0
	s_barrier
; #define LWRITE(S, buf) do { bf16_t* sA_ = sbase + (buf) * BUF; bf16_t* sB_ = sA_ + 256 * PITCH; \
;     _Pragma("unroll") for (int i_ = 0; i_ < 4; ++i_) *(u32x4*)(sA_ + (sr + i_ * 64) * PITCH + scv * 8) = ra[S][i_]; \
;     _Pragma("unroll") for (int i_ = 0; i_ < 2; ++i_) *(u32x4*)(sB_ + (sr + i_ * 64) * PITCH + scv * 8) = rb[S][i_]; } while (0)
; template <class Epi>
; DI void gemm_tile(char* smem, const bf16_t* __restrict__ A0, int lda0, int ksplit, const bf16_t* __restrict__ A1, int lda1,
;                   const bf16_t* __restrict__ Bt, int K, int row0, int col0, const Epi& epi, int tid) {
;     ...
;   __syncthreads();
;   {
;     const int last = nk - 1;
;     GLOAD(0, 0);
;     __builtin_amdgcn_sched_barrier(0);
;     GLOAD(1, 1);
;     __builtin_amdgcn_sched_barrier(0);
;     LWRITE(0, 0);
;     __builtin_amdgcn_sched_barrier(0);
;     GLOAD(0, (2 < last ? 2 : last));
;     __builtin_amdgcn_sched_barrier(0);
;     __syncthreads();
;     for (int kt = 0; kt < nk; kt += 2) {
;       LWRITE(1, 1);
;       __builtin_amdgcn_sched_barrier(0);
;       GLOAD(1, (kt + 3 < last ? kt + 3 : last));
;       __builtin_amdgcn_sched_barrier(0);
;       COMPUTE(0);
;       __syncthreads();
;       LWRITE(0, 0);
;       __builtin_amdgcn_sched_barrier(0);
;       GLOAD(0, (kt + 4 < last ? kt + 4 : last));
;       __builtin_amdgcn_sched_barrier(0);
;       COMPUTE(1);
;       __syncthreads();
	ds_write_b128 v125, v[24:27]
	ds_write_b128 v125, v[28:31] offset:4096
	ds_write_b128 v125, v[32:35] offset:8192
	ds_write_b128 v125, v[36:39] offset:12288
	ds_write_b128 v125, v[40:43] offset:16384
	ds_write_b128 v125, v[44:47] offset:20480
	ds_read_b128 v[8:11], v126 offset:40960
	ds_read_b128 v[212:215], v126 offset:41984
	ds_read_b128 v[216:219], v126 offset:43008
	ds_read_b128 v[220:223], v126 offset:44032
	ds_read_b128 v[12:15], v127 offset:26624
	ds_read_b128 v[24:27], v127 offset:27648
	ds_read_b128 v[28:31], v127 offset:28672
	ds_read_b128 v[32:35], v127 offset:29696
	ds_read_b128 v[36:39], v127 offset:24576
	ds_read_b128 v[224:227], v127 offset:30720
	ds_read_b128 v[40:43], v127 offset:25600
	ds_read_b128 v[228:231], v128 offset:24576
	s_setprio 1
	s_waitcnt lgkmcnt(3)
	v_mfma_f32_16x16x32_bf16 v[232:235], v[8:11], v[36:39], v[72:75]
	v_mfma_f32_16x16x32_bf16 v[236:239], v[212:215], v[36:39], v[76:79]
	v_mfma_f32_16x16x32_bf16 v[240:243], v[216:219], v[36:39], v[80:83]
	v_mfma_f32_16x16x32_bf16 v[244:247], v[220:223], v[36:39], v[16:19]
	s_waitcnt lgkmcnt(1)
	v_mfma_f32_16x16x32_bf16 v[108:111], v[8:11], v[40:43], v[84:87]
	v_mfma_f32_16x16x32_bf16 v[104:107], v[212:215], v[40:43], v[88:91]
	v_mfma_f32_16x16x32_bf16 v[100:103], v[216:219], v[40:43], v[92:95]
	v_mfma_f32_16x16x32_bf16 v[96:99], v[220:223], v[40:43], v[20:23]
	v_mfma_f32_16x16x32_bf16 v[92:95], v[8:11], v[12:15], v[116:119]
	v_mfma_f32_16x16x32_bf16 v[88:91], v[212:215], v[12:15], v[130:133]
	v_mfma_f32_16x16x32_bf16 v[84:87], v[216:219], v[12:15], v[138:141]
	v_mfma_f32_16x16x32_bf16 v[80:83], v[220:223], v[12:15], v[48:51]
	v_mfma_f32_16x16x32_bf16 v[76:79], v[8:11], v[24:27], v[142:145]
	v_mfma_f32_16x16x32_bf16 v[72:75], v[212:215], v[24:27], v[146:149]
	v_mfma_f32_16x16x32_bf16 v[68:71], v[216:219], v[24:27], v[150:153]
	v_mfma_f32_16x16x32_bf16 v[64:67], v[220:223], v[24:27], v[52:55]
	v_mfma_f32_16x16x32_bf16 v[60:63], v[8:11], v[28:31], v[154:157]
	v_mfma_f32_16x16x32_bf16 v[56:59], v[212:215], v[28:31], v[158:161]
	v_mfma_f32_16x16x32_bf16 v[52:55], v[216:219], v[28:31], v[162:165]
	v_mfma_f32_16x16x32_bf16 v[48:51], v[220:223], v[28:31], v[166:169]
	v_mfma_f32_16x16x32_bf16 v[44:47], v[8:11], v[32:35], v[170:173]
	v_mfma_f32_16x16x32_bf16 v[40:43], v[212:215], v[32:35], v[174:177]
	v_mfma_f32_16x16x32_bf16 v[36:39], v[216:219], v[32:35], v[178:181]
	v_mfma_f32_16x16x32_bf16 v[32:35], v[220:223], v[32:35], v[182:185]
	v_mfma_f32_16x16x32_bf16 v[28:31], v[8:11], v[224:227], v[186:189]
	v_mfma_f32_16x16x32_bf16 v[24:27], v[212:215], v[224:227], v[190:193]
	v_mfma_f32_16x16x32_bf16 v[20:23], v[216:219], v[224:227], v[196:199]
	v_mfma_f32_16x16x32_bf16 v[16:19], v[220:223], v[224:227], v[200:203]
	s_waitcnt lgkmcnt(0)
	v_mfma_f32_16x16x32_bf16 v[12:15], v[8:11], v[228:231], v[0:3]
	v_mfma_f32_16x16x32_bf16 v[8:11], v[212:215], v[228:231], v[4:7]
	v_mfma_f32_16x16x32_bf16 v[4:7], v[216:219], v[228:231], v[204:207]
	v_mfma_f32_16x16x32_bf16 v[0:3], v[220:223], v[228:231], v[208:211]
	s_setprio 0
	v_or_b32_e32 v118, s19, v124
	v_ashrrev_i32_e32 v119, 31, v118
	v_lshl_add_u64 v[116:117], v[118:119], 2, s[58:59]
	s_barrier
	global_load_dwordx4 v[130:133], v[116:117], off offset:2048
	v_add_u32_e32 v120, s18, v123
	v_ashrrev_i32_e32 v121, 31, v120
	v_lshlrev_b64 v[134:135], 10, v[120:121]
	v_lshlrev_b64 v[118:119], 1, v[118:119]
	v_lshl_add_u64 v[134:135], s[0:1], 0, v[134:135]
	v_lshl_add_u64 v[134:135], v[134:135], 0, v[118:119]
	s_add_i32 s9, s9, s8
	s_add_i32 s15, s15, s16
	s_waitcnt vmcnt(0)
	v_add_f32_e32 v121, v232, v130
	v_add_f32_e32 v129, v233, v131
	v_add_f32_e32 v130, v234, v132
	v_add_f32_e32 v131, v235, v133
	v_mul_f32_e32 v121, 0xbfb8aa3b, v121
	v_mul_f32_e32 v129, 0xbfb8aa3b, v129
	v_mul_f32_e32 v130, 0xbfb8aa3b, v130
	v_mul_f32_e32 v131, 0xbfb8aa3b, v131
	v_exp_f32_e32 v121, v121
	v_exp_f32_e32 v129, v129
	v_exp_f32_e32 v130, v130
	v_exp_f32_e32 v131, v131
	v_add_f32_e32 v121, 1.0, v121
	v_add_f32_e32 v129, 1.0, v129
	v_add_f32_e32 v132, 1.0, v130
	v_add_f32_e32 v131, 1.0, v131
	v_rcp_f32_e32 v130, v121
	v_rcp_f32_e32 v132, v132
	v_rcp_f32_e32 v133, v131
	v_rcp_f32_e32 v131, v129
	v_pk_mul_f32 v[132:133], v[132:133], s[6:7] op_sel_hi:[1,0]
	v_pk_mul_f32 v[130:131], v[130:131], s[6:7] op_sel_hi:[1,0]
	s_nop 0
	v_cvt_pk_bf16_f32 v130, v130, v131
	v_cvt_pk_bf16_f32 v131, v132, v133
	global_store_dwordx2 v[134:135], v[130:131], off
	global_load_dwordx4 v[130:133], v[116:117], off offset:2112
	s_waitcnt vmcnt(0)
	v_add_f32_e32 v121, v236, v130
	v_add_f32_e32 v129, v237, v131
	v_add_f32_e32 v130, v238, v132
	v_add_f32_e32 v131, v239, v133
	v_mul_f32_e32 v121, 0xbfb8aa3b, v121
	v_mul_f32_e32 v129, 0xbfb8aa3b, v129
	v_mul_f32_e32 v130, 0xbfb8aa3b, v130
	v_mul_f32_e32 v131, 0xbfb8aa3b, v131
	v_exp_f32_e32 v121, v121
	v_exp_f32_e32 v129, v129
	v_exp_f32_e32 v130, v130
	v_exp_f32_e32 v131, v131
	v_add_f32_e32 v121, 1.0, v121
	v_add_f32_e32 v129, 1.0, v129
	v_add_f32_e32 v132, 1.0, v130
	v_add_f32_e32 v131, 1.0, v131
	v_rcp_f32_e32 v130, v121
	v_rcp_f32_e32 v132, v132
	v_rcp_f32_e32 v133, v131
	v_rcp_f32_e32 v131, v129
	v_pk_mul_f32 v[132:133], v[132:133], s[6:7] op_sel_hi:[1,0]
	v_pk_mul_f32 v[130:131], v[130:131], s[6:7] op_sel_hi:[1,0]
	s_nop 0
	v_cvt_pk_bf16_f32 v130, v130, v131
	v_cvt_pk_bf16_f32 v131, v132, v133
	global_store_dwordx2 v[134:135], v[130:131], off offset:32
	global_load_dwordx4 v[130:133], v[116:117], off offset:2176
	s_waitcnt vmcnt(0)
; template <class Epi>
; DI void gemm_tile(char* smem, const bf16_t* __restrict__ A0, int lda0, int ksplit, const bf16_t* __restrict__ A1, int lda1,
;                   const bf16_t* __restrict__ Bt, int K, int row0, int col0, const Epi& epi, int tid) {
;     ...
; #pragma unroll
;   for (int m = 0; m < 8; ++m)
; #pragma unroll
;     for (int n = 0; n < 4; ++n) epi(row0 + wr * 128 + m * 16 + fr, col0 + wc * 64 + n * 16 + fq * 4, acc[m][n]);
	v_add_f32_e32 v121, v240, v130
	v_add_f32_e32 v129, v241, v131
	v_add_f32_e32 v130, v242, v132
	v_add_f32_e32 v131, v243, v133
	v_mul_f32_e32 v121, 0xbfb8aa3b, v121
	v_mul_f32_e32 v129, 0xbfb8aa3b, v129
	v_mul_f32_e32 v130, 0xbfb8aa3b, v130
	v_mul_f32_e32 v131, 0xbfb8aa3b, v131
	v_exp_f32_e32 v121, v121
	v_exp_f32_e32 v129, v129
	v_exp_f32_e32 v130, v130
	v_exp_f32_e32 v131, v131
	v_add_f32_e32 v121, 1.0, v121
	v_add_f32_e32 v129, 1.0, v129
	v_add_f32_e32 v132, 1.0, v130
	v_add_f32_e32 v131, 1.0, v131
	v_rcp_f32_e32 v130, v121
	v_rcp_f32_e32 v132, v132
	v_rcp_f32_e32 v133, v131
	v_rcp_f32_e32 v131, v129
	v_pk_mul_f32 v[132:133], v[132:133], s[6:7] op_sel_hi:[1,0]
	v_pk_mul_f32 v[130:131], v[130:131], s[6:7] op_sel_hi:[1,0]
	s_nop 0
	v_cvt_pk_bf16_f32 v130, v130, v131
	v_cvt_pk_bf16_f32 v131, v132, v133
	global_store_dwordx2 v[134:135], v[130:131], off offset:64
	global_load_dwordx4 v[130:133], v[116:117], off offset:2240
	s_waitcnt vmcnt(0)
	v_add_f32_e32 v121, v244, v130
	v_add_f32_e32 v129, v245, v131
	v_add_f32_e32 v130, v246, v132
	v_add_f32_e32 v131, v247, v133
	v_mul_f32_e32 v121, 0xbfb8aa3b, v121
	v_mul_f32_e32 v129, 0xbfb8aa3b, v129
	v_mul_f32_e32 v130, 0xbfb8aa3b, v130
	v_mul_f32_e32 v131, 0xbfb8aa3b, v131
	v_exp_f32_e32 v121, v121
	v_exp_f32_e32 v129, v129
	v_exp_f32_e32 v130, v130
	v_exp_f32_e32 v131, v131
	v_add_f32_e32 v121, 1.0, v121
	v_add_f32_e32 v129, 1.0, v129
	v_add_f32_e32 v132, 1.0, v130
	v_add_f32_e32 v131, 1.0, v131
	v_rcp_f32_e32 v130, v121
	v_rcp_f32_e32 v132, v132
	v_rcp_f32_e32 v133, v131
	v_rcp_f32_e32 v131, v129
	v_pk_mul_f32 v[132:133], v[132:133], s[6:7] op_sel_hi:[1,0]
	v_pk_mul_f32 v[130:131], v[130:131], s[6:7] op_sel_hi:[1,0]
	s_nop 0
	v_cvt_pk_bf16_f32 v130, v130, v131
	v_cvt_pk_bf16_f32 v131, v132, v133
	global_store_dwordx2 v[134:135], v[130:131], off offset:96
	global_load_dwordx4 v[130:133], v[116:117], off offset:2048
	v_or_b32_e32 v134, 16, v120
	v_ashrrev_i32_e32 v135, 31, v134
	v_lshlrev_b64 v[134:135], 10, v[134:135]
	s_waitcnt vmcnt(0)
	v_add_f32_e32 v108, v108, v130
	v_add_f32_e32 v109, v109, v131
	v_add_f32_e32 v110, v110, v132
	v_add_f32_e32 v111, v111, v133
	v_mul_f32_e32 v108, 0xbfb8aa3b, v108
	v_mul_f32_e32 v109, 0xbfb8aa3b, v109
	v_mul_f32_e32 v110, 0xbfb8aa3b, v110
	v_mul_f32_e32 v111, 0xbfb8aa3b, v111
	v_exp_f32_e32 v108, v108
	v_exp_f32_e32 v109, v109
	v_exp_f32_e32 v110, v110
	v_exp_f32_e32 v111, v111
	v_add_f32_e32 v108, 1.0, v108
	v_add_f32_e32 v109, 1.0, v109
	v_add_f32_e32 v110, 1.0, v110
	v_add_f32_e32 v111, 1.0, v111
	v_rcp_f32_e32 v108, v108
	v_rcp_f32_e32 v110, v110
	v_rcp_f32_e32 v111, v111
	v_rcp_f32_e32 v109, v109
	v_lshl_add_u64 v[130:131], s[0:1], 0, v[134:135]
	v_lshl_add_u64 v[130:131], v[130:131], 0, v[118:119]
	v_pk_mul_f32 v[110:111], v[110:111], s[6:7] op_sel_hi:[1,0]
	v_pk_mul_f32 v[108:109], v[108:109], s[6:7] op_sel_hi:[1,0]
	s_nop 0
	v_cvt_pk_bf16_f32 v108, v108, v109
	v_cvt_pk_bf16_f32 v109, v110, v111
	global_store_dwordx2 v[130:131], v[108:109], off
	global_load_dwordx4 v[108:111], v[116:117], off offset:2112
	s_waitcnt vmcnt(0)
	v_add_f32_e32 v104, v104, v108
	v_add_f32_e32 v105, v105, v109
	v_add_f32_e32 v106, v106, v110
	v_add_f32_e32 v107, v107, v111
	v_mul_f32_e32 v104, 0xbfb8aa3b, v104
	v_mul_f32_e32 v105, 0xbfb8aa3b, v105
	v_mul_f32_e32 v106, 0xbfb8aa3b, v106
	v_mul_f32_e32 v107, 0xbfb8aa3b, v107
	v_exp_f32_e32 v104, v104
	v_exp_f32_e32 v105, v105
	v_exp_f32_e32 v106, v106
	v_exp_f32_e32 v107, v107
	v_add_f32_e32 v104, 1.0, v104
	v_add_f32_e32 v105, 1.0, v105
	v_add_f32_e32 v106, 1.0, v106
	v_add_f32_e32 v107, 1.0, v107
	v_rcp_f32_e32 v104, v104
	v_rcp_f32_e32 v106, v106
	v_rcp_f32_e32 v107, v107
	v_rcp_f32_e32 v105, v105
	v_pk_mul_f32 v[106:107], v[106:107], s[6:7] op_sel_hi:[1,0]
	v_pk_mul_f32 v[104:105], v[104:105], s[6:7] op_sel_hi:[1,0]
	s_nop 0
	v_cvt_pk_bf16_f32 v104, v104, v105
	v_cvt_pk_bf16_f32 v105, v106, v107
	global_store_dwordx2 v[130:131], v[104:105], off offset:32
	global_load_dwordx4 v[104:107], v[116:117], off offset:2176
	s_waitcnt vmcnt(0)
	v_add_f32_e32 v100, v100, v104
	v_add_f32_e32 v101, v101, v105
	v_add_f32_e32 v102, v102, v106
	v_add_f32_e32 v103, v103, v107
	v_mul_f32_e32 v100, 0xbfb8aa3b, v100
	v_mul_f32_e32 v101, 0xbfb8aa3b, v101
	v_mul_f32_e32 v102, 0xbfb8aa3b, v102
	v_mul_f32_e32 v103, 0xbfb8aa3b, v103
	v_exp_f32_e32 v100, v100
	v_exp_f32_e32 v101, v101
	v_exp_f32_e32 v102, v102
	v_exp_f32_e32 v103, v103
	v_add_f32_e32 v100, 1.0, v100
	v_add_f32_e32 v101, 1.0, v101
	v_add_f32_e32 v102, 1.0, v102
	v_add_f32_e32 v103, 1.0, v103
	v_rcp_f32_e32 v100, v100
	v_rcp_f32_e32 v102, v102
	v_rcp_f32_e32 v103, v103
	v_rcp_f32_e32 v101, v101
	v_pk_mul_f32 v[102:103], v[102:103], s[6:7] op_sel_hi:[1,0]
	v_pk_mul_f32 v[100:101], v[100:101], s[6:7] op_sel_hi:[1,0]
	s_nop 0
	v_cvt_pk_bf16_f32 v100, v100, v101
	v_cvt_pk_bf16_f32 v101, v102, v103
	global_store_dwordx2 v[130:131], v[100:101], off offset:64
	global_load_dwordx4 v[100:103], v[116:117], off offset:2240
	s_waitcnt vmcnt(0)
	v_add_f32_e32 v96, v96, v100
	v_add_f32_e32 v97, v97, v101
	v_add_f32_e32 v98, v98, v102
	v_add_f32_e32 v99, v99, v103
	v_mul_f32_e32 v96, 0xbfb8aa3b, v96
	v_mul_f32_e32 v97, 0xbfb8aa3b, v97
	v_mul_f32_e32 v98, 0xbfb8aa3b, v98
	v_mul_f32_e32 v99, 0xbfb8aa3b, v99
	v_exp_f32_e32 v96, v96
	v_exp_f32_e32 v97, v97
	v_exp_f32_e32 v98, v98
	v_exp_f32_e32 v99, v99
	v_add_f32_e32 v96, 1.0, v96
	v_add_f32_e32 v97, 1.0, v97
	v_add_f32_e32 v98, 1.0, v98
	v_add_f32_e32 v99, 1.0, v99
	v_rcp_f32_e32 v96, v96
	v_rcp_f32_e32 v98, v98
	v_rcp_f32_e32 v99, v99
	v_rcp_f32_e32 v97, v97
	v_or_b32_e32 v100, 32, v120
	v_ashrrev_i32_e32 v101, 31, v100
	v_pk_mul_f32 v[98:99], v[98:99], s[6:7] op_sel_hi:[1,0]
	v_pk_mul_f32 v[96:97], v[96:97], s[6:7] op_sel_hi:[1,0]
	v_lshlrev_b64 v[100:101], 10, v[100:101]
	v_cvt_pk_bf16_f32 v96, v96, v97
	v_cvt_pk_bf16_f32 v97, v98, v99
	global_store_dwordx2 v[130:131], v[96:97], off offset:96
	global_load_dwordx4 v[96:99], v[116:117], off offset:2048
	s_waitcnt vmcnt(0)
; template <class Epi>
; DI void gemm_tile(char* smem, const bf16_t* __restrict__ A0, int lda0, int ksplit, const bf16_t* __restrict__ A1, int lda1,
;                   const bf16_t* __restrict__ Bt, int K, int row0, int col0, const Epi& epi, int tid) {
;     ...
; #pragma unroll
;   for (int m = 0; m < 8; ++m)
; #pragma unroll
;     for (int n = 0; n < 4; ++n) epi(row0 + wr * 128 + m * 16 + fr, col0 + wc * 64 + n * 16 + fq * 4, acc[m][n]);
	v_add_f32_e32 v92, v92, v96
	v_add_f32_e32 v93, v93, v97
	v_add_f32_e32 v94, v94, v98
	v_add_f32_e32 v95, v95, v99
	v_mul_f32_e32 v92, 0xbfb8aa3b, v92
	v_mul_f32_e32 v93, 0xbfb8aa3b, v93
	v_mul_f32_e32 v94, 0xbfb8aa3b, v94
	v_mul_f32_e32 v95, 0xbfb8aa3b, v95
	v_exp_f32_e32 v92, v92
	v_exp_f32_e32 v93, v93
	v_exp_f32_e32 v94, v94
	v_exp_f32_e32 v95, v95
	v_add_f32_e32 v92, 1.0, v92
	v_add_f32_e32 v93, 1.0, v93
	v_add_f32_e32 v94, 1.0, v94
	v_add_f32_e32 v95, 1.0, v95
	v_rcp_f32_e32 v92, v92
	v_rcp_f32_e32 v94, v94
	v_rcp_f32_e32 v95, v95
	v_rcp_f32_e32 v93, v93
	v_lshl_add_u64 v[96:97], s[0:1], 0, v[100:101]
	v_lshl_add_u64 v[96:97], v[96:97], 0, v[118:119]
	v_pk_mul_f32 v[94:95], v[94:95], s[6:7] op_sel_hi:[1,0]
	v_pk_mul_f32 v[92:93], v[92:93], s[6:7] op_sel_hi:[1,0]
	s_nop 0
	v_cvt_pk_bf16_f32 v92, v92, v93
	v_cvt_pk_bf16_f32 v93, v94, v95
	global_store_dwordx2 v[96:97], v[92:93], off
	global_load_dwordx4 v[92:95], v[116:117], off offset:2112
	s_waitcnt vmcnt(0)
	v_add_f32_e32 v88, v88, v92
	v_add_f32_e32 v89, v89, v93
	v_add_f32_e32 v90, v90, v94
	v_add_f32_e32 v91, v91, v95
	v_mul_f32_e32 v88, 0xbfb8aa3b, v88
	v_mul_f32_e32 v89, 0xbfb8aa3b, v89
	v_mul_f32_e32 v90, 0xbfb8aa3b, v90
	v_mul_f32_e32 v91, 0xbfb8aa3b, v91
	v_exp_f32_e32 v88, v88
	v_exp_f32_e32 v89, v89
	v_exp_f32_e32 v90, v90
	v_exp_f32_e32 v91, v91
	v_add_f32_e32 v88, 1.0, v88
	v_add_f32_e32 v89, 1.0, v89
	v_add_f32_e32 v90, 1.0, v90
	v_add_f32_e32 v91, 1.0, v91
	v_rcp_f32_e32 v88, v88
	v_rcp_f32_e32 v90, v90
	v_rcp_f32_e32 v91, v91
	v_rcp_f32_e32 v89, v89
	v_pk_mul_f32 v[90:91], v[90:91], s[6:7] op_sel_hi:[1,0]
	v_pk_mul_f32 v[88:89], v[88:89], s[6:7] op_sel_hi:[1,0]
	s_nop 0
	v_cvt_pk_bf16_f32 v88, v88, v89
	v_cvt_pk_bf16_f32 v89, v90, v91
	global_store_dwordx2 v[96:97], v[88:89], off offset:32
	global_load_dwordx4 v[88:91], v[116:117], off offset:2176
	s_waitcnt vmcnt(0)
	v_add_f32_e32 v84, v84, v88
	v_add_f32_e32 v85, v85, v89
	v_add_f32_e32 v86, v86, v90
	v_add_f32_e32 v87, v87, v91
	v_mul_f32_e32 v84, 0xbfb8aa3b, v84
	v_mul_f32_e32 v85, 0xbfb8aa3b, v85
	v_mul_f32_e32 v86, 0xbfb8aa3b, v86
	v_mul_f32_e32 v87, 0xbfb8aa3b, v87
	v_exp_f32_e32 v84, v84
	v_exp_f32_e32 v85, v85
	v_exp_f32_e32 v86, v86
	v_exp_f32_e32 v87, v87
	v_add_f32_e32 v84, 1.0, v84
	v_add_f32_e32 v85, 1.0, v85
	v_add_f32_e32 v86, 1.0, v86
	v_add_f32_e32 v87, 1.0, v87
	v_rcp_f32_e32 v84, v84
	v_rcp_f32_e32 v86, v86
	v_rcp_f32_e32 v87, v87
	v_rcp_f32_e32 v85, v85
	v_pk_mul_f32 v[86:87], v[86:87], s[6:7] op_sel_hi:[1,0]
	v_pk_mul_f32 v[84:85], v[84:85], s[6:7] op_sel_hi:[1,0]
	s_nop 0
	v_cvt_pk_bf16_f32 v84, v84, v85
	v_cvt_pk_bf16_f32 v85, v86, v87
	global_store_dwordx2 v[96:97], v[84:85], off offset:64
	global_load_dwordx4 v[84:87], v[116:117], off offset:2240
	s_waitcnt vmcnt(0)
	v_add_f32_e32 v80, v80, v84
	v_add_f32_e32 v81, v81, v85
	v_add_f32_e32 v82, v82, v86
	v_add_f32_e32 v83, v83, v87
	v_mul_f32_e32 v80, 0xbfb8aa3b, v80
	v_mul_f32_e32 v81, 0xbfb8aa3b, v81
	v_mul_f32_e32 v82, 0xbfb8aa3b, v82
	v_mul_f32_e32 v83, 0xbfb8aa3b, v83
	v_exp_f32_e32 v80, v80
	v_exp_f32_e32 v81, v81
	v_exp_f32_e32 v82, v82
	v_exp_f32_e32 v83, v83
	v_add_f32_e32 v80, 1.0, v80
	v_add_f32_e32 v81, 1.0, v81
	v_add_f32_e32 v82, 1.0, v82
	v_add_f32_e32 v83, 1.0, v83
	v_rcp_f32_e32 v80, v80
	v_rcp_f32_e32 v82, v82
	v_rcp_f32_e32 v83, v83
	v_rcp_f32_e32 v81, v81
	v_or_b32_e32 v84, 48, v120
	v_ashrrev_i32_e32 v85, 31, v84
	v_pk_mul_f32 v[82:83], v[82:83], s[6:7] op_sel_hi:[1,0]
	v_pk_mul_f32 v[80:81], v[80:81], s[6:7] op_sel_hi:[1,0]
	v_lshlrev_b64 v[84:85], 10, v[84:85]
	v_cvt_pk_bf16_f32 v80, v80, v81
	v_cvt_pk_bf16_f32 v81, v82, v83
	global_store_dwordx2 v[96:97], v[80:81], off offset:96
	global_load_dwordx4 v[80:83], v[116:117], off offset:2048
	s_waitcnt vmcnt(0)
	v_add_f32_e32 v76, v76, v80
	v_add_f32_e32 v77, v77, v81
	v_add_f32_e32 v78, v78, v82
	v_add_f32_e32 v79, v79, v83
	v_mul_f32_e32 v76, 0xbfb8aa3b, v76
	v_mul_f32_e32 v77, 0xbfb8aa3b, v77
	v_mul_f32_e32 v78, 0xbfb8aa3b, v78
	v_mul_f32_e32 v79, 0xbfb8aa3b, v79
	v_exp_f32_e32 v76, v76
	v_exp_f32_e32 v77, v77
	v_exp_f32_e32 v78, v78
	v_exp_f32_e32 v79, v79
	v_add_f32_e32 v76, 1.0, v76
	v_add_f32_e32 v77, 1.0, v77
	v_add_f32_e32 v78, 1.0, v78
	v_add_f32_e32 v79, 1.0, v79
	v_rcp_f32_e32 v76, v76
	v_rcp_f32_e32 v78, v78
	v_rcp_f32_e32 v79, v79
	v_rcp_f32_e32 v77, v77
	v_lshl_add_u64 v[80:81], s[0:1], 0, v[84:85]
	v_lshl_add_u64 v[80:81], v[80:81], 0, v[118:119]
	v_pk_mul_f32 v[78:79], v[78:79], s[6:7] op_sel_hi:[1,0]
	v_pk_mul_f32 v[76:77], v[76:77], s[6:7] op_sel_hi:[1,0]
	s_nop 0
	v_cvt_pk_bf16_f32 v76, v76, v77
	v_cvt_pk_bf16_f32 v77, v78, v79
	global_store_dwordx2 v[80:81], v[76:77], off
	global_load_dwordx4 v[76:79], v[116:117], off offset:2112
	s_waitcnt vmcnt(0)
	v_add_f32_e32 v72, v72, v76
	v_add_f32_e32 v73, v73, v77
	v_add_f32_e32 v74, v74, v78
	v_add_f32_e32 v75, v75, v79
	v_mul_f32_e32 v72, 0xbfb8aa3b, v72
	v_mul_f32_e32 v73, 0xbfb8aa3b, v73
	v_mul_f32_e32 v74, 0xbfb8aa3b, v74
	v_mul_f32_e32 v75, 0xbfb8aa3b, v75
	v_exp_f32_e32 v72, v72
	v_exp_f32_e32 v73, v73
	v_exp_f32_e32 v74, v74
	v_exp_f32_e32 v75, v75
	v_add_f32_e32 v72, 1.0, v72
	v_add_f32_e32 v73, 1.0, v73
	v_add_f32_e32 v74, 1.0, v74
	v_add_f32_e32 v75, 1.0, v75
	v_rcp_f32_e32 v72, v72
	v_rcp_f32_e32 v74, v74
	v_rcp_f32_e32 v75, v75
	v_rcp_f32_e32 v73, v73
	v_pk_mul_f32 v[74:75], v[74:75], s[6:7] op_sel_hi:[1,0]
	v_pk_mul_f32 v[72:73], v[72:73], s[6:7] op_sel_hi:[1,0]
	s_nop 0
	v_cvt_pk_bf16_f32 v72, v72, v73
	v_cvt_pk_bf16_f32 v73, v74, v75
	global_store_dwordx2 v[80:81], v[72:73], off offset:32
	global_load_dwordx4 v[72:75], v[116:117], off offset:2176
	s_waitcnt vmcnt(0)
; template <class Epi>
; DI void gemm_tile(char* smem, const bf16_t* __restrict__ A0, int lda0, int ksplit, const bf16_t* __restrict__ A1, int lda1,
;                   const bf16_t* __restrict__ Bt, int K, int row0, int col0, const Epi& epi, int tid) {
;     ...
; #pragma unroll
;   for (int m = 0; m < 8; ++m)
; #pragma unroll
;     for (int n = 0; n < 4; ++n) epi(row0 + wr * 128 + m * 16 + fr, col0 + wc * 64 + n * 16 + fq * 4, acc[m][n]);
	v_add_f32_e32 v68, v68, v72
	v_add_f32_e32 v69, v69, v73
	v_add_f32_e32 v70, v70, v74
	v_add_f32_e32 v71, v71, v75
	v_mul_f32_e32 v68, 0xbfb8aa3b, v68
	v_mul_f32_e32 v69, 0xbfb8aa3b, v69
	v_mul_f32_e32 v70, 0xbfb8aa3b, v70
	v_mul_f32_e32 v71, 0xbfb8aa3b, v71
	v_exp_f32_e32 v68, v68
	v_exp_f32_e32 v69, v69
	v_exp_f32_e32 v70, v70
	v_exp_f32_e32 v71, v71
	v_add_f32_e32 v68, 1.0, v68
	v_add_f32_e32 v69, 1.0, v69
	v_add_f32_e32 v70, 1.0, v70
	v_add_f32_e32 v71, 1.0, v71
	v_rcp_f32_e32 v68, v68
	v_rcp_f32_e32 v70, v70
	v_rcp_f32_e32 v71, v71
	v_rcp_f32_e32 v69, v69
	v_pk_mul_f32 v[70:71], v[70:71], s[6:7] op_sel_hi:[1,0]
	v_pk_mul_f32 v[68:69], v[68:69], s[6:7] op_sel_hi:[1,0]
	s_nop 0
	v_cvt_pk_bf16_f32 v68, v68, v69
	v_cvt_pk_bf16_f32 v69, v70, v71
	global_store_dwordx2 v[80:81], v[68:69], off offset:64
	global_load_dwordx4 v[68:71], v[116:117], off offset:2240
	s_waitcnt vmcnt(0)
	v_add_f32_e32 v64, v64, v68
	v_add_f32_e32 v65, v65, v69
	v_add_f32_e32 v66, v66, v70
	v_add_f32_e32 v67, v67, v71
	v_mul_f32_e32 v64, 0xbfb8aa3b, v64
	v_mul_f32_e32 v65, 0xbfb8aa3b, v65
	v_mul_f32_e32 v66, 0xbfb8aa3b, v66
	v_mul_f32_e32 v67, 0xbfb8aa3b, v67
	v_exp_f32_e32 v64, v64
	v_exp_f32_e32 v65, v65
	v_exp_f32_e32 v66, v66
	v_exp_f32_e32 v67, v67
	v_add_f32_e32 v64, 1.0, v64
	v_add_f32_e32 v65, 1.0, v65
	v_add_f32_e32 v66, 1.0, v66
	v_add_f32_e32 v67, 1.0, v67
	v_rcp_f32_e32 v64, v64
	v_rcp_f32_e32 v66, v66
	v_rcp_f32_e32 v67, v67
	v_rcp_f32_e32 v65, v65
	v_or_b32_e32 v68, 64, v120
	v_ashrrev_i32_e32 v69, 31, v68
	v_pk_mul_f32 v[66:67], v[66:67], s[6:7] op_sel_hi:[1,0]
	v_pk_mul_f32 v[64:65], v[64:65], s[6:7] op_sel_hi:[1,0]
	v_lshlrev_b64 v[68:69], 10, v[68:69]
	v_cvt_pk_bf16_f32 v64, v64, v65
	v_cvt_pk_bf16_f32 v65, v66, v67
	global_store_dwordx2 v[80:81], v[64:65], off offset:96
	global_load_dwordx4 v[64:67], v[116:117], off offset:2048
	s_waitcnt vmcnt(0)
	v_add_f32_e32 v60, v60, v64
	v_add_f32_e32 v61, v61, v65
	v_add_f32_e32 v62, v62, v66
	v_add_f32_e32 v63, v63, v67
	v_mul_f32_e32 v60, 0xbfb8aa3b, v60
	v_mul_f32_e32 v61, 0xbfb8aa3b, v61
	v_mul_f32_e32 v62, 0xbfb8aa3b, v62
	v_mul_f32_e32 v63, 0xbfb8aa3b, v63
	v_exp_f32_e32 v60, v60
	v_exp_f32_e32 v61, v61
	v_exp_f32_e32 v62, v62
	v_exp_f32_e32 v63, v63
	v_add_f32_e32 v60, 1.0, v60
	v_add_f32_e32 v61, 1.0, v61
	v_add_f32_e32 v62, 1.0, v62
	v_add_f32_e32 v63, 1.0, v63
	v_rcp_f32_e32 v60, v60
	v_rcp_f32_e32 v62, v62
	v_rcp_f32_e32 v63, v63
	v_rcp_f32_e32 v61, v61
	v_lshl_add_u64 v[64:65], s[0:1], 0, v[68:69]
	v_lshl_add_u64 v[64:65], v[64:65], 0, v[118:119]
	v_pk_mul_f32 v[62:63], v[62:63], s[6:7] op_sel_hi:[1,0]
	v_pk_mul_f32 v[60:61], v[60:61], s[6:7] op_sel_hi:[1,0]
	s_nop 0
	v_cvt_pk_bf16_f32 v60, v60, v61
	v_cvt_pk_bf16_f32 v61, v62, v63
	global_store_dwordx2 v[64:65], v[60:61], off
	global_load_dwordx4 v[60:63], v[116:117], off offset:2112
	s_waitcnt vmcnt(0)
	v_add_f32_e32 v56, v56, v60
	v_add_f32_e32 v57, v57, v61
	v_add_f32_e32 v58, v58, v62
	v_add_f32_e32 v59, v59, v63
	v_mul_f32_e32 v56, 0xbfb8aa3b, v56
	v_mul_f32_e32 v57, 0xbfb8aa3b, v57
	v_mul_f32_e32 v58, 0xbfb8aa3b, v58
	v_mul_f32_e32 v59, 0xbfb8aa3b, v59
	v_exp_f32_e32 v56, v56
	v_exp_f32_e32 v57, v57
	v_exp_f32_e32 v58, v58
	v_exp_f32_e32 v59, v59
	v_add_f32_e32 v56, 1.0, v56
	v_add_f32_e32 v57, 1.0, v57
	v_add_f32_e32 v58, 1.0, v58
	v_add_f32_e32 v59, 1.0, v59
	v_rcp_f32_e32 v56, v56
	v_rcp_f32_e32 v58, v58
	v_rcp_f32_e32 v59, v59
	v_rcp_f32_e32 v57, v57
	v_pk_mul_f32 v[58:59], v[58:59], s[6:7] op_sel_hi:[1,0]
	v_pk_mul_f32 v[56:57], v[56:57], s[6:7] op_sel_hi:[1,0]
	s_nop 0
	v_cvt_pk_bf16_f32 v56, v56, v57
	v_cvt_pk_bf16_f32 v57, v58, v59
	global_store_dwordx2 v[64:65], v[56:57], off offset:32
	global_load_dwordx4 v[56:59], v[116:117], off offset:2176
	s_waitcnt vmcnt(0)
	v_add_f32_e32 v52, v52, v56
	v_add_f32_e32 v53, v53, v57
	v_add_f32_e32 v54, v54, v58
	v_add_f32_e32 v55, v55, v59
	v_mul_f32_e32 v52, 0xbfb8aa3b, v52
	v_mul_f32_e32 v53, 0xbfb8aa3b, v53
	v_mul_f32_e32 v54, 0xbfb8aa3b, v54
	v_mul_f32_e32 v55, 0xbfb8aa3b, v55
	v_exp_f32_e32 v52, v52
	v_exp_f32_e32 v53, v53
	v_exp_f32_e32 v54, v54
	v_exp_f32_e32 v55, v55
	v_add_f32_e32 v52, 1.0, v52
	v_add_f32_e32 v53, 1.0, v53
	v_add_f32_e32 v54, 1.0, v54
	v_add_f32_e32 v55, 1.0, v55
	v_rcp_f32_e32 v52, v52
	v_rcp_f32_e32 v54, v54
	v_rcp_f32_e32 v55, v55
	v_rcp_f32_e32 v53, v53
	v_pk_mul_f32 v[54:55], v[54:55], s[6:7] op_sel_hi:[1,0]
	v_pk_mul_f32 v[52:53], v[52:53], s[6:7] op_sel_hi:[1,0]
	s_nop 0
	v_cvt_pk_bf16_f32 v52, v52, v53
	v_cvt_pk_bf16_f32 v53, v54, v55
	global_store_dwordx2 v[64:65], v[52:53], off offset:64
	global_load_dwordx4 v[52:55], v[116:117], off offset:2240
	s_waitcnt vmcnt(0)
	v_add_f32_e32 v48, v48, v52
	v_add_f32_e32 v49, v49, v53
	v_add_f32_e32 v50, v50, v54
	v_add_f32_e32 v51, v51, v55
	v_mul_f32_e32 v48, 0xbfb8aa3b, v48
	v_mul_f32_e32 v49, 0xbfb8aa3b, v49
	v_mul_f32_e32 v50, 0xbfb8aa3b, v50
	v_mul_f32_e32 v51, 0xbfb8aa3b, v51
	v_exp_f32_e32 v48, v48
	v_exp_f32_e32 v49, v49
	v_exp_f32_e32 v50, v50
	v_exp_f32_e32 v51, v51
	v_add_f32_e32 v48, 1.0, v48
	v_add_f32_e32 v49, 1.0, v49
	v_add_f32_e32 v50, 1.0, v50
	v_add_f32_e32 v51, 1.0, v51
	v_rcp_f32_e32 v48, v48
	v_rcp_f32_e32 v50, v50
	v_rcp_f32_e32 v51, v51
	v_rcp_f32_e32 v49, v49
	v_or_b32_e32 v52, 0x50, v120
	v_ashrrev_i32_e32 v53, 31, v52
	v_pk_mul_f32 v[50:51], v[50:51], s[6:7] op_sel_hi:[1,0]
	v_pk_mul_f32 v[48:49], v[48:49], s[6:7] op_sel_hi:[1,0]
	v_lshlrev_b64 v[52:53], 10, v[52:53]
	v_cvt_pk_bf16_f32 v48, v48, v49
	v_cvt_pk_bf16_f32 v49, v50, v51
	global_store_dwordx2 v[64:65], v[48:49], off offset:96
	global_load_dwordx4 v[48:51], v[116:117], off offset:2048
	s_waitcnt vmcnt(0)
; template <class Epi>
; DI void gemm_tile(char* smem, const bf16_t* __restrict__ A0, int lda0, int ksplit, const bf16_t* __restrict__ A1, int lda1,
;                   const bf16_t* __restrict__ Bt, int K, int row0, int col0, const Epi& epi, int tid) {
;     ...
; #pragma unroll
;   for (int m = 0; m < 8; ++m)
; #pragma unroll
;     for (int n = 0; n < 4; ++n) epi(row0 + wr * 128 + m * 16 + fr, col0 + wc * 64 + n * 16 + fq * 4, acc[m][n]);
	v_add_f32_e32 v44, v44, v48
	v_add_f32_e32 v45, v45, v49
	v_add_f32_e32 v46, v46, v50
	v_add_f32_e32 v47, v47, v51
	v_mul_f32_e32 v44, 0xbfb8aa3b, v44
	v_mul_f32_e32 v45, 0xbfb8aa3b, v45
	v_mul_f32_e32 v46, 0xbfb8aa3b, v46
	v_mul_f32_e32 v47, 0xbfb8aa3b, v47
	v_exp_f32_e32 v44, v44
	v_exp_f32_e32 v45, v45
	v_exp_f32_e32 v46, v46
	v_exp_f32_e32 v47, v47
	v_add_f32_e32 v44, 1.0, v44
	v_add_f32_e32 v45, 1.0, v45
	v_add_f32_e32 v46, 1.0, v46
	v_add_f32_e32 v47, 1.0, v47
	v_rcp_f32_e32 v44, v44
	v_rcp_f32_e32 v46, v46
	v_rcp_f32_e32 v47, v47
	v_rcp_f32_e32 v45, v45
	v_lshl_add_u64 v[48:49], s[0:1], 0, v[52:53]
	v_lshl_add_u64 v[48:49], v[48:49], 0, v[118:119]
	v_pk_mul_f32 v[46:47], v[46:47], s[6:7] op_sel_hi:[1,0]
	v_pk_mul_f32 v[44:45], v[44:45], s[6:7] op_sel_hi:[1,0]
	s_nop 0
	v_cvt_pk_bf16_f32 v44, v44, v45
	v_cvt_pk_bf16_f32 v45, v46, v47
	global_store_dwordx2 v[48:49], v[44:45], off
	global_load_dwordx4 v[44:47], v[116:117], off offset:2112
	s_waitcnt vmcnt(0)
	v_add_f32_e32 v40, v40, v44
	v_add_f32_e32 v41, v41, v45
	v_add_f32_e32 v42, v42, v46
	v_add_f32_e32 v43, v43, v47
	v_mul_f32_e32 v40, 0xbfb8aa3b, v40
	v_mul_f32_e32 v41, 0xbfb8aa3b, v41
	v_mul_f32_e32 v42, 0xbfb8aa3b, v42
	v_mul_f32_e32 v43, 0xbfb8aa3b, v43
	v_exp_f32_e32 v40, v40
	v_exp_f32_e32 v41, v41
	v_exp_f32_e32 v42, v42
	v_exp_f32_e32 v43, v43
	v_add_f32_e32 v40, 1.0, v40
	v_add_f32_e32 v41, 1.0, v41
	v_add_f32_e32 v42, 1.0, v42
	v_add_f32_e32 v43, 1.0, v43
	v_rcp_f32_e32 v40, v40
	v_rcp_f32_e32 v42, v42
	v_rcp_f32_e32 v43, v43
	v_rcp_f32_e32 v41, v41
	v_pk_mul_f32 v[42:43], v[42:43], s[6:7] op_sel_hi:[1,0]
	v_pk_mul_f32 v[40:41], v[40:41], s[6:7] op_sel_hi:[1,0]
	s_nop 0
	v_cvt_pk_bf16_f32 v40, v40, v41
	v_cvt_pk_bf16_f32 v41, v42, v43
	global_store_dwordx2 v[48:49], v[40:41], off offset:32
	global_load_dwordx4 v[40:43], v[116:117], off offset:2176
	s_waitcnt vmcnt(0)
	v_add_f32_e32 v36, v36, v40
	v_add_f32_e32 v37, v37, v41
	v_add_f32_e32 v38, v38, v42
	v_add_f32_e32 v39, v39, v43
	v_mul_f32_e32 v36, 0xbfb8aa3b, v36
	v_mul_f32_e32 v37, 0xbfb8aa3b, v37
	v_mul_f32_e32 v38, 0xbfb8aa3b, v38
	v_mul_f32_e32 v39, 0xbfb8aa3b, v39
	v_exp_f32_e32 v36, v36
	v_exp_f32_e32 v37, v37
	v_exp_f32_e32 v38, v38
	v_exp_f32_e32 v39, v39
	v_add_f32_e32 v36, 1.0, v36
	v_add_f32_e32 v37, 1.0, v37
	v_add_f32_e32 v38, 1.0, v38
	v_add_f32_e32 v39, 1.0, v39
	v_rcp_f32_e32 v36, v36
	v_rcp_f32_e32 v38, v38
	v_rcp_f32_e32 v39, v39
	v_rcp_f32_e32 v37, v37
	v_pk_mul_f32 v[38:39], v[38:39], s[6:7] op_sel_hi:[1,0]
	v_pk_mul_f32 v[36:37], v[36:37], s[6:7] op_sel_hi:[1,0]
	s_nop 0
	v_cvt_pk_bf16_f32 v36, v36, v37
	v_cvt_pk_bf16_f32 v37, v38, v39
	global_store_dwordx2 v[48:49], v[36:37], off offset:64
	global_load_dwordx4 v[36:39], v[116:117], off offset:2240
	s_waitcnt vmcnt(0)
	v_add_f32_e32 v32, v32, v36
	v_add_f32_e32 v33, v33, v37
	v_add_f32_e32 v34, v34, v38
	v_add_f32_e32 v35, v35, v39
	v_mul_f32_e32 v32, 0xbfb8aa3b, v32
	v_mul_f32_e32 v33, 0xbfb8aa3b, v33
	v_mul_f32_e32 v34, 0xbfb8aa3b, v34
	v_mul_f32_e32 v35, 0xbfb8aa3b, v35
	v_exp_f32_e32 v32, v32
	v_exp_f32_e32 v33, v33
	v_exp_f32_e32 v34, v34
	v_exp_f32_e32 v35, v35
	v_add_f32_e32 v32, 1.0, v32
	v_add_f32_e32 v33, 1.0, v33
	v_add_f32_e32 v34, 1.0, v34
	v_add_f32_e32 v35, 1.0, v35
	v_rcp_f32_e32 v32, v32
	v_rcp_f32_e32 v34, v34
	v_rcp_f32_e32 v35, v35
	v_rcp_f32_e32 v33, v33
	v_or_b32_e32 v36, 0x60, v120
	v_ashrrev_i32_e32 v37, 31, v36
	v_pk_mul_f32 v[34:35], v[34:35], s[6:7] op_sel_hi:[1,0]
	v_pk_mul_f32 v[32:33], v[32:33], s[6:7] op_sel_hi:[1,0]
	v_lshlrev_b64 v[36:37], 10, v[36:37]
	v_cvt_pk_bf16_f32 v32, v32, v33
	v_cvt_pk_bf16_f32 v33, v34, v35
	global_store_dwordx2 v[48:49], v[32:33], off offset:96
	global_load_dwordx4 v[32:35], v[116:117], off offset:2048
	s_waitcnt vmcnt(0)
	v_add_f32_e32 v28, v28, v32
	v_add_f32_e32 v29, v29, v33
	v_add_f32_e32 v30, v30, v34
	v_add_f32_e32 v31, v31, v35
	v_mul_f32_e32 v28, 0xbfb8aa3b, v28
	v_mul_f32_e32 v29, 0xbfb8aa3b, v29
	v_mul_f32_e32 v30, 0xbfb8aa3b, v30
	v_mul_f32_e32 v31, 0xbfb8aa3b, v31
	v_exp_f32_e32 v28, v28
	v_exp_f32_e32 v29, v29
	v_exp_f32_e32 v30, v30
	v_exp_f32_e32 v31, v31
	v_add_f32_e32 v28, 1.0, v28
	v_add_f32_e32 v29, 1.0, v29
	v_add_f32_e32 v30, 1.0, v30
	v_add_f32_e32 v31, 1.0, v31
	v_rcp_f32_e32 v28, v28
	v_rcp_f32_e32 v30, v30
	v_rcp_f32_e32 v31, v31
	v_rcp_f32_e32 v29, v29
	v_lshl_add_u64 v[32:33], s[0:1], 0, v[36:37]
	v_lshl_add_u64 v[32:33], v[32:33], 0, v[118:119]
	v_pk_mul_f32 v[30:31], v[30:31], s[6:7] op_sel_hi:[1,0]
	v_pk_mul_f32 v[28:29], v[28:29], s[6:7] op_sel_hi:[1,0]
	s_nop 0
	v_cvt_pk_bf16_f32 v28, v28, v29
	v_cvt_pk_bf16_f32 v29, v30, v31
	global_store_dwordx2 v[32:33], v[28:29], off
	global_load_dwordx4 v[28:31], v[116:117], off offset:2112
	s_waitcnt vmcnt(0)
	v_add_f32_e32 v24, v24, v28
	v_add_f32_e32 v25, v25, v29
	v_add_f32_e32 v26, v26, v30
	v_add_f32_e32 v27, v27, v31
	v_mul_f32_e32 v24, 0xbfb8aa3b, v24
	v_mul_f32_e32 v25, 0xbfb8aa3b, v25
	v_mul_f32_e32 v26, 0xbfb8aa3b, v26
	v_mul_f32_e32 v27, 0xbfb8aa3b, v27
	v_exp_f32_e32 v24, v24
	v_exp_f32_e32 v25, v25
	v_exp_f32_e32 v26, v26
	v_exp_f32_e32 v27, v27
	v_add_f32_e32 v24, 1.0, v24
	v_add_f32_e32 v25, 1.0, v25
	v_add_f32_e32 v26, 1.0, v26
	v_add_f32_e32 v27, 1.0, v27
	v_rcp_f32_e32 v24, v24
	v_rcp_f32_e32 v26, v26
	v_rcp_f32_e32 v27, v27
	v_rcp_f32_e32 v25, v25
	v_pk_mul_f32 v[26:27], v[26:27], s[6:7] op_sel_hi:[1,0]
	v_pk_mul_f32 v[24:25], v[24:25], s[6:7] op_sel_hi:[1,0]
	s_nop 0
	v_cvt_pk_bf16_f32 v24, v24, v25
	v_cvt_pk_bf16_f32 v25, v26, v27
	global_store_dwordx2 v[32:33], v[24:25], off offset:32
	global_load_dwordx4 v[24:27], v[116:117], off offset:2176
	s_waitcnt vmcnt(0)
; template <class Epi>
; DI void gemm_tile(char* smem, const bf16_t* __restrict__ A0, int lda0, int ksplit, const bf16_t* __restrict__ A1, int lda1,
;                   const bf16_t* __restrict__ Bt, int K, int row0, int col0, const Epi& epi, int tid) {
;     ...
; #pragma unroll
;   for (int m = 0; m < 8; ++m)
; #pragma unroll
;     for (int n = 0; n < 4; ++n) epi(row0 + wr * 128 + m * 16 + fr, col0 + wc * 64 + n * 16 + fq * 4, acc[m][n]);
; template <class Epi>
; DI void gemm_phase(char* smem, const bf16_t* A0, int lda0, int ksplit, const bf16_t* A1, int lda1, const bf16_t* Bt, int K, int nN, const Epi& epi, int tid) {
;     ...
;     for (int q = l; q < tot; q += L) { const int rgl = q / per, rem = q % per, ct = rem >> 3, rt = (x * 2 + rgl) * 8 + (rem & 7);
	v_add_f32_e32 v20, v20, v24
	v_add_f32_e32 v21, v21, v25
	v_add_f32_e32 v22, v22, v26
	v_add_f32_e32 v23, v23, v27
	v_mul_f32_e32 v20, 0xbfb8aa3b, v20
	v_mul_f32_e32 v21, 0xbfb8aa3b, v21
	v_mul_f32_e32 v22, 0xbfb8aa3b, v22
	v_mul_f32_e32 v23, 0xbfb8aa3b, v23
	v_exp_f32_e32 v20, v20
	v_exp_f32_e32 v21, v21
	v_exp_f32_e32 v22, v22
	v_exp_f32_e32 v23, v23
	v_add_f32_e32 v20, 1.0, v20
	v_add_f32_e32 v21, 1.0, v21
	v_add_f32_e32 v22, 1.0, v22
	v_add_f32_e32 v23, 1.0, v23
	v_rcp_f32_e32 v20, v20
	v_rcp_f32_e32 v22, v22
	v_rcp_f32_e32 v23, v23
	v_rcp_f32_e32 v21, v21
	v_pk_mul_f32 v[22:23], v[22:23], s[6:7] op_sel_hi:[1,0]
	v_pk_mul_f32 v[20:21], v[20:21], s[6:7] op_sel_hi:[1,0]
	s_nop 0
	v_cvt_pk_bf16_f32 v20, v20, v21
	v_cvt_pk_bf16_f32 v21, v22, v23
	global_store_dwordx2 v[32:33], v[20:21], off offset:64
	global_load_dwordx4 v[20:23], v[116:117], off offset:2240
	s_waitcnt vmcnt(0)
	v_add_f32_e32 v16, v16, v20
	v_add_f32_e32 v17, v17, v21
	v_add_f32_e32 v18, v18, v22
	v_add_f32_e32 v19, v19, v23
	v_mul_f32_e32 v16, 0xbfb8aa3b, v16
	v_mul_f32_e32 v17, 0xbfb8aa3b, v17
	v_mul_f32_e32 v18, 0xbfb8aa3b, v18
	v_mul_f32_e32 v19, 0xbfb8aa3b, v19
	v_exp_f32_e32 v16, v16
	v_exp_f32_e32 v17, v17
	v_exp_f32_e32 v18, v18
	v_exp_f32_e32 v19, v19
	v_add_f32_e32 v16, 1.0, v16
	v_add_f32_e32 v17, 1.0, v17
	v_add_f32_e32 v18, 1.0, v18
	v_add_f32_e32 v19, 1.0, v19
	v_rcp_f32_e32 v16, v16
	v_rcp_f32_e32 v18, v18
	v_rcp_f32_e32 v19, v19
	v_rcp_f32_e32 v17, v17
	v_or_b32_e32 v20, 0x70, v120
	v_ashrrev_i32_e32 v21, 31, v20
	v_pk_mul_f32 v[18:19], v[18:19], s[6:7] op_sel_hi:[1,0]
	v_pk_mul_f32 v[16:17], v[16:17], s[6:7] op_sel_hi:[1,0]
	v_lshlrev_b64 v[20:21], 10, v[20:21]
	v_cvt_pk_bf16_f32 v16, v16, v17
	v_cvt_pk_bf16_f32 v17, v18, v19
	global_store_dwordx2 v[32:33], v[16:17], off offset:96
	global_load_dwordx4 v[16:19], v[116:117], off offset:2048
	s_waitcnt vmcnt(0)
	v_add_f32_e32 v12, v12, v16
	v_add_f32_e32 v13, v13, v17
	v_add_f32_e32 v14, v14, v18
	v_add_f32_e32 v15, v15, v19
	v_mul_f32_e32 v12, 0xbfb8aa3b, v12
	v_mul_f32_e32 v13, 0xbfb8aa3b, v13
	v_mul_f32_e32 v14, 0xbfb8aa3b, v14
	v_mul_f32_e32 v15, 0xbfb8aa3b, v15
	v_exp_f32_e32 v12, v12
	v_exp_f32_e32 v13, v13
	v_exp_f32_e32 v14, v14
	v_exp_f32_e32 v15, v15
	v_add_f32_e32 v12, 1.0, v12
	v_add_f32_e32 v13, 1.0, v13
	v_add_f32_e32 v14, 1.0, v14
	v_add_f32_e32 v15, 1.0, v15
	v_rcp_f32_e32 v12, v12
	v_rcp_f32_e32 v14, v14
	v_rcp_f32_e32 v15, v15
	v_rcp_f32_e32 v13, v13
	v_lshl_add_u64 v[16:17], s[0:1], 0, v[20:21]
	v_lshl_add_u64 v[16:17], v[16:17], 0, v[118:119]
	v_pk_mul_f32 v[14:15], v[14:15], s[6:7] op_sel_hi:[1,0]
	v_pk_mul_f32 v[12:13], v[12:13], s[6:7] op_sel_hi:[1,0]
	s_nop 0
	v_cvt_pk_bf16_f32 v12, v12, v13
	v_cvt_pk_bf16_f32 v13, v14, v15
	global_store_dwordx2 v[16:17], v[12:13], off
	global_load_dwordx4 v[12:15], v[116:117], off offset:2112
	s_waitcnt vmcnt(0)
	v_add_f32_e32 v8, v8, v12
	v_add_f32_e32 v9, v9, v13
	v_add_f32_e32 v10, v10, v14
	v_add_f32_e32 v11, v11, v15
	v_mul_f32_e32 v8, 0xbfb8aa3b, v8
	v_mul_f32_e32 v9, 0xbfb8aa3b, v9
	v_mul_f32_e32 v10, 0xbfb8aa3b, v10
	v_mul_f32_e32 v11, 0xbfb8aa3b, v11
	v_exp_f32_e32 v8, v8
	v_exp_f32_e32 v9, v9
	v_exp_f32_e32 v10, v10
	v_exp_f32_e32 v11, v11
	v_add_f32_e32 v8, 1.0, v8
	v_add_f32_e32 v9, 1.0, v9
	v_add_f32_e32 v10, 1.0, v10
	v_add_f32_e32 v11, 1.0, v11
	v_rcp_f32_e32 v8, v8
	v_rcp_f32_e32 v10, v10
	v_rcp_f32_e32 v11, v11
	v_rcp_f32_e32 v9, v9
	v_pk_mul_f32 v[10:11], v[10:11], s[6:7] op_sel_hi:[1,0]
	v_pk_mul_f32 v[8:9], v[8:9], s[6:7] op_sel_hi:[1,0]
	s_nop 0
	v_cvt_pk_bf16_f32 v8, v8, v9
	v_cvt_pk_bf16_f32 v9, v10, v11
	global_store_dwordx2 v[16:17], v[8:9], off offset:32
	global_load_dwordx4 v[8:11], v[116:117], off offset:2176
	s_waitcnt vmcnt(0)
	v_add_f32_e32 v4, v4, v8
	v_add_f32_e32 v5, v5, v9
	v_add_f32_e32 v6, v6, v10
	v_add_f32_e32 v7, v7, v11
	v_mul_f32_e32 v4, 0xbfb8aa3b, v4
	v_mul_f32_e32 v5, 0xbfb8aa3b, v5
	v_mul_f32_e32 v6, 0xbfb8aa3b, v6
	v_mul_f32_e32 v7, 0xbfb8aa3b, v7
	v_exp_f32_e32 v4, v4
	v_exp_f32_e32 v5, v5
	v_exp_f32_e32 v6, v6
	v_exp_f32_e32 v7, v7
	v_add_f32_e32 v4, 1.0, v4
	v_add_f32_e32 v5, 1.0, v5
	v_add_f32_e32 v6, 1.0, v6
	v_add_f32_e32 v7, 1.0, v7
	v_rcp_f32_e32 v4, v4
	v_rcp_f32_e32 v6, v6
	v_rcp_f32_e32 v7, v7
	v_rcp_f32_e32 v5, v5
	v_pk_mul_f32 v[6:7], v[6:7], s[6:7] op_sel_hi:[1,0]
	v_pk_mul_f32 v[4:5], v[4:5], s[6:7] op_sel_hi:[1,0]
	s_add_i32 s7, s7, s11
	v_cvt_pk_bf16_f32 v4, v4, v5
	v_cvt_pk_bf16_f32 v5, v6, v7
	global_store_dwordx2 v[16:17], v[4:5], off offset:64
	global_load_dwordx4 v[4:7], v[116:117], off offset:2240
	s_cmp_gt_i32 s9, 63
	s_waitcnt vmcnt(0)
	v_add_f32_e32 v0, v0, v4
	v_add_f32_e32 v1, v1, v5
	v_add_f32_e32 v2, v2, v6
	v_add_f32_e32 v3, v3, v7
	v_mul_f32_e32 v0, 0xbfb8aa3b, v0
	v_mul_f32_e32 v1, 0xbfb8aa3b, v1
	v_mul_f32_e32 v2, 0xbfb8aa3b, v2
	v_mul_f32_e32 v3, 0xbfb8aa3b, v3
	v_exp_f32_e32 v0, v0
	v_exp_f32_e32 v1, v1
	v_exp_f32_e32 v2, v2
	v_exp_f32_e32 v3, v3
	v_add_f32_e32 v0, 1.0, v0
	v_add_f32_e32 v1, 1.0, v1
	v_add_f32_e32 v2, 1.0, v2
	v_add_f32_e32 v3, 1.0, v3
	v_rcp_f32_e32 v0, v0
	v_rcp_f32_e32 v2, v2
	v_rcp_f32_e32 v3, v3
	v_rcp_f32_e32 v1, v1
	v_pk_mul_f32 v[2:3], v[2:3], s[6:7] op_sel_hi:[1,0]
	v_pk_mul_f32 v[0:1], v[0:1], s[6:7] op_sel_hi:[1,0]
	s_nop 0
	v_cvt_pk_bf16_f32 v0, v0, v1
	v_cvt_pk_bf16_f32 v1, v2, v3
	global_store_dwordx2 v[16:17], v[0:1], off offset:96
	s_cbranch_scc0 .LBB0_567
; #define LWRITE(S, buf) do { bf16_t* sA_ = sbase + (buf) * BUF; bf16_t* sB_ = sA_ + 256 * PITCH; \
;     _Pragma("unroll") for (int i_ = 0; i_ < 4; ++i_) *(u32x4*)(sA_ + (sr + i_ * 64) * PITCH + scv * 8) = ra[S][i_]; \
;     _Pragma("unroll") for (int i_ = 0; i_ < 2; ++i_) *(u32x4*)(sB_ + (sr + i_ * 64) * PITCH + scv * 8) = rb[S][i_]; } while (0)
; template <class Epi>
; DI void gemm_tile(char* smem, const bf16_t* __restrict__ A0, int lda0, int ksplit, const bf16_t* __restrict__ A1, int lda1,
;                   const bf16_t* __restrict__ Bt, int K, int row0, int col0, const Epi& epi, int tid) {
;   constexpr int BK = 32, PITCH = 40, BUF = (256 + 128) * PITCH;
;   bf16_t* sbase = (bf16_t*)smem;
;   const int lane = tid & 63, wid = tid >> 6, wr = wid >> 1, wc = wid & 1, fr = lane & 15, fq = lane >> 4;
;   f32x4 acc[8][4];
; #pragma unroll
;   for (int m = 0; m < 8; ++m)
; #pragma unroll
;     for (int n = 0; n < 4; ++n) acc[m][n] = (f32x4){0.f, 0.f, 0.f, 0.f};
;   u32x4 ra[2][4], rb[2][2];
;   const int nk = K / BK;
;   const int sr = tid >> 2, scv = tid & 3;
;     ...
;   __syncthreads();
;   {
;     const int last = nk - 1;
;     GLOAD(0, 0);
;     __builtin_amdgcn_sched_barrier(0);
;     GLOAD(1, 1);
;     __builtin_amdgcn_sched_barrier(0);
;     LWRITE(0, 0);
;     __builtin_amdgcn_sched_barrier(0);
;     GLOAD(0, (2 < last ? 2 : last));
;     __builtin_amdgcn_sched_barrier(0);
;     __syncthreads();
;     for (int kt = 0; kt < nk; kt += 2) {
;       LWRITE(1, 1);
;       __builtin_amdgcn_sched_barrier(0);
;       GLOAD(1, (kt + 3 < last ? kt + 3 : last));
;       __builtin_amdgcn_sched_barrier(0);
;       COMPUTE(0);
;       __syncthreads();
;       LWRITE(0, 0);
;       __builtin_amdgcn_sched_barrier(0);
;       GLOAD(0, (kt + 4 < last ? kt + 4 : last));
;       __builtin_amdgcn_sched_barrier(0);
;       COMPUTE(1);
;       __syncthreads();
;     }
; DI void phase_rw_small_gemms(const Ctx& c, char* smem) {
;     ...
;   gemm_phase(smem, sm + 64, 256, 1 << 30, sm, 256, A2, 64, 4, EpiSmall{1, p.rw_a0, Ab}, tid);
.LBB0_568:
	s_add_u32 s4, s92, 0xb800000
	s_addc_u32 s5, s93, 0
	s_add_u32 s0, s92, 0x34c0000
	s_addc_u32 s1, s93, 0
	s_add_u32 s6, s92, 0x1ea00080
	s_addc_u32 s7, s93, 0
	s_and_b64 vcc, exec, s[2:3]
	s_cbranch_vccz .LBB0_573
	s_load_dwordx16 s[16:31], s[74:75], 0x40
	s_cmpk_gt_i32 s96, 0x1ff
	s_cbranch_scc1 .LBB0_572
	v_and_b32_e32 v0, 3, v136
	v_lshlrev_b32_e32 v0, 4, v0
	v_mov_b32_e32 v1, 0
	v_ashrrev_i32_e32 v118, 2, v137
	v_lshl_add_u64 v[108:109], s[6:7], 0, v[0:1]
	v_lshl_add_u64 v[110:111], s[0:1], 0, v[0:1]
	v_bfe_u32 v1, v136, 4, 2
	s_movk_i32 s8, 0x40
	v_and_b32_e32 v3, 0x4f, v137
	v_and_b32_e32 v119, 0xffffff8f, v137
	v_or_b32_e32 v6, 0x70, v137
	v_add_u32_e32 v0, 0, v0
	v_mul_lo_u32 v2, v118, s8
	v_lshl_add_u32 v4, v1, 4, 0
	v_mul_u32_u24_e32 v3, 0x40, v3
	v_mul_lo_u32 v5, v119, s8
	v_mul_lo_u32 v6, v6, s8
	v_lshlrev_b32_e32 v1, 2, v1
	s_waitcnt lgkmcnt(0)
	s_mov_b64 s[58:59], s[22:23]
	v_and_or_b32 v120, v137, 64, v1
	s_lshl_b32 s15, s96, 7
	s_lshl_b32 s16, s12, 7
	s_mov_b64 s[8:9], 0x10000
	s_mov_b32 s17, 0x10000
	s_mov_b64 s[10:11], 0x18000
	s_mov_b32 s18, 0x18000
	v_add_u32_e32 v121, v0, v2
	v_add_u32_e32 v122, v4, v3
	v_add_u32_e32 v123, v4, v5
	v_add_u32_e32 v124, v4, v6
	v_mbcnt_lo_u32_b32 v2, -1, 0
	v_mbcnt_hi_u32_b32 v2, -1, v2
	v_bfe_u32 v3, v2, 3, 1
	v_bfe_u32 v2, v2, 5, 1
	v_mul_u32_u24_e32 v3, 48, v3
	v_mul_u32_u24_e32 v2, 48, v2
	v_xor_b32_e32 v121, v121, v2
	v_xor_b32_e32 v122, v122, v3
	v_xor_b32_e32 v123, v123, v3
	v_xor_b32_e32 v124, v124, v3
	s_mov_b32 s19, s96
.LBB0_571:
	s_ashr_i32 s20, s19, 31
	s_lshr_b32 s20, s20, 30
	s_add_i32 s20, s19, s20
	s_ashr_i32 s21, s20, 2
	s_lshl_b32 s20, s21, 8
	v_add_u32_e32 v0, s20, v118
	v_ashrrev_i32_e32 v1, 31, v0
	v_lshlrev_b64 v[0:1], 9, v[0:1]
	v_lshl_add_u64 v[24:25], v[108:109], 0, v[0:1]
	s_mov_b32 s22, 0x8000
	s_lshl_b32 s21, s21, 9
	v_add_co_u32_e32 v4, vcc, s22, v24
	s_sub_i32 s21, s15, s21
	s_nop 0
	v_addc_co_u32_e32 v5, vcc, 0, v25, vcc
	v_add_u32_e32 v16, s21, v118
	v_add_co_u32_e32 v8, vcc, s17, v24
	v_ashrrev_i32_e32 v17, 31, v16
	s_nop 0
	v_addc_co_u32_e32 v9, vcc, 0, v25, vcc
	v_lshlrev_b64 v[18:19], 7, v[16:17]
	v_add_u32_e32 v16, 64, v16
	v_add_co_u32_e32 v12, vcc, s18, v24
	v_ashrrev_i32_e32 v17, 31, v16
	s_nop 0
	v_addc_co_u32_e32 v13, vcc, 0, v25, vcc
	v_lshl_add_u64 v[40:41], v[110:111], 0, v[18:19]
	v_lshlrev_b64 v[16:17], 7, v[16:17]
	s_barrier
	global_load_dwordx4 v[0:3], v[24:25], off
	s_nop 0
	global_load_dwordx4 v[4:7], v[4:5], off
	s_nop 0
	global_load_dwordx4 v[8:11], v[8:9], off
	s_nop 0
	global_load_dwordx4 v[12:15], v[12:13], off
	v_lshl_add_u64 v[44:45], v[110:111], 0, v[16:17]
	global_load_dwordx4 v[16:19], v[40:41], off
	global_load_dwordx4 v[20:23], v[44:45], off
	s_mov_b64 s[22:23], 0x8000
	v_lshl_add_u64 v[28:29], v[24:25], 0, s[22:23]
	v_lshl_add_u64 v[32:33], v[24:25], 0, s[8:9]
	v_lshl_add_u64 v[36:37], v[24:25], 0, s[10:11]
	global_load_dwordx4 v[24:27], v[24:25], off offset:64
	s_nop 0
	global_load_dwordx4 v[28:31], v[28:29], off offset:64
	s_nop 0
	global_load_dwordx4 v[32:35], v[32:33], off offset:64
	s_nop 0
	global_load_dwordx4 v[36:39], v[36:37], off offset:64
	s_nop 0
	global_load_dwordx4 v[40:43], v[40:41], off offset:64
	s_nop 0
	global_load_dwordx4 v[44:47], v[44:45], off offset:64
	s_waitcnt vmcnt(11)
	ds_write_b128 v121, v[0:3]
	s_waitcnt vmcnt(10)
	ds_write_b128 v121, v[4:7] offset:4096
	s_waitcnt vmcnt(9)
	ds_write_b128 v121, v[8:11] offset:8192
	s_waitcnt vmcnt(8)
	ds_write_b128 v121, v[12:15] offset:12288
	s_waitcnt vmcnt(7)
	ds_write_b128 v121, v[16:19] offset:16384
	s_waitcnt vmcnt(6)
	ds_write_b128 v121, v[20:23] offset:20480
	s_waitcnt lgkmcnt(0)
	s_barrier
	s_waitcnt vmcnt(5)
	ds_write_b128 v121, v[24:27] offset:24576
	s_waitcnt vmcnt(4)
	ds_write_b128 v121, v[28:31] offset:28672
	s_waitcnt vmcnt(3)
	ds_write_b128 v121, v[32:35] offset:32768
	s_waitcnt vmcnt(2)
	ds_write_b128 v121, v[36:39] offset:36864
	s_waitcnt vmcnt(1)
	ds_write_b128 v121, v[40:43] offset:40960
	s_waitcnt vmcnt(0)
	ds_write_b128 v121, v[44:47] offset:45056
	ds_read_b128 v[0:3], v122 offset:16384
	ds_read_b128 v[4:7], v122 offset:17408
	ds_read_b128 v[8:11], v122 offset:18432
	ds_read_b128 v[12:15], v122 offset:19456
	ds_read_b128 v[16:19], v123
	ds_read_b128 v[20:23], v123 offset:1024
	ds_read_b128 v[48:51], v123 offset:2048
	ds_read_b128 v[52:55], v123 offset:3072
	ds_read_b128 v[56:59], v123 offset:4096
	ds_read_b128 v[60:63], v123 offset:5120
	ds_read_b128 v[64:67], v123 offset:6144
	ds_read_b128 v[68:71], v124
	s_setprio 1
	s_waitcnt lgkmcnt(7)
	v_mfma_f32_16x16x32_bf16 v[72:75], v[0:3], v[16:19], 0
	v_mfma_f32_16x16x32_bf16 v[76:79], v[4:7], v[16:19], 0
	v_mfma_f32_16x16x32_bf16 v[80:83], v[8:11], v[16:19], 0
	v_mfma_f32_16x16x32_bf16 v[16:19], v[12:15], v[16:19], 0
	s_waitcnt lgkmcnt(6)
	v_mfma_f32_16x16x32_bf16 v[84:87], v[0:3], v[20:23], 0
	v_mfma_f32_16x16x32_bf16 v[88:91], v[4:7], v[20:23], 0
	v_mfma_f32_16x16x32_bf16 v[92:95], v[8:11], v[20:23], 0
	v_mfma_f32_16x16x32_bf16 v[20:23], v[12:15], v[20:23], 0
	s_waitcnt lgkmcnt(5)
	v_mfma_f32_16x16x32_bf16 v[112:115], v[0:3], v[48:51], 0
	v_mfma_f32_16x16x32_bf16 v[126:129], v[4:7], v[48:51], 0
	v_mfma_f32_16x16x32_bf16 v[130:133], v[8:11], v[48:51], 0
	v_mfma_f32_16x16x32_bf16 v[48:51], v[12:15], v[48:51], 0
	s_waitcnt lgkmcnt(4)
	v_mfma_f32_16x16x32_bf16 v[138:141], v[0:3], v[52:55], 0
	v_mfma_f32_16x16x32_bf16 v[142:145], v[4:7], v[52:55], 0
	v_mfma_f32_16x16x32_bf16 v[146:149], v[8:11], v[52:55], 0
	v_mfma_f32_16x16x32_bf16 v[52:55], v[12:15], v[52:55], 0
	s_waitcnt lgkmcnt(3)
	v_mfma_f32_16x16x32_bf16 v[150:153], v[0:3], v[56:59], 0
	v_mfma_f32_16x16x32_bf16 v[154:157], v[4:7], v[56:59], 0
	v_mfma_f32_16x16x32_bf16 v[158:161], v[8:11], v[56:59], 0
	v_mfma_f32_16x16x32_bf16 v[162:165], v[12:15], v[56:59], 0
	s_waitcnt lgkmcnt(2)
	v_mfma_f32_16x16x32_bf16 v[166:169], v[0:3], v[60:63], 0
	v_mfma_f32_16x16x32_bf16 v[170:173], v[4:7], v[60:63], 0
	v_mfma_f32_16x16x32_bf16 v[174:177], v[8:11], v[60:63], 0
	v_mfma_f32_16x16x32_bf16 v[178:181], v[12:15], v[60:63], 0
	s_waitcnt lgkmcnt(1)
	v_mfma_f32_16x16x32_bf16 v[182:185], v[0:3], v[64:67], 0
	v_mfma_f32_16x16x32_bf16 v[186:189], v[4:7], v[64:67], 0
	v_mfma_f32_16x16x32_bf16 v[190:193], v[8:11], v[64:67], 0
	v_mfma_f32_16x16x32_bf16 v[196:199], v[12:15], v[64:67], 0
	s_waitcnt lgkmcnt(0)
	v_mfma_f32_16x16x32_bf16 v[0:3], v[0:3], v[68:71], 0
	v_mfma_f32_16x16x32_bf16 v[4:7], v[4:7], v[68:71], 0
	v_mfma_f32_16x16x32_bf16 v[200:203], v[8:11], v[68:71], 0
	v_mfma_f32_16x16x32_bf16 v[204:207], v[12:15], v[68:71], 0
	s_setprio 0
	s_barrier
; #define LWRITE(S, buf) do { bf16_t* sA_ = sbase + (buf) * BUF; bf16_t* sB_ = sA_ + 256 * PITCH; \
;     _Pragma("unroll") for (int i_ = 0; i_ < 4; ++i_) *(u32x4*)(sA_ + (sr + i_ * 64) * PITCH + scv * 8) = ra[S][i_]; \
;     _Pragma("unroll") for (int i_ = 0; i_ < 2; ++i_) *(u32x4*)(sB_ + (sr + i_ * 64) * PITCH + scv * 8) = rb[S][i_]; } while (0)
; template <class Epi>
; DI void gemm_tile(char* smem, const bf16_t* __restrict__ A0, int lda0, int ksplit, const bf16_t* __restrict__ A1, int lda1,
;                   const bf16_t* __restrict__ Bt, int K, int row0, int col0, const Epi& epi, int tid) {
;     ...
;   __syncthreads();
;   {
;     const int last = nk - 1;
;     GLOAD(0, 0);
;     __builtin_amdgcn_sched_barrier(0);
;     GLOAD(1, 1);
;     __builtin_amdgcn_sched_barrier(0);
;     LWRITE(0, 0);
;     __builtin_amdgcn_sched_barrier(0);
;     GLOAD(0, (2 < last ? 2 : last));
;     __builtin_amdgcn_sched_barrier(0);
;     __syncthreads();
;     for (int kt = 0; kt < nk; kt += 2) {
;       LWRITE(1, 1);
;       __builtin_amdgcn_sched_barrier(0);
;       GLOAD(1, (kt + 3 < last ? kt + 3 : last));
;       __builtin_amdgcn_sched_barrier(0);
;       COMPUTE(0);
;       __syncthreads();
;       LWRITE(0, 0);
;       __builtin_amdgcn_sched_barrier(0);
;       GLOAD(0, (kt + 4 < last ? kt + 4 : last));
;       __builtin_amdgcn_sched_barrier(0);
;       COMPUTE(1);
;       __syncthreads();
	ds_write_b128 v121, v[24:27]
	ds_write_b128 v121, v[28:31] offset:4096
	ds_write_b128 v121, v[32:35] offset:8192
	ds_write_b128 v121, v[36:39] offset:12288
	ds_write_b128 v121, v[40:43] offset:16384
	ds_write_b128 v121, v[44:47] offset:20480
	ds_read_b128 v[8:11], v122 offset:40960
	ds_read_b128 v[208:211], v122 offset:41984
	ds_read_b128 v[212:215], v122 offset:43008
	ds_read_b128 v[216:219], v122 offset:44032
	ds_read_b128 v[12:15], v123 offset:26624
	ds_read_b128 v[24:27], v123 offset:27648
	ds_read_b128 v[28:31], v123 offset:28672
	ds_read_b128 v[32:35], v123 offset:29696
	ds_read_b128 v[36:39], v123 offset:24576
	ds_read_b128 v[220:223], v123 offset:30720
	ds_read_b128 v[40:43], v123 offset:25600
	ds_read_b128 v[224:227], v124 offset:24576
	s_setprio 1
	s_waitcnt lgkmcnt(3)
	v_mfma_f32_16x16x32_bf16 v[228:231], v[8:11], v[36:39], v[72:75]
	v_mfma_f32_16x16x32_bf16 v[232:235], v[208:211], v[36:39], v[76:79]
	v_mfma_f32_16x16x32_bf16 v[236:239], v[212:215], v[36:39], v[80:83]
	v_mfma_f32_16x16x32_bf16 v[240:243], v[216:219], v[36:39], v[16:19]
	s_waitcnt lgkmcnt(1)
	v_mfma_f32_16x16x32_bf16 v[244:247], v[8:11], v[40:43], v[84:87]
	v_mfma_f32_16x16x32_bf16 v[104:107], v[208:211], v[40:43], v[88:91]
	v_mfma_f32_16x16x32_bf16 v[100:103], v[212:215], v[40:43], v[92:95]
	v_mfma_f32_16x16x32_bf16 v[96:99], v[216:219], v[40:43], v[20:23]
	v_mfma_f32_16x16x32_bf16 v[92:95], v[8:11], v[12:15], v[112:115]
	v_mfma_f32_16x16x32_bf16 v[88:91], v[208:211], v[12:15], v[126:129]
	v_mfma_f32_16x16x32_bf16 v[84:87], v[212:215], v[12:15], v[130:133]
	v_mfma_f32_16x16x32_bf16 v[80:83], v[216:219], v[12:15], v[48:51]
	v_mfma_f32_16x16x32_bf16 v[76:79], v[8:11], v[24:27], v[138:141]
	v_mfma_f32_16x16x32_bf16 v[72:75], v[208:211], v[24:27], v[142:145]
	v_mfma_f32_16x16x32_bf16 v[68:71], v[212:215], v[24:27], v[146:149]
	v_mfma_f32_16x16x32_bf16 v[64:67], v[216:219], v[24:27], v[52:55]
	v_mfma_f32_16x16x32_bf16 v[60:63], v[8:11], v[28:31], v[150:153]
	v_mfma_f32_16x16x32_bf16 v[56:59], v[208:211], v[28:31], v[154:157]
	v_mfma_f32_16x16x32_bf16 v[52:55], v[212:215], v[28:31], v[158:161]
	v_mfma_f32_16x16x32_bf16 v[48:51], v[216:219], v[28:31], v[162:165]
	v_mfma_f32_16x16x32_bf16 v[44:47], v[8:11], v[32:35], v[166:169]
	v_mfma_f32_16x16x32_bf16 v[40:43], v[208:211], v[32:35], v[170:173]
	v_mfma_f32_16x16x32_bf16 v[36:39], v[212:215], v[32:35], v[174:177]
	v_mfma_f32_16x16x32_bf16 v[32:35], v[216:219], v[32:35], v[178:181]
	v_mfma_f32_16x16x32_bf16 v[28:31], v[8:11], v[220:223], v[182:185]
	v_mfma_f32_16x16x32_bf16 v[24:27], v[208:211], v[220:223], v[186:189]
	v_mfma_f32_16x16x32_bf16 v[20:23], v[212:215], v[220:223], v[190:193]
	v_mfma_f32_16x16x32_bf16 v[16:19], v[216:219], v[220:223], v[196:199]
	s_waitcnt lgkmcnt(0)
	v_mfma_f32_16x16x32_bf16 v[12:15], v[8:11], v[224:227], v[0:3]
	v_mfma_f32_16x16x32_bf16 v[8:11], v[208:211], v[224:227], v[4:7]
	v_mfma_f32_16x16x32_bf16 v[4:7], v[212:215], v[224:227], v[200:203]
	v_mfma_f32_16x16x32_bf16 v[0:3], v[216:219], v[224:227], v[204:207]
	s_setprio 0
	v_add_u32_e32 v114, s21, v120
	v_ashrrev_i32_e32 v115, 31, v114
	v_lshl_add_u64 v[112:113], v[114:115], 2, s[58:59]
	s_barrier
	global_load_dwordx4 v[126:129], v[112:113], off
	v_add_u32_e32 v116, s20, v119
	v_ashrrev_i32_e32 v117, 31, v116
	v_lshlrev_b64 v[130:131], 10, v[116:117]
	v_lshlrev_b64 v[114:115], 1, v[114:115]
	s_add_i32 s19, s19, s12
	s_add_i32 s15, s15, s16
	s_cmpk_lt_i32 s19, 0x200
	s_waitcnt vmcnt(0)
	v_add_f32_e32 v117, v228, v126
	v_add_f32_e32 v125, v229, v127
	v_add_f32_e32 v126, v230, v128
	v_add_f32_e32 v127, v231, v129
	v_mul_f32_e32 v117, 0xbfb8aa3b, v117
	v_mul_f32_e32 v125, 0xbfb8aa3b, v125
	v_mul_f32_e32 v126, 0xbfb8aa3b, v126
	v_mul_f32_e32 v127, 0xbfb8aa3b, v127
	v_exp_f32_e32 v117, v117
	v_exp_f32_e32 v125, v125
	v_exp_f32_e32 v126, v126
	v_exp_f32_e32 v127, v127
	v_add_f32_e32 v117, 1.0, v117
	v_add_f32_e32 v125, 1.0, v125
	v_add_f32_e32 v126, 1.0, v126
	v_add_f32_e32 v127, 1.0, v127
	v_rcp_f32_e32 v117, v117
	v_rcp_f32_e32 v125, v125
	v_rcp_f32_e32 v128, v126
	v_rcp_f32_e32 v129, v127
	v_lshl_add_u64 v[126:127], s[4:5], 0, v[130:131]
	v_lshl_add_u64 v[130:131], v[126:127], 0, v[114:115]
	v_cvt_pk_bf16_f32 v126, v117, v125
	v_cvt_pk_bf16_f32 v127, v128, v129
	global_store_dwordx2 v[130:131], v[126:127], off
	global_load_dwordx4 v[126:129], v[112:113], off offset:64
	s_waitcnt vmcnt(0)
	v_add_f32_e32 v117, v232, v126
	v_add_f32_e32 v125, v233, v127
	v_add_f32_e32 v126, v234, v128
	v_add_f32_e32 v127, v235, v129
	v_mul_f32_e32 v117, 0xbfb8aa3b, v117
	v_mul_f32_e32 v125, 0xbfb8aa3b, v125
	v_mul_f32_e32 v126, 0xbfb8aa3b, v126
	v_mul_f32_e32 v127, 0xbfb8aa3b, v127
	v_exp_f32_e32 v117, v117
	v_exp_f32_e32 v125, v125
	v_exp_f32_e32 v126, v126
	v_exp_f32_e32 v127, v127
	v_add_f32_e32 v117, 1.0, v117
	v_add_f32_e32 v125, 1.0, v125
	v_add_f32_e32 v126, 1.0, v126
	v_add_f32_e32 v127, 1.0, v127
	v_rcp_f32_e32 v117, v117
	v_rcp_f32_e32 v125, v125
	v_rcp_f32_e32 v128, v126
	v_rcp_f32_e32 v127, v127
	v_cvt_pk_bf16_f32 v126, v117, v125
	v_cvt_pk_bf16_f32 v127, v128, v127
	global_store_dwordx2 v[130:131], v[126:127], off offset:32
	global_load_dwordx4 v[126:129], v[112:113], off offset:128
	s_waitcnt vmcnt(0)
	v_add_f32_e32 v117, v236, v126
	v_add_f32_e32 v125, v237, v127
	v_add_f32_e32 v126, v238, v128
	v_add_f32_e32 v127, v239, v129
	v_mul_f32_e32 v117, 0xbfb8aa3b, v117
	v_mul_f32_e32 v125, 0xbfb8aa3b, v125
	v_mul_f32_e32 v126, 0xbfb8aa3b, v126
	v_mul_f32_e32 v127, 0xbfb8aa3b, v127
	v_exp_f32_e32 v117, v117
	v_exp_f32_e32 v125, v125
	v_exp_f32_e32 v126, v126
	v_exp_f32_e32 v127, v127
	v_add_f32_e32 v117, 1.0, v117
	v_add_f32_e32 v125, 1.0, v125
	v_add_f32_e32 v126, 1.0, v126
	v_add_f32_e32 v127, 1.0, v127
	v_rcp_f32_e32 v117, v117
	v_rcp_f32_e32 v125, v125
	v_rcp_f32_e32 v128, v126
	v_rcp_f32_e32 v127, v127
	v_cvt_pk_bf16_f32 v126, v117, v125
	v_cvt_pk_bf16_f32 v127, v128, v127
	global_store_dwordx2 v[130:131], v[126:127], off offset:64
	global_load_dwordx4 v[126:129], v[112:113], off offset:192
	s_waitcnt vmcnt(0)
; template <class Epi>
; DI void gemm_tile(char* smem, const bf16_t* __restrict__ A0, int lda0, int ksplit, const bf16_t* __restrict__ A1, int lda1,
;                   const bf16_t* __restrict__ Bt, int K, int row0, int col0, const Epi& epi, int tid) {
;     ...
; #pragma unroll
;   for (int m = 0; m < 8; ++m)
; #pragma unroll
;     for (int n = 0; n < 4; ++n) epi(row0 + wr * 128 + m * 16 + fr, col0 + wc * 64 + n * 16 + fq * 4, acc[m][n]);
	v_add_f32_e32 v117, v240, v126
	v_add_f32_e32 v125, v241, v127
	v_add_f32_e32 v126, v242, v128
	v_add_f32_e32 v127, v243, v129
	v_mul_f32_e32 v117, 0xbfb8aa3b, v117
	v_mul_f32_e32 v125, 0xbfb8aa3b, v125
	v_mul_f32_e32 v126, 0xbfb8aa3b, v126
	v_mul_f32_e32 v127, 0xbfb8aa3b, v127
	v_exp_f32_e32 v117, v117
	v_exp_f32_e32 v125, v125
	v_exp_f32_e32 v126, v126
	v_exp_f32_e32 v127, v127
	v_add_f32_e32 v117, 1.0, v117
	v_add_f32_e32 v125, 1.0, v125
	v_add_f32_e32 v126, 1.0, v126
	v_add_f32_e32 v127, 1.0, v127
	v_rcp_f32_e32 v117, v117
	v_rcp_f32_e32 v125, v125
	v_rcp_f32_e32 v128, v126
	v_rcp_f32_e32 v127, v127
	v_cvt_pk_bf16_f32 v126, v117, v125
	v_cvt_pk_bf16_f32 v127, v128, v127
	global_store_dwordx2 v[130:131], v[126:127], off offset:96
	global_load_dwordx4 v[126:129], v[112:113], off
	v_or_b32_e32 v130, 16, v116
	v_ashrrev_i32_e32 v131, 31, v130
	v_lshlrev_b64 v[130:131], 10, v[130:131]
	s_waitcnt vmcnt(0)
	v_add_f32_e32 v117, v244, v126
	v_add_f32_e32 v125, v245, v127
	v_add_f32_e32 v126, v246, v128
	v_add_f32_e32 v127, v247, v129
	v_mul_f32_e32 v117, 0xbfb8aa3b, v117
	v_mul_f32_e32 v125, 0xbfb8aa3b, v125
	v_mul_f32_e32 v126, 0xbfb8aa3b, v126
	v_mul_f32_e32 v127, 0xbfb8aa3b, v127
	v_exp_f32_e32 v117, v117
	v_exp_f32_e32 v125, v125
	v_exp_f32_e32 v126, v126
	v_exp_f32_e32 v127, v127
	v_add_f32_e32 v117, 1.0, v117
	v_add_f32_e32 v125, 1.0, v125
	v_add_f32_e32 v126, 1.0, v126
	v_add_f32_e32 v127, 1.0, v127
	v_rcp_f32_e32 v117, v117
	v_rcp_f32_e32 v125, v125
	v_rcp_f32_e32 v128, v126
	v_rcp_f32_e32 v129, v127
	v_lshl_add_u64 v[126:127], s[4:5], 0, v[130:131]
	v_lshl_add_u64 v[130:131], v[126:127], 0, v[114:115]
	v_cvt_pk_bf16_f32 v126, v117, v125
	v_cvt_pk_bf16_f32 v127, v128, v129
	global_store_dwordx2 v[130:131], v[126:127], off
	global_load_dwordx4 v[126:129], v[112:113], off offset:64
	s_waitcnt vmcnt(0)
	v_add_f32_e32 v104, v104, v126
	v_add_f32_e32 v105, v105, v127
	v_add_f32_e32 v106, v106, v128
	v_add_f32_e32 v107, v107, v129
	v_mul_f32_e32 v104, 0xbfb8aa3b, v104
	v_mul_f32_e32 v105, 0xbfb8aa3b, v105
	v_mul_f32_e32 v106, 0xbfb8aa3b, v106
	v_mul_f32_e32 v107, 0xbfb8aa3b, v107
	v_exp_f32_e32 v104, v104
	v_exp_f32_e32 v105, v105
	v_exp_f32_e32 v106, v106
	v_exp_f32_e32 v107, v107
	v_add_f32_e32 v104, 1.0, v104
	v_add_f32_e32 v105, 1.0, v105
	v_add_f32_e32 v106, 1.0, v106
	v_add_f32_e32 v107, 1.0, v107
	v_rcp_f32_e32 v104, v104
	v_rcp_f32_e32 v105, v105
	v_rcp_f32_e32 v106, v106
	v_rcp_f32_e32 v107, v107
	v_cvt_pk_bf16_f32 v104, v104, v105
	v_cvt_pk_bf16_f32 v105, v106, v107
	global_store_dwordx2 v[130:131], v[104:105], off offset:32
	global_load_dwordx4 v[104:107], v[112:113], off offset:128
	s_waitcnt vmcnt(0)
	v_add_f32_e32 v100, v100, v104
	v_add_f32_e32 v101, v101, v105
	v_add_f32_e32 v102, v102, v106
	v_add_f32_e32 v103, v103, v107
	v_mul_f32_e32 v100, 0xbfb8aa3b, v100
	v_mul_f32_e32 v101, 0xbfb8aa3b, v101
	v_mul_f32_e32 v102, 0xbfb8aa3b, v102
	v_mul_f32_e32 v103, 0xbfb8aa3b, v103
	v_exp_f32_e32 v100, v100
	v_exp_f32_e32 v101, v101
	v_exp_f32_e32 v102, v102
	v_exp_f32_e32 v103, v103
	v_add_f32_e32 v100, 1.0, v100
	v_add_f32_e32 v101, 1.0, v101
	v_add_f32_e32 v102, 1.0, v102
	v_add_f32_e32 v103, 1.0, v103
	v_rcp_f32_e32 v100, v100
	v_rcp_f32_e32 v101, v101
	v_rcp_f32_e32 v102, v102
	v_rcp_f32_e32 v103, v103
	v_cvt_pk_bf16_f32 v100, v100, v101
	v_cvt_pk_bf16_f32 v101, v102, v103
	global_store_dwordx2 v[130:131], v[100:101], off offset:64
	global_load_dwordx4 v[100:103], v[112:113], off offset:192
	s_waitcnt vmcnt(0)
	v_add_f32_e32 v96, v96, v100
	v_add_f32_e32 v97, v97, v101
	v_add_f32_e32 v98, v98, v102
	v_add_f32_e32 v99, v99, v103
	v_mul_f32_e32 v96, 0xbfb8aa3b, v96
	v_mul_f32_e32 v97, 0xbfb8aa3b, v97
	v_mul_f32_e32 v98, 0xbfb8aa3b, v98
	v_mul_f32_e32 v99, 0xbfb8aa3b, v99
	v_exp_f32_e32 v96, v96
	v_exp_f32_e32 v97, v97
	v_exp_f32_e32 v98, v98
	v_exp_f32_e32 v99, v99
	v_add_f32_e32 v96, 1.0, v96
	v_add_f32_e32 v97, 1.0, v97
	v_add_f32_e32 v98, 1.0, v98
	v_add_f32_e32 v99, 1.0, v99
	v_rcp_f32_e32 v96, v96
	v_rcp_f32_e32 v97, v97
	v_rcp_f32_e32 v98, v98
	v_rcp_f32_e32 v99, v99
	v_or_b32_e32 v100, 32, v116
	v_cvt_pk_bf16_f32 v96, v96, v97
	v_ashrrev_i32_e32 v101, 31, v100
	v_cvt_pk_bf16_f32 v97, v98, v99
	global_store_dwordx2 v[130:131], v[96:97], off offset:96
	global_load_dwordx4 v[96:99], v[112:113], off
	v_lshlrev_b64 v[100:101], 10, v[100:101]
	s_waitcnt vmcnt(0)
	v_add_f32_e32 v92, v92, v96
	v_add_f32_e32 v93, v93, v97
	v_add_f32_e32 v94, v94, v98
	v_add_f32_e32 v95, v95, v99
	v_mul_f32_e32 v92, 0xbfb8aa3b, v92
	v_mul_f32_e32 v93, 0xbfb8aa3b, v93
	v_mul_f32_e32 v94, 0xbfb8aa3b, v94
	v_mul_f32_e32 v95, 0xbfb8aa3b, v95
	v_exp_f32_e32 v92, v92
	v_exp_f32_e32 v93, v93
	v_exp_f32_e32 v94, v94
	v_exp_f32_e32 v95, v95
	v_add_f32_e32 v92, 1.0, v92
	v_add_f32_e32 v93, 1.0, v93
	v_add_f32_e32 v94, 1.0, v94
	v_add_f32_e32 v95, 1.0, v95
	v_rcp_f32_e32 v98, v92
	v_rcp_f32_e32 v99, v93
	v_rcp_f32_e32 v94, v94
	v_rcp_f32_e32 v95, v95
	v_lshl_add_u64 v[92:93], s[4:5], 0, v[100:101]
	v_lshl_add_u64 v[96:97], v[92:93], 0, v[114:115]
	v_cvt_pk_bf16_f32 v92, v98, v99
	v_cvt_pk_bf16_f32 v93, v94, v95
	global_store_dwordx2 v[96:97], v[92:93], off
	global_load_dwordx4 v[92:95], v[112:113], off offset:64
	s_waitcnt vmcnt(0)
	v_add_f32_e32 v88, v88, v92
	v_add_f32_e32 v89, v89, v93
	v_add_f32_e32 v90, v90, v94
	v_add_f32_e32 v91, v91, v95
	v_mul_f32_e32 v88, 0xbfb8aa3b, v88
	v_mul_f32_e32 v89, 0xbfb8aa3b, v89
	v_mul_f32_e32 v90, 0xbfb8aa3b, v90
	v_mul_f32_e32 v91, 0xbfb8aa3b, v91
	v_exp_f32_e32 v88, v88
	v_exp_f32_e32 v89, v89
	v_exp_f32_e32 v90, v90
	v_exp_f32_e32 v91, v91
	v_add_f32_e32 v88, 1.0, v88
	v_add_f32_e32 v89, 1.0, v89
	v_add_f32_e32 v90, 1.0, v90
	v_add_f32_e32 v91, 1.0, v91
	v_rcp_f32_e32 v88, v88
	v_rcp_f32_e32 v89, v89
	v_rcp_f32_e32 v90, v90
	v_rcp_f32_e32 v91, v91
	v_cvt_pk_bf16_f32 v88, v88, v89
	v_cvt_pk_bf16_f32 v89, v90, v91
	global_store_dwordx2 v[96:97], v[88:89], off offset:32
	global_load_dwordx4 v[88:91], v[112:113], off offset:128
	s_waitcnt vmcnt(0)
; template <class Epi>
; DI void gemm_tile(char* smem, const bf16_t* __restrict__ A0, int lda0, int ksplit, const bf16_t* __restrict__ A1, int lda1,
;                   const bf16_t* __restrict__ Bt, int K, int row0, int col0, const Epi& epi, int tid) {
;     ...
; #pragma unroll
;   for (int m = 0; m < 8; ++m)
; #pragma unroll
;     for (int n = 0; n < 4; ++n) epi(row0 + wr * 128 + m * 16 + fr, col0 + wc * 64 + n * 16 + fq * 4, acc[m][n]);
	v_add_f32_e32 v84, v84, v88
	v_add_f32_e32 v85, v85, v89
	v_add_f32_e32 v86, v86, v90
	v_add_f32_e32 v87, v87, v91
	v_mul_f32_e32 v84, 0xbfb8aa3b, v84
	v_mul_f32_e32 v85, 0xbfb8aa3b, v85
	v_mul_f32_e32 v86, 0xbfb8aa3b, v86
	v_mul_f32_e32 v87, 0xbfb8aa3b, v87
	v_exp_f32_e32 v84, v84
	v_exp_f32_e32 v85, v85
	v_exp_f32_e32 v86, v86
	v_exp_f32_e32 v87, v87
	v_add_f32_e32 v84, 1.0, v84
	v_add_f32_e32 v85, 1.0, v85
	v_add_f32_e32 v86, 1.0, v86
	v_add_f32_e32 v87, 1.0, v87
	v_rcp_f32_e32 v84, v84
	v_rcp_f32_e32 v85, v85
	v_rcp_f32_e32 v86, v86
	v_rcp_f32_e32 v87, v87
	v_cvt_pk_bf16_f32 v84, v84, v85
	v_cvt_pk_bf16_f32 v85, v86, v87
	global_store_dwordx2 v[96:97], v[84:85], off offset:64
	global_load_dwordx4 v[84:87], v[112:113], off offset:192
	s_waitcnt vmcnt(0)
	v_add_f32_e32 v80, v80, v84
	v_add_f32_e32 v81, v81, v85
	v_add_f32_e32 v82, v82, v86
	v_add_f32_e32 v83, v83, v87
	v_mul_f32_e32 v80, 0xbfb8aa3b, v80
	v_mul_f32_e32 v81, 0xbfb8aa3b, v81
	v_mul_f32_e32 v82, 0xbfb8aa3b, v82
	v_mul_f32_e32 v83, 0xbfb8aa3b, v83
	v_exp_f32_e32 v80, v80
	v_exp_f32_e32 v81, v81
	v_exp_f32_e32 v82, v82
	v_exp_f32_e32 v83, v83
	v_add_f32_e32 v80, 1.0, v80
	v_add_f32_e32 v81, 1.0, v81
	v_add_f32_e32 v82, 1.0, v82
	v_add_f32_e32 v83, 1.0, v83
	v_rcp_f32_e32 v80, v80
	v_rcp_f32_e32 v81, v81
	v_rcp_f32_e32 v82, v82
	v_rcp_f32_e32 v83, v83
	v_or_b32_e32 v84, 48, v116
	v_cvt_pk_bf16_f32 v80, v80, v81
	v_ashrrev_i32_e32 v85, 31, v84
	v_cvt_pk_bf16_f32 v81, v82, v83
	global_store_dwordx2 v[96:97], v[80:81], off offset:96
	global_load_dwordx4 v[80:83], v[112:113], off
	v_lshlrev_b64 v[84:85], 10, v[84:85]
	s_waitcnt vmcnt(0)
	v_add_f32_e32 v76, v76, v80
	v_add_f32_e32 v77, v77, v81
	v_add_f32_e32 v78, v78, v82
	v_add_f32_e32 v79, v79, v83
	v_mul_f32_e32 v76, 0xbfb8aa3b, v76
	v_mul_f32_e32 v77, 0xbfb8aa3b, v77
	v_mul_f32_e32 v78, 0xbfb8aa3b, v78
	v_mul_f32_e32 v79, 0xbfb8aa3b, v79
	v_exp_f32_e32 v76, v76
	v_exp_f32_e32 v77, v77
	v_exp_f32_e32 v78, v78
	v_exp_f32_e32 v79, v79
	v_add_f32_e32 v76, 1.0, v76
	v_add_f32_e32 v77, 1.0, v77
	v_add_f32_e32 v78, 1.0, v78
	v_add_f32_e32 v79, 1.0, v79
	v_rcp_f32_e32 v82, v76
	v_rcp_f32_e32 v83, v77
	v_rcp_f32_e32 v78, v78
	v_rcp_f32_e32 v79, v79
	v_lshl_add_u64 v[76:77], s[4:5], 0, v[84:85]
	v_lshl_add_u64 v[80:81], v[76:77], 0, v[114:115]
	v_cvt_pk_bf16_f32 v76, v82, v83
	v_cvt_pk_bf16_f32 v77, v78, v79
	global_store_dwordx2 v[80:81], v[76:77], off
	global_load_dwordx4 v[76:79], v[112:113], off offset:64
	s_waitcnt vmcnt(0)
	v_add_f32_e32 v72, v72, v76
	v_add_f32_e32 v73, v73, v77
	v_add_f32_e32 v74, v74, v78
	v_add_f32_e32 v75, v75, v79
	v_mul_f32_e32 v72, 0xbfb8aa3b, v72
	v_mul_f32_e32 v73, 0xbfb8aa3b, v73
	v_mul_f32_e32 v74, 0xbfb8aa3b, v74
	v_mul_f32_e32 v75, 0xbfb8aa3b, v75
	v_exp_f32_e32 v72, v72
	v_exp_f32_e32 v73, v73
	v_exp_f32_e32 v74, v74
	v_exp_f32_e32 v75, v75
	v_add_f32_e32 v72, 1.0, v72
	v_add_f32_e32 v73, 1.0, v73
	v_add_f32_e32 v74, 1.0, v74
	v_add_f32_e32 v75, 1.0, v75
	v_rcp_f32_e32 v72, v72
	v_rcp_f32_e32 v73, v73
	v_rcp_f32_e32 v74, v74
	v_rcp_f32_e32 v75, v75
	v_cvt_pk_bf16_f32 v72, v72, v73
	v_cvt_pk_bf16_f32 v73, v74, v75
	global_store_dwordx2 v[80:81], v[72:73], off offset:32
	global_load_dwordx4 v[72:75], v[112:113], off offset:128
	s_waitcnt vmcnt(0)
	v_add_f32_e32 v68, v68, v72
	v_add_f32_e32 v69, v69, v73
	v_add_f32_e32 v70, v70, v74
	v_add_f32_e32 v71, v71, v75
	v_mul_f32_e32 v68, 0xbfb8aa3b, v68
	v_mul_f32_e32 v69, 0xbfb8aa3b, v69
	v_mul_f32_e32 v70, 0xbfb8aa3b, v70
	v_mul_f32_e32 v71, 0xbfb8aa3b, v71
	v_exp_f32_e32 v68, v68
	v_exp_f32_e32 v69, v69
	v_exp_f32_e32 v70, v70
	v_exp_f32_e32 v71, v71
	v_add_f32_e32 v68, 1.0, v68
	v_add_f32_e32 v69, 1.0, v69
	v_add_f32_e32 v70, 1.0, v70
	v_add_f32_e32 v71, 1.0, v71
	v_rcp_f32_e32 v68, v68
	v_rcp_f32_e32 v69, v69
	v_rcp_f32_e32 v70, v70
	v_rcp_f32_e32 v71, v71
	v_cvt_pk_bf16_f32 v68, v68, v69
	v_cvt_pk_bf16_f32 v69, v70, v71
	global_store_dwordx2 v[80:81], v[68:69], off offset:64
	global_load_dwordx4 v[68:71], v[112:113], off offset:192
	s_waitcnt vmcnt(0)
	v_add_f32_e32 v64, v64, v68
	v_add_f32_e32 v65, v65, v69
	v_add_f32_e32 v66, v66, v70
	v_add_f32_e32 v67, v67, v71
	v_mul_f32_e32 v64, 0xbfb8aa3b, v64
	v_mul_f32_e32 v65, 0xbfb8aa3b, v65
	v_mul_f32_e32 v66, 0xbfb8aa3b, v66
	v_mul_f32_e32 v67, 0xbfb8aa3b, v67
	v_exp_f32_e32 v64, v64
	v_exp_f32_e32 v65, v65
	v_exp_f32_e32 v66, v66
	v_exp_f32_e32 v67, v67
	v_add_f32_e32 v64, 1.0, v64
	v_add_f32_e32 v65, 1.0, v65
	v_add_f32_e32 v66, 1.0, v66
	v_add_f32_e32 v67, 1.0, v67
	v_rcp_f32_e32 v64, v64
	v_rcp_f32_e32 v65, v65
	v_rcp_f32_e32 v66, v66
	v_rcp_f32_e32 v67, v67
	v_or_b32_e32 v68, 64, v116
	v_cvt_pk_bf16_f32 v64, v64, v65
	v_ashrrev_i32_e32 v69, 31, v68
	v_cvt_pk_bf16_f32 v65, v66, v67
	global_store_dwordx2 v[80:81], v[64:65], off offset:96
	global_load_dwordx4 v[64:67], v[112:113], off
	v_lshlrev_b64 v[68:69], 10, v[68:69]
	s_waitcnt vmcnt(0)
	v_add_f32_e32 v60, v60, v64
	v_add_f32_e32 v61, v61, v65
	v_add_f32_e32 v62, v62, v66
	v_add_f32_e32 v63, v63, v67
	v_mul_f32_e32 v60, 0xbfb8aa3b, v60
	v_mul_f32_e32 v61, 0xbfb8aa3b, v61
	v_mul_f32_e32 v62, 0xbfb8aa3b, v62
	v_mul_f32_e32 v63, 0xbfb8aa3b, v63
	v_exp_f32_e32 v60, v60
	v_exp_f32_e32 v61, v61
	v_exp_f32_e32 v62, v62
	v_exp_f32_e32 v63, v63
	v_add_f32_e32 v60, 1.0, v60
	v_add_f32_e32 v61, 1.0, v61
	v_add_f32_e32 v62, 1.0, v62
	v_add_f32_e32 v63, 1.0, v63
	v_rcp_f32_e32 v66, v60
	v_rcp_f32_e32 v67, v61
	v_rcp_f32_e32 v62, v62
	v_rcp_f32_e32 v63, v63
	v_lshl_add_u64 v[60:61], s[4:5], 0, v[68:69]
	v_lshl_add_u64 v[64:65], v[60:61], 0, v[114:115]
	v_cvt_pk_bf16_f32 v60, v66, v67
	v_cvt_pk_bf16_f32 v61, v62, v63
	global_store_dwordx2 v[64:65], v[60:61], off
	global_load_dwordx4 v[60:63], v[112:113], off offset:64
	s_waitcnt vmcnt(0)
; template <class Epi>
; DI void gemm_tile(char* smem, const bf16_t* __restrict__ A0, int lda0, int ksplit, const bf16_t* __restrict__ A1, int lda1,
;                   const bf16_t* __restrict__ Bt, int K, int row0, int col0, const Epi& epi, int tid) {
;     ...
; #pragma unroll
;   for (int m = 0; m < 8; ++m)
; #pragma unroll
;     for (int n = 0; n < 4; ++n) epi(row0 + wr * 128 + m * 16 + fr, col0 + wc * 64 + n * 16 + fq * 4, acc[m][n]);
	v_add_f32_e32 v56, v56, v60
	v_add_f32_e32 v57, v57, v61
	v_add_f32_e32 v58, v58, v62
	v_add_f32_e32 v59, v59, v63
	v_mul_f32_e32 v56, 0xbfb8aa3b, v56
	v_mul_f32_e32 v57, 0xbfb8aa3b, v57
	v_mul_f32_e32 v58, 0xbfb8aa3b, v58
	v_mul_f32_e32 v59, 0xbfb8aa3b, v59
	v_exp_f32_e32 v56, v56
	v_exp_f32_e32 v57, v57
	v_exp_f32_e32 v58, v58
	v_exp_f32_e32 v59, v59
	v_add_f32_e32 v56, 1.0, v56
	v_add_f32_e32 v57, 1.0, v57
	v_add_f32_e32 v58, 1.0, v58
	v_add_f32_e32 v59, 1.0, v59
	v_rcp_f32_e32 v56, v56
	v_rcp_f32_e32 v57, v57
	v_rcp_f32_e32 v58, v58
	v_rcp_f32_e32 v59, v59
	v_cvt_pk_bf16_f32 v56, v56, v57
	v_cvt_pk_bf16_f32 v57, v58, v59
	global_store_dwordx2 v[64:65], v[56:57], off offset:32
	global_load_dwordx4 v[56:59], v[112:113], off offset:128
	s_waitcnt vmcnt(0)
	v_add_f32_e32 v52, v52, v56
	v_add_f32_e32 v53, v53, v57
	v_add_f32_e32 v54, v54, v58
	v_add_f32_e32 v55, v55, v59
	v_mul_f32_e32 v52, 0xbfb8aa3b, v52
	v_mul_f32_e32 v53, 0xbfb8aa3b, v53
	v_mul_f32_e32 v54, 0xbfb8aa3b, v54
	v_mul_f32_e32 v55, 0xbfb8aa3b, v55
	v_exp_f32_e32 v52, v52
	v_exp_f32_e32 v53, v53
	v_exp_f32_e32 v54, v54
	v_exp_f32_e32 v55, v55
	v_add_f32_e32 v52, 1.0, v52
	v_add_f32_e32 v53, 1.0, v53
	v_add_f32_e32 v54, 1.0, v54
	v_add_f32_e32 v55, 1.0, v55
	v_rcp_f32_e32 v52, v52
	v_rcp_f32_e32 v53, v53
	v_rcp_f32_e32 v54, v54
	v_rcp_f32_e32 v55, v55
	v_cvt_pk_bf16_f32 v52, v52, v53
	v_cvt_pk_bf16_f32 v53, v54, v55
	global_store_dwordx2 v[64:65], v[52:53], off offset:64
	global_load_dwordx4 v[52:55], v[112:113], off offset:192
	s_waitcnt vmcnt(0)
	v_add_f32_e32 v48, v48, v52
	v_add_f32_e32 v49, v49, v53
	v_add_f32_e32 v50, v50, v54
	v_add_f32_e32 v51, v51, v55
	v_mul_f32_e32 v48, 0xbfb8aa3b, v48
	v_mul_f32_e32 v49, 0xbfb8aa3b, v49
	v_mul_f32_e32 v50, 0xbfb8aa3b, v50
	v_mul_f32_e32 v51, 0xbfb8aa3b, v51
	v_exp_f32_e32 v48, v48
	v_exp_f32_e32 v49, v49
	v_exp_f32_e32 v50, v50
	v_exp_f32_e32 v51, v51
	v_add_f32_e32 v48, 1.0, v48
	v_add_f32_e32 v49, 1.0, v49
	v_add_f32_e32 v50, 1.0, v50
	v_add_f32_e32 v51, 1.0, v51
	v_rcp_f32_e32 v48, v48
	v_rcp_f32_e32 v49, v49
	v_rcp_f32_e32 v50, v50
	v_rcp_f32_e32 v51, v51
	v_or_b32_e32 v52, 0x50, v116
	v_cvt_pk_bf16_f32 v48, v48, v49
	v_ashrrev_i32_e32 v53, 31, v52
	v_cvt_pk_bf16_f32 v49, v50, v51
	global_store_dwordx2 v[64:65], v[48:49], off offset:96
	global_load_dwordx4 v[48:51], v[112:113], off
	v_lshlrev_b64 v[52:53], 10, v[52:53]
	s_waitcnt vmcnt(0)
	v_add_f32_e32 v44, v44, v48
	v_add_f32_e32 v45, v45, v49
	v_add_f32_e32 v46, v46, v50
	v_add_f32_e32 v47, v47, v51
	v_mul_f32_e32 v44, 0xbfb8aa3b, v44
	v_mul_f32_e32 v45, 0xbfb8aa3b, v45
	v_mul_f32_e32 v46, 0xbfb8aa3b, v46
	v_mul_f32_e32 v47, 0xbfb8aa3b, v47
	v_exp_f32_e32 v44, v44
	v_exp_f32_e32 v45, v45
	v_exp_f32_e32 v46, v46
	v_exp_f32_e32 v47, v47
	v_add_f32_e32 v44, 1.0, v44
	v_add_f32_e32 v45, 1.0, v45
	v_add_f32_e32 v46, 1.0, v46
	v_add_f32_e32 v47, 1.0, v47
	v_rcp_f32_e32 v50, v44
	v_rcp_f32_e32 v51, v45
	v_rcp_f32_e32 v46, v46
	v_rcp_f32_e32 v47, v47
	v_lshl_add_u64 v[44:45], s[4:5], 0, v[52:53]
	v_lshl_add_u64 v[48:49], v[44:45], 0, v[114:115]
	v_cvt_pk_bf16_f32 v44, v50, v51
	v_cvt_pk_bf16_f32 v45, v46, v47
	global_store_dwordx2 v[48:49], v[44:45], off
	global_load_dwordx4 v[44:47], v[112:113], off offset:64
	s_waitcnt vmcnt(0)
	v_add_f32_e32 v40, v40, v44
	v_add_f32_e32 v41, v41, v45
	v_add_f32_e32 v42, v42, v46
	v_add_f32_e32 v43, v43, v47
	v_mul_f32_e32 v40, 0xbfb8aa3b, v40
	v_mul_f32_e32 v41, 0xbfb8aa3b, v41
	v_mul_f32_e32 v42, 0xbfb8aa3b, v42
	v_mul_f32_e32 v43, 0xbfb8aa3b, v43
	v_exp_f32_e32 v40, v40
	v_exp_f32_e32 v41, v41
	v_exp_f32_e32 v42, v42
	v_exp_f32_e32 v43, v43
	v_add_f32_e32 v40, 1.0, v40
	v_add_f32_e32 v41, 1.0, v41
	v_add_f32_e32 v42, 1.0, v42
	v_add_f32_e32 v43, 1.0, v43
	v_rcp_f32_e32 v40, v40
	v_rcp_f32_e32 v41, v41
	v_rcp_f32_e32 v42, v42
	v_rcp_f32_e32 v43, v43
	v_cvt_pk_bf16_f32 v40, v40, v41
	v_cvt_pk_bf16_f32 v41, v42, v43
	global_store_dwordx2 v[48:49], v[40:41], off offset:32
	global_load_dwordx4 v[40:43], v[112:113], off offset:128
	s_waitcnt vmcnt(0)
	v_add_f32_e32 v36, v36, v40
	v_add_f32_e32 v37, v37, v41
	v_add_f32_e32 v38, v38, v42
	v_add_f32_e32 v39, v39, v43
	v_mul_f32_e32 v36, 0xbfb8aa3b, v36
	v_mul_f32_e32 v37, 0xbfb8aa3b, v37
	v_mul_f32_e32 v38, 0xbfb8aa3b, v38
	v_mul_f32_e32 v39, 0xbfb8aa3b, v39
	v_exp_f32_e32 v36, v36
	v_exp_f32_e32 v37, v37
	v_exp_f32_e32 v38, v38
	v_exp_f32_e32 v39, v39
	v_add_f32_e32 v36, 1.0, v36
	v_add_f32_e32 v37, 1.0, v37
	v_add_f32_e32 v38, 1.0, v38
	v_add_f32_e32 v39, 1.0, v39
	v_rcp_f32_e32 v36, v36
	v_rcp_f32_e32 v37, v37
	v_rcp_f32_e32 v38, v38
	v_rcp_f32_e32 v39, v39
	v_cvt_pk_bf16_f32 v36, v36, v37
	v_cvt_pk_bf16_f32 v37, v38, v39
	global_store_dwordx2 v[48:49], v[36:37], off offset:64
	global_load_dwordx4 v[36:39], v[112:113], off offset:192
	s_waitcnt vmcnt(0)
	v_add_f32_e32 v32, v32, v36
	v_add_f32_e32 v33, v33, v37
	v_add_f32_e32 v34, v34, v38
	v_add_f32_e32 v35, v35, v39
	v_mul_f32_e32 v32, 0xbfb8aa3b, v32
	v_mul_f32_e32 v33, 0xbfb8aa3b, v33
	v_mul_f32_e32 v34, 0xbfb8aa3b, v34
	v_mul_f32_e32 v35, 0xbfb8aa3b, v35
	v_exp_f32_e32 v32, v32
	v_exp_f32_e32 v33, v33
	v_exp_f32_e32 v34, v34
	v_exp_f32_e32 v35, v35
	v_add_f32_e32 v32, 1.0, v32
	v_add_f32_e32 v33, 1.0, v33
	v_add_f32_e32 v34, 1.0, v34
	v_add_f32_e32 v35, 1.0, v35
	v_rcp_f32_e32 v32, v32
	v_rcp_f32_e32 v33, v33
	v_rcp_f32_e32 v34, v34
	v_rcp_f32_e32 v35, v35
	v_or_b32_e32 v36, 0x60, v116
	v_cvt_pk_bf16_f32 v32, v32, v33
	v_ashrrev_i32_e32 v37, 31, v36
	v_cvt_pk_bf16_f32 v33, v34, v35
	global_store_dwordx2 v[48:49], v[32:33], off offset:96
	global_load_dwordx4 v[32:35], v[112:113], off
	v_lshlrev_b64 v[36:37], 10, v[36:37]
	s_waitcnt vmcnt(0)
; DI unsigned pack2(float lo, float hi) { const f32x2c v = {lo, hi}; return __builtin_bit_cast(unsigned, __builtin_convertvector(v, bf16x2c)); }
; DI void st_bf16x4(bf16_t* o, f32x4 v) { u32x2 q; q.x = pack2(v[0], v[1]); q.y = pack2(v[2], v[3]); *(u32x2*)o = q; }
;   DI void operator()(int row, int col, f32x4 v) const {
;     if (col < n0) st_bf16x4(o0 + (size_t)row * ld0 + col, v);
;     else { const int c = col - n0; if (c < n1) st_bf16x4(o1 + (size_t)row * ld1 + c, v); }
;   }
	v_add_f32_e32 v28, v28, v32
	v_add_f32_e32 v29, v29, v33
	v_add_f32_e32 v30, v30, v34
	v_add_f32_e32 v31, v31, v35
	v_mul_f32_e32 v28, 0xbfb8aa3b, v28
	v_mul_f32_e32 v29, 0xbfb8aa3b, v29
	v_mul_f32_e32 v30, 0xbfb8aa3b, v30
	v_mul_f32_e32 v31, 0xbfb8aa3b, v31
	v_exp_f32_e32 v28, v28
	v_exp_f32_e32 v29, v29
	v_exp_f32_e32 v30, v30
	v_exp_f32_e32 v31, v31
	v_add_f32_e32 v28, 1.0, v28
	v_add_f32_e32 v29, 1.0, v29
	v_add_f32_e32 v30, 1.0, v30
	v_add_f32_e32 v31, 1.0, v31
	v_rcp_f32_e32 v34, v28
	v_rcp_f32_e32 v35, v29
	v_rcp_f32_e32 v30, v30
	v_rcp_f32_e32 v31, v31
	v_lshl_add_u64 v[28:29], s[4:5], 0, v[36:37]
	v_lshl_add_u64 v[32:33], v[28:29], 0, v[114:115]
	v_cvt_pk_bf16_f32 v28, v34, v35
	v_cvt_pk_bf16_f32 v29, v30, v31
	global_store_dwordx2 v[32:33], v[28:29], off
	global_load_dwordx4 v[28:31], v[112:113], off offset:64
	s_waitcnt vmcnt(0)
	v_add_f32_e32 v24, v24, v28
	v_add_f32_e32 v25, v25, v29
	v_add_f32_e32 v26, v26, v30
	v_add_f32_e32 v27, v27, v31
	v_mul_f32_e32 v24, 0xbfb8aa3b, v24
	v_mul_f32_e32 v25, 0xbfb8aa3b, v25
	v_mul_f32_e32 v26, 0xbfb8aa3b, v26
	v_mul_f32_e32 v27, 0xbfb8aa3b, v27
	v_exp_f32_e32 v24, v24
	v_exp_f32_e32 v25, v25
	v_exp_f32_e32 v26, v26
	v_exp_f32_e32 v27, v27
	v_add_f32_e32 v24, 1.0, v24
	v_add_f32_e32 v25, 1.0, v25
	v_add_f32_e32 v26, 1.0, v26
	v_add_f32_e32 v27, 1.0, v27
	v_rcp_f32_e32 v24, v24
	v_rcp_f32_e32 v25, v25
	v_rcp_f32_e32 v26, v26
	v_rcp_f32_e32 v27, v27
	v_cvt_pk_bf16_f32 v24, v24, v25
	v_cvt_pk_bf16_f32 v25, v26, v27
	global_store_dwordx2 v[32:33], v[24:25], off offset:32
	global_load_dwordx4 v[24:27], v[112:113], off offset:128
	s_waitcnt vmcnt(0)
	v_add_f32_e32 v20, v20, v24
	v_add_f32_e32 v21, v21, v25
	v_add_f32_e32 v22, v22, v26
	v_add_f32_e32 v23, v23, v27
	v_mul_f32_e32 v20, 0xbfb8aa3b, v20
	v_mul_f32_e32 v21, 0xbfb8aa3b, v21
	v_mul_f32_e32 v22, 0xbfb8aa3b, v22
	v_mul_f32_e32 v23, 0xbfb8aa3b, v23
	v_exp_f32_e32 v20, v20
	v_exp_f32_e32 v21, v21
	v_exp_f32_e32 v22, v22
	v_exp_f32_e32 v23, v23
	v_add_f32_e32 v20, 1.0, v20
	v_add_f32_e32 v21, 1.0, v21
	v_add_f32_e32 v22, 1.0, v22
	v_add_f32_e32 v23, 1.0, v23
	v_rcp_f32_e32 v20, v20
	v_rcp_f32_e32 v21, v21
	v_rcp_f32_e32 v22, v22
	v_rcp_f32_e32 v23, v23
	v_cvt_pk_bf16_f32 v20, v20, v21
	v_cvt_pk_bf16_f32 v21, v22, v23
	global_store_dwordx2 v[32:33], v[20:21], off offset:64
	global_load_dwordx4 v[20:23], v[112:113], off offset:192
	s_waitcnt vmcnt(0)
	v_add_f32_e32 v16, v16, v20
	v_add_f32_e32 v17, v17, v21
	v_add_f32_e32 v18, v18, v22
	v_add_f32_e32 v19, v19, v23
	v_mul_f32_e32 v16, 0xbfb8aa3b, v16
	v_mul_f32_e32 v17, 0xbfb8aa3b, v17
	v_mul_f32_e32 v18, 0xbfb8aa3b, v18
	v_mul_f32_e32 v19, 0xbfb8aa3b, v19
	v_exp_f32_e32 v16, v16
	v_exp_f32_e32 v17, v17
	v_exp_f32_e32 v18, v18
	v_exp_f32_e32 v19, v19
	v_add_f32_e32 v16, 1.0, v16
	v_add_f32_e32 v17, 1.0, v17
	v_add_f32_e32 v18, 1.0, v18
	v_add_f32_e32 v19, 1.0, v19
	v_rcp_f32_e32 v16, v16
	v_rcp_f32_e32 v17, v17
	v_rcp_f32_e32 v18, v18
	v_rcp_f32_e32 v19, v19
	v_or_b32_e32 v20, 0x70, v116
	v_cvt_pk_bf16_f32 v16, v16, v17
	v_ashrrev_i32_e32 v21, 31, v20
	v_cvt_pk_bf16_f32 v17, v18, v19
	global_store_dwordx2 v[32:33], v[16:17], off offset:96
	global_load_dwordx4 v[16:19], v[112:113], off
	v_lshlrev_b64 v[20:21], 10, v[20:21]
	s_waitcnt vmcnt(0)
	v_add_f32_e32 v12, v12, v16
	v_add_f32_e32 v13, v13, v17
	v_add_f32_e32 v14, v14, v18
	v_add_f32_e32 v15, v15, v19
	v_mul_f32_e32 v12, 0xbfb8aa3b, v12
	v_mul_f32_e32 v13, 0xbfb8aa3b, v13
	v_mul_f32_e32 v14, 0xbfb8aa3b, v14
	v_mul_f32_e32 v15, 0xbfb8aa3b, v15
	v_exp_f32_e32 v12, v12
	v_exp_f32_e32 v13, v13
	v_exp_f32_e32 v14, v14
	v_exp_f32_e32 v15, v15
	v_add_f32_e32 v12, 1.0, v12
	v_add_f32_e32 v13, 1.0, v13
	v_add_f32_e32 v14, 1.0, v14
	v_add_f32_e32 v15, 1.0, v15
	v_rcp_f32_e32 v18, v12
	v_rcp_f32_e32 v19, v13
	v_rcp_f32_e32 v14, v14
	v_rcp_f32_e32 v15, v15
	v_lshl_add_u64 v[12:13], s[4:5], 0, v[20:21]
	v_lshl_add_u64 v[16:17], v[12:13], 0, v[114:115]
	v_cvt_pk_bf16_f32 v12, v18, v19
	v_cvt_pk_bf16_f32 v13, v14, v15
	global_store_dwordx2 v[16:17], v[12:13], off
	global_load_dwordx4 v[12:15], v[112:113], off offset:64
	s_waitcnt vmcnt(0)
	v_add_f32_e32 v8, v8, v12
	v_add_f32_e32 v9, v9, v13
	v_add_f32_e32 v10, v10, v14
	v_add_f32_e32 v11, v11, v15
	v_mul_f32_e32 v8, 0xbfb8aa3b, v8
	v_mul_f32_e32 v9, 0xbfb8aa3b, v9
	v_mul_f32_e32 v10, 0xbfb8aa3b, v10
	v_mul_f32_e32 v11, 0xbfb8aa3b, v11
	v_exp_f32_e32 v8, v8
	v_exp_f32_e32 v9, v9
	v_exp_f32_e32 v10, v10
	v_exp_f32_e32 v11, v11
	v_add_f32_e32 v8, 1.0, v8
	v_add_f32_e32 v9, 1.0, v9
	v_add_f32_e32 v10, 1.0, v10
	v_add_f32_e32 v11, 1.0, v11
	v_rcp_f32_e32 v8, v8
	v_rcp_f32_e32 v9, v9
	v_rcp_f32_e32 v10, v10
	v_rcp_f32_e32 v11, v11
	v_cvt_pk_bf16_f32 v8, v8, v9
	v_cvt_pk_bf16_f32 v9, v10, v11
	global_store_dwordx2 v[16:17], v[8:9], off offset:32
	global_load_dwordx4 v[8:11], v[112:113], off offset:128
	s_waitcnt vmcnt(0)
	v_add_f32_e32 v4, v4, v8
	v_add_f32_e32 v5, v5, v9
	v_add_f32_e32 v6, v6, v10
	v_add_f32_e32 v7, v7, v11
	v_mul_f32_e32 v4, 0xbfb8aa3b, v4
	v_mul_f32_e32 v5, 0xbfb8aa3b, v5
	v_mul_f32_e32 v6, 0xbfb8aa3b, v6
	v_mul_f32_e32 v7, 0xbfb8aa3b, v7
	v_exp_f32_e32 v4, v4
	v_exp_f32_e32 v5, v5
	v_exp_f32_e32 v6, v6
	v_exp_f32_e32 v7, v7
	v_add_f32_e32 v4, 1.0, v4
	v_add_f32_e32 v5, 1.0, v5
	v_add_f32_e32 v6, 1.0, v6
	v_add_f32_e32 v7, 1.0, v7
	v_rcp_f32_e32 v4, v4
	v_rcp_f32_e32 v5, v5
	v_rcp_f32_e32 v6, v6
	v_rcp_f32_e32 v7, v7
	v_cvt_pk_bf16_f32 v4, v4, v5
	v_cvt_pk_bf16_f32 v5, v6, v7
	global_store_dwordx2 v[16:17], v[4:5], off offset:64
	global_load_dwordx4 v[4:7], v[112:113], off offset:192
	s_waitcnt vmcnt(0)
	v_add_f32_e32 v0, v0, v4
	v_add_f32_e32 v1, v1, v5
	v_add_f32_e32 v2, v2, v6
	v_add_f32_e32 v3, v3, v7
	v_mul_f32_e32 v0, 0xbfb8aa3b, v0
	v_mul_f32_e32 v1, 0xbfb8aa3b, v1
	v_mul_f32_e32 v2, 0xbfb8aa3b, v2
	v_mul_f32_e32 v3, 0xbfb8aa3b, v3
	v_exp_f32_e32 v0, v0
	v_exp_f32_e32 v1, v1
	v_exp_f32_e32 v2, v2
	v_exp_f32_e32 v3, v3
	v_add_f32_e32 v0, 1.0, v0
	v_add_f32_e32 v1, 1.0, v1
	v_add_f32_e32 v2, 1.0, v2
	v_add_f32_e32 v3, 1.0, v3
	v_rcp_f32_e32 v0, v0
	v_rcp_f32_e32 v1, v1
	v_rcp_f32_e32 v2, v2
	v_rcp_f32_e32 v3, v3
	v_cvt_pk_bf16_f32 v0, v0, v1
	v_cvt_pk_bf16_f32 v1, v2, v3
	global_store_dwordx2 v[16:17], v[0:1], off offset:96
	s_cbranch_scc1 .LBB0_571

; #define LWRITE(S, buf) do { bf16_t* sA_ = sbase + (buf) * BUF; bf16_t* sB_ = sA_ + 256 * PITCH; \
;     _Pragma("unroll") for (int i_ = 0; i_ < 4; ++i_) *(u32x4*)(sA_ + (sr + i_ * 64) * PITCH + scv * 8) = ra[S][i_]; \
;     _Pragma("unroll") for (int i_ = 0; i_ < 2; ++i_) *(u32x4*)(sB_ + (sr + i_ * 64) * PITCH + scv * 8) = rb[S][i_]; } while (0)
; template <class Epi>
; DI void gemm_tile(char* smem, const bf16_t* __restrict__ A0, int lda0, int ksplit, const bf16_t* __restrict__ A1, int lda1,
;                   const bf16_t* __restrict__ Bt, int K, int row0, int col0, const Epi& epi, int tid) {
;   constexpr int BK = 32, PITCH = 40, BUF = (256 + 128) * PITCH;
;   bf16_t* sbase = (bf16_t*)smem;
;   const int lane = tid & 63, wid = tid >> 6, wr = wid >> 1, wc = wid & 1, fr = lane & 15, fq = lane >> 4;
;   f32x4 acc[8][4];
; #pragma unroll
;   for (int m = 0; m < 8; ++m)
; #pragma unroll
;     for (int n = 0; n < 4; ++n) acc[m][n] = (f32x4){0.f, 0.f, 0.f, 0.f};
;   u32x4 ra[2][4], rb[2][2];
;   const int nk = K / BK;
;   const int sr = tid >> 2, scv = tid & 3;
;     ...
;   __syncthreads();
;   {
;     const int last = nk - 1;
;     GLOAD(0, 0);
;     __builtin_amdgcn_sched_barrier(0);
;     GLOAD(1, 1);
;     __builtin_amdgcn_sched_barrier(0);
;     LWRITE(0, 0);
;     __builtin_amdgcn_sched_barrier(0);
;     GLOAD(0, (2 < last ? 2 : last));
;     __builtin_amdgcn_sched_barrier(0);
;     __syncthreads();
;     for (int kt = 0; kt < nk; kt += 2) {
;       LWRITE(1, 1);
;       __builtin_amdgcn_sched_barrier(0);
;       GLOAD(1, (kt + 3 < last ? kt + 3 : last));
;       __builtin_amdgcn_sched_barrier(0);
;       COMPUTE(0);
.LBB0_573:
.LBB0_574:
	s_cmpk_gt_u32 s96, 0x1ff
	s_cbranch_scc1 .LBB0_577
	s_waitcnt lgkmcnt(0)
	s_load_dwordx16 s[56:71], s[74:75], 0x40
	v_and_b32_e32 v0, 3, v136
	v_lshlrev_b32_e32 v0, 4, v0
	v_mov_b32_e32 v1, 0
	v_ashrrev_i32_e32 v138, 2, v137
	v_lshl_add_u64 v[124:125], s[6:7], 0, v[0:1]
	v_lshl_add_u64 v[126:127], s[0:1], 0, v[0:1]
	v_bfe_u32 v1, v136, 4, 2
	s_movk_i32 s0, 0x40
	v_and_b32_e32 v4, 0x4f, v137
	v_and_b32_e32 v139, 0xffffff8f, v137
	v_or_b32_e32 v7, 0x70, v137
	s_ashr_i32 s8, s12, 3
	s_lshr_b32 s9, s96, 3
	s_lshl_b32 s10, s96, 1
	v_add_u32_e32 v0, 0, v0
	v_mul_lo_u32 v2, v138, s0
	v_and_b32_e32 v3, 64, v137
	v_lshl_add_u32 v5, v1, 4, 0
	v_mul_u32_u24_e32 v4, 0x40, v4
	v_mul_lo_u32 v6, v139, s0
	v_mul_lo_u32 v7, v7, s0
	s_and_b32 s10, s10, 14
	s_waitcnt vmcnt(6)
	v_lshl_or_b32 v140, v1, 2, v3
	s_lshl_b32 s11, s9, 8
	s_lshl_b32 s15, s8, 8
	s_lshl_b32 s16, s9, 4
	s_lshl_b32 s17, s8, 4
	s_mov_b64 s[0:1], 0x18000
	s_mov_b32 s18, 0x18000
	s_mov_b64 s[6:7], 0x2000
	s_movk_i32 s19, 0x2000
	v_add_u32_e32 v141, v0, v2
	v_add_u32_e32 v142, v5, v4
	v_add_u32_e32 v143, v5, v6
	s_waitcnt vmcnt(5)
	v_add_u32_e32 v144, v5, v7
	v_mbcnt_lo_u32_b32 v2, -1, 0
	v_mbcnt_hi_u32_b32 v2, -1, v2
	v_bfe_u32 v4, v2, 3, 1
	v_bfe_u32 v2, v2, 5, 1
	v_mul_u32_u24_e32 v4, 48, v4
	v_mul_u32_u24_e32 v2, 48, v2
	v_xor_b32_e32 v141, v141, v2
	v_xor_b32_e32 v142, v142, v4
	v_xor_b32_e32 v143, v143, v4
	v_xor_b32_e32 v144, v144, v4
	s_waitcnt lgkmcnt(0)
	s_mov_b64 s[58:59], s[62:63]
.LBB0_576:
	s_ashr_i32 s20, s9, 31
	s_lshr_b32 s20, s20, 27
	s_add_i32 s20, s9, s20
	s_ashr_i32 s20, s20, 5
	s_add_i32 s21, s20, s10
	s_lshl_b32 s21, s21, 11
	s_and_b32 s22, s11, 0x700
	s_or_b32 s22, s21, s22
	v_add_u32_e32 v0, s22, v138
	s_lshl_b32 s20, s20, 9
	v_ashrrev_i32_e32 v1, 31, v0
	s_sub_i32 s20, s16, s20
	v_lshlrev_b64 v[0:1], 9, v[0:1]
	s_and_b32 s23, s20, 0xffffff80
	v_lshl_add_u64 v[24:25], v[124:125], 0, v[0:1]
	s_mov_b32 s20, 0x8000
	v_add_co_u32_e32 v4, vcc, s20, v24
	s_mov_b32 s20, 0x10000
	s_nop 0
	v_addc_co_u32_e32 v5, vcc, 0, v25, vcc
	v_add_co_u32_e32 v8, vcc, s20, v24
	v_add_u32_e32 v16, s23, v138
	s_nop 0
	v_addc_co_u32_e32 v9, vcc, 0, v25, vcc
	v_ashrrev_i32_e32 v17, 31, v16
	v_add_co_u32_e32 v12, vcc, s18, v24
	v_lshlrev_b64 v[16:17], 7, v[16:17]
	s_nop 0
	v_addc_co_u32_e32 v13, vcc, 0, v25, vcc
	v_lshl_add_u64 v[40:41], v[126:127], 0, v[16:17]
	v_add_co_u32_e32 v20, vcc, s19, v40
	s_nop 1
	v_addc_co_u32_e32 v21, vcc, 0, v41, vcc
	s_barrier
	global_load_dwordx4 v[0:3], v[24:25], off
	s_nop 0
	global_load_dwordx4 v[4:7], v[4:5], off
	s_nop 0
	global_load_dwordx4 v[8:11], v[8:9], off
	s_nop 0
	global_load_dwordx4 v[12:15], v[12:13], off
	s_nop 0
	global_load_dwordx4 v[16:19], v[40:41], off
	s_nop 0
	global_load_dwordx4 v[20:23], v[20:21], off
	s_mov_b64 s[20:21], 0x8000
	v_lshl_add_u64 v[28:29], v[24:25], 0, s[20:21]
	s_mov_b64 s[20:21], 0x10000
	v_lshl_add_u64 v[32:33], v[24:25], 0, s[20:21]
	v_lshl_add_u64 v[36:37], v[24:25], 0, s[0:1]
	v_lshl_add_u64 v[44:45], v[40:41], 0, s[6:7]
	global_load_dwordx4 v[24:27], v[24:25], off offset:64
	s_nop 0
	global_load_dwordx4 v[28:31], v[28:29], off offset:64
	s_nop 0
	global_load_dwordx4 v[32:35], v[32:33], off offset:64
	s_nop 0
	global_load_dwordx4 v[36:39], v[36:37], off offset:64
	s_nop 0
	global_load_dwordx4 v[40:43], v[40:41], off offset:64
	s_nop 0
	global_load_dwordx4 v[44:47], v[44:45], off offset:64
	s_waitcnt vmcnt(11)
	ds_write_b128 v141, v[0:3]
	s_waitcnt vmcnt(10)
	ds_write_b128 v141, v[4:7] offset:4096
	s_waitcnt vmcnt(9)
	ds_write_b128 v141, v[8:11] offset:8192
	s_waitcnt vmcnt(8)
	ds_write_b128 v141, v[12:15] offset:12288
	s_waitcnt vmcnt(7)
	ds_write_b128 v141, v[16:19] offset:16384
	s_waitcnt vmcnt(6)
	ds_write_b128 v141, v[20:23] offset:20480
	s_waitcnt lgkmcnt(0)
	s_barrier
	s_waitcnt vmcnt(5)
	ds_write_b128 v141, v[24:27] offset:24576
	s_waitcnt vmcnt(4)
	ds_write_b128 v141, v[28:31] offset:28672
	s_waitcnt vmcnt(3)
	ds_write_b128 v141, v[32:35] offset:32768
	s_waitcnt vmcnt(2)
	ds_write_b128 v141, v[36:39] offset:36864
	s_waitcnt vmcnt(1)
	ds_write_b128 v141, v[40:43] offset:40960
	s_waitcnt vmcnt(0)
	ds_write_b128 v141, v[44:47] offset:45056
	ds_read_b128 v[0:3], v142 offset:16384
	ds_read_b128 v[4:7], v142 offset:17408
	ds_read_b128 v[8:11], v142 offset:18432
	ds_read_b128 v[12:15], v142 offset:19456
	ds_read_b128 v[16:19], v143
	ds_read_b128 v[20:23], v143 offset:1024
	ds_read_b128 v[48:51], v143 offset:2048
	ds_read_b128 v[52:55], v143 offset:3072
	ds_read_b128 v[56:59], v143 offset:4096
	ds_read_b128 v[60:63], v143 offset:5120
	ds_read_b128 v[64:67], v143 offset:6144
	ds_read_b128 v[68:71], v144
	s_setprio 1
	s_waitcnt lgkmcnt(7)
	v_mfma_f32_16x16x32_bf16 v[72:75], v[0:3], v[16:19], 0
	v_mfma_f32_16x16x32_bf16 v[76:79], v[4:7], v[16:19], 0
	v_mfma_f32_16x16x32_bf16 v[80:83], v[8:11], v[16:19], 0
	v_mfma_f32_16x16x32_bf16 v[16:19], v[12:15], v[16:19], 0
	s_waitcnt lgkmcnt(6)
	v_mfma_f32_16x16x32_bf16 v[84:87], v[0:3], v[20:23], 0
	v_mfma_f32_16x16x32_bf16 v[88:91], v[4:7], v[20:23], 0
	v_mfma_f32_16x16x32_bf16 v[92:95], v[8:11], v[20:23], 0
	v_mfma_f32_16x16x32_bf16 v[20:23], v[12:15], v[20:23], 0
	s_waitcnt lgkmcnt(5)
	v_mfma_f32_16x16x32_bf16 v[128:131], v[0:3], v[48:51], 0
	v_mfma_f32_16x16x32_bf16 v[132:135], v[4:7], v[48:51], 0
	v_mfma_f32_16x16x32_bf16 v[146:149], v[8:11], v[48:51], 0
	v_mfma_f32_16x16x32_bf16 v[48:51], v[12:15], v[48:51], 0
	s_waitcnt lgkmcnt(4)
	v_mfma_f32_16x16x32_bf16 v[150:153], v[0:3], v[52:55], 0
	v_mfma_f32_16x16x32_bf16 v[154:157], v[4:7], v[52:55], 0
	v_mfma_f32_16x16x32_bf16 v[158:161], v[8:11], v[52:55], 0
	v_mfma_f32_16x16x32_bf16 v[52:55], v[12:15], v[52:55], 0
	s_waitcnt lgkmcnt(3)
	v_mfma_f32_16x16x32_bf16 v[162:165], v[0:3], v[56:59], 0
	v_mfma_f32_16x16x32_bf16 v[166:169], v[4:7], v[56:59], 0
	v_mfma_f32_16x16x32_bf16 v[170:173], v[8:11], v[56:59], 0
	v_mfma_f32_16x16x32_bf16 v[174:177], v[12:15], v[56:59], 0
	s_waitcnt lgkmcnt(2)
	v_mfma_f32_16x16x32_bf16 v[178:181], v[0:3], v[60:63], 0
	v_mfma_f32_16x16x32_bf16 v[182:185], v[4:7], v[60:63], 0
	v_mfma_f32_16x16x32_bf16 v[186:189], v[8:11], v[60:63], 0
	v_mfma_f32_16x16x32_bf16 v[190:193], v[12:15], v[60:63], 0
	s_waitcnt lgkmcnt(1)
	v_mfma_f32_16x16x32_bf16 v[196:199], v[0:3], v[64:67], 0
	v_mfma_f32_16x16x32_bf16 v[200:203], v[4:7], v[64:67], 0
	v_mfma_f32_16x16x32_bf16 v[204:207], v[8:11], v[64:67], 0
	v_mfma_f32_16x16x32_bf16 v[208:211], v[12:15], v[64:67], 0
	s_waitcnt lgkmcnt(0)
	v_mfma_f32_16x16x32_bf16 v[0:3], v[0:3], v[68:71], 0
	v_mfma_f32_16x16x32_bf16 v[4:7], v[4:7], v[68:71], 0
	v_mfma_f32_16x16x32_bf16 v[212:215], v[8:11], v[68:71], 0
	v_mfma_f32_16x16x32_bf16 v[216:219], v[12:15], v[68:71], 0
	s_setprio 0
	s_barrier
; #define LWRITE(S, buf) do { bf16_t* sA_ = sbase + (buf) * BUF; bf16_t* sB_ = sA_ + 256 * PITCH; \
;     _Pragma("unroll") for (int i_ = 0; i_ < 4; ++i_) *(u32x4*)(sA_ + (sr + i_ * 64) * PITCH + scv * 8) = ra[S][i_]; \
;     _Pragma("unroll") for (int i_ = 0; i_ < 2; ++i_) *(u32x4*)(sB_ + (sr + i_ * 64) * PITCH + scv * 8) = rb[S][i_]; } while (0)
; template <class Epi>
; DI void gemm_tile(char* smem, const bf16_t* __restrict__ A0, int lda0, int ksplit, const bf16_t* __restrict__ A1, int lda1,
;                   const bf16_t* __restrict__ Bt, int K, int row0, int col0, const Epi& epi, int tid) {
;     ...
;   __syncthreads();
;   {
;     const int last = nk - 1;
;     GLOAD(0, 0);
;     __builtin_amdgcn_sched_barrier(0);
;     GLOAD(1, 1);
;     __builtin_amdgcn_sched_barrier(0);
;     LWRITE(0, 0);
;     __builtin_amdgcn_sched_barrier(0);
;     GLOAD(0, (2 < last ? 2 : last));
;     __builtin_amdgcn_sched_barrier(0);
;     __syncthreads();
;     for (int kt = 0; kt < nk; kt += 2) {
;       LWRITE(1, 1);
;       __builtin_amdgcn_sched_barrier(0);
;       GLOAD(1, (kt + 3 < last ? kt + 3 : last));
;       __builtin_amdgcn_sched_barrier(0);
;       COMPUTE(0);
;       __syncthreads();
;       LWRITE(0, 0);
;       __builtin_amdgcn_sched_barrier(0);
;       GLOAD(0, (kt + 4 < last ? kt + 4 : last));
;       __builtin_amdgcn_sched_barrier(0);
;       COMPUTE(1);
;       __syncthreads();
;     }
	ds_write_b128 v141, v[24:27]
	ds_write_b128 v141, v[28:31] offset:4096
	ds_write_b128 v141, v[32:35] offset:8192
	ds_write_b128 v141, v[36:39] offset:12288
	ds_write_b128 v141, v[40:43] offset:16384
	ds_write_b128 v141, v[44:47] offset:20480
	ds_read_b128 v[8:11], v142 offset:40960
	ds_read_b128 v[220:223], v142 offset:41984
	ds_read_b128 v[224:227], v142 offset:43008
	ds_read_b128 v[228:231], v142 offset:44032
	ds_read_b128 v[12:15], v143 offset:26624
	ds_read_b128 v[24:27], v143 offset:27648
	ds_read_b128 v[28:31], v143 offset:28672
	ds_read_b128 v[32:35], v143 offset:29696
	ds_read_b128 v[36:39], v143 offset:24576
	ds_read_b128 v[232:235], v143 offset:30720
	ds_read_b128 v[40:43], v143 offset:25600
	ds_read_b128 v[236:239], v144 offset:24576
	s_setprio 1
	s_waitcnt lgkmcnt(3)
	v_mfma_f32_16x16x32_bf16 v[240:243], v[8:11], v[36:39], v[72:75]
	v_mfma_f32_16x16x32_bf16 v[120:123], v[220:223], v[36:39], v[76:79]
	v_mfma_f32_16x16x32_bf16 v[116:119], v[224:227], v[36:39], v[80:83]
	v_mfma_f32_16x16x32_bf16 v[112:115], v[228:231], v[36:39], v[16:19]
	s_waitcnt lgkmcnt(1)
	v_mfma_f32_16x16x32_bf16 v[108:111], v[8:11], v[40:43], v[84:87]
	v_mfma_f32_16x16x32_bf16 v[104:107], v[220:223], v[40:43], v[88:91]
	v_mfma_f32_16x16x32_bf16 v[100:103], v[224:227], v[40:43], v[92:95]
	v_mfma_f32_16x16x32_bf16 v[96:99], v[228:231], v[40:43], v[20:23]
	v_mfma_f32_16x16x32_bf16 v[92:95], v[8:11], v[12:15], v[128:131]
	v_mfma_f32_16x16x32_bf16 v[88:91], v[220:223], v[12:15], v[132:135]
	v_mfma_f32_16x16x32_bf16 v[84:87], v[224:227], v[12:15], v[146:149]
	v_mfma_f32_16x16x32_bf16 v[80:83], v[228:231], v[12:15], v[48:51]
	v_mfma_f32_16x16x32_bf16 v[76:79], v[8:11], v[24:27], v[150:153]
	v_mfma_f32_16x16x32_bf16 v[72:75], v[220:223], v[24:27], v[154:157]
	v_mfma_f32_16x16x32_bf16 v[68:71], v[224:227], v[24:27], v[158:161]
	v_mfma_f32_16x16x32_bf16 v[64:67], v[228:231], v[24:27], v[52:55]
	v_mfma_f32_16x16x32_bf16 v[60:63], v[8:11], v[28:31], v[162:165]
	v_mfma_f32_16x16x32_bf16 v[56:59], v[220:223], v[28:31], v[166:169]
	v_mfma_f32_16x16x32_bf16 v[52:55], v[224:227], v[28:31], v[170:173]
	v_mfma_f32_16x16x32_bf16 v[48:51], v[228:231], v[28:31], v[174:177]
	v_mfma_f32_16x16x32_bf16 v[44:47], v[8:11], v[32:35], v[178:181]
	v_mfma_f32_16x16x32_bf16 v[40:43], v[220:223], v[32:35], v[182:185]
	v_mfma_f32_16x16x32_bf16 v[36:39], v[224:227], v[32:35], v[186:189]
	v_mfma_f32_16x16x32_bf16 v[32:35], v[228:231], v[32:35], v[190:193]
	v_mfma_f32_16x16x32_bf16 v[28:31], v[8:11], v[232:235], v[196:199]
	v_mfma_f32_16x16x32_bf16 v[24:27], v[220:223], v[232:235], v[200:203]
	v_mfma_f32_16x16x32_bf16 v[20:23], v[224:227], v[232:235], v[204:207]
	v_mfma_f32_16x16x32_bf16 v[16:19], v[228:231], v[232:235], v[208:211]
	s_waitcnt lgkmcnt(0)
	v_mfma_f32_16x16x32_bf16 v[12:15], v[8:11], v[236:239], v[0:3]
	v_mfma_f32_16x16x32_bf16 v[8:11], v[220:223], v[236:239], v[4:7]
	v_mfma_f32_16x16x32_bf16 v[4:7], v[224:227], v[236:239], v[212:215]
	v_mfma_f32_16x16x32_bf16 v[0:3], v[228:231], v[236:239], v[216:219]
	s_setprio 0
	v_or_b32_e32 v130, s23, v140
	v_ashrrev_i32_e32 v131, 31, v130
	v_lshl_add_u64 v[128:129], v[130:131], 2, s[58:59]
	s_barrier
	global_load_dwordx4 v[146:149], v[128:129], off
	v_add_u32_e32 v132, s22, v139
	v_ashrrev_i32_e32 v133, 31, v132
	v_lshlrev_b64 v[134:135], 10, v[132:133]
	v_lshl_add_u64 v[134:135], s[4:5], 0, v[134:135]
	v_lshlrev_b64 v[130:131], 1, v[130:131]
	v_lshl_add_u64 v[134:135], v[134:135], 0, v[130:131]
	s_add_i32 s9, s9, s8
	s_add_i32 s11, s11, s15
	s_add_i32 s16, s16, s17
	s_cmp_gt_i32 s9, 63
	s_waitcnt vmcnt(0)
	v_add_f32_e32 v133, v240, v146
	v_add_f32_e32 v146, v242, v148
	v_mul_f32_e32 v146, 0xbfb8aa3b, v146
	v_exp_f32_e32 v146, v146
	v_add_f32_e32 v145, v241, v147
	v_mul_f32_e32 v133, 0xbfb8aa3b, v133
	v_mul_f32_e32 v145, 0xbfb8aa3b, v145
	v_add_f32_e32 v146, 1.0, v146
	v_rcp_f32_e32 v147, v146
	v_add_f32_e32 v146, v243, v149
	v_mul_f32_e32 v146, 0xbfb8aa3b, v146
	v_exp_f32_e32 v133, v133
	v_exp_f32_e32 v145, v145
	v_exp_f32_e32 v146, v146
	v_add_f32_e32 v133, 1.0, v133
	v_add_f32_e32 v145, 1.0, v145
	v_add_f32_e32 v146, 1.0, v146
	v_rcp_f32_e32 v133, v133
	v_rcp_f32_e32 v145, v145
	v_rcp_f32_e32 v148, v146
	v_cvt_pk_bf16_f32 v146, v133, v145
	v_cvt_pk_bf16_f32 v147, v147, v148
	global_store_dwordx2 v[134:135], v[146:147], off
	global_load_dwordx4 v[146:149], v[128:129], off offset:64
	s_waitcnt vmcnt(0)
	v_add_f32_e32 v120, v120, v146
	v_add_f32_e32 v121, v121, v147
	v_add_f32_e32 v122, v122, v148
	v_add_f32_e32 v123, v123, v149
	v_mul_f32_e32 v120, 0xbfb8aa3b, v120
	v_mul_f32_e32 v121, 0xbfb8aa3b, v121
	v_mul_f32_e32 v122, 0xbfb8aa3b, v122
	v_mul_f32_e32 v123, 0xbfb8aa3b, v123
	v_exp_f32_e32 v120, v120
	v_exp_f32_e32 v121, v121
	v_exp_f32_e32 v122, v122
	v_exp_f32_e32 v123, v123
	v_add_f32_e32 v120, 1.0, v120
	v_add_f32_e32 v121, 1.0, v121
	v_add_f32_e32 v122, 1.0, v122
	v_add_f32_e32 v123, 1.0, v123
	v_rcp_f32_e32 v120, v120
	v_rcp_f32_e32 v121, v121
	v_rcp_f32_e32 v122, v122
	v_rcp_f32_e32 v123, v123
	v_cvt_pk_bf16_f32 v120, v120, v121
	v_cvt_pk_bf16_f32 v121, v122, v123
	global_store_dwordx2 v[134:135], v[120:121], off offset:32
	global_load_dwordx4 v[120:123], v[128:129], off offset:128
	s_waitcnt vmcnt(0)
	v_add_f32_e32 v116, v116, v120
	v_add_f32_e32 v117, v117, v121
	v_add_f32_e32 v118, v118, v122
	v_add_f32_e32 v119, v119, v123
	v_mul_f32_e32 v116, 0xbfb8aa3b, v116
	v_mul_f32_e32 v117, 0xbfb8aa3b, v117
	v_mul_f32_e32 v118, 0xbfb8aa3b, v118
	v_mul_f32_e32 v119, 0xbfb8aa3b, v119
	v_exp_f32_e32 v116, v116
	v_exp_f32_e32 v117, v117
	v_exp_f32_e32 v118, v118
	v_exp_f32_e32 v119, v119
	v_add_f32_e32 v116, 1.0, v116
	v_add_f32_e32 v117, 1.0, v117
	v_add_f32_e32 v118, 1.0, v118
	v_add_f32_e32 v119, 1.0, v119
	v_rcp_f32_e32 v116, v116
	v_rcp_f32_e32 v117, v117
	v_rcp_f32_e32 v118, v118
	v_rcp_f32_e32 v119, v119
	v_cvt_pk_bf16_f32 v116, v116, v117
	v_cvt_pk_bf16_f32 v117, v118, v119
	global_store_dwordx2 v[134:135], v[116:117], off offset:64
	global_load_dwordx4 v[116:119], v[128:129], off offset:192
	s_waitcnt vmcnt(0)
; DI unsigned pack2(float lo, float hi) { const f32x2c v = {lo, hi}; return __builtin_bit_cast(unsigned, __builtin_convertvector(v, bf16x2c)); }
; DI void st_bf16x4(bf16_t* o, f32x4 v) { u32x2 q; q.x = pack2(v[0], v[1]); q.y = pack2(v[2], v[3]); *(u32x2*)o = q; }
;   DI void operator()(int row, int col, f32x4 v) const {
;     if (col < n0) st_bf16x4(o0 + (size_t)row * ld0 + col, v);
;     else { const int c = col - n0; if (c < n1) st_bf16x4(o1 + (size_t)row * ld1 + c, v); }
;   }
	v_add_f32_e32 v112, v112, v116
	v_add_f32_e32 v113, v113, v117
	v_add_f32_e32 v114, v114, v118
	v_add_f32_e32 v115, v115, v119
	v_mul_f32_e32 v112, 0xbfb8aa3b, v112
	v_mul_f32_e32 v113, 0xbfb8aa3b, v113
	v_mul_f32_e32 v114, 0xbfb8aa3b, v114
	v_mul_f32_e32 v115, 0xbfb8aa3b, v115
	v_exp_f32_e32 v112, v112
	v_exp_f32_e32 v113, v113
	v_exp_f32_e32 v114, v114
	v_exp_f32_e32 v115, v115
	v_add_f32_e32 v112, 1.0, v112
	v_add_f32_e32 v113, 1.0, v113
	v_add_f32_e32 v114, 1.0, v114
	v_add_f32_e32 v115, 1.0, v115
	v_rcp_f32_e32 v112, v112
	v_rcp_f32_e32 v113, v113
	v_rcp_f32_e32 v114, v114
	v_rcp_f32_e32 v115, v115
	v_cvt_pk_bf16_f32 v112, v112, v113
	v_cvt_pk_bf16_f32 v113, v114, v115
	global_store_dwordx2 v[134:135], v[112:113], off offset:96
	v_or_b32_e32 v112, 16, v132
	v_ashrrev_i32_e32 v113, 31, v112
	v_lshlrev_b64 v[116:117], 10, v[112:113]
	global_load_dwordx4 v[112:115], v[128:129], off
	s_waitcnt vmcnt(0)
	v_add_f32_e32 v108, v108, v112
	v_mul_f32_e32 v108, 0xbfb8aa3b, v108
	v_exp_f32_e32 v108, v108
	s_nop 0
	v_add_f32_e32 v108, 1.0, v108
	v_rcp_f32_e32 v112, v108
	v_add_f32_e32 v108, v109, v113
	v_mul_f32_e32 v108, 0xbfb8aa3b, v108
	v_exp_f32_e32 v108, v108
	s_nop 0
	v_add_f32_e32 v108, 1.0, v108
	v_rcp_f32_e32 v113, v108
	v_add_f32_e32 v108, v110, v114
	v_mul_f32_e32 v108, 0xbfb8aa3b, v108
	v_exp_f32_e32 v108, v108
	v_cvt_pk_bf16_f32 v110, v112, v113
	v_add_f32_e32 v108, 1.0, v108
	v_rcp_f32_e32 v114, v108
	v_add_f32_e32 v108, v111, v115
	v_mul_f32_e32 v108, 0xbfb8aa3b, v108
	v_exp_f32_e32 v108, v108
	s_nop 0
	v_add_f32_e32 v108, 1.0, v108
	v_rcp_f32_e32 v111, v108
	v_lshl_add_u64 v[108:109], s[4:5], 0, v[116:117]
	v_lshl_add_u64 v[108:109], v[108:109], 0, v[130:131]
	v_cvt_pk_bf16_f32 v111, v114, v111
	global_store_dwordx2 v[108:109], v[110:111], off
	global_load_dwordx4 v[110:113], v[128:129], off offset:64
	s_waitcnt vmcnt(0)
	v_add_f32_e32 v104, v104, v110
	v_add_f32_e32 v105, v105, v111
	v_add_f32_e32 v106, v106, v112
	v_add_f32_e32 v107, v107, v113
	v_mul_f32_e32 v104, 0xbfb8aa3b, v104
	v_mul_f32_e32 v105, 0xbfb8aa3b, v105
	v_mul_f32_e32 v106, 0xbfb8aa3b, v106
	v_mul_f32_e32 v107, 0xbfb8aa3b, v107
	v_exp_f32_e32 v104, v104
	v_exp_f32_e32 v105, v105
	v_exp_f32_e32 v106, v106
	v_exp_f32_e32 v107, v107
	v_add_f32_e32 v104, 1.0, v104
	v_add_f32_e32 v105, 1.0, v105
	v_add_f32_e32 v106, 1.0, v106
	v_add_f32_e32 v107, 1.0, v107
	v_rcp_f32_e32 v104, v104
	v_rcp_f32_e32 v105, v105
	v_rcp_f32_e32 v106, v106
	v_rcp_f32_e32 v107, v107
	v_cvt_pk_bf16_f32 v104, v104, v105
	v_cvt_pk_bf16_f32 v105, v106, v107
	global_store_dwordx2 v[108:109], v[104:105], off offset:32
	global_load_dwordx4 v[104:107], v[128:129], off offset:128
	s_waitcnt vmcnt(0)
	v_add_f32_e32 v100, v100, v104
	v_add_f32_e32 v101, v101, v105
	v_add_f32_e32 v102, v102, v106
	v_add_f32_e32 v103, v103, v107
	v_mul_f32_e32 v100, 0xbfb8aa3b, v100
	v_mul_f32_e32 v101, 0xbfb8aa3b, v101
	v_mul_f32_e32 v102, 0xbfb8aa3b, v102
	v_mul_f32_e32 v103, 0xbfb8aa3b, v103
	v_exp_f32_e32 v100, v100
	v_exp_f32_e32 v101, v101
	v_exp_f32_e32 v102, v102
	v_exp_f32_e32 v103, v103
	v_add_f32_e32 v100, 1.0, v100
	v_add_f32_e32 v101, 1.0, v101
	v_add_f32_e32 v102, 1.0, v102
	v_add_f32_e32 v103, 1.0, v103
	v_rcp_f32_e32 v100, v100
	v_rcp_f32_e32 v101, v101
	v_rcp_f32_e32 v102, v102
	v_rcp_f32_e32 v103, v103
	v_cvt_pk_bf16_f32 v100, v100, v101
	v_cvt_pk_bf16_f32 v101, v102, v103
	global_store_dwordx2 v[108:109], v[100:101], off offset:64
	global_load_dwordx4 v[100:103], v[128:129], off offset:192
	s_waitcnt vmcnt(0)
	v_add_f32_e32 v96, v96, v100
	v_add_f32_e32 v97, v97, v101
	v_add_f32_e32 v98, v98, v102
	v_add_f32_e32 v99, v99, v103
	v_mul_f32_e32 v96, 0xbfb8aa3b, v96
	v_mul_f32_e32 v97, 0xbfb8aa3b, v97
	v_mul_f32_e32 v98, 0xbfb8aa3b, v98
	v_mul_f32_e32 v99, 0xbfb8aa3b, v99
	v_exp_f32_e32 v96, v96
	v_exp_f32_e32 v97, v97
	v_exp_f32_e32 v98, v98
	v_exp_f32_e32 v99, v99
	v_add_f32_e32 v96, 1.0, v96
	v_add_f32_e32 v97, 1.0, v97
	v_add_f32_e32 v98, 1.0, v98
	v_add_f32_e32 v99, 1.0, v99
	v_rcp_f32_e32 v96, v96
	v_rcp_f32_e32 v97, v97
	v_rcp_f32_e32 v98, v98
	v_rcp_f32_e32 v99, v99
	v_cvt_pk_bf16_f32 v96, v96, v97
	v_cvt_pk_bf16_f32 v97, v98, v99
	global_store_dwordx2 v[108:109], v[96:97], off offset:96
	v_or_b32_e32 v96, 32, v132
	v_ashrrev_i32_e32 v97, 31, v96
	v_lshlrev_b64 v[100:101], 10, v[96:97]
	global_load_dwordx4 v[96:99], v[128:129], off
	s_waitcnt vmcnt(0)
	v_add_f32_e32 v92, v92, v96
	v_mul_f32_e32 v92, 0xbfb8aa3b, v92
	v_exp_f32_e32 v92, v92
	s_nop 0
	v_add_f32_e32 v92, 1.0, v92
	v_rcp_f32_e32 v96, v92
	v_add_f32_e32 v92, v93, v97
	v_mul_f32_e32 v92, 0xbfb8aa3b, v92
	v_exp_f32_e32 v92, v92
	s_nop 0
	v_add_f32_e32 v92, 1.0, v92
	v_rcp_f32_e32 v97, v92
	v_add_f32_e32 v92, v94, v98
	v_mul_f32_e32 v92, 0xbfb8aa3b, v92
	v_exp_f32_e32 v92, v92
	v_cvt_pk_bf16_f32 v94, v96, v97
	v_add_f32_e32 v92, 1.0, v92
	v_rcp_f32_e32 v98, v92
	v_add_f32_e32 v92, v95, v99
	v_mul_f32_e32 v92, 0xbfb8aa3b, v92
	v_exp_f32_e32 v92, v92
	s_nop 0
	v_add_f32_e32 v92, 1.0, v92
	v_rcp_f32_e32 v95, v92
	v_lshl_add_u64 v[92:93], s[4:5], 0, v[100:101]
	v_lshl_add_u64 v[92:93], v[92:93], 0, v[130:131]
	v_cvt_pk_bf16_f32 v95, v98, v95
	global_store_dwordx2 v[92:93], v[94:95], off
	global_load_dwordx4 v[94:97], v[128:129], off offset:64
	s_waitcnt vmcnt(0)
	v_add_f32_e32 v88, v88, v94
	v_add_f32_e32 v89, v89, v95
	v_add_f32_e32 v90, v90, v96
	v_add_f32_e32 v91, v91, v97
	v_mul_f32_e32 v88, 0xbfb8aa3b, v88
	v_mul_f32_e32 v89, 0xbfb8aa3b, v89
	v_mul_f32_e32 v90, 0xbfb8aa3b, v90
	v_mul_f32_e32 v91, 0xbfb8aa3b, v91
	v_exp_f32_e32 v88, v88
	v_exp_f32_e32 v89, v89
	v_exp_f32_e32 v90, v90
	v_exp_f32_e32 v91, v91
	v_add_f32_e32 v88, 1.0, v88
	v_add_f32_e32 v89, 1.0, v89
	v_add_f32_e32 v90, 1.0, v90
	v_add_f32_e32 v91, 1.0, v91
	v_rcp_f32_e32 v88, v88
	v_rcp_f32_e32 v89, v89
	v_rcp_f32_e32 v90, v90
	v_rcp_f32_e32 v91, v91
	v_cvt_pk_bf16_f32 v88, v88, v89
	v_cvt_pk_bf16_f32 v89, v90, v91
	global_store_dwordx2 v[92:93], v[88:89], off offset:32
	global_load_dwordx4 v[88:91], v[128:129], off offset:128
	s_waitcnt vmcnt(0)
; DI unsigned pack2(float lo, float hi) { const f32x2c v = {lo, hi}; return __builtin_bit_cast(unsigned, __builtin_convertvector(v, bf16x2c)); }
; DI void st_bf16x4(bf16_t* o, f32x4 v) { u32x2 q; q.x = pack2(v[0], v[1]); q.y = pack2(v[2], v[3]); *(u32x2*)o = q; }
;   DI void operator()(int row, int col, f32x4 v) const {
;     if (col < n0) st_bf16x4(o0 + (size_t)row * ld0 + col, v);
;     else { const int c = col - n0; if (c < n1) st_bf16x4(o1 + (size_t)row * ld1 + c, v); }
;   }
	v_add_f32_e32 v84, v84, v88
	v_add_f32_e32 v85, v85, v89
	v_add_f32_e32 v86, v86, v90
	v_add_f32_e32 v87, v87, v91
	v_mul_f32_e32 v84, 0xbfb8aa3b, v84
	v_mul_f32_e32 v85, 0xbfb8aa3b, v85
	v_mul_f32_e32 v86, 0xbfb8aa3b, v86
	v_mul_f32_e32 v87, 0xbfb8aa3b, v87
	v_exp_f32_e32 v84, v84
	v_exp_f32_e32 v85, v85
	v_exp_f32_e32 v86, v86
	v_exp_f32_e32 v87, v87
	v_add_f32_e32 v84, 1.0, v84
	v_add_f32_e32 v85, 1.0, v85
	v_add_f32_e32 v86, 1.0, v86
	v_add_f32_e32 v87, 1.0, v87
	v_rcp_f32_e32 v84, v84
	v_rcp_f32_e32 v85, v85
	v_rcp_f32_e32 v86, v86
	v_rcp_f32_e32 v87, v87
	v_cvt_pk_bf16_f32 v84, v84, v85
	v_cvt_pk_bf16_f32 v85, v86, v87
	global_store_dwordx2 v[92:93], v[84:85], off offset:64
	global_load_dwordx4 v[84:87], v[128:129], off offset:192
	s_waitcnt vmcnt(0)
	v_add_f32_e32 v80, v80, v84
	v_add_f32_e32 v81, v81, v85
	v_add_f32_e32 v82, v82, v86
	v_add_f32_e32 v83, v83, v87
	v_mul_f32_e32 v80, 0xbfb8aa3b, v80
	v_mul_f32_e32 v81, 0xbfb8aa3b, v81
	v_mul_f32_e32 v82, 0xbfb8aa3b, v82
	v_mul_f32_e32 v83, 0xbfb8aa3b, v83
	v_exp_f32_e32 v80, v80
	v_exp_f32_e32 v81, v81
	v_exp_f32_e32 v82, v82
	v_exp_f32_e32 v83, v83
	v_add_f32_e32 v80, 1.0, v80
	v_add_f32_e32 v81, 1.0, v81
	v_add_f32_e32 v82, 1.0, v82
	v_add_f32_e32 v83, 1.0, v83
	v_rcp_f32_e32 v80, v80
	v_rcp_f32_e32 v81, v81
	v_rcp_f32_e32 v82, v82
	v_rcp_f32_e32 v83, v83
	v_cvt_pk_bf16_f32 v80, v80, v81
	v_cvt_pk_bf16_f32 v81, v82, v83
	global_store_dwordx2 v[92:93], v[80:81], off offset:96
	v_or_b32_e32 v80, 48, v132
	v_ashrrev_i32_e32 v81, 31, v80
	v_lshlrev_b64 v[84:85], 10, v[80:81]
	global_load_dwordx4 v[80:83], v[128:129], off
	s_waitcnt vmcnt(0)
	v_add_f32_e32 v76, v76, v80
	v_mul_f32_e32 v76, 0xbfb8aa3b, v76
	v_exp_f32_e32 v76, v76
	s_nop 0
	v_add_f32_e32 v76, 1.0, v76
	v_rcp_f32_e32 v80, v76
	v_add_f32_e32 v76, v77, v81
	v_mul_f32_e32 v76, 0xbfb8aa3b, v76
	v_exp_f32_e32 v76, v76
	s_nop 0
	v_add_f32_e32 v76, 1.0, v76
	v_rcp_f32_e32 v81, v76
	v_add_f32_e32 v76, v78, v82
	v_mul_f32_e32 v76, 0xbfb8aa3b, v76
	v_exp_f32_e32 v76, v76
	v_cvt_pk_bf16_f32 v78, v80, v81
	v_add_f32_e32 v76, 1.0, v76
	v_rcp_f32_e32 v82, v76
	v_add_f32_e32 v76, v79, v83
	v_mul_f32_e32 v76, 0xbfb8aa3b, v76
	v_exp_f32_e32 v76, v76
	s_nop 0
	v_add_f32_e32 v76, 1.0, v76
	v_rcp_f32_e32 v79, v76
	v_lshl_add_u64 v[76:77], s[4:5], 0, v[84:85]
	v_lshl_add_u64 v[76:77], v[76:77], 0, v[130:131]
	v_cvt_pk_bf16_f32 v79, v82, v79
	global_store_dwordx2 v[76:77], v[78:79], off
	global_load_dwordx4 v[78:81], v[128:129], off offset:64
	s_waitcnt vmcnt(0)
	v_add_f32_e32 v72, v72, v78
	v_add_f32_e32 v73, v73, v79
	v_add_f32_e32 v74, v74, v80
	v_add_f32_e32 v75, v75, v81
	v_mul_f32_e32 v72, 0xbfb8aa3b, v72
	v_mul_f32_e32 v73, 0xbfb8aa3b, v73
	v_mul_f32_e32 v74, 0xbfb8aa3b, v74
	v_mul_f32_e32 v75, 0xbfb8aa3b, v75
	v_exp_f32_e32 v72, v72
	v_exp_f32_e32 v73, v73
	v_exp_f32_e32 v74, v74
	v_exp_f32_e32 v75, v75
	v_add_f32_e32 v72, 1.0, v72
	v_add_f32_e32 v73, 1.0, v73
	v_add_f32_e32 v74, 1.0, v74
	v_add_f32_e32 v75, 1.0, v75
	v_rcp_f32_e32 v72, v72
	v_rcp_f32_e32 v73, v73
	v_rcp_f32_e32 v74, v74
	v_rcp_f32_e32 v75, v75
	v_cvt_pk_bf16_f32 v72, v72, v73
	v_cvt_pk_bf16_f32 v73, v74, v75
	global_store_dwordx2 v[76:77], v[72:73], off offset:32
	global_load_dwordx4 v[72:75], v[128:129], off offset:128
	s_waitcnt vmcnt(0)
	v_add_f32_e32 v68, v68, v72
	v_add_f32_e32 v69, v69, v73
	v_add_f32_e32 v70, v70, v74
	v_add_f32_e32 v71, v71, v75
	v_mul_f32_e32 v68, 0xbfb8aa3b, v68
	v_mul_f32_e32 v69, 0xbfb8aa3b, v69
	v_mul_f32_e32 v70, 0xbfb8aa3b, v70
	v_mul_f32_e32 v71, 0xbfb8aa3b, v71
	v_exp_f32_e32 v68, v68
	v_exp_f32_e32 v69, v69
	v_exp_f32_e32 v70, v70
	v_exp_f32_e32 v71, v71
	v_add_f32_e32 v68, 1.0, v68
	v_add_f32_e32 v69, 1.0, v69
	v_add_f32_e32 v70, 1.0, v70
	v_add_f32_e32 v71, 1.0, v71
	v_rcp_f32_e32 v68, v68
	v_rcp_f32_e32 v69, v69
	v_rcp_f32_e32 v70, v70
	v_rcp_f32_e32 v71, v71
	v_cvt_pk_bf16_f32 v68, v68, v69
	v_cvt_pk_bf16_f32 v69, v70, v71
	global_store_dwordx2 v[76:77], v[68:69], off offset:64
	global_load_dwordx4 v[68:71], v[128:129], off offset:192
	s_waitcnt vmcnt(0)
	v_add_f32_e32 v64, v64, v68
	v_add_f32_e32 v65, v65, v69
	v_add_f32_e32 v66, v66, v70
	v_add_f32_e32 v67, v67, v71
	v_mul_f32_e32 v64, 0xbfb8aa3b, v64
	v_mul_f32_e32 v65, 0xbfb8aa3b, v65
	v_mul_f32_e32 v66, 0xbfb8aa3b, v66
	v_mul_f32_e32 v67, 0xbfb8aa3b, v67
	v_exp_f32_e32 v64, v64
	v_exp_f32_e32 v65, v65
	v_exp_f32_e32 v66, v66
	v_exp_f32_e32 v67, v67
	v_add_f32_e32 v64, 1.0, v64
	v_add_f32_e32 v65, 1.0, v65
	v_add_f32_e32 v66, 1.0, v66
	v_add_f32_e32 v67, 1.0, v67
	v_rcp_f32_e32 v64, v64
	v_rcp_f32_e32 v65, v65
	v_rcp_f32_e32 v66, v66
	v_rcp_f32_e32 v67, v67
	v_cvt_pk_bf16_f32 v64, v64, v65
	v_cvt_pk_bf16_f32 v65, v66, v67
	global_store_dwordx2 v[76:77], v[64:65], off offset:96
	v_or_b32_e32 v64, 64, v132
	v_ashrrev_i32_e32 v65, 31, v64
	v_lshlrev_b64 v[68:69], 10, v[64:65]
	global_load_dwordx4 v[64:67], v[128:129], off
	s_waitcnt vmcnt(0)
	v_add_f32_e32 v60, v60, v64
	v_mul_f32_e32 v60, 0xbfb8aa3b, v60
	v_exp_f32_e32 v60, v60
	s_nop 0
	v_add_f32_e32 v60, 1.0, v60
	v_rcp_f32_e32 v64, v60
	v_add_f32_e32 v60, v61, v65
	v_mul_f32_e32 v60, 0xbfb8aa3b, v60
	v_exp_f32_e32 v60, v60
	s_nop 0
	v_add_f32_e32 v60, 1.0, v60
	v_rcp_f32_e32 v65, v60
	v_add_f32_e32 v60, v62, v66
	v_mul_f32_e32 v60, 0xbfb8aa3b, v60
	v_exp_f32_e32 v60, v60
	v_cvt_pk_bf16_f32 v62, v64, v65
	v_add_f32_e32 v60, 1.0, v60
	v_rcp_f32_e32 v66, v60
	v_add_f32_e32 v60, v63, v67
	v_mul_f32_e32 v60, 0xbfb8aa3b, v60
	v_exp_f32_e32 v60, v60
	s_nop 0
	v_add_f32_e32 v60, 1.0, v60
	v_rcp_f32_e32 v63, v60
	v_lshl_add_u64 v[60:61], s[4:5], 0, v[68:69]
	v_lshl_add_u64 v[60:61], v[60:61], 0, v[130:131]
	v_cvt_pk_bf16_f32 v63, v66, v63
	global_store_dwordx2 v[60:61], v[62:63], off
	global_load_dwordx4 v[62:65], v[128:129], off offset:64
	s_waitcnt vmcnt(0)
; DI unsigned pack2(float lo, float hi) { const f32x2c v = {lo, hi}; return __builtin_bit_cast(unsigned, __builtin_convertvector(v, bf16x2c)); }
; DI void st_bf16x4(bf16_t* o, f32x4 v) { u32x2 q; q.x = pack2(v[0], v[1]); q.y = pack2(v[2], v[3]); *(u32x2*)o = q; }
;   DI void operator()(int row, int col, f32x4 v) const {
;     if (col < n0) st_bf16x4(o0 + (size_t)row * ld0 + col, v);
;     else { const int c = col - n0; if (c < n1) st_bf16x4(o1 + (size_t)row * ld1 + c, v); }
;   }
	v_add_f32_e32 v56, v56, v62
	v_add_f32_e32 v57, v57, v63
	v_add_f32_e32 v58, v58, v64
	v_add_f32_e32 v59, v59, v65
	v_mul_f32_e32 v56, 0xbfb8aa3b, v56
	v_mul_f32_e32 v57, 0xbfb8aa3b, v57
	v_mul_f32_e32 v58, 0xbfb8aa3b, v58
	v_mul_f32_e32 v59, 0xbfb8aa3b, v59
	v_exp_f32_e32 v56, v56
	v_exp_f32_e32 v57, v57
	v_exp_f32_e32 v58, v58
	v_exp_f32_e32 v59, v59
	v_add_f32_e32 v56, 1.0, v56
	v_add_f32_e32 v57, 1.0, v57
	v_add_f32_e32 v58, 1.0, v58
	v_add_f32_e32 v59, 1.0, v59
	v_rcp_f32_e32 v56, v56
	v_rcp_f32_e32 v57, v57
	v_rcp_f32_e32 v58, v58
	v_rcp_f32_e32 v59, v59
	v_cvt_pk_bf16_f32 v56, v56, v57
	v_cvt_pk_bf16_f32 v57, v58, v59
	global_store_dwordx2 v[60:61], v[56:57], off offset:32
	global_load_dwordx4 v[56:59], v[128:129], off offset:128
	s_waitcnt vmcnt(0)
	v_add_f32_e32 v52, v52, v56
	v_add_f32_e32 v53, v53, v57
	v_add_f32_e32 v54, v54, v58
	v_add_f32_e32 v55, v55, v59
	v_mul_f32_e32 v52, 0xbfb8aa3b, v52
	v_mul_f32_e32 v53, 0xbfb8aa3b, v53
	v_mul_f32_e32 v54, 0xbfb8aa3b, v54
	v_mul_f32_e32 v55, 0xbfb8aa3b, v55
	v_exp_f32_e32 v52, v52
	v_exp_f32_e32 v53, v53
	v_exp_f32_e32 v54, v54
	v_exp_f32_e32 v55, v55
	v_add_f32_e32 v52, 1.0, v52
	v_add_f32_e32 v53, 1.0, v53
	v_add_f32_e32 v54, 1.0, v54
	v_add_f32_e32 v55, 1.0, v55
	v_rcp_f32_e32 v52, v52
	v_rcp_f32_e32 v53, v53
	v_rcp_f32_e32 v54, v54
	v_rcp_f32_e32 v55, v55
	v_cvt_pk_bf16_f32 v52, v52, v53
	v_cvt_pk_bf16_f32 v53, v54, v55
	global_store_dwordx2 v[60:61], v[52:53], off offset:64
	global_load_dwordx4 v[52:55], v[128:129], off offset:192
	s_waitcnt vmcnt(0)
	v_add_f32_e32 v48, v48, v52
	v_add_f32_e32 v49, v49, v53
	v_add_f32_e32 v50, v50, v54
	v_add_f32_e32 v51, v51, v55
	v_mul_f32_e32 v48, 0xbfb8aa3b, v48
	v_mul_f32_e32 v49, 0xbfb8aa3b, v49
	v_mul_f32_e32 v50, 0xbfb8aa3b, v50
	v_mul_f32_e32 v51, 0xbfb8aa3b, v51
	v_exp_f32_e32 v48, v48
	v_exp_f32_e32 v49, v49
	v_exp_f32_e32 v50, v50
	v_exp_f32_e32 v51, v51
	v_add_f32_e32 v48, 1.0, v48
	v_add_f32_e32 v49, 1.0, v49
	v_add_f32_e32 v50, 1.0, v50
	v_add_f32_e32 v51, 1.0, v51
	v_rcp_f32_e32 v48, v48
	v_rcp_f32_e32 v49, v49
	v_rcp_f32_e32 v50, v50
	v_rcp_f32_e32 v51, v51
	v_cvt_pk_bf16_f32 v48, v48, v49
	v_cvt_pk_bf16_f32 v49, v50, v51
	global_store_dwordx2 v[60:61], v[48:49], off offset:96
	v_or_b32_e32 v48, 0x50, v132
	v_ashrrev_i32_e32 v49, 31, v48
	v_lshlrev_b64 v[52:53], 10, v[48:49]
	global_load_dwordx4 v[48:51], v[128:129], off
	s_waitcnt vmcnt(0)
	v_add_f32_e32 v44, v44, v48
	v_mul_f32_e32 v44, 0xbfb8aa3b, v44
	v_exp_f32_e32 v44, v44
	s_nop 0
	v_add_f32_e32 v44, 1.0, v44
	v_rcp_f32_e32 v48, v44
	v_add_f32_e32 v44, v45, v49
	v_mul_f32_e32 v44, 0xbfb8aa3b, v44
	v_exp_f32_e32 v44, v44
	s_nop 0
	v_add_f32_e32 v44, 1.0, v44
	v_rcp_f32_e32 v49, v44
	v_add_f32_e32 v44, v46, v50
	v_mul_f32_e32 v44, 0xbfb8aa3b, v44
	v_exp_f32_e32 v44, v44
	v_cvt_pk_bf16_f32 v46, v48, v49
	v_add_f32_e32 v44, 1.0, v44
	v_rcp_f32_e32 v50, v44
	v_add_f32_e32 v44, v47, v51
	v_mul_f32_e32 v44, 0xbfb8aa3b, v44
	v_exp_f32_e32 v44, v44
	s_nop 0
	v_add_f32_e32 v44, 1.0, v44
	v_rcp_f32_e32 v47, v44
	v_lshl_add_u64 v[44:45], s[4:5], 0, v[52:53]
	v_lshl_add_u64 v[44:45], v[44:45], 0, v[130:131]
	v_cvt_pk_bf16_f32 v47, v50, v47
	global_store_dwordx2 v[44:45], v[46:47], off
	global_load_dwordx4 v[46:49], v[128:129], off offset:64
	s_waitcnt vmcnt(0)
	v_add_f32_e32 v40, v40, v46
	v_add_f32_e32 v41, v41, v47
	v_add_f32_e32 v42, v42, v48
	v_add_f32_e32 v43, v43, v49
	v_mul_f32_e32 v40, 0xbfb8aa3b, v40
	v_mul_f32_e32 v41, 0xbfb8aa3b, v41
	v_mul_f32_e32 v42, 0xbfb8aa3b, v42
	v_mul_f32_e32 v43, 0xbfb8aa3b, v43
	v_exp_f32_e32 v40, v40
	v_exp_f32_e32 v41, v41
	v_exp_f32_e32 v42, v42
	v_exp_f32_e32 v43, v43
	v_add_f32_e32 v40, 1.0, v40
	v_add_f32_e32 v41, 1.0, v41
	v_add_f32_e32 v42, 1.0, v42
	v_add_f32_e32 v43, 1.0, v43
	v_rcp_f32_e32 v40, v40
	v_rcp_f32_e32 v41, v41
	v_rcp_f32_e32 v42, v42
	v_rcp_f32_e32 v43, v43
	v_cvt_pk_bf16_f32 v40, v40, v41
	v_cvt_pk_bf16_f32 v41, v42, v43
	global_store_dwordx2 v[44:45], v[40:41], off offset:32
	global_load_dwordx4 v[40:43], v[128:129], off offset:128
	s_waitcnt vmcnt(0)
	v_add_f32_e32 v36, v36, v40
	v_add_f32_e32 v37, v37, v41
	v_add_f32_e32 v38, v38, v42
	v_add_f32_e32 v39, v39, v43
	v_mul_f32_e32 v36, 0xbfb8aa3b, v36
	v_mul_f32_e32 v37, 0xbfb8aa3b, v37
	v_mul_f32_e32 v38, 0xbfb8aa3b, v38
	v_mul_f32_e32 v39, 0xbfb8aa3b, v39
	v_exp_f32_e32 v36, v36
	v_exp_f32_e32 v37, v37
	v_exp_f32_e32 v38, v38
	v_exp_f32_e32 v39, v39
	v_add_f32_e32 v36, 1.0, v36
	v_add_f32_e32 v37, 1.0, v37
	v_add_f32_e32 v38, 1.0, v38
	v_add_f32_e32 v39, 1.0, v39
	v_rcp_f32_e32 v36, v36
	v_rcp_f32_e32 v37, v37
	v_rcp_f32_e32 v38, v38
	v_rcp_f32_e32 v39, v39
	v_cvt_pk_bf16_f32 v36, v36, v37
	v_cvt_pk_bf16_f32 v37, v38, v39
	global_store_dwordx2 v[44:45], v[36:37], off offset:64
	global_load_dwordx4 v[36:39], v[128:129], off offset:192
	s_waitcnt vmcnt(0)
	v_add_f32_e32 v32, v32, v36
	v_add_f32_e32 v33, v33, v37
	v_add_f32_e32 v34, v34, v38
	v_add_f32_e32 v35, v35, v39
	v_mul_f32_e32 v32, 0xbfb8aa3b, v32
	v_mul_f32_e32 v33, 0xbfb8aa3b, v33
	v_mul_f32_e32 v34, 0xbfb8aa3b, v34
	v_mul_f32_e32 v35, 0xbfb8aa3b, v35
	v_exp_f32_e32 v32, v32
	v_exp_f32_e32 v33, v33
	v_exp_f32_e32 v34, v34
	v_exp_f32_e32 v35, v35
	v_add_f32_e32 v32, 1.0, v32
	v_add_f32_e32 v33, 1.0, v33
	v_add_f32_e32 v34, 1.0, v34
	v_add_f32_e32 v35, 1.0, v35
	v_rcp_f32_e32 v32, v32
	v_rcp_f32_e32 v33, v33
	v_rcp_f32_e32 v34, v34
	v_rcp_f32_e32 v35, v35
	v_cvt_pk_bf16_f32 v32, v32, v33
	v_cvt_pk_bf16_f32 v33, v34, v35
	global_store_dwordx2 v[44:45], v[32:33], off offset:96
	v_or_b32_e32 v32, 0x60, v132
	v_ashrrev_i32_e32 v33, 31, v32
	v_lshlrev_b64 v[36:37], 10, v[32:33]
	global_load_dwordx4 v[32:35], v[128:129], off
	s_waitcnt vmcnt(0)
; DI unsigned pack2(float lo, float hi) { const f32x2c v = {lo, hi}; return __builtin_bit_cast(unsigned, __builtin_convertvector(v, bf16x2c)); }
; DI void st_bf16x4(bf16_t* o, f32x4 v) { u32x2 q; q.x = pack2(v[0], v[1]); q.y = pack2(v[2], v[3]); *(u32x2*)o = q; }
;   DI void operator()(int row, int col, f32x4 v) const {
;     if (col < n0) st_bf16x4(o0 + (size_t)row * ld0 + col, v);
;     else { const int c = col - n0; if (c < n1) st_bf16x4(o1 + (size_t)row * ld1 + c, v); }
;   }
	v_add_f32_e32 v28, v28, v32
	v_mul_f32_e32 v28, 0xbfb8aa3b, v28
	v_exp_f32_e32 v28, v28
	s_nop 0
	v_add_f32_e32 v28, 1.0, v28
	v_rcp_f32_e32 v32, v28
	v_add_f32_e32 v28, v29, v33
	v_mul_f32_e32 v28, 0xbfb8aa3b, v28
	v_exp_f32_e32 v28, v28
	s_nop 0
	v_add_f32_e32 v28, 1.0, v28
	v_rcp_f32_e32 v33, v28
	v_add_f32_e32 v28, v30, v34
	v_mul_f32_e32 v28, 0xbfb8aa3b, v28
	v_exp_f32_e32 v28, v28
	v_cvt_pk_bf16_f32 v30, v32, v33
	v_add_f32_e32 v28, 1.0, v28
	v_rcp_f32_e32 v34, v28
	v_add_f32_e32 v28, v31, v35
	v_mul_f32_e32 v28, 0xbfb8aa3b, v28
	v_exp_f32_e32 v28, v28
	s_nop 0
	v_add_f32_e32 v28, 1.0, v28
	v_rcp_f32_e32 v31, v28
	v_lshl_add_u64 v[28:29], s[4:5], 0, v[36:37]
	v_lshl_add_u64 v[28:29], v[28:29], 0, v[130:131]
	v_cvt_pk_bf16_f32 v31, v34, v31
	global_store_dwordx2 v[28:29], v[30:31], off
	global_load_dwordx4 v[30:33], v[128:129], off offset:64
	s_waitcnt vmcnt(0)
	v_add_f32_e32 v24, v24, v30
	v_add_f32_e32 v25, v25, v31
	v_add_f32_e32 v26, v26, v32
	v_add_f32_e32 v27, v27, v33
	v_mul_f32_e32 v24, 0xbfb8aa3b, v24
	v_mul_f32_e32 v25, 0xbfb8aa3b, v25
	v_mul_f32_e32 v26, 0xbfb8aa3b, v26
	v_mul_f32_e32 v27, 0xbfb8aa3b, v27
	v_exp_f32_e32 v24, v24
	v_exp_f32_e32 v25, v25
	v_exp_f32_e32 v26, v26
	v_exp_f32_e32 v27, v27
	v_add_f32_e32 v24, 1.0, v24
	v_add_f32_e32 v25, 1.0, v25
	v_add_f32_e32 v26, 1.0, v26
	v_add_f32_e32 v27, 1.0, v27
	v_rcp_f32_e32 v24, v24
	v_rcp_f32_e32 v25, v25
	v_rcp_f32_e32 v26, v26
	v_rcp_f32_e32 v27, v27
	v_cvt_pk_bf16_f32 v24, v24, v25
	v_cvt_pk_bf16_f32 v25, v26, v27
	global_store_dwordx2 v[28:29], v[24:25], off offset:32
	global_load_dwordx4 v[24:27], v[128:129], off offset:128
	s_waitcnt vmcnt(0)
	v_add_f32_e32 v20, v20, v24
	v_add_f32_e32 v21, v21, v25
	v_add_f32_e32 v22, v22, v26
	v_add_f32_e32 v23, v23, v27
	v_mul_f32_e32 v20, 0xbfb8aa3b, v20
	v_mul_f32_e32 v21, 0xbfb8aa3b, v21
	v_mul_f32_e32 v22, 0xbfb8aa3b, v22
	v_mul_f32_e32 v23, 0xbfb8aa3b, v23
	v_exp_f32_e32 v20, v20
	v_exp_f32_e32 v21, v21
	v_exp_f32_e32 v22, v22
	v_exp_f32_e32 v23, v23
	v_add_f32_e32 v20, 1.0, v20
	v_add_f32_e32 v21, 1.0, v21
	v_add_f32_e32 v22, 1.0, v22
	v_add_f32_e32 v23, 1.0, v23
	v_rcp_f32_e32 v20, v20
	v_rcp_f32_e32 v21, v21
	v_rcp_f32_e32 v22, v22
	v_rcp_f32_e32 v23, v23
	v_cvt_pk_bf16_f32 v20, v20, v21
	v_cvt_pk_bf16_f32 v21, v22, v23
	global_store_dwordx2 v[28:29], v[20:21], off offset:64
	global_load_dwordx4 v[20:23], v[128:129], off offset:192
	s_waitcnt vmcnt(0)
	v_add_f32_e32 v16, v16, v20
	v_add_f32_e32 v17, v17, v21
	v_add_f32_e32 v18, v18, v22
	v_add_f32_e32 v19, v19, v23
	v_mul_f32_e32 v16, 0xbfb8aa3b, v16
	v_mul_f32_e32 v17, 0xbfb8aa3b, v17
	v_mul_f32_e32 v18, 0xbfb8aa3b, v18
	v_mul_f32_e32 v19, 0xbfb8aa3b, v19
	v_exp_f32_e32 v16, v16
	v_exp_f32_e32 v17, v17
	v_exp_f32_e32 v18, v18
	v_exp_f32_e32 v19, v19
	v_add_f32_e32 v16, 1.0, v16
	v_add_f32_e32 v17, 1.0, v17
	v_add_f32_e32 v18, 1.0, v18
	v_add_f32_e32 v19, 1.0, v19
	v_rcp_f32_e32 v16, v16
	v_rcp_f32_e32 v17, v17
	v_rcp_f32_e32 v18, v18
	v_rcp_f32_e32 v19, v19
	v_cvt_pk_bf16_f32 v16, v16, v17
	v_cvt_pk_bf16_f32 v17, v18, v19
	global_store_dwordx2 v[28:29], v[16:17], off offset:96
	v_or_b32_e32 v16, 0x70, v132
	v_ashrrev_i32_e32 v17, 31, v16
	v_lshlrev_b64 v[20:21], 10, v[16:17]
	global_load_dwordx4 v[16:19], v[128:129], off
	s_waitcnt vmcnt(0)
	v_add_f32_e32 v12, v12, v16
	v_mul_f32_e32 v12, 0xbfb8aa3b, v12
	v_exp_f32_e32 v12, v12
	s_nop 0
	v_add_f32_e32 v12, 1.0, v12
	v_rcp_f32_e32 v16, v12
	v_add_f32_e32 v12, v13, v17
	v_mul_f32_e32 v12, 0xbfb8aa3b, v12
	v_exp_f32_e32 v12, v12
	s_nop 0
	v_add_f32_e32 v12, 1.0, v12
	v_rcp_f32_e32 v17, v12
	v_add_f32_e32 v12, v14, v18
	v_mul_f32_e32 v12, 0xbfb8aa3b, v12
	v_exp_f32_e32 v12, v12
	v_cvt_pk_bf16_f32 v14, v16, v17
	v_add_f32_e32 v12, 1.0, v12
	v_rcp_f32_e32 v18, v12
	v_add_f32_e32 v12, v15, v19
	v_mul_f32_e32 v12, 0xbfb8aa3b, v12
	v_exp_f32_e32 v12, v12
	s_nop 0
	v_add_f32_e32 v12, 1.0, v12
	v_rcp_f32_e32 v15, v12
	v_lshl_add_u64 v[12:13], s[4:5], 0, v[20:21]
	v_lshl_add_u64 v[12:13], v[12:13], 0, v[130:131]
	v_cvt_pk_bf16_f32 v15, v18, v15
	global_store_dwordx2 v[12:13], v[14:15], off
	global_load_dwordx4 v[14:17], v[128:129], off offset:64
	s_waitcnt vmcnt(0)
	v_add_f32_e32 v8, v8, v14
	v_add_f32_e32 v9, v9, v15
	v_add_f32_e32 v10, v10, v16
	v_add_f32_e32 v11, v11, v17
	v_mul_f32_e32 v8, 0xbfb8aa3b, v8
	v_mul_f32_e32 v9, 0xbfb8aa3b, v9
	v_mul_f32_e32 v10, 0xbfb8aa3b, v10
	v_mul_f32_e32 v11, 0xbfb8aa3b, v11
	v_exp_f32_e32 v8, v8
	v_exp_f32_e32 v9, v9
	v_exp_f32_e32 v10, v10
	v_exp_f32_e32 v11, v11
	v_add_f32_e32 v8, 1.0, v8
	v_add_f32_e32 v9, 1.0, v9
	v_add_f32_e32 v10, 1.0, v10
	v_add_f32_e32 v11, 1.0, v11
	v_rcp_f32_e32 v8, v8
	v_rcp_f32_e32 v9, v9
	v_rcp_f32_e32 v10, v10
	v_rcp_f32_e32 v11, v11
	v_cvt_pk_bf16_f32 v8, v8, v9
	v_cvt_pk_bf16_f32 v9, v10, v11
	global_store_dwordx2 v[12:13], v[8:9], off offset:32
	global_load_dwordx4 v[8:11], v[128:129], off offset:128
	s_waitcnt vmcnt(0)
	v_add_f32_e32 v4, v4, v8
	v_add_f32_e32 v5, v5, v9
	v_add_f32_e32 v6, v6, v10
	v_add_f32_e32 v7, v7, v11
	v_mul_f32_e32 v4, 0xbfb8aa3b, v4
	v_mul_f32_e32 v5, 0xbfb8aa3b, v5
	v_mul_f32_e32 v6, 0xbfb8aa3b, v6
	v_mul_f32_e32 v7, 0xbfb8aa3b, v7
	v_exp_f32_e32 v4, v4
	v_exp_f32_e32 v5, v5
	v_exp_f32_e32 v6, v6
	v_exp_f32_e32 v7, v7
	v_add_f32_e32 v4, 1.0, v4
	v_add_f32_e32 v5, 1.0, v5
	v_add_f32_e32 v6, 1.0, v6
	v_add_f32_e32 v7, 1.0, v7
	v_rcp_f32_e32 v4, v4
	v_rcp_f32_e32 v5, v5
	v_rcp_f32_e32 v6, v6
	v_rcp_f32_e32 v7, v7
	v_cvt_pk_bf16_f32 v4, v4, v5
	v_cvt_pk_bf16_f32 v5, v6, v7
	global_store_dwordx2 v[12:13], v[4:5], off offset:64
	global_load_dwordx4 v[4:7], v[128:129], off offset:192
	s_waitcnt vmcnt(0)
	v_add_f32_e32 v0, v0, v4
	v_add_f32_e32 v1, v1, v5
	v_add_f32_e32 v2, v2, v6
	v_add_f32_e32 v3, v3, v7
	v_mul_f32_e32 v0, 0xbfb8aa3b, v0
	v_mul_f32_e32 v1, 0xbfb8aa3b, v1
	v_mul_f32_e32 v2, 0xbfb8aa3b, v2
	v_mul_f32_e32 v3, 0xbfb8aa3b, v3
	v_exp_f32_e32 v0, v0
	v_exp_f32_e32 v1, v1
	v_exp_f32_e32 v2, v2
	v_exp_f32_e32 v3, v3
	v_add_f32_e32 v0, 1.0, v0
	v_add_f32_e32 v1, 1.0, v1
	v_add_f32_e32 v2, 1.0, v2
	v_add_f32_e32 v3, 1.0, v3
	v_rcp_f32_e32 v0, v0
	v_rcp_f32_e32 v1, v1
	v_rcp_f32_e32 v2, v2
	v_rcp_f32_e32 v3, v3
	v_cvt_pk_bf16_f32 v0, v0, v1
	v_cvt_pk_bf16_f32 v1, v2, v3
	global_store_dwordx2 v[12:13], v[0:1], off offset:96
	s_cbranch_scc0 .LBB0_576
; #define LWRITE(S, buf) do { bf16_t* sA_ = sbase + (buf) * BUF; bf16_t* sB_ = sA_ + 256 * PITCH; \
;     _Pragma("unroll") for (int i_ = 0; i_ < 4; ++i_) *(u32x4*)(sA_ + (sr + i_ * 64) * PITCH + scv * 8) = ra[S][i_]; \
;     _Pragma("unroll") for (int i_ = 0; i_ < 2; ++i_) *(u32x4*)(sB_ + (sr + i_ * 64) * PITCH + scv * 8) = rb[S][i_]; } while (0)
; template <class Epi>
; DI void gemm_tile(char* smem, const bf16_t* __restrict__ A0, int lda0, int ksplit, const bf16_t* __restrict__ A1, int lda1,
;                   const bf16_t* __restrict__ Bt, int K, int row0, int col0, const Epi& epi, int tid) {
;   constexpr int BK = 32, PITCH = 40, BUF = (256 + 128) * PITCH;
;   bf16_t* sbase = (bf16_t*)smem;
;   const int lane = tid & 63, wid = tid >> 6, wr = wid >> 1, wc = wid & 1, fr = lane & 15, fq = lane >> 4;
;   f32x4 acc[8][4];
; #pragma unroll
;   for (int m = 0; m < 8; ++m)
; #pragma unroll
;     for (int n = 0; n < 4; ++n) acc[m][n] = (f32x4){0.f, 0.f, 0.f, 0.f};
;   u32x4 ra[2][4], rb[2][2];
;   const int nk = K / BK;
;   const int sr = tid >> 2, scv = tid & 3;
;     ...
;   __syncthreads();
;   {
;     const int last = nk - 1;
;     GLOAD(0, 0);
;     __builtin_amdgcn_sched_barrier(0);
;     GLOAD(1, 1);
;     __builtin_amdgcn_sched_barrier(0);
;     LWRITE(0, 0);
;     __builtin_amdgcn_sched_barrier(0);
;     GLOAD(0, (2 < last ? 2 : last));
;     __builtin_amdgcn_sched_barrier(0);
;     __syncthreads();
;     for (int kt = 0; kt < nk; kt += 2) {
;       LWRITE(1, 1);
;       __builtin_amdgcn_sched_barrier(0);
;       GLOAD(1, (kt + 3 < last ? kt + 3 : last));
;       __builtin_amdgcn_sched_barrier(0);
;       COMPUTE(0);
; template <class Epi>
; DI void gemm_phase(char* smem, const bf16_t* A0, int lda0, int ksplit, const bf16_t* A1, int lda1, const bf16_t* Bt, int K, int nN, const Epi& epi, int tid) {
;     ...
;   } else {
;     const int ntiles = (NTOK / 256) * nN;
;     for (int u = blockIdx.x; u < ntiles; u += G) { const int rt = u / nN, ct = u % nN; gemm_tile(smem, A0, lda0, ksplit, A1, lda1, Bt, K, rt * 256, ct * 128, epi, tid); }
.LBB0_577:
	s_add_u32 s0, s92, 0x3800000
	s_addc_u32 s1, s93, 0
	s_add_u32 s4, s92, 0x3480000
	s_addc_u32 s5, s93, 0
	s_add_u32 s6, s92, 0x1ea00100
	s_addc_u32 s7, s93, 0
	s_and_b64 vcc, exec, s[2:3]
	s_cbranch_vccz .LBB0_582
	s_cmpk_gt_i32 s96, 0x1ff
	s_cbranch_scc1 .LBB0_581
	v_and_b32_e32 v0, 3, v136
	v_lshlrev_b32_e32 v4, 4, v0
	v_mov_b32_e32 v5, 0
	v_ashrrev_i32_e32 v8, 2, v137
	v_bfe_u32 v10, v136, 4, 2
	s_movk_i32 s8, 0x40
	v_lshl_add_u64 v[6:7], s[92:93], 0, v[4:5]
	s_mov_b64 s[2:3], 0x1ea00180
	v_and_b32_e32 v13, 0x4f, v137
	v_and_b32_e32 v9, 0xffffff8f, v137
	v_or_b32_e32 v16, 0x70, v137
	v_lshl_add_u64 v[0:1], s[6:7], 0, v[4:5]
	v_lshl_add_u64 v[2:3], s[4:5], 0, v[4:5]
	v_add_u32_e32 v11, 0, v4
	v_mul_lo_u32 v12, v8, s8
	v_lshl_add_u64 v[4:5], v[6:7], 0, s[2:3]
	s_mov_b64 s[2:3], 0x3480080
	v_lshl_add_u32 v14, v10, 4, 0
	v_mul_u32_u24_e32 v13, 0x40, v13
	v_mul_lo_u32 v15, v9, s8
	v_mul_lo_u32 v16, v16, s8
	v_lshlrev_b32_e32 v10, 2, v10
	v_lshl_add_u64 v[6:7], v[6:7], 0, s[2:3]
	v_and_or_b32 v10, v137, 64, v10
	s_lshl_b32 s15, s96, 7
	s_waitcnt lgkmcnt(0)
	s_lshl_b32 s16, s12, 7
	s_mov_b64 s[2:3], 0x8000
	s_mov_b64 s[8:9], 0x10000
	s_mov_b64 s[10:11], 0x18000
	v_add_u32_e32 v11, v11, v12
	v_add_u32_e32 v12, v14, v13
	v_add_u32_e32 v13, v14, v15
	v_add_u32_e32 v14, v14, v16
	v_mbcnt_lo_u32_b32 v15, -1, 0
	v_mbcnt_hi_u32_b32 v15, -1, v15
	v_bfe_u32 v16, v15, 3, 1
	v_bfe_u32 v15, v15, 5, 1
	v_mul_u32_u24_e32 v16, 48, v16
	v_mul_u32_u24_e32 v15, 48, v15
	v_xor_b32_e32 v11, v11, v15
	v_xor_b32_e32 v12, v12, v16
	v_xor_b32_e32 v13, v13, v16
	v_xor_b32_e32 v14, v14, v16
	s_mov_b32 s17, s96
.LBB0_580:
	s_ashr_i32 s18, s17, 31
	s_lshr_b32 s18, s18, 30
	s_add_i32 s18, s17, s18
	s_ashr_i32 s19, s18, 2
	s_lshl_b32 s18, s19, 8
	s_lshl_b32 s19, s19, 9
	s_sub_i32 s19, s15, s19
	v_add_u32_e32 v16, s18, v8
	v_add_u32_e32 v32, s19, v8
	v_ashrrev_i32_e32 v17, 31, v16
	v_ashrrev_i32_e32 v33, 31, v32
	v_lshlrev_b64 v[64:65], 9, v[16:17]
	v_lshlrev_b64 v[80:81], 8, v[32:33]
	v_add_u32_e32 v32, 64, v32
	v_lshl_add_u64 v[72:73], v[64:65], 0, s[8:9]
	v_ashrrev_i32_e32 v33, 31, v32
	v_lshl_add_u64 v[66:67], v[0:1], 0, v[64:65]
	v_lshl_add_u64 v[68:69], v[64:65], 0, s[2:3]
	v_lshl_add_u64 v[74:75], v[0:1], 0, v[72:73]
	v_lshl_add_u64 v[76:77], v[64:65], 0, s[10:11]
	v_lshl_add_u64 v[82:83], v[2:3], 0, v[80:81]
	v_lshlrev_b64 v[84:85], 8, v[32:33]
	s_barrier
	v_lshl_add_u64 v[70:71], v[0:1], 0, v[68:69]
	global_load_dwordx4 v[16:19], v[66:67], off
	global_load_dwordx4 v[20:23], v[70:71], off
	v_lshl_add_u64 v[78:79], v[0:1], 0, v[76:77]
	global_load_dwordx4 v[24:27], v[74:75], off
	global_load_dwordx4 v[28:31], v[78:79], off
	v_lshl_add_u64 v[86:87], v[2:3], 0, v[84:85]
	global_load_dwordx4 v[32:35], v[82:83], off
	global_load_dwordx4 v[36:39], v[86:87], off
	global_load_dwordx4 v[40:43], v[66:67], off offset:64
	global_load_dwordx4 v[44:47], v[70:71], off offset:64
	global_load_dwordx4 v[48:51], v[74:75], off offset:64
	global_load_dwordx4 v[52:55], v[78:79], off offset:64
	global_load_dwordx4 v[56:59], v[82:83], off offset:64
	global_load_dwordx4 v[60:63], v[86:87], off offset:64
	s_waitcnt vmcnt(11)
	ds_write_b128 v11, v[16:19]
	s_waitcnt vmcnt(10)
	ds_write_b128 v11, v[20:23] offset:4096
	s_waitcnt vmcnt(9)
	ds_write_b128 v11, v[24:27] offset:8192
	s_waitcnt vmcnt(8)
	ds_write_b128 v11, v[28:31] offset:12288
	s_waitcnt vmcnt(7)
	ds_write_b128 v11, v[32:35] offset:16384
	s_waitcnt vmcnt(6)
	ds_write_b128 v11, v[36:39] offset:20480
	v_lshl_add_u64 v[16:17], v[4:5], 0, v[64:65]
	v_lshl_add_u64 v[20:21], v[4:5], 0, v[68:69]
	v_lshl_add_u64 v[24:25], v[4:5], 0, v[72:73]
	v_lshl_add_u64 v[28:29], v[4:5], 0, v[76:77]
	v_lshl_add_u64 v[32:33], v[6:7], 0, v[80:81]
	v_lshl_add_u64 v[36:37], v[6:7], 0, v[84:85]
	global_load_dwordx4 v[16:19], v[16:17], off
	s_nop 0
	global_load_dwordx4 v[20:23], v[20:21], off
	s_nop 0
	global_load_dwordx4 v[24:27], v[24:25], off
	s_nop 0
	global_load_dwordx4 v[28:31], v[28:29], off
	s_nop 0
	global_load_dwordx4 v[32:35], v[32:33], off
	s_nop 0
	global_load_dwordx4 v[36:39], v[36:37], off
	s_waitcnt lgkmcnt(0)
	s_barrier
	global_load_dwordx4 v[64:67], v[66:67], off offset:192
	s_nop 0
	global_load_dwordx4 v[68:71], v[70:71], off offset:192
	s_nop 0
	global_load_dwordx4 v[72:75], v[74:75], off offset:192
	s_nop 0
	global_load_dwordx4 v[76:79], v[78:79], off offset:192
	s_nop 0
	global_load_dwordx4 v[80:83], v[82:83], off offset:192
	s_nop 0
	global_load_dwordx4 v[84:87], v[86:87], off offset:192
	s_waitcnt vmcnt(17)
	ds_write_b128 v11, v[40:43] offset:24576
	s_waitcnt vmcnt(16)
	ds_write_b128 v11, v[44:47] offset:28672
	s_waitcnt vmcnt(15)
	ds_write_b128 v11, v[48:51] offset:32768
	s_waitcnt vmcnt(14)
	ds_write_b128 v11, v[52:55] offset:36864
	s_waitcnt vmcnt(13)
	ds_write_b128 v11, v[56:59] offset:40960
	s_waitcnt vmcnt(12)
	ds_write_b128 v11, v[60:63] offset:45056
	ds_read_b128 v[40:43], v12 offset:16384
	ds_read_b128 v[44:47], v12 offset:17408
	ds_read_b128 v[48:51], v12 offset:18432
	ds_read_b128 v[52:55], v12 offset:19456
	ds_read_b128 v[56:59], v13
	ds_read_b128 v[60:63], v13 offset:1024
	ds_read_b128 v[88:91], v13 offset:2048
	ds_read_b128 v[92:95], v13 offset:3072
	ds_read_b128 v[96:99], v13 offset:4096
	ds_read_b128 v[100:103], v13 offset:5120
	ds_read_b128 v[104:107], v13 offset:6144
	ds_read_b128 v[108:111], v14
	s_setprio 1
	s_waitcnt lgkmcnt(7)
	v_mfma_f32_16x16x32_bf16 v[112:115], v[40:43], v[56:59], 0
	v_mfma_f32_16x16x32_bf16 v[116:119], v[44:47], v[56:59], 0
	v_mfma_f32_16x16x32_bf16 v[120:123], v[48:51], v[56:59], 0
	v_mfma_f32_16x16x32_bf16 v[56:59], v[52:55], v[56:59], 0
	s_waitcnt lgkmcnt(6)
; #define LWRITE(S, buf) do { bf16_t* sA_ = sbase + (buf) * BUF; bf16_t* sB_ = sA_ + 256 * PITCH; \
;     _Pragma("unroll") for (int i_ = 0; i_ < 4; ++i_) *(u32x4*)(sA_ + (sr + i_ * 64) * PITCH + scv * 8) = ra[S][i_]; \
;     _Pragma("unroll") for (int i_ = 0; i_ < 2; ++i_) *(u32x4*)(sB_ + (sr + i_ * 64) * PITCH + scv * 8) = rb[S][i_]; } while (0)
; template <class Epi>
; DI void gemm_tile(char* smem, const bf16_t* __restrict__ A0, int lda0, int ksplit, const bf16_t* __restrict__ A1, int lda1,
;                   const bf16_t* __restrict__ Bt, int K, int row0, int col0, const Epi& epi, int tid) {
;     ...
;   __syncthreads();
;   {
;     const int last = nk - 1;
;     GLOAD(0, 0);
;     __builtin_amdgcn_sched_barrier(0);
;     GLOAD(1, 1);
;     __builtin_amdgcn_sched_barrier(0);
;     LWRITE(0, 0);
;     __builtin_amdgcn_sched_barrier(0);
;     GLOAD(0, (2 < last ? 2 : last));
;     __builtin_amdgcn_sched_barrier(0);
;     __syncthreads();
;     for (int kt = 0; kt < nk; kt += 2) {
;       LWRITE(1, 1);
;       __builtin_amdgcn_sched_barrier(0);
;       GLOAD(1, (kt + 3 < last ? kt + 3 : last));
;       __builtin_amdgcn_sched_barrier(0);
;       COMPUTE(0);
;       __syncthreads();
;       LWRITE(0, 0);
	v_mfma_f32_16x16x32_bf16 v[124:127], v[40:43], v[60:63], 0
	v_mfma_f32_16x16x32_bf16 v[128:131], v[44:47], v[60:63], 0
	v_mfma_f32_16x16x32_bf16 v[132:135], v[48:51], v[60:63], 0
	v_mfma_f32_16x16x32_bf16 v[60:63], v[52:55], v[60:63], 0
	s_waitcnt lgkmcnt(5)
	v_mfma_f32_16x16x32_bf16 v[138:141], v[40:43], v[88:91], 0
	v_mfma_f32_16x16x32_bf16 v[142:145], v[44:47], v[88:91], 0
	v_mfma_f32_16x16x32_bf16 v[146:149], v[48:51], v[88:91], 0
	v_mfma_f32_16x16x32_bf16 v[88:91], v[52:55], v[88:91], 0
	s_waitcnt lgkmcnt(4)
	v_mfma_f32_16x16x32_bf16 v[150:153], v[40:43], v[92:95], 0
	v_mfma_f32_16x16x32_bf16 v[154:157], v[44:47], v[92:95], 0
	v_mfma_f32_16x16x32_bf16 v[158:161], v[48:51], v[92:95], 0
	v_mfma_f32_16x16x32_bf16 v[92:95], v[52:55], v[92:95], 0
	s_waitcnt lgkmcnt(3)
	v_mfma_f32_16x16x32_bf16 v[162:165], v[40:43], v[96:99], 0
	v_mfma_f32_16x16x32_bf16 v[166:169], v[44:47], v[96:99], 0
	v_mfma_f32_16x16x32_bf16 v[170:173], v[48:51], v[96:99], 0
	v_mfma_f32_16x16x32_bf16 v[96:99], v[52:55], v[96:99], 0
	s_waitcnt lgkmcnt(2)
	v_mfma_f32_16x16x32_bf16 v[174:177], v[40:43], v[100:103], 0
	v_mfma_f32_16x16x32_bf16 v[178:181], v[44:47], v[100:103], 0
	v_mfma_f32_16x16x32_bf16 v[182:185], v[48:51], v[100:103], 0
	v_mfma_f32_16x16x32_bf16 v[100:103], v[52:55], v[100:103], 0
	s_waitcnt lgkmcnt(1)
	v_mfma_f32_16x16x32_bf16 v[186:189], v[40:43], v[104:107], 0
	v_mfma_f32_16x16x32_bf16 v[190:193], v[44:47], v[104:107], 0
	v_mfma_f32_16x16x32_bf16 v[196:199], v[48:51], v[104:107], 0
	v_mfma_f32_16x16x32_bf16 v[104:107], v[52:55], v[104:107], 0
	s_waitcnt lgkmcnt(0)
	v_mfma_f32_16x16x32_bf16 v[40:43], v[40:43], v[108:111], 0
	v_mfma_f32_16x16x32_bf16 v[44:47], v[44:47], v[108:111], 0
	v_mfma_f32_16x16x32_bf16 v[48:51], v[48:51], v[108:111], 0
	v_mfma_f32_16x16x32_bf16 v[52:55], v[52:55], v[108:111], 0
	s_setprio 0
	s_barrier
	s_waitcnt vmcnt(11)
	ds_write_b128 v11, v[16:19]
	s_waitcnt vmcnt(10)
	ds_write_b128 v11, v[20:23] offset:4096
	s_waitcnt vmcnt(9)
	ds_write_b128 v11, v[24:27] offset:8192
	s_waitcnt vmcnt(8)
	ds_write_b128 v11, v[28:31] offset:12288
	s_waitcnt vmcnt(7)
	ds_write_b128 v11, v[32:35] offset:16384
	s_waitcnt vmcnt(6)
	ds_write_b128 v11, v[36:39] offset:20480
	ds_read_b128 v[16:19], v12 offset:40960
	ds_read_b128 v[20:23], v12 offset:41984
	ds_read_b128 v[24:27], v12 offset:43008
	ds_read_b128 v[28:31], v12 offset:44032
	ds_read_b128 v[32:35], v13 offset:26624
	ds_read_b128 v[36:39], v13 offset:27648
	ds_read_b128 v[108:111], v13 offset:28672
	ds_read_b128 v[200:203], v13 offset:29696
	ds_read_b128 v[204:207], v13 offset:24576
	ds_read_b128 v[208:211], v13 offset:30720
	ds_read_b128 v[212:215], v13 offset:25600
	ds_read_b128 v[216:219], v14 offset:24576
	s_setprio 1
	s_waitcnt lgkmcnt(3)
	v_mfma_f32_16x16x32_bf16 v[112:115], v[16:19], v[204:207], v[112:115]
	v_mfma_f32_16x16x32_bf16 v[116:119], v[20:23], v[204:207], v[116:119]
	v_mfma_f32_16x16x32_bf16 v[120:123], v[24:27], v[204:207], v[120:123]
	v_mfma_f32_16x16x32_bf16 v[56:59], v[28:31], v[204:207], v[56:59]
	s_waitcnt lgkmcnt(1)
	v_mfma_f32_16x16x32_bf16 v[124:127], v[16:19], v[212:215], v[124:127]
	v_mfma_f32_16x16x32_bf16 v[128:131], v[20:23], v[212:215], v[128:131]
	v_mfma_f32_16x16x32_bf16 v[132:135], v[24:27], v[212:215], v[132:135]
	v_mfma_f32_16x16x32_bf16 v[60:63], v[28:31], v[212:215], v[60:63]
	v_mfma_f32_16x16x32_bf16 v[138:141], v[16:19], v[32:35], v[138:141]
	v_mfma_f32_16x16x32_bf16 v[142:145], v[20:23], v[32:35], v[142:145]
	v_mfma_f32_16x16x32_bf16 v[146:149], v[24:27], v[32:35], v[146:149]
	v_mfma_f32_16x16x32_bf16 v[32:35], v[28:31], v[32:35], v[88:91]
	v_mfma_f32_16x16x32_bf16 v[88:91], v[16:19], v[36:39], v[150:153]
	v_mfma_f32_16x16x32_bf16 v[150:153], v[20:23], v[36:39], v[154:157]
	v_mfma_f32_16x16x32_bf16 v[154:157], v[24:27], v[36:39], v[158:161]
	v_mfma_f32_16x16x32_bf16 v[36:39], v[28:31], v[36:39], v[92:95]
	v_mfma_f32_16x16x32_bf16 v[92:95], v[16:19], v[108:111], v[162:165]
	v_mfma_f32_16x16x32_bf16 v[158:161], v[20:23], v[108:111], v[166:169]
	v_mfma_f32_16x16x32_bf16 v[162:165], v[24:27], v[108:111], v[170:173]
	v_mfma_f32_16x16x32_bf16 v[96:99], v[28:31], v[108:111], v[96:99]
	v_mfma_f32_16x16x32_bf16 v[108:111], v[16:19], v[200:203], v[174:177]
	v_mfma_f32_16x16x32_bf16 v[166:169], v[20:23], v[200:203], v[178:181]
	v_mfma_f32_16x16x32_bf16 v[170:173], v[24:27], v[200:203], v[182:185]
	v_mfma_f32_16x16x32_bf16 v[100:103], v[28:31], v[200:203], v[100:103]
	v_mfma_f32_16x16x32_bf16 v[174:177], v[16:19], v[208:211], v[186:189]
	v_mfma_f32_16x16x32_bf16 v[178:181], v[20:23], v[208:211], v[190:193]
	v_mfma_f32_16x16x32_bf16 v[182:185], v[24:27], v[208:211], v[196:199]
	v_mfma_f32_16x16x32_bf16 v[104:107], v[28:31], v[208:211], v[104:107]
	s_waitcnt lgkmcnt(0)
	v_mfma_f32_16x16x32_bf16 v[16:19], v[16:19], v[216:219], v[40:43]
	v_mfma_f32_16x16x32_bf16 v[20:23], v[20:23], v[216:219], v[44:47]
	v_mfma_f32_16x16x32_bf16 v[24:27], v[24:27], v[216:219], v[48:51]
	v_mfma_f32_16x16x32_bf16 v[28:31], v[28:31], v[216:219], v[52:55]
	s_setprio 0
	s_barrier
; #define LWRITE(S, buf) do { bf16_t* sA_ = sbase + (buf) * BUF; bf16_t* sB_ = sA_ + 256 * PITCH; \
;     _Pragma("unroll") for (int i_ = 0; i_ < 4; ++i_) *(u32x4*)(sA_ + (sr + i_ * 64) * PITCH + scv * 8) = ra[S][i_]; \
;     _Pragma("unroll") for (int i_ = 0; i_ < 2; ++i_) *(u32x4*)(sB_ + (sr + i_ * 64) * PITCH + scv * 8) = rb[S][i_]; } while (0)
; template <class Epi>
; DI void gemm_tile(char* smem, const bf16_t* __restrict__ A0, int lda0, int ksplit, const bf16_t* __restrict__ A1, int lda1,
;                   const bf16_t* __restrict__ Bt, int K, int row0, int col0, const Epi& epi, int tid) {
;     ...
;   __syncthreads();
;   {
;     const int last = nk - 1;
;     GLOAD(0, 0);
;     __builtin_amdgcn_sched_barrier(0);
;     GLOAD(1, 1);
;     __builtin_amdgcn_sched_barrier(0);
;     LWRITE(0, 0);
;     __builtin_amdgcn_sched_barrier(0);
;     GLOAD(0, (2 < last ? 2 : last));
;     __builtin_amdgcn_sched_barrier(0);
;     __syncthreads();
;     for (int kt = 0; kt < nk; kt += 2) {
;       LWRITE(1, 1);
;       __builtin_amdgcn_sched_barrier(0);
;       GLOAD(1, (kt + 3 < last ? kt + 3 : last));
;       __builtin_amdgcn_sched_barrier(0);
;       COMPUTE(0);
;       __syncthreads();
;       LWRITE(0, 0);
;       __builtin_amdgcn_sched_barrier(0);
;       GLOAD(0, (kt + 4 < last ? kt + 4 : last));
;       __builtin_amdgcn_sched_barrier(0);
;       COMPUTE(1);
;       __syncthreads();
;     }
	s_waitcnt vmcnt(5)
	ds_write_b128 v11, v[64:67] offset:24576
	s_waitcnt vmcnt(4)
	ds_write_b128 v11, v[68:71] offset:28672
	s_waitcnt vmcnt(3)
	ds_write_b128 v11, v[72:75] offset:32768
	s_waitcnt vmcnt(2)
	ds_write_b128 v11, v[76:79] offset:36864
	s_waitcnt vmcnt(1)
	ds_write_b128 v11, v[80:83] offset:40960
	s_waitcnt vmcnt(0)
	ds_write_b128 v11, v[84:87] offset:45056
	ds_read_b128 v[40:43], v12 offset:16384
	ds_read_b128 v[44:47], v12 offset:17408
	ds_read_b128 v[48:51], v12 offset:18432
	ds_read_b128 v[52:55], v12 offset:19456
	ds_read_b128 v[186:189], v13
	ds_read_b128 v[190:193], v13 offset:1024
	ds_read_b128 v[196:199], v13 offset:2048
	ds_read_b128 v[200:203], v13 offset:3072
	ds_read_b128 v[204:207], v13 offset:4096
	ds_read_b128 v[208:211], v13 offset:5120
	ds_read_b128 v[212:215], v13 offset:6144
	ds_read_b128 v[216:219], v14
	s_setprio 1
	s_waitcnt lgkmcnt(7)
	v_mfma_f32_16x16x32_bf16 v[112:115], v[40:43], v[186:189], v[112:115]
	v_mfma_f32_16x16x32_bf16 v[116:119], v[44:47], v[186:189], v[116:119]
	v_mfma_f32_16x16x32_bf16 v[120:123], v[48:51], v[186:189], v[120:123]
	v_mfma_f32_16x16x32_bf16 v[56:59], v[52:55], v[186:189], v[56:59]
	s_waitcnt lgkmcnt(6)
	v_mfma_f32_16x16x32_bf16 v[124:127], v[40:43], v[190:193], v[124:127]
	v_mfma_f32_16x16x32_bf16 v[128:131], v[44:47], v[190:193], v[128:131]
	v_mfma_f32_16x16x32_bf16 v[132:135], v[48:51], v[190:193], v[132:135]
	v_mfma_f32_16x16x32_bf16 v[60:63], v[52:55], v[190:193], v[60:63]
	s_waitcnt lgkmcnt(5)
	v_mfma_f32_16x16x32_bf16 v[138:141], v[40:43], v[196:199], v[138:141]
	v_mfma_f32_16x16x32_bf16 v[142:145], v[44:47], v[196:199], v[142:145]
	v_mfma_f32_16x16x32_bf16 v[146:149], v[48:51], v[196:199], v[146:149]
	v_mfma_f32_16x16x32_bf16 v[32:35], v[52:55], v[196:199], v[32:35]
	s_waitcnt lgkmcnt(4)
	v_mfma_f32_16x16x32_bf16 v[88:91], v[40:43], v[200:203], v[88:91]
	v_mfma_f32_16x16x32_bf16 v[150:153], v[44:47], v[200:203], v[150:153]
	v_mfma_f32_16x16x32_bf16 v[154:157], v[48:51], v[200:203], v[154:157]
	v_mfma_f32_16x16x32_bf16 v[36:39], v[52:55], v[200:203], v[36:39]
	s_waitcnt lgkmcnt(3)
	v_mfma_f32_16x16x32_bf16 v[92:95], v[40:43], v[204:207], v[92:95]
	v_mfma_f32_16x16x32_bf16 v[158:161], v[44:47], v[204:207], v[158:161]
	v_mfma_f32_16x16x32_bf16 v[162:165], v[48:51], v[204:207], v[162:165]
	v_mfma_f32_16x16x32_bf16 v[96:99], v[52:55], v[204:207], v[96:99]
	s_waitcnt lgkmcnt(2)
	v_mfma_f32_16x16x32_bf16 v[108:111], v[40:43], v[208:211], v[108:111]
	v_mfma_f32_16x16x32_bf16 v[166:169], v[44:47], v[208:211], v[166:169]
	v_mfma_f32_16x16x32_bf16 v[170:173], v[48:51], v[208:211], v[170:173]
	v_mfma_f32_16x16x32_bf16 v[100:103], v[52:55], v[208:211], v[100:103]
	s_waitcnt lgkmcnt(1)
	v_mfma_f32_16x16x32_bf16 v[174:177], v[40:43], v[212:215], v[174:177]
	v_mfma_f32_16x16x32_bf16 v[178:181], v[44:47], v[212:215], v[178:181]
	v_mfma_f32_16x16x32_bf16 v[182:185], v[48:51], v[212:215], v[182:185]
	v_mfma_f32_16x16x32_bf16 v[104:107], v[52:55], v[212:215], v[104:107]
	s_waitcnt lgkmcnt(0)
	v_mfma_f32_16x16x32_bf16 v[16:19], v[40:43], v[216:219], v[16:19]
	v_mfma_f32_16x16x32_bf16 v[20:23], v[44:47], v[216:219], v[20:23]
	v_mfma_f32_16x16x32_bf16 v[24:27], v[48:51], v[216:219], v[24:27]
	v_mfma_f32_16x16x32_bf16 v[28:31], v[52:55], v[216:219], v[28:31]
	s_setprio 0
	s_barrier
	ds_write_b128 v11, v[64:67]
	ds_write_b128 v11, v[68:71] offset:4096
	ds_write_b128 v11, v[72:75] offset:8192
	ds_write_b128 v11, v[76:79] offset:12288
	ds_write_b128 v11, v[80:83] offset:16384
	ds_write_b128 v11, v[84:87] offset:20480
	ds_read_b128 v[40:43], v12 offset:40960
	ds_read_b128 v[44:47], v12 offset:41984
	ds_read_b128 v[48:51], v12 offset:43008
	ds_read_b128 v[52:55], v12 offset:44032
	ds_read_b128 v[64:67], v13 offset:26624
	ds_read_b128 v[68:71], v13 offset:27648
	ds_read_b128 v[72:75], v13 offset:28672
	ds_read_b128 v[76:79], v13 offset:29696
	ds_read_b128 v[80:83], v13 offset:24576
	ds_read_b128 v[84:87], v13 offset:30720
	ds_read_b128 v[186:189], v13 offset:25600
	ds_read_b128 v[190:193], v14 offset:24576
	s_setprio 1
	s_waitcnt lgkmcnt(3)
	v_mfma_f32_16x16x32_bf16 v[112:115], v[40:43], v[80:83], v[112:115]
	v_mfma_f32_16x16x32_bf16 v[116:119], v[44:47], v[80:83], v[116:119]
	v_mfma_f32_16x16x32_bf16 v[120:123], v[48:51], v[80:83], v[120:123]
	v_mfma_f32_16x16x32_bf16 v[56:59], v[52:55], v[80:83], v[56:59]
	s_waitcnt lgkmcnt(1)
	v_mfma_f32_16x16x32_bf16 v[80:83], v[40:43], v[186:189], v[124:127]
	v_mfma_f32_16x16x32_bf16 v[124:127], v[44:47], v[186:189], v[128:131]
	v_mfma_f32_16x16x32_bf16 v[128:131], v[48:51], v[186:189], v[132:135]
	v_mfma_f32_16x16x32_bf16 v[60:63], v[52:55], v[186:189], v[60:63]
	v_mfma_f32_16x16x32_bf16 v[132:135], v[40:43], v[64:67], v[138:141]
	v_mfma_f32_16x16x32_bf16 v[138:141], v[44:47], v[64:67], v[142:145]
	v_mfma_f32_16x16x32_bf16 v[142:145], v[48:51], v[64:67], v[146:149]
	v_mfma_f32_16x16x32_bf16 v[32:35], v[52:55], v[64:67], v[32:35]
	v_mfma_f32_16x16x32_bf16 v[64:67], v[40:43], v[68:71], v[88:91]
	v_mfma_f32_16x16x32_bf16 v[88:91], v[44:47], v[68:71], v[150:153]
	v_mfma_f32_16x16x32_bf16 v[146:149], v[48:51], v[68:71], v[154:157]
	v_mfma_f32_16x16x32_bf16 v[36:39], v[52:55], v[68:71], v[36:39]
	v_mfma_f32_16x16x32_bf16 v[68:71], v[40:43], v[72:75], v[92:95]
	v_mfma_f32_16x16x32_bf16 v[92:95], v[44:47], v[72:75], v[158:161]
	v_mfma_f32_16x16x32_bf16 v[150:153], v[48:51], v[72:75], v[162:165]
	v_mfma_f32_16x16x32_bf16 v[72:75], v[52:55], v[72:75], v[96:99]
	v_mfma_f32_16x16x32_bf16 v[96:99], v[40:43], v[76:79], v[108:111]
	v_mfma_f32_16x16x32_bf16 v[108:111], v[44:47], v[76:79], v[166:169]
	v_mfma_f32_16x16x32_bf16 v[154:157], v[48:51], v[76:79], v[170:173]
	v_mfma_f32_16x16x32_bf16 v[76:79], v[52:55], v[76:79], v[100:103]
	v_mfma_f32_16x16x32_bf16 v[100:103], v[40:43], v[84:87], v[174:177]
	v_mfma_f32_16x16x32_bf16 v[158:161], v[44:47], v[84:87], v[178:181]
	v_mfma_f32_16x16x32_bf16 v[162:165], v[48:51], v[84:87], v[182:185]
	v_mfma_f32_16x16x32_bf16 v[84:87], v[52:55], v[84:87], v[104:107]
	s_waitcnt lgkmcnt(0)
	v_mfma_f32_16x16x32_bf16 v[16:19], v[40:43], v[190:193], v[16:19]
	v_mfma_f32_16x16x32_bf16 v[20:23], v[44:47], v[190:193], v[20:23]
	v_mfma_f32_16x16x32_bf16 v[24:27], v[48:51], v[190:193], v[24:27]
	v_mfma_f32_16x16x32_bf16 v[28:31], v[52:55], v[190:193], v[28:31]
	s_setprio 0
	v_add_u32_e32 v40, s18, v9
	v_add_u32_e32 v42, s19, v10
	v_ashrrev_i32_e32 v41, 31, v40
	v_lshlrev_b64 v[44:45], 10, v[40:41]
	v_ashrrev_i32_e32 v43, 31, v42
	v_lshl_add_u64 v[44:45], s[0:1], 0, v[44:45]
	v_lshlrev_b64 v[42:43], 1, v[42:43]
	v_lshl_add_u64 v[44:45], v[44:45], 0, v[42:43]
	v_cvt_pk_bf16_f32 v46, v112, v113
	v_cvt_pk_bf16_f32 v47, v114, v115
	s_barrier
; DI unsigned pack2(float lo, float hi) { const f32x2c v = {lo, hi}; return __builtin_bit_cast(unsigned, __builtin_convertvector(v, bf16x2c)); }
; template <class Epi>
; DI void gemm_tile(char* smem, const bf16_t* __restrict__ A0, int lda0, int ksplit, const bf16_t* __restrict__ A1, int lda1,
;                   const bf16_t* __restrict__ Bt, int K, int row0, int col0, const Epi& epi, int tid) {
;     ...
; #pragma unroll
;   for (int m = 0; m < 8; ++m)
; #pragma unroll
;     for (int n = 0; n < 4; ++n) epi(row0 + wr * 128 + m * 16 + fr, col0 + wc * 64 + n * 16 + fq * 4, acc[m][n]);
; }
; DI void st_bf16x4(bf16_t* o, f32x4 v) { u32x2 q; q.x = pack2(v[0], v[1]); q.y = pack2(v[2], v[3]); *(u32x2*)o = q; }
;   DI void operator()(int row, int col, f32x4 v) const {
;     if (col < n0) st_bf16x4(o0 + (size_t)row * ld0 + col, v);
;     else { const int c = col - n0; if (c < n1) st_bf16x4(o1 + (size_t)row * ld1 + c, v); }
;   }
	global_store_dwordx2 v[44:45], v[46:47], off
	v_cvt_pk_bf16_f32 v46, v116, v117
	v_cvt_pk_bf16_f32 v47, v118, v119
	global_store_dwordx2 v[44:45], v[46:47], off offset:32
	v_cvt_pk_bf16_f32 v46, v120, v121
	v_cvt_pk_bf16_f32 v47, v122, v123
	global_store_dwordx2 v[44:45], v[46:47], off offset:64
	v_cvt_pk_bf16_f32 v46, v56, v57
	v_cvt_pk_bf16_f32 v47, v58, v59
	global_store_dwordx2 v[44:45], v[46:47], off offset:96
	v_or_b32_e32 v44, 16, v40
	v_ashrrev_i32_e32 v45, 31, v44
	v_lshlrev_b64 v[44:45], 10, v[44:45]
	v_lshl_add_u64 v[44:45], s[0:1], 0, v[44:45]
	v_lshl_add_u64 v[44:45], v[44:45], 0, v[42:43]
	v_cvt_pk_bf16_f32 v46, v80, v81
	v_cvt_pk_bf16_f32 v47, v82, v83
	global_store_dwordx2 v[44:45], v[46:47], off
	v_cvt_pk_bf16_f32 v46, v124, v125
	v_cvt_pk_bf16_f32 v47, v126, v127
	global_store_dwordx2 v[44:45], v[46:47], off offset:32
	v_cvt_pk_bf16_f32 v46, v128, v129
	v_cvt_pk_bf16_f32 v47, v130, v131
	global_store_dwordx2 v[44:45], v[46:47], off offset:64
	v_cvt_pk_bf16_f32 v46, v60, v61
	v_cvt_pk_bf16_f32 v47, v62, v63
	global_store_dwordx2 v[44:45], v[46:47], off offset:96
	v_or_b32_e32 v44, 32, v40
	v_ashrrev_i32_e32 v45, 31, v44
	v_lshlrev_b64 v[44:45], 10, v[44:45]
	v_lshl_add_u64 v[44:45], s[0:1], 0, v[44:45]
	v_lshl_add_u64 v[44:45], v[44:45], 0, v[42:43]
	v_cvt_pk_bf16_f32 v32, v32, v33
	v_cvt_pk_bf16_f32 v33, v34, v35
	global_store_dwordx2 v[44:45], v[32:33], off offset:96
	v_or_b32_e32 v32, 48, v40
	v_ashrrev_i32_e32 v33, 31, v32
	v_lshlrev_b64 v[32:33], 10, v[32:33]
	v_lshl_add_u64 v[32:33], s[0:1], 0, v[32:33]
	v_lshl_add_u64 v[32:33], v[32:33], 0, v[42:43]
	v_cvt_pk_bf16_f32 v34, v64, v65
	v_cvt_pk_bf16_f32 v35, v66, v67
	global_store_dwordx2 v[32:33], v[34:35], off
	v_cvt_pk_bf16_f32 v34, v88, v89
	v_cvt_pk_bf16_f32 v35, v90, v91
	global_store_dwordx2 v[32:33], v[34:35], off offset:32
	v_cvt_pk_bf16_f32 v34, v146, v147
	v_cvt_pk_bf16_f32 v35, v148, v149
	global_store_dwordx2 v[32:33], v[34:35], off offset:64
	v_cvt_pk_bf16_f32 v34, v36, v37
	v_cvt_pk_bf16_f32 v35, v38, v39
	global_store_dwordx2 v[32:33], v[34:35], off offset:96
	v_or_b32_e32 v32, 64, v40
	v_ashrrev_i32_e32 v33, 31, v32
	v_lshlrev_b64 v[32:33], 10, v[32:33]
	v_lshl_add_u64 v[32:33], s[0:1], 0, v[32:33]
	v_lshl_add_u64 v[32:33], v[32:33], 0, v[42:43]
	v_cvt_pk_bf16_f32 v34, v68, v69
	v_cvt_pk_bf16_f32 v35, v70, v71
	global_store_dwordx2 v[32:33], v[34:35], off
	v_cvt_pk_bf16_f32 v34, v92, v93
	v_cvt_pk_bf16_f32 v35, v94, v95
	global_store_dwordx2 v[32:33], v[34:35], off offset:32
	v_cvt_pk_bf16_f32 v34, v150, v151
	v_cvt_pk_bf16_f32 v35, v152, v153
	global_store_dwordx2 v[32:33], v[34:35], off offset:64
	v_cvt_pk_bf16_f32 v34, v72, v73
	v_cvt_pk_bf16_f32 v35, v74, v75
	global_store_dwordx2 v[32:33], v[34:35], off offset:96
	v_or_b32_e32 v32, 0x50, v40
	v_ashrrev_i32_e32 v33, 31, v32
	v_lshlrev_b64 v[32:33], 10, v[32:33]
	v_lshl_add_u64 v[32:33], s[0:1], 0, v[32:33]
	v_lshl_add_u64 v[32:33], v[32:33], 0, v[42:43]
	v_cvt_pk_bf16_f32 v34, v96, v97
	v_cvt_pk_bf16_f32 v35, v98, v99
	global_store_dwordx2 v[32:33], v[34:35], off
	v_cvt_pk_bf16_f32 v34, v108, v109
	v_cvt_pk_bf16_f32 v35, v110, v111
	global_store_dwordx2 v[32:33], v[34:35], off offset:32
	v_cvt_pk_bf16_f32 v34, v154, v155
	v_cvt_pk_bf16_f32 v35, v156, v157
	global_store_dwordx2 v[32:33], v[34:35], off offset:64
	v_cvt_pk_bf16_f32 v34, v76, v77
	v_cvt_pk_bf16_f32 v35, v78, v79
	global_store_dwordx2 v[32:33], v[34:35], off offset:96
	v_or_b32_e32 v32, 0x60, v40
	v_ashrrev_i32_e32 v33, 31, v32
	v_lshlrev_b64 v[32:33], 10, v[32:33]
	v_lshl_add_u64 v[32:33], s[0:1], 0, v[32:33]
	v_lshl_add_u64 v[32:33], v[32:33], 0, v[42:43]
	v_cvt_pk_bf16_f32 v34, v100, v101
	v_cvt_pk_bf16_f32 v35, v102, v103
	global_store_dwordx2 v[32:33], v[34:35], off
	v_cvt_pk_bf16_f32 v34, v158, v159
	v_cvt_pk_bf16_f32 v35, v160, v161
	global_store_dwordx2 v[32:33], v[34:35], off offset:32
	v_cvt_pk_bf16_f32 v34, v162, v163
	v_cvt_pk_bf16_f32 v35, v164, v165
	global_store_dwordx2 v[32:33], v[34:35], off offset:64
	v_cvt_pk_bf16_f32 v34, v84, v85
	v_cvt_pk_bf16_f32 v35, v86, v87
	global_store_dwordx2 v[32:33], v[34:35], off offset:96
	v_or_b32_e32 v32, 0x70, v40
	v_ashrrev_i32_e32 v33, 31, v32
	v_lshlrev_b64 v[32:33], 10, v[32:33]
	v_lshl_add_u64 v[32:33], s[0:1], 0, v[32:33]
	v_lshl_add_u64 v[32:33], v[32:33], 0, v[42:43]
	v_cvt_pk_bf16_f32 v16, v16, v17
	v_cvt_pk_bf16_f32 v17, v18, v19
	v_cvt_pk_bf16_f32 v46, v132, v133
	v_cvt_pk_bf16_f32 v47, v134, v135
	global_store_dwordx2 v[32:33], v[16:17], off
	v_cvt_pk_bf16_f32 v16, v20, v21
	v_cvt_pk_bf16_f32 v17, v22, v23
	global_store_dwordx2 v[44:45], v[46:47], off
	v_cvt_pk_bf16_f32 v46, v138, v139
	v_cvt_pk_bf16_f32 v47, v140, v141
	global_store_dwordx2 v[32:33], v[16:17], off offset:32
	v_cvt_pk_bf16_f32 v16, v24, v25
	v_cvt_pk_bf16_f32 v17, v26, v27
	s_add_i32 s17, s17, s12
	s_add_i32 s15, s15, s16
	global_store_dwordx2 v[44:45], v[46:47], off offset:32
	v_cvt_pk_bf16_f32 v46, v142, v143
	v_cvt_pk_bf16_f32 v47, v144, v145
	global_store_dwordx2 v[32:33], v[16:17], off offset:64
	v_cvt_pk_bf16_f32 v16, v28, v29
	v_cvt_pk_bf16_f32 v17, v30, v31
	s_cmpk_lt_i32 s17, 0x200
	global_store_dwordx2 v[44:45], v[46:47], off offset:64
	global_store_dwordx2 v[32:33], v[16:17], off offset:96
	s_cbranch_scc1 .LBB0_580

; #define LWRITE(S, buf) do { bf16_t* sA_ = sbase + (buf) * BUF; bf16_t* sB_ = sA_ + 256 * PITCH; \
;     _Pragma("unroll") for (int i_ = 0; i_ < 4; ++i_) *(u32x4*)(sA_ + (sr + i_ * 64) * PITCH + scv * 8) = ra[S][i_]; \
;     _Pragma("unroll") for (int i_ = 0; i_ < 2; ++i_) *(u32x4*)(sB_ + (sr + i_ * 64) * PITCH + scv * 8) = rb[S][i_]; } while (0)
; template <class Epi>
; DI void gemm_tile(char* smem, const bf16_t* __restrict__ A0, int lda0, int ksplit, const bf16_t* __restrict__ A1, int lda1,
;                   const bf16_t* __restrict__ Bt, int K, int row0, int col0, const Epi& epi, int tid) {
;   constexpr int BK = 32, PITCH = 40, BUF = (256 + 128) * PITCH;
;   bf16_t* sbase = (bf16_t*)smem;
;   const int lane = tid & 63, wid = tid >> 6, wr = wid >> 1, wc = wid & 1, fr = lane & 15, fq = lane >> 4;
;   f32x4 acc[8][4];
; #pragma unroll
;   for (int m = 0; m < 8; ++m)
; #pragma unroll
;     for (int n = 0; n < 4; ++n) acc[m][n] = (f32x4){0.f, 0.f, 0.f, 0.f};
;   u32x4 ra[2][4], rb[2][2];
;   const int nk = K / BK;
;   const int sr = tid >> 2, scv = tid & 3;
;     ...
;   __syncthreads();
;   {
;     const int last = nk - 1;
;     GLOAD(0, 0);
;     __builtin_amdgcn_sched_barrier(0);
;     GLOAD(1, 1);
;     __builtin_amdgcn_sched_barrier(0);
;     LWRITE(0, 0);
;     __builtin_amdgcn_sched_barrier(0);
;     GLOAD(0, (2 < last ? 2 : last));
;     __builtin_amdgcn_sched_barrier(0);
;     __syncthreads();
;     for (int kt = 0; kt < nk; kt += 2) {
;       LWRITE(1, 1);
;       __builtin_amdgcn_sched_barrier(0);
;       GLOAD(1, (kt + 3 < last ? kt + 3 : last));
;       __builtin_amdgcn_sched_barrier(0);
;       COMPUTE(0);
; template <class Epi>
; DI void gemm_phase(char* smem, const bf16_t* A0, int lda0, int ksplit, const bf16_t* A1, int lda1, const bf16_t* Bt, int K, int nN, const Epi& epi, int tid) {
;     ...
;   if ((G & 7) == 0) {
;     const int x = blockIdx.x & 7, l = blockIdx.x >> 3, L = G >> 3, per = 8 * nN, tot = 2 * per;
;     for (int q = l; q < tot; q += L) { const int rgl = q / per, rem = q % per, ct = rem >> 3, rt = (x * 2 + rgl) * 8 + (rem & 7);
;       gemm_tile(smem, A0, lda0, ksplit, A1, lda1, Bt, K, rt * 256, ct * 128, epi, tid); }
.LBB0_582:
.LBB0_583:
	s_cmpk_gt_u32 s96, 0x1ff
	s_cbranch_scc1 .LBB0_586
	v_and_b32_e32 v0, 3, v136
	s_lshl_b32 s2, s96, 1
	v_lshlrev_b32_e32 v4, 4, v0
	v_mov_b32_e32 v5, 0
	s_and_b32 s15, s2, 14
	v_ashrrev_i32_e32 v8, 2, v137
	v_lshl_add_u64 v[2:3], s[4:5], 0, v[4:5]
	v_bfe_u32 v10, v136, 4, 2
	s_movk_i32 s4, 0x40
	v_lshl_add_u64 v[6:7], s[92:93], 0, v[4:5]
	s_mov_b64 s[2:3], 0x1ea00180
	v_and_b32_e32 v14, 0x4f, v137
	v_and_b32_e32 v9, 0xffffff8f, v137
	v_or_b32_e32 v17, 0x70, v137
	s_ashr_i32 s10, s12, 3
	s_lshr_b32 s11, s96, 3
	v_lshl_add_u64 v[0:1], s[6:7], 0, v[4:5]
	v_add_u32_e32 v11, 0, v4
	v_mul_lo_u32 v12, v8, s4
	v_lshl_add_u64 v[4:5], v[6:7], 0, s[2:3]
	s_mov_b64 s[2:3], 0x3480080
	v_and_b32_e32 v13, 64, v137
	v_lshl_add_u32 v15, v10, 4, 0
	v_mul_u32_u24_e32 v14, 0x40, v14
	v_mul_lo_u32 v16, v9, s4
	v_mul_lo_u32 v17, v17, s4
	v_lshl_add_u64 v[6:7], v[6:7], 0, s[2:3]
	v_lshl_or_b32 v10, v10, 2, v13
	s_waitcnt lgkmcnt(0)
	s_lshl_b32 s16, s11, 8
	s_lshl_b32 s17, s10, 8
	s_lshl_b32 s18, s11, 4
	s_lshl_b32 s19, s10, 4
	s_mov_b64 s[2:3], 0x8000
	s_mov_b64 s[4:5], 0x10000
	s_mov_b64 s[6:7], 0x18000
	s_mov_b64 s[8:9], 0x4000
	v_add_u32_e32 v11, v11, v12
	v_add_u32_e32 v12, v15, v14
	v_add_u32_e32 v13, v15, v16
	v_add_u32_e32 v14, v15, v17
	v_mbcnt_lo_u32_b32 v16, -1, 0
	v_mbcnt_hi_u32_b32 v16, -1, v16
	v_bfe_u32 v17, v16, 3, 1
	v_bfe_u32 v16, v16, 5, 1
	v_mul_u32_u24_e32 v17, 48, v17
	v_mul_u32_u24_e32 v16, 48, v16
	v_xor_b32_e32 v11, v11, v16
	v_xor_b32_e32 v12, v12, v17
	v_xor_b32_e32 v13, v13, v17
	v_xor_b32_e32 v14, v14, v17
.LBB0_585:
	s_ashr_i32 s20, s11, 31
	s_lshr_b32 s20, s20, 27
	s_add_i32 s20, s11, s20
	s_ashr_i32 s21, s20, 5
	s_add_i32 s20, s21, s15
	s_lshl_b32 s20, s20, 11
	s_and_b32 s22, s16, 0x700
	s_lshl_b32 s21, s21, 9
	s_or_b32 s20, s20, s22
	s_sub_i32 s21, s18, s21
	s_and_b32 s21, s21, 0xffffff80
	v_add_u32_e32 v16, s20, v8
	v_ashrrev_i32_e32 v17, 31, v16
	v_add_u32_e32 v32, s21, v8
	v_lshlrev_b64 v[64:65], 9, v[16:17]
	v_ashrrev_i32_e32 v33, 31, v32
	v_lshl_add_u64 v[72:73], v[64:65], 0, s[4:5]
	v_lshlrev_b64 v[80:81], 8, v[32:33]
	v_lshl_add_u64 v[66:67], v[0:1], 0, v[64:65]
	v_lshl_add_u64 v[68:69], v[64:65], 0, s[2:3]
	v_lshl_add_u64 v[74:75], v[0:1], 0, v[72:73]
	v_lshl_add_u64 v[76:77], v[64:65], 0, s[6:7]
	v_lshl_add_u64 v[82:83], v[2:3], 0, v[80:81]
	v_lshl_add_u64 v[84:85], v[80:81], 0, s[8:9]
	s_barrier
	v_lshl_add_u64 v[70:71], v[0:1], 0, v[68:69]
	global_load_dwordx4 v[16:19], v[66:67], off
	global_load_dwordx4 v[20:23], v[70:71], off
	v_lshl_add_u64 v[78:79], v[0:1], 0, v[76:77]
	global_load_dwordx4 v[24:27], v[74:75], off
	global_load_dwordx4 v[28:31], v[78:79], off
	v_lshl_add_u64 v[86:87], v[2:3], 0, v[84:85]
	global_load_dwordx4 v[32:35], v[82:83], off
	global_load_dwordx4 v[36:39], v[86:87], off
	global_load_dwordx4 v[40:43], v[66:67], off offset:64
	global_load_dwordx4 v[44:47], v[70:71], off offset:64
	global_load_dwordx4 v[48:51], v[74:75], off offset:64
	global_load_dwordx4 v[52:55], v[78:79], off offset:64
	global_load_dwordx4 v[56:59], v[82:83], off offset:64
	global_load_dwordx4 v[60:63], v[86:87], off offset:64
	s_waitcnt vmcnt(11)
	ds_write_b128 v11, v[16:19]
	s_waitcnt vmcnt(10)
	ds_write_b128 v11, v[20:23] offset:4096
	s_waitcnt vmcnt(9)
	ds_write_b128 v11, v[24:27] offset:8192
	s_waitcnt vmcnt(8)
	ds_write_b128 v11, v[28:31] offset:12288
	s_waitcnt vmcnt(7)
	ds_write_b128 v11, v[32:35] offset:16384
	s_waitcnt vmcnt(6)
	ds_write_b128 v11, v[36:39] offset:20480
	v_lshl_add_u64 v[16:17], v[4:5], 0, v[64:65]
	v_lshl_add_u64 v[20:21], v[4:5], 0, v[68:69]
	v_lshl_add_u64 v[24:25], v[4:5], 0, v[72:73]
	v_lshl_add_u64 v[28:29], v[4:5], 0, v[76:77]
	v_lshl_add_u64 v[32:33], v[6:7], 0, v[80:81]
	v_lshl_add_u64 v[36:37], v[6:7], 0, v[84:85]
	global_load_dwordx4 v[16:19], v[16:17], off
	s_nop 0
	global_load_dwordx4 v[20:23], v[20:21], off
	s_nop 0
	global_load_dwordx4 v[24:27], v[24:25], off
	s_nop 0
	global_load_dwordx4 v[28:31], v[28:29], off
	s_nop 0
	global_load_dwordx4 v[32:35], v[32:33], off
	s_nop 0
	global_load_dwordx4 v[36:39], v[36:37], off
	s_waitcnt lgkmcnt(0)
	s_barrier
	global_load_dwordx4 v[64:67], v[66:67], off offset:192
	s_nop 0
	global_load_dwordx4 v[68:71], v[70:71], off offset:192
	s_nop 0
	global_load_dwordx4 v[72:75], v[74:75], off offset:192
	s_nop 0
	global_load_dwordx4 v[76:79], v[78:79], off offset:192
	s_nop 0
	global_load_dwordx4 v[80:83], v[82:83], off offset:192
	s_nop 0
	global_load_dwordx4 v[84:87], v[86:87], off offset:192
	s_waitcnt vmcnt(17)
	ds_write_b128 v11, v[40:43] offset:24576
	s_waitcnt vmcnt(16)
	ds_write_b128 v11, v[44:47] offset:28672
	s_waitcnt vmcnt(15)
	ds_write_b128 v11, v[48:51] offset:32768
	s_waitcnt vmcnt(14)
	ds_write_b128 v11, v[52:55] offset:36864
	s_waitcnt vmcnt(13)
	ds_write_b128 v11, v[56:59] offset:40960
	s_waitcnt vmcnt(12)
	ds_write_b128 v11, v[60:63] offset:45056
	ds_read_b128 v[40:43], v12 offset:16384
	ds_read_b128 v[44:47], v12 offset:17408
	ds_read_b128 v[48:51], v12 offset:18432
	ds_read_b128 v[52:55], v12 offset:19456
	ds_read_b128 v[56:59], v13
	ds_read_b128 v[60:63], v13 offset:1024
	ds_read_b128 v[88:91], v13 offset:2048
	ds_read_b128 v[92:95], v13 offset:3072
	ds_read_b128 v[96:99], v13 offset:4096
	ds_read_b128 v[100:103], v13 offset:5120
	ds_read_b128 v[104:107], v13 offset:6144
	ds_read_b128 v[108:111], v14
	s_setprio 1
	s_waitcnt lgkmcnt(7)
	v_mfma_f32_16x16x32_bf16 v[112:115], v[40:43], v[56:59], 0
	v_mfma_f32_16x16x32_bf16 v[116:119], v[44:47], v[56:59], 0
	v_mfma_f32_16x16x32_bf16 v[120:123], v[48:51], v[56:59], 0
	v_mfma_f32_16x16x32_bf16 v[56:59], v[52:55], v[56:59], 0
	s_waitcnt lgkmcnt(6)
; #define LWRITE(S, buf) do { bf16_t* sA_ = sbase + (buf) * BUF; bf16_t* sB_ = sA_ + 256 * PITCH; \
;     _Pragma("unroll") for (int i_ = 0; i_ < 4; ++i_) *(u32x4*)(sA_ + (sr + i_ * 64) * PITCH + scv * 8) = ra[S][i_]; \
;     _Pragma("unroll") for (int i_ = 0; i_ < 2; ++i_) *(u32x4*)(sB_ + (sr + i_ * 64) * PITCH + scv * 8) = rb[S][i_]; } while (0)
; template <class Epi>
; DI void gemm_tile(char* smem, const bf16_t* __restrict__ A0, int lda0, int ksplit, const bf16_t* __restrict__ A1, int lda1,
;                   const bf16_t* __restrict__ Bt, int K, int row0, int col0, const Epi& epi, int tid) {
;     ...
;   __syncthreads();
;   {
;     const int last = nk - 1;
;     GLOAD(0, 0);
;     __builtin_amdgcn_sched_barrier(0);
;     GLOAD(1, 1);
;     __builtin_amdgcn_sched_barrier(0);
;     LWRITE(0, 0);
;     __builtin_amdgcn_sched_barrier(0);
;     GLOAD(0, (2 < last ? 2 : last));
;     __builtin_amdgcn_sched_barrier(0);
;     __syncthreads();
;     for (int kt = 0; kt < nk; kt += 2) {
;       LWRITE(1, 1);
;       __builtin_amdgcn_sched_barrier(0);
;       GLOAD(1, (kt + 3 < last ? kt + 3 : last));
;       __builtin_amdgcn_sched_barrier(0);
;       COMPUTE(0);
;       __syncthreads();
;       LWRITE(0, 0);
	v_mfma_f32_16x16x32_bf16 v[124:127], v[40:43], v[60:63], 0
	v_mfma_f32_16x16x32_bf16 v[128:131], v[44:47], v[60:63], 0
	v_mfma_f32_16x16x32_bf16 v[132:135], v[48:51], v[60:63], 0
	v_mfma_f32_16x16x32_bf16 v[60:63], v[52:55], v[60:63], 0
	s_waitcnt lgkmcnt(5)
	v_mfma_f32_16x16x32_bf16 v[138:141], v[40:43], v[88:91], 0
	v_mfma_f32_16x16x32_bf16 v[142:145], v[44:47], v[88:91], 0
	v_mfma_f32_16x16x32_bf16 v[146:149], v[48:51], v[88:91], 0
	v_mfma_f32_16x16x32_bf16 v[88:91], v[52:55], v[88:91], 0
	s_waitcnt lgkmcnt(4)
	v_mfma_f32_16x16x32_bf16 v[150:153], v[40:43], v[92:95], 0
	v_mfma_f32_16x16x32_bf16 v[154:157], v[44:47], v[92:95], 0
	v_mfma_f32_16x16x32_bf16 v[158:161], v[48:51], v[92:95], 0
	v_mfma_f32_16x16x32_bf16 v[92:95], v[52:55], v[92:95], 0
	s_waitcnt lgkmcnt(3)
	v_mfma_f32_16x16x32_bf16 v[162:165], v[40:43], v[96:99], 0
	v_mfma_f32_16x16x32_bf16 v[166:169], v[44:47], v[96:99], 0
	v_mfma_f32_16x16x32_bf16 v[170:173], v[48:51], v[96:99], 0
	v_mfma_f32_16x16x32_bf16 v[96:99], v[52:55], v[96:99], 0
	s_waitcnt lgkmcnt(2)
	v_mfma_f32_16x16x32_bf16 v[174:177], v[40:43], v[100:103], 0
	v_mfma_f32_16x16x32_bf16 v[178:181], v[44:47], v[100:103], 0
	v_mfma_f32_16x16x32_bf16 v[182:185], v[48:51], v[100:103], 0
	v_mfma_f32_16x16x32_bf16 v[100:103], v[52:55], v[100:103], 0
	s_waitcnt lgkmcnt(1)
	v_mfma_f32_16x16x32_bf16 v[186:189], v[40:43], v[104:107], 0
	v_mfma_f32_16x16x32_bf16 v[190:193], v[44:47], v[104:107], 0
	v_mfma_f32_16x16x32_bf16 v[196:199], v[48:51], v[104:107], 0
	v_mfma_f32_16x16x32_bf16 v[104:107], v[52:55], v[104:107], 0
	s_waitcnt lgkmcnt(0)
	v_mfma_f32_16x16x32_bf16 v[40:43], v[40:43], v[108:111], 0
	v_mfma_f32_16x16x32_bf16 v[44:47], v[44:47], v[108:111], 0
	v_mfma_f32_16x16x32_bf16 v[48:51], v[48:51], v[108:111], 0
	v_mfma_f32_16x16x32_bf16 v[52:55], v[52:55], v[108:111], 0
	s_setprio 0
	s_barrier
	s_waitcnt vmcnt(11)
	ds_write_b128 v11, v[16:19]
	s_waitcnt vmcnt(10)
	ds_write_b128 v11, v[20:23] offset:4096
	s_waitcnt vmcnt(9)
	ds_write_b128 v11, v[24:27] offset:8192
	s_waitcnt vmcnt(8)
	ds_write_b128 v11, v[28:31] offset:12288
	s_waitcnt vmcnt(7)
	ds_write_b128 v11, v[32:35] offset:16384
	s_waitcnt vmcnt(6)
	ds_write_b128 v11, v[36:39] offset:20480
	ds_read_b128 v[16:19], v12 offset:40960
	ds_read_b128 v[20:23], v12 offset:41984
	ds_read_b128 v[24:27], v12 offset:43008
	ds_read_b128 v[28:31], v12 offset:44032
	ds_read_b128 v[32:35], v13 offset:26624
	ds_read_b128 v[36:39], v13 offset:27648
	ds_read_b128 v[108:111], v13 offset:28672
	ds_read_b128 v[200:203], v13 offset:29696
	ds_read_b128 v[204:207], v13 offset:24576
	ds_read_b128 v[208:211], v13 offset:30720
	ds_read_b128 v[212:215], v13 offset:25600
	ds_read_b128 v[216:219], v14 offset:24576
	s_setprio 1
	s_waitcnt lgkmcnt(3)
	v_mfma_f32_16x16x32_bf16 v[112:115], v[16:19], v[204:207], v[112:115]
	v_mfma_f32_16x16x32_bf16 v[116:119], v[20:23], v[204:207], v[116:119]
	v_mfma_f32_16x16x32_bf16 v[120:123], v[24:27], v[204:207], v[120:123]
	v_mfma_f32_16x16x32_bf16 v[56:59], v[28:31], v[204:207], v[56:59]
	s_waitcnt lgkmcnt(1)
	v_mfma_f32_16x16x32_bf16 v[124:127], v[16:19], v[212:215], v[124:127]
	v_mfma_f32_16x16x32_bf16 v[128:131], v[20:23], v[212:215], v[128:131]
	v_mfma_f32_16x16x32_bf16 v[132:135], v[24:27], v[212:215], v[132:135]
	v_mfma_f32_16x16x32_bf16 v[60:63], v[28:31], v[212:215], v[60:63]
	v_mfma_f32_16x16x32_bf16 v[138:141], v[16:19], v[32:35], v[138:141]
	v_mfma_f32_16x16x32_bf16 v[142:145], v[20:23], v[32:35], v[142:145]
	v_mfma_f32_16x16x32_bf16 v[146:149], v[24:27], v[32:35], v[146:149]
	v_mfma_f32_16x16x32_bf16 v[32:35], v[28:31], v[32:35], v[88:91]
	v_mfma_f32_16x16x32_bf16 v[88:91], v[16:19], v[36:39], v[150:153]
	v_mfma_f32_16x16x32_bf16 v[150:153], v[20:23], v[36:39], v[154:157]
	v_mfma_f32_16x16x32_bf16 v[154:157], v[24:27], v[36:39], v[158:161]
	v_mfma_f32_16x16x32_bf16 v[36:39], v[28:31], v[36:39], v[92:95]
	v_mfma_f32_16x16x32_bf16 v[92:95], v[16:19], v[108:111], v[162:165]
	v_mfma_f32_16x16x32_bf16 v[158:161], v[20:23], v[108:111], v[166:169]
	v_mfma_f32_16x16x32_bf16 v[162:165], v[24:27], v[108:111], v[170:173]
	v_mfma_f32_16x16x32_bf16 v[96:99], v[28:31], v[108:111], v[96:99]
	v_mfma_f32_16x16x32_bf16 v[108:111], v[16:19], v[200:203], v[174:177]
	v_mfma_f32_16x16x32_bf16 v[166:169], v[20:23], v[200:203], v[178:181]
	v_mfma_f32_16x16x32_bf16 v[170:173], v[24:27], v[200:203], v[182:185]
	v_mfma_f32_16x16x32_bf16 v[100:103], v[28:31], v[200:203], v[100:103]
	v_mfma_f32_16x16x32_bf16 v[174:177], v[16:19], v[208:211], v[186:189]
	v_mfma_f32_16x16x32_bf16 v[178:181], v[20:23], v[208:211], v[190:193]
	v_mfma_f32_16x16x32_bf16 v[182:185], v[24:27], v[208:211], v[196:199]
	v_mfma_f32_16x16x32_bf16 v[104:107], v[28:31], v[208:211], v[104:107]
	s_waitcnt lgkmcnt(0)
	v_mfma_f32_16x16x32_bf16 v[16:19], v[16:19], v[216:219], v[40:43]
	v_mfma_f32_16x16x32_bf16 v[20:23], v[20:23], v[216:219], v[44:47]
	v_mfma_f32_16x16x32_bf16 v[24:27], v[24:27], v[216:219], v[48:51]
	v_mfma_f32_16x16x32_bf16 v[28:31], v[28:31], v[216:219], v[52:55]
	s_setprio 0
	s_barrier
; #define LWRITE(S, buf) do { bf16_t* sA_ = sbase + (buf) * BUF; bf16_t* sB_ = sA_ + 256 * PITCH; \
;     _Pragma("unroll") for (int i_ = 0; i_ < 4; ++i_) *(u32x4*)(sA_ + (sr + i_ * 64) * PITCH + scv * 8) = ra[S][i_]; \
;     _Pragma("unroll") for (int i_ = 0; i_ < 2; ++i_) *(u32x4*)(sB_ + (sr + i_ * 64) * PITCH + scv * 8) = rb[S][i_]; } while (0)
; template <class Epi>
; DI void gemm_tile(char* smem, const bf16_t* __restrict__ A0, int lda0, int ksplit, const bf16_t* __restrict__ A1, int lda1,
;                   const bf16_t* __restrict__ Bt, int K, int row0, int col0, const Epi& epi, int tid) {
;     ...
;   __syncthreads();
;   {
;     const int last = nk - 1;
;     GLOAD(0, 0);
;     __builtin_amdgcn_sched_barrier(0);
;     GLOAD(1, 1);
;     __builtin_amdgcn_sched_barrier(0);
;     LWRITE(0, 0);
;     __builtin_amdgcn_sched_barrier(0);
;     GLOAD(0, (2 < last ? 2 : last));
;     __builtin_amdgcn_sched_barrier(0);
;     __syncthreads();
;     for (int kt = 0; kt < nk; kt += 2) {
;       LWRITE(1, 1);
;       __builtin_amdgcn_sched_barrier(0);
;       GLOAD(1, (kt + 3 < last ? kt + 3 : last));
;       __builtin_amdgcn_sched_barrier(0);
;       COMPUTE(0);
;       __syncthreads();
;       LWRITE(0, 0);
;       __builtin_amdgcn_sched_barrier(0);
;       GLOAD(0, (kt + 4 < last ? kt + 4 : last));
;       __builtin_amdgcn_sched_barrier(0);
;       COMPUTE(1);
;       __syncthreads();
;     }
	s_waitcnt vmcnt(5)
	ds_write_b128 v11, v[64:67] offset:24576
	s_waitcnt vmcnt(4)
	ds_write_b128 v11, v[68:71] offset:28672
	s_waitcnt vmcnt(3)
	ds_write_b128 v11, v[72:75] offset:32768
	s_waitcnt vmcnt(2)
	ds_write_b128 v11, v[76:79] offset:36864
	s_waitcnt vmcnt(1)
	ds_write_b128 v11, v[80:83] offset:40960
	s_waitcnt vmcnt(0)
	ds_write_b128 v11, v[84:87] offset:45056
	ds_read_b128 v[40:43], v12 offset:16384
	ds_read_b128 v[44:47], v12 offset:17408
	ds_read_b128 v[48:51], v12 offset:18432
	ds_read_b128 v[52:55], v12 offset:19456
	ds_read_b128 v[186:189], v13
	ds_read_b128 v[190:193], v13 offset:1024
	ds_read_b128 v[196:199], v13 offset:2048
	ds_read_b128 v[200:203], v13 offset:3072
	ds_read_b128 v[204:207], v13 offset:4096
	ds_read_b128 v[208:211], v13 offset:5120
	ds_read_b128 v[212:215], v13 offset:6144
	ds_read_b128 v[216:219], v14
	s_setprio 1
	s_waitcnt lgkmcnt(7)
	v_mfma_f32_16x16x32_bf16 v[112:115], v[40:43], v[186:189], v[112:115]
	v_mfma_f32_16x16x32_bf16 v[116:119], v[44:47], v[186:189], v[116:119]
	v_mfma_f32_16x16x32_bf16 v[120:123], v[48:51], v[186:189], v[120:123]
	v_mfma_f32_16x16x32_bf16 v[56:59], v[52:55], v[186:189], v[56:59]
	s_waitcnt lgkmcnt(6)
	v_mfma_f32_16x16x32_bf16 v[124:127], v[40:43], v[190:193], v[124:127]
	v_mfma_f32_16x16x32_bf16 v[128:131], v[44:47], v[190:193], v[128:131]
	v_mfma_f32_16x16x32_bf16 v[132:135], v[48:51], v[190:193], v[132:135]
	v_mfma_f32_16x16x32_bf16 v[60:63], v[52:55], v[190:193], v[60:63]
	s_waitcnt lgkmcnt(5)
	v_mfma_f32_16x16x32_bf16 v[138:141], v[40:43], v[196:199], v[138:141]
	v_mfma_f32_16x16x32_bf16 v[142:145], v[44:47], v[196:199], v[142:145]
	v_mfma_f32_16x16x32_bf16 v[146:149], v[48:51], v[196:199], v[146:149]
	v_mfma_f32_16x16x32_bf16 v[32:35], v[52:55], v[196:199], v[32:35]
	s_waitcnt lgkmcnt(4)
	v_mfma_f32_16x16x32_bf16 v[88:91], v[40:43], v[200:203], v[88:91]
	v_mfma_f32_16x16x32_bf16 v[150:153], v[44:47], v[200:203], v[150:153]
	v_mfma_f32_16x16x32_bf16 v[154:157], v[48:51], v[200:203], v[154:157]
	v_mfma_f32_16x16x32_bf16 v[36:39], v[52:55], v[200:203], v[36:39]
	s_waitcnt lgkmcnt(3)
	v_mfma_f32_16x16x32_bf16 v[92:95], v[40:43], v[204:207], v[92:95]
	v_mfma_f32_16x16x32_bf16 v[158:161], v[44:47], v[204:207], v[158:161]
	v_mfma_f32_16x16x32_bf16 v[162:165], v[48:51], v[204:207], v[162:165]
	v_mfma_f32_16x16x32_bf16 v[96:99], v[52:55], v[204:207], v[96:99]
	s_waitcnt lgkmcnt(2)
	v_mfma_f32_16x16x32_bf16 v[108:111], v[40:43], v[208:211], v[108:111]
	v_mfma_f32_16x16x32_bf16 v[166:169], v[44:47], v[208:211], v[166:169]
	v_mfma_f32_16x16x32_bf16 v[170:173], v[48:51], v[208:211], v[170:173]
	v_mfma_f32_16x16x32_bf16 v[100:103], v[52:55], v[208:211], v[100:103]
	s_waitcnt lgkmcnt(1)
	v_mfma_f32_16x16x32_bf16 v[174:177], v[40:43], v[212:215], v[174:177]
	v_mfma_f32_16x16x32_bf16 v[178:181], v[44:47], v[212:215], v[178:181]
	v_mfma_f32_16x16x32_bf16 v[182:185], v[48:51], v[212:215], v[182:185]
	v_mfma_f32_16x16x32_bf16 v[104:107], v[52:55], v[212:215], v[104:107]
	s_waitcnt lgkmcnt(0)
	v_mfma_f32_16x16x32_bf16 v[16:19], v[40:43], v[216:219], v[16:19]
	v_mfma_f32_16x16x32_bf16 v[20:23], v[44:47], v[216:219], v[20:23]
	v_mfma_f32_16x16x32_bf16 v[24:27], v[48:51], v[216:219], v[24:27]
	v_mfma_f32_16x16x32_bf16 v[28:31], v[52:55], v[216:219], v[28:31]
	s_setprio 0
	s_barrier
	ds_write_b128 v11, v[64:67]
	ds_write_b128 v11, v[68:71] offset:4096
	ds_write_b128 v11, v[72:75] offset:8192
	ds_write_b128 v11, v[76:79] offset:12288
	ds_write_b128 v11, v[80:83] offset:16384
	ds_write_b128 v11, v[84:87] offset:20480
	ds_read_b128 v[40:43], v12 offset:40960
	ds_read_b128 v[44:47], v12 offset:41984
	ds_read_b128 v[48:51], v12 offset:43008
	ds_read_b128 v[52:55], v12 offset:44032
	ds_read_b128 v[64:67], v13 offset:26624
	ds_read_b128 v[68:71], v13 offset:27648
	ds_read_b128 v[72:75], v13 offset:28672
	ds_read_b128 v[76:79], v13 offset:29696
	ds_read_b128 v[80:83], v13 offset:24576
	ds_read_b128 v[84:87], v13 offset:30720
	ds_read_b128 v[186:189], v13 offset:25600
	ds_read_b128 v[190:193], v14 offset:24576
	s_setprio 1
	s_waitcnt lgkmcnt(3)
	v_mfma_f32_16x16x32_bf16 v[112:115], v[40:43], v[80:83], v[112:115]
	v_mfma_f32_16x16x32_bf16 v[116:119], v[44:47], v[80:83], v[116:119]
	v_mfma_f32_16x16x32_bf16 v[120:123], v[48:51], v[80:83], v[120:123]
	v_mfma_f32_16x16x32_bf16 v[56:59], v[52:55], v[80:83], v[56:59]
	s_waitcnt lgkmcnt(1)
	v_mfma_f32_16x16x32_bf16 v[80:83], v[40:43], v[186:189], v[124:127]
	v_mfma_f32_16x16x32_bf16 v[124:127], v[44:47], v[186:189], v[128:131]
	v_mfma_f32_16x16x32_bf16 v[128:131], v[48:51], v[186:189], v[132:135]
	v_mfma_f32_16x16x32_bf16 v[60:63], v[52:55], v[186:189], v[60:63]
	v_mfma_f32_16x16x32_bf16 v[132:135], v[40:43], v[64:67], v[138:141]
	v_mfma_f32_16x16x32_bf16 v[138:141], v[44:47], v[64:67], v[142:145]
	v_mfma_f32_16x16x32_bf16 v[142:145], v[48:51], v[64:67], v[146:149]
	v_mfma_f32_16x16x32_bf16 v[32:35], v[52:55], v[64:67], v[32:35]
	v_mfma_f32_16x16x32_bf16 v[64:67], v[40:43], v[68:71], v[88:91]
	v_mfma_f32_16x16x32_bf16 v[88:91], v[44:47], v[68:71], v[150:153]
	v_mfma_f32_16x16x32_bf16 v[146:149], v[48:51], v[68:71], v[154:157]
	v_mfma_f32_16x16x32_bf16 v[36:39], v[52:55], v[68:71], v[36:39]
	v_mfma_f32_16x16x32_bf16 v[68:71], v[40:43], v[72:75], v[92:95]
	v_mfma_f32_16x16x32_bf16 v[92:95], v[44:47], v[72:75], v[158:161]
	v_mfma_f32_16x16x32_bf16 v[150:153], v[48:51], v[72:75], v[162:165]
	v_mfma_f32_16x16x32_bf16 v[72:75], v[52:55], v[72:75], v[96:99]
	v_mfma_f32_16x16x32_bf16 v[96:99], v[40:43], v[76:79], v[108:111]
	v_mfma_f32_16x16x32_bf16 v[108:111], v[44:47], v[76:79], v[166:169]
	v_mfma_f32_16x16x32_bf16 v[154:157], v[48:51], v[76:79], v[170:173]
	v_mfma_f32_16x16x32_bf16 v[76:79], v[52:55], v[76:79], v[100:103]
	v_mfma_f32_16x16x32_bf16 v[100:103], v[40:43], v[84:87], v[174:177]
	v_mfma_f32_16x16x32_bf16 v[158:161], v[44:47], v[84:87], v[178:181]
	v_mfma_f32_16x16x32_bf16 v[162:165], v[48:51], v[84:87], v[182:185]
	v_mfma_f32_16x16x32_bf16 v[84:87], v[52:55], v[84:87], v[104:107]
	s_waitcnt lgkmcnt(0)
	v_mfma_f32_16x16x32_bf16 v[16:19], v[40:43], v[190:193], v[16:19]
	v_mfma_f32_16x16x32_bf16 v[20:23], v[44:47], v[190:193], v[20:23]
	v_mfma_f32_16x16x32_bf16 v[24:27], v[48:51], v[190:193], v[24:27]
	v_mfma_f32_16x16x32_bf16 v[28:31], v[52:55], v[190:193], v[28:31]
	s_setprio 0
	v_add_u32_e32 v40, s20, v9
	v_or_b32_e32 v42, s21, v10
	v_ashrrev_i32_e32 v41, 31, v40
	v_lshlrev_b64 v[44:45], 10, v[40:41]
	v_ashrrev_i32_e32 v43, 31, v42
	v_lshl_add_u64 v[44:45], s[0:1], 0, v[44:45]
	v_lshlrev_b64 v[42:43], 1, v[42:43]
	v_lshl_add_u64 v[44:45], v[44:45], 0, v[42:43]
	v_cvt_pk_bf16_f32 v46, v112, v113
	v_cvt_pk_bf16_f32 v47, v114, v115
	s_barrier
; DI unsigned pack2(float lo, float hi) { const f32x2c v = {lo, hi}; return __builtin_bit_cast(unsigned, __builtin_convertvector(v, bf16x2c)); }
; template <class Epi>
; DI void gemm_tile(char* smem, const bf16_t* __restrict__ A0, int lda0, int ksplit, const bf16_t* __restrict__ A1, int lda1,
;                   const bf16_t* __restrict__ Bt, int K, int row0, int col0, const Epi& epi, int tid) {
;     ...
; #pragma unroll
;   for (int m = 0; m < 8; ++m)
; #pragma unroll
;     for (int n = 0; n < 4; ++n) epi(row0 + wr * 128 + m * 16 + fr, col0 + wc * 64 + n * 16 + fq * 4, acc[m][n]);
; }
; DI void st_bf16x4(bf16_t* o, f32x4 v) { u32x2 q; q.x = pack2(v[0], v[1]); q.y = pack2(v[2], v[3]); *(u32x2*)o = q; }
;   DI void operator()(int row, int col, f32x4 v) const {
;     if (col < n0) st_bf16x4(o0 + (size_t)row * ld0 + col, v);
;     else { const int c = col - n0; if (c < n1) st_bf16x4(o1 + (size_t)row * ld1 + c, v); }
;   }
	global_store_dwordx2 v[44:45], v[46:47], off
	v_cvt_pk_bf16_f32 v46, v116, v117
	v_cvt_pk_bf16_f32 v47, v118, v119
	global_store_dwordx2 v[44:45], v[46:47], off offset:32
	v_cvt_pk_bf16_f32 v46, v120, v121
	v_cvt_pk_bf16_f32 v47, v122, v123
	global_store_dwordx2 v[44:45], v[46:47], off offset:64
	v_cvt_pk_bf16_f32 v46, v56, v57
	v_cvt_pk_bf16_f32 v47, v58, v59
	global_store_dwordx2 v[44:45], v[46:47], off offset:96
	v_or_b32_e32 v44, 16, v40
	v_ashrrev_i32_e32 v45, 31, v44
	v_lshlrev_b64 v[44:45], 10, v[44:45]
	v_lshl_add_u64 v[44:45], s[0:1], 0, v[44:45]
	v_lshl_add_u64 v[44:45], v[44:45], 0, v[42:43]
	v_cvt_pk_bf16_f32 v46, v80, v81
	v_cvt_pk_bf16_f32 v47, v82, v83
	global_store_dwordx2 v[44:45], v[46:47], off
	v_cvt_pk_bf16_f32 v46, v124, v125
	v_cvt_pk_bf16_f32 v47, v126, v127
	global_store_dwordx2 v[44:45], v[46:47], off offset:32
	v_cvt_pk_bf16_f32 v46, v128, v129
	v_cvt_pk_bf16_f32 v47, v130, v131
	global_store_dwordx2 v[44:45], v[46:47], off offset:64
	v_cvt_pk_bf16_f32 v46, v60, v61
	v_cvt_pk_bf16_f32 v47, v62, v63
	global_store_dwordx2 v[44:45], v[46:47], off offset:96
	v_or_b32_e32 v44, 32, v40
	v_ashrrev_i32_e32 v45, 31, v44
	v_lshlrev_b64 v[44:45], 10, v[44:45]
	v_lshl_add_u64 v[44:45], s[0:1], 0, v[44:45]
	v_lshl_add_u64 v[44:45], v[44:45], 0, v[42:43]
	v_cvt_pk_bf16_f32 v32, v32, v33
	v_cvt_pk_bf16_f32 v33, v34, v35
	global_store_dwordx2 v[44:45], v[32:33], off offset:96
	v_or_b32_e32 v32, 48, v40
	v_ashrrev_i32_e32 v33, 31, v32
	v_lshlrev_b64 v[32:33], 10, v[32:33]
	v_lshl_add_u64 v[32:33], s[0:1], 0, v[32:33]
	v_lshl_add_u64 v[32:33], v[32:33], 0, v[42:43]
	v_cvt_pk_bf16_f32 v34, v64, v65
	v_cvt_pk_bf16_f32 v35, v66, v67
	global_store_dwordx2 v[32:33], v[34:35], off
	v_cvt_pk_bf16_f32 v34, v88, v89
	v_cvt_pk_bf16_f32 v35, v90, v91
	global_store_dwordx2 v[32:33], v[34:35], off offset:32
	v_cvt_pk_bf16_f32 v34, v146, v147
	v_cvt_pk_bf16_f32 v35, v148, v149
	global_store_dwordx2 v[32:33], v[34:35], off offset:64
	v_cvt_pk_bf16_f32 v34, v36, v37
	v_cvt_pk_bf16_f32 v35, v38, v39
	global_store_dwordx2 v[32:33], v[34:35], off offset:96
	v_or_b32_e32 v32, 64, v40
	v_ashrrev_i32_e32 v33, 31, v32
	v_lshlrev_b64 v[32:33], 10, v[32:33]
	v_lshl_add_u64 v[32:33], s[0:1], 0, v[32:33]
	v_lshl_add_u64 v[32:33], v[32:33], 0, v[42:43]
	v_cvt_pk_bf16_f32 v34, v68, v69
	v_cvt_pk_bf16_f32 v35, v70, v71
	global_store_dwordx2 v[32:33], v[34:35], off
	v_cvt_pk_bf16_f32 v34, v92, v93
	v_cvt_pk_bf16_f32 v35, v94, v95
	global_store_dwordx2 v[32:33], v[34:35], off offset:32
	v_cvt_pk_bf16_f32 v34, v150, v151
	v_cvt_pk_bf16_f32 v35, v152, v153
	global_store_dwordx2 v[32:33], v[34:35], off offset:64
	v_cvt_pk_bf16_f32 v34, v72, v73
	v_cvt_pk_bf16_f32 v35, v74, v75
	global_store_dwordx2 v[32:33], v[34:35], off offset:96
	v_or_b32_e32 v32, 0x50, v40
	v_ashrrev_i32_e32 v33, 31, v32
	v_lshlrev_b64 v[32:33], 10, v[32:33]
	v_lshl_add_u64 v[32:33], s[0:1], 0, v[32:33]
	v_lshl_add_u64 v[32:33], v[32:33], 0, v[42:43]
	v_cvt_pk_bf16_f32 v34, v96, v97
	v_cvt_pk_bf16_f32 v35, v98, v99
	global_store_dwordx2 v[32:33], v[34:35], off
	v_cvt_pk_bf16_f32 v34, v108, v109
	v_cvt_pk_bf16_f32 v35, v110, v111
	global_store_dwordx2 v[32:33], v[34:35], off offset:32
	v_cvt_pk_bf16_f32 v34, v154, v155
	v_cvt_pk_bf16_f32 v35, v156, v157
	global_store_dwordx2 v[32:33], v[34:35], off offset:64
	v_cvt_pk_bf16_f32 v34, v76, v77
	v_cvt_pk_bf16_f32 v35, v78, v79
	global_store_dwordx2 v[32:33], v[34:35], off offset:96
	v_or_b32_e32 v32, 0x60, v40
	v_ashrrev_i32_e32 v33, 31, v32
	v_lshlrev_b64 v[32:33], 10, v[32:33]
	v_lshl_add_u64 v[32:33], s[0:1], 0, v[32:33]
	v_lshl_add_u64 v[32:33], v[32:33], 0, v[42:43]
	v_cvt_pk_bf16_f32 v34, v100, v101
	v_cvt_pk_bf16_f32 v35, v102, v103
	global_store_dwordx2 v[32:33], v[34:35], off
	v_cvt_pk_bf16_f32 v34, v158, v159
	v_cvt_pk_bf16_f32 v35, v160, v161
	global_store_dwordx2 v[32:33], v[34:35], off offset:32
	v_cvt_pk_bf16_f32 v34, v162, v163
	v_cvt_pk_bf16_f32 v35, v164, v165
	global_store_dwordx2 v[32:33], v[34:35], off offset:64
	v_cvt_pk_bf16_f32 v34, v84, v85
	v_cvt_pk_bf16_f32 v35, v86, v87
	global_store_dwordx2 v[32:33], v[34:35], off offset:96
	v_or_b32_e32 v32, 0x70, v40
	v_ashrrev_i32_e32 v33, 31, v32
	v_lshlrev_b64 v[32:33], 10, v[32:33]
	v_lshl_add_u64 v[32:33], s[0:1], 0, v[32:33]
	v_lshl_add_u64 v[32:33], v[32:33], 0, v[42:43]
	v_cvt_pk_bf16_f32 v16, v16, v17
	v_cvt_pk_bf16_f32 v17, v18, v19
	v_cvt_pk_bf16_f32 v46, v132, v133
	v_cvt_pk_bf16_f32 v47, v134, v135
	global_store_dwordx2 v[32:33], v[16:17], off
	v_cvt_pk_bf16_f32 v16, v20, v21
	v_cvt_pk_bf16_f32 v17, v22, v23
	global_store_dwordx2 v[44:45], v[46:47], off
	v_cvt_pk_bf16_f32 v46, v138, v139
	v_cvt_pk_bf16_f32 v47, v140, v141
	global_store_dwordx2 v[32:33], v[16:17], off offset:32
	v_cvt_pk_bf16_f32 v16, v24, v25
	v_cvt_pk_bf16_f32 v17, v26, v27
	s_add_i32 s11, s11, s10
	s_add_i32 s16, s16, s17
	s_add_i32 s18, s18, s19
	global_store_dwordx2 v[44:45], v[46:47], off offset:32
	v_cvt_pk_bf16_f32 v46, v142, v143
	v_cvt_pk_bf16_f32 v47, v144, v145
	global_store_dwordx2 v[32:33], v[16:17], off offset:64
	v_cvt_pk_bf16_f32 v16, v28, v29
	v_cvt_pk_bf16_f32 v17, v30, v31
	s_cmp_gt_i32 s11, 63
	global_store_dwordx2 v[44:45], v[46:47], off offset:64
	global_store_dwordx2 v[32:33], v[16:17], off offset:96
	s_cbranch_scc0 .LBB0_585

; #define LWRITE(S, buf) do { bf16_t* sA_ = sbase + (buf) * BUF; bf16_t* sB_ = sA_ + 256 * PITCH; \
;     _Pragma("unroll") for (int i_ = 0; i_ < 4; ++i_) *(u32x4*)(sA_ + (sr + i_ * 64) * PITCH + scv * 8) = ra[S][i_]; \
;     _Pragma("unroll") for (int i_ = 0; i_ < 2; ++i_) *(u32x4*)(sB_ + (sr + i_ * 64) * PITCH + scv * 8) = rb[S][i_]; } while (0)
; template <class Epi>
; DI void gemm_tile(char* smem, const bf16_t* __restrict__ A0, int lda0, int ksplit, const bf16_t* __restrict__ A1, int lda1,
;                   const bf16_t* __restrict__ Bt, int K, int row0, int col0, const Epi& epi, int tid) {
;   constexpr int BK = 32, PITCH = 40, BUF = (256 + 128) * PITCH;
;   bf16_t* sbase = (bf16_t*)smem;
;   const int lane = tid & 63, wid = tid >> 6, wr = wid >> 1, wc = wid & 1, fr = lane & 15, fq = lane >> 4;
;   f32x4 acc[8][4];
; #pragma unroll
;   for (int m = 0; m < 8; ++m)
; #pragma unroll
;     for (int n = 0; n < 4; ++n) acc[m][n] = (f32x4){0.f, 0.f, 0.f, 0.f};
;   u32x4 ra[2][4], rb[2][2];
;   const int nk = K / BK;
;   const int sr = tid >> 2, scv = tid & 3;
;     ...
;   __syncthreads();
;   {
;     const int last = nk - 1;
;     GLOAD(0, 0);
;     __builtin_amdgcn_sched_barrier(0);
;     GLOAD(1, 1);
;     __builtin_amdgcn_sched_barrier(0);
;     LWRITE(0, 0);
;     __builtin_amdgcn_sched_barrier(0);
;     GLOAD(0, (2 < last ? 2 : last));
; template <class Epi>
; DI void gemm_phase(char* smem, const bf16_t* A0, int lda0, int ksplit, const bf16_t* A1, int lda1, const bf16_t* Bt, int K, int nN, const Epi& epi, int tid) {
;   const int G = gridDim.x;
;   if ((G & 7) == 0) {
;     const int x = blockIdx.x & 7, l = blockIdx.x >> 3, L = G >> 3, per = 8 * nN, tot = 2 * per;
;     for (int q = l; q < tot; q += L) { const int rgl = q / per, rem = q % per, ct = rem >> 3, rt = (x * 2 + rgl) * 8 + (rem & 7);
;       gemm_tile(smem, A0, lda0, ksplit, A1, lda1, Bt, K, rt * 256, ct * 128, epi, tid); }
.LBB0_855:
	s_cmp_gt_i32 s94, 6
	s_cselect_b64 s[0:1], -1, 0
	s_cmp_lt_i32 s95, 7
	s_cselect_b64 s[2:3], -1, 0
	s_or_b64 s[0:1], s[0:1], s[2:3]
	s_and_b64 vcc, exec, s[0:1]
	s_cbranch_vccnz .LBB0_883
	s_add_u32 s0, s92, 0x7800000
	s_load_dword s12, s[74:75], 0x180
	s_addc_u32 s1, s93, 0
	s_add_u32 s6, s92, 0xe800000
	s_addc_u32 s7, s93, 0
	s_add_u32 s2, s92, 0x8c0000
	s_addc_u32 s3, s93, 0
	s_and_b32 s8, s72, 0xffffffc0
	v_mbcnt_hi_u32_b32 v195, -1, v194
	s_waitcnt lgkmcnt(0)
	s_and_b32 s10, s12, 7
	s_cmp_lg_u32 s10, 0
	s_waitcnt vmcnt(16)
	v_add_u32_e32 v196, s8, v195
	v_mbcnt_lo_u32_b32 v240, -1, 0
	v_mbcnt_hi_u32_b32 v240, -1, v240
	s_lshr_b32 s20, s72, 6
	s_lshl_b32 s13, s20, 10
	v_and_b32_e32 v241, 15, v240
	v_lshrrev_b32_e32 v242, 4, v240
	v_bfe_u32 v243, v240, 3, 1
	v_mul_u32_u24_e32 v243, 3, v243
	v_xor_b32_e32 v243, v242, v243
	v_lshlrev_b32_e32 v243, 4, v243
	v_lshl_add_u32 v243, v241, 6, v243
	s_lshr_b32 s19, s20, 1
	s_lshl_b32 s19, s19, 13
	v_add_u32_e32 v230, s19, v243
	s_and_b32 s19, s20, 1
	s_lshl_b32 s19, s19, 12
	s_add_u32 s19, s19, 16384
	v_add_u32_e32 v231, s19, v243
	s_lshr_b32 s19, s20, 1
	s_lshl_b32 s19, s19, 7
	v_add_u32_e32 v244, s19, v241
	s_and_b32 s19, s20, 1
	s_lshl_b32 s19, s19, 6
	v_lshl_add_u32 v245, v242, 2, s19
	s_movk_i32 s19, 0x1000
	v_mul_lo_u32 v246, v244, s19
	v_lshl_add_u32 v234, v245, 2, v246
	v_lshrrev_b32_e32 v241, 2, v240
	s_lshl_b32 s19, s20, 4
	v_add_u32_e32 v241, s19, v241
	v_bfe_u32 v242, v240, 5, 1
	v_mul_u32_u24_e32 v242, 3, v242
	v_and_b32_e32 v243, 3, v240
	v_xor_b32_e32 v243, v243, v242
	v_lshlrev_b32_e32 v243, 4, v243
	s_mov_b32 s19, 1024
	v_mad_u32_u24 v224, v241, s19, v243
	v_add_u32_e32 v225, 0x10000, v224
	v_add_u32_e32 v226, 0x20000, v224
	v_add_u32_e32 v227, 0x30000, v224
	s_mov_b32 s19, 5184
	v_mad_u32_u24 v236, v241, s19, v243
	v_add_u32_e32 v237, 0x51000, v236
	v_add_u32_e32 v238, 0xa2000, v236
	v_add_u32_e32 v239, 0xf3000, v236
	v_mov_b32_e32 v248, v224
	v_mov_b32_e32 v249, v225
	v_mov_b32_e32 v250, v226
	v_mov_b32_e32 v251, v227
	s_mov_b32 s19, 3072
	v_mad_u32_u24 v228, v241, s19, v243
	v_add_u32_e32 v229, 0x30000, v228
	s_load_dwordx2 s[6:7], s[74:75], 0x168
	s_load_dwordx2 s[14:15], s[74:75], 0x0
	s_lshr_b32 s9, s96, 3
	s_and_b32 s11, s96, 7
	s_lshl_b32 s11, s11, 1
	s_waitcnt lgkmcnt(0)
.Lg6_tile:
	s_cmpk_ge_u32 s9, 128
	s_cbranch_scc1 .Lg6_done
	s_cmpk_ge_u32 s9, 64
	s_cselect_b32 s20, 1, 0
	s_cselect_b32 s19, 64, 0
	s_sub_u32 s19, s9, s19
	s_and_b32 s98, s19, 7
	s_lshl_b32 s98, s98, 3
	s_bfe_u32 s21, s19, 0x30003
	s_or_b32 s98, s98, s21
	s_andn2_b32 s19, s19, 63
	s_or_b32 s19, s19, s98
	s_add_u32 s20, s20, s11
	s_lshl_b32 s20, s20, 3
	s_and_b32 s98, s19, 7
	s_add_u32 s98, s98, s20
	s_lshl_b32 s98, s98, 8
	s_lshr_b32 s21, s19, 3
	s_lshl_b32 s21, s21, 7
	s_mul_i32 s20, s98, 1024
	s_add_u32 s20, s20, 0x7800000
	s_add_u32 s0, s92, s20
	s_addc_u32 s1, s93, 0
	s_mul_i32 s20, s21, 3072
	s_add_u32 s20, s20, 0x8c0000
	s_add_u32 s2, s92, s20
	s_addc_u32 s3, s93, 0
	v_mov_b32_e32 v224, v248
	v_mov_b32_e32 v225, v249
	v_mov_b32_e32 v226, v250
	v_mov_b32_e32 v227, v251
	s_mov_b32 s22, 0
	s_mov_b32 s99, 0
	s_add_u32 s19, s99, s13
	s_add_u32 m0, s19, 0
	s_nop 0
	global_load_lds_dwordx4 v224, s[0:1]
	s_add_u32 m0, s19, 4096
	s_nop 0
	global_load_lds_dwordx4 v225, s[0:1]
	s_add_u32 m0, s19, 8192
	s_nop 0
	global_load_lds_dwordx4 v226, s[0:1]
	s_add_u32 m0, s19, 12288
	s_nop 0
	global_load_lds_dwordx4 v227, s[0:1]
	s_add_u32 m0, s19, 16384
	s_nop 0
	global_load_lds_dwordx4 v228, s[2:3]
	s_add_u32 m0, s19, 20480
	s_nop 0
	global_load_lds_dwordx4 v229, s[2:3]
	s_add_u32 s0, s0, 64
	s_addc_u32 s1, s1, 0
	s_add_u32 s2, s2, 64
	s_addc_u32 s3, s3, 0
	s_add_u32 s22, s22, 1
	s_add_u32 s99, s99, 24576
	s_cmp_eq_u32 s99, 73728
	s_cselect_b32 s99, 0, s99
	s_add_u32 s19, s99, s13
	s_add_u32 m0, s19, 0
	s_nop 0
	global_load_lds_dwordx4 v224, s[0:1]
	s_add_u32 m0, s19, 4096
	s_nop 0
	global_load_lds_dwordx4 v225, s[0:1]
	s_add_u32 m0, s19, 8192
	s_nop 0
	global_load_lds_dwordx4 v226, s[0:1]
	s_add_u32 m0, s19, 12288
	s_nop 0
	global_load_lds_dwordx4 v227, s[0:1]
	s_add_u32 m0, s19, 16384
	s_nop 0
	global_load_lds_dwordx4 v228, s[2:3]
	s_add_u32 m0, s19, 20480
	s_nop 0
	global_load_lds_dwordx4 v229, s[2:3]
	s_add_u32 s0, s0, 64
	s_addc_u32 s1, s1, 0
	s_add_u32 s2, s2, 64
	s_addc_u32 s3, s3, 0
	s_add_u32 s22, s22, 1
	s_add_u32 s99, s99, 24576
	s_cmp_eq_u32 s99, 73728
	s_cselect_b32 s99, 0, s99
	s_add_u32 s19, s99, s13
	s_add_u32 m0, s19, 0
	s_nop 0
	global_load_lds_dwordx4 v224, s[0:1]
	s_add_u32 m0, s19, 4096
	s_nop 0
	global_load_lds_dwordx4 v225, s[0:1]
	s_add_u32 m0, s19, 8192
	s_nop 0
	global_load_lds_dwordx4 v226, s[0:1]
	s_add_u32 m0, s19, 12288
	s_nop 0
	global_load_lds_dwordx4 v227, s[0:1]
	s_add_u32 m0, s19, 16384
	s_nop 0
	global_load_lds_dwordx4 v228, s[2:3]
	s_add_u32 m0, s19, 20480
	s_nop 0
	global_load_lds_dwordx4 v229, s[2:3]
	s_add_u32 s0, s0, 64
	s_addc_u32 s1, s1, 0
	s_add_u32 s2, s2, 64
	s_addc_u32 s3, s3, 0
	s_add_u32 s22, s22, 1
	s_add_u32 s99, s99, 24576
	s_cmp_eq_u32 s99, 73728
	s_cselect_b32 s99, 0, s99
	v_mov_b32_e32 v0, 0
	v_mov_b32_e32 v1, 0
	v_mov_b32_e32 v2, 0
	v_mov_b32_e32 v3, 0
	v_mov_b32_e32 v4, 0
	v_mov_b32_e32 v5, 0
	v_mov_b32_e32 v6, 0
	v_mov_b32_e32 v7, 0
	v_mov_b32_e32 v8, 0
	v_mov_b32_e32 v9, 0
	v_mov_b32_e32 v10, 0
	v_mov_b32_e32 v11, 0
	v_mov_b32_e32 v12, 0
	v_mov_b32_e32 v13, 0
	v_mov_b32_e32 v14, 0
	v_mov_b32_e32 v15, 0
	v_mov_b32_e32 v16, 0
	v_mov_b32_e32 v17, 0
	v_mov_b32_e32 v18, 0
	v_mov_b32_e32 v19, 0
	v_mov_b32_e32 v20, 0
	v_mov_b32_e32 v21, 0
	v_mov_b32_e32 v22, 0
	v_mov_b32_e32 v23, 0
	v_mov_b32_e32 v24, 0
	v_mov_b32_e32 v25, 0
	v_mov_b32_e32 v26, 0
; #define LWRITE(S, buf) do { bf16_t* sA_ = sbase + (buf) * BUF; bf16_t* sB_ = sA_ + 256 * PITCH; \
;     _Pragma("unroll") for (int i_ = 0; i_ < 4; ++i_) *(u32x4*)(sA_ + (sr + i_ * 64) * PITCH + scv * 8) = ra[S][i_]; \
;     _Pragma("unroll") for (int i_ = 0; i_ < 2; ++i_) *(u32x4*)(sB_ + (sr + i_ * 64) * PITCH + scv * 8) = rb[S][i_]; } while (0)
; template <class Epi>
; DI void gemm_tile(char* smem, const bf16_t* __restrict__ A0, int lda0, int ksplit, const bf16_t* __restrict__ A1, int lda1,
;                   const bf16_t* __restrict__ Bt, int K, int row0, int col0, const Epi& epi, int tid) {
;     ...
; #pragma unroll
;   for (int m = 0; m < 8; ++m)
; #pragma unroll
;     for (int n = 0; n < 4; ++n) acc[m][n] = (f32x4){0.f, 0.f, 0.f, 0.f};
;   u32x4 ra[2][4], rb[2][2];
;   const int nk = K / BK;
;   const int sr = tid >> 2, scv = tid & 3;
;     ...
;   __syncthreads();
;   {
;     const int last = nk - 1;
;     GLOAD(0, 0);
;     __builtin_amdgcn_sched_barrier(0);
;     GLOAD(1, 1);
;     __builtin_amdgcn_sched_barrier(0);
;     LWRITE(0, 0);
;     __builtin_amdgcn_sched_barrier(0);
;     GLOAD(0, (2 < last ? 2 : last));
;     __builtin_amdgcn_sched_barrier(0);
;     __syncthreads();
;     for (int kt = 0; kt < nk; kt += 2) {
;       LWRITE(1, 1);
;       __builtin_amdgcn_sched_barrier(0);
;       GLOAD(1, (kt + 3 < last ? kt + 3 : last));
;       __builtin_amdgcn_sched_barrier(0);
;       COMPUTE(0);
;       __syncthreads();
;       LWRITE(0, 0);
;       __builtin_amdgcn_sched_barrier(0);
;       GLOAD(0, (kt + 4 < last ? kt + 4 : last));
;       __builtin_amdgcn_sched_barrier(0);
;       COMPUTE(1);
;       __syncthreads();
;     }
	v_mov_b32_e32 v27, 0
	v_mov_b32_e32 v28, 0
	v_mov_b32_e32 v29, 0
	v_mov_b32_e32 v30, 0
	v_mov_b32_e32 v31, 0
	v_mov_b32_e32 v32, 0
	v_mov_b32_e32 v33, 0
	v_mov_b32_e32 v34, 0
	v_mov_b32_e32 v35, 0
	v_mov_b32_e32 v36, 0
	v_mov_b32_e32 v37, 0
	v_mov_b32_e32 v38, 0
	v_mov_b32_e32 v39, 0
	v_mov_b32_e32 v40, 0
	v_mov_b32_e32 v41, 0
	v_mov_b32_e32 v42, 0
	v_mov_b32_e32 v43, 0
	v_mov_b32_e32 v44, 0
	v_mov_b32_e32 v45, 0
	v_mov_b32_e32 v46, 0
	v_mov_b32_e32 v47, 0
	v_mov_b32_e32 v48, 0
	v_mov_b32_e32 v49, 0
	v_mov_b32_e32 v50, 0
	v_mov_b32_e32 v51, 0
	v_mov_b32_e32 v52, 0
	v_mov_b32_e32 v53, 0
	v_mov_b32_e32 v54, 0
	v_mov_b32_e32 v55, 0
	v_mov_b32_e32 v56, 0
	v_mov_b32_e32 v57, 0
	v_mov_b32_e32 v58, 0
	v_mov_b32_e32 v59, 0
	v_mov_b32_e32 v60, 0
	v_mov_b32_e32 v61, 0
	v_mov_b32_e32 v62, 0
	v_mov_b32_e32 v63, 0
	v_mov_b32_e32 v64, 0
	v_mov_b32_e32 v65, 0
	v_mov_b32_e32 v66, 0
	v_mov_b32_e32 v67, 0
	v_mov_b32_e32 v68, 0
	v_mov_b32_e32 v69, 0
	v_mov_b32_e32 v70, 0
	v_mov_b32_e32 v71, 0
	v_mov_b32_e32 v72, 0
	v_mov_b32_e32 v73, 0
	v_mov_b32_e32 v74, 0
	v_mov_b32_e32 v75, 0
	v_mov_b32_e32 v76, 0
	v_mov_b32_e32 v77, 0
	v_mov_b32_e32 v78, 0
	v_mov_b32_e32 v79, 0
	v_mov_b32_e32 v80, 0
	v_mov_b32_e32 v81, 0
	v_mov_b32_e32 v82, 0
	v_mov_b32_e32 v83, 0
	v_mov_b32_e32 v84, 0
	v_mov_b32_e32 v85, 0
	v_mov_b32_e32 v86, 0
	v_mov_b32_e32 v87, 0
	v_mov_b32_e32 v88, 0
	v_mov_b32_e32 v89, 0
	v_mov_b32_e32 v90, 0
	v_mov_b32_e32 v91, 0
	v_mov_b32_e32 v92, 0
	v_mov_b32_e32 v93, 0
	v_mov_b32_e32 v94, 0
	v_mov_b32_e32 v95, 0
	v_mov_b32_e32 v96, 0
	v_mov_b32_e32 v97, 0
	v_mov_b32_e32 v98, 0
	v_mov_b32_e32 v99, 0
	v_mov_b32_e32 v100, 0
	v_mov_b32_e32 v101, 0
	v_mov_b32_e32 v102, 0
	v_mov_b32_e32 v103, 0
	v_mov_b32_e32 v104, 0
	v_mov_b32_e32 v105, 0
	v_mov_b32_e32 v106, 0
	v_mov_b32_e32 v107, 0
	v_mov_b32_e32 v108, 0
	v_mov_b32_e32 v109, 0
	v_mov_b32_e32 v110, 0
	v_mov_b32_e32 v111, 0
	v_mov_b32_e32 v112, 0
	v_mov_b32_e32 v113, 0
	v_mov_b32_e32 v114, 0
	v_mov_b32_e32 v115, 0
	v_mov_b32_e32 v116, 0
	v_mov_b32_e32 v117, 0
	v_mov_b32_e32 v118, 0
	v_mov_b32_e32 v119, 0
	v_mov_b32_e32 v120, 0
	v_mov_b32_e32 v121, 0
	v_mov_b32_e32 v122, 0
	v_mov_b32_e32 v123, 0
	v_mov_b32_e32 v124, 0
	v_mov_b32_e32 v125, 0
	v_mov_b32_e32 v126, 0
	v_mov_b32_e32 v127, 0
	s_mov_b32 s101, 0
	s_mov_b32 s100, 24576
	s_waitcnt vmcnt(12)
	s_barrier
	ds_read_b128 v[128:131], v231 offset:0
	ds_read_b128 v[132:135], v231 offset:1024
	ds_read_b128 v[136:139], v231 offset:2048
	ds_read_b128 v[140:143], v231 offset:3072
	ds_read_b128 v[144:147], v230 offset:0
	ds_read_b128 v[148:151], v230 offset:1024
	ds_read_b128 v[152:155], v230 offset:2048
	ds_read_b128 v[156:159], v230 offset:3072
	ds_read_b128 v[160:163], v230 offset:4096
	ds_read_b128 v[164:167], v230 offset:5120
	ds_read_b128 v[168:171], v230 offset:6144
	ds_read_b128 v[172:175], v230 offset:7168
.Lg6_kloop:
	s_cmp_eq_u32 s22, 16
	s_cbranch_scc1 .Lg6_sw0
.Lg6_swb0:
	s_waitcnt vmcnt(6)
	s_waitcnt lgkmcnt(0)
	s_barrier
	v_add_u32_e32 v232, s100, v230
	v_add_u32_e32 v233, s100, v231
	s_add_u32 s19, s99, s13
	v_mfma_f32_16x16x32_bf16 v[0:3], v[128:131], v[144:147], v[0:3]
	v_mfma_f32_16x16x32_bf16 v[4:7], v[132:135], v[144:147], v[4:7]
	v_mfma_f32_16x16x32_bf16 v[8:11], v[136:139], v[144:147], v[8:11]
	v_mfma_f32_16x16x32_bf16 v[12:15], v[140:143], v[144:147], v[12:15]
	ds_read_b128 v[176:179], v233 offset:0
	ds_read_b128 v[180:183], v233 offset:1024
	s_add_u32 m0, s19, 0
	s_nop 0
	global_load_lds_dwordx4 v224, s[0:1]
	v_mfma_f32_16x16x32_bf16 v[16:19], v[128:131], v[148:151], v[16:19]
	v_mfma_f32_16x16x32_bf16 v[20:23], v[132:135], v[148:151], v[20:23]
	v_mfma_f32_16x16x32_bf16 v[24:27], v[136:139], v[148:151], v[24:27]
	v_mfma_f32_16x16x32_bf16 v[28:31], v[140:143], v[148:151], v[28:31]
	ds_read_b128 v[184:187], v233 offset:2048
	ds_read_b128 v[188:191], v233 offset:3072
	s_add_u32 m0, s19, 4096
	s_nop 0
	global_load_lds_dwordx4 v225, s[0:1]
	v_mfma_f32_16x16x32_bf16 v[32:35], v[128:131], v[152:155], v[32:35]
	v_mfma_f32_16x16x32_bf16 v[36:39], v[132:135], v[152:155], v[36:39]
	v_mfma_f32_16x16x32_bf16 v[40:43], v[136:139], v[152:155], v[40:43]
	v_mfma_f32_16x16x32_bf16 v[44:47], v[140:143], v[152:155], v[44:47]
	ds_read_b128 v[192:195], v232 offset:0
	ds_read_b128 v[196:199], v232 offset:1024
	s_add_u32 m0, s19, 8192
	s_nop 0
	global_load_lds_dwordx4 v226, s[0:1]
	v_mfma_f32_16x16x32_bf16 v[48:51], v[128:131], v[156:159], v[48:51]
	v_mfma_f32_16x16x32_bf16 v[52:55], v[132:135], v[156:159], v[52:55]
	v_mfma_f32_16x16x32_bf16 v[56:59], v[136:139], v[156:159], v[56:59]
	v_mfma_f32_16x16x32_bf16 v[60:63], v[140:143], v[156:159], v[60:63]
	ds_read_b128 v[200:203], v232 offset:2048
	ds_read_b128 v[204:207], v232 offset:3072
	s_add_u32 m0, s19, 12288
	s_nop 0
	global_load_lds_dwordx4 v227, s[0:1]
	v_mfma_f32_16x16x32_bf16 v[64:67], v[128:131], v[160:163], v[64:67]
	v_mfma_f32_16x16x32_bf16 v[68:71], v[132:135], v[160:163], v[68:71]
	v_mfma_f32_16x16x32_bf16 v[72:75], v[136:139], v[160:163], v[72:75]
	v_mfma_f32_16x16x32_bf16 v[76:79], v[140:143], v[160:163], v[76:79]
	ds_read_b128 v[208:211], v232 offset:4096
	s_add_u32 m0, s19, 16384
	s_nop 0
	global_load_lds_dwordx4 v228, s[2:3]
	v_mfma_f32_16x16x32_bf16 v[80:83], v[128:131], v[164:167], v[80:83]
	v_mfma_f32_16x16x32_bf16 v[84:87], v[132:135], v[164:167], v[84:87]
	v_mfma_f32_16x16x32_bf16 v[88:91], v[136:139], v[164:167], v[88:91]
	v_mfma_f32_16x16x32_bf16 v[92:95], v[140:143], v[164:167], v[92:95]
	ds_read_b128 v[212:215], v232 offset:5120
	s_add_u32 m0, s19, 20480
	s_nop 0
	global_load_lds_dwordx4 v229, s[2:3]
	v_mfma_f32_16x16x32_bf16 v[96:99], v[128:131], v[168:171], v[96:99]
	v_mfma_f32_16x16x32_bf16 v[100:103], v[132:135], v[168:171], v[100:103]
	v_mfma_f32_16x16x32_bf16 v[104:107], v[136:139], v[168:171], v[104:107]
	v_mfma_f32_16x16x32_bf16 v[108:111], v[140:143], v[168:171], v[108:111]
	ds_read_b128 v[216:219], v232 offset:6144
	s_add_u32 s0, s0, 64
	s_addc_u32 s1, s1, 0
	s_add_u32 s2, s2, 64
	s_addc_u32 s3, s3, 0
	s_add_u32 s22, s22, 1
	s_add_u32 s99, s99, 24576
	s_cmp_eq_u32 s99, 73728
	s_cselect_b32 s99, 0, s99
	s_add_u32 s100, s100, 24576
	s_cmp_eq_u32 s100, 73728
	s_cselect_b32 s100, 0, s100
	v_mfma_f32_16x16x32_bf16 v[112:115], v[128:131], v[172:175], v[112:115]
	v_mfma_f32_16x16x32_bf16 v[116:119], v[132:135], v[172:175], v[116:119]
	v_mfma_f32_16x16x32_bf16 v[120:123], v[136:139], v[172:175], v[120:123]
	v_mfma_f32_16x16x32_bf16 v[124:127], v[140:143], v[172:175], v[124:127]
	ds_read_b128 v[220:223], v232 offset:7168
	s_cmp_eq_u32 s22, 16
	s_cbranch_scc1 .Lg6_sw1
; #define LWRITE(S, buf) do { bf16_t* sA_ = sbase + (buf) * BUF; bf16_t* sB_ = sA_ + 256 * PITCH; \
;     _Pragma("unroll") for (int i_ = 0; i_ < 4; ++i_) *(u32x4*)(sA_ + (sr + i_ * 64) * PITCH + scv * 8) = ra[S][i_]; \
;     _Pragma("unroll") for (int i_ = 0; i_ < 2; ++i_) *(u32x4*)(sB_ + (sr + i_ * 64) * PITCH + scv * 8) = rb[S][i_]; } while (0)
; template <class Epi>
; DI void gemm_tile(char* smem, const bf16_t* __restrict__ A0, int lda0, int ksplit, const bf16_t* __restrict__ A1, int lda1,
;                   const bf16_t* __restrict__ Bt, int K, int row0, int col0, const Epi& epi, int tid) {
;     ...
;     for (int kt = 0; kt < nk; kt += 2) {
;       LWRITE(1, 1);
;       __builtin_amdgcn_sched_barrier(0);
;       GLOAD(1, (kt + 3 < last ? kt + 3 : last));
;       __builtin_amdgcn_sched_barrier(0);
;       COMPUTE(0);
;       __syncthreads();
;       LWRITE(0, 0);
;       __builtin_amdgcn_sched_barrier(0);
;       GLOAD(0, (kt + 4 < last ? kt + 4 : last));
;       __builtin_amdgcn_sched_barrier(0);
;       COMPUTE(1);
;       __syncthreads();
;     }
.Lg6_swb1:
	s_waitcnt vmcnt(6)
	s_waitcnt lgkmcnt(0)
	s_barrier
	v_add_u32_e32 v232, s100, v230
	v_add_u32_e32 v233, s100, v231
	s_add_u32 s19, s99, s13
	v_mfma_f32_16x16x32_bf16 v[0:3], v[176:179], v[192:195], v[0:3]
	v_mfma_f32_16x16x32_bf16 v[4:7], v[180:183], v[192:195], v[4:7]
	v_mfma_f32_16x16x32_bf16 v[8:11], v[184:187], v[192:195], v[8:11]
	v_mfma_f32_16x16x32_bf16 v[12:15], v[188:191], v[192:195], v[12:15]
	ds_read_b128 v[128:131], v233 offset:0
	ds_read_b128 v[132:135], v233 offset:1024
	s_add_u32 m0, s19, 0
	s_nop 0
	global_load_lds_dwordx4 v224, s[0:1]
	v_mfma_f32_16x16x32_bf16 v[16:19], v[176:179], v[196:199], v[16:19]
	v_mfma_f32_16x16x32_bf16 v[20:23], v[180:183], v[196:199], v[20:23]
	v_mfma_f32_16x16x32_bf16 v[24:27], v[184:187], v[196:199], v[24:27]
	v_mfma_f32_16x16x32_bf16 v[28:31], v[188:191], v[196:199], v[28:31]
	ds_read_b128 v[136:139], v233 offset:2048
	ds_read_b128 v[140:143], v233 offset:3072
	s_add_u32 m0, s19, 4096
	s_nop 0
	global_load_lds_dwordx4 v225, s[0:1]
	v_mfma_f32_16x16x32_bf16 v[32:35], v[176:179], v[200:203], v[32:35]
	v_mfma_f32_16x16x32_bf16 v[36:39], v[180:183], v[200:203], v[36:39]
	v_mfma_f32_16x16x32_bf16 v[40:43], v[184:187], v[200:203], v[40:43]
	v_mfma_f32_16x16x32_bf16 v[44:47], v[188:191], v[200:203], v[44:47]
	ds_read_b128 v[144:147], v232 offset:0
	ds_read_b128 v[148:151], v232 offset:1024
	s_add_u32 m0, s19, 8192
	s_nop 0
	global_load_lds_dwordx4 v226, s[0:1]
	v_mfma_f32_16x16x32_bf16 v[48:51], v[176:179], v[204:207], v[48:51]
	v_mfma_f32_16x16x32_bf16 v[52:55], v[180:183], v[204:207], v[52:55]
	v_mfma_f32_16x16x32_bf16 v[56:59], v[184:187], v[204:207], v[56:59]
	v_mfma_f32_16x16x32_bf16 v[60:63], v[188:191], v[204:207], v[60:63]
	ds_read_b128 v[152:155], v232 offset:2048
	ds_read_b128 v[156:159], v232 offset:3072
	s_add_u32 m0, s19, 12288
	s_nop 0
	global_load_lds_dwordx4 v227, s[0:1]
	v_mfma_f32_16x16x32_bf16 v[64:67], v[176:179], v[208:211], v[64:67]
	v_mfma_f32_16x16x32_bf16 v[68:71], v[180:183], v[208:211], v[68:71]
	v_mfma_f32_16x16x32_bf16 v[72:75], v[184:187], v[208:211], v[72:75]
	v_mfma_f32_16x16x32_bf16 v[76:79], v[188:191], v[208:211], v[76:79]
	ds_read_b128 v[160:163], v232 offset:4096
	s_add_u32 m0, s19, 16384
	s_nop 0
	global_load_lds_dwordx4 v228, s[2:3]
	v_mfma_f32_16x16x32_bf16 v[80:83], v[176:179], v[212:215], v[80:83]
	v_mfma_f32_16x16x32_bf16 v[84:87], v[180:183], v[212:215], v[84:87]
	v_mfma_f32_16x16x32_bf16 v[88:91], v[184:187], v[212:215], v[88:91]
	v_mfma_f32_16x16x32_bf16 v[92:95], v[188:191], v[212:215], v[92:95]
	ds_read_b128 v[164:167], v232 offset:5120
	s_add_u32 m0, s19, 20480
	s_nop 0
	global_load_lds_dwordx4 v229, s[2:3]
	v_mfma_f32_16x16x32_bf16 v[96:99], v[176:179], v[216:219], v[96:99]
	v_mfma_f32_16x16x32_bf16 v[100:103], v[180:183], v[216:219], v[100:103]
	v_mfma_f32_16x16x32_bf16 v[104:107], v[184:187], v[216:219], v[104:107]
	v_mfma_f32_16x16x32_bf16 v[108:111], v[188:191], v[216:219], v[108:111]
	ds_read_b128 v[168:171], v232 offset:6144
	s_add_u32 s0, s0, 64
	s_addc_u32 s1, s1, 0
	s_add_u32 s2, s2, 64
	s_addc_u32 s3, s3, 0
	s_add_u32 s22, s22, 1
	s_add_u32 s99, s99, 24576
	s_cmp_eq_u32 s99, 73728
	s_cselect_b32 s99, 0, s99
	s_add_u32 s100, s100, 24576
	s_cmp_eq_u32 s100, 73728
	s_cselect_b32 s100, 0, s100
	v_mfma_f32_16x16x32_bf16 v[112:115], v[176:179], v[220:223], v[112:115]
	v_mfma_f32_16x16x32_bf16 v[116:119], v[180:183], v[220:223], v[116:119]
	v_mfma_f32_16x16x32_bf16 v[120:123], v[184:187], v[220:223], v[120:123]
	v_mfma_f32_16x16x32_bf16 v[124:127], v[188:191], v[220:223], v[124:127]
	ds_read_b128 v[172:175], v232 offset:7168
	s_add_u32 s101, s101, 2
	s_cmp_lt_u32 s101, 44
	s_cbranch_scc1 .Lg6_kloop
	s_cmp_eq_u32 s22, 16
	s_cbranch_scc1 .Lg6_sw2
.Lg6_swb2:
	s_waitcnt vmcnt(6)
	s_waitcnt lgkmcnt(0)
	s_barrier
	v_add_u32_e32 v232, s100, v230
	v_add_u32_e32 v233, s100, v231
	s_add_u32 s19, s99, s13
	v_mfma_f32_16x16x32_bf16 v[0:3], v[128:131], v[144:147], v[0:3]
	v_mfma_f32_16x16x32_bf16 v[4:7], v[132:135], v[144:147], v[4:7]
	v_mfma_f32_16x16x32_bf16 v[8:11], v[136:139], v[144:147], v[8:11]
	v_mfma_f32_16x16x32_bf16 v[12:15], v[140:143], v[144:147], v[12:15]
	ds_read_b128 v[176:179], v233 offset:0
	ds_read_b128 v[180:183], v233 offset:1024
	s_add_u32 m0, s19, 0
	s_nop 0
	global_load_lds_dwordx4 v224, s[0:1]
	v_mfma_f32_16x16x32_bf16 v[16:19], v[128:131], v[148:151], v[16:19]
	v_mfma_f32_16x16x32_bf16 v[20:23], v[132:135], v[148:151], v[20:23]
	v_mfma_f32_16x16x32_bf16 v[24:27], v[136:139], v[148:151], v[24:27]
	v_mfma_f32_16x16x32_bf16 v[28:31], v[140:143], v[148:151], v[28:31]
	ds_read_b128 v[184:187], v233 offset:2048
	ds_read_b128 v[188:191], v233 offset:3072
	s_add_u32 m0, s19, 4096
	s_nop 0
	global_load_lds_dwordx4 v225, s[0:1]
	v_mfma_f32_16x16x32_bf16 v[32:35], v[128:131], v[152:155], v[32:35]
	v_mfma_f32_16x16x32_bf16 v[36:39], v[132:135], v[152:155], v[36:39]
	v_mfma_f32_16x16x32_bf16 v[40:43], v[136:139], v[152:155], v[40:43]
	v_mfma_f32_16x16x32_bf16 v[44:47], v[140:143], v[152:155], v[44:47]
	ds_read_b128 v[192:195], v232 offset:0
	ds_read_b128 v[196:199], v232 offset:1024
	s_add_u32 m0, s19, 8192
	s_nop 0
	global_load_lds_dwordx4 v226, s[0:1]
	v_mfma_f32_16x16x32_bf16 v[48:51], v[128:131], v[156:159], v[48:51]
	v_mfma_f32_16x16x32_bf16 v[52:55], v[132:135], v[156:159], v[52:55]
	v_mfma_f32_16x16x32_bf16 v[56:59], v[136:139], v[156:159], v[56:59]
	v_mfma_f32_16x16x32_bf16 v[60:63], v[140:143], v[156:159], v[60:63]
	ds_read_b128 v[200:203], v232 offset:2048
	ds_read_b128 v[204:207], v232 offset:3072
	s_add_u32 m0, s19, 12288
	s_nop 0
	global_load_lds_dwordx4 v227, s[0:1]
	v_mfma_f32_16x16x32_bf16 v[64:67], v[128:131], v[160:163], v[64:67]
; #define LWRITE(S, buf) do { bf16_t* sA_ = sbase + (buf) * BUF; bf16_t* sB_ = sA_ + 256 * PITCH; \
;     _Pragma("unroll") for (int i_ = 0; i_ < 4; ++i_) *(u32x4*)(sA_ + (sr + i_ * 64) * PITCH + scv * 8) = ra[S][i_]; \
;     _Pragma("unroll") for (int i_ = 0; i_ < 2; ++i_) *(u32x4*)(sB_ + (sr + i_ * 64) * PITCH + scv * 8) = rb[S][i_]; } while (0)
; template <class Epi>
; DI void gemm_tile(char* smem, const bf16_t* __restrict__ A0, int lda0, int ksplit, const bf16_t* __restrict__ A1, int lda1,
;                   const bf16_t* __restrict__ Bt, int K, int row0, int col0, const Epi& epi, int tid) {
;     ...
;   __syncthreads();
;   {
;     const int last = nk - 1;
;     GLOAD(0, 0);
;     __builtin_amdgcn_sched_barrier(0);
;     GLOAD(1, 1);
;     __builtin_amdgcn_sched_barrier(0);
;     LWRITE(0, 0);
;     __builtin_amdgcn_sched_barrier(0);
;     GLOAD(0, (2 < last ? 2 : last));
;     __builtin_amdgcn_sched_barrier(0);
;     __syncthreads();
;     for (int kt = 0; kt < nk; kt += 2) {
;       LWRITE(1, 1);
;       __builtin_amdgcn_sched_barrier(0);
;       GLOAD(1, (kt + 3 < last ? kt + 3 : last));
;       __builtin_amdgcn_sched_barrier(0);
;       COMPUTE(0);
;       __syncthreads();
;       LWRITE(0, 0);
;       __builtin_amdgcn_sched_barrier(0);
;       GLOAD(0, (kt + 4 < last ? kt + 4 : last));
;       __builtin_amdgcn_sched_barrier(0);
;       COMPUTE(1);
;       __syncthreads();
;     }
	v_mfma_f32_16x16x32_bf16 v[68:71], v[132:135], v[160:163], v[68:71]
	v_mfma_f32_16x16x32_bf16 v[72:75], v[136:139], v[160:163], v[72:75]
	v_mfma_f32_16x16x32_bf16 v[76:79], v[140:143], v[160:163], v[76:79]
	ds_read_b128 v[208:211], v232 offset:4096
	s_add_u32 m0, s19, 16384
	s_nop 0
	global_load_lds_dwordx4 v228, s[2:3]
	v_mfma_f32_16x16x32_bf16 v[80:83], v[128:131], v[164:167], v[80:83]
	v_mfma_f32_16x16x32_bf16 v[84:87], v[132:135], v[164:167], v[84:87]
	v_mfma_f32_16x16x32_bf16 v[88:91], v[136:139], v[164:167], v[88:91]
	v_mfma_f32_16x16x32_bf16 v[92:95], v[140:143], v[164:167], v[92:95]
	ds_read_b128 v[212:215], v232 offset:5120
	s_add_u32 m0, s19, 20480
	s_nop 0
	global_load_lds_dwordx4 v229, s[2:3]
	v_mfma_f32_16x16x32_bf16 v[96:99], v[128:131], v[168:171], v[96:99]
	v_mfma_f32_16x16x32_bf16 v[100:103], v[132:135], v[168:171], v[100:103]
	v_mfma_f32_16x16x32_bf16 v[104:107], v[136:139], v[168:171], v[104:107]
	v_mfma_f32_16x16x32_bf16 v[108:111], v[140:143], v[168:171], v[108:111]
	ds_read_b128 v[216:219], v232 offset:6144
	s_add_u32 s0, s0, 64
	s_addc_u32 s1, s1, 0
	s_add_u32 s2, s2, 64
	s_addc_u32 s3, s3, 0
	s_add_u32 s22, s22, 1
	s_add_u32 s99, s99, 24576
	s_cmp_eq_u32 s99, 73728
	s_cselect_b32 s99, 0, s99
	s_add_u32 s100, s100, 24576
	s_cmp_eq_u32 s100, 73728
	s_cselect_b32 s100, 0, s100
	v_mfma_f32_16x16x32_bf16 v[112:115], v[128:131], v[172:175], v[112:115]
	v_mfma_f32_16x16x32_bf16 v[116:119], v[132:135], v[172:175], v[116:119]
	v_mfma_f32_16x16x32_bf16 v[120:123], v[136:139], v[172:175], v[120:123]
	v_mfma_f32_16x16x32_bf16 v[124:127], v[140:143], v[172:175], v[124:127]
	ds_read_b128 v[220:223], v232 offset:7168
	s_waitcnt vmcnt(6)
	s_waitcnt lgkmcnt(0)
	s_barrier
	v_add_u32_e32 v232, s100, v230
	v_add_u32_e32 v233, s100, v231
	v_mfma_f32_16x16x32_bf16 v[0:3], v[176:179], v[192:195], v[0:3]
	v_mfma_f32_16x16x32_bf16 v[4:7], v[180:183], v[192:195], v[4:7]
	v_mfma_f32_16x16x32_bf16 v[8:11], v[184:187], v[192:195], v[8:11]
	v_mfma_f32_16x16x32_bf16 v[12:15], v[188:191], v[192:195], v[12:15]
	ds_read_b128 v[128:131], v233 offset:0
	ds_read_b128 v[132:135], v233 offset:1024
	v_mfma_f32_16x16x32_bf16 v[16:19], v[176:179], v[196:199], v[16:19]
	v_mfma_f32_16x16x32_bf16 v[20:23], v[180:183], v[196:199], v[20:23]
	v_mfma_f32_16x16x32_bf16 v[24:27], v[184:187], v[196:199], v[24:27]
	v_mfma_f32_16x16x32_bf16 v[28:31], v[188:191], v[196:199], v[28:31]
	ds_read_b128 v[136:139], v233 offset:2048
	ds_read_b128 v[140:143], v233 offset:3072
	v_mfma_f32_16x16x32_bf16 v[32:35], v[176:179], v[200:203], v[32:35]
	v_mfma_f32_16x16x32_bf16 v[36:39], v[180:183], v[200:203], v[36:39]
	v_mfma_f32_16x16x32_bf16 v[40:43], v[184:187], v[200:203], v[40:43]
	v_mfma_f32_16x16x32_bf16 v[44:47], v[188:191], v[200:203], v[44:47]
	ds_read_b128 v[144:147], v232 offset:0
	ds_read_b128 v[148:151], v232 offset:1024
	v_mfma_f32_16x16x32_bf16 v[48:51], v[176:179], v[204:207], v[48:51]
	v_mfma_f32_16x16x32_bf16 v[52:55], v[180:183], v[204:207], v[52:55]
	v_mfma_f32_16x16x32_bf16 v[56:59], v[184:187], v[204:207], v[56:59]
	v_mfma_f32_16x16x32_bf16 v[60:63], v[188:191], v[204:207], v[60:63]
	ds_read_b128 v[152:155], v232 offset:2048
	ds_read_b128 v[156:159], v232 offset:3072
	v_mfma_f32_16x16x32_bf16 v[64:67], v[176:179], v[208:211], v[64:67]
	v_mfma_f32_16x16x32_bf16 v[68:71], v[180:183], v[208:211], v[68:71]
	v_mfma_f32_16x16x32_bf16 v[72:75], v[184:187], v[208:211], v[72:75]
	v_mfma_f32_16x16x32_bf16 v[76:79], v[188:191], v[208:211], v[76:79]
	ds_read_b128 v[160:163], v232 offset:4096
	v_mfma_f32_16x16x32_bf16 v[80:83], v[176:179], v[212:215], v[80:83]
	v_mfma_f32_16x16x32_bf16 v[84:87], v[180:183], v[212:215], v[84:87]
	v_mfma_f32_16x16x32_bf16 v[88:91], v[184:187], v[212:215], v[88:91]
	v_mfma_f32_16x16x32_bf16 v[92:95], v[188:191], v[212:215], v[92:95]
	ds_read_b128 v[164:167], v232 offset:5120
	v_mfma_f32_16x16x32_bf16 v[96:99], v[176:179], v[216:219], v[96:99]
	v_mfma_f32_16x16x32_bf16 v[100:103], v[180:183], v[216:219], v[100:103]
	v_mfma_f32_16x16x32_bf16 v[104:107], v[184:187], v[216:219], v[104:107]
	v_mfma_f32_16x16x32_bf16 v[108:111], v[188:191], v[216:219], v[108:111]
	ds_read_b128 v[168:171], v232 offset:6144
	s_add_u32 s100, s100, 24576
	s_cmp_eq_u32 s100, 73728
	s_cselect_b32 s100, 0, s100
	v_mfma_f32_16x16x32_bf16 v[112:115], v[176:179], v[220:223], v[112:115]
	v_mfma_f32_16x16x32_bf16 v[116:119], v[180:183], v[220:223], v[116:119]
	v_mfma_f32_16x16x32_bf16 v[120:123], v[184:187], v[220:223], v[120:123]
	v_mfma_f32_16x16x32_bf16 v[124:127], v[188:191], v[220:223], v[124:127]
	ds_read_b128 v[172:175], v232 offset:7168
	s_waitcnt vmcnt(0)
	s_waitcnt lgkmcnt(0)
	s_barrier
; #define LWRITE(S, buf) do { bf16_t* sA_ = sbase + (buf) * BUF; bf16_t* sB_ = sA_ + 256 * PITCH; \
;     _Pragma("unroll") for (int i_ = 0; i_ < 4; ++i_) *(u32x4*)(sA_ + (sr + i_ * 64) * PITCH + scv * 8) = ra[S][i_]; \
;     _Pragma("unroll") for (int i_ = 0; i_ < 2; ++i_) *(u32x4*)(sB_ + (sr + i_ * 64) * PITCH + scv * 8) = rb[S][i_]; } while (0)
; template <class Epi>
; DI void gemm_tile(char* smem, const bf16_t* __restrict__ A0, int lda0, int ksplit, const bf16_t* __restrict__ A1, int lda1,
;                   const bf16_t* __restrict__ Bt, int K, int row0, int col0, const Epi& epi, int tid) {
;     ...
;   __syncthreads();
;   {
;     const int last = nk - 1;
;     GLOAD(0, 0);
;     __builtin_amdgcn_sched_barrier(0);
;     GLOAD(1, 1);
;     __builtin_amdgcn_sched_barrier(0);
;     LWRITE(0, 0);
;     __builtin_amdgcn_sched_barrier(0);
;     GLOAD(0, (2 < last ? 2 : last));
;     __builtin_amdgcn_sched_barrier(0);
;     __syncthreads();
;     for (int kt = 0; kt < nk; kt += 2) {
;       LWRITE(1, 1);
;       __builtin_amdgcn_sched_barrier(0);
;       GLOAD(1, (kt + 3 < last ? kt + 3 : last));
;       __builtin_amdgcn_sched_barrier(0);
;       COMPUTE(0);
;       __syncthreads();
;       LWRITE(0, 0);
;       __builtin_amdgcn_sched_barrier(0);
;       GLOAD(0, (kt + 4 < last ? kt + 4 : last));
;       __builtin_amdgcn_sched_barrier(0);
;       COMPUTE(1);
;       __syncthreads();
;     }
	v_add_u32_e32 v232, s100, v230
	v_add_u32_e32 v233, s100, v231
	v_mfma_f32_16x16x32_bf16 v[0:3], v[128:131], v[144:147], v[0:3]
	v_mfma_f32_16x16x32_bf16 v[4:7], v[132:135], v[144:147], v[4:7]
	v_mfma_f32_16x16x32_bf16 v[8:11], v[136:139], v[144:147], v[8:11]
	v_mfma_f32_16x16x32_bf16 v[12:15], v[140:143], v[144:147], v[12:15]
	ds_read_b128 v[176:179], v233 offset:0
	ds_read_b128 v[180:183], v233 offset:1024
	v_mfma_f32_16x16x32_bf16 v[16:19], v[128:131], v[148:151], v[16:19]
	v_mfma_f32_16x16x32_bf16 v[20:23], v[132:135], v[148:151], v[20:23]
	v_mfma_f32_16x16x32_bf16 v[24:27], v[136:139], v[148:151], v[24:27]
	v_mfma_f32_16x16x32_bf16 v[28:31], v[140:143], v[148:151], v[28:31]
	ds_read_b128 v[184:187], v233 offset:2048
	ds_read_b128 v[188:191], v233 offset:3072
	v_mfma_f32_16x16x32_bf16 v[32:35], v[128:131], v[152:155], v[32:35]
	v_mfma_f32_16x16x32_bf16 v[36:39], v[132:135], v[152:155], v[36:39]
	v_mfma_f32_16x16x32_bf16 v[40:43], v[136:139], v[152:155], v[40:43]
	v_mfma_f32_16x16x32_bf16 v[44:47], v[140:143], v[152:155], v[44:47]
	ds_read_b128 v[192:195], v232 offset:0
	ds_read_b128 v[196:199], v232 offset:1024
	v_mfma_f32_16x16x32_bf16 v[48:51], v[128:131], v[156:159], v[48:51]
	v_mfma_f32_16x16x32_bf16 v[52:55], v[132:135], v[156:159], v[52:55]
	v_mfma_f32_16x16x32_bf16 v[56:59], v[136:139], v[156:159], v[56:59]
	v_mfma_f32_16x16x32_bf16 v[60:63], v[140:143], v[156:159], v[60:63]
	ds_read_b128 v[200:203], v232 offset:2048
	ds_read_b128 v[204:207], v232 offset:3072
	v_mfma_f32_16x16x32_bf16 v[64:67], v[128:131], v[160:163], v[64:67]
	v_mfma_f32_16x16x32_bf16 v[68:71], v[132:135], v[160:163], v[68:71]
	v_mfma_f32_16x16x32_bf16 v[72:75], v[136:139], v[160:163], v[72:75]
	v_mfma_f32_16x16x32_bf16 v[76:79], v[140:143], v[160:163], v[76:79]
	ds_read_b128 v[208:211], v232 offset:4096
	v_mfma_f32_16x16x32_bf16 v[80:83], v[128:131], v[164:167], v[80:83]
	v_mfma_f32_16x16x32_bf16 v[84:87], v[132:135], v[164:167], v[84:87]
	v_mfma_f32_16x16x32_bf16 v[88:91], v[136:139], v[164:167], v[88:91]
	v_mfma_f32_16x16x32_bf16 v[92:95], v[140:143], v[164:167], v[92:95]
	ds_read_b128 v[212:215], v232 offset:5120
	v_mfma_f32_16x16x32_bf16 v[96:99], v[128:131], v[168:171], v[96:99]
	v_mfma_f32_16x16x32_bf16 v[100:103], v[132:135], v[168:171], v[100:103]
	v_mfma_f32_16x16x32_bf16 v[104:107], v[136:139], v[168:171], v[104:107]
	v_mfma_f32_16x16x32_bf16 v[108:111], v[140:143], v[168:171], v[108:111]
	ds_read_b128 v[216:219], v232 offset:6144
	s_add_u32 s100, s100, 24576
	s_cmp_eq_u32 s100, 73728
	s_cselect_b32 s100, 0, s100
	v_mfma_f32_16x16x32_bf16 v[112:115], v[128:131], v[172:175], v[112:115]
	v_mfma_f32_16x16x32_bf16 v[116:119], v[132:135], v[172:175], v[116:119]
	v_mfma_f32_16x16x32_bf16 v[120:123], v[136:139], v[172:175], v[120:123]
	v_mfma_f32_16x16x32_bf16 v[124:127], v[140:143], v[172:175], v[124:127]
	ds_read_b128 v[220:223], v232 offset:7168
	s_waitcnt lgkmcnt(0)
	s_barrier
	v_mfma_f32_16x16x32_bf16 v[0:3], v[176:179], v[192:195], v[0:3]
	v_mfma_f32_16x16x32_bf16 v[4:7], v[180:183], v[192:195], v[4:7]
	v_mfma_f32_16x16x32_bf16 v[8:11], v[184:187], v[192:195], v[8:11]
	v_mfma_f32_16x16x32_bf16 v[12:15], v[188:191], v[192:195], v[12:15]
	v_mfma_f32_16x16x32_bf16 v[16:19], v[176:179], v[196:199], v[16:19]
	v_mfma_f32_16x16x32_bf16 v[20:23], v[180:183], v[196:199], v[20:23]
	v_mfma_f32_16x16x32_bf16 v[24:27], v[184:187], v[196:199], v[24:27]
	v_mfma_f32_16x16x32_bf16 v[28:31], v[188:191], v[196:199], v[28:31]
	v_mfma_f32_16x16x32_bf16 v[32:35], v[176:179], v[200:203], v[32:35]
	v_mfma_f32_16x16x32_bf16 v[36:39], v[180:183], v[200:203], v[36:39]
	v_mfma_f32_16x16x32_bf16 v[40:43], v[184:187], v[200:203], v[40:43]
	v_mfma_f32_16x16x32_bf16 v[44:47], v[188:191], v[200:203], v[44:47]
	v_mfma_f32_16x16x32_bf16 v[48:51], v[176:179], v[204:207], v[48:51]
	v_mfma_f32_16x16x32_bf16 v[52:55], v[180:183], v[204:207], v[52:55]
	v_mfma_f32_16x16x32_bf16 v[56:59], v[184:187], v[204:207], v[56:59]
	v_mfma_f32_16x16x32_bf16 v[60:63], v[188:191], v[204:207], v[60:63]
	v_mfma_f32_16x16x32_bf16 v[64:67], v[176:179], v[208:211], v[64:67]
	v_mfma_f32_16x16x32_bf16 v[68:71], v[180:183], v[208:211], v[68:71]
	v_mfma_f32_16x16x32_bf16 v[72:75], v[184:187], v[208:211], v[72:75]
	v_mfma_f32_16x16x32_bf16 v[76:79], v[188:191], v[208:211], v[76:79]
	v_mfma_f32_16x16x32_bf16 v[80:83], v[176:179], v[212:215], v[80:83]
	v_mfma_f32_16x16x32_bf16 v[84:87], v[180:183], v[212:215], v[84:87]
	v_mfma_f32_16x16x32_bf16 v[88:91], v[184:187], v[212:215], v[88:91]
	v_mfma_f32_16x16x32_bf16 v[92:95], v[188:191], v[212:215], v[92:95]
	v_mfma_f32_16x16x32_bf16 v[96:99], v[176:179], v[216:219], v[96:99]
	v_mfma_f32_16x16x32_bf16 v[100:103], v[180:183], v[216:219], v[100:103]
	v_mfma_f32_16x16x32_bf16 v[104:107], v[184:187], v[216:219], v[104:107]
	v_mfma_f32_16x16x32_bf16 v[108:111], v[188:191], v[216:219], v[108:111]
	v_mfma_f32_16x16x32_bf16 v[112:115], v[176:179], v[220:223], v[112:115]
	v_mfma_f32_16x16x32_bf16 v[116:119], v[180:183], v[220:223], v[116:119]
	v_mfma_f32_16x16x32_bf16 v[120:123], v[184:187], v[220:223], v[120:123]
	v_mfma_f32_16x16x32_bf16 v[124:127], v[188:191], v[220:223], v[124:127]
	s_branch .Lg6_epi
.Lg6_sw0:
	s_mul_i32 s20, s98, 5184
	s_add_u32 s20, s20, 0xe800000
	s_add_u32 s0, s92, s20
	s_addc_u32 s1, s93, 0
	v_mov_b32_e32 v224, v236
	v_mov_b32_e32 v225, v237
	v_mov_b32_e32 v226, v238
	v_mov_b32_e32 v227, v239
	s_branch .Lg6_swb0

; template <class Epi>
; DI void gemm_tile(char* smem, const bf16_t* __restrict__ A0, int lda0, int ksplit, const bf16_t* __restrict__ A1, int lda1,
;                   const bf16_t* __restrict__ Bt, int K, int row0, int col0, const Epi& epi, int tid) {
;     ...
; #pragma unroll
;   for (int m = 0; m < 8; ++m)
; #pragma unroll
;     for (int n = 0; n < 4; ++n) epi(row0 + wr * 128 + m * 16 + fr, col0 + wc * 64 + n * 16 + fq * 4, acc[m][n]);
.Lg6_epi:
	s_nop 7
	s_nop 7
	s_lshl_b32 s20, s98, 12
	s_lshl_b32 s19, s21, 2
	s_add_u32 s20, s20, s19
	s_add_u32 s4, s6, s20
	s_addc_u32 s5, s7, 0
	s_lshl_b32 s20, s98, 12
	s_lshl_b32 s19, s21, 2
	s_add_u32 s20, s20, s19
	s_add_u32 s16, s14, s20
	s_addc_u32 s17, s15, 0
	global_load_dwordx4 v[128:131], v234, s[16:17] offset:0
	global_load_dwordx4 v[132:135], v234, s[16:17] offset:64
	global_load_dwordx4 v[136:139], v234, s[16:17] offset:128
	global_load_dwordx4 v[140:143], v234, s[16:17] offset:192
	s_add_u32 s16, s16, 0x10000
	s_addc_u32 s17, s17, 0
	global_load_dwordx4 v[144:147], v234, s[16:17] offset:0
	global_load_dwordx4 v[148:151], v234, s[16:17] offset:64
	global_load_dwordx4 v[152:155], v234, s[16:17] offset:128
	global_load_dwordx4 v[156:159], v234, s[16:17] offset:192
	s_add_u32 s16, s16, 0x10000
	s_addc_u32 s17, s17, 0
	global_load_dwordx4 v[160:163], v234, s[16:17] offset:0
	global_load_dwordx4 v[164:167], v234, s[16:17] offset:64
	global_load_dwordx4 v[168:171], v234, s[16:17] offset:128
	global_load_dwordx4 v[172:175], v234, s[16:17] offset:192
	s_add_u32 s16, s16, 0x10000
	s_addc_u32 s17, s17, 0
	global_load_dwordx4 v[176:179], v234, s[16:17] offset:0
	global_load_dwordx4 v[180:183], v234, s[16:17] offset:64
	global_load_dwordx4 v[184:187], v234, s[16:17] offset:128
	global_load_dwordx4 v[188:191], v234, s[16:17] offset:192
	s_add_u32 s16, s16, 0x10000
	s_addc_u32 s17, s17, 0
	s_waitcnt vmcnt(15)
	v_pk_add_f32 v[128:129], v[128:129], v[0:1]
	v_pk_add_f32 v[130:131], v[130:131], v[2:3]
	global_store_dwordx4 v234, v[128:131], s[4:5] offset:0
	s_waitcnt vmcnt(15)
	v_pk_add_f32 v[132:133], v[132:133], v[4:5]
	v_pk_add_f32 v[134:135], v[134:135], v[6:7]
	global_store_dwordx4 v234, v[132:135], s[4:5] offset:64
	s_waitcnt vmcnt(15)
	v_pk_add_f32 v[136:137], v[136:137], v[8:9]
	v_pk_add_f32 v[138:139], v[138:139], v[10:11]
	global_store_dwordx4 v234, v[136:139], s[4:5] offset:128
	s_waitcnt vmcnt(15)
	v_pk_add_f32 v[140:141], v[140:141], v[12:13]
	v_pk_add_f32 v[142:143], v[142:143], v[14:15]
	global_store_dwordx4 v234, v[140:143], s[4:5] offset:192
	s_add_u32 s4, s4, 0x10000
	s_addc_u32 s5, s5, 0
	s_waitcnt vmcnt(15)
	v_pk_add_f32 v[144:145], v[144:145], v[16:17]
	v_pk_add_f32 v[146:147], v[146:147], v[18:19]
	global_store_dwordx4 v234, v[144:147], s[4:5] offset:0
	s_waitcnt vmcnt(15)
	v_pk_add_f32 v[148:149], v[148:149], v[20:21]
	v_pk_add_f32 v[150:151], v[150:151], v[22:23]
	global_store_dwordx4 v234, v[148:151], s[4:5] offset:64
	s_waitcnt vmcnt(15)
	v_pk_add_f32 v[152:153], v[152:153], v[24:25]
	v_pk_add_f32 v[154:155], v[154:155], v[26:27]
	global_store_dwordx4 v234, v[152:155], s[4:5] offset:128
	s_waitcnt vmcnt(15)
	v_pk_add_f32 v[156:157], v[156:157], v[28:29]
	v_pk_add_f32 v[158:159], v[158:159], v[30:31]
	global_store_dwordx4 v234, v[156:159], s[4:5] offset:192
	s_add_u32 s4, s4, 0x10000
	s_addc_u32 s5, s5, 0
	s_waitcnt vmcnt(15)
	v_pk_add_f32 v[160:161], v[160:161], v[32:33]
	v_pk_add_f32 v[162:163], v[162:163], v[34:35]
	global_store_dwordx4 v234, v[160:163], s[4:5] offset:0
	s_waitcnt vmcnt(15)
	v_pk_add_f32 v[164:165], v[164:165], v[36:37]
	v_pk_add_f32 v[166:167], v[166:167], v[38:39]
	global_store_dwordx4 v234, v[164:167], s[4:5] offset:64
	s_waitcnt vmcnt(15)
	v_pk_add_f32 v[168:169], v[168:169], v[40:41]
	v_pk_add_f32 v[170:171], v[170:171], v[42:43]
	global_store_dwordx4 v234, v[168:171], s[4:5] offset:128
	s_waitcnt vmcnt(15)
	v_pk_add_f32 v[172:173], v[172:173], v[44:45]
	v_pk_add_f32 v[174:175], v[174:175], v[46:47]
	global_store_dwordx4 v234, v[172:175], s[4:5] offset:192
	s_add_u32 s4, s4, 0x10000
	s_addc_u32 s5, s5, 0
	s_waitcnt vmcnt(15)
	v_pk_add_f32 v[176:177], v[176:177], v[48:49]
	v_pk_add_f32 v[178:179], v[178:179], v[50:51]
	global_store_dwordx4 v234, v[176:179], s[4:5] offset:0
	s_waitcnt vmcnt(15)
	v_pk_add_f32 v[180:181], v[180:181], v[52:53]
	v_pk_add_f32 v[182:183], v[182:183], v[54:55]
	global_store_dwordx4 v234, v[180:183], s[4:5] offset:64
	s_waitcnt vmcnt(15)
	v_pk_add_f32 v[184:185], v[184:185], v[56:57]
	v_pk_add_f32 v[186:187], v[186:187], v[58:59]
	global_store_dwordx4 v234, v[184:187], s[4:5] offset:128
	s_waitcnt vmcnt(15)
; template <class Epi>
; DI void gemm_tile(char* smem, const bf16_t* __restrict__ A0, int lda0, int ksplit, const bf16_t* __restrict__ A1, int lda1,
;                   const bf16_t* __restrict__ Bt, int K, int row0, int col0, const Epi& epi, int tid) {
;     ...
; #pragma unroll
;   for (int m = 0; m < 8; ++m)
; #pragma unroll
;     for (int n = 0; n < 4; ++n) epi(row0 + wr * 128 + m * 16 + fr, col0 + wc * 64 + n * 16 + fq * 4, acc[m][n]);
	v_pk_add_f32 v[188:189], v[188:189], v[60:61]
	v_pk_add_f32 v[190:191], v[190:191], v[62:63]
	global_store_dwordx4 v234, v[188:191], s[4:5] offset:192
	s_add_u32 s4, s4, 0x10000
	s_addc_u32 s5, s5, 0
	s_nop 1
	global_load_dwordx4 v[128:131], v234, s[16:17] offset:0
	global_load_dwordx4 v[132:135], v234, s[16:17] offset:64
	global_load_dwordx4 v[136:139], v234, s[16:17] offset:128
	global_load_dwordx4 v[140:143], v234, s[16:17] offset:192
	s_add_u32 s16, s16, 0x10000
	s_addc_u32 s17, s17, 0
	global_load_dwordx4 v[144:147], v234, s[16:17] offset:0
	global_load_dwordx4 v[148:151], v234, s[16:17] offset:64
	global_load_dwordx4 v[152:155], v234, s[16:17] offset:128
	global_load_dwordx4 v[156:159], v234, s[16:17] offset:192
	s_add_u32 s16, s16, 0x10000
	s_addc_u32 s17, s17, 0
	global_load_dwordx4 v[160:163], v234, s[16:17] offset:0
	global_load_dwordx4 v[164:167], v234, s[16:17] offset:64
	global_load_dwordx4 v[168:171], v234, s[16:17] offset:128
	global_load_dwordx4 v[172:175], v234, s[16:17] offset:192
	s_add_u32 s16, s16, 0x10000
	s_addc_u32 s17, s17, 0
	global_load_dwordx4 v[176:179], v234, s[16:17] offset:0
	global_load_dwordx4 v[180:183], v234, s[16:17] offset:64
	global_load_dwordx4 v[184:187], v234, s[16:17] offset:128
	global_load_dwordx4 v[188:191], v234, s[16:17] offset:192
	s_waitcnt vmcnt(15)
	v_pk_add_f32 v[128:129], v[128:129], v[64:65]
	v_pk_add_f32 v[130:131], v[130:131], v[66:67]
	global_store_dwordx4 v234, v[128:131], s[4:5] offset:0
	s_waitcnt vmcnt(15)
	v_pk_add_f32 v[132:133], v[132:133], v[68:69]
	v_pk_add_f32 v[134:135], v[134:135], v[70:71]
	global_store_dwordx4 v234, v[132:135], s[4:5] offset:64
	s_waitcnt vmcnt(15)
	v_pk_add_f32 v[136:137], v[136:137], v[72:73]
	v_pk_add_f32 v[138:139], v[138:139], v[74:75]
	global_store_dwordx4 v234, v[136:139], s[4:5] offset:128
	s_waitcnt vmcnt(15)
	v_pk_add_f32 v[140:141], v[140:141], v[76:77]
	v_pk_add_f32 v[142:143], v[142:143], v[78:79]
	global_store_dwordx4 v234, v[140:143], s[4:5] offset:192
	s_add_u32 s4, s4, 0x10000
	s_addc_u32 s5, s5, 0
	s_waitcnt vmcnt(15)
	v_pk_add_f32 v[144:145], v[144:145], v[80:81]
	v_pk_add_f32 v[146:147], v[146:147], v[82:83]
	global_store_dwordx4 v234, v[144:147], s[4:5] offset:0
	s_waitcnt vmcnt(15)
	v_pk_add_f32 v[148:149], v[148:149], v[84:85]
	v_pk_add_f32 v[150:151], v[150:151], v[86:87]
	global_store_dwordx4 v234, v[148:151], s[4:5] offset:64
	s_waitcnt vmcnt(15)
	v_pk_add_f32 v[152:153], v[152:153], v[88:89]
	v_pk_add_f32 v[154:155], v[154:155], v[90:91]
	global_store_dwordx4 v234, v[152:155], s[4:5] offset:128
	s_waitcnt vmcnt(15)
	v_pk_add_f32 v[156:157], v[156:157], v[92:93]
	v_pk_add_f32 v[158:159], v[158:159], v[94:95]
	global_store_dwordx4 v234, v[156:159], s[4:5] offset:192
	s_add_u32 s4, s4, 0x10000
	s_addc_u32 s5, s5, 0
	s_waitcnt vmcnt(15)
	v_pk_add_f32 v[160:161], v[160:161], v[96:97]
	v_pk_add_f32 v[162:163], v[162:163], v[98:99]
	global_store_dwordx4 v234, v[160:163], s[4:5] offset:0
	s_waitcnt vmcnt(15)
	v_pk_add_f32 v[164:165], v[164:165], v[100:101]
	v_pk_add_f32 v[166:167], v[166:167], v[102:103]
	global_store_dwordx4 v234, v[164:167], s[4:5] offset:64
	s_waitcnt vmcnt(15)
	v_pk_add_f32 v[168:169], v[168:169], v[104:105]
	v_pk_add_f32 v[170:171], v[170:171], v[106:107]
	global_store_dwordx4 v234, v[168:171], s[4:5] offset:128
	s_waitcnt vmcnt(15)
	v_pk_add_f32 v[172:173], v[172:173], v[108:109]
	v_pk_add_f32 v[174:175], v[174:175], v[110:111]
	global_store_dwordx4 v234, v[172:175], s[4:5] offset:192
	s_add_u32 s4, s4, 0x10000
	s_addc_u32 s5, s5, 0
	s_waitcnt vmcnt(15)
	v_pk_add_f32 v[176:177], v[176:177], v[112:113]
	v_pk_add_f32 v[178:179], v[178:179], v[114:115]
	global_store_dwordx4 v234, v[176:179], s[4:5] offset:0
	s_waitcnt vmcnt(15)
	v_pk_add_f32 v[180:181], v[180:181], v[116:117]
	v_pk_add_f32 v[182:183], v[182:183], v[118:119]
	global_store_dwordx4 v234, v[180:183], s[4:5] offset:64
	s_waitcnt vmcnt(15)
	v_pk_add_f32 v[184:185], v[184:185], v[120:121]
	v_pk_add_f32 v[186:187], v[186:187], v[122:123]
	global_store_dwordx4 v234, v[184:187], s[4:5] offset:128
	s_waitcnt vmcnt(15)
	v_pk_add_f32 v[188:189], v[188:189], v[124:125]
	v_pk_add_f32 v[190:191], v[190:191], v[126:127]
	global_store_dwordx4 v234, v[188:191], s[4:5] offset:192
	s_add_u32 s4, s4, 0x10000
	s_addc_u32 s5, s5, 0
	s_nop 1
	s_add_u32 s9, s9, 64
	s_branch .Lg6_tile

; #define LWRITE(S, buf) do { bf16_t* sA_ = sbase + (buf) * BUF; bf16_t* sB_ = sA_ + 256 * PITCH; \
;     _Pragma("unroll") for (int i_ = 0; i_ < 4; ++i_) *(u32x4*)(sA_ + (sr + i_ * 64) * PITCH + scv * 8) = ra[S][i_]; \
;     _Pragma("unroll") for (int i_ = 0; i_ < 2; ++i_) *(u32x4*)(sB_ + (sr + i_ * 64) * PITCH + scv * 8) = rb[S][i_]; } while (0)
; template <class Epi>
; DI void gemm_tile(char* smem, const bf16_t* __restrict__ A0, int lda0, int ksplit, const bf16_t* __restrict__ A1, int lda1,
;                   const bf16_t* __restrict__ Bt, int K, int row0, int col0, const Epi& epi, int tid) {
;   constexpr int BK = 32, PITCH = 40, BUF = (256 + 128) * PITCH;
;   bf16_t* sbase = (bf16_t*)smem;
;   const int lane = tid & 63, wid = tid >> 6, wr = wid >> 1, wc = wid & 1, fr = lane & 15, fq = lane >> 4;
;   f32x4 acc[8][4];
; #pragma unroll
;   for (int m = 0; m < 8; ++m)
; #pragma unroll
;     for (int n = 0; n < 4; ++n) acc[m][n] = (f32x4){0.f, 0.f, 0.f, 0.f};
;   u32x4 ra[2][4], rb[2][2];
;   const int nk = K / BK;
;   const int sr = tid >> 2, scv = tid & 3;
;     ...
;   __syncthreads();
;   {
;     const int last = nk - 1;
;     GLOAD(0, 0);
;     __builtin_amdgcn_sched_barrier(0);
;     GLOAD(1, 1);
;     __builtin_amdgcn_sched_barrier(0);
;     LWRITE(0, 0);
;     __builtin_amdgcn_sched_barrier(0);
;     GLOAD(0, (2 < last ? 2 : last));
;     __builtin_amdgcn_sched_barrier(0);
;     __syncthreads();
; template <class Epi>
; DI void gemm_phase(char* smem, const bf16_t* A0, int lda0, int ksplit, const bf16_t* A1, int lda1, const bf16_t* Bt, int K, int nN, const Epi& epi, int tid) {
;     ...
;   if ((G & 7) == 0) {
;     const int x = blockIdx.x & 7, l = blockIdx.x >> 3, L = G >> 3, per = 8 * nN, tot = 2 * per;
;     for (int q = l; q < tot; q += L) { const int rgl = q / per, rem = q % per, ct = rem >> 3, rt = (x * 2 + rgl) * 8 + (rem & 7);
;       gemm_tile(smem, A0, lda0, ksplit, A1, lda1, Bt, K, rt * 256, ct * 128, epi, tid); }
.LBB0_901:
	s_cmp_gt_i32 s94, 8
	s_cselect_b64 s[0:1], -1, 0
	s_cmp_lt_i32 s95, 9
	s_cselect_b64 s[2:3], -1, 0
	s_or_b64 s[0:1], s[0:1], s[2:3]
	s_and_b64 vcc, exec, s[0:1]
	s_cbranch_vccnz .LBB0_929
	s_add_u32 s2, s92, 0x3800000
	s_waitcnt lgkmcnt(0)
	s_load_dword s14, s[74:75], 0x180
	s_addc_u32 s3, s93, 0
	s_add_u32 s4, s92, 0xbc0000
	s_addc_u32 s5, s93, 0
	s_add_u32 s0, s92, 0x7800000
	s_addc_u32 s1, s93, 0
	s_and_b32 s16, s72, 0xffffffc0
	v_mbcnt_hi_u32_b32 v195, -1, v194
	s_waitcnt lgkmcnt(0)
	s_and_b32 s15, s14, 7
	s_cmp_lg_u32 s15, 0
	s_waitcnt vmcnt(16)
	v_add_u32_e32 v196, s16, v195
	v_mbcnt_lo_u32_b32 v240, -1, 0
	v_mbcnt_hi_u32_b32 v240, -1, v240
	s_lshr_b32 s12, s72, 6
	s_lshl_b32 s101, s12, 10
	v_and_b32_e32 v241, 15, v240
	v_lshrrev_b32_e32 v242, 4, v240
	v_bfe_u32 v243, v240, 3, 1
	v_mul_u32_u24_e32 v243, 3, v243
	v_xor_b32_e32 v243, v242, v243
	v_lshlrev_b32_e32 v243, 4, v243
	v_lshl_add_u32 v243, v241, 6, v243
	s_lshr_b32 s11, s12, 1
	s_lshl_b32 s11, s11, 13
	v_add_u32_e32 v230, s11, v243
	s_and_b32 s11, s12, 1
	s_lshl_b32 s11, s11, 12
	s_add_u32 s11, s11, 16384
	v_add_u32_e32 v231, s11, v243
	s_lshr_b32 s11, s12, 1
	s_lshl_b32 s11, s11, 7
	v_add_u32_e32 v244, s11, v241
	s_and_b32 s11, s12, 1
	s_lshl_b32 s11, s11, 6
	v_lshl_add_u32 v245, v242, 2, s11
	s_movk_i32 s11, 0x2000
	v_mul_lo_u32 v246, v244, s11
	v_lshl_add_u32 v234, v245, 1, v246
	v_lshrrev_b32_e32 v241, 2, v240
	s_lshl_b32 s11, s12, 4
	v_add_u32_e32 v241, s11, v241
	v_bfe_u32 v242, v240, 5, 1
	v_mul_u32_u24_e32 v242, 3, v242
	v_and_b32_e32 v243, 3, v240
	v_xor_b32_e32 v243, v243, v242
	v_lshlrev_b32_e32 v243, 4, v243
	s_mov_b32 s11, 2048
	v_mad_u32_u24 v224, v241, s11, v243
	v_add_u32_e32 v225, 0x20000, v224
	v_add_u32_e32 v226, 0x40000, v224
	v_add_u32_e32 v227, 0x60000, v224
	s_mov_b32 s11, 2048
	v_mad_u32_u24 v228, v241, s11, v243
	v_add_u32_e32 v229, 0x20000, v228
	s_lshr_b32 s17, s96, 3
	s_and_b32 s20, s96, 7
	s_lshl_b32 s20, s20, 1
	s_waitcnt lgkmcnt(0)
.Lg8_tile:
	s_cmpk_ge_u32 s17, 512
	s_cbranch_scc1 .Lg8_done
	s_cmpk_ge_u32 s17, 256
	s_cselect_b32 s12, 1, 0
	s_cselect_b32 s11, 256, 0
	s_sub_u32 s11, s17, s11
	s_and_b32 s18, s11, 7
	s_lshl_b32 s18, s18, 3
	s_bfe_u32 s13, s11, 0x30003
	s_or_b32 s18, s18, s13
	s_andn2_b32 s11, s11, 63
	s_or_b32 s11, s11, s18
	s_add_u32 s12, s12, s20
	s_lshl_b32 s12, s12, 3
	s_and_b32 s18, s11, 7
	s_add_u32 s18, s18, s12
	s_lshl_b32 s18, s18, 8
	s_lshr_b32 s13, s11, 3
	s_lshl_b32 s13, s13, 7
	s_mul_i32 s12, s18, 2048
	s_add_u32 s12, s12, 0x3800000
	s_add_u32 s0, s92, s12
	s_addc_u32 s1, s93, 0
	s_mul_i32 s12, s13, 2048
	s_add_u32 s12, s12, 0xbc0000
	s_add_u32 s2, s92, s12
	s_addc_u32 s3, s93, 0
	s_mov_b32 s100, 0
	s_mov_b32 s19, 0
	s_add_u32 s11, s19, s101
	s_add_u32 m0, s11, 0
	s_nop 0
	global_load_lds_dwordx4 v224, s[0:1]
	s_add_u32 m0, s11, 4096
	s_nop 0
	global_load_lds_dwordx4 v225, s[0:1]
	s_add_u32 m0, s11, 8192
	s_nop 0
	global_load_lds_dwordx4 v226, s[0:1]
	s_add_u32 m0, s11, 12288
	s_nop 0
	global_load_lds_dwordx4 v227, s[0:1]
	s_add_u32 m0, s11, 16384
	s_nop 0
	global_load_lds_dwordx4 v228, s[2:3]
	s_add_u32 m0, s11, 20480
	s_nop 0
	global_load_lds_dwordx4 v229, s[2:3]
	s_add_u32 s0, s0, 64
	s_addc_u32 s1, s1, 0
	s_add_u32 s2, s2, 64
	s_addc_u32 s3, s3, 0
	s_add_u32 s100, s100, 1
	s_add_u32 s19, s19, 24576
	s_cmp_eq_u32 s19, 73728
	s_cselect_b32 s19, 0, s19
	s_add_u32 s11, s19, s101
	s_add_u32 m0, s11, 0
	s_nop 0
	global_load_lds_dwordx4 v224, s[0:1]
	s_add_u32 m0, s11, 4096
	s_nop 0
	global_load_lds_dwordx4 v225, s[0:1]
	s_add_u32 m0, s11, 8192
	s_nop 0
	global_load_lds_dwordx4 v226, s[0:1]
	s_add_u32 m0, s11, 12288
	s_nop 0
	global_load_lds_dwordx4 v227, s[0:1]
	s_add_u32 m0, s11, 16384
	s_nop 0
	global_load_lds_dwordx4 v228, s[2:3]
	s_add_u32 m0, s11, 20480
	s_nop 0
	global_load_lds_dwordx4 v229, s[2:3]
	s_add_u32 s0, s0, 64
	s_addc_u32 s1, s1, 0
	s_add_u32 s2, s2, 64
	s_addc_u32 s3, s3, 0
	s_add_u32 s100, s100, 1
	s_add_u32 s19, s19, 24576
	s_cmp_eq_u32 s19, 73728
	s_cselect_b32 s19, 0, s19
	s_add_u32 s11, s19, s101
	s_add_u32 m0, s11, 0
	s_nop 0
	global_load_lds_dwordx4 v224, s[0:1]
	s_add_u32 m0, s11, 4096
	s_nop 0
	global_load_lds_dwordx4 v225, s[0:1]
	s_add_u32 m0, s11, 8192
	s_nop 0
	global_load_lds_dwordx4 v226, s[0:1]
	s_add_u32 m0, s11, 12288
	s_nop 0
	global_load_lds_dwordx4 v227, s[0:1]
	s_add_u32 m0, s11, 16384
	s_nop 0
	global_load_lds_dwordx4 v228, s[2:3]
	s_add_u32 m0, s11, 20480
	s_nop 0
	global_load_lds_dwordx4 v229, s[2:3]
	s_add_u32 s0, s0, 64
	s_addc_u32 s1, s1, 0
	s_add_u32 s2, s2, 64
	s_addc_u32 s3, s3, 0
	s_add_u32 s100, s100, 1
	s_add_u32 s19, s19, 24576
	s_cmp_eq_u32 s19, 73728
	s_cselect_b32 s19, 0, s19
	v_mov_b32_e32 v0, 0
	v_mov_b32_e32 v1, 0
	v_mov_b32_e32 v2, 0
	v_mov_b32_e32 v3, 0
	v_mov_b32_e32 v4, 0
	v_mov_b32_e32 v5, 0
	v_mov_b32_e32 v6, 0
	v_mov_b32_e32 v7, 0
	v_mov_b32_e32 v8, 0
	v_mov_b32_e32 v9, 0
	v_mov_b32_e32 v10, 0
	v_mov_b32_e32 v11, 0
	v_mov_b32_e32 v12, 0
	v_mov_b32_e32 v13, 0
	v_mov_b32_e32 v14, 0
	v_mov_b32_e32 v15, 0
	v_mov_b32_e32 v16, 0
	v_mov_b32_e32 v17, 0
	v_mov_b32_e32 v18, 0
	v_mov_b32_e32 v19, 0
	v_mov_b32_e32 v20, 0
	v_mov_b32_e32 v21, 0
	v_mov_b32_e32 v22, 0
	v_mov_b32_e32 v23, 0
	v_mov_b32_e32 v24, 0
	v_mov_b32_e32 v25, 0
	v_mov_b32_e32 v26, 0
	v_mov_b32_e32 v27, 0
	v_mov_b32_e32 v28, 0
	v_mov_b32_e32 v29, 0
	v_mov_b32_e32 v30, 0
	v_mov_b32_e32 v31, 0
	v_mov_b32_e32 v32, 0
	v_mov_b32_e32 v33, 0
	v_mov_b32_e32 v34, 0
	v_mov_b32_e32 v35, 0
	v_mov_b32_e32 v36, 0
	v_mov_b32_e32 v37, 0
	v_mov_b32_e32 v38, 0
	v_mov_b32_e32 v39, 0
	v_mov_b32_e32 v40, 0
	v_mov_b32_e32 v41, 0
	v_mov_b32_e32 v42, 0
	v_mov_b32_e32 v43, 0
	v_mov_b32_e32 v44, 0
	v_mov_b32_e32 v45, 0
; #define LWRITE(S, buf) do { bf16_t* sA_ = sbase + (buf) * BUF; bf16_t* sB_ = sA_ + 256 * PITCH; \
;     _Pragma("unroll") for (int i_ = 0; i_ < 4; ++i_) *(u32x4*)(sA_ + (sr + i_ * 64) * PITCH + scv * 8) = ra[S][i_]; \
;     _Pragma("unroll") for (int i_ = 0; i_ < 2; ++i_) *(u32x4*)(sB_ + (sr + i_ * 64) * PITCH + scv * 8) = rb[S][i_]; } while (0)
; template <class Epi>
; DI void gemm_tile(char* smem, const bf16_t* __restrict__ A0, int lda0, int ksplit, const bf16_t* __restrict__ A1, int lda1,
;                   const bf16_t* __restrict__ Bt, int K, int row0, int col0, const Epi& epi, int tid) {
;     ...
;   f32x4 acc[8][4];
; #pragma unroll
;   for (int m = 0; m < 8; ++m)
; #pragma unroll
;     for (int n = 0; n < 4; ++n) acc[m][n] = (f32x4){0.f, 0.f, 0.f, 0.f};
;   u32x4 ra[2][4], rb[2][2];
;   const int nk = K / BK;
;   const int sr = tid >> 2, scv = tid & 3;
;     ...
;   __syncthreads();
;   {
;     const int last = nk - 1;
;     GLOAD(0, 0);
;     __builtin_amdgcn_sched_barrier(0);
;     GLOAD(1, 1);
;     __builtin_amdgcn_sched_barrier(0);
;     LWRITE(0, 0);
;     __builtin_amdgcn_sched_barrier(0);
;     GLOAD(0, (2 < last ? 2 : last));
;     __builtin_amdgcn_sched_barrier(0);
;     __syncthreads();
;     for (int kt = 0; kt < nk; kt += 2) {
;       LWRITE(1, 1);
;       __builtin_amdgcn_sched_barrier(0);
;       GLOAD(1, (kt + 3 < last ? kt + 3 : last));
;       __builtin_amdgcn_sched_barrier(0);
;       COMPUTE(0);
;       __syncthreads();
;       LWRITE(0, 0);
;       __builtin_amdgcn_sched_barrier(0);
;       GLOAD(0, (kt + 4 < last ? kt + 4 : last));
;       __builtin_amdgcn_sched_barrier(0);
;       COMPUTE(1);
;       __syncthreads();
;     }
	v_mov_b32_e32 v46, 0
	v_mov_b32_e32 v47, 0
	v_mov_b32_e32 v48, 0
	v_mov_b32_e32 v49, 0
	v_mov_b32_e32 v50, 0
	v_mov_b32_e32 v51, 0
	v_mov_b32_e32 v52, 0
	v_mov_b32_e32 v53, 0
	v_mov_b32_e32 v54, 0
	v_mov_b32_e32 v55, 0
	v_mov_b32_e32 v56, 0
	v_mov_b32_e32 v57, 0
	v_mov_b32_e32 v58, 0
	v_mov_b32_e32 v59, 0
	v_mov_b32_e32 v60, 0
	v_mov_b32_e32 v61, 0
	v_mov_b32_e32 v62, 0
	v_mov_b32_e32 v63, 0
	v_mov_b32_e32 v64, 0
	v_mov_b32_e32 v65, 0
	v_mov_b32_e32 v66, 0
	v_mov_b32_e32 v67, 0
	v_mov_b32_e32 v68, 0
	v_mov_b32_e32 v69, 0
	v_mov_b32_e32 v70, 0
	v_mov_b32_e32 v71, 0
	v_mov_b32_e32 v72, 0
	v_mov_b32_e32 v73, 0
	v_mov_b32_e32 v74, 0
	v_mov_b32_e32 v75, 0
	v_mov_b32_e32 v76, 0
	v_mov_b32_e32 v77, 0
	v_mov_b32_e32 v78, 0
	v_mov_b32_e32 v79, 0
	v_mov_b32_e32 v80, 0
	v_mov_b32_e32 v81, 0
	v_mov_b32_e32 v82, 0
	v_mov_b32_e32 v83, 0
	v_mov_b32_e32 v84, 0
	v_mov_b32_e32 v85, 0
	v_mov_b32_e32 v86, 0
	v_mov_b32_e32 v87, 0
	v_mov_b32_e32 v88, 0
	v_mov_b32_e32 v89, 0
	v_mov_b32_e32 v90, 0
	v_mov_b32_e32 v91, 0
	v_mov_b32_e32 v92, 0
	v_mov_b32_e32 v93, 0
	v_mov_b32_e32 v94, 0
	v_mov_b32_e32 v95, 0
	v_mov_b32_e32 v96, 0
	v_mov_b32_e32 v97, 0
	v_mov_b32_e32 v98, 0
	v_mov_b32_e32 v99, 0
	v_mov_b32_e32 v100, 0
	v_mov_b32_e32 v101, 0
	v_mov_b32_e32 v102, 0
	v_mov_b32_e32 v103, 0
	v_mov_b32_e32 v104, 0
	v_mov_b32_e32 v105, 0
	v_mov_b32_e32 v106, 0
	v_mov_b32_e32 v107, 0
	v_mov_b32_e32 v108, 0
	v_mov_b32_e32 v109, 0
	v_mov_b32_e32 v110, 0
	v_mov_b32_e32 v111, 0
	v_mov_b32_e32 v112, 0
	v_mov_b32_e32 v113, 0
	v_mov_b32_e32 v114, 0
	v_mov_b32_e32 v115, 0
	v_mov_b32_e32 v116, 0
	v_mov_b32_e32 v117, 0
	v_mov_b32_e32 v118, 0
	v_mov_b32_e32 v119, 0
	v_mov_b32_e32 v120, 0
	v_mov_b32_e32 v121, 0
	v_mov_b32_e32 v122, 0
	v_mov_b32_e32 v123, 0
	v_mov_b32_e32 v124, 0
	v_mov_b32_e32 v125, 0
	v_mov_b32_e32 v126, 0
	v_mov_b32_e32 v127, 0
	s_mov_b32 s99, 0
	s_mov_b32 s98, 24576
	s_waitcnt vmcnt(12)
	s_barrier
	ds_read_b128 v[128:131], v231 offset:0
	ds_read_b128 v[132:135], v231 offset:1024
	ds_read_b128 v[136:139], v231 offset:2048
	ds_read_b128 v[140:143], v231 offset:3072
	ds_read_b128 v[144:147], v230 offset:0
	ds_read_b128 v[148:151], v230 offset:1024
	ds_read_b128 v[152:155], v230 offset:2048
	ds_read_b128 v[156:159], v230 offset:3072
	ds_read_b128 v[160:163], v230 offset:4096
	ds_read_b128 v[164:167], v230 offset:5120
	ds_read_b128 v[168:171], v230 offset:6144
	ds_read_b128 v[172:175], v230 offset:7168
.Lg8_kloop:
	s_waitcnt vmcnt(6)
	s_waitcnt lgkmcnt(0)
	s_barrier
	v_add_u32_e32 v232, s98, v230
	v_add_u32_e32 v233, s98, v231
	s_add_u32 s11, s19, s101
	v_mfma_f32_16x16x32_bf16 v[0:3], v[128:131], v[144:147], v[0:3]
	v_mfma_f32_16x16x32_bf16 v[4:7], v[132:135], v[144:147], v[4:7]
	v_mfma_f32_16x16x32_bf16 v[8:11], v[136:139], v[144:147], v[8:11]
	v_mfma_f32_16x16x32_bf16 v[12:15], v[140:143], v[144:147], v[12:15]
	ds_read_b128 v[176:179], v233 offset:0
	ds_read_b128 v[180:183], v233 offset:1024
	s_add_u32 m0, s11, 0
	s_nop 0
	global_load_lds_dwordx4 v224, s[0:1]
	v_mfma_f32_16x16x32_bf16 v[16:19], v[128:131], v[148:151], v[16:19]
	v_mfma_f32_16x16x32_bf16 v[20:23], v[132:135], v[148:151], v[20:23]
	v_mfma_f32_16x16x32_bf16 v[24:27], v[136:139], v[148:151], v[24:27]
	v_mfma_f32_16x16x32_bf16 v[28:31], v[140:143], v[148:151], v[28:31]
	ds_read_b128 v[184:187], v233 offset:2048
	ds_read_b128 v[188:191], v233 offset:3072
	s_add_u32 m0, s11, 4096
	s_nop 0
	global_load_lds_dwordx4 v225, s[0:1]
	v_mfma_f32_16x16x32_bf16 v[32:35], v[128:131], v[152:155], v[32:35]
	v_mfma_f32_16x16x32_bf16 v[36:39], v[132:135], v[152:155], v[36:39]
	v_mfma_f32_16x16x32_bf16 v[40:43], v[136:139], v[152:155], v[40:43]
	v_mfma_f32_16x16x32_bf16 v[44:47], v[140:143], v[152:155], v[44:47]
	ds_read_b128 v[192:195], v232 offset:0
	ds_read_b128 v[196:199], v232 offset:1024
	s_add_u32 m0, s11, 8192
	s_nop 0
	global_load_lds_dwordx4 v226, s[0:1]
	v_mfma_f32_16x16x32_bf16 v[48:51], v[128:131], v[156:159], v[48:51]
	v_mfma_f32_16x16x32_bf16 v[52:55], v[132:135], v[156:159], v[52:55]
	v_mfma_f32_16x16x32_bf16 v[56:59], v[136:139], v[156:159], v[56:59]
	v_mfma_f32_16x16x32_bf16 v[60:63], v[140:143], v[156:159], v[60:63]
	ds_read_b128 v[200:203], v232 offset:2048
	ds_read_b128 v[204:207], v232 offset:3072
	s_add_u32 m0, s11, 12288
	s_nop 0
	global_load_lds_dwordx4 v227, s[0:1]
	v_mfma_f32_16x16x32_bf16 v[64:67], v[128:131], v[160:163], v[64:67]
	v_mfma_f32_16x16x32_bf16 v[68:71], v[132:135], v[160:163], v[68:71]
	v_mfma_f32_16x16x32_bf16 v[72:75], v[136:139], v[160:163], v[72:75]
	v_mfma_f32_16x16x32_bf16 v[76:79], v[140:143], v[160:163], v[76:79]
	ds_read_b128 v[208:211], v232 offset:4096
	s_add_u32 m0, s11, 16384
	s_nop 0
	global_load_lds_dwordx4 v228, s[2:3]
	v_mfma_f32_16x16x32_bf16 v[80:83], v[128:131], v[164:167], v[80:83]
	v_mfma_f32_16x16x32_bf16 v[84:87], v[132:135], v[164:167], v[84:87]
	v_mfma_f32_16x16x32_bf16 v[88:91], v[136:139], v[164:167], v[88:91]
	v_mfma_f32_16x16x32_bf16 v[92:95], v[140:143], v[164:167], v[92:95]
	ds_read_b128 v[212:215], v232 offset:5120
	s_add_u32 m0, s11, 20480
	s_nop 0
	global_load_lds_dwordx4 v229, s[2:3]
	v_mfma_f32_16x16x32_bf16 v[96:99], v[128:131], v[168:171], v[96:99]
	v_mfma_f32_16x16x32_bf16 v[100:103], v[132:135], v[168:171], v[100:103]
	v_mfma_f32_16x16x32_bf16 v[104:107], v[136:139], v[168:171], v[104:107]
	v_mfma_f32_16x16x32_bf16 v[108:111], v[140:143], v[168:171], v[108:111]
	ds_read_b128 v[216:219], v232 offset:6144
	s_add_u32 s0, s0, 64
	s_addc_u32 s1, s1, 0
	s_add_u32 s2, s2, 64
	s_addc_u32 s3, s3, 0
	s_add_u32 s100, s100, 1
	s_add_u32 s19, s19, 24576
	s_cmp_eq_u32 s19, 73728
	s_cselect_b32 s19, 0, s19
	s_add_u32 s98, s98, 24576
	s_cmp_eq_u32 s98, 73728
	s_cselect_b32 s98, 0, s98
	v_mfma_f32_16x16x32_bf16 v[112:115], v[128:131], v[172:175], v[112:115]
	v_mfma_f32_16x16x32_bf16 v[116:119], v[132:135], v[172:175], v[116:119]
	v_mfma_f32_16x16x32_bf16 v[120:123], v[136:139], v[172:175], v[120:123]
	v_mfma_f32_16x16x32_bf16 v[124:127], v[140:143], v[172:175], v[124:127]
	ds_read_b128 v[220:223], v232 offset:7168
	s_waitcnt vmcnt(6)
	s_waitcnt lgkmcnt(0)
	s_barrier
; #define LWRITE(S, buf) do { bf16_t* sA_ = sbase + (buf) * BUF; bf16_t* sB_ = sA_ + 256 * PITCH; \
;     _Pragma("unroll") for (int i_ = 0; i_ < 4; ++i_) *(u32x4*)(sA_ + (sr + i_ * 64) * PITCH + scv * 8) = ra[S][i_]; \
;     _Pragma("unroll") for (int i_ = 0; i_ < 2; ++i_) *(u32x4*)(sB_ + (sr + i_ * 64) * PITCH + scv * 8) = rb[S][i_]; } while (0)
; template <class Epi>
; DI void gemm_tile(char* smem, const bf16_t* __restrict__ A0, int lda0, int ksplit, const bf16_t* __restrict__ A1, int lda1,
;                   const bf16_t* __restrict__ Bt, int K, int row0, int col0, const Epi& epi, int tid) {
;     ...
;     for (int kt = 0; kt < nk; kt += 2) {
;       LWRITE(1, 1);
;       __builtin_amdgcn_sched_barrier(0);
;       GLOAD(1, (kt + 3 < last ? kt + 3 : last));
;       __builtin_amdgcn_sched_barrier(0);
;       COMPUTE(0);
;       __syncthreads();
;       LWRITE(0, 0);
;       __builtin_amdgcn_sched_barrier(0);
;       GLOAD(0, (kt + 4 < last ? kt + 4 : last));
;       __builtin_amdgcn_sched_barrier(0);
;       COMPUTE(1);
;       __syncthreads();
;     }
	v_add_u32_e32 v232, s98, v230
	v_add_u32_e32 v233, s98, v231
	s_add_u32 s11, s19, s101
	v_mfma_f32_16x16x32_bf16 v[0:3], v[176:179], v[192:195], v[0:3]
	v_mfma_f32_16x16x32_bf16 v[4:7], v[180:183], v[192:195], v[4:7]
	v_mfma_f32_16x16x32_bf16 v[8:11], v[184:187], v[192:195], v[8:11]
	v_mfma_f32_16x16x32_bf16 v[12:15], v[188:191], v[192:195], v[12:15]
	ds_read_b128 v[128:131], v233 offset:0
	ds_read_b128 v[132:135], v233 offset:1024
	s_add_u32 m0, s11, 0
	s_nop 0
	global_load_lds_dwordx4 v224, s[0:1]
	v_mfma_f32_16x16x32_bf16 v[16:19], v[176:179], v[196:199], v[16:19]
	v_mfma_f32_16x16x32_bf16 v[20:23], v[180:183], v[196:199], v[20:23]
	v_mfma_f32_16x16x32_bf16 v[24:27], v[184:187], v[196:199], v[24:27]
	v_mfma_f32_16x16x32_bf16 v[28:31], v[188:191], v[196:199], v[28:31]
	ds_read_b128 v[136:139], v233 offset:2048
	ds_read_b128 v[140:143], v233 offset:3072
	s_add_u32 m0, s11, 4096
	s_nop 0
	global_load_lds_dwordx4 v225, s[0:1]
	v_mfma_f32_16x16x32_bf16 v[32:35], v[176:179], v[200:203], v[32:35]
	v_mfma_f32_16x16x32_bf16 v[36:39], v[180:183], v[200:203], v[36:39]
	v_mfma_f32_16x16x32_bf16 v[40:43], v[184:187], v[200:203], v[40:43]
	v_mfma_f32_16x16x32_bf16 v[44:47], v[188:191], v[200:203], v[44:47]
	ds_read_b128 v[144:147], v232 offset:0
	ds_read_b128 v[148:151], v232 offset:1024
	s_add_u32 m0, s11, 8192
	s_nop 0
	global_load_lds_dwordx4 v226, s[0:1]
	v_mfma_f32_16x16x32_bf16 v[48:51], v[176:179], v[204:207], v[48:51]
	v_mfma_f32_16x16x32_bf16 v[52:55], v[180:183], v[204:207], v[52:55]
	v_mfma_f32_16x16x32_bf16 v[56:59], v[184:187], v[204:207], v[56:59]
	v_mfma_f32_16x16x32_bf16 v[60:63], v[188:191], v[204:207], v[60:63]
	ds_read_b128 v[152:155], v232 offset:2048
	ds_read_b128 v[156:159], v232 offset:3072
	s_add_u32 m0, s11, 12288
	s_nop 0
	global_load_lds_dwordx4 v227, s[0:1]
	v_mfma_f32_16x16x32_bf16 v[64:67], v[176:179], v[208:211], v[64:67]
	v_mfma_f32_16x16x32_bf16 v[68:71], v[180:183], v[208:211], v[68:71]
	v_mfma_f32_16x16x32_bf16 v[72:75], v[184:187], v[208:211], v[72:75]
	v_mfma_f32_16x16x32_bf16 v[76:79], v[188:191], v[208:211], v[76:79]
	ds_read_b128 v[160:163], v232 offset:4096
	s_add_u32 m0, s11, 16384
	s_nop 0
	global_load_lds_dwordx4 v228, s[2:3]
	v_mfma_f32_16x16x32_bf16 v[80:83], v[176:179], v[212:215], v[80:83]
	v_mfma_f32_16x16x32_bf16 v[84:87], v[180:183], v[212:215], v[84:87]
	v_mfma_f32_16x16x32_bf16 v[88:91], v[184:187], v[212:215], v[88:91]
	v_mfma_f32_16x16x32_bf16 v[92:95], v[188:191], v[212:215], v[92:95]
	ds_read_b128 v[164:167], v232 offset:5120
	s_add_u32 m0, s11, 20480
	s_nop 0
	global_load_lds_dwordx4 v229, s[2:3]
	v_mfma_f32_16x16x32_bf16 v[96:99], v[176:179], v[216:219], v[96:99]
	v_mfma_f32_16x16x32_bf16 v[100:103], v[180:183], v[216:219], v[100:103]
	v_mfma_f32_16x16x32_bf16 v[104:107], v[184:187], v[216:219], v[104:107]
	v_mfma_f32_16x16x32_bf16 v[108:111], v[188:191], v[216:219], v[108:111]
	ds_read_b128 v[168:171], v232 offset:6144
	s_add_u32 s0, s0, 64
	s_addc_u32 s1, s1, 0
	s_add_u32 s2, s2, 64
	s_addc_u32 s3, s3, 0
	s_add_u32 s100, s100, 1
	s_add_u32 s19, s19, 24576
	s_cmp_eq_u32 s19, 73728
	s_cselect_b32 s19, 0, s19
	s_add_u32 s98, s98, 24576
	s_cmp_eq_u32 s98, 73728
	s_cselect_b32 s98, 0, s98
	v_mfma_f32_16x16x32_bf16 v[112:115], v[176:179], v[220:223], v[112:115]
	v_mfma_f32_16x16x32_bf16 v[116:119], v[180:183], v[220:223], v[116:119]
	v_mfma_f32_16x16x32_bf16 v[120:123], v[184:187], v[220:223], v[120:123]
	v_mfma_f32_16x16x32_bf16 v[124:127], v[188:191], v[220:223], v[124:127]
	ds_read_b128 v[172:175], v232 offset:7168
	s_add_u32 s99, s99, 2
	s_cmp_lt_u32 s99, 28
	s_cbranch_scc1 .Lg8_kloop
	s_waitcnt vmcnt(6)
	s_waitcnt lgkmcnt(0)
	s_barrier
	v_add_u32_e32 v232, s98, v230
	v_add_u32_e32 v233, s98, v231
	s_add_u32 s11, s19, s101
	v_mfma_f32_16x16x32_bf16 v[0:3], v[128:131], v[144:147], v[0:3]
	v_mfma_f32_16x16x32_bf16 v[4:7], v[132:135], v[144:147], v[4:7]
	v_mfma_f32_16x16x32_bf16 v[8:11], v[136:139], v[144:147], v[8:11]
	v_mfma_f32_16x16x32_bf16 v[12:15], v[140:143], v[144:147], v[12:15]
	ds_read_b128 v[176:179], v233 offset:0
	ds_read_b128 v[180:183], v233 offset:1024
	s_add_u32 m0, s11, 0
	s_nop 0
	global_load_lds_dwordx4 v224, s[0:1]
	v_mfma_f32_16x16x32_bf16 v[16:19], v[128:131], v[148:151], v[16:19]
	v_mfma_f32_16x16x32_bf16 v[20:23], v[132:135], v[148:151], v[20:23]
	v_mfma_f32_16x16x32_bf16 v[24:27], v[136:139], v[148:151], v[24:27]
	v_mfma_f32_16x16x32_bf16 v[28:31], v[140:143], v[148:151], v[28:31]
	ds_read_b128 v[184:187], v233 offset:2048
	ds_read_b128 v[188:191], v233 offset:3072
	s_add_u32 m0, s11, 4096
	s_nop 0
	global_load_lds_dwordx4 v225, s[0:1]
	v_mfma_f32_16x16x32_bf16 v[32:35], v[128:131], v[152:155], v[32:35]
	v_mfma_f32_16x16x32_bf16 v[36:39], v[132:135], v[152:155], v[36:39]
	v_mfma_f32_16x16x32_bf16 v[40:43], v[136:139], v[152:155], v[40:43]
	v_mfma_f32_16x16x32_bf16 v[44:47], v[140:143], v[152:155], v[44:47]
	ds_read_b128 v[192:195], v232 offset:0
	ds_read_b128 v[196:199], v232 offset:1024
	s_add_u32 m0, s11, 8192
	s_nop 0
	global_load_lds_dwordx4 v226, s[0:1]
	v_mfma_f32_16x16x32_bf16 v[48:51], v[128:131], v[156:159], v[48:51]
	v_mfma_f32_16x16x32_bf16 v[52:55], v[132:135], v[156:159], v[52:55]
	v_mfma_f32_16x16x32_bf16 v[56:59], v[136:139], v[156:159], v[56:59]
	v_mfma_f32_16x16x32_bf16 v[60:63], v[140:143], v[156:159], v[60:63]
	ds_read_b128 v[200:203], v232 offset:2048
	ds_read_b128 v[204:207], v232 offset:3072
	s_add_u32 m0, s11, 12288
	s_nop 0
	global_load_lds_dwordx4 v227, s[0:1]
	v_mfma_f32_16x16x32_bf16 v[64:67], v[128:131], v[160:163], v[64:67]
	v_mfma_f32_16x16x32_bf16 v[68:71], v[132:135], v[160:163], v[68:71]
	v_mfma_f32_16x16x32_bf16 v[72:75], v[136:139], v[160:163], v[72:75]
; #define LWRITE(S, buf) do { bf16_t* sA_ = sbase + (buf) * BUF; bf16_t* sB_ = sA_ + 256 * PITCH; \
;     _Pragma("unroll") for (int i_ = 0; i_ < 4; ++i_) *(u32x4*)(sA_ + (sr + i_ * 64) * PITCH + scv * 8) = ra[S][i_]; \
;     _Pragma("unroll") for (int i_ = 0; i_ < 2; ++i_) *(u32x4*)(sB_ + (sr + i_ * 64) * PITCH + scv * 8) = rb[S][i_]; } while (0)
; template <class Epi>
; DI void gemm_tile(char* smem, const bf16_t* __restrict__ A0, int lda0, int ksplit, const bf16_t* __restrict__ A1, int lda1,
;                   const bf16_t* __restrict__ Bt, int K, int row0, int col0, const Epi& epi, int tid) {
;     ...
;     for (int kt = 0; kt < nk; kt += 2) {
;       LWRITE(1, 1);
;       __builtin_amdgcn_sched_barrier(0);
;       GLOAD(1, (kt + 3 < last ? kt + 3 : last));
;       __builtin_amdgcn_sched_barrier(0);
;       COMPUTE(0);
;       __syncthreads();
;       LWRITE(0, 0);
;       __builtin_amdgcn_sched_barrier(0);
;       GLOAD(0, (kt + 4 < last ? kt + 4 : last));
;       __builtin_amdgcn_sched_barrier(0);
;       COMPUTE(1);
;       __syncthreads();
;     }
	v_mfma_f32_16x16x32_bf16 v[76:79], v[140:143], v[160:163], v[76:79]
	ds_read_b128 v[208:211], v232 offset:4096
	s_add_u32 m0, s11, 16384
	s_nop 0
	global_load_lds_dwordx4 v228, s[2:3]
	v_mfma_f32_16x16x32_bf16 v[80:83], v[128:131], v[164:167], v[80:83]
	v_mfma_f32_16x16x32_bf16 v[84:87], v[132:135], v[164:167], v[84:87]
	v_mfma_f32_16x16x32_bf16 v[88:91], v[136:139], v[164:167], v[88:91]
	v_mfma_f32_16x16x32_bf16 v[92:95], v[140:143], v[164:167], v[92:95]
	ds_read_b128 v[212:215], v232 offset:5120
	s_add_u32 m0, s11, 20480
	s_nop 0
	global_load_lds_dwordx4 v229, s[2:3]
	v_mfma_f32_16x16x32_bf16 v[96:99], v[128:131], v[168:171], v[96:99]
	v_mfma_f32_16x16x32_bf16 v[100:103], v[132:135], v[168:171], v[100:103]
	v_mfma_f32_16x16x32_bf16 v[104:107], v[136:139], v[168:171], v[104:107]
	v_mfma_f32_16x16x32_bf16 v[108:111], v[140:143], v[168:171], v[108:111]
	ds_read_b128 v[216:219], v232 offset:6144
	s_add_u32 s0, s0, 64
	s_addc_u32 s1, s1, 0
	s_add_u32 s2, s2, 64
	s_addc_u32 s3, s3, 0
	s_add_u32 s100, s100, 1
	s_add_u32 s19, s19, 24576
	s_cmp_eq_u32 s19, 73728
	s_cselect_b32 s19, 0, s19
	s_add_u32 s98, s98, 24576
	s_cmp_eq_u32 s98, 73728
	s_cselect_b32 s98, 0, s98
	v_mfma_f32_16x16x32_bf16 v[112:115], v[128:131], v[172:175], v[112:115]
	v_mfma_f32_16x16x32_bf16 v[116:119], v[132:135], v[172:175], v[116:119]
	v_mfma_f32_16x16x32_bf16 v[120:123], v[136:139], v[172:175], v[120:123]
	v_mfma_f32_16x16x32_bf16 v[124:127], v[140:143], v[172:175], v[124:127]
	ds_read_b128 v[220:223], v232 offset:7168
	s_waitcnt vmcnt(6)
	s_waitcnt lgkmcnt(0)
	s_barrier
	v_add_u32_e32 v232, s98, v230
	v_add_u32_e32 v233, s98, v231
	v_mfma_f32_16x16x32_bf16 v[0:3], v[176:179], v[192:195], v[0:3]
	v_mfma_f32_16x16x32_bf16 v[4:7], v[180:183], v[192:195], v[4:7]
	v_mfma_f32_16x16x32_bf16 v[8:11], v[184:187], v[192:195], v[8:11]
	v_mfma_f32_16x16x32_bf16 v[12:15], v[188:191], v[192:195], v[12:15]
	ds_read_b128 v[128:131], v233 offset:0
	ds_read_b128 v[132:135], v233 offset:1024
	v_mfma_f32_16x16x32_bf16 v[16:19], v[176:179], v[196:199], v[16:19]
	v_mfma_f32_16x16x32_bf16 v[20:23], v[180:183], v[196:199], v[20:23]
	v_mfma_f32_16x16x32_bf16 v[24:27], v[184:187], v[196:199], v[24:27]
	v_mfma_f32_16x16x32_bf16 v[28:31], v[188:191], v[196:199], v[28:31]
	ds_read_b128 v[136:139], v233 offset:2048
	ds_read_b128 v[140:143], v233 offset:3072
	v_mfma_f32_16x16x32_bf16 v[32:35], v[176:179], v[200:203], v[32:35]
	v_mfma_f32_16x16x32_bf16 v[36:39], v[180:183], v[200:203], v[36:39]
	v_mfma_f32_16x16x32_bf16 v[40:43], v[184:187], v[200:203], v[40:43]
	v_mfma_f32_16x16x32_bf16 v[44:47], v[188:191], v[200:203], v[44:47]
	ds_read_b128 v[144:147], v232 offset:0
	ds_read_b128 v[148:151], v232 offset:1024
	v_mfma_f32_16x16x32_bf16 v[48:51], v[176:179], v[204:207], v[48:51]
	v_mfma_f32_16x16x32_bf16 v[52:55], v[180:183], v[204:207], v[52:55]
	v_mfma_f32_16x16x32_bf16 v[56:59], v[184:187], v[204:207], v[56:59]
	v_mfma_f32_16x16x32_bf16 v[60:63], v[188:191], v[204:207], v[60:63]
	ds_read_b128 v[152:155], v232 offset:2048
	ds_read_b128 v[156:159], v232 offset:3072
	v_mfma_f32_16x16x32_bf16 v[64:67], v[176:179], v[208:211], v[64:67]
	v_mfma_f32_16x16x32_bf16 v[68:71], v[180:183], v[208:211], v[68:71]
	v_mfma_f32_16x16x32_bf16 v[72:75], v[184:187], v[208:211], v[72:75]
	v_mfma_f32_16x16x32_bf16 v[76:79], v[188:191], v[208:211], v[76:79]
	ds_read_b128 v[160:163], v232 offset:4096
	v_mfma_f32_16x16x32_bf16 v[80:83], v[176:179], v[212:215], v[80:83]
	v_mfma_f32_16x16x32_bf16 v[84:87], v[180:183], v[212:215], v[84:87]
	v_mfma_f32_16x16x32_bf16 v[88:91], v[184:187], v[212:215], v[88:91]
	v_mfma_f32_16x16x32_bf16 v[92:95], v[188:191], v[212:215], v[92:95]
	ds_read_b128 v[164:167], v232 offset:5120
	v_mfma_f32_16x16x32_bf16 v[96:99], v[176:179], v[216:219], v[96:99]
	v_mfma_f32_16x16x32_bf16 v[100:103], v[180:183], v[216:219], v[100:103]
	v_mfma_f32_16x16x32_bf16 v[104:107], v[184:187], v[216:219], v[104:107]
	v_mfma_f32_16x16x32_bf16 v[108:111], v[188:191], v[216:219], v[108:111]
	ds_read_b128 v[168:171], v232 offset:6144
	s_add_u32 s98, s98, 24576
	s_cmp_eq_u32 s98, 73728
	s_cselect_b32 s98, 0, s98
	v_mfma_f32_16x16x32_bf16 v[112:115], v[176:179], v[220:223], v[112:115]
	v_mfma_f32_16x16x32_bf16 v[116:119], v[180:183], v[220:223], v[116:119]
	v_mfma_f32_16x16x32_bf16 v[120:123], v[184:187], v[220:223], v[120:123]
	v_mfma_f32_16x16x32_bf16 v[124:127], v[188:191], v[220:223], v[124:127]
	ds_read_b128 v[172:175], v232 offset:7168
	s_waitcnt vmcnt(0)
	s_waitcnt lgkmcnt(0)
	s_barrier
; #define LWRITE(S, buf) do { bf16_t* sA_ = sbase + (buf) * BUF; bf16_t* sB_ = sA_ + 256 * PITCH; \
;     _Pragma("unroll") for (int i_ = 0; i_ < 4; ++i_) *(u32x4*)(sA_ + (sr + i_ * 64) * PITCH + scv * 8) = ra[S][i_]; \
;     _Pragma("unroll") for (int i_ = 0; i_ < 2; ++i_) *(u32x4*)(sB_ + (sr + i_ * 64) * PITCH + scv * 8) = rb[S][i_]; } while (0)
; template <class Epi>
; DI void gemm_tile(char* smem, const bf16_t* __restrict__ A0, int lda0, int ksplit, const bf16_t* __restrict__ A1, int lda1,
;                   const bf16_t* __restrict__ Bt, int K, int row0, int col0, const Epi& epi, int tid) {
;     ...
;   __syncthreads();
;   {
;     const int last = nk - 1;
;     GLOAD(0, 0);
;     __builtin_amdgcn_sched_barrier(0);
;     GLOAD(1, 1);
;     __builtin_amdgcn_sched_barrier(0);
;     LWRITE(0, 0);
;     __builtin_amdgcn_sched_barrier(0);
;     GLOAD(0, (2 < last ? 2 : last));
;     __builtin_amdgcn_sched_barrier(0);
;     __syncthreads();
;     for (int kt = 0; kt < nk; kt += 2) {
;       LWRITE(1, 1);
;       __builtin_amdgcn_sched_barrier(0);
;       GLOAD(1, (kt + 3 < last ? kt + 3 : last));
;       __builtin_amdgcn_sched_barrier(0);
;       COMPUTE(0);
;       __syncthreads();
;       LWRITE(0, 0);
;       __builtin_amdgcn_sched_barrier(0);
;       GLOAD(0, (kt + 4 < last ? kt + 4 : last));
;       __builtin_amdgcn_sched_barrier(0);
;       COMPUTE(1);
;       __syncthreads();
;     }
	v_add_u32_e32 v232, s98, v230
	v_add_u32_e32 v233, s98, v231
	v_mfma_f32_16x16x32_bf16 v[0:3], v[128:131], v[144:147], v[0:3]
	v_mfma_f32_16x16x32_bf16 v[4:7], v[132:135], v[144:147], v[4:7]
	v_mfma_f32_16x16x32_bf16 v[8:11], v[136:139], v[144:147], v[8:11]
	v_mfma_f32_16x16x32_bf16 v[12:15], v[140:143], v[144:147], v[12:15]
	ds_read_b128 v[176:179], v233 offset:0
	ds_read_b128 v[180:183], v233 offset:1024
	v_mfma_f32_16x16x32_bf16 v[16:19], v[128:131], v[148:151], v[16:19]
	v_mfma_f32_16x16x32_bf16 v[20:23], v[132:135], v[148:151], v[20:23]
	v_mfma_f32_16x16x32_bf16 v[24:27], v[136:139], v[148:151], v[24:27]
	v_mfma_f32_16x16x32_bf16 v[28:31], v[140:143], v[148:151], v[28:31]
	ds_read_b128 v[184:187], v233 offset:2048
	ds_read_b128 v[188:191], v233 offset:3072
	v_mfma_f32_16x16x32_bf16 v[32:35], v[128:131], v[152:155], v[32:35]
	v_mfma_f32_16x16x32_bf16 v[36:39], v[132:135], v[152:155], v[36:39]
	v_mfma_f32_16x16x32_bf16 v[40:43], v[136:139], v[152:155], v[40:43]
	v_mfma_f32_16x16x32_bf16 v[44:47], v[140:143], v[152:155], v[44:47]
	ds_read_b128 v[192:195], v232 offset:0
	ds_read_b128 v[196:199], v232 offset:1024
	v_mfma_f32_16x16x32_bf16 v[48:51], v[128:131], v[156:159], v[48:51]
	v_mfma_f32_16x16x32_bf16 v[52:55], v[132:135], v[156:159], v[52:55]
	v_mfma_f32_16x16x32_bf16 v[56:59], v[136:139], v[156:159], v[56:59]
	v_mfma_f32_16x16x32_bf16 v[60:63], v[140:143], v[156:159], v[60:63]
	ds_read_b128 v[200:203], v232 offset:2048
	ds_read_b128 v[204:207], v232 offset:3072
	v_mfma_f32_16x16x32_bf16 v[64:67], v[128:131], v[160:163], v[64:67]
	v_mfma_f32_16x16x32_bf16 v[68:71], v[132:135], v[160:163], v[68:71]
	v_mfma_f32_16x16x32_bf16 v[72:75], v[136:139], v[160:163], v[72:75]
	v_mfma_f32_16x16x32_bf16 v[76:79], v[140:143], v[160:163], v[76:79]
	ds_read_b128 v[208:211], v232 offset:4096
	v_mfma_f32_16x16x32_bf16 v[80:83], v[128:131], v[164:167], v[80:83]
	v_mfma_f32_16x16x32_bf16 v[84:87], v[132:135], v[164:167], v[84:87]
	v_mfma_f32_16x16x32_bf16 v[88:91], v[136:139], v[164:167], v[88:91]
	v_mfma_f32_16x16x32_bf16 v[92:95], v[140:143], v[164:167], v[92:95]
	ds_read_b128 v[212:215], v232 offset:5120
	v_mfma_f32_16x16x32_bf16 v[96:99], v[128:131], v[168:171], v[96:99]
	v_mfma_f32_16x16x32_bf16 v[100:103], v[132:135], v[168:171], v[100:103]
	v_mfma_f32_16x16x32_bf16 v[104:107], v[136:139], v[168:171], v[104:107]
	v_mfma_f32_16x16x32_bf16 v[108:111], v[140:143], v[168:171], v[108:111]
	ds_read_b128 v[216:219], v232 offset:6144
	s_add_u32 s98, s98, 24576
	s_cmp_eq_u32 s98, 73728
	s_cselect_b32 s98, 0, s98
	v_mfma_f32_16x16x32_bf16 v[112:115], v[128:131], v[172:175], v[112:115]
	v_mfma_f32_16x16x32_bf16 v[116:119], v[132:135], v[172:175], v[116:119]
	v_mfma_f32_16x16x32_bf16 v[120:123], v[136:139], v[172:175], v[120:123]
	v_mfma_f32_16x16x32_bf16 v[124:127], v[140:143], v[172:175], v[124:127]
	ds_read_b128 v[220:223], v232 offset:7168
	s_waitcnt lgkmcnt(0)
	s_barrier
	v_mfma_f32_16x16x32_bf16 v[0:3], v[176:179], v[192:195], v[0:3]
	v_mfma_f32_16x16x32_bf16 v[4:7], v[180:183], v[192:195], v[4:7]
	v_mfma_f32_16x16x32_bf16 v[8:11], v[184:187], v[192:195], v[8:11]
	v_mfma_f32_16x16x32_bf16 v[12:15], v[188:191], v[192:195], v[12:15]
	v_mfma_f32_16x16x32_bf16 v[16:19], v[176:179], v[196:199], v[16:19]
	v_mfma_f32_16x16x32_bf16 v[20:23], v[180:183], v[196:199], v[20:23]
	v_mfma_f32_16x16x32_bf16 v[24:27], v[184:187], v[196:199], v[24:27]
	v_mfma_f32_16x16x32_bf16 v[28:31], v[188:191], v[196:199], v[28:31]
	v_mfma_f32_16x16x32_bf16 v[32:35], v[176:179], v[200:203], v[32:35]
	v_mfma_f32_16x16x32_bf16 v[36:39], v[180:183], v[200:203], v[36:39]
	v_mfma_f32_16x16x32_bf16 v[40:43], v[184:187], v[200:203], v[40:43]
	v_mfma_f32_16x16x32_bf16 v[44:47], v[188:191], v[200:203], v[44:47]
	v_mfma_f32_16x16x32_bf16 v[48:51], v[176:179], v[204:207], v[48:51]
	v_mfma_f32_16x16x32_bf16 v[52:55], v[180:183], v[204:207], v[52:55]
	v_mfma_f32_16x16x32_bf16 v[56:59], v[184:187], v[204:207], v[56:59]
	v_mfma_f32_16x16x32_bf16 v[60:63], v[188:191], v[204:207], v[60:63]
	v_mfma_f32_16x16x32_bf16 v[64:67], v[176:179], v[208:211], v[64:67]
	v_mfma_f32_16x16x32_bf16 v[68:71], v[180:183], v[208:211], v[68:71]
	v_mfma_f32_16x16x32_bf16 v[72:75], v[184:187], v[208:211], v[72:75]
	v_mfma_f32_16x16x32_bf16 v[76:79], v[188:191], v[208:211], v[76:79]
	v_mfma_f32_16x16x32_bf16 v[80:83], v[176:179], v[212:215], v[80:83]
	v_mfma_f32_16x16x32_bf16 v[84:87], v[180:183], v[212:215], v[84:87]
	v_mfma_f32_16x16x32_bf16 v[88:91], v[184:187], v[212:215], v[88:91]
	v_mfma_f32_16x16x32_bf16 v[92:95], v[188:191], v[212:215], v[92:95]
	v_mfma_f32_16x16x32_bf16 v[96:99], v[176:179], v[216:219], v[96:99]
	v_mfma_f32_16x16x32_bf16 v[100:103], v[180:183], v[216:219], v[100:103]
	v_mfma_f32_16x16x32_bf16 v[104:107], v[184:187], v[216:219], v[104:107]
	v_mfma_f32_16x16x32_bf16 v[108:111], v[188:191], v[216:219], v[108:111]
	v_mfma_f32_16x16x32_bf16 v[112:115], v[176:179], v[220:223], v[112:115]
	v_mfma_f32_16x16x32_bf16 v[116:119], v[180:183], v[220:223], v[116:119]
	v_mfma_f32_16x16x32_bf16 v[120:123], v[184:187], v[220:223], v[120:123]
	v_mfma_f32_16x16x32_bf16 v[124:127], v[188:191], v[220:223], v[124:127]
	s_branch .Lg8_epi
; template <class Epi>
; DI void gemm_tile(char* smem, const bf16_t* __restrict__ A0, int lda0, int ksplit, const bf16_t* __restrict__ A1, int lda1,
;                   const bf16_t* __restrict__ Bt, int K, int row0, int col0, const Epi& epi, int tid) {
;     ...
; #pragma unroll
;   for (int m = 0; m < 8; ++m)
; #pragma unroll
;     for (int n = 0; n < 4; ++n) epi(row0 + wr * 128 + m * 16 + fr, col0 + wc * 64 + n * 16 + fq * 4, acc[m][n]);
.Lg8_epi:
	s_nop 7
	s_nop 7
	s_mul_i32 s12, s18, 8192
	s_lshl_b32 s11, s13, 1
	s_add_u32 s12, s12, s11
	s_add_u32 s12, s12, 0x7800000
	s_add_u32 s4, s92, s12
	s_addc_u32 s5, s93, 0
	v_max_f32_e32 v0, 0, v0
	v_max_f32_e32 v1, 0, v1
	v_max_f32_e32 v2, 0, v2
	v_max_f32_e32 v3, 0, v3
	v_pk_mul_f32 v[0:1], v[0:1], v[0:1]
	v_pk_mul_f32 v[2:3], v[2:3], v[2:3]
	v_cvt_pk_bf16_f32 v128, v0, v1
	v_cvt_pk_bf16_f32 v129, v2, v3
	global_store_dwordx2 v234, v[128:129], s[4:5] offset:0
	v_max_f32_e32 v4, 0, v4
	v_max_f32_e32 v5, 0, v5
	v_max_f32_e32 v6, 0, v6
	v_max_f32_e32 v7, 0, v7
	v_pk_mul_f32 v[4:5], v[4:5], v[4:5]
	v_pk_mul_f32 v[6:7], v[6:7], v[6:7]
	v_cvt_pk_bf16_f32 v130, v4, v5
	v_cvt_pk_bf16_f32 v131, v6, v7
	global_store_dwordx2 v234, v[130:131], s[4:5] offset:32
	v_max_f32_e32 v8, 0, v8
	v_max_f32_e32 v9, 0, v9
	v_max_f32_e32 v10, 0, v10
	v_max_f32_e32 v11, 0, v11
	v_pk_mul_f32 v[8:9], v[8:9], v[8:9]
	v_pk_mul_f32 v[10:11], v[10:11], v[10:11]
	v_cvt_pk_bf16_f32 v132, v8, v9
	v_cvt_pk_bf16_f32 v133, v10, v11
	global_store_dwordx2 v234, v[132:133], s[4:5] offset:64
	v_max_f32_e32 v12, 0, v12
	v_max_f32_e32 v13, 0, v13
	v_max_f32_e32 v14, 0, v14
	v_max_f32_e32 v15, 0, v15
	v_pk_mul_f32 v[12:13], v[12:13], v[12:13]
	v_pk_mul_f32 v[14:15], v[14:15], v[14:15]
	v_cvt_pk_bf16_f32 v134, v12, v13
	v_cvt_pk_bf16_f32 v135, v14, v15
	global_store_dwordx2 v234, v[134:135], s[4:5] offset:96
	s_add_u32 s4, s4, 0x20000
	s_addc_u32 s5, s5, 0
	v_max_f32_e32 v16, 0, v16
	v_max_f32_e32 v17, 0, v17
	v_max_f32_e32 v18, 0, v18
	v_max_f32_e32 v19, 0, v19
	v_pk_mul_f32 v[16:17], v[16:17], v[16:17]
	v_pk_mul_f32 v[18:19], v[18:19], v[18:19]
	v_cvt_pk_bf16_f32 v136, v16, v17
	v_cvt_pk_bf16_f32 v137, v18, v19
	global_store_dwordx2 v234, v[136:137], s[4:5] offset:0
	v_max_f32_e32 v20, 0, v20
	v_max_f32_e32 v21, 0, v21
	v_max_f32_e32 v22, 0, v22
	v_max_f32_e32 v23, 0, v23
	v_pk_mul_f32 v[20:21], v[20:21], v[20:21]
	v_pk_mul_f32 v[22:23], v[22:23], v[22:23]
	v_cvt_pk_bf16_f32 v138, v20, v21
	v_cvt_pk_bf16_f32 v139, v22, v23
	global_store_dwordx2 v234, v[138:139], s[4:5] offset:32
	v_max_f32_e32 v24, 0, v24
	v_max_f32_e32 v25, 0, v25
	v_max_f32_e32 v26, 0, v26
	v_max_f32_e32 v27, 0, v27
	v_pk_mul_f32 v[24:25], v[24:25], v[24:25]
	v_pk_mul_f32 v[26:27], v[26:27], v[26:27]
	v_cvt_pk_bf16_f32 v140, v24, v25
	v_cvt_pk_bf16_f32 v141, v26, v27
	global_store_dwordx2 v234, v[140:141], s[4:5] offset:64
	v_max_f32_e32 v28, 0, v28
	v_max_f32_e32 v29, 0, v29
	v_max_f32_e32 v30, 0, v30
	v_max_f32_e32 v31, 0, v31
	v_pk_mul_f32 v[28:29], v[28:29], v[28:29]
	v_pk_mul_f32 v[30:31], v[30:31], v[30:31]
	v_cvt_pk_bf16_f32 v142, v28, v29
	v_cvt_pk_bf16_f32 v143, v30, v31
	global_store_dwordx2 v234, v[142:143], s[4:5] offset:96
	s_add_u32 s4, s4, 0x20000
	s_addc_u32 s5, s5, 0
	v_max_f32_e32 v32, 0, v32
	v_max_f32_e32 v33, 0, v33
	v_max_f32_e32 v34, 0, v34
	v_max_f32_e32 v35, 0, v35
	v_pk_mul_f32 v[32:33], v[32:33], v[32:33]
	v_pk_mul_f32 v[34:35], v[34:35], v[34:35]
	v_cvt_pk_bf16_f32 v144, v32, v33
	v_cvt_pk_bf16_f32 v145, v34, v35
	global_store_dwordx2 v234, v[144:145], s[4:5] offset:0
	v_max_f32_e32 v36, 0, v36
	v_max_f32_e32 v37, 0, v37
	v_max_f32_e32 v38, 0, v38
	v_max_f32_e32 v39, 0, v39
	v_pk_mul_f32 v[36:37], v[36:37], v[36:37]
	v_pk_mul_f32 v[38:39], v[38:39], v[38:39]
	v_cvt_pk_bf16_f32 v146, v36, v37
	v_cvt_pk_bf16_f32 v147, v38, v39
	global_store_dwordx2 v234, v[146:147], s[4:5] offset:32
	v_max_f32_e32 v40, 0, v40
	v_max_f32_e32 v41, 0, v41
	v_max_f32_e32 v42, 0, v42
	v_max_f32_e32 v43, 0, v43
	v_pk_mul_f32 v[40:41], v[40:41], v[40:41]
	v_pk_mul_f32 v[42:43], v[42:43], v[42:43]
	v_cvt_pk_bf16_f32 v148, v40, v41
	v_cvt_pk_bf16_f32 v149, v42, v43
	global_store_dwordx2 v234, v[148:149], s[4:5] offset:64
	v_max_f32_e32 v44, 0, v44
	v_max_f32_e32 v45, 0, v45
	v_max_f32_e32 v46, 0, v46
	v_max_f32_e32 v47, 0, v47
	v_pk_mul_f32 v[44:45], v[44:45], v[44:45]
	v_pk_mul_f32 v[46:47], v[46:47], v[46:47]
	v_cvt_pk_bf16_f32 v150, v44, v45
	v_cvt_pk_bf16_f32 v151, v46, v47
	global_store_dwordx2 v234, v[150:151], s[4:5] offset:96
	s_add_u32 s4, s4, 0x20000
	s_addc_u32 s5, s5, 0
	v_max_f32_e32 v48, 0, v48
	v_max_f32_e32 v49, 0, v49
	v_max_f32_e32 v50, 0, v50
	v_max_f32_e32 v51, 0, v51
	v_pk_mul_f32 v[48:49], v[48:49], v[48:49]
	v_pk_mul_f32 v[50:51], v[50:51], v[50:51]
	v_cvt_pk_bf16_f32 v152, v48, v49
	v_cvt_pk_bf16_f32 v153, v50, v51
	global_store_dwordx2 v234, v[152:153], s[4:5] offset:0
	v_max_f32_e32 v52, 0, v52
	v_max_f32_e32 v53, 0, v53
	v_max_f32_e32 v54, 0, v54
	v_max_f32_e32 v55, 0, v55
	v_pk_mul_f32 v[52:53], v[52:53], v[52:53]
	v_pk_mul_f32 v[54:55], v[54:55], v[54:55]
	v_cvt_pk_bf16_f32 v154, v52, v53
	v_cvt_pk_bf16_f32 v155, v54, v55
	global_store_dwordx2 v234, v[154:155], s[4:5] offset:32
	v_max_f32_e32 v56, 0, v56
	v_max_f32_e32 v57, 0, v57
	v_max_f32_e32 v58, 0, v58
	v_max_f32_e32 v59, 0, v59
	v_pk_mul_f32 v[56:57], v[56:57], v[56:57]
	v_pk_mul_f32 v[58:59], v[58:59], v[58:59]
	v_cvt_pk_bf16_f32 v156, v56, v57
	v_cvt_pk_bf16_f32 v157, v58, v59
	global_store_dwordx2 v234, v[156:157], s[4:5] offset:64
	v_max_f32_e32 v60, 0, v60
	v_max_f32_e32 v61, 0, v61
	v_max_f32_e32 v62, 0, v62
	v_max_f32_e32 v63, 0, v63
	v_pk_mul_f32 v[60:61], v[60:61], v[60:61]
	v_pk_mul_f32 v[62:63], v[62:63], v[62:63]
	v_cvt_pk_bf16_f32 v158, v60, v61
	v_cvt_pk_bf16_f32 v159, v62, v63
	global_store_dwordx2 v234, v[158:159], s[4:5] offset:96
	s_add_u32 s4, s4, 0x20000
	s_addc_u32 s5, s5, 0
	v_max_f32_e32 v64, 0, v64
; template <class Epi>
; DI void gemm_tile(char* smem, const bf16_t* __restrict__ A0, int lda0, int ksplit, const bf16_t* __restrict__ A1, int lda1,
;                   const bf16_t* __restrict__ Bt, int K, int row0, int col0, const Epi& epi, int tid) {
;     ...
; #pragma unroll
;   for (int m = 0; m < 8; ++m)
; #pragma unroll
;     for (int n = 0; n < 4; ++n) epi(row0 + wr * 128 + m * 16 + fr, col0 + wc * 64 + n * 16 + fq * 4, acc[m][n]);
	v_max_f32_e32 v65, 0, v65
	v_max_f32_e32 v66, 0, v66
	v_max_f32_e32 v67, 0, v67
	v_pk_mul_f32 v[64:65], v[64:65], v[64:65]
	v_pk_mul_f32 v[66:67], v[66:67], v[66:67]
	v_cvt_pk_bf16_f32 v128, v64, v65
	v_cvt_pk_bf16_f32 v129, v66, v67
	global_store_dwordx2 v234, v[128:129], s[4:5] offset:0
	v_max_f32_e32 v68, 0, v68
	v_max_f32_e32 v69, 0, v69
	v_max_f32_e32 v70, 0, v70
	v_max_f32_e32 v71, 0, v71
	v_pk_mul_f32 v[68:69], v[68:69], v[68:69]
	v_pk_mul_f32 v[70:71], v[70:71], v[70:71]
	v_cvt_pk_bf16_f32 v130, v68, v69
	v_cvt_pk_bf16_f32 v131, v70, v71
	global_store_dwordx2 v234, v[130:131], s[4:5] offset:32
	v_max_f32_e32 v72, 0, v72
	v_max_f32_e32 v73, 0, v73
	v_max_f32_e32 v74, 0, v74
	v_max_f32_e32 v75, 0, v75
	v_pk_mul_f32 v[72:73], v[72:73], v[72:73]
	v_pk_mul_f32 v[74:75], v[74:75], v[74:75]
	v_cvt_pk_bf16_f32 v132, v72, v73
	v_cvt_pk_bf16_f32 v133, v74, v75
	global_store_dwordx2 v234, v[132:133], s[4:5] offset:64
	v_max_f32_e32 v76, 0, v76
	v_max_f32_e32 v77, 0, v77
	v_max_f32_e32 v78, 0, v78
	v_max_f32_e32 v79, 0, v79
	v_pk_mul_f32 v[76:77], v[76:77], v[76:77]
	v_pk_mul_f32 v[78:79], v[78:79], v[78:79]
	v_cvt_pk_bf16_f32 v134, v76, v77
	v_cvt_pk_bf16_f32 v135, v78, v79
	global_store_dwordx2 v234, v[134:135], s[4:5] offset:96
	s_add_u32 s4, s4, 0x20000
	s_addc_u32 s5, s5, 0
	v_max_f32_e32 v80, 0, v80
	v_max_f32_e32 v81, 0, v81
	v_max_f32_e32 v82, 0, v82
	v_max_f32_e32 v83, 0, v83
	v_pk_mul_f32 v[80:81], v[80:81], v[80:81]
	v_pk_mul_f32 v[82:83], v[82:83], v[82:83]
	v_cvt_pk_bf16_f32 v136, v80, v81
	v_cvt_pk_bf16_f32 v137, v82, v83
	global_store_dwordx2 v234, v[136:137], s[4:5] offset:0
	v_max_f32_e32 v84, 0, v84
	v_max_f32_e32 v85, 0, v85
	v_max_f32_e32 v86, 0, v86
	v_max_f32_e32 v87, 0, v87
	v_pk_mul_f32 v[84:85], v[84:85], v[84:85]
	v_pk_mul_f32 v[86:87], v[86:87], v[86:87]
	v_cvt_pk_bf16_f32 v138, v84, v85
	v_cvt_pk_bf16_f32 v139, v86, v87
	global_store_dwordx2 v234, v[138:139], s[4:5] offset:32
	v_max_f32_e32 v88, 0, v88
	v_max_f32_e32 v89, 0, v89
	v_max_f32_e32 v90, 0, v90
	v_max_f32_e32 v91, 0, v91
	v_pk_mul_f32 v[88:89], v[88:89], v[88:89]
	v_pk_mul_f32 v[90:91], v[90:91], v[90:91]
	v_cvt_pk_bf16_f32 v140, v88, v89
	v_cvt_pk_bf16_f32 v141, v90, v91
	global_store_dwordx2 v234, v[140:141], s[4:5] offset:64
	v_max_f32_e32 v92, 0, v92
	v_max_f32_e32 v93, 0, v93
	v_max_f32_e32 v94, 0, v94
	v_max_f32_e32 v95, 0, v95
	v_pk_mul_f32 v[92:93], v[92:93], v[92:93]
	v_pk_mul_f32 v[94:95], v[94:95], v[94:95]
	v_cvt_pk_bf16_f32 v142, v92, v93
	v_cvt_pk_bf16_f32 v143, v94, v95
	global_store_dwordx2 v234, v[142:143], s[4:5] offset:96
	s_add_u32 s4, s4, 0x20000
	s_addc_u32 s5, s5, 0
	v_max_f32_e32 v96, 0, v96
	v_max_f32_e32 v97, 0, v97
	v_max_f32_e32 v98, 0, v98
	v_max_f32_e32 v99, 0, v99
	v_pk_mul_f32 v[96:97], v[96:97], v[96:97]
	v_pk_mul_f32 v[98:99], v[98:99], v[98:99]
	v_cvt_pk_bf16_f32 v144, v96, v97
	v_cvt_pk_bf16_f32 v145, v98, v99
	global_store_dwordx2 v234, v[144:145], s[4:5] offset:0
	v_max_f32_e32 v100, 0, v100
	v_max_f32_e32 v101, 0, v101
	v_max_f32_e32 v102, 0, v102
	v_max_f32_e32 v103, 0, v103
	v_pk_mul_f32 v[100:101], v[100:101], v[100:101]
	v_pk_mul_f32 v[102:103], v[102:103], v[102:103]
	v_cvt_pk_bf16_f32 v146, v100, v101
	v_cvt_pk_bf16_f32 v147, v102, v103
	global_store_dwordx2 v234, v[146:147], s[4:5] offset:32
	v_max_f32_e32 v104, 0, v104
	v_max_f32_e32 v105, 0, v105
	v_max_f32_e32 v106, 0, v106
	v_max_f32_e32 v107, 0, v107
	v_pk_mul_f32 v[104:105], v[104:105], v[104:105]
	v_pk_mul_f32 v[106:107], v[106:107], v[106:107]
	v_cvt_pk_bf16_f32 v148, v104, v105
	v_cvt_pk_bf16_f32 v149, v106, v107
	global_store_dwordx2 v234, v[148:149], s[4:5] offset:64
	v_max_f32_e32 v108, 0, v108
	v_max_f32_e32 v109, 0, v109
	v_max_f32_e32 v110, 0, v110
	v_max_f32_e32 v111, 0, v111
	v_pk_mul_f32 v[108:109], v[108:109], v[108:109]
	v_pk_mul_f32 v[110:111], v[110:111], v[110:111]
	v_cvt_pk_bf16_f32 v150, v108, v109
	v_cvt_pk_bf16_f32 v151, v110, v111
	global_store_dwordx2 v234, v[150:151], s[4:5] offset:96
	s_add_u32 s4, s4, 0x20000
	s_addc_u32 s5, s5, 0
	v_max_f32_e32 v112, 0, v112
	v_max_f32_e32 v113, 0, v113
	v_max_f32_e32 v114, 0, v114
	v_max_f32_e32 v115, 0, v115
	v_pk_mul_f32 v[112:113], v[112:113], v[112:113]
	v_pk_mul_f32 v[114:115], v[114:115], v[114:115]
	v_cvt_pk_bf16_f32 v152, v112, v113
	v_cvt_pk_bf16_f32 v153, v114, v115
	global_store_dwordx2 v234, v[152:153], s[4:5] offset:0
	v_max_f32_e32 v116, 0, v116
	v_max_f32_e32 v117, 0, v117
	v_max_f32_e32 v118, 0, v118
	v_max_f32_e32 v119, 0, v119
	v_pk_mul_f32 v[116:117], v[116:117], v[116:117]
	v_pk_mul_f32 v[118:119], v[118:119], v[118:119]
	v_cvt_pk_bf16_f32 v154, v116, v117
	v_cvt_pk_bf16_f32 v155, v118, v119
	global_store_dwordx2 v234, v[154:155], s[4:5] offset:32
	v_max_f32_e32 v120, 0, v120
	v_max_f32_e32 v121, 0, v121
	v_max_f32_e32 v122, 0, v122
	v_max_f32_e32 v123, 0, v123
	v_pk_mul_f32 v[120:121], v[120:121], v[120:121]
	v_pk_mul_f32 v[122:123], v[122:123], v[122:123]
	v_cvt_pk_bf16_f32 v156, v120, v121
	v_cvt_pk_bf16_f32 v157, v122, v123
	global_store_dwordx2 v234, v[156:157], s[4:5] offset:64
	v_max_f32_e32 v124, 0, v124
	v_max_f32_e32 v125, 0, v125
	v_max_f32_e32 v126, 0, v126
	v_max_f32_e32 v127, 0, v127
	v_pk_mul_f32 v[124:125], v[124:125], v[124:125]
	v_pk_mul_f32 v[126:127], v[126:127], v[126:127]
	v_cvt_pk_bf16_f32 v158, v124, v125
	v_cvt_pk_bf16_f32 v159, v126, v127
	global_store_dwordx2 v234, v[158:159], s[4:5] offset:96
	s_add_u32 s17, s17, 64
	s_branch .Lg8_tile

; #define LWRITE(S, buf) do { bf16_t* sA_ = sbase + (buf) * BUF; bf16_t* sB_ = sA_ + 256 * PITCH; \
;     _Pragma("unroll") for (int i_ = 0; i_ < 4; ++i_) *(u32x4*)(sA_ + (sr + i_ * 64) * PITCH + scv * 8) = ra[S][i_]; \
;     _Pragma("unroll") for (int i_ = 0; i_ < 2; ++i_) *(u32x4*)(sB_ + (sr + i_ * 64) * PITCH + scv * 8) = rb[S][i_]; } while (0)
; template <class Epi>
; DI void gemm_tile(char* smem, const bf16_t* __restrict__ A0, int lda0, int ksplit, const bf16_t* __restrict__ A1, int lda1,
;                   const bf16_t* __restrict__ Bt, int K, int row0, int col0, const Epi& epi, int tid) {
;   constexpr int BK = 32, PITCH = 40, BUF = (256 + 128) * PITCH;
;   bf16_t* sbase = (bf16_t*)smem;
;   const int lane = tid & 63, wid = tid >> 6, wr = wid >> 1, wc = wid & 1, fr = lane & 15, fq = lane >> 4;
;   f32x4 acc[8][4];
; #pragma unroll
;   for (int m = 0; m < 8; ++m)
; #pragma unroll
;     for (int n = 0; n < 4; ++n) acc[m][n] = (f32x4){0.f, 0.f, 0.f, 0.f};
;   u32x4 ra[2][4], rb[2][2];
;   const int nk = K / BK;
;   const int sr = tid >> 2, scv = tid & 3;
;     ...
;   __syncthreads();
;   {
;     const int last = nk - 1;
;     GLOAD(0, 0);
;     __builtin_amdgcn_sched_barrier(0);
;     GLOAD(1, 1);
;     __builtin_amdgcn_sched_barrier(0);
;     LWRITE(0, 0);
;     __builtin_amdgcn_sched_barrier(0);
;     GLOAD(0, (2 < last ? 2 : last));
;     __builtin_amdgcn_sched_barrier(0);
;     __syncthreads();
; template <class Epi>
; DI void gemm_phase(char* smem, const bf16_t* A0, int lda0, int ksplit, const bf16_t* A1, int lda1, const bf16_t* Bt, int K, int nN, const Epi& epi, int tid) {
;     ...
;   if ((G & 7) == 0) {
;     const int x = blockIdx.x & 7, l = blockIdx.x >> 3, L = G >> 3, per = 8 * nN, tot = 2 * per;
;     for (int q = l; q < tot; q += L) { const int rgl = q / per, rem = q % per, ct = rem >> 3, rt = (x * 2 + rgl) * 8 + (rem & 7);
;       gemm_tile(smem, A0, lda0, ksplit, A1, lda1, Bt, K, rt * 256, ct * 128, epi, tid); }
.LBB0_929:
	s_cmp_gt_i32 s94, 9
	s_cselect_b64 s[0:1], -1, 0
	s_cmp_lt_i32 s95, 10
	s_cselect_b64 s[2:3], -1, 0
	s_or_b64 s[0:1], s[0:1], s[2:3]
	s_and_b64 vcc, exec, s[0:1]
	s_cbranch_vccnz .LBB0_957
	s_load_dword s12, s[74:75], 0x180
	s_add_u32 s0, s92, 0x7800000
	s_addc_u32 s1, s93, 0
	s_add_u32 s2, s92, 0x1bc0000
	s_addc_u32 s3, s93, 0
	s_waitcnt lgkmcnt(0)
	s_and_b32 s14, s72, 0xffffffc0
	v_mbcnt_hi_u32_b32 v195, -1, v194
	s_and_b32 s13, s12, 7
	s_cmp_lg_u32 s13, 0
	s_waitcnt vmcnt(16)
	v_add_u32_e32 v196, s14, v195
	v_mbcnt_lo_u32_b32 v240, -1, 0
	v_mbcnt_hi_u32_b32 v240, -1, v240
	s_lshr_b32 s10, s72, 6
	s_lshl_b32 s101, s10, 10
	v_and_b32_e32 v241, 15, v240
	v_lshrrev_b32_e32 v242, 4, v240
	v_bfe_u32 v243, v240, 3, 1
	v_mul_u32_u24_e32 v243, 3, v243
	v_xor_b32_e32 v243, v242, v243
	v_lshlrev_b32_e32 v243, 4, v243
	v_lshl_add_u32 v243, v241, 6, v243
	s_lshr_b32 s9, s10, 1
	s_lshl_b32 s9, s9, 13
	v_add_u32_e32 v230, s9, v243
	s_and_b32 s9, s10, 1
	s_lshl_b32 s9, s9, 12
	s_add_u32 s9, s9, 16384
	v_add_u32_e32 v231, s9, v243
	s_lshr_b32 s9, s10, 1
	s_lshl_b32 s9, s9, 7
	v_add_u32_e32 v244, s9, v241
	s_and_b32 s9, s10, 1
	s_lshl_b32 s9, s9, 6
	v_lshl_add_u32 v245, v242, 2, s9
	s_movk_i32 s9, 0x1000
	v_mul_lo_u32 v246, v244, s9
	v_lshl_add_u32 v234, v245, 2, v246
	v_lshrrev_b32_e32 v241, 2, v240
	s_lshl_b32 s9, s10, 4
	v_add_u32_e32 v241, s9, v241
	v_bfe_u32 v242, v240, 5, 1
	v_mul_u32_u24_e32 v242, 3, v242
	v_and_b32_e32 v243, 3, v240
	v_xor_b32_e32 v243, v243, v242
	v_lshlrev_b32_e32 v243, 4, v243
	s_mov_b32 s9, 8192
	v_mad_u32_u24 v224, v241, s9, v243
	v_add_u32_e32 v225, 0x80000, v224
	v_add_u32_e32 v226, 0x100000, v224
	v_add_u32_e32 v227, 0x180000, v224
	s_mov_b32 s9, 8192
	v_mad_u32_u24 v228, v241, s9, v243
	v_add_u32_e32 v229, 0x80000, v228
	s_load_dwordx2 s[6:7], s[74:75], 0x168
	s_lshr_b32 s15, s96, 3
	s_and_b32 s18, s96, 7
	s_lshl_b32 s18, s18, 1
	s_waitcnt lgkmcnt(0)
.Lg9_tile:
	s_cmpk_ge_u32 s15, 128
	s_cbranch_scc1 .Lg9_done
	s_cmpk_ge_u32 s15, 64
	s_cselect_b32 s10, 1, 0
	s_cselect_b32 s9, 64, 0
	s_sub_u32 s9, s15, s9
	s_and_b32 s16, s9, 7
	s_lshl_b32 s16, s16, 3
	s_bfe_u32 s11, s9, 0x30003
	s_or_b32 s16, s16, s11
	s_andn2_b32 s9, s9, 63
	s_or_b32 s9, s9, s16
	s_add_u32 s10, s10, s18
	s_lshl_b32 s10, s10, 3
	s_and_b32 s16, s9, 7
	s_add_u32 s16, s16, s10
	s_lshl_b32 s16, s16, 8
	s_lshr_b32 s11, s9, 3
	s_lshl_b32 s11, s11, 7
	s_mul_i32 s10, s16, 8192
	s_add_u32 s10, s10, 0x7800000
	s_add_u32 s0, s92, s10
	s_addc_u32 s1, s93, 0
	s_mul_i32 s10, s11, 8192
	s_add_u32 s10, s10, 0x1bc0000
	s_add_u32 s2, s92, s10
	s_addc_u32 s3, s93, 0
	s_mov_b32 s100, 0
	s_mov_b32 s17, 0
	s_add_u32 s9, s17, s101
	s_add_u32 m0, s9, 0
	s_nop 0
	global_load_lds_dwordx4 v224, s[0:1]
	s_add_u32 m0, s9, 4096
	s_nop 0
	global_load_lds_dwordx4 v225, s[0:1]
	s_add_u32 m0, s9, 8192
	s_nop 0
	global_load_lds_dwordx4 v226, s[0:1]
	s_add_u32 m0, s9, 12288
	s_nop 0
	global_load_lds_dwordx4 v227, s[0:1]
	s_add_u32 m0, s9, 16384
	s_nop 0
	global_load_lds_dwordx4 v228, s[2:3]
	s_add_u32 m0, s9, 20480
	s_nop 0
	global_load_lds_dwordx4 v229, s[2:3]
	s_add_u32 s0, s0, 64
	s_addc_u32 s1, s1, 0
	s_add_u32 s2, s2, 64
	s_addc_u32 s3, s3, 0
	s_add_u32 s100, s100, 1
	s_add_u32 s17, s17, 24576
	s_cmp_eq_u32 s17, 73728
	s_cselect_b32 s17, 0, s17
	s_add_u32 s9, s17, s101
	s_add_u32 m0, s9, 0
	s_nop 0
	global_load_lds_dwordx4 v224, s[0:1]
	s_add_u32 m0, s9, 4096
	s_nop 0
	global_load_lds_dwordx4 v225, s[0:1]
	s_add_u32 m0, s9, 8192
	s_nop 0
	global_load_lds_dwordx4 v226, s[0:1]
	s_add_u32 m0, s9, 12288
	s_nop 0
	global_load_lds_dwordx4 v227, s[0:1]
	s_add_u32 m0, s9, 16384
	s_nop 0
	global_load_lds_dwordx4 v228, s[2:3]
	s_add_u32 m0, s9, 20480
	s_nop 0
	global_load_lds_dwordx4 v229, s[2:3]
	s_add_u32 s0, s0, 64
	s_addc_u32 s1, s1, 0
	s_add_u32 s2, s2, 64
	s_addc_u32 s3, s3, 0
	s_add_u32 s100, s100, 1
	s_add_u32 s17, s17, 24576
	s_cmp_eq_u32 s17, 73728
	s_cselect_b32 s17, 0, s17
	s_add_u32 s9, s17, s101
	s_add_u32 m0, s9, 0
	s_nop 0
	global_load_lds_dwordx4 v224, s[0:1]
	s_add_u32 m0, s9, 4096
	s_nop 0
	global_load_lds_dwordx4 v225, s[0:1]
	s_add_u32 m0, s9, 8192
	s_nop 0
	global_load_lds_dwordx4 v226, s[0:1]
	s_add_u32 m0, s9, 12288
	s_nop 0
	global_load_lds_dwordx4 v227, s[0:1]
	s_add_u32 m0, s9, 16384
	s_nop 0
	global_load_lds_dwordx4 v228, s[2:3]
	s_add_u32 m0, s9, 20480
	s_nop 0
	global_load_lds_dwordx4 v229, s[2:3]
	s_add_u32 s0, s0, 64
	s_addc_u32 s1, s1, 0
	s_add_u32 s2, s2, 64
	s_addc_u32 s3, s3, 0
	s_add_u32 s100, s100, 1
	s_add_u32 s17, s17, 24576
	s_cmp_eq_u32 s17, 73728
	s_cselect_b32 s17, 0, s17
	v_mov_b32_e32 v0, 0
	v_mov_b32_e32 v1, 0
	v_mov_b32_e32 v2, 0
	v_mov_b32_e32 v3, 0
	v_mov_b32_e32 v4, 0
	v_mov_b32_e32 v5, 0
	v_mov_b32_e32 v6, 0
	v_mov_b32_e32 v7, 0
	v_mov_b32_e32 v8, 0
	v_mov_b32_e32 v9, 0
	v_mov_b32_e32 v10, 0
	v_mov_b32_e32 v11, 0
	v_mov_b32_e32 v12, 0
	v_mov_b32_e32 v13, 0
	v_mov_b32_e32 v14, 0
	v_mov_b32_e32 v15, 0
	v_mov_b32_e32 v16, 0
	v_mov_b32_e32 v17, 0
	v_mov_b32_e32 v18, 0
	v_mov_b32_e32 v19, 0
	v_mov_b32_e32 v20, 0
	v_mov_b32_e32 v21, 0
	v_mov_b32_e32 v22, 0
	v_mov_b32_e32 v23, 0
	v_mov_b32_e32 v24, 0
	v_mov_b32_e32 v25, 0
	v_mov_b32_e32 v26, 0
	v_mov_b32_e32 v27, 0
	v_mov_b32_e32 v28, 0
	v_mov_b32_e32 v29, 0
	v_mov_b32_e32 v30, 0
	v_mov_b32_e32 v31, 0
	v_mov_b32_e32 v32, 0
	v_mov_b32_e32 v33, 0
	v_mov_b32_e32 v34, 0
	v_mov_b32_e32 v35, 0
	v_mov_b32_e32 v36, 0
	v_mov_b32_e32 v37, 0
	v_mov_b32_e32 v38, 0
	v_mov_b32_e32 v39, 0
	v_mov_b32_e32 v40, 0
	v_mov_b32_e32 v41, 0
	v_mov_b32_e32 v42, 0
	v_mov_b32_e32 v43, 0
	v_mov_b32_e32 v44, 0
	v_mov_b32_e32 v45, 0
	v_mov_b32_e32 v46, 0
	v_mov_b32_e32 v47, 0
	v_mov_b32_e32 v48, 0
	v_mov_b32_e32 v49, 0
; #define LWRITE(S, buf) do { bf16_t* sA_ = sbase + (buf) * BUF; bf16_t* sB_ = sA_ + 256 * PITCH; \
;     _Pragma("unroll") for (int i_ = 0; i_ < 4; ++i_) *(u32x4*)(sA_ + (sr + i_ * 64) * PITCH + scv * 8) = ra[S][i_]; \
;     _Pragma("unroll") for (int i_ = 0; i_ < 2; ++i_) *(u32x4*)(sB_ + (sr + i_ * 64) * PITCH + scv * 8) = rb[S][i_]; } while (0)
; template <class Epi>
; DI void gemm_tile(char* smem, const bf16_t* __restrict__ A0, int lda0, int ksplit, const bf16_t* __restrict__ A1, int lda1,
;                   const bf16_t* __restrict__ Bt, int K, int row0, int col0, const Epi& epi, int tid) {
;     ...
;   f32x4 acc[8][4];
; #pragma unroll
;   for (int m = 0; m < 8; ++m)
; #pragma unroll
;     for (int n = 0; n < 4; ++n) acc[m][n] = (f32x4){0.f, 0.f, 0.f, 0.f};
;   u32x4 ra[2][4], rb[2][2];
;   const int nk = K / BK;
;   const int sr = tid >> 2, scv = tid & 3;
;     ...
;   __syncthreads();
;   {
;     const int last = nk - 1;
;     GLOAD(0, 0);
;     __builtin_amdgcn_sched_barrier(0);
;     GLOAD(1, 1);
;     __builtin_amdgcn_sched_barrier(0);
;     LWRITE(0, 0);
;     __builtin_amdgcn_sched_barrier(0);
;     GLOAD(0, (2 < last ? 2 : last));
;     __builtin_amdgcn_sched_barrier(0);
;     __syncthreads();
;     for (int kt = 0; kt < nk; kt += 2) {
;       LWRITE(1, 1);
;       __builtin_amdgcn_sched_barrier(0);
;       GLOAD(1, (kt + 3 < last ? kt + 3 : last));
;       __builtin_amdgcn_sched_barrier(0);
;       COMPUTE(0);
;       __syncthreads();
;       LWRITE(0, 0);
;       __builtin_amdgcn_sched_barrier(0);
;       GLOAD(0, (kt + 4 < last ? kt + 4 : last));
;       __builtin_amdgcn_sched_barrier(0);
;       COMPUTE(1);
;       __syncthreads();
;     }
	v_mov_b32_e32 v50, 0
	v_mov_b32_e32 v51, 0
	v_mov_b32_e32 v52, 0
	v_mov_b32_e32 v53, 0
	v_mov_b32_e32 v54, 0
	v_mov_b32_e32 v55, 0
	v_mov_b32_e32 v56, 0
	v_mov_b32_e32 v57, 0
	v_mov_b32_e32 v58, 0
	v_mov_b32_e32 v59, 0
	v_mov_b32_e32 v60, 0
	v_mov_b32_e32 v61, 0
	v_mov_b32_e32 v62, 0
	v_mov_b32_e32 v63, 0
	v_mov_b32_e32 v64, 0
	v_mov_b32_e32 v65, 0
	v_mov_b32_e32 v66, 0
	v_mov_b32_e32 v67, 0
	v_mov_b32_e32 v68, 0
	v_mov_b32_e32 v69, 0
	v_mov_b32_e32 v70, 0
	v_mov_b32_e32 v71, 0
	v_mov_b32_e32 v72, 0
	v_mov_b32_e32 v73, 0
	v_mov_b32_e32 v74, 0
	v_mov_b32_e32 v75, 0
	v_mov_b32_e32 v76, 0
	v_mov_b32_e32 v77, 0
	v_mov_b32_e32 v78, 0
	v_mov_b32_e32 v79, 0
	v_mov_b32_e32 v80, 0
	v_mov_b32_e32 v81, 0
	v_mov_b32_e32 v82, 0
	v_mov_b32_e32 v83, 0
	v_mov_b32_e32 v84, 0
	v_mov_b32_e32 v85, 0
	v_mov_b32_e32 v86, 0
	v_mov_b32_e32 v87, 0
	v_mov_b32_e32 v88, 0
	v_mov_b32_e32 v89, 0
	v_mov_b32_e32 v90, 0
	v_mov_b32_e32 v91, 0
	v_mov_b32_e32 v92, 0
	v_mov_b32_e32 v93, 0
	v_mov_b32_e32 v94, 0
	v_mov_b32_e32 v95, 0
	v_mov_b32_e32 v96, 0
	v_mov_b32_e32 v97, 0
	v_mov_b32_e32 v98, 0
	v_mov_b32_e32 v99, 0
	v_mov_b32_e32 v100, 0
	v_mov_b32_e32 v101, 0
	v_mov_b32_e32 v102, 0
	v_mov_b32_e32 v103, 0
	v_mov_b32_e32 v104, 0
	v_mov_b32_e32 v105, 0
	v_mov_b32_e32 v106, 0
	v_mov_b32_e32 v107, 0
	v_mov_b32_e32 v108, 0
	v_mov_b32_e32 v109, 0
	v_mov_b32_e32 v110, 0
	v_mov_b32_e32 v111, 0
	v_mov_b32_e32 v112, 0
	v_mov_b32_e32 v113, 0
	v_mov_b32_e32 v114, 0
	v_mov_b32_e32 v115, 0
	v_mov_b32_e32 v116, 0
	v_mov_b32_e32 v117, 0
	v_mov_b32_e32 v118, 0
	v_mov_b32_e32 v119, 0
	v_mov_b32_e32 v120, 0
	v_mov_b32_e32 v121, 0
	v_mov_b32_e32 v122, 0
	v_mov_b32_e32 v123, 0
	v_mov_b32_e32 v124, 0
	v_mov_b32_e32 v125, 0
	v_mov_b32_e32 v126, 0
	v_mov_b32_e32 v127, 0
	s_mov_b32 s99, 0
	s_mov_b32 s98, 24576
	s_waitcnt vmcnt(12)
	s_barrier
	ds_read_b128 v[128:131], v231 offset:0
	ds_read_b128 v[132:135], v231 offset:1024
	ds_read_b128 v[136:139], v231 offset:2048
	ds_read_b128 v[140:143], v231 offset:3072
	ds_read_b128 v[144:147], v230 offset:0
	ds_read_b128 v[148:151], v230 offset:1024
	ds_read_b128 v[152:155], v230 offset:2048
	ds_read_b128 v[156:159], v230 offset:3072
	ds_read_b128 v[160:163], v230 offset:4096
	ds_read_b128 v[164:167], v230 offset:5120
	ds_read_b128 v[168:171], v230 offset:6144
	ds_read_b128 v[172:175], v230 offset:7168
.Lg9_kloop:
	s_waitcnt vmcnt(6)
	s_waitcnt lgkmcnt(0)
	s_barrier
	v_add_u32_e32 v232, s98, v230
	v_add_u32_e32 v233, s98, v231
	s_add_u32 s9, s17, s101
	v_mfma_f32_16x16x32_bf16 v[0:3], v[128:131], v[144:147], v[0:3]
	v_mfma_f32_16x16x32_bf16 v[4:7], v[132:135], v[144:147], v[4:7]
	v_mfma_f32_16x16x32_bf16 v[8:11], v[136:139], v[144:147], v[8:11]
	v_mfma_f32_16x16x32_bf16 v[12:15], v[140:143], v[144:147], v[12:15]
	ds_read_b128 v[176:179], v233 offset:0
	ds_read_b128 v[180:183], v233 offset:1024
	s_add_u32 m0, s9, 0
	s_nop 0
	global_load_lds_dwordx4 v224, s[0:1]
	v_mfma_f32_16x16x32_bf16 v[16:19], v[128:131], v[148:151], v[16:19]
	v_mfma_f32_16x16x32_bf16 v[20:23], v[132:135], v[148:151], v[20:23]
	v_mfma_f32_16x16x32_bf16 v[24:27], v[136:139], v[148:151], v[24:27]
	v_mfma_f32_16x16x32_bf16 v[28:31], v[140:143], v[148:151], v[28:31]
	ds_read_b128 v[184:187], v233 offset:2048
	ds_read_b128 v[188:191], v233 offset:3072
	s_add_u32 m0, s9, 4096
	s_nop 0
	global_load_lds_dwordx4 v225, s[0:1]
	v_mfma_f32_16x16x32_bf16 v[32:35], v[128:131], v[152:155], v[32:35]
	v_mfma_f32_16x16x32_bf16 v[36:39], v[132:135], v[152:155], v[36:39]
	v_mfma_f32_16x16x32_bf16 v[40:43], v[136:139], v[152:155], v[40:43]
	v_mfma_f32_16x16x32_bf16 v[44:47], v[140:143], v[152:155], v[44:47]
	ds_read_b128 v[192:195], v232 offset:0
	ds_read_b128 v[196:199], v232 offset:1024
	s_add_u32 m0, s9, 8192
	s_nop 0
	global_load_lds_dwordx4 v226, s[0:1]
	v_mfma_f32_16x16x32_bf16 v[48:51], v[128:131], v[156:159], v[48:51]
	v_mfma_f32_16x16x32_bf16 v[52:55], v[132:135], v[156:159], v[52:55]
	v_mfma_f32_16x16x32_bf16 v[56:59], v[136:139], v[156:159], v[56:59]
	v_mfma_f32_16x16x32_bf16 v[60:63], v[140:143], v[156:159], v[60:63]
	ds_read_b128 v[200:203], v232 offset:2048
	ds_read_b128 v[204:207], v232 offset:3072
	s_add_u32 m0, s9, 12288
	s_nop 0
	global_load_lds_dwordx4 v227, s[0:1]
	v_mfma_f32_16x16x32_bf16 v[64:67], v[128:131], v[160:163], v[64:67]
	v_mfma_f32_16x16x32_bf16 v[68:71], v[132:135], v[160:163], v[68:71]
	v_mfma_f32_16x16x32_bf16 v[72:75], v[136:139], v[160:163], v[72:75]
	v_mfma_f32_16x16x32_bf16 v[76:79], v[140:143], v[160:163], v[76:79]
	ds_read_b128 v[208:211], v232 offset:4096
	s_add_u32 m0, s9, 16384
	s_nop 0
	global_load_lds_dwordx4 v228, s[2:3]
	v_mfma_f32_16x16x32_bf16 v[80:83], v[128:131], v[164:167], v[80:83]
	v_mfma_f32_16x16x32_bf16 v[84:87], v[132:135], v[164:167], v[84:87]
	v_mfma_f32_16x16x32_bf16 v[88:91], v[136:139], v[164:167], v[88:91]
	v_mfma_f32_16x16x32_bf16 v[92:95], v[140:143], v[164:167], v[92:95]
	ds_read_b128 v[212:215], v232 offset:5120
	s_add_u32 m0, s9, 20480
	s_nop 0
	global_load_lds_dwordx4 v229, s[2:3]
	v_mfma_f32_16x16x32_bf16 v[96:99], v[128:131], v[168:171], v[96:99]
	v_mfma_f32_16x16x32_bf16 v[100:103], v[132:135], v[168:171], v[100:103]
	v_mfma_f32_16x16x32_bf16 v[104:107], v[136:139], v[168:171], v[104:107]
	v_mfma_f32_16x16x32_bf16 v[108:111], v[140:143], v[168:171], v[108:111]
	ds_read_b128 v[216:219], v232 offset:6144
	s_add_u32 s0, s0, 64
	s_addc_u32 s1, s1, 0
	s_add_u32 s2, s2, 64
	s_addc_u32 s3, s3, 0
	s_add_u32 s100, s100, 1
	s_add_u32 s17, s17, 24576
	s_cmp_eq_u32 s17, 73728
	s_cselect_b32 s17, 0, s17
	s_add_u32 s98, s98, 24576
	s_cmp_eq_u32 s98, 73728
	s_cselect_b32 s98, 0, s98
	v_mfma_f32_16x16x32_bf16 v[112:115], v[128:131], v[172:175], v[112:115]
	v_mfma_f32_16x16x32_bf16 v[116:119], v[132:135], v[172:175], v[116:119]
	v_mfma_f32_16x16x32_bf16 v[120:123], v[136:139], v[172:175], v[120:123]
	v_mfma_f32_16x16x32_bf16 v[124:127], v[140:143], v[172:175], v[124:127]
	ds_read_b128 v[220:223], v232 offset:7168
	s_waitcnt vmcnt(6)
	s_waitcnt lgkmcnt(0)
	s_barrier
; #define LWRITE(S, buf) do { bf16_t* sA_ = sbase + (buf) * BUF; bf16_t* sB_ = sA_ + 256 * PITCH; \
;     _Pragma("unroll") for (int i_ = 0; i_ < 4; ++i_) *(u32x4*)(sA_ + (sr + i_ * 64) * PITCH + scv * 8) = ra[S][i_]; \
;     _Pragma("unroll") for (int i_ = 0; i_ < 2; ++i_) *(u32x4*)(sB_ + (sr + i_ * 64) * PITCH + scv * 8) = rb[S][i_]; } while (0)
; template <class Epi>
; DI void gemm_tile(char* smem, const bf16_t* __restrict__ A0, int lda0, int ksplit, const bf16_t* __restrict__ A1, int lda1,
;                   const bf16_t* __restrict__ Bt, int K, int row0, int col0, const Epi& epi, int tid) {
;     ...
;     for (int kt = 0; kt < nk; kt += 2) {
;       LWRITE(1, 1);
;       __builtin_amdgcn_sched_barrier(0);
;       GLOAD(1, (kt + 3 < last ? kt + 3 : last));
;       __builtin_amdgcn_sched_barrier(0);
;       COMPUTE(0);
;       __syncthreads();
;       LWRITE(0, 0);
;       __builtin_amdgcn_sched_barrier(0);
;       GLOAD(0, (kt + 4 < last ? kt + 4 : last));
;       __builtin_amdgcn_sched_barrier(0);
;       COMPUTE(1);
;       __syncthreads();
;     }
	v_add_u32_e32 v232, s98, v230
	v_add_u32_e32 v233, s98, v231
	s_add_u32 s9, s17, s101
	v_mfma_f32_16x16x32_bf16 v[0:3], v[176:179], v[192:195], v[0:3]
	v_mfma_f32_16x16x32_bf16 v[4:7], v[180:183], v[192:195], v[4:7]
	v_mfma_f32_16x16x32_bf16 v[8:11], v[184:187], v[192:195], v[8:11]
	v_mfma_f32_16x16x32_bf16 v[12:15], v[188:191], v[192:195], v[12:15]
	ds_read_b128 v[128:131], v233 offset:0
	ds_read_b128 v[132:135], v233 offset:1024
	s_add_u32 m0, s9, 0
	s_nop 0
	global_load_lds_dwordx4 v224, s[0:1]
	v_mfma_f32_16x16x32_bf16 v[16:19], v[176:179], v[196:199], v[16:19]
	v_mfma_f32_16x16x32_bf16 v[20:23], v[180:183], v[196:199], v[20:23]
	v_mfma_f32_16x16x32_bf16 v[24:27], v[184:187], v[196:199], v[24:27]
	v_mfma_f32_16x16x32_bf16 v[28:31], v[188:191], v[196:199], v[28:31]
	ds_read_b128 v[136:139], v233 offset:2048
	ds_read_b128 v[140:143], v233 offset:3072
	s_add_u32 m0, s9, 4096
	s_nop 0
	global_load_lds_dwordx4 v225, s[0:1]
	v_mfma_f32_16x16x32_bf16 v[32:35], v[176:179], v[200:203], v[32:35]
	v_mfma_f32_16x16x32_bf16 v[36:39], v[180:183], v[200:203], v[36:39]
	v_mfma_f32_16x16x32_bf16 v[40:43], v[184:187], v[200:203], v[40:43]
	v_mfma_f32_16x16x32_bf16 v[44:47], v[188:191], v[200:203], v[44:47]
	ds_read_b128 v[144:147], v232 offset:0
	ds_read_b128 v[148:151], v232 offset:1024
	s_add_u32 m0, s9, 8192
	s_nop 0
	global_load_lds_dwordx4 v226, s[0:1]
	v_mfma_f32_16x16x32_bf16 v[48:51], v[176:179], v[204:207], v[48:51]
	v_mfma_f32_16x16x32_bf16 v[52:55], v[180:183], v[204:207], v[52:55]
	v_mfma_f32_16x16x32_bf16 v[56:59], v[184:187], v[204:207], v[56:59]
	v_mfma_f32_16x16x32_bf16 v[60:63], v[188:191], v[204:207], v[60:63]
	ds_read_b128 v[152:155], v232 offset:2048
	ds_read_b128 v[156:159], v232 offset:3072
	s_add_u32 m0, s9, 12288
	s_nop 0
	global_load_lds_dwordx4 v227, s[0:1]
	v_mfma_f32_16x16x32_bf16 v[64:67], v[176:179], v[208:211], v[64:67]
	v_mfma_f32_16x16x32_bf16 v[68:71], v[180:183], v[208:211], v[68:71]
	v_mfma_f32_16x16x32_bf16 v[72:75], v[184:187], v[208:211], v[72:75]
	v_mfma_f32_16x16x32_bf16 v[76:79], v[188:191], v[208:211], v[76:79]
	ds_read_b128 v[160:163], v232 offset:4096
	s_add_u32 m0, s9, 16384
	s_nop 0
	global_load_lds_dwordx4 v228, s[2:3]
	v_mfma_f32_16x16x32_bf16 v[80:83], v[176:179], v[212:215], v[80:83]
	v_mfma_f32_16x16x32_bf16 v[84:87], v[180:183], v[212:215], v[84:87]
	v_mfma_f32_16x16x32_bf16 v[88:91], v[184:187], v[212:215], v[88:91]
	v_mfma_f32_16x16x32_bf16 v[92:95], v[188:191], v[212:215], v[92:95]
	ds_read_b128 v[164:167], v232 offset:5120
	s_add_u32 m0, s9, 20480
	s_nop 0
	global_load_lds_dwordx4 v229, s[2:3]
	v_mfma_f32_16x16x32_bf16 v[96:99], v[176:179], v[216:219], v[96:99]
	v_mfma_f32_16x16x32_bf16 v[100:103], v[180:183], v[216:219], v[100:103]
	v_mfma_f32_16x16x32_bf16 v[104:107], v[184:187], v[216:219], v[104:107]
	v_mfma_f32_16x16x32_bf16 v[108:111], v[188:191], v[216:219], v[108:111]
	ds_read_b128 v[168:171], v232 offset:6144
	s_add_u32 s0, s0, 64
	s_addc_u32 s1, s1, 0
	s_add_u32 s2, s2, 64
	s_addc_u32 s3, s3, 0
	s_add_u32 s100, s100, 1
	s_add_u32 s17, s17, 24576
	s_cmp_eq_u32 s17, 73728
	s_cselect_b32 s17, 0, s17
	s_add_u32 s98, s98, 24576
	s_cmp_eq_u32 s98, 73728
	s_cselect_b32 s98, 0, s98
	v_mfma_f32_16x16x32_bf16 v[112:115], v[176:179], v[220:223], v[112:115]
	v_mfma_f32_16x16x32_bf16 v[116:119], v[180:183], v[220:223], v[116:119]
	v_mfma_f32_16x16x32_bf16 v[120:123], v[184:187], v[220:223], v[120:123]
	v_mfma_f32_16x16x32_bf16 v[124:127], v[188:191], v[220:223], v[124:127]
	ds_read_b128 v[172:175], v232 offset:7168
	s_add_u32 s99, s99, 2
	s_cmp_lt_u32 s99, 124
	s_cbranch_scc1 .Lg9_kloop
	s_waitcnt vmcnt(6)
	s_waitcnt lgkmcnt(0)
	s_barrier
	v_add_u32_e32 v232, s98, v230
	v_add_u32_e32 v233, s98, v231
	s_add_u32 s9, s17, s101
	v_mfma_f32_16x16x32_bf16 v[0:3], v[128:131], v[144:147], v[0:3]
	v_mfma_f32_16x16x32_bf16 v[4:7], v[132:135], v[144:147], v[4:7]
	v_mfma_f32_16x16x32_bf16 v[8:11], v[136:139], v[144:147], v[8:11]
	v_mfma_f32_16x16x32_bf16 v[12:15], v[140:143], v[144:147], v[12:15]
	ds_read_b128 v[176:179], v233 offset:0
	ds_read_b128 v[180:183], v233 offset:1024
	s_add_u32 m0, s9, 0
	s_nop 0
	global_load_lds_dwordx4 v224, s[0:1]
	v_mfma_f32_16x16x32_bf16 v[16:19], v[128:131], v[148:151], v[16:19]
	v_mfma_f32_16x16x32_bf16 v[20:23], v[132:135], v[148:151], v[20:23]
	v_mfma_f32_16x16x32_bf16 v[24:27], v[136:139], v[148:151], v[24:27]
	v_mfma_f32_16x16x32_bf16 v[28:31], v[140:143], v[148:151], v[28:31]
	ds_read_b128 v[184:187], v233 offset:2048
	ds_read_b128 v[188:191], v233 offset:3072
	s_add_u32 m0, s9, 4096
	s_nop 0
	global_load_lds_dwordx4 v225, s[0:1]
	v_mfma_f32_16x16x32_bf16 v[32:35], v[128:131], v[152:155], v[32:35]
	v_mfma_f32_16x16x32_bf16 v[36:39], v[132:135], v[152:155], v[36:39]
	v_mfma_f32_16x16x32_bf16 v[40:43], v[136:139], v[152:155], v[40:43]
	v_mfma_f32_16x16x32_bf16 v[44:47], v[140:143], v[152:155], v[44:47]
	ds_read_b128 v[192:195], v232 offset:0
	ds_read_b128 v[196:199], v232 offset:1024
	s_add_u32 m0, s9, 8192
	s_nop 0
	global_load_lds_dwordx4 v226, s[0:1]
	v_mfma_f32_16x16x32_bf16 v[48:51], v[128:131], v[156:159], v[48:51]
	v_mfma_f32_16x16x32_bf16 v[52:55], v[132:135], v[156:159], v[52:55]
	v_mfma_f32_16x16x32_bf16 v[56:59], v[136:139], v[156:159], v[56:59]
	v_mfma_f32_16x16x32_bf16 v[60:63], v[140:143], v[156:159], v[60:63]
	ds_read_b128 v[200:203], v232 offset:2048
	ds_read_b128 v[204:207], v232 offset:3072
	s_add_u32 m0, s9, 12288
	s_nop 0
	global_load_lds_dwordx4 v227, s[0:1]
	v_mfma_f32_16x16x32_bf16 v[64:67], v[128:131], v[160:163], v[64:67]
	v_mfma_f32_16x16x32_bf16 v[68:71], v[132:135], v[160:163], v[68:71]
	v_mfma_f32_16x16x32_bf16 v[72:75], v[136:139], v[160:163], v[72:75]
; #define LWRITE(S, buf) do { bf16_t* sA_ = sbase + (buf) * BUF; bf16_t* sB_ = sA_ + 256 * PITCH; \
;     _Pragma("unroll") for (int i_ = 0; i_ < 4; ++i_) *(u32x4*)(sA_ + (sr + i_ * 64) * PITCH + scv * 8) = ra[S][i_]; \
;     _Pragma("unroll") for (int i_ = 0; i_ < 2; ++i_) *(u32x4*)(sB_ + (sr + i_ * 64) * PITCH + scv * 8) = rb[S][i_]; } while (0)
; template <class Epi>
; DI void gemm_tile(char* smem, const bf16_t* __restrict__ A0, int lda0, int ksplit, const bf16_t* __restrict__ A1, int lda1,
;                   const bf16_t* __restrict__ Bt, int K, int row0, int col0, const Epi& epi, int tid) {
;     ...
;   __syncthreads();
;   {
;     const int last = nk - 1;
;     GLOAD(0, 0);
;     __builtin_amdgcn_sched_barrier(0);
;     GLOAD(1, 1);
;     __builtin_amdgcn_sched_barrier(0);
;     LWRITE(0, 0);
;     __builtin_amdgcn_sched_barrier(0);
;     GLOAD(0, (2 < last ? 2 : last));
;     __builtin_amdgcn_sched_barrier(0);
;     __syncthreads();
;     for (int kt = 0; kt < nk; kt += 2) {
;       LWRITE(1, 1);
;       __builtin_amdgcn_sched_barrier(0);
;       GLOAD(1, (kt + 3 < last ? kt + 3 : last));
;       __builtin_amdgcn_sched_barrier(0);
;       COMPUTE(0);
;       __syncthreads();
;       LWRITE(0, 0);
;       __builtin_amdgcn_sched_barrier(0);
;       GLOAD(0, (kt + 4 < last ? kt + 4 : last));
;       __builtin_amdgcn_sched_barrier(0);
;       COMPUTE(1);
;       __syncthreads();
;     }
	v_mfma_f32_16x16x32_bf16 v[76:79], v[140:143], v[160:163], v[76:79]
	ds_read_b128 v[208:211], v232 offset:4096
	s_add_u32 m0, s9, 16384
	s_nop 0
	global_load_lds_dwordx4 v228, s[2:3]
	v_mfma_f32_16x16x32_bf16 v[80:83], v[128:131], v[164:167], v[80:83]
	v_mfma_f32_16x16x32_bf16 v[84:87], v[132:135], v[164:167], v[84:87]
	v_mfma_f32_16x16x32_bf16 v[88:91], v[136:139], v[164:167], v[88:91]
	v_mfma_f32_16x16x32_bf16 v[92:95], v[140:143], v[164:167], v[92:95]
	ds_read_b128 v[212:215], v232 offset:5120
	s_add_u32 m0, s9, 20480
	s_nop 0
	global_load_lds_dwordx4 v229, s[2:3]
	v_mfma_f32_16x16x32_bf16 v[96:99], v[128:131], v[168:171], v[96:99]
	v_mfma_f32_16x16x32_bf16 v[100:103], v[132:135], v[168:171], v[100:103]
	v_mfma_f32_16x16x32_bf16 v[104:107], v[136:139], v[168:171], v[104:107]
	v_mfma_f32_16x16x32_bf16 v[108:111], v[140:143], v[168:171], v[108:111]
	ds_read_b128 v[216:219], v232 offset:6144
	s_add_u32 s0, s0, 64
	s_addc_u32 s1, s1, 0
	s_add_u32 s2, s2, 64
	s_addc_u32 s3, s3, 0
	s_add_u32 s100, s100, 1
	s_add_u32 s17, s17, 24576
	s_cmp_eq_u32 s17, 73728
	s_cselect_b32 s17, 0, s17
	s_add_u32 s98, s98, 24576
	s_cmp_eq_u32 s98, 73728
	s_cselect_b32 s98, 0, s98
	v_mfma_f32_16x16x32_bf16 v[112:115], v[128:131], v[172:175], v[112:115]
	v_mfma_f32_16x16x32_bf16 v[116:119], v[132:135], v[172:175], v[116:119]
	v_mfma_f32_16x16x32_bf16 v[120:123], v[136:139], v[172:175], v[120:123]
	v_mfma_f32_16x16x32_bf16 v[124:127], v[140:143], v[172:175], v[124:127]
	ds_read_b128 v[220:223], v232 offset:7168
	s_waitcnt vmcnt(6)
	s_waitcnt lgkmcnt(0)
	s_barrier
	v_add_u32_e32 v232, s98, v230
	v_add_u32_e32 v233, s98, v231
	v_mfma_f32_16x16x32_bf16 v[0:3], v[176:179], v[192:195], v[0:3]
	v_mfma_f32_16x16x32_bf16 v[4:7], v[180:183], v[192:195], v[4:7]
	v_mfma_f32_16x16x32_bf16 v[8:11], v[184:187], v[192:195], v[8:11]
	v_mfma_f32_16x16x32_bf16 v[12:15], v[188:191], v[192:195], v[12:15]
	ds_read_b128 v[128:131], v233 offset:0
	ds_read_b128 v[132:135], v233 offset:1024
	v_mfma_f32_16x16x32_bf16 v[16:19], v[176:179], v[196:199], v[16:19]
	v_mfma_f32_16x16x32_bf16 v[20:23], v[180:183], v[196:199], v[20:23]
	v_mfma_f32_16x16x32_bf16 v[24:27], v[184:187], v[196:199], v[24:27]
	v_mfma_f32_16x16x32_bf16 v[28:31], v[188:191], v[196:199], v[28:31]
	ds_read_b128 v[136:139], v233 offset:2048
	ds_read_b128 v[140:143], v233 offset:3072
	v_mfma_f32_16x16x32_bf16 v[32:35], v[176:179], v[200:203], v[32:35]
	v_mfma_f32_16x16x32_bf16 v[36:39], v[180:183], v[200:203], v[36:39]
	v_mfma_f32_16x16x32_bf16 v[40:43], v[184:187], v[200:203], v[40:43]
	v_mfma_f32_16x16x32_bf16 v[44:47], v[188:191], v[200:203], v[44:47]
	ds_read_b128 v[144:147], v232 offset:0
	ds_read_b128 v[148:151], v232 offset:1024
	v_mfma_f32_16x16x32_bf16 v[48:51], v[176:179], v[204:207], v[48:51]
	v_mfma_f32_16x16x32_bf16 v[52:55], v[180:183], v[204:207], v[52:55]
	v_mfma_f32_16x16x32_bf16 v[56:59], v[184:187], v[204:207], v[56:59]
	v_mfma_f32_16x16x32_bf16 v[60:63], v[188:191], v[204:207], v[60:63]
	ds_read_b128 v[152:155], v232 offset:2048
	ds_read_b128 v[156:159], v232 offset:3072
	v_mfma_f32_16x16x32_bf16 v[64:67], v[176:179], v[208:211], v[64:67]
	v_mfma_f32_16x16x32_bf16 v[68:71], v[180:183], v[208:211], v[68:71]
	v_mfma_f32_16x16x32_bf16 v[72:75], v[184:187], v[208:211], v[72:75]
	v_mfma_f32_16x16x32_bf16 v[76:79], v[188:191], v[208:211], v[76:79]
	ds_read_b128 v[160:163], v232 offset:4096
	v_mfma_f32_16x16x32_bf16 v[80:83], v[176:179], v[212:215], v[80:83]
	v_mfma_f32_16x16x32_bf16 v[84:87], v[180:183], v[212:215], v[84:87]
	v_mfma_f32_16x16x32_bf16 v[88:91], v[184:187], v[212:215], v[88:91]
	v_mfma_f32_16x16x32_bf16 v[92:95], v[188:191], v[212:215], v[92:95]
	ds_read_b128 v[164:167], v232 offset:5120
	v_mfma_f32_16x16x32_bf16 v[96:99], v[176:179], v[216:219], v[96:99]
	v_mfma_f32_16x16x32_bf16 v[100:103], v[180:183], v[216:219], v[100:103]
	v_mfma_f32_16x16x32_bf16 v[104:107], v[184:187], v[216:219], v[104:107]
	v_mfma_f32_16x16x32_bf16 v[108:111], v[188:191], v[216:219], v[108:111]
	ds_read_b128 v[168:171], v232 offset:6144
	s_add_u32 s98, s98, 24576
	s_cmp_eq_u32 s98, 73728
	s_cselect_b32 s98, 0, s98
	v_mfma_f32_16x16x32_bf16 v[112:115], v[176:179], v[220:223], v[112:115]
	v_mfma_f32_16x16x32_bf16 v[116:119], v[180:183], v[220:223], v[116:119]
	v_mfma_f32_16x16x32_bf16 v[120:123], v[184:187], v[220:223], v[120:123]
	v_mfma_f32_16x16x32_bf16 v[124:127], v[188:191], v[220:223], v[124:127]
	ds_read_b128 v[172:175], v232 offset:7168
	s_waitcnt vmcnt(0)
	s_waitcnt lgkmcnt(0)
	s_barrier
; #define LWRITE(S, buf) do { bf16_t* sA_ = sbase + (buf) * BUF; bf16_t* sB_ = sA_ + 256 * PITCH; \
;     _Pragma("unroll") for (int i_ = 0; i_ < 4; ++i_) *(u32x4*)(sA_ + (sr + i_ * 64) * PITCH + scv * 8) = ra[S][i_]; \
;     _Pragma("unroll") for (int i_ = 0; i_ < 2; ++i_) *(u32x4*)(sB_ + (sr + i_ * 64) * PITCH + scv * 8) = rb[S][i_]; } while (0)
; template <class Epi>
; DI void gemm_tile(char* smem, const bf16_t* __restrict__ A0, int lda0, int ksplit, const bf16_t* __restrict__ A1, int lda1,
;                   const bf16_t* __restrict__ Bt, int K, int row0, int col0, const Epi& epi, int tid) {
;     ...
;   __syncthreads();
;   {
;     const int last = nk - 1;
;     GLOAD(0, 0);
;     __builtin_amdgcn_sched_barrier(0);
;     GLOAD(1, 1);
;     __builtin_amdgcn_sched_barrier(0);
;     LWRITE(0, 0);
;     __builtin_amdgcn_sched_barrier(0);
;     GLOAD(0, (2 < last ? 2 : last));
;     __builtin_amdgcn_sched_barrier(0);
;     __syncthreads();
;     for (int kt = 0; kt < nk; kt += 2) {
;       LWRITE(1, 1);
;       __builtin_amdgcn_sched_barrier(0);
;       GLOAD(1, (kt + 3 < last ? kt + 3 : last));
;       __builtin_amdgcn_sched_barrier(0);
;       COMPUTE(0);
;       __syncthreads();
;       LWRITE(0, 0);
;       __builtin_amdgcn_sched_barrier(0);
;       GLOAD(0, (kt + 4 < last ? kt + 4 : last));
;       __builtin_amdgcn_sched_barrier(0);
;       COMPUTE(1);
;       __syncthreads();
;     }
	v_add_u32_e32 v232, s98, v230
	v_add_u32_e32 v233, s98, v231
	v_mfma_f32_16x16x32_bf16 v[0:3], v[128:131], v[144:147], v[0:3]
	v_mfma_f32_16x16x32_bf16 v[4:7], v[132:135], v[144:147], v[4:7]
	v_mfma_f32_16x16x32_bf16 v[8:11], v[136:139], v[144:147], v[8:11]
	v_mfma_f32_16x16x32_bf16 v[12:15], v[140:143], v[144:147], v[12:15]
	ds_read_b128 v[176:179], v233 offset:0
	ds_read_b128 v[180:183], v233 offset:1024
	v_mfma_f32_16x16x32_bf16 v[16:19], v[128:131], v[148:151], v[16:19]
	v_mfma_f32_16x16x32_bf16 v[20:23], v[132:135], v[148:151], v[20:23]
	v_mfma_f32_16x16x32_bf16 v[24:27], v[136:139], v[148:151], v[24:27]
	v_mfma_f32_16x16x32_bf16 v[28:31], v[140:143], v[148:151], v[28:31]
	ds_read_b128 v[184:187], v233 offset:2048
	ds_read_b128 v[188:191], v233 offset:3072
	v_mfma_f32_16x16x32_bf16 v[32:35], v[128:131], v[152:155], v[32:35]
	v_mfma_f32_16x16x32_bf16 v[36:39], v[132:135], v[152:155], v[36:39]
	v_mfma_f32_16x16x32_bf16 v[40:43], v[136:139], v[152:155], v[40:43]
	v_mfma_f32_16x16x32_bf16 v[44:47], v[140:143], v[152:155], v[44:47]
	ds_read_b128 v[192:195], v232 offset:0
	ds_read_b128 v[196:199], v232 offset:1024
	v_mfma_f32_16x16x32_bf16 v[48:51], v[128:131], v[156:159], v[48:51]
	v_mfma_f32_16x16x32_bf16 v[52:55], v[132:135], v[156:159], v[52:55]
	v_mfma_f32_16x16x32_bf16 v[56:59], v[136:139], v[156:159], v[56:59]
	v_mfma_f32_16x16x32_bf16 v[60:63], v[140:143], v[156:159], v[60:63]
	ds_read_b128 v[200:203], v232 offset:2048
	ds_read_b128 v[204:207], v232 offset:3072
	v_mfma_f32_16x16x32_bf16 v[64:67], v[128:131], v[160:163], v[64:67]
	v_mfma_f32_16x16x32_bf16 v[68:71], v[132:135], v[160:163], v[68:71]
	v_mfma_f32_16x16x32_bf16 v[72:75], v[136:139], v[160:163], v[72:75]
	v_mfma_f32_16x16x32_bf16 v[76:79], v[140:143], v[160:163], v[76:79]
	ds_read_b128 v[208:211], v232 offset:4096
	v_mfma_f32_16x16x32_bf16 v[80:83], v[128:131], v[164:167], v[80:83]
	v_mfma_f32_16x16x32_bf16 v[84:87], v[132:135], v[164:167], v[84:87]
	v_mfma_f32_16x16x32_bf16 v[88:91], v[136:139], v[164:167], v[88:91]
	v_mfma_f32_16x16x32_bf16 v[92:95], v[140:143], v[164:167], v[92:95]
	ds_read_b128 v[212:215], v232 offset:5120
	v_mfma_f32_16x16x32_bf16 v[96:99], v[128:131], v[168:171], v[96:99]
	v_mfma_f32_16x16x32_bf16 v[100:103], v[132:135], v[168:171], v[100:103]
	v_mfma_f32_16x16x32_bf16 v[104:107], v[136:139], v[168:171], v[104:107]
	v_mfma_f32_16x16x32_bf16 v[108:111], v[140:143], v[168:171], v[108:111]
	ds_read_b128 v[216:219], v232 offset:6144
	s_add_u32 s98, s98, 24576
	s_cmp_eq_u32 s98, 73728
	s_cselect_b32 s98, 0, s98
	v_mfma_f32_16x16x32_bf16 v[112:115], v[128:131], v[172:175], v[112:115]
	v_mfma_f32_16x16x32_bf16 v[116:119], v[132:135], v[172:175], v[116:119]
	v_mfma_f32_16x16x32_bf16 v[120:123], v[136:139], v[172:175], v[120:123]
	v_mfma_f32_16x16x32_bf16 v[124:127], v[140:143], v[172:175], v[124:127]
	ds_read_b128 v[220:223], v232 offset:7168
	s_waitcnt lgkmcnt(0)
	s_barrier
	v_mfma_f32_16x16x32_bf16 v[0:3], v[176:179], v[192:195], v[0:3]
	v_mfma_f32_16x16x32_bf16 v[4:7], v[180:183], v[192:195], v[4:7]
	v_mfma_f32_16x16x32_bf16 v[8:11], v[184:187], v[192:195], v[8:11]
	v_mfma_f32_16x16x32_bf16 v[12:15], v[188:191], v[192:195], v[12:15]
	v_mfma_f32_16x16x32_bf16 v[16:19], v[176:179], v[196:199], v[16:19]
	v_mfma_f32_16x16x32_bf16 v[20:23], v[180:183], v[196:199], v[20:23]
	v_mfma_f32_16x16x32_bf16 v[24:27], v[184:187], v[196:199], v[24:27]
	v_mfma_f32_16x16x32_bf16 v[28:31], v[188:191], v[196:199], v[28:31]
	v_mfma_f32_16x16x32_bf16 v[32:35], v[176:179], v[200:203], v[32:35]
	v_mfma_f32_16x16x32_bf16 v[36:39], v[180:183], v[200:203], v[36:39]
	v_mfma_f32_16x16x32_bf16 v[40:43], v[184:187], v[200:203], v[40:43]
	v_mfma_f32_16x16x32_bf16 v[44:47], v[188:191], v[200:203], v[44:47]
	v_mfma_f32_16x16x32_bf16 v[48:51], v[176:179], v[204:207], v[48:51]
	v_mfma_f32_16x16x32_bf16 v[52:55], v[180:183], v[204:207], v[52:55]
	v_mfma_f32_16x16x32_bf16 v[56:59], v[184:187], v[204:207], v[56:59]
	v_mfma_f32_16x16x32_bf16 v[60:63], v[188:191], v[204:207], v[60:63]
	v_mfma_f32_16x16x32_bf16 v[64:67], v[176:179], v[208:211], v[64:67]
	v_mfma_f32_16x16x32_bf16 v[68:71], v[180:183], v[208:211], v[68:71]
	v_mfma_f32_16x16x32_bf16 v[72:75], v[184:187], v[208:211], v[72:75]
	v_mfma_f32_16x16x32_bf16 v[76:79], v[188:191], v[208:211], v[76:79]
	v_mfma_f32_16x16x32_bf16 v[80:83], v[176:179], v[212:215], v[80:83]
	v_mfma_f32_16x16x32_bf16 v[84:87], v[180:183], v[212:215], v[84:87]
	v_mfma_f32_16x16x32_bf16 v[88:91], v[184:187], v[212:215], v[88:91]
	v_mfma_f32_16x16x32_bf16 v[92:95], v[188:191], v[212:215], v[92:95]
	v_mfma_f32_16x16x32_bf16 v[96:99], v[176:179], v[216:219], v[96:99]
	v_mfma_f32_16x16x32_bf16 v[100:103], v[180:183], v[216:219], v[100:103]
	v_mfma_f32_16x16x32_bf16 v[104:107], v[184:187], v[216:219], v[104:107]
	v_mfma_f32_16x16x32_bf16 v[108:111], v[188:191], v[216:219], v[108:111]
	v_mfma_f32_16x16x32_bf16 v[112:115], v[176:179], v[220:223], v[112:115]
	v_mfma_f32_16x16x32_bf16 v[116:119], v[180:183], v[220:223], v[116:119]
	v_mfma_f32_16x16x32_bf16 v[120:123], v[184:187], v[220:223], v[120:123]
	v_mfma_f32_16x16x32_bf16 v[124:127], v[188:191], v[220:223], v[124:127]
	s_branch .Lg9_epi
; template <class Epi>
; DI void gemm_tile(char* smem, const bf16_t* __restrict__ A0, int lda0, int ksplit, const bf16_t* __restrict__ A1, int lda1,
;                   const bf16_t* __restrict__ Bt, int K, int row0, int col0, const Epi& epi, int tid) {
;     ...
; #pragma unroll
;   for (int m = 0; m < 8; ++m)
; #pragma unroll
;     for (int n = 0; n < 4; ++n) epi(row0 + wr * 128 + m * 16 + fr, col0 + wc * 64 + n * 16 + fq * 4, acc[m][n]);
.Lg9_epi:
	s_nop 7
	s_nop 7
	s_lshl_b32 s10, s16, 12
	s_lshl_b32 s9, s11, 2
	s_add_u32 s10, s10, s9
	s_add_u32 s4, s6, s10
	s_addc_u32 s5, s7, 0
	global_load_dwordx4 v[128:131], v234, s[4:5] offset:0
	global_load_dwordx4 v[132:135], v234, s[4:5] offset:64
	global_load_dwordx4 v[136:139], v234, s[4:5] offset:128
	global_load_dwordx4 v[140:143], v234, s[4:5] offset:192
	s_add_u32 s4, s4, 0x10000
	s_addc_u32 s5, s5, 0
	global_load_dwordx4 v[144:147], v234, s[4:5] offset:0
	global_load_dwordx4 v[148:151], v234, s[4:5] offset:64
	global_load_dwordx4 v[152:155], v234, s[4:5] offset:128
	global_load_dwordx4 v[156:159], v234, s[4:5] offset:192
	s_add_u32 s4, s4, 0x10000
	s_addc_u32 s5, s5, 0
	global_load_dwordx4 v[160:163], v234, s[4:5] offset:0
	global_load_dwordx4 v[164:167], v234, s[4:5] offset:64
	global_load_dwordx4 v[168:171], v234, s[4:5] offset:128
	global_load_dwordx4 v[172:175], v234, s[4:5] offset:192
	s_add_u32 s4, s4, 0x10000
	s_addc_u32 s5, s5, 0
	global_load_dwordx4 v[176:179], v234, s[4:5] offset:0
	global_load_dwordx4 v[180:183], v234, s[4:5] offset:64
	global_load_dwordx4 v[184:187], v234, s[4:5] offset:128
	global_load_dwordx4 v[188:191], v234, s[4:5] offset:192
	s_add_u32 s4, s4, 0x10000
	s_addc_u32 s5, s5, 0
	s_sub_u32 s4, s4, 0x40000
	s_subb_u32 s5, s5, 0
	s_waitcnt vmcnt(15)
	v_pk_add_f32 v[128:129], v[128:129], v[0:1]
	v_pk_add_f32 v[130:131], v[130:131], v[2:3]
	global_store_dwordx4 v234, v[128:131], s[4:5] offset:0
	s_waitcnt vmcnt(15)
	v_pk_add_f32 v[132:133], v[132:133], v[4:5]
	v_pk_add_f32 v[134:135], v[134:135], v[6:7]
	global_store_dwordx4 v234, v[132:135], s[4:5] offset:64
	s_waitcnt vmcnt(15)
	v_pk_add_f32 v[136:137], v[136:137], v[8:9]
	v_pk_add_f32 v[138:139], v[138:139], v[10:11]
	global_store_dwordx4 v234, v[136:139], s[4:5] offset:128
	s_waitcnt vmcnt(15)
	v_pk_add_f32 v[140:141], v[140:141], v[12:13]
	v_pk_add_f32 v[142:143], v[142:143], v[14:15]
	global_store_dwordx4 v234, v[140:143], s[4:5] offset:192
	s_add_u32 s4, s4, 0x10000
	s_addc_u32 s5, s5, 0
	s_waitcnt vmcnt(15)
	v_pk_add_f32 v[144:145], v[144:145], v[16:17]
	v_pk_add_f32 v[146:147], v[146:147], v[18:19]
	global_store_dwordx4 v234, v[144:147], s[4:5] offset:0
	s_waitcnt vmcnt(15)
	v_pk_add_f32 v[148:149], v[148:149], v[20:21]
	v_pk_add_f32 v[150:151], v[150:151], v[22:23]
	global_store_dwordx4 v234, v[148:151], s[4:5] offset:64
	s_waitcnt vmcnt(15)
	v_pk_add_f32 v[152:153], v[152:153], v[24:25]
	v_pk_add_f32 v[154:155], v[154:155], v[26:27]
	global_store_dwordx4 v234, v[152:155], s[4:5] offset:128
	s_waitcnt vmcnt(15)
	v_pk_add_f32 v[156:157], v[156:157], v[28:29]
	v_pk_add_f32 v[158:159], v[158:159], v[30:31]
	global_store_dwordx4 v234, v[156:159], s[4:5] offset:192
	s_add_u32 s4, s4, 0x10000
	s_addc_u32 s5, s5, 0
	s_waitcnt vmcnt(15)
	v_pk_add_f32 v[160:161], v[160:161], v[32:33]
	v_pk_add_f32 v[162:163], v[162:163], v[34:35]
	global_store_dwordx4 v234, v[160:163], s[4:5] offset:0
	s_waitcnt vmcnt(15)
	v_pk_add_f32 v[164:165], v[164:165], v[36:37]
	v_pk_add_f32 v[166:167], v[166:167], v[38:39]
	global_store_dwordx4 v234, v[164:167], s[4:5] offset:64
	s_waitcnt vmcnt(15)
	v_pk_add_f32 v[168:169], v[168:169], v[40:41]
	v_pk_add_f32 v[170:171], v[170:171], v[42:43]
	global_store_dwordx4 v234, v[168:171], s[4:5] offset:128
	s_waitcnt vmcnt(15)
	v_pk_add_f32 v[172:173], v[172:173], v[44:45]
	v_pk_add_f32 v[174:175], v[174:175], v[46:47]
	global_store_dwordx4 v234, v[172:175], s[4:5] offset:192
	s_add_u32 s4, s4, 0x10000
	s_addc_u32 s5, s5, 0
	s_waitcnt vmcnt(15)
	v_pk_add_f32 v[176:177], v[176:177], v[48:49]
	v_pk_add_f32 v[178:179], v[178:179], v[50:51]
	global_store_dwordx4 v234, v[176:179], s[4:5] offset:0
	s_waitcnt vmcnt(15)
	v_pk_add_f32 v[180:181], v[180:181], v[52:53]
	v_pk_add_f32 v[182:183], v[182:183], v[54:55]
	global_store_dwordx4 v234, v[180:183], s[4:5] offset:64
	s_waitcnt vmcnt(15)
	v_pk_add_f32 v[184:185], v[184:185], v[56:57]
	v_pk_add_f32 v[186:187], v[186:187], v[58:59]
	global_store_dwordx4 v234, v[184:187], s[4:5] offset:128
	s_waitcnt vmcnt(15)
; template <class Epi>
; DI void gemm_tile(char* smem, const bf16_t* __restrict__ A0, int lda0, int ksplit, const bf16_t* __restrict__ A1, int lda1,
;                   const bf16_t* __restrict__ Bt, int K, int row0, int col0, const Epi& epi, int tid) {
;     ...
; #pragma unroll
;   for (int m = 0; m < 8; ++m)
; #pragma unroll
;     for (int n = 0; n < 4; ++n) epi(row0 + wr * 128 + m * 16 + fr, col0 + wc * 64 + n * 16 + fq * 4, acc[m][n]);
	v_pk_add_f32 v[188:189], v[188:189], v[60:61]
	v_pk_add_f32 v[190:191], v[190:191], v[62:63]
	global_store_dwordx4 v234, v[188:191], s[4:5] offset:192
	s_add_u32 s4, s4, 0x10000
	s_addc_u32 s5, s5, 0
	s_nop 1
	global_load_dwordx4 v[128:131], v234, s[4:5] offset:0
	global_load_dwordx4 v[132:135], v234, s[4:5] offset:64
	global_load_dwordx4 v[136:139], v234, s[4:5] offset:128
	global_load_dwordx4 v[140:143], v234, s[4:5] offset:192
	s_add_u32 s4, s4, 0x10000
	s_addc_u32 s5, s5, 0
	global_load_dwordx4 v[144:147], v234, s[4:5] offset:0
	global_load_dwordx4 v[148:151], v234, s[4:5] offset:64
	global_load_dwordx4 v[152:155], v234, s[4:5] offset:128
	global_load_dwordx4 v[156:159], v234, s[4:5] offset:192
	s_add_u32 s4, s4, 0x10000
	s_addc_u32 s5, s5, 0
	global_load_dwordx4 v[160:163], v234, s[4:5] offset:0
	global_load_dwordx4 v[164:167], v234, s[4:5] offset:64
	global_load_dwordx4 v[168:171], v234, s[4:5] offset:128
	global_load_dwordx4 v[172:175], v234, s[4:5] offset:192
	s_add_u32 s4, s4, 0x10000
	s_addc_u32 s5, s5, 0
	global_load_dwordx4 v[176:179], v234, s[4:5] offset:0
	global_load_dwordx4 v[180:183], v234, s[4:5] offset:64
	global_load_dwordx4 v[184:187], v234, s[4:5] offset:128
	global_load_dwordx4 v[188:191], v234, s[4:5] offset:192
	s_sub_u32 s4, s4, 0x30000
	s_subb_u32 s5, s5, 0
	s_waitcnt vmcnt(15)
	v_pk_add_f32 v[128:129], v[128:129], v[64:65]
	v_pk_add_f32 v[130:131], v[130:131], v[66:67]
	global_store_dwordx4 v234, v[128:131], s[4:5] offset:0
	s_waitcnt vmcnt(15)
	v_pk_add_f32 v[132:133], v[132:133], v[68:69]
	v_pk_add_f32 v[134:135], v[134:135], v[70:71]
	global_store_dwordx4 v234, v[132:135], s[4:5] offset:64
	s_waitcnt vmcnt(15)
	v_pk_add_f32 v[136:137], v[136:137], v[72:73]
	v_pk_add_f32 v[138:139], v[138:139], v[74:75]
	global_store_dwordx4 v234, v[136:139], s[4:5] offset:128
	s_waitcnt vmcnt(15)
	v_pk_add_f32 v[140:141], v[140:141], v[76:77]
	v_pk_add_f32 v[142:143], v[142:143], v[78:79]
	global_store_dwordx4 v234, v[140:143], s[4:5] offset:192
	s_add_u32 s4, s4, 0x10000
	s_addc_u32 s5, s5, 0
	s_waitcnt vmcnt(15)
	v_pk_add_f32 v[144:145], v[144:145], v[80:81]
	v_pk_add_f32 v[146:147], v[146:147], v[82:83]
	global_store_dwordx4 v234, v[144:147], s[4:5] offset:0
	s_waitcnt vmcnt(15)
	v_pk_add_f32 v[148:149], v[148:149], v[84:85]
	v_pk_add_f32 v[150:151], v[150:151], v[86:87]
	global_store_dwordx4 v234, v[148:151], s[4:5] offset:64
	s_waitcnt vmcnt(15)
	v_pk_add_f32 v[152:153], v[152:153], v[88:89]
	v_pk_add_f32 v[154:155], v[154:155], v[90:91]
	global_store_dwordx4 v234, v[152:155], s[4:5] offset:128
	s_waitcnt vmcnt(15)
	v_pk_add_f32 v[156:157], v[156:157], v[92:93]
	v_pk_add_f32 v[158:159], v[158:159], v[94:95]
	global_store_dwordx4 v234, v[156:159], s[4:5] offset:192
	s_add_u32 s4, s4, 0x10000
	s_addc_u32 s5, s5, 0
	s_waitcnt vmcnt(15)
	v_pk_add_f32 v[160:161], v[160:161], v[96:97]
	v_pk_add_f32 v[162:163], v[162:163], v[98:99]
	global_store_dwordx4 v234, v[160:163], s[4:5] offset:0
	s_waitcnt vmcnt(15)
	v_pk_add_f32 v[164:165], v[164:165], v[100:101]
	v_pk_add_f32 v[166:167], v[166:167], v[102:103]
	global_store_dwordx4 v234, v[164:167], s[4:5] offset:64
	s_waitcnt vmcnt(15)
	v_pk_add_f32 v[168:169], v[168:169], v[104:105]
	v_pk_add_f32 v[170:171], v[170:171], v[106:107]
	global_store_dwordx4 v234, v[168:171], s[4:5] offset:128
	s_waitcnt vmcnt(15)
	v_pk_add_f32 v[172:173], v[172:173], v[108:109]
	v_pk_add_f32 v[174:175], v[174:175], v[110:111]
	global_store_dwordx4 v234, v[172:175], s[4:5] offset:192
	s_add_u32 s4, s4, 0x10000
	s_addc_u32 s5, s5, 0
	s_waitcnt vmcnt(15)
	v_pk_add_f32 v[176:177], v[176:177], v[112:113]
	v_pk_add_f32 v[178:179], v[178:179], v[114:115]
	global_store_dwordx4 v234, v[176:179], s[4:5] offset:0
	s_waitcnt vmcnt(15)
	v_pk_add_f32 v[180:181], v[180:181], v[116:117]
	v_pk_add_f32 v[182:183], v[182:183], v[118:119]
	global_store_dwordx4 v234, v[180:183], s[4:5] offset:64
	s_waitcnt vmcnt(15)
	v_pk_add_f32 v[184:185], v[184:185], v[120:121]
	v_pk_add_f32 v[186:187], v[186:187], v[122:123]
	global_store_dwordx4 v234, v[184:187], s[4:5] offset:128
	s_waitcnt vmcnt(15)
	v_pk_add_f32 v[188:189], v[188:189], v[124:125]
	v_pk_add_f32 v[190:191], v[190:191], v[126:127]
	global_store_dwordx4 v234, v[188:191], s[4:5] offset:192
	s_add_u32 s4, s4, 0x10000
	s_addc_u32 s5, s5, 0
	s_nop 1
	s_add_u32 s15, s15, 64
	s_branch .Lg9_tile

; #define LWRITE(S, buf) do { bf16_t* sA_ = sbase + (buf) * BUF; bf16_t* sB_ = sA_ + 256 * PITCH; \
;     _Pragma("unroll") for (int i_ = 0; i_ < 4; ++i_) *(u32x4*)(sA_ + (sr + i_ * 64) * PITCH + scv * 8) = ra[S][i_]; \
;     _Pragma("unroll") for (int i_ = 0; i_ < 2; ++i_) *(u32x4*)(sB_ + (sr + i_ * 64) * PITCH + scv * 8) = rb[S][i_]; } while (0)
; template <class Epi>
; DI void gemm_tile(char* smem, const bf16_t* __restrict__ A0, int lda0, int ksplit, const bf16_t* __restrict__ A1, int lda1,
;                   const bf16_t* __restrict__ Bt, int K, int row0, int col0, const Epi& epi, int tid) {
;   constexpr int BK = 32, PITCH = 40, BUF = (256 + 128) * PITCH;
;   bf16_t* sbase = (bf16_t*)smem;
;   const int lane = tid & 63, wid = tid >> 6, wr = wid >> 1, wc = wid & 1, fr = lane & 15, fq = lane >> 4;
;   f32x4 acc[8][4];
; #pragma unroll
;   for (int m = 0; m < 8; ++m)
; #pragma unroll
;     for (int n = 0; n < 4; ++n) acc[m][n] = (f32x4){0.f, 0.f, 0.f, 0.f};
;   u32x4 ra[2][4], rb[2][2];
;   const int nk = K / BK;
;   const int sr = tid >> 2, scv = tid & 3;
;     ...
;   __syncthreads();
;   {
;     const int last = nk - 1;
;     GLOAD(0, 0);
;     __builtin_amdgcn_sched_barrier(0);
;     GLOAD(1, 1);
;     __builtin_amdgcn_sched_barrier(0);
;     LWRITE(0, 0);
;     __builtin_amdgcn_sched_barrier(0);
;     GLOAD(0, (2 < last ? 2 : last));
;     __builtin_amdgcn_sched_barrier(0);
;     __syncthreads();
; template <class Epi>
; DI void gemm_phase(char* smem, const bf16_t* A0, int lda0, int ksplit, const bf16_t* A1, int lda1, const bf16_t* Bt, int K, int nN, const Epi& epi, int tid) {
;     ...
;   if ((G & 7) == 0) {
;     const int x = blockIdx.x & 7, l = blockIdx.x >> 3, L = G >> 3, per = 8 * nN, tot = 2 * per;
;     for (int q = l; q < tot; q += L) { const int rgl = q / per, rem = q % per, ct = rem >> 3, rt = (x * 2 + rgl) * 8 + (rem & 7);
;       gemm_tile(smem, A0, lda0, ksplit, A1, lda1, Bt, K, rt * 256, ct * 128, epi, tid); }
.LBB0_975:
	s_cmp_gt_i32 s94, 11
	s_cselect_b64 s[0:1], -1, 0
	s_cmp_lt_i32 s95, 12
	s_cselect_b64 s[2:3], -1, 0
	s_or_b64 s[0:1], s[0:1], s[2:3]
	s_and_b64 vcc, exec, s[0:1]
	s_cbranch_vccnz .LBB0_1259
	s_load_dword s34, s[74:75], 0x180
	s_add_u32 s0, s92, 0x3800000
	s_addc_u32 s1, s93, 0
	s_add_u32 s10, s92, 0x2bc0000
	s_addc_u32 s11, s93, 0
	s_and_b32 s36, s72, 0xffffffc0
	v_mbcnt_hi_u32_b32 v195, -1, v194
	s_waitcnt lgkmcnt(0)
	s_and_b32 s35, s34, 7
	s_cmp_lg_u32 s35, 0
	s_waitcnt vmcnt(16)
	v_add_u32_e32 v196, s36, v195
	v_mbcnt_lo_u32_b32 v240, -1, 0
	v_mbcnt_hi_u32_b32 v240, -1, v240
	s_lshr_b32 s26, s72, 6
	s_lshl_b32 s99, s26, 10
	v_and_b32_e32 v241, 15, v240
	v_lshrrev_b32_e32 v242, 4, v240
	v_bfe_u32 v243, v240, 3, 1
	v_mul_u32_u24_e32 v243, 3, v243
	v_xor_b32_e32 v243, v242, v243
	v_lshlrev_b32_e32 v243, 4, v243
	v_lshl_add_u32 v243, v241, 6, v243
	s_lshr_b32 s25, s26, 1
	s_lshl_b32 s25, s25, 13
	v_add_u32_e32 v230, s25, v243
	s_and_b32 s25, s26, 1
	s_lshl_b32 s25, s25, 12
	s_add_u32 s25, s25, 16384
	v_add_u32_e32 v231, s25, v243
	s_lshr_b32 s25, s26, 1
	s_lshl_b32 s25, s25, 7
	v_add_u32_e32 v244, s25, v241
	s_and_b32 s25, s26, 1
	s_lshl_b32 s25, s25, 6
	v_lshl_add_u32 v245, v242, 2, s25
	s_movk_i32 s25, 1024
	v_mul_lo_u32 v246, v244, s25
	v_lshl_add_u32 v234, v245, 1, v246
	s_movk_i32 s25, 4160
	v_mul_lo_u32 v246, v244, s25
	v_lshl_add_u32 v235, v245, 1, v246
	v_lshrrev_b32_e32 v241, 2, v240
	s_lshl_b32 s25, s26, 4
	v_add_u32_e32 v241, s25, v241
	v_bfe_u32 v242, v240, 5, 1
	v_mul_u32_u24_e32 v242, 3, v242
	v_and_b32_e32 v243, 3, v240
	v_xor_b32_e32 v243, v243, v242
	v_lshlrev_b32_e32 v243, 4, v243
	s_mov_b32 s25, 2048
	v_mad_u32_u24 v224, v241, s25, v243
	v_add_u32_e32 v225, 0x20000, v224
	v_add_u32_e32 v226, 0x40000, v224
	v_add_u32_e32 v227, 0x60000, v224
	s_mov_b32 s25, 2048
	v_mad_u32_u24 v228, v241, s25, v243
	v_add_u32_e32 v229, 0x20000, v228
	s_lshr_b32 s101, s96, 3
	s_and_b32 s100, s96, 7
	s_lshl_b32 s100, s100, 1
	s_waitcnt lgkmcnt(0)
.Lg11_tile:
	s_cmpk_ge_u32 s101, 336
	s_cbranch_scc1 .Lg11_done
	s_cmpk_ge_u32 s101, 168
	s_cselect_b32 s26, 1, 0
	s_cselect_b32 s25, 168, 0
	s_sub_u32 s25, s101, s25
	s_add_u32 s26, s26, s100
	s_lshl_b32 s26, s26, 3
	s_and_b32 s28, s25, 7
	s_add_u32 s28, s28, s26
	s_lshl_b32 s28, s28, 8
	s_lshr_b32 s27, s25, 3
	s_lshl_b32 s27, s27, 7
	s_mul_i32 s26, s28, 2048
	s_add_u32 s26, s26, 0x3800000
	s_add_u32 s0, s92, s26
	s_addc_u32 s1, s93, 0
	s_mul_i32 s26, s27, 2048
	s_add_u32 s26, s26, 0x2bc0000
	s_add_u32 s2, s92, s26
	s_addc_u32 s3, s93, 0
	s_mov_b32 s98, 0
	s_mov_b32 s29, 0
	s_add_u32 s25, s29, s99
	s_add_u32 m0, s25, 0
	s_nop 0
	global_load_lds_dwordx4 v224, s[0:1]
	s_add_u32 m0, s25, 4096
	s_nop 0
	global_load_lds_dwordx4 v225, s[0:1]
	s_add_u32 m0, s25, 8192
	s_nop 0
	global_load_lds_dwordx4 v226, s[0:1]
	s_add_u32 m0, s25, 12288
	s_nop 0
	global_load_lds_dwordx4 v227, s[0:1]
	s_add_u32 m0, s25, 16384
	s_nop 0
	global_load_lds_dwordx4 v228, s[2:3]
	s_add_u32 m0, s25, 20480
	s_nop 0
	global_load_lds_dwordx4 v229, s[2:3]
	s_add_u32 s0, s0, 64
	s_addc_u32 s1, s1, 0
	s_add_u32 s2, s2, 64
	s_addc_u32 s3, s3, 0
	s_add_u32 s98, s98, 1
	s_add_u32 s29, s29, 24576
	s_cmp_eq_u32 s29, 73728
	s_cselect_b32 s29, 0, s29
	s_add_u32 s25, s29, s99
	s_add_u32 m0, s25, 0
	s_nop 0
	global_load_lds_dwordx4 v224, s[0:1]
	s_add_u32 m0, s25, 4096
	s_nop 0
	global_load_lds_dwordx4 v225, s[0:1]
	s_add_u32 m0, s25, 8192
	s_nop 0
	global_load_lds_dwordx4 v226, s[0:1]
	s_add_u32 m0, s25, 12288
	s_nop 0
	global_load_lds_dwordx4 v227, s[0:1]
	s_add_u32 m0, s25, 16384
	s_nop 0
	global_load_lds_dwordx4 v228, s[2:3]
	s_add_u32 m0, s25, 20480
	s_nop 0
	global_load_lds_dwordx4 v229, s[2:3]
	s_add_u32 s0, s0, 64
	s_addc_u32 s1, s1, 0
	s_add_u32 s2, s2, 64
	s_addc_u32 s3, s3, 0
	s_add_u32 s98, s98, 1
	s_add_u32 s29, s29, 24576
	s_cmp_eq_u32 s29, 73728
	s_cselect_b32 s29, 0, s29
	s_add_u32 s25, s29, s99
	s_add_u32 m0, s25, 0
	s_nop 0
	global_load_lds_dwordx4 v224, s[0:1]
	s_add_u32 m0, s25, 4096
	s_nop 0
	global_load_lds_dwordx4 v225, s[0:1]
	s_add_u32 m0, s25, 8192
	s_nop 0
	global_load_lds_dwordx4 v226, s[0:1]
	s_add_u32 m0, s25, 12288
	s_nop 0
	global_load_lds_dwordx4 v227, s[0:1]
	s_add_u32 m0, s25, 16384
	s_nop 0
	global_load_lds_dwordx4 v228, s[2:3]
	s_add_u32 m0, s25, 20480
	s_nop 0
	global_load_lds_dwordx4 v229, s[2:3]
	s_add_u32 s0, s0, 64
	s_addc_u32 s1, s1, 0
	s_add_u32 s2, s2, 64
	s_addc_u32 s3, s3, 0
	s_add_u32 s98, s98, 1
	s_add_u32 s29, s29, 24576
	s_cmp_eq_u32 s29, 73728
	s_cselect_b32 s29, 0, s29
	v_mov_b32_e32 v0, 0
	v_mov_b32_e32 v1, 0
	v_mov_b32_e32 v2, 0
	v_mov_b32_e32 v3, 0
	v_mov_b32_e32 v4, 0
	v_mov_b32_e32 v5, 0
	v_mov_b32_e32 v6, 0
	v_mov_b32_e32 v7, 0
	v_mov_b32_e32 v8, 0
	v_mov_b32_e32 v9, 0
	v_mov_b32_e32 v10, 0
	v_mov_b32_e32 v11, 0
	v_mov_b32_e32 v12, 0
	v_mov_b32_e32 v13, 0
	v_mov_b32_e32 v14, 0
	v_mov_b32_e32 v15, 0
	v_mov_b32_e32 v16, 0
	v_mov_b32_e32 v17, 0
	v_mov_b32_e32 v18, 0
	v_mov_b32_e32 v19, 0
	v_mov_b32_e32 v20, 0
	v_mov_b32_e32 v21, 0
	v_mov_b32_e32 v22, 0
	v_mov_b32_e32 v23, 0
	v_mov_b32_e32 v24, 0
	v_mov_b32_e32 v25, 0
	v_mov_b32_e32 v26, 0
	v_mov_b32_e32 v27, 0
	v_mov_b32_e32 v28, 0
	v_mov_b32_e32 v29, 0
	v_mov_b32_e32 v30, 0
	v_mov_b32_e32 v31, 0
	v_mov_b32_e32 v32, 0
	v_mov_b32_e32 v33, 0
	v_mov_b32_e32 v34, 0
	v_mov_b32_e32 v35, 0
	v_mov_b32_e32 v36, 0
	v_mov_b32_e32 v37, 0
	v_mov_b32_e32 v38, 0
	v_mov_b32_e32 v39, 0
	v_mov_b32_e32 v40, 0
	v_mov_b32_e32 v41, 0
	v_mov_b32_e32 v42, 0
	v_mov_b32_e32 v43, 0
	v_mov_b32_e32 v44, 0
	v_mov_b32_e32 v45, 0
	v_mov_b32_e32 v46, 0
	v_mov_b32_e32 v47, 0
	v_mov_b32_e32 v48, 0
	v_mov_b32_e32 v49, 0
	v_mov_b32_e32 v50, 0
	v_mov_b32_e32 v51, 0
; #define LWRITE(S, buf) do { bf16_t* sA_ = sbase + (buf) * BUF; bf16_t* sB_ = sA_ + 256 * PITCH; \
;     _Pragma("unroll") for (int i_ = 0; i_ < 4; ++i_) *(u32x4*)(sA_ + (sr + i_ * 64) * PITCH + scv * 8) = ra[S][i_]; \
;     _Pragma("unroll") for (int i_ = 0; i_ < 2; ++i_) *(u32x4*)(sB_ + (sr + i_ * 64) * PITCH + scv * 8) = rb[S][i_]; } while (0)
; template <class Epi>
; DI void gemm_tile(char* smem, const bf16_t* __restrict__ A0, int lda0, int ksplit, const bf16_t* __restrict__ A1, int lda1,
;                   const bf16_t* __restrict__ Bt, int K, int row0, int col0, const Epi& epi, int tid) {
;     ...
;   f32x4 acc[8][4];
; #pragma unroll
;   for (int m = 0; m < 8; ++m)
; #pragma unroll
;     for (int n = 0; n < 4; ++n) acc[m][n] = (f32x4){0.f, 0.f, 0.f, 0.f};
;   u32x4 ra[2][4], rb[2][2];
;   const int nk = K / BK;
;   const int sr = tid >> 2, scv = tid & 3;
;     ...
;   __syncthreads();
;   {
;     const int last = nk - 1;
;     GLOAD(0, 0);
;     __builtin_amdgcn_sched_barrier(0);
;     GLOAD(1, 1);
;     __builtin_amdgcn_sched_barrier(0);
;     LWRITE(0, 0);
;     __builtin_amdgcn_sched_barrier(0);
;     GLOAD(0, (2 < last ? 2 : last));
;     __builtin_amdgcn_sched_barrier(0);
;     __syncthreads();
;     for (int kt = 0; kt < nk; kt += 2) {
;       LWRITE(1, 1);
;       __builtin_amdgcn_sched_barrier(0);
;       GLOAD(1, (kt + 3 < last ? kt + 3 : last));
;       __builtin_amdgcn_sched_barrier(0);
;       COMPUTE(0);
;       __syncthreads();
;       LWRITE(0, 0);
;       __builtin_amdgcn_sched_barrier(0);
;       GLOAD(0, (kt + 4 < last ? kt + 4 : last));
;       __builtin_amdgcn_sched_barrier(0);
;       COMPUTE(1);
;       __syncthreads();
;     }
	v_mov_b32_e32 v52, 0
	v_mov_b32_e32 v53, 0
	v_mov_b32_e32 v54, 0
	v_mov_b32_e32 v55, 0
	v_mov_b32_e32 v56, 0
	v_mov_b32_e32 v57, 0
	v_mov_b32_e32 v58, 0
	v_mov_b32_e32 v59, 0
	v_mov_b32_e32 v60, 0
	v_mov_b32_e32 v61, 0
	v_mov_b32_e32 v62, 0
	v_mov_b32_e32 v63, 0
	v_mov_b32_e32 v64, 0
	v_mov_b32_e32 v65, 0
	v_mov_b32_e32 v66, 0
	v_mov_b32_e32 v67, 0
	v_mov_b32_e32 v68, 0
	v_mov_b32_e32 v69, 0
	v_mov_b32_e32 v70, 0
	v_mov_b32_e32 v71, 0
	v_mov_b32_e32 v72, 0
	v_mov_b32_e32 v73, 0
	v_mov_b32_e32 v74, 0
	v_mov_b32_e32 v75, 0
	v_mov_b32_e32 v76, 0
	v_mov_b32_e32 v77, 0
	v_mov_b32_e32 v78, 0
	v_mov_b32_e32 v79, 0
	v_mov_b32_e32 v80, 0
	v_mov_b32_e32 v81, 0
	v_mov_b32_e32 v82, 0
	v_mov_b32_e32 v83, 0
	v_mov_b32_e32 v84, 0
	v_mov_b32_e32 v85, 0
	v_mov_b32_e32 v86, 0
	v_mov_b32_e32 v87, 0
	v_mov_b32_e32 v88, 0
	v_mov_b32_e32 v89, 0
	v_mov_b32_e32 v90, 0
	v_mov_b32_e32 v91, 0
	v_mov_b32_e32 v92, 0
	v_mov_b32_e32 v93, 0
	v_mov_b32_e32 v94, 0
	v_mov_b32_e32 v95, 0
	v_mov_b32_e32 v96, 0
	v_mov_b32_e32 v97, 0
	v_mov_b32_e32 v98, 0
	v_mov_b32_e32 v99, 0
	v_mov_b32_e32 v100, 0
	v_mov_b32_e32 v101, 0
	v_mov_b32_e32 v102, 0
	v_mov_b32_e32 v103, 0
	v_mov_b32_e32 v104, 0
	v_mov_b32_e32 v105, 0
	v_mov_b32_e32 v106, 0
	v_mov_b32_e32 v107, 0
	v_mov_b32_e32 v108, 0
	v_mov_b32_e32 v109, 0
	v_mov_b32_e32 v110, 0
	v_mov_b32_e32 v111, 0
	v_mov_b32_e32 v112, 0
	v_mov_b32_e32 v113, 0
	v_mov_b32_e32 v114, 0
	v_mov_b32_e32 v115, 0
	v_mov_b32_e32 v116, 0
	v_mov_b32_e32 v117, 0
	v_mov_b32_e32 v118, 0
	v_mov_b32_e32 v119, 0
	v_mov_b32_e32 v120, 0
	v_mov_b32_e32 v121, 0
	v_mov_b32_e32 v122, 0
	v_mov_b32_e32 v123, 0
	v_mov_b32_e32 v124, 0
	v_mov_b32_e32 v125, 0
	v_mov_b32_e32 v126, 0
	v_mov_b32_e32 v127, 0
	s_mov_b32 s31, 0
	s_mov_b32 s30, 24576
	s_waitcnt vmcnt(12)
	s_barrier
	ds_read_b128 v[128:131], v231 offset:0
	ds_read_b128 v[132:135], v231 offset:1024
	ds_read_b128 v[136:139], v231 offset:2048
	ds_read_b128 v[140:143], v231 offset:3072
	ds_read_b128 v[144:147], v230 offset:0
	ds_read_b128 v[148:151], v230 offset:1024
	ds_read_b128 v[152:155], v230 offset:2048
	ds_read_b128 v[156:159], v230 offset:3072
	ds_read_b128 v[160:163], v230 offset:4096
	ds_read_b128 v[164:167], v230 offset:5120
	ds_read_b128 v[168:171], v230 offset:6144
	ds_read_b128 v[172:175], v230 offset:7168
.Lg11_kloop:
	s_waitcnt vmcnt(6)
	s_waitcnt lgkmcnt(0)
	s_barrier
	v_add_u32_e32 v232, s30, v230
	v_add_u32_e32 v233, s30, v231
	s_add_u32 s25, s29, s99
	v_mfma_f32_16x16x32_bf16 v[0:3], v[128:131], v[144:147], v[0:3]
	v_mfma_f32_16x16x32_bf16 v[4:7], v[132:135], v[144:147], v[4:7]
	v_mfma_f32_16x16x32_bf16 v[8:11], v[136:139], v[144:147], v[8:11]
	v_mfma_f32_16x16x32_bf16 v[12:15], v[140:143], v[144:147], v[12:15]
	ds_read_b128 v[176:179], v233 offset:0
	ds_read_b128 v[180:183], v233 offset:1024
	s_add_u32 m0, s25, 0
	s_nop 0
	global_load_lds_dwordx4 v224, s[0:1]
	v_mfma_f32_16x16x32_bf16 v[16:19], v[128:131], v[148:151], v[16:19]
	v_mfma_f32_16x16x32_bf16 v[20:23], v[132:135], v[148:151], v[20:23]
	v_mfma_f32_16x16x32_bf16 v[24:27], v[136:139], v[148:151], v[24:27]
	v_mfma_f32_16x16x32_bf16 v[28:31], v[140:143], v[148:151], v[28:31]
	ds_read_b128 v[184:187], v233 offset:2048
	ds_read_b128 v[188:191], v233 offset:3072
	s_add_u32 m0, s25, 4096
	s_nop 0
	global_load_lds_dwordx4 v225, s[0:1]
	v_mfma_f32_16x16x32_bf16 v[32:35], v[128:131], v[152:155], v[32:35]
	v_mfma_f32_16x16x32_bf16 v[36:39], v[132:135], v[152:155], v[36:39]
	v_mfma_f32_16x16x32_bf16 v[40:43], v[136:139], v[152:155], v[40:43]
	v_mfma_f32_16x16x32_bf16 v[44:47], v[140:143], v[152:155], v[44:47]
	ds_read_b128 v[192:195], v232 offset:0
	ds_read_b128 v[196:199], v232 offset:1024
	s_add_u32 m0, s25, 8192
	s_nop 0
	global_load_lds_dwordx4 v226, s[0:1]
	v_mfma_f32_16x16x32_bf16 v[48:51], v[128:131], v[156:159], v[48:51]
	v_mfma_f32_16x16x32_bf16 v[52:55], v[132:135], v[156:159], v[52:55]
	v_mfma_f32_16x16x32_bf16 v[56:59], v[136:139], v[156:159], v[56:59]
	v_mfma_f32_16x16x32_bf16 v[60:63], v[140:143], v[156:159], v[60:63]
	ds_read_b128 v[200:203], v232 offset:2048
	ds_read_b128 v[204:207], v232 offset:3072
	s_add_u32 m0, s25, 12288
	s_nop 0
	global_load_lds_dwordx4 v227, s[0:1]
	v_mfma_f32_16x16x32_bf16 v[64:67], v[128:131], v[160:163], v[64:67]
	v_mfma_f32_16x16x32_bf16 v[68:71], v[132:135], v[160:163], v[68:71]
	v_mfma_f32_16x16x32_bf16 v[72:75], v[136:139], v[160:163], v[72:75]
	v_mfma_f32_16x16x32_bf16 v[76:79], v[140:143], v[160:163], v[76:79]
	ds_read_b128 v[208:211], v232 offset:4096
	s_add_u32 m0, s25, 16384
	s_nop 0
	global_load_lds_dwordx4 v228, s[2:3]
	v_mfma_f32_16x16x32_bf16 v[80:83], v[128:131], v[164:167], v[80:83]
	v_mfma_f32_16x16x32_bf16 v[84:87], v[132:135], v[164:167], v[84:87]
	v_mfma_f32_16x16x32_bf16 v[88:91], v[136:139], v[164:167], v[88:91]
	v_mfma_f32_16x16x32_bf16 v[92:95], v[140:143], v[164:167], v[92:95]
	ds_read_b128 v[212:215], v232 offset:5120
	s_add_u32 m0, s25, 20480
	s_nop 0
	global_load_lds_dwordx4 v229, s[2:3]
	v_mfma_f32_16x16x32_bf16 v[96:99], v[128:131], v[168:171], v[96:99]
	v_mfma_f32_16x16x32_bf16 v[100:103], v[132:135], v[168:171], v[100:103]
	v_mfma_f32_16x16x32_bf16 v[104:107], v[136:139], v[168:171], v[104:107]
	v_mfma_f32_16x16x32_bf16 v[108:111], v[140:143], v[168:171], v[108:111]
	ds_read_b128 v[216:219], v232 offset:6144
	s_add_u32 s0, s0, 64
	s_addc_u32 s1, s1, 0
	s_add_u32 s2, s2, 64
	s_addc_u32 s3, s3, 0
	s_add_u32 s98, s98, 1
	s_add_u32 s29, s29, 24576
	s_cmp_eq_u32 s29, 73728
	s_cselect_b32 s29, 0, s29
	s_add_u32 s30, s30, 24576
	s_cmp_eq_u32 s30, 73728
	s_cselect_b32 s30, 0, s30
	v_mfma_f32_16x16x32_bf16 v[112:115], v[128:131], v[172:175], v[112:115]
	v_mfma_f32_16x16x32_bf16 v[116:119], v[132:135], v[172:175], v[116:119]
	v_mfma_f32_16x16x32_bf16 v[120:123], v[136:139], v[172:175], v[120:123]
	v_mfma_f32_16x16x32_bf16 v[124:127], v[140:143], v[172:175], v[124:127]
	ds_read_b128 v[220:223], v232 offset:7168
	s_waitcnt vmcnt(6)
	s_waitcnt lgkmcnt(0)
	s_barrier
; #define LWRITE(S, buf) do { bf16_t* sA_ = sbase + (buf) * BUF; bf16_t* sB_ = sA_ + 256 * PITCH; \
;     _Pragma("unroll") for (int i_ = 0; i_ < 4; ++i_) *(u32x4*)(sA_ + (sr + i_ * 64) * PITCH + scv * 8) = ra[S][i_]; \
;     _Pragma("unroll") for (int i_ = 0; i_ < 2; ++i_) *(u32x4*)(sB_ + (sr + i_ * 64) * PITCH + scv * 8) = rb[S][i_]; } while (0)
; template <class Epi>
; DI void gemm_tile(char* smem, const bf16_t* __restrict__ A0, int lda0, int ksplit, const bf16_t* __restrict__ A1, int lda1,
;                   const bf16_t* __restrict__ Bt, int K, int row0, int col0, const Epi& epi, int tid) {
;     ...
;   __syncthreads();
;   {
;     const int last = nk - 1;
;     GLOAD(0, 0);
;     __builtin_amdgcn_sched_barrier(0);
;     GLOAD(1, 1);
;     __builtin_amdgcn_sched_barrier(0);
;     LWRITE(0, 0);
;     __builtin_amdgcn_sched_barrier(0);
;     GLOAD(0, (2 < last ? 2 : last));
;     __builtin_amdgcn_sched_barrier(0);
;     __syncthreads();
;     for (int kt = 0; kt < nk; kt += 2) {
;       LWRITE(1, 1);
;       __builtin_amdgcn_sched_barrier(0);
;       GLOAD(1, (kt + 3 < last ? kt + 3 : last));
;       __builtin_amdgcn_sched_barrier(0);
;       COMPUTE(0);
;       __syncthreads();
;       LWRITE(0, 0);
;       __builtin_amdgcn_sched_barrier(0);
;       GLOAD(0, (kt + 4 < last ? kt + 4 : last));
;       __builtin_amdgcn_sched_barrier(0);
;       COMPUTE(1);
;       __syncthreads();
;     }
	v_add_u32_e32 v232, s30, v230
	v_add_u32_e32 v233, s30, v231
	s_add_u32 s25, s29, s99
	v_mfma_f32_16x16x32_bf16 v[0:3], v[176:179], v[192:195], v[0:3]
	v_mfma_f32_16x16x32_bf16 v[4:7], v[180:183], v[192:195], v[4:7]
	v_mfma_f32_16x16x32_bf16 v[8:11], v[184:187], v[192:195], v[8:11]
	v_mfma_f32_16x16x32_bf16 v[12:15], v[188:191], v[192:195], v[12:15]
	ds_read_b128 v[128:131], v233 offset:0
	ds_read_b128 v[132:135], v233 offset:1024
	s_add_u32 m0, s25, 0
	s_nop 0
	global_load_lds_dwordx4 v224, s[0:1]
	v_mfma_f32_16x16x32_bf16 v[16:19], v[176:179], v[196:199], v[16:19]
	v_mfma_f32_16x16x32_bf16 v[20:23], v[180:183], v[196:199], v[20:23]
	v_mfma_f32_16x16x32_bf16 v[24:27], v[184:187], v[196:199], v[24:27]
	v_mfma_f32_16x16x32_bf16 v[28:31], v[188:191], v[196:199], v[28:31]
	ds_read_b128 v[136:139], v233 offset:2048
	ds_read_b128 v[140:143], v233 offset:3072
	s_add_u32 m0, s25, 4096
	s_nop 0
	global_load_lds_dwordx4 v225, s[0:1]
	v_mfma_f32_16x16x32_bf16 v[32:35], v[176:179], v[200:203], v[32:35]
	v_mfma_f32_16x16x32_bf16 v[36:39], v[180:183], v[200:203], v[36:39]
	v_mfma_f32_16x16x32_bf16 v[40:43], v[184:187], v[200:203], v[40:43]
	v_mfma_f32_16x16x32_bf16 v[44:47], v[188:191], v[200:203], v[44:47]
	ds_read_b128 v[144:147], v232 offset:0
	ds_read_b128 v[148:151], v232 offset:1024
	s_add_u32 m0, s25, 8192
	s_nop 0
	global_load_lds_dwordx4 v226, s[0:1]
	v_mfma_f32_16x16x32_bf16 v[48:51], v[176:179], v[204:207], v[48:51]
	v_mfma_f32_16x16x32_bf16 v[52:55], v[180:183], v[204:207], v[52:55]
	v_mfma_f32_16x16x32_bf16 v[56:59], v[184:187], v[204:207], v[56:59]
	v_mfma_f32_16x16x32_bf16 v[60:63], v[188:191], v[204:207], v[60:63]
	ds_read_b128 v[152:155], v232 offset:2048
	ds_read_b128 v[156:159], v232 offset:3072
	s_add_u32 m0, s25, 12288
	s_nop 0
	global_load_lds_dwordx4 v227, s[0:1]
	v_mfma_f32_16x16x32_bf16 v[64:67], v[176:179], v[208:211], v[64:67]
	v_mfma_f32_16x16x32_bf16 v[68:71], v[180:183], v[208:211], v[68:71]
	v_mfma_f32_16x16x32_bf16 v[72:75], v[184:187], v[208:211], v[72:75]
	v_mfma_f32_16x16x32_bf16 v[76:79], v[188:191], v[208:211], v[76:79]
	ds_read_b128 v[160:163], v232 offset:4096
	s_add_u32 m0, s25, 16384
	s_nop 0
	global_load_lds_dwordx4 v228, s[2:3]
	v_mfma_f32_16x16x32_bf16 v[80:83], v[176:179], v[212:215], v[80:83]
	v_mfma_f32_16x16x32_bf16 v[84:87], v[180:183], v[212:215], v[84:87]
	v_mfma_f32_16x16x32_bf16 v[88:91], v[184:187], v[212:215], v[88:91]
	v_mfma_f32_16x16x32_bf16 v[92:95], v[188:191], v[212:215], v[92:95]
	ds_read_b128 v[164:167], v232 offset:5120
	s_add_u32 m0, s25, 20480
	s_nop 0
	global_load_lds_dwordx4 v229, s[2:3]
	v_mfma_f32_16x16x32_bf16 v[96:99], v[176:179], v[216:219], v[96:99]
	v_mfma_f32_16x16x32_bf16 v[100:103], v[180:183], v[216:219], v[100:103]
	v_mfma_f32_16x16x32_bf16 v[104:107], v[184:187], v[216:219], v[104:107]
	v_mfma_f32_16x16x32_bf16 v[108:111], v[188:191], v[216:219], v[108:111]
	ds_read_b128 v[168:171], v232 offset:6144
	s_add_u32 s0, s0, 64
	s_addc_u32 s1, s1, 0
	s_add_u32 s2, s2, 64
	s_addc_u32 s3, s3, 0
	s_add_u32 s98, s98, 1
	s_add_u32 s29, s29, 24576
	s_cmp_eq_u32 s29, 73728
	s_cselect_b32 s29, 0, s29
	s_add_u32 s30, s30, 24576
	s_cmp_eq_u32 s30, 73728
	s_cselect_b32 s30, 0, s30
	v_mfma_f32_16x16x32_bf16 v[112:115], v[176:179], v[220:223], v[112:115]
	v_mfma_f32_16x16x32_bf16 v[116:119], v[180:183], v[220:223], v[116:119]
	v_mfma_f32_16x16x32_bf16 v[120:123], v[184:187], v[220:223], v[120:123]
	v_mfma_f32_16x16x32_bf16 v[124:127], v[188:191], v[220:223], v[124:127]
	ds_read_b128 v[172:175], v232 offset:7168
	s_add_u32 s31, s31, 2
	s_cmp_lt_u32 s31, 28
	s_cbranch_scc1 .Lg11_kloop
	s_waitcnt vmcnt(6)
	s_waitcnt lgkmcnt(0)
	s_barrier
	v_add_u32_e32 v232, s30, v230
	v_add_u32_e32 v233, s30, v231
	s_add_u32 s25, s29, s99
	v_mfma_f32_16x16x32_bf16 v[0:3], v[128:131], v[144:147], v[0:3]
	v_mfma_f32_16x16x32_bf16 v[4:7], v[132:135], v[144:147], v[4:7]
	v_mfma_f32_16x16x32_bf16 v[8:11], v[136:139], v[144:147], v[8:11]
	v_mfma_f32_16x16x32_bf16 v[12:15], v[140:143], v[144:147], v[12:15]
	ds_read_b128 v[176:179], v233 offset:0
	ds_read_b128 v[180:183], v233 offset:1024
	s_add_u32 m0, s25, 0
	s_nop 0
	global_load_lds_dwordx4 v224, s[0:1]
	v_mfma_f32_16x16x32_bf16 v[16:19], v[128:131], v[148:151], v[16:19]
	v_mfma_f32_16x16x32_bf16 v[20:23], v[132:135], v[148:151], v[20:23]
	v_mfma_f32_16x16x32_bf16 v[24:27], v[136:139], v[148:151], v[24:27]
	v_mfma_f32_16x16x32_bf16 v[28:31], v[140:143], v[148:151], v[28:31]
	ds_read_b128 v[184:187], v233 offset:2048
	ds_read_b128 v[188:191], v233 offset:3072
	s_add_u32 m0, s25, 4096
	s_nop 0
	global_load_lds_dwordx4 v225, s[0:1]
	v_mfma_f32_16x16x32_bf16 v[32:35], v[128:131], v[152:155], v[32:35]
	v_mfma_f32_16x16x32_bf16 v[36:39], v[132:135], v[152:155], v[36:39]
	v_mfma_f32_16x16x32_bf16 v[40:43], v[136:139], v[152:155], v[40:43]
	v_mfma_f32_16x16x32_bf16 v[44:47], v[140:143], v[152:155], v[44:47]
	ds_read_b128 v[192:195], v232 offset:0
	ds_read_b128 v[196:199], v232 offset:1024
	s_add_u32 m0, s25, 8192
	s_nop 0
	global_load_lds_dwordx4 v226, s[0:1]
	v_mfma_f32_16x16x32_bf16 v[48:51], v[128:131], v[156:159], v[48:51]
	v_mfma_f32_16x16x32_bf16 v[52:55], v[132:135], v[156:159], v[52:55]
	v_mfma_f32_16x16x32_bf16 v[56:59], v[136:139], v[156:159], v[56:59]
	v_mfma_f32_16x16x32_bf16 v[60:63], v[140:143], v[156:159], v[60:63]
	ds_read_b128 v[200:203], v232 offset:2048
	ds_read_b128 v[204:207], v232 offset:3072
	s_add_u32 m0, s25, 12288
	s_nop 0
	global_load_lds_dwordx4 v227, s[0:1]
	v_mfma_f32_16x16x32_bf16 v[64:67], v[128:131], v[160:163], v[64:67]
	v_mfma_f32_16x16x32_bf16 v[68:71], v[132:135], v[160:163], v[68:71]
	v_mfma_f32_16x16x32_bf16 v[72:75], v[136:139], v[160:163], v[72:75]
; #define LWRITE(S, buf) do { bf16_t* sA_ = sbase + (buf) * BUF; bf16_t* sB_ = sA_ + 256 * PITCH; \
;     _Pragma("unroll") for (int i_ = 0; i_ < 4; ++i_) *(u32x4*)(sA_ + (sr + i_ * 64) * PITCH + scv * 8) = ra[S][i_]; \
;     _Pragma("unroll") for (int i_ = 0; i_ < 2; ++i_) *(u32x4*)(sB_ + (sr + i_ * 64) * PITCH + scv * 8) = rb[S][i_]; } while (0)
; template <class Epi>
; DI void gemm_tile(char* smem, const bf16_t* __restrict__ A0, int lda0, int ksplit, const bf16_t* __restrict__ A1, int lda1,
;                   const bf16_t* __restrict__ Bt, int K, int row0, int col0, const Epi& epi, int tid) {
;     ...
;   __syncthreads();
;   {
;     const int last = nk - 1;
;     GLOAD(0, 0);
;     __builtin_amdgcn_sched_barrier(0);
;     GLOAD(1, 1);
;     __builtin_amdgcn_sched_barrier(0);
;     LWRITE(0, 0);
;     __builtin_amdgcn_sched_barrier(0);
;     GLOAD(0, (2 < last ? 2 : last));
;     __builtin_amdgcn_sched_barrier(0);
;     __syncthreads();
;     for (int kt = 0; kt < nk; kt += 2) {
;       LWRITE(1, 1);
;       __builtin_amdgcn_sched_barrier(0);
;       GLOAD(1, (kt + 3 < last ? kt + 3 : last));
;       __builtin_amdgcn_sched_barrier(0);
;       COMPUTE(0);
;       __syncthreads();
;       LWRITE(0, 0);
;       __builtin_amdgcn_sched_barrier(0);
;       GLOAD(0, (kt + 4 < last ? kt + 4 : last));
;       __builtin_amdgcn_sched_barrier(0);
;       COMPUTE(1);
;       __syncthreads();
;     }
	v_mfma_f32_16x16x32_bf16 v[76:79], v[140:143], v[160:163], v[76:79]
	ds_read_b128 v[208:211], v232 offset:4096
	s_add_u32 m0, s25, 16384
	s_nop 0
	global_load_lds_dwordx4 v228, s[2:3]
	v_mfma_f32_16x16x32_bf16 v[80:83], v[128:131], v[164:167], v[80:83]
	v_mfma_f32_16x16x32_bf16 v[84:87], v[132:135], v[164:167], v[84:87]
	v_mfma_f32_16x16x32_bf16 v[88:91], v[136:139], v[164:167], v[88:91]
	v_mfma_f32_16x16x32_bf16 v[92:95], v[140:143], v[164:167], v[92:95]
	ds_read_b128 v[212:215], v232 offset:5120
	s_add_u32 m0, s25, 20480
	s_nop 0
	global_load_lds_dwordx4 v229, s[2:3]
	v_mfma_f32_16x16x32_bf16 v[96:99], v[128:131], v[168:171], v[96:99]
	v_mfma_f32_16x16x32_bf16 v[100:103], v[132:135], v[168:171], v[100:103]
	v_mfma_f32_16x16x32_bf16 v[104:107], v[136:139], v[168:171], v[104:107]
	v_mfma_f32_16x16x32_bf16 v[108:111], v[140:143], v[168:171], v[108:111]
	ds_read_b128 v[216:219], v232 offset:6144
	s_add_u32 s0, s0, 64
	s_addc_u32 s1, s1, 0
	s_add_u32 s2, s2, 64
	s_addc_u32 s3, s3, 0
	s_add_u32 s98, s98, 1
	s_add_u32 s29, s29, 24576
	s_cmp_eq_u32 s29, 73728
	s_cselect_b32 s29, 0, s29
	s_add_u32 s30, s30, 24576
	s_cmp_eq_u32 s30, 73728
	s_cselect_b32 s30, 0, s30
	v_mfma_f32_16x16x32_bf16 v[112:115], v[128:131], v[172:175], v[112:115]
	v_mfma_f32_16x16x32_bf16 v[116:119], v[132:135], v[172:175], v[116:119]
	v_mfma_f32_16x16x32_bf16 v[120:123], v[136:139], v[172:175], v[120:123]
	v_mfma_f32_16x16x32_bf16 v[124:127], v[140:143], v[172:175], v[124:127]
	ds_read_b128 v[220:223], v232 offset:7168
	s_waitcnt vmcnt(6)
	s_waitcnt lgkmcnt(0)
	s_barrier
	v_add_u32_e32 v232, s30, v230
	v_add_u32_e32 v233, s30, v231
	v_mfma_f32_16x16x32_bf16 v[0:3], v[176:179], v[192:195], v[0:3]
	v_mfma_f32_16x16x32_bf16 v[4:7], v[180:183], v[192:195], v[4:7]
	v_mfma_f32_16x16x32_bf16 v[8:11], v[184:187], v[192:195], v[8:11]
	v_mfma_f32_16x16x32_bf16 v[12:15], v[188:191], v[192:195], v[12:15]
	ds_read_b128 v[128:131], v233 offset:0
	ds_read_b128 v[132:135], v233 offset:1024
	v_mfma_f32_16x16x32_bf16 v[16:19], v[176:179], v[196:199], v[16:19]
	v_mfma_f32_16x16x32_bf16 v[20:23], v[180:183], v[196:199], v[20:23]
	v_mfma_f32_16x16x32_bf16 v[24:27], v[184:187], v[196:199], v[24:27]
	v_mfma_f32_16x16x32_bf16 v[28:31], v[188:191], v[196:199], v[28:31]
	ds_read_b128 v[136:139], v233 offset:2048
	ds_read_b128 v[140:143], v233 offset:3072
	v_mfma_f32_16x16x32_bf16 v[32:35], v[176:179], v[200:203], v[32:35]
	v_mfma_f32_16x16x32_bf16 v[36:39], v[180:183], v[200:203], v[36:39]
	v_mfma_f32_16x16x32_bf16 v[40:43], v[184:187], v[200:203], v[40:43]
	v_mfma_f32_16x16x32_bf16 v[44:47], v[188:191], v[200:203], v[44:47]
	ds_read_b128 v[144:147], v232 offset:0
	ds_read_b128 v[148:151], v232 offset:1024
	v_mfma_f32_16x16x32_bf16 v[48:51], v[176:179], v[204:207], v[48:51]
	v_mfma_f32_16x16x32_bf16 v[52:55], v[180:183], v[204:207], v[52:55]
	v_mfma_f32_16x16x32_bf16 v[56:59], v[184:187], v[204:207], v[56:59]
	v_mfma_f32_16x16x32_bf16 v[60:63], v[188:191], v[204:207], v[60:63]
	ds_read_b128 v[152:155], v232 offset:2048
	ds_read_b128 v[156:159], v232 offset:3072
	v_mfma_f32_16x16x32_bf16 v[64:67], v[176:179], v[208:211], v[64:67]
	v_mfma_f32_16x16x32_bf16 v[68:71], v[180:183], v[208:211], v[68:71]
	v_mfma_f32_16x16x32_bf16 v[72:75], v[184:187], v[208:211], v[72:75]
	v_mfma_f32_16x16x32_bf16 v[76:79], v[188:191], v[208:211], v[76:79]
	ds_read_b128 v[160:163], v232 offset:4096
	v_mfma_f32_16x16x32_bf16 v[80:83], v[176:179], v[212:215], v[80:83]
	v_mfma_f32_16x16x32_bf16 v[84:87], v[180:183], v[212:215], v[84:87]
	v_mfma_f32_16x16x32_bf16 v[88:91], v[184:187], v[212:215], v[88:91]
	v_mfma_f32_16x16x32_bf16 v[92:95], v[188:191], v[212:215], v[92:95]
	ds_read_b128 v[164:167], v232 offset:5120
	v_mfma_f32_16x16x32_bf16 v[96:99], v[176:179], v[216:219], v[96:99]
	v_mfma_f32_16x16x32_bf16 v[100:103], v[180:183], v[216:219], v[100:103]
	v_mfma_f32_16x16x32_bf16 v[104:107], v[184:187], v[216:219], v[104:107]
	v_mfma_f32_16x16x32_bf16 v[108:111], v[188:191], v[216:219], v[108:111]
	ds_read_b128 v[168:171], v232 offset:6144
	s_add_u32 s30, s30, 24576
	s_cmp_eq_u32 s30, 73728
	s_cselect_b32 s30, 0, s30
	v_mfma_f32_16x16x32_bf16 v[112:115], v[176:179], v[220:223], v[112:115]
	v_mfma_f32_16x16x32_bf16 v[116:119], v[180:183], v[220:223], v[116:119]
	v_mfma_f32_16x16x32_bf16 v[120:123], v[184:187], v[220:223], v[120:123]
	v_mfma_f32_16x16x32_bf16 v[124:127], v[188:191], v[220:223], v[124:127]
	ds_read_b128 v[172:175], v232 offset:7168
	s_waitcnt vmcnt(0)
	s_waitcnt lgkmcnt(0)
	s_barrier
; #define LWRITE(S, buf) do { bf16_t* sA_ = sbase + (buf) * BUF; bf16_t* sB_ = sA_ + 256 * PITCH; \
;     _Pragma("unroll") for (int i_ = 0; i_ < 4; ++i_) *(u32x4*)(sA_ + (sr + i_ * 64) * PITCH + scv * 8) = ra[S][i_]; \
;     _Pragma("unroll") for (int i_ = 0; i_ < 2; ++i_) *(u32x4*)(sB_ + (sr + i_ * 64) * PITCH + scv * 8) = rb[S][i_]; } while (0)
; template <class Epi>
; DI void gemm_tile(char* smem, const bf16_t* __restrict__ A0, int lda0, int ksplit, const bf16_t* __restrict__ A1, int lda1,
;                   const bf16_t* __restrict__ Bt, int K, int row0, int col0, const Epi& epi, int tid) {
;     ...
;   __syncthreads();
;   {
;     const int last = nk - 1;
;     GLOAD(0, 0);
;     __builtin_amdgcn_sched_barrier(0);
;     GLOAD(1, 1);
;     __builtin_amdgcn_sched_barrier(0);
;     LWRITE(0, 0);
;     __builtin_amdgcn_sched_barrier(0);
;     GLOAD(0, (2 < last ? 2 : last));
;     __builtin_amdgcn_sched_barrier(0);
;     __syncthreads();
;     for (int kt = 0; kt < nk; kt += 2) {
;       LWRITE(1, 1);
;       __builtin_amdgcn_sched_barrier(0);
;       GLOAD(1, (kt + 3 < last ? kt + 3 : last));
;       __builtin_amdgcn_sched_barrier(0);
;       COMPUTE(0);
;       __syncthreads();
;       LWRITE(0, 0);
;       __builtin_amdgcn_sched_barrier(0);
;       GLOAD(0, (kt + 4 < last ? kt + 4 : last));
;       __builtin_amdgcn_sched_barrier(0);
;       COMPUTE(1);
;       __syncthreads();
;     }
	v_add_u32_e32 v232, s30, v230
	v_add_u32_e32 v233, s30, v231
	v_mfma_f32_16x16x32_bf16 v[0:3], v[128:131], v[144:147], v[0:3]
	v_mfma_f32_16x16x32_bf16 v[4:7], v[132:135], v[144:147], v[4:7]
	v_mfma_f32_16x16x32_bf16 v[8:11], v[136:139], v[144:147], v[8:11]
	v_mfma_f32_16x16x32_bf16 v[12:15], v[140:143], v[144:147], v[12:15]
	ds_read_b128 v[176:179], v233 offset:0
	ds_read_b128 v[180:183], v233 offset:1024
	v_mfma_f32_16x16x32_bf16 v[16:19], v[128:131], v[148:151], v[16:19]
	v_mfma_f32_16x16x32_bf16 v[20:23], v[132:135], v[148:151], v[20:23]
	v_mfma_f32_16x16x32_bf16 v[24:27], v[136:139], v[148:151], v[24:27]
	v_mfma_f32_16x16x32_bf16 v[28:31], v[140:143], v[148:151], v[28:31]
	ds_read_b128 v[184:187], v233 offset:2048
	ds_read_b128 v[188:191], v233 offset:3072
	v_mfma_f32_16x16x32_bf16 v[32:35], v[128:131], v[152:155], v[32:35]
	v_mfma_f32_16x16x32_bf16 v[36:39], v[132:135], v[152:155], v[36:39]
	v_mfma_f32_16x16x32_bf16 v[40:43], v[136:139], v[152:155], v[40:43]
	v_mfma_f32_16x16x32_bf16 v[44:47], v[140:143], v[152:155], v[44:47]
	ds_read_b128 v[192:195], v232 offset:0
	ds_read_b128 v[196:199], v232 offset:1024
	v_mfma_f32_16x16x32_bf16 v[48:51], v[128:131], v[156:159], v[48:51]
	v_mfma_f32_16x16x32_bf16 v[52:55], v[132:135], v[156:159], v[52:55]
	v_mfma_f32_16x16x32_bf16 v[56:59], v[136:139], v[156:159], v[56:59]
	v_mfma_f32_16x16x32_bf16 v[60:63], v[140:143], v[156:159], v[60:63]
	ds_read_b128 v[200:203], v232 offset:2048
	ds_read_b128 v[204:207], v232 offset:3072
	v_mfma_f32_16x16x32_bf16 v[64:67], v[128:131], v[160:163], v[64:67]
	v_mfma_f32_16x16x32_bf16 v[68:71], v[132:135], v[160:163], v[68:71]
	v_mfma_f32_16x16x32_bf16 v[72:75], v[136:139], v[160:163], v[72:75]
	v_mfma_f32_16x16x32_bf16 v[76:79], v[140:143], v[160:163], v[76:79]
	ds_read_b128 v[208:211], v232 offset:4096
	v_mfma_f32_16x16x32_bf16 v[80:83], v[128:131], v[164:167], v[80:83]
	v_mfma_f32_16x16x32_bf16 v[84:87], v[132:135], v[164:167], v[84:87]
	v_mfma_f32_16x16x32_bf16 v[88:91], v[136:139], v[164:167], v[88:91]
	v_mfma_f32_16x16x32_bf16 v[92:95], v[140:143], v[164:167], v[92:95]
	ds_read_b128 v[212:215], v232 offset:5120
	v_mfma_f32_16x16x32_bf16 v[96:99], v[128:131], v[168:171], v[96:99]
	v_mfma_f32_16x16x32_bf16 v[100:103], v[132:135], v[168:171], v[100:103]
	v_mfma_f32_16x16x32_bf16 v[104:107], v[136:139], v[168:171], v[104:107]
	v_mfma_f32_16x16x32_bf16 v[108:111], v[140:143], v[168:171], v[108:111]
	ds_read_b128 v[216:219], v232 offset:6144
	s_add_u32 s30, s30, 24576
	s_cmp_eq_u32 s30, 73728
	s_cselect_b32 s30, 0, s30
	v_mfma_f32_16x16x32_bf16 v[112:115], v[128:131], v[172:175], v[112:115]
	v_mfma_f32_16x16x32_bf16 v[116:119], v[132:135], v[172:175], v[116:119]
	v_mfma_f32_16x16x32_bf16 v[120:123], v[136:139], v[172:175], v[120:123]
	v_mfma_f32_16x16x32_bf16 v[124:127], v[140:143], v[172:175], v[124:127]
	ds_read_b128 v[220:223], v232 offset:7168
	s_waitcnt lgkmcnt(0)
	s_barrier
	v_mfma_f32_16x16x32_bf16 v[0:3], v[176:179], v[192:195], v[0:3]
	v_mfma_f32_16x16x32_bf16 v[4:7], v[180:183], v[192:195], v[4:7]
	v_mfma_f32_16x16x32_bf16 v[8:11], v[184:187], v[192:195], v[8:11]
	v_mfma_f32_16x16x32_bf16 v[12:15], v[188:191], v[192:195], v[12:15]
	v_mfma_f32_16x16x32_bf16 v[16:19], v[176:179], v[196:199], v[16:19]
	v_mfma_f32_16x16x32_bf16 v[20:23], v[180:183], v[196:199], v[20:23]
	v_mfma_f32_16x16x32_bf16 v[24:27], v[184:187], v[196:199], v[24:27]
	v_mfma_f32_16x16x32_bf16 v[28:31], v[188:191], v[196:199], v[28:31]
	v_mfma_f32_16x16x32_bf16 v[32:35], v[176:179], v[200:203], v[32:35]
	v_mfma_f32_16x16x32_bf16 v[36:39], v[180:183], v[200:203], v[36:39]
	v_mfma_f32_16x16x32_bf16 v[40:43], v[184:187], v[200:203], v[40:43]
	v_mfma_f32_16x16x32_bf16 v[44:47], v[188:191], v[200:203], v[44:47]
	v_mfma_f32_16x16x32_bf16 v[48:51], v[176:179], v[204:207], v[48:51]
	v_mfma_f32_16x16x32_bf16 v[52:55], v[180:183], v[204:207], v[52:55]
	v_mfma_f32_16x16x32_bf16 v[56:59], v[184:187], v[204:207], v[56:59]
	v_mfma_f32_16x16x32_bf16 v[60:63], v[188:191], v[204:207], v[60:63]
	v_mfma_f32_16x16x32_bf16 v[64:67], v[176:179], v[208:211], v[64:67]
	v_mfma_f32_16x16x32_bf16 v[68:71], v[180:183], v[208:211], v[68:71]
	v_mfma_f32_16x16x32_bf16 v[72:75], v[184:187], v[208:211], v[72:75]
	v_mfma_f32_16x16x32_bf16 v[76:79], v[188:191], v[208:211], v[76:79]
	v_mfma_f32_16x16x32_bf16 v[80:83], v[176:179], v[212:215], v[80:83]
	v_mfma_f32_16x16x32_bf16 v[84:87], v[180:183], v[212:215], v[84:87]
	v_mfma_f32_16x16x32_bf16 v[88:91], v[184:187], v[212:215], v[88:91]
	v_mfma_f32_16x16x32_bf16 v[92:95], v[188:191], v[212:215], v[92:95]
	v_mfma_f32_16x16x32_bf16 v[96:99], v[176:179], v[216:219], v[96:99]
	v_mfma_f32_16x16x32_bf16 v[100:103], v[180:183], v[216:219], v[100:103]
	v_mfma_f32_16x16x32_bf16 v[104:107], v[184:187], v[216:219], v[104:107]
	v_mfma_f32_16x16x32_bf16 v[108:111], v[188:191], v[216:219], v[108:111]
	v_mfma_f32_16x16x32_bf16 v[112:115], v[176:179], v[220:223], v[112:115]
	v_mfma_f32_16x16x32_bf16 v[116:119], v[180:183], v[220:223], v[116:119]
	v_mfma_f32_16x16x32_bf16 v[120:123], v[184:187], v[220:223], v[120:123]
	v_mfma_f32_16x16x32_bf16 v[124:127], v[188:191], v[220:223], v[124:127]
	s_branch .Lg11_epi
; DI unsigned pack2(float lo, float hi) { const f32x2c v = {lo, hi}; return __builtin_bit_cast(unsigned, __builtin_convertvector(v, bf16x2c)); }
; #define PH(k) case k: if (ONLY_PHASE >= 0 && ONLY_PHASE != k) break;
; template <class Epi>
; DI void gemm_tile(char* smem, const bf16_t* __restrict__ A0, int lda0, int ksplit, const bf16_t* __restrict__ A1, int lda1,
;                   const bf16_t* __restrict__ Bt, int K, int row0, int col0, const Epi& epi, int tid) {
;     ...
; #pragma unroll
;   for (int m = 0; m < 8; ++m)
; #pragma unroll
;     for (int n = 0; n < 4; ++n) epi(row0 + wr * 128 + m * 16 + fr, col0 + wc * 64 + n * 16 + fq * 4, acc[m][n]);
; }
; DI void st_bf16x4(bf16_t* o, f32x4 v) { u32x2 q; q.x = pack2(v[0], v[1]); q.y = pack2(v[2], v[3]); *(u32x2*)o = q; }
;   DI void operator()(int row, int col, f32x4 v) const {
;     if (col < n0) st_bf16x4(o0 + (size_t)row * ld0 + col, v);
;     else { const int c = col - n0; if (c < n1) st_bf16x4(o1 + (size_t)row * ld1 + c, v); }
;   }
; template <int ph> DI void run_phase(const Ctx& c, char* smem) {
;     ...
;     PH(11) gemm_phase(smem, XN, 1024, 1 << 30, XN, 1024, (const bf16_t*)(ws + OFF_WCDIN), 1024, 21,
;                         EpiSplit{(bf16_t*)(ws + OFF_S5U), 512, 512, (bf16_t*)(ws + OFF_MLRAW), 2080, 2080}, TIDX); break;
.Lg11_epi:
	s_nop 7
	s_nop 7
	s_cmpk_ge_u32 s27, 512
	s_cbranch_scc1 .Lg11_eo1
	s_mul_i32 s26, s28, 1024
	s_lshl_b32 s25, s27, 1
	s_add_u32 s26, s26, s25
	s_add_u32 s26, s26, 0x7800000
	s_add_u32 s4, s92, s26
	s_addc_u32 s5, s93, 0
	v_cvt_pk_bf16_f32 v128, v0, v1
	v_cvt_pk_bf16_f32 v129, v2, v3
	global_store_dwordx2 v234, v[128:129], s[4:5] offset:0
	v_cvt_pk_bf16_f32 v130, v4, v5
	v_cvt_pk_bf16_f32 v131, v6, v7
	global_store_dwordx2 v234, v[130:131], s[4:5] offset:32
	v_cvt_pk_bf16_f32 v132, v8, v9
	v_cvt_pk_bf16_f32 v133, v10, v11
	global_store_dwordx2 v234, v[132:133], s[4:5] offset:64
	v_cvt_pk_bf16_f32 v134, v12, v13
	v_cvt_pk_bf16_f32 v135, v14, v15
	global_store_dwordx2 v234, v[134:135], s[4:5] offset:96
	s_add_u32 s4, s4, 0x4000
	s_addc_u32 s5, s5, 0
	v_cvt_pk_bf16_f32 v136, v16, v17
	v_cvt_pk_bf16_f32 v137, v18, v19
	global_store_dwordx2 v234, v[136:137], s[4:5] offset:0
	v_cvt_pk_bf16_f32 v138, v20, v21
	v_cvt_pk_bf16_f32 v139, v22, v23
	global_store_dwordx2 v234, v[138:139], s[4:5] offset:32
	v_cvt_pk_bf16_f32 v140, v24, v25
	v_cvt_pk_bf16_f32 v141, v26, v27
	global_store_dwordx2 v234, v[140:141], s[4:5] offset:64
	v_cvt_pk_bf16_f32 v142, v28, v29
	v_cvt_pk_bf16_f32 v143, v30, v31
	global_store_dwordx2 v234, v[142:143], s[4:5] offset:96
	s_add_u32 s4, s4, 0x4000
	s_addc_u32 s5, s5, 0
	v_cvt_pk_bf16_f32 v144, v32, v33
	v_cvt_pk_bf16_f32 v145, v34, v35
	global_store_dwordx2 v234, v[144:145], s[4:5] offset:0
	v_cvt_pk_bf16_f32 v146, v36, v37
	v_cvt_pk_bf16_f32 v147, v38, v39
	global_store_dwordx2 v234, v[146:147], s[4:5] offset:32
	v_cvt_pk_bf16_f32 v148, v40, v41
	v_cvt_pk_bf16_f32 v149, v42, v43
	global_store_dwordx2 v234, v[148:149], s[4:5] offset:64
	v_cvt_pk_bf16_f32 v150, v44, v45
	v_cvt_pk_bf16_f32 v151, v46, v47
	global_store_dwordx2 v234, v[150:151], s[4:5] offset:96
	s_add_u32 s4, s4, 0x4000
	s_addc_u32 s5, s5, 0
	v_cvt_pk_bf16_f32 v152, v48, v49
	v_cvt_pk_bf16_f32 v153, v50, v51
	global_store_dwordx2 v234, v[152:153], s[4:5] offset:0
	v_cvt_pk_bf16_f32 v154, v52, v53
	v_cvt_pk_bf16_f32 v155, v54, v55
	global_store_dwordx2 v234, v[154:155], s[4:5] offset:32
	v_cvt_pk_bf16_f32 v156, v56, v57
	v_cvt_pk_bf16_f32 v157, v58, v59
	global_store_dwordx2 v234, v[156:157], s[4:5] offset:64
	v_cvt_pk_bf16_f32 v158, v60, v61
	v_cvt_pk_bf16_f32 v159, v62, v63
	global_store_dwordx2 v234, v[158:159], s[4:5] offset:96
	s_add_u32 s4, s4, 0x4000
	s_addc_u32 s5, s5, 0
	v_cvt_pk_bf16_f32 v128, v64, v65
	v_cvt_pk_bf16_f32 v129, v66, v67
	global_store_dwordx2 v234, v[128:129], s[4:5] offset:0
	v_cvt_pk_bf16_f32 v130, v68, v69
	v_cvt_pk_bf16_f32 v131, v70, v71
	global_store_dwordx2 v234, v[130:131], s[4:5] offset:32
	v_cvt_pk_bf16_f32 v132, v72, v73
	v_cvt_pk_bf16_f32 v133, v74, v75
	global_store_dwordx2 v234, v[132:133], s[4:5] offset:64
	v_cvt_pk_bf16_f32 v134, v76, v77
	v_cvt_pk_bf16_f32 v135, v78, v79
	global_store_dwordx2 v234, v[134:135], s[4:5] offset:96
	s_add_u32 s4, s4, 0x4000
	s_addc_u32 s5, s5, 0
	v_cvt_pk_bf16_f32 v136, v80, v81
	v_cvt_pk_bf16_f32 v137, v82, v83
	global_store_dwordx2 v234, v[136:137], s[4:5] offset:0
	v_cvt_pk_bf16_f32 v138, v84, v85
	v_cvt_pk_bf16_f32 v139, v86, v87
	global_store_dwordx2 v234, v[138:139], s[4:5] offset:32
	v_cvt_pk_bf16_f32 v140, v88, v89
	v_cvt_pk_bf16_f32 v141, v90, v91
	global_store_dwordx2 v234, v[140:141], s[4:5] offset:64
	v_cvt_pk_bf16_f32 v142, v92, v93
	v_cvt_pk_bf16_f32 v143, v94, v95
	global_store_dwordx2 v234, v[142:143], s[4:5] offset:96
	s_add_u32 s4, s4, 0x4000
	s_addc_u32 s5, s5, 0
	v_cvt_pk_bf16_f32 v144, v96, v97
	v_cvt_pk_bf16_f32 v145, v98, v99
	global_store_dwordx2 v234, v[144:145], s[4:5] offset:0
	v_cvt_pk_bf16_f32 v146, v100, v101
	v_cvt_pk_bf16_f32 v147, v102, v103
	global_store_dwordx2 v234, v[146:147], s[4:5] offset:32
	v_cvt_pk_bf16_f32 v148, v104, v105
	v_cvt_pk_bf16_f32 v149, v106, v107
	global_store_dwordx2 v234, v[148:149], s[4:5] offset:64
	v_cvt_pk_bf16_f32 v150, v108, v109
	v_cvt_pk_bf16_f32 v151, v110, v111
	global_store_dwordx2 v234, v[150:151], s[4:5] offset:96
	s_add_u32 s4, s4, 0x4000
	s_addc_u32 s5, s5, 0
	v_cvt_pk_bf16_f32 v152, v112, v113
	v_cvt_pk_bf16_f32 v153, v114, v115
	global_store_dwordx2 v234, v[152:153], s[4:5] offset:0
	v_cvt_pk_bf16_f32 v154, v116, v117
	v_cvt_pk_bf16_f32 v155, v118, v119
	global_store_dwordx2 v234, v[154:155], s[4:5] offset:32
	v_cvt_pk_bf16_f32 v156, v120, v121
	v_cvt_pk_bf16_f32 v157, v122, v123
	global_store_dwordx2 v234, v[156:157], s[4:5] offset:64
	v_cvt_pk_bf16_f32 v158, v124, v125
	v_cvt_pk_bf16_f32 v159, v126, v127
	global_store_dwordx2 v234, v[158:159], s[4:5] offset:96
	s_branch .Lg11_enext
.Lg11_eo1:
	s_mul_i32 s26, s28, 4160
	s_sub_u32 s25, s27, 512
	s_lshl_b32 s25, s25, 1
	s_add_u32 s26, s26, s25
	s_add_u32 s26, s26, 0x9800000
	s_add_u32 s4, s92, s26
	s_addc_u32 s5, s93, 0
	s_sub_u32 s25, s27, 512
	s_sub_u32 s25, 2080, s25
	s_lshr_b32 s26, s99, 4
	s_and_b32 s26, s26, 64
	s_sub_u32 s25, s25, s26
	v_cvt_pk_bf16_f32 v128, v0, v1
	v_cvt_pk_bf16_f32 v129, v2, v3
	s_cmp_gt_i32 s25, 0
	s_cbranch_scc0 .Lg11_ps0
	global_store_dwordx2 v235, v[128:129], s[4:5] offset:0
.Lg11_ps0:
	v_cvt_pk_bf16_f32 v130, v4, v5
	v_cvt_pk_bf16_f32 v131, v6, v7
	s_cmp_gt_i32 s25, 16
	s_cbranch_scc0 .Lg11_ps1
	global_store_dwordx2 v235, v[130:131], s[4:5] offset:32
.Lg11_ps1:
	v_cvt_pk_bf16_f32 v132, v8, v9
	v_cvt_pk_bf16_f32 v133, v10, v11
	s_cmp_gt_i32 s25, 32
	s_cbranch_scc0 .Lg11_ps2
	global_store_dwordx2 v235, v[132:133], s[4:5] offset:64
.Lg11_ps2:
	v_cvt_pk_bf16_f32 v134, v12, v13
	v_cvt_pk_bf16_f32 v135, v14, v15
	s_cmp_gt_i32 s25, 48
	s_cbranch_scc0 .Lg11_ps3
	global_store_dwordx2 v235, v[134:135], s[4:5] offset:96
; DI void st_bf16x4(bf16_t* o, f32x4 v) { u32x2 q; q.x = pack2(v[0], v[1]); q.y = pack2(v[2], v[3]); *(u32x2*)o = q; }
;   DI void operator()(int row, int col, f32x4 v) const {
;     if (col < n0) st_bf16x4(o0 + (size_t)row * ld0 + col, v);
;     else { const int c = col - n0; if (c < n1) st_bf16x4(o1 + (size_t)row * ld1 + c, v); }
;   }
; template <class Epi>
; DI void gemm_phase(char* smem, const bf16_t* A0, int lda0, int ksplit, const bf16_t* A1, int lda1, const bf16_t* Bt, int K, int nN, const Epi& epi, int tid) {
;     ...
;     const int x = blockIdx.x & 7, l = blockIdx.x >> 3, L = G >> 3, per = 8 * nN, tot = 2 * per;
;     for (int q = l; q < tot; q += L) { const int rgl = q / per, rem = q % per, ct = rem >> 3, rt = (x * 2 + rgl) * 8 + (rem & 7);
;       gemm_tile(smem, A0, lda0, ksplit, A1, lda1, Bt, K, rt * 256, ct * 128, epi, tid); }
.Lg11_ps3:
	s_add_u32 s4, s4, 0x10400
	s_addc_u32 s5, s5, 0
	v_cvt_pk_bf16_f32 v136, v16, v17
	v_cvt_pk_bf16_f32 v137, v18, v19
	s_cmp_gt_i32 s25, 0
	s_cbranch_scc0 .Lg11_ps4
	global_store_dwordx2 v235, v[136:137], s[4:5] offset:0
.Lg11_ps4:
	v_cvt_pk_bf16_f32 v138, v20, v21
	v_cvt_pk_bf16_f32 v139, v22, v23
	s_cmp_gt_i32 s25, 16
	s_cbranch_scc0 .Lg11_ps5
	global_store_dwordx2 v235, v[138:139], s[4:5] offset:32
.Lg11_ps5:
	v_cvt_pk_bf16_f32 v140, v24, v25
	v_cvt_pk_bf16_f32 v141, v26, v27
	s_cmp_gt_i32 s25, 32
	s_cbranch_scc0 .Lg11_ps6
	global_store_dwordx2 v235, v[140:141], s[4:5] offset:64
.Lg11_ps6:
	v_cvt_pk_bf16_f32 v142, v28, v29
	v_cvt_pk_bf16_f32 v143, v30, v31
	s_cmp_gt_i32 s25, 48
	s_cbranch_scc0 .Lg11_ps7
	global_store_dwordx2 v235, v[142:143], s[4:5] offset:96
.Lg11_ps7:
	s_add_u32 s4, s4, 0x10400
	s_addc_u32 s5, s5, 0
	v_cvt_pk_bf16_f32 v144, v32, v33
	v_cvt_pk_bf16_f32 v145, v34, v35
	s_cmp_gt_i32 s25, 0
	s_cbranch_scc0 .Lg11_ps8
	global_store_dwordx2 v235, v[144:145], s[4:5] offset:0
.Lg11_ps8:
	v_cvt_pk_bf16_f32 v146, v36, v37
	v_cvt_pk_bf16_f32 v147, v38, v39
	s_cmp_gt_i32 s25, 16
	s_cbranch_scc0 .Lg11_ps9
	global_store_dwordx2 v235, v[146:147], s[4:5] offset:32
.Lg11_ps9:
	v_cvt_pk_bf16_f32 v148, v40, v41
	v_cvt_pk_bf16_f32 v149, v42, v43
	s_cmp_gt_i32 s25, 32
	s_cbranch_scc0 .Lg11_ps10
	global_store_dwordx2 v235, v[148:149], s[4:5] offset:64
.Lg11_ps10:
	v_cvt_pk_bf16_f32 v150, v44, v45
	v_cvt_pk_bf16_f32 v151, v46, v47
	s_cmp_gt_i32 s25, 48
	s_cbranch_scc0 .Lg11_ps11
	global_store_dwordx2 v235, v[150:151], s[4:5] offset:96
.Lg11_ps11:
	s_add_u32 s4, s4, 0x10400
	s_addc_u32 s5, s5, 0
	v_cvt_pk_bf16_f32 v152, v48, v49
	v_cvt_pk_bf16_f32 v153, v50, v51
	s_cmp_gt_i32 s25, 0
	s_cbranch_scc0 .Lg11_ps12
	global_store_dwordx2 v235, v[152:153], s[4:5] offset:0
.Lg11_ps12:
	v_cvt_pk_bf16_f32 v154, v52, v53
	v_cvt_pk_bf16_f32 v155, v54, v55
	s_cmp_gt_i32 s25, 16
	s_cbranch_scc0 .Lg11_ps13
	global_store_dwordx2 v235, v[154:155], s[4:5] offset:32
.Lg11_ps13:
	v_cvt_pk_bf16_f32 v156, v56, v57
	v_cvt_pk_bf16_f32 v157, v58, v59
	s_cmp_gt_i32 s25, 32
	s_cbranch_scc0 .Lg11_ps14
	global_store_dwordx2 v235, v[156:157], s[4:5] offset:64
.Lg11_ps14:
	v_cvt_pk_bf16_f32 v158, v60, v61
	v_cvt_pk_bf16_f32 v159, v62, v63
	s_cmp_gt_i32 s25, 48
	s_cbranch_scc0 .Lg11_ps15
	global_store_dwordx2 v235, v[158:159], s[4:5] offset:96
.Lg11_ps15:
	s_add_u32 s4, s4, 0x10400
	s_addc_u32 s5, s5, 0
	v_cvt_pk_bf16_f32 v128, v64, v65
	v_cvt_pk_bf16_f32 v129, v66, v67
	s_cmp_gt_i32 s25, 0
	s_cbranch_scc0 .Lg11_ps16
	global_store_dwordx2 v235, v[128:129], s[4:5] offset:0
.Lg11_ps16:
	v_cvt_pk_bf16_f32 v130, v68, v69
	v_cvt_pk_bf16_f32 v131, v70, v71
	s_cmp_gt_i32 s25, 16
	s_cbranch_scc0 .Lg11_ps17
	global_store_dwordx2 v235, v[130:131], s[4:5] offset:32
.Lg11_ps17:
	v_cvt_pk_bf16_f32 v132, v72, v73
	v_cvt_pk_bf16_f32 v133, v74, v75
	s_cmp_gt_i32 s25, 32
	s_cbranch_scc0 .Lg11_ps18
	global_store_dwordx2 v235, v[132:133], s[4:5] offset:64
.Lg11_ps18:
	v_cvt_pk_bf16_f32 v134, v76, v77
	v_cvt_pk_bf16_f32 v135, v78, v79
	s_cmp_gt_i32 s25, 48
	s_cbranch_scc0 .Lg11_ps19
	global_store_dwordx2 v235, v[134:135], s[4:5] offset:96
.Lg11_ps19:
	s_add_u32 s4, s4, 0x10400
	s_addc_u32 s5, s5, 0
	v_cvt_pk_bf16_f32 v136, v80, v81
	v_cvt_pk_bf16_f32 v137, v82, v83
	s_cmp_gt_i32 s25, 0
	s_cbranch_scc0 .Lg11_ps20
	global_store_dwordx2 v235, v[136:137], s[4:5] offset:0
.Lg11_ps20:
	v_cvt_pk_bf16_f32 v138, v84, v85
	v_cvt_pk_bf16_f32 v139, v86, v87
	s_cmp_gt_i32 s25, 16
	s_cbranch_scc0 .Lg11_ps21
	global_store_dwordx2 v235, v[138:139], s[4:5] offset:32
.Lg11_ps21:
	v_cvt_pk_bf16_f32 v140, v88, v89
	v_cvt_pk_bf16_f32 v141, v90, v91
	s_cmp_gt_i32 s25, 32
	s_cbranch_scc0 .Lg11_ps22
	global_store_dwordx2 v235, v[140:141], s[4:5] offset:64
.Lg11_ps22:
	v_cvt_pk_bf16_f32 v142, v92, v93
	v_cvt_pk_bf16_f32 v143, v94, v95
	s_cmp_gt_i32 s25, 48
	s_cbranch_scc0 .Lg11_ps23
	global_store_dwordx2 v235, v[142:143], s[4:5] offset:96
.Lg11_ps23:
	s_add_u32 s4, s4, 0x10400
	s_addc_u32 s5, s5, 0
	v_cvt_pk_bf16_f32 v144, v96, v97
	v_cvt_pk_bf16_f32 v145, v98, v99
	s_cmp_gt_i32 s25, 0
	s_cbranch_scc0 .Lg11_ps24
	global_store_dwordx2 v235, v[144:145], s[4:5] offset:0
.Lg11_ps24:
	v_cvt_pk_bf16_f32 v146, v100, v101
	v_cvt_pk_bf16_f32 v147, v102, v103
	s_cmp_gt_i32 s25, 16
	s_cbranch_scc0 .Lg11_ps25
	global_store_dwordx2 v235, v[146:147], s[4:5] offset:32
.Lg11_ps25:
	v_cvt_pk_bf16_f32 v148, v104, v105
	v_cvt_pk_bf16_f32 v149, v106, v107
	s_cmp_gt_i32 s25, 32
	s_cbranch_scc0 .Lg11_ps26
	global_store_dwordx2 v235, v[148:149], s[4:5] offset:64
.Lg11_ps26:
	v_cvt_pk_bf16_f32 v150, v108, v109
	v_cvt_pk_bf16_f32 v151, v110, v111
	s_cmp_gt_i32 s25, 48
	s_cbranch_scc0 .Lg11_ps27
	global_store_dwordx2 v235, v[150:151], s[4:5] offset:96
.Lg11_ps27:
	s_add_u32 s4, s4, 0x10400
	s_addc_u32 s5, s5, 0
	v_cvt_pk_bf16_f32 v152, v112, v113
	v_cvt_pk_bf16_f32 v153, v114, v115
	s_cmp_gt_i32 s25, 0
	s_cbranch_scc0 .Lg11_ps28
	global_store_dwordx2 v235, v[152:153], s[4:5] offset:0
.Lg11_ps28:
	v_cvt_pk_bf16_f32 v154, v116, v117
	v_cvt_pk_bf16_f32 v155, v118, v119
	s_cmp_gt_i32 s25, 16
	s_cbranch_scc0 .Lg11_ps29
	global_store_dwordx2 v235, v[154:155], s[4:5] offset:32
.Lg11_ps29:
	v_cvt_pk_bf16_f32 v156, v120, v121
	v_cvt_pk_bf16_f32 v157, v122, v123
	s_cmp_gt_i32 s25, 32
	s_cbranch_scc0 .Lg11_ps30
	global_store_dwordx2 v235, v[156:157], s[4:5] offset:64
.Lg11_ps30:
	v_cvt_pk_bf16_f32 v158, v124, v125
	v_cvt_pk_bf16_f32 v159, v126, v127
	s_cmp_gt_i32 s25, 48
	s_cbranch_scc0 .Lg11_ps31
	global_store_dwordx2 v235, v[158:159], s[4:5] offset:96
.Lg11_ps31:
.Lg11_enext:
	s_add_u32 s101, s101, 64
	s_branch .Lg11_tile

; #define LWRITE(S, buf) do { bf16_t* sA_ = sbase + (buf) * BUF; bf16_t* sB_ = sA_ + 256 * PITCH; \
;     _Pragma("unroll") for (int i_ = 0; i_ < 4; ++i_) *(u32x4*)(sA_ + (sr + i_ * 64) * PITCH + scv * 8) = ra[S][i_]; \
;     _Pragma("unroll") for (int i_ = 0; i_ < 2; ++i_) *(u32x4*)(sB_ + (sr + i_ * 64) * PITCH + scv * 8) = rb[S][i_]; } while (0)
; template <class Epi>
; DI void gemm_tile(char* smem, const bf16_t* __restrict__ A0, int lda0, int ksplit, const bf16_t* __restrict__ A1, int lda1,
;                   const bf16_t* __restrict__ Bt, int K, int row0, int col0, const Epi& epi, int tid) {
;   constexpr int BK = 32, PITCH = 40, BUF = (256 + 128) * PITCH;
;   bf16_t* sbase = (bf16_t*)smem;
;   const int lane = tid & 63, wid = tid >> 6, wr = wid >> 1, wc = wid & 1, fr = lane & 15, fq = lane >> 4;
;   f32x4 acc[8][4];
; #pragma unroll
;   for (int m = 0; m < 8; ++m)
; #pragma unroll
;     for (int n = 0; n < 4; ++n) acc[m][n] = (f32x4){0.f, 0.f, 0.f, 0.f};
;   u32x4 ra[2][4], rb[2][2];
;   const int nk = K / BK;
;   const int sr = tid >> 2, scv = tid & 3;
;     ...
;   __syncthreads();
;   {
;     const int last = nk - 1;
;     GLOAD(0, 0);
;     __builtin_amdgcn_sched_barrier(0);
;     GLOAD(1, 1);
;     __builtin_amdgcn_sched_barrier(0);
;     LWRITE(0, 0);
;     __builtin_amdgcn_sched_barrier(0);
;     GLOAD(0, (2 < last ? 2 : last));
;     __builtin_amdgcn_sched_barrier(0);
;     __syncthreads();
; template <class Epi>
; DI void gemm_phase(char* smem, const bf16_t* A0, int lda0, int ksplit, const bf16_t* A1, int lda1, const bf16_t* Bt, int K, int nN, const Epi& epi, int tid) {
;   const int G = gridDim.x;
;   if ((G & 7) == 0) {
;     const int x = blockIdx.x & 7, l = blockIdx.x >> 3, L = G >> 3, per = 8 * nN, tot = 2 * per;
;     for (int q = l; q < tot; q += L) { const int rgl = q / per, rem = q % per, ct = rem >> 3, rt = (x * 2 + rgl) * 8 + (rem & 7);
;       gemm_tile(smem, A0, lda0, ksplit, A1, lda1, Bt, K, rt * 256, ct * 128, epi, tid); }
;   } else {
;     const int ntiles = (NTOK / 256) * nN;
;     for (int u = blockIdx.x; u < ntiles; u += G) { const int rt = u / nN, ct = u % nN; gemm_tile(smem, A0, lda0, ksplit, A1, lda1, Bt, K, rt * 256, ct * 128, epi, tid); }
.LBB0_1816:
	s_cmp_gt_i32 s94, 14
	s_cselect_b64 s[0:1], -1, 0
	s_cmp_lt_i32 s95, 15
	s_cselect_b64 s[2:3], -1, 0
	s_or_b64 s[0:1], s[0:1], s[2:3]
	v_readlane_b32 s36, v252, 8
	s_and_b64 vcc, exec, s[0:1]
	v_readlane_b32 s40, v252, 12
	v_readlane_b32 s41, v252, 13
	v_readlane_b32 s42, v252, 14
	v_readlane_b32 s43, v252, 15
	v_readlane_b32 s37, v252, 9
	v_readlane_b32 s38, v252, 10
	v_readlane_b32 s39, v252, 11
	v_readlane_b32 s44, v252, 16
	v_readlane_b32 s45, v252, 17
	v_readlane_b32 s46, v252, 18
	v_readlane_b32 s47, v252, 19
	v_readlane_b32 s48, v252, 20
	v_readlane_b32 s49, v252, 21
	v_readlane_b32 s50, v252, 22
	v_readlane_b32 s51, v252, 23
	s_cbranch_vccnz .LBB0_1844
	s_add_u32 s2, s92, 0x1da00000
	s_waitcnt lgkmcnt(0)
	s_load_dword s14, s[74:75], 0x180
	s_addc_u32 s3, s93, 0
	s_add_u32 s0, s92, 0x3400000
	s_addc_u32 s1, s93, 0
	s_add_u32 s4, s92, 0x11a00000
	s_addc_u32 s5, s93, 0
	s_and_b32 s16, s72, 0xffffffc0
	v_mbcnt_hi_u32_b32 v195, -1, v194
	s_waitcnt lgkmcnt(0)
	s_and_b32 s15, s14, 7
	s_cmp_lg_u32 s15, 0
	s_waitcnt vmcnt(16)
	v_add_u32_e32 v196, s16, v195
	s_cbranch_scc0 .LBB0_1824
	s_cmpk_gt_i32 s96, 0x1ff
	s_cbranch_scc1 .LBB0_1823
	v_and_b32_e32 v0, 3, v195
	v_lshlrev_b32_e32 v176, 4, v0
	v_mov_b32_e32 v177, 0
	v_ashrrev_i32_e32 v197, 2, v196
	v_lshl_add_u64 v[178:179], s[2:3], 0, v[176:177]
	v_lshl_add_u64 v[180:181], s[0:1], 0, v[176:177]
	v_add_u32_e32 v0, 0, v176
	s_movk_i32 s6, 0x40
	v_bfe_u32 v2, v195, 4, 2
	v_and_b32_e32 v3, 0x4f, v196
	v_and_b32_e32 v176, 0xffffff8f, v196
	v_or_b32_e32 v6, 0x70, v196
	v_mul_lo_u32 v1, v197, s6
	v_lshl_add_u32 v4, v2, 4, 0
	v_mul_u32_u24_e32 v3, 0x40, v3
	v_mul_lo_u32 v5, v176, s6
	v_mul_lo_u32 v6, v6, s6
	v_and_b32_e32 v7, 64, v196
	s_mov_b32 s7, 0
	v_lshl_or_b32 v198, v2, 2, v7
	s_mov_b64 s[8:9], 0x10000
	s_mov_b64 s[10:11], 0x20000
	s_mov_b64 s[12:13], 0x30000
	v_add_u32_e32 v199, v0, v1
	v_add_u32_e32 v200, v4, v3
	v_add_u32_e32 v201, v4, v5
	v_add_u32_e32 v202, v4, v6
	v_mbcnt_lo_u32_b32 v1, -1, 0
	v_mbcnt_hi_u32_b32 v1, -1, v1
	v_bfe_u32 v3, v1, 3, 1
	v_bfe_u32 v1, v1, 5, 1
	v_mul_u32_u24_e32 v3, 48, v3
	v_mul_u32_u24_e32 v1, 48, v1
	v_xor_b32_e32 v199, v199, v1
	v_xor_b32_e32 v200, v200, v3
	v_xor_b32_e32 v201, v201, v3
	v_xor_b32_e32 v202, v202, v3
	s_mov_b32 s17, s96
.LBB0_1820:
	s_ashr_i32 s6, s17, 31
	s_lshr_b32 s6, s6, 30
	s_add_i32 s6, s17, s6
	s_and_b32 s18, s6, 0x1fffffc
	s_lshl_b32 s6, s6, 6
	s_sub_i32 s19, s17, s18
	s_and_b32 s18, s6, 0xffffff00
	s_lshl_b32 s19, s19, 7
	v_add_u32_e32 v0, s18, v197
	v_ashrrev_i32_e32 v1, 31, v0
	v_add_u32_e32 v16, s19, v197
	v_lshlrev_b64 v[182:183], 10, v[0:1]
	v_ashrrev_i32_e32 v17, 31, v16
	v_lshl_add_u64 v[186:187], v[182:183], 0, s[10:11]
	v_lshlrev_b64 v[190:191], 10, v[16:17]
	v_lshl_add_u64 v[24:25], v[178:179], 0, v[182:183]
	v_lshl_add_u64 v[184:185], v[182:183], 0, s[8:9]
	v_lshl_add_u64 v[28:29], v[178:179], 0, v[186:187]
	v_lshl_add_u64 v[188:189], v[182:183], 0, s[12:13]
	v_lshl_add_u64 v[32:33], v[180:181], 0, v[190:191]
	v_lshl_add_u64 v[192:193], v[190:191], 0, s[8:9]
	s_barrier
	v_lshl_add_u64 v[26:27], v[178:179], 0, v[184:185]
	global_load_dwordx4 v[0:3], v[24:25], off
	global_load_dwordx4 v[4:7], v[26:27], off
	v_lshl_add_u64 v[30:31], v[178:179], 0, v[188:189]
	global_load_dwordx4 v[8:11], v[28:29], off
	global_load_dwordx4 v[12:15], v[30:31], off
	v_lshl_add_u64 v[34:35], v[180:181], 0, v[192:193]
	global_load_dwordx4 v[16:19], v[32:33], off
	global_load_dwordx4 v[20:23], v[34:35], off
	global_load_dwordx4 v[128:131], v[24:25], off offset:64
	global_load_dwordx4 v[132:135], v[26:27], off offset:64
	global_load_dwordx4 v[136:139], v[28:29], off offset:64
	global_load_dwordx4 v[140:143], v[30:31], off offset:64
	global_load_dwordx4 v[144:147], v[32:33], off offset:64
	global_load_dwordx4 v[148:151], v[34:35], off offset:64
	s_waitcnt vmcnt(11)
	ds_write_b128 v199, v[0:3]
	s_waitcnt vmcnt(10)
	ds_write_b128 v199, v[4:7] offset:4096
	s_waitcnt vmcnt(9)
	ds_write_b128 v199, v[8:11] offset:8192
	s_waitcnt vmcnt(8)
	ds_write_b128 v199, v[12:15] offset:12288
	s_waitcnt vmcnt(7)
	ds_write_b128 v199, v[16:19] offset:16384
	s_waitcnt vmcnt(6)
	ds_write_b128 v199, v[20:23] offset:20480
	global_load_dwordx4 v[152:155], v[24:25], off offset:128
	global_load_dwordx4 v[156:159], v[26:27], off offset:128
	global_load_dwordx4 v[160:163], v[28:29], off offset:128
	global_load_dwordx4 v[164:167], v[30:31], off offset:128
	global_load_dwordx4 v[168:171], v[32:33], off offset:128
	global_load_dwordx4 v[172:175], v[34:35], off offset:128
	s_mov_b32 s20, -2
	v_mov_b32_e32 v96, 0
	v_mov_b32_e32 v97, v177
	v_mov_b32_e32 v98, v177
	v_mov_b32_e32 v99, v177
	v_mov_b32_e32 v100, 0
	v_mov_b32_e32 v101, v177
	v_mov_b32_e32 v102, v177
	v_mov_b32_e32 v103, v177
	v_mov_b32_e32 v104, 0
	v_mov_b32_e32 v105, v177
	v_mov_b32_e32 v106, v177
	v_mov_b32_e32 v107, v177
	v_mov_b32_e32 v108, 0
	v_mov_b32_e32 v109, v177
	v_mov_b32_e32 v110, v177
	v_mov_b32_e32 v111, v177
	v_mov_b32_e32 v112, 0
	v_mov_b32_e32 v113, v177
	v_mov_b32_e32 v114, v177
	v_mov_b32_e32 v115, v177
	v_mov_b32_e32 v116, 0
	v_mov_b32_e32 v117, v177
	v_mov_b32_e32 v118, v177
	v_mov_b32_e32 v119, v177
	v_mov_b32_e32 v120, 0
	v_mov_b32_e32 v121, v177
	v_mov_b32_e32 v122, v177
	v_mov_b32_e32 v123, v177
	v_mov_b32_e32 v124, 0
	v_mov_b32_e32 v125, v177
	v_mov_b32_e32 v126, v177
	v_mov_b32_e32 v127, v177
	v_mov_b32_e32 v92, 0
	v_mov_b32_e32 v93, v177
	v_mov_b32_e32 v94, v177
	v_mov_b32_e32 v95, v177
	v_mov_b32_e32 v88, 0
	v_mov_b32_e32 v89, v177
	v_mov_b32_e32 v90, v177
	v_mov_b32_e32 v91, v177
	v_mov_b32_e32 v84, 0
	v_mov_b32_e32 v85, v177
	v_mov_b32_e32 v86, v177
	v_mov_b32_e32 v87, v177
; #define LWRITE(S, buf) do { bf16_t* sA_ = sbase + (buf) * BUF; bf16_t* sB_ = sA_ + 256 * PITCH; \
;     _Pragma("unroll") for (int i_ = 0; i_ < 4; ++i_) *(u32x4*)(sA_ + (sr + i_ * 64) * PITCH + scv * 8) = ra[S][i_]; \
;     _Pragma("unroll") for (int i_ = 0; i_ < 2; ++i_) *(u32x4*)(sB_ + (sr + i_ * 64) * PITCH + scv * 8) = rb[S][i_]; } while (0)
; template <class Epi>
; DI void gemm_tile(char* smem, const bf16_t* __restrict__ A0, int lda0, int ksplit, const bf16_t* __restrict__ A1, int lda1,
;                   const bf16_t* __restrict__ Bt, int K, int row0, int col0, const Epi& epi, int tid) {
;     ...
;   for (int m = 0; m < 8; ++m)
; #pragma unroll
;     for (int n = 0; n < 4; ++n) acc[m][n] = (f32x4){0.f, 0.f, 0.f, 0.f};
;   u32x4 ra[2][4], rb[2][2];
;   const int nk = K / BK;
;   const int sr = tid >> 2, scv = tid & 3;
;     ...
;   __syncthreads();
;   {
;     const int last = nk - 1;
;     GLOAD(0, 0);
;     __builtin_amdgcn_sched_barrier(0);
;     GLOAD(1, 1);
;     __builtin_amdgcn_sched_barrier(0);
;     LWRITE(0, 0);
;     __builtin_amdgcn_sched_barrier(0);
;     GLOAD(0, (2 < last ? 2 : last));
;     __builtin_amdgcn_sched_barrier(0);
;     __syncthreads();
;     for (int kt = 0; kt < nk; kt += 2) {
;       LWRITE(1, 1);
;       __builtin_amdgcn_sched_barrier(0);
;       GLOAD(1, (kt + 3 < last ? kt + 3 : last));
;       __builtin_amdgcn_sched_barrier(0);
;       COMPUTE(0);
	v_mov_b32_e32 v80, 0
	v_mov_b32_e32 v81, v177
	v_mov_b32_e32 v82, v177
	v_mov_b32_e32 v83, v177
	v_mov_b32_e32 v76, 0
	v_mov_b32_e32 v77, v177
	v_mov_b32_e32 v78, v177
	v_mov_b32_e32 v79, v177
	v_mov_b32_e32 v72, 0
	v_mov_b32_e32 v73, v177
	v_mov_b32_e32 v74, v177
	v_mov_b32_e32 v75, v177
	v_mov_b32_e32 v68, 0
	v_mov_b32_e32 v69, v177
	v_mov_b32_e32 v70, v177
	v_mov_b32_e32 v71, v177
	v_mov_b32_e32 v64, 0
	v_mov_b32_e32 v65, v177
	v_mov_b32_e32 v66, v177
	v_mov_b32_e32 v67, v177
	v_mov_b32_e32 v60, 0
	v_mov_b32_e32 v61, v177
	v_mov_b32_e32 v62, v177
	v_mov_b32_e32 v63, v177
	v_mov_b32_e32 v56, 0
	v_mov_b32_e32 v57, v177
	v_mov_b32_e32 v58, v177
	v_mov_b32_e32 v59, v177
	v_mov_b32_e32 v52, 0
	v_mov_b32_e32 v53, v177
	v_mov_b32_e32 v54, v177
	v_mov_b32_e32 v55, v177
	v_mov_b32_e32 v48, 0
	v_mov_b32_e32 v49, v177
	v_mov_b32_e32 v50, v177
	v_mov_b32_e32 v51, v177
	v_mov_b32_e32 v44, 0
	v_mov_b32_e32 v45, v177
	v_mov_b32_e32 v46, v177
	v_mov_b32_e32 v47, v177
	v_mov_b32_e32 v40, 0
	v_mov_b32_e32 v41, v177
	v_mov_b32_e32 v42, v177
	v_mov_b32_e32 v43, v177
	v_mov_b32_e32 v36, 0
	v_mov_b32_e32 v37, v177
	v_mov_b32_e32 v38, v177
	v_mov_b32_e32 v39, v177
	v_mov_b32_e32 v32, 0
	v_mov_b32_e32 v33, v177
	v_mov_b32_e32 v34, v177
	v_mov_b32_e32 v35, v177
	v_mov_b32_e32 v28, 0
	v_mov_b32_e32 v29, v177
	v_mov_b32_e32 v30, v177
	v_mov_b32_e32 v31, v177
	v_mov_b32_e32 v24, 0
	v_mov_b32_e32 v25, v177
	v_mov_b32_e32 v26, v177
	v_mov_b32_e32 v27, v177
	v_mov_b32_e32 v20, 0
	v_mov_b32_e32 v21, v177
	v_mov_b32_e32 v22, v177
	v_mov_b32_e32 v23, v177
	v_mov_b32_e32 v16, 0
	v_mov_b32_e32 v17, v177
	v_mov_b32_e32 v18, v177
	v_mov_b32_e32 v19, v177
	v_mov_b32_e32 v12, 0
	v_mov_b32_e32 v13, v177
	v_mov_b32_e32 v14, v177
	v_mov_b32_e32 v15, v177
	v_mov_b32_e32 v8, 0
	v_mov_b32_e32 v9, v177
	v_mov_b32_e32 v10, v177
	v_mov_b32_e32 v11, v177
	v_mov_b32_e32 v4, 0
	v_mov_b32_e32 v5, v177
	v_mov_b32_e32 v6, v177
	v_mov_b32_e32 v7, v177
	v_mov_b32_e32 v0, 0
	v_mov_b32_e32 v1, v177
	v_mov_b32_e32 v2, v177
	v_mov_b32_e32 v3, v177
	s_waitcnt lgkmcnt(0)
	s_barrier
.LBB0_1821:
	s_add_i32 s20, s20, 2
	s_waitcnt vmcnt(11)
	ds_write_b128 v199, v[128:131] offset:24576
	s_waitcnt vmcnt(10)
	ds_write_b128 v199, v[132:135] offset:28672
	s_waitcnt vmcnt(9)
	ds_write_b128 v199, v[136:139] offset:32768
	s_waitcnt vmcnt(8)
	ds_write_b128 v199, v[140:143] offset:36864
	s_waitcnt vmcnt(7)
	ds_write_b128 v199, v[144:147] offset:40960
	s_waitcnt vmcnt(6)
	ds_write_b128 v199, v[148:151] offset:45056
	s_min_u32 s6, s20, 12
	s_lshl_b32 s6, s6, 6
	v_lshl_add_u64 v[136:137], v[178:179], 0, s[6:7]
	v_lshl_add_u64 v[144:145], v[180:181], 0, s[6:7]
	v_lshl_add_u64 v[128:129], v[136:137], 0, v[182:183]
	v_lshl_add_u64 v[132:133], v[136:137], 0, v[184:185]
	v_lshl_add_u64 v[138:139], v[136:137], 0, v[186:187]
	v_lshl_add_u64 v[140:141], v[136:137], 0, v[188:189]
	v_lshl_add_u64 v[146:147], v[144:145], 0, v[190:191]
	v_lshl_add_u64 v[148:149], v[144:145], 0, v[192:193]
	ds_read_b128 v[204:207], v200 offset:16384
	ds_read_b128 v[208:211], v200 offset:17408
	ds_read_b128 v[212:215], v200 offset:18432
	ds_read_b128 v[216:219], v200 offset:19456
	ds_read_b128 v[220:223], v201
	ds_read_b128 v[224:227], v201 offset:1024
	ds_read_b128 v[228:231], v201 offset:2048
	ds_read_b128 v[232:235], v201 offset:3072
	ds_read_b128 v[236:239], v201 offset:4096
	ds_read_b128 v[240:243], v201 offset:5120
	ds_read_b128 v[244:247], v201 offset:6144
	ds_read_b128 v[248:251], v202
	s_setprio 1
	s_waitcnt lgkmcnt(7)
	v_mfma_f32_16x16x32_bf16 v[124:127], v[204:207], v[220:223], v[124:127]
	v_mfma_f32_16x16x32_bf16 v[120:123], v[208:211], v[220:223], v[120:123]
	v_mfma_f32_16x16x32_bf16 v[116:119], v[212:215], v[220:223], v[116:119]
	v_mfma_f32_16x16x32_bf16 v[112:115], v[216:219], v[220:223], v[112:115]
	global_load_dwordx4 v[128:131], v[128:129], off offset:192
	s_waitcnt lgkmcnt(6)
	v_mfma_f32_16x16x32_bf16 v[108:111], v[204:207], v[224:227], v[108:111]
	v_mfma_f32_16x16x32_bf16 v[104:107], v[208:211], v[224:227], v[104:107]
	v_mfma_f32_16x16x32_bf16 v[100:103], v[212:215], v[224:227], v[100:103]
	v_mfma_f32_16x16x32_bf16 v[96:99], v[216:219], v[224:227], v[96:99]
	global_load_dwordx4 v[132:135], v[132:133], off offset:192
	s_waitcnt lgkmcnt(5)
	v_mfma_f32_16x16x32_bf16 v[92:95], v[204:207], v[228:231], v[92:95]
	v_mfma_f32_16x16x32_bf16 v[88:91], v[208:211], v[228:231], v[88:91]
	v_mfma_f32_16x16x32_bf16 v[84:87], v[212:215], v[228:231], v[84:87]
	v_mfma_f32_16x16x32_bf16 v[80:83], v[216:219], v[228:231], v[80:83]
	global_load_dwordx4 v[136:139], v[138:139], off offset:192
	s_waitcnt lgkmcnt(4)
	v_mfma_f32_16x16x32_bf16 v[76:79], v[204:207], v[232:235], v[76:79]
	v_mfma_f32_16x16x32_bf16 v[72:75], v[208:211], v[232:235], v[72:75]
	v_mfma_f32_16x16x32_bf16 v[68:71], v[212:215], v[232:235], v[68:71]
	v_mfma_f32_16x16x32_bf16 v[64:67], v[216:219], v[232:235], v[64:67]
	global_load_dwordx4 v[140:143], v[140:141], off offset:192
	s_waitcnt lgkmcnt(3)
	v_mfma_f32_16x16x32_bf16 v[60:63], v[204:207], v[236:239], v[60:63]
	v_mfma_f32_16x16x32_bf16 v[56:59], v[208:211], v[236:239], v[56:59]
	v_mfma_f32_16x16x32_bf16 v[52:55], v[212:215], v[236:239], v[52:55]
	v_mfma_f32_16x16x32_bf16 v[48:51], v[216:219], v[236:239], v[48:51]
	global_load_dwordx4 v[144:147], v[146:147], off offset:192
	s_waitcnt lgkmcnt(2)
	v_mfma_f32_16x16x32_bf16 v[44:47], v[204:207], v[240:243], v[44:47]
	v_mfma_f32_16x16x32_bf16 v[40:43], v[208:211], v[240:243], v[40:43]
	v_mfma_f32_16x16x32_bf16 v[36:39], v[212:215], v[240:243], v[36:39]
	v_mfma_f32_16x16x32_bf16 v[32:35], v[216:219], v[240:243], v[32:35]
	global_load_dwordx4 v[148:151], v[148:149], off offset:192
	s_waitcnt lgkmcnt(1)
	v_mfma_f32_16x16x32_bf16 v[28:31], v[204:207], v[244:247], v[28:31]
	v_mfma_f32_16x16x32_bf16 v[24:27], v[208:211], v[244:247], v[24:27]
	v_mfma_f32_16x16x32_bf16 v[20:23], v[212:215], v[244:247], v[20:23]
	v_mfma_f32_16x16x32_bf16 v[16:19], v[216:219], v[244:247], v[16:19]
	s_waitcnt lgkmcnt(0)
	v_mfma_f32_16x16x32_bf16 v[12:15], v[204:207], v[248:251], v[12:15]
	v_mfma_f32_16x16x32_bf16 v[8:11], v[208:211], v[248:251], v[8:11]
	v_mfma_f32_16x16x32_bf16 v[4:7], v[212:215], v[248:251], v[4:7]
	v_mfma_f32_16x16x32_bf16 v[0:3], v[216:219], v[248:251], v[0:3]
	s_setprio 0
	s_barrier
; #define LWRITE(S, buf) do { bf16_t* sA_ = sbase + (buf) * BUF; bf16_t* sB_ = sA_ + 256 * PITCH; \
;     _Pragma("unroll") for (int i_ = 0; i_ < 4; ++i_) *(u32x4*)(sA_ + (sr + i_ * 64) * PITCH + scv * 8) = ra[S][i_]; \
;     _Pragma("unroll") for (int i_ = 0; i_ < 2; ++i_) *(u32x4*)(sB_ + (sr + i_ * 64) * PITCH + scv * 8) = rb[S][i_]; } while (0)
; template <class Epi>
; DI void gemm_tile(char* smem, const bf16_t* __restrict__ A0, int lda0, int ksplit, const bf16_t* __restrict__ A1, int lda1,
;                   const bf16_t* __restrict__ Bt, int K, int row0, int col0, const Epi& epi, int tid) {
;     ...
;       LWRITE(0, 0);
;       __builtin_amdgcn_sched_barrier(0);
;       GLOAD(0, (kt + 4 < last ? kt + 4 : last));
;       __builtin_amdgcn_sched_barrier(0);
;       COMPUTE(1);
;       __syncthreads();
;     }
;   }
;     ...
; #pragma unroll
;   for (int m = 0; m < 8; ++m)
; #pragma unroll
;     for (int n = 0; n < 4; ++n) epi(row0 + wr * 128 + m * 16 + fr, col0 + wc * 64 + n * 16 + fq * 4, acc[m][n]);
; }
	s_waitcnt vmcnt(11)
	ds_write_b128 v199, v[152:155]
	s_waitcnt vmcnt(10)
	ds_write_b128 v199, v[156:159] offset:4096
	s_waitcnt vmcnt(9)
	ds_write_b128 v199, v[160:163] offset:8192
	s_waitcnt vmcnt(8)
	ds_write_b128 v199, v[164:167] offset:12288
	s_waitcnt vmcnt(7)
	ds_write_b128 v199, v[168:171] offset:16384
	s_waitcnt vmcnt(6)
	ds_write_b128 v199, v[172:175] offset:20480
	s_min_u32 s6, s20, 11
	s_lshl_b32 s6, s6, 6
	v_lshl_add_u64 v[160:161], v[178:179], 0, s[6:7]
	v_lshl_add_u64 v[168:169], v[180:181], 0, s[6:7]
	v_lshl_add_u64 v[152:153], v[160:161], 0, v[182:183]
	v_lshl_add_u64 v[156:157], v[160:161], 0, v[184:185]
	v_lshl_add_u64 v[162:163], v[160:161], 0, v[186:187]
	v_lshl_add_u64 v[164:165], v[160:161], 0, v[188:189]
	v_lshl_add_u64 v[170:171], v[168:169], 0, v[190:191]
	v_lshl_add_u64 v[172:173], v[168:169], 0, v[192:193]
	ds_read_b128 v[204:207], v200 offset:40960
	ds_read_b128 v[208:211], v200 offset:41984
	ds_read_b128 v[212:215], v200 offset:43008
	ds_read_b128 v[216:219], v200 offset:44032
	ds_read_b128 v[220:223], v201 offset:26624
	ds_read_b128 v[224:227], v201 offset:27648
	ds_read_b128 v[228:231], v201 offset:28672
	ds_read_b128 v[232:235], v201 offset:29696
	ds_read_b128 v[236:239], v201 offset:24576
	ds_read_b128 v[240:243], v201 offset:30720
	ds_read_b128 v[244:247], v201 offset:25600
	ds_read_b128 v[248:251], v202 offset:24576
	s_setprio 1
	s_waitcnt lgkmcnt(3)
	v_mfma_f32_16x16x32_bf16 v[124:127], v[204:207], v[236:239], v[124:127]
	v_mfma_f32_16x16x32_bf16 v[120:123], v[208:211], v[236:239], v[120:123]
	v_mfma_f32_16x16x32_bf16 v[116:119], v[212:215], v[236:239], v[116:119]
	v_mfma_f32_16x16x32_bf16 v[112:115], v[216:219], v[236:239], v[112:115]
	global_load_dwordx4 v[152:155], v[152:153], off offset:256
	s_waitcnt lgkmcnt(1)
	v_mfma_f32_16x16x32_bf16 v[108:111], v[204:207], v[244:247], v[108:111]
	v_mfma_f32_16x16x32_bf16 v[104:107], v[208:211], v[244:247], v[104:107]
	v_mfma_f32_16x16x32_bf16 v[100:103], v[212:215], v[244:247], v[100:103]
	v_mfma_f32_16x16x32_bf16 v[96:99], v[216:219], v[244:247], v[96:99]
	global_load_dwordx4 v[156:159], v[156:157], off offset:256
	v_mfma_f32_16x16x32_bf16 v[92:95], v[204:207], v[220:223], v[92:95]
	v_mfma_f32_16x16x32_bf16 v[88:91], v[208:211], v[220:223], v[88:91]
	v_mfma_f32_16x16x32_bf16 v[84:87], v[212:215], v[220:223], v[84:87]
	v_mfma_f32_16x16x32_bf16 v[80:83], v[216:219], v[220:223], v[80:83]
	global_load_dwordx4 v[160:163], v[162:163], off offset:256
	v_mfma_f32_16x16x32_bf16 v[76:79], v[204:207], v[224:227], v[76:79]
	v_mfma_f32_16x16x32_bf16 v[72:75], v[208:211], v[224:227], v[72:75]
	v_mfma_f32_16x16x32_bf16 v[68:71], v[212:215], v[224:227], v[68:71]
	v_mfma_f32_16x16x32_bf16 v[64:67], v[216:219], v[224:227], v[64:67]
	global_load_dwordx4 v[164:167], v[164:165], off offset:256
	v_mfma_f32_16x16x32_bf16 v[60:63], v[204:207], v[228:231], v[60:63]
	v_mfma_f32_16x16x32_bf16 v[56:59], v[208:211], v[228:231], v[56:59]
	v_mfma_f32_16x16x32_bf16 v[52:55], v[212:215], v[228:231], v[52:55]
	v_mfma_f32_16x16x32_bf16 v[48:51], v[216:219], v[228:231], v[48:51]
	global_load_dwordx4 v[168:171], v[170:171], off offset:256
	v_mfma_f32_16x16x32_bf16 v[44:47], v[204:207], v[232:235], v[44:47]
	v_mfma_f32_16x16x32_bf16 v[40:43], v[208:211], v[232:235], v[40:43]
	v_mfma_f32_16x16x32_bf16 v[36:39], v[212:215], v[232:235], v[36:39]
	v_mfma_f32_16x16x32_bf16 v[32:35], v[216:219], v[232:235], v[32:35]
	global_load_dwordx4 v[172:175], v[172:173], off offset:256
	v_mfma_f32_16x16x32_bf16 v[28:31], v[204:207], v[240:243], v[28:31]
	v_mfma_f32_16x16x32_bf16 v[24:27], v[208:211], v[240:243], v[24:27]
	v_mfma_f32_16x16x32_bf16 v[20:23], v[212:215], v[240:243], v[20:23]
	v_mfma_f32_16x16x32_bf16 v[16:19], v[216:219], v[240:243], v[16:19]
	s_waitcnt lgkmcnt(0)
	v_mfma_f32_16x16x32_bf16 v[12:15], v[204:207], v[248:251], v[12:15]
	v_mfma_f32_16x16x32_bf16 v[8:11], v[208:211], v[248:251], v[8:11]
	v_mfma_f32_16x16x32_bf16 v[4:7], v[212:215], v[248:251], v[4:7]
	v_mfma_f32_16x16x32_bf16 v[0:3], v[216:219], v[248:251], v[0:3]
	s_setprio 0
	s_cmp_lt_u32 s20, 14
	s_barrier
	s_cbranch_scc1 .LBB0_1821
	s_waitcnt vmcnt(11)
	v_or_b32_e32 v130, s19, v198
	v_ashrrev_i32_e32 v131, 31, v130
	v_lshl_add_u64 v[128:129], v[130:131], 2, s[82:83]
	global_load_dwordx4 v[134:137], v[128:129], off
	s_waitcnt vmcnt(11)
	v_add_u32_e32 v132, s18, v176
	v_ashrrev_i32_e32 v133, 31, v132
	s_waitcnt vmcnt(10)
	v_lshlrev_b64 v[138:139], 10, v[132:133]
	v_lshlrev_b64 v[130:131], 1, v[130:131]
	s_waitcnt vmcnt(9)
	v_lshl_add_u64 v[140:141], s[2:3], 0, v[138:139]
	v_lshl_add_u64 v[140:141], v[140:141], 0, v[130:131]
	global_load_dwordx2 v[142:143], v[140:141], off
	v_lshl_add_u64 v[138:139], s[4:5], 0, v[138:139]
	v_lshl_add_u64 v[138:139], v[138:139], 0, v[130:131]
	global_load_dwordx2 v[144:145], v[140:141], off offset:32
	global_load_dwordx2 v[146:147], v[140:141], off offset:64
	s_nop 0
	global_load_dwordx2 v[140:141], v[140:141], off offset:96
	s_add_i32 s17, s17, s14
	s_cmpk_lt_i32 s17, 0x200
	s_waitcnt vmcnt(4)
	v_add_f32_e32 v124, v124, v134
	v_add_f32_e32 v125, v125, v135
	v_add_f32_e32 v126, v126, v136
	v_add_f32_e32 v127, v127, v137
	v_mul_f32_e32 v124, 0xbfb8aa3b, v124
	v_mul_f32_e32 v125, 0xbfb8aa3b, v125
	v_mul_f32_e32 v126, 0xbfb8aa3b, v126
	v_mul_f32_e32 v127, 0xbfb8aa3b, v127
	v_exp_f32_e32 v133, v124
	v_exp_f32_e32 v134, v125
	v_exp_f32_e32 v126, v126
	v_exp_f32_e32 v127, v127
	v_add_f32_e32 v133, 1.0, v133
	v_add_f32_e32 v134, 1.0, v134
	v_add_f32_e32 v135, 1.0, v126
	v_add_f32_e32 v136, 1.0, v127
	v_rcp_f32_e32 v126, v133
	v_rcp_f32_e32 v127, v134
	v_rcp_f32_e32 v134, v135
	v_rcp_f32_e32 v135, v136
	s_waitcnt vmcnt(3)
; template <class Epi>
; DI void gemm_tile(char* smem, const bf16_t* __restrict__ A0, int lda0, int ksplit, const bf16_t* __restrict__ A1, int lda1,
;                   const bf16_t* __restrict__ Bt, int K, int row0, int col0, const Epi& epi, int tid) {
;     ...
; #pragma unroll
;   for (int m = 0; m < 8; ++m)
; #pragma unroll
;     for (int n = 0; n < 4; ++n) epi(row0 + wr * 128 + m * 16 + fr, col0 + wc * 64 + n * 16 + fq * 4, acc[m][n]);
	v_lshlrev_b32_e32 v124, 16, v142
	v_and_b32_e32 v125, 0xffff0000, v142
	v_lshlrev_b32_e32 v136, 16, v143
	v_and_b32_e32 v137, 0xffff0000, v143
	v_pk_mul_f32 v[124:125], v[126:127], v[124:125]
	v_pk_mul_f32 v[126:127], v[134:135], v[136:137]
	v_cvt_pk_bf16_f32 v124, v124, v125
	v_cvt_pk_bf16_f32 v125, v126, v127
	global_store_dwordx2 v[138:139], v[124:125], off
	global_load_dwordx4 v[124:127], v[128:129], off offset:64
	s_waitcnt vmcnt(4)
	v_lshlrev_b32_e32 v134, 16, v144
	v_and_b32_e32 v135, 0xffff0000, v144
	s_waitcnt vmcnt(0)
	v_add_f32_e32 v120, v120, v124
	v_add_f32_e32 v121, v121, v125
	v_add_f32_e32 v122, v122, v126
	v_add_f32_e32 v123, v123, v127
	v_mul_f32_e32 v120, 0xbfb8aa3b, v120
	v_mul_f32_e32 v121, 0xbfb8aa3b, v121
	v_mul_f32_e32 v122, 0xbfb8aa3b, v122
	v_mul_f32_e32 v123, 0xbfb8aa3b, v123
	v_exp_f32_e32 v120, v120
	v_exp_f32_e32 v121, v121
	v_exp_f32_e32 v122, v122
	v_exp_f32_e32 v123, v123
	v_add_f32_e32 v120, 1.0, v120
	v_add_f32_e32 v121, 1.0, v121
	v_add_f32_e32 v122, 1.0, v122
	v_add_f32_e32 v123, 1.0, v123
	v_rcp_f32_e32 v120, v120
	v_rcp_f32_e32 v121, v121
	v_rcp_f32_e32 v122, v122
	v_rcp_f32_e32 v123, v123
	v_lshlrev_b32_e32 v124, 16, v145
	v_and_b32_e32 v125, 0xffff0000, v145
	v_pk_mul_f32 v[120:121], v[120:121], v[134:135]
	v_pk_mul_f32 v[122:123], v[122:123], v[124:125]
	v_cvt_pk_bf16_f32 v120, v120, v121
	v_cvt_pk_bf16_f32 v121, v122, v123
	global_store_dwordx2 v[138:139], v[120:121], off offset:32
	global_load_dwordx4 v[120:123], v[128:129], off offset:128
	v_lshlrev_b32_e32 v124, 16, v146
	v_and_b32_e32 v125, 0xffff0000, v146
	v_lshlrev_b32_e32 v126, 16, v140
	v_and_b32_e32 v127, 0xffff0000, v140
	s_waitcnt vmcnt(0)
	v_add_f32_e32 v116, v116, v120
	v_add_f32_e32 v117, v117, v121
	v_add_f32_e32 v118, v118, v122
	v_add_f32_e32 v119, v119, v123
	v_mul_f32_e32 v116, 0xbfb8aa3b, v116
	v_mul_f32_e32 v117, 0xbfb8aa3b, v117
	v_mul_f32_e32 v118, 0xbfb8aa3b, v118
	v_mul_f32_e32 v119, 0xbfb8aa3b, v119
	v_exp_f32_e32 v116, v116
	v_exp_f32_e32 v117, v117
	v_exp_f32_e32 v118, v118
	v_exp_f32_e32 v119, v119
	v_add_f32_e32 v116, 1.0, v116
	v_add_f32_e32 v117, 1.0, v117
	v_add_f32_e32 v118, 1.0, v118
	v_add_f32_e32 v119, 1.0, v119
	v_rcp_f32_e32 v116, v116
	v_rcp_f32_e32 v117, v117
	v_rcp_f32_e32 v118, v118
	v_rcp_f32_e32 v119, v119
	v_lshlrev_b32_e32 v120, 16, v147
	v_and_b32_e32 v121, 0xffff0000, v147
	v_pk_mul_f32 v[116:117], v[116:117], v[124:125]
	v_pk_mul_f32 v[118:119], v[118:119], v[120:121]
	v_cvt_pk_bf16_f32 v116, v116, v117
	v_cvt_pk_bf16_f32 v117, v118, v119
	global_store_dwordx2 v[138:139], v[116:117], off offset:64
	global_load_dwordx4 v[116:119], v[128:129], off offset:192
	v_or_b32_e32 v120, 16, v132
	v_ashrrev_i32_e32 v121, 31, v120
	v_lshlrev_b64 v[120:121], 10, v[120:121]
	v_lshl_add_u64 v[122:123], s[2:3], 0, v[120:121]
	v_lshl_add_u64 v[122:123], v[122:123], 0, v[130:131]
	global_load_dwordx2 v[124:125], v[122:123], off
	s_waitcnt vmcnt(1)
	v_add_f32_e32 v112, v112, v116
	v_add_f32_e32 v113, v113, v117
	v_add_f32_e32 v114, v114, v118
	v_add_f32_e32 v115, v115, v119
	v_mul_f32_e32 v112, 0xbfb8aa3b, v112
	v_mul_f32_e32 v113, 0xbfb8aa3b, v113
	v_mul_f32_e32 v114, 0xbfb8aa3b, v114
	v_mul_f32_e32 v115, 0xbfb8aa3b, v115
	v_exp_f32_e32 v112, v112
	v_exp_f32_e32 v113, v113
	v_exp_f32_e32 v114, v114
	v_exp_f32_e32 v115, v115
	v_add_f32_e32 v112, 1.0, v112
	v_add_f32_e32 v113, 1.0, v113
	v_add_f32_e32 v114, 1.0, v114
	v_add_f32_e32 v115, 1.0, v115
	v_rcp_f32_e32 v112, v112
	v_rcp_f32_e32 v113, v113
	v_rcp_f32_e32 v114, v114
	v_rcp_f32_e32 v115, v115
	v_lshlrev_b32_e32 v116, 16, v141
	v_and_b32_e32 v117, 0xffff0000, v141
	v_pk_mul_f32 v[112:113], v[112:113], v[126:127]
	v_pk_mul_f32 v[114:115], v[114:115], v[116:117]
	v_cvt_pk_bf16_f32 v112, v112, v113
	v_cvt_pk_bf16_f32 v113, v114, v115
	global_store_dwordx2 v[138:139], v[112:113], off offset:96
	global_load_dwordx4 v[112:115], v[128:129], off
	s_waitcnt vmcnt(2)
	v_lshlrev_b32_e32 v126, 16, v124
	v_and_b32_e32 v127, 0xffff0000, v124
	v_lshl_add_u64 v[116:117], s[4:5], 0, v[120:121]
	v_lshl_add_u64 v[116:117], v[116:117], 0, v[130:131]
	global_load_dwordx2 v[118:119], v[122:123], off offset:32
	global_load_dwordx2 v[120:121], v[122:123], off offset:64
	s_nop 0
	global_load_dwordx2 v[122:123], v[122:123], off offset:96
	s_waitcnt vmcnt(3)
	v_add_f32_e32 v108, v108, v112
	v_add_f32_e32 v109, v109, v113
	v_add_f32_e32 v110, v110, v114
	v_add_f32_e32 v111, v111, v115
	v_mul_f32_e32 v108, 0xbfb8aa3b, v108
	v_mul_f32_e32 v109, 0xbfb8aa3b, v109
	v_mul_f32_e32 v110, 0xbfb8aa3b, v110
	v_mul_f32_e32 v111, 0xbfb8aa3b, v111
	v_exp_f32_e32 v108, v108
	v_exp_f32_e32 v109, v109
	v_exp_f32_e32 v110, v110
	v_exp_f32_e32 v111, v111
	v_add_f32_e32 v108, 1.0, v108
	v_add_f32_e32 v109, 1.0, v109
	v_add_f32_e32 v110, 1.0, v110
	v_add_f32_e32 v111, 1.0, v111
	v_rcp_f32_e32 v108, v108
	v_rcp_f32_e32 v109, v109
	v_rcp_f32_e32 v110, v110
	v_rcp_f32_e32 v111, v111
	v_lshlrev_b32_e32 v112, 16, v125
	v_and_b32_e32 v113, 0xffff0000, v125
	v_pk_mul_f32 v[108:109], v[108:109], v[126:127]
	v_pk_mul_f32 v[110:111], v[110:111], v[112:113]
	v_cvt_pk_bf16_f32 v108, v108, v109
	v_cvt_pk_bf16_f32 v109, v110, v111
	global_store_dwordx2 v[116:117], v[108:109], off
	global_load_dwordx4 v[108:111], v[128:129], off offset:64
	s_waitcnt vmcnt(4)
	v_lshlrev_b32_e32 v112, 16, v118
	v_and_b32_e32 v113, 0xffff0000, v118
	s_waitcnt vmcnt(0)
; template <class Epi>
; DI void gemm_tile(char* smem, const bf16_t* __restrict__ A0, int lda0, int ksplit, const bf16_t* __restrict__ A1, int lda1,
;                   const bf16_t* __restrict__ Bt, int K, int row0, int col0, const Epi& epi, int tid) {
;     ...
; #pragma unroll
;   for (int m = 0; m < 8; ++m)
; #pragma unroll
;     for (int n = 0; n < 4; ++n) epi(row0 + wr * 128 + m * 16 + fr, col0 + wc * 64 + n * 16 + fq * 4, acc[m][n]);
	v_add_f32_e32 v104, v104, v108
	v_add_f32_e32 v105, v105, v109
	v_add_f32_e32 v106, v106, v110
	v_add_f32_e32 v107, v107, v111
	v_mul_f32_e32 v104, 0xbfb8aa3b, v104
	v_mul_f32_e32 v105, 0xbfb8aa3b, v105
	v_mul_f32_e32 v106, 0xbfb8aa3b, v106
	v_mul_f32_e32 v107, 0xbfb8aa3b, v107
	v_exp_f32_e32 v104, v104
	v_exp_f32_e32 v105, v105
	v_exp_f32_e32 v106, v106
	v_exp_f32_e32 v107, v107
	v_add_f32_e32 v104, 1.0, v104
	v_add_f32_e32 v105, 1.0, v105
	v_add_f32_e32 v106, 1.0, v106
	v_add_f32_e32 v107, 1.0, v107
	v_rcp_f32_e32 v104, v104
	v_rcp_f32_e32 v105, v105
	v_rcp_f32_e32 v106, v106
	v_rcp_f32_e32 v107, v107
	v_lshlrev_b32_e32 v108, 16, v119
	v_and_b32_e32 v109, 0xffff0000, v119
	v_pk_mul_f32 v[104:105], v[104:105], v[112:113]
	v_pk_mul_f32 v[106:107], v[106:107], v[108:109]
	v_cvt_pk_bf16_f32 v104, v104, v105
	v_cvt_pk_bf16_f32 v105, v106, v107
	global_store_dwordx2 v[116:117], v[104:105], off offset:32
	global_load_dwordx4 v[104:107], v[128:129], off offset:128
	v_lshlrev_b32_e32 v108, 16, v120
	v_and_b32_e32 v109, 0xffff0000, v120
	v_lshlrev_b32_e32 v110, 16, v122
	v_and_b32_e32 v111, 0xffff0000, v122
	s_waitcnt vmcnt(0)
	v_add_f32_e32 v100, v100, v104
	v_add_f32_e32 v101, v101, v105
	v_add_f32_e32 v102, v102, v106
	v_add_f32_e32 v103, v103, v107
	v_mul_f32_e32 v100, 0xbfb8aa3b, v100
	v_mul_f32_e32 v101, 0xbfb8aa3b, v101
	v_mul_f32_e32 v102, 0xbfb8aa3b, v102
	v_mul_f32_e32 v103, 0xbfb8aa3b, v103
	v_exp_f32_e32 v100, v100
	v_exp_f32_e32 v101, v101
	v_exp_f32_e32 v102, v102
	v_exp_f32_e32 v103, v103
	v_add_f32_e32 v100, 1.0, v100
	v_add_f32_e32 v101, 1.0, v101
	v_add_f32_e32 v102, 1.0, v102
	v_add_f32_e32 v103, 1.0, v103
	v_rcp_f32_e32 v100, v100
	v_rcp_f32_e32 v101, v101
	v_rcp_f32_e32 v102, v102
	v_rcp_f32_e32 v103, v103
	v_lshlrev_b32_e32 v104, 16, v121
	v_and_b32_e32 v105, 0xffff0000, v121
	v_pk_mul_f32 v[100:101], v[100:101], v[108:109]
	v_pk_mul_f32 v[102:103], v[102:103], v[104:105]
	v_cvt_pk_bf16_f32 v100, v100, v101
	v_cvt_pk_bf16_f32 v101, v102, v103
	global_store_dwordx2 v[116:117], v[100:101], off offset:64
	global_load_dwordx4 v[100:103], v[128:129], off offset:192
	v_or_b32_e32 v104, 32, v132
	v_ashrrev_i32_e32 v105, 31, v104
	v_lshlrev_b64 v[104:105], 10, v[104:105]
	v_lshl_add_u64 v[106:107], s[2:3], 0, v[104:105]
	v_lshl_add_u64 v[106:107], v[106:107], 0, v[130:131]
	global_load_dwordx2 v[108:109], v[106:107], off
	s_waitcnt vmcnt(1)
	v_add_f32_e32 v96, v96, v100
	v_add_f32_e32 v97, v97, v101
	v_add_f32_e32 v98, v98, v102
	v_add_f32_e32 v99, v99, v103
	v_mul_f32_e32 v96, 0xbfb8aa3b, v96
	v_mul_f32_e32 v97, 0xbfb8aa3b, v97
	v_mul_f32_e32 v98, 0xbfb8aa3b, v98
	v_mul_f32_e32 v99, 0xbfb8aa3b, v99
	v_exp_f32_e32 v96, v96
	v_exp_f32_e32 v97, v97
	v_exp_f32_e32 v98, v98
	v_exp_f32_e32 v99, v99
	v_add_f32_e32 v96, 1.0, v96
	v_add_f32_e32 v97, 1.0, v97
	v_add_f32_e32 v98, 1.0, v98
	v_add_f32_e32 v99, 1.0, v99
	v_rcp_f32_e32 v96, v96
	v_rcp_f32_e32 v97, v97
	v_rcp_f32_e32 v98, v98
	v_rcp_f32_e32 v99, v99
	v_lshlrev_b32_e32 v100, 16, v123
	v_and_b32_e32 v101, 0xffff0000, v123
	v_pk_mul_f32 v[96:97], v[96:97], v[110:111]
	v_pk_mul_f32 v[98:99], v[98:99], v[100:101]
	v_cvt_pk_bf16_f32 v96, v96, v97
	v_cvt_pk_bf16_f32 v97, v98, v99
	global_store_dwordx2 v[116:117], v[96:97], off offset:96
	global_load_dwordx4 v[96:99], v[128:129], off
	s_waitcnt vmcnt(2)
	v_lshlrev_b32_e32 v110, 16, v108
	v_and_b32_e32 v111, 0xffff0000, v108
	v_lshl_add_u64 v[100:101], s[4:5], 0, v[104:105]
	v_lshl_add_u64 v[100:101], v[100:101], 0, v[130:131]
	global_load_dwordx2 v[102:103], v[106:107], off offset:32
	global_load_dwordx2 v[104:105], v[106:107], off offset:64
	s_nop 0
	global_load_dwordx2 v[106:107], v[106:107], off offset:96
	s_waitcnt vmcnt(3)
	v_add_f32_e32 v92, v92, v96
	v_add_f32_e32 v93, v93, v97
	v_add_f32_e32 v94, v94, v98
	v_add_f32_e32 v95, v95, v99
	v_mul_f32_e32 v92, 0xbfb8aa3b, v92
	v_mul_f32_e32 v93, 0xbfb8aa3b, v93
	v_mul_f32_e32 v94, 0xbfb8aa3b, v94
	v_mul_f32_e32 v95, 0xbfb8aa3b, v95
	v_exp_f32_e32 v92, v92
	v_exp_f32_e32 v93, v93
	v_exp_f32_e32 v94, v94
	v_exp_f32_e32 v95, v95
	v_add_f32_e32 v92, 1.0, v92
	v_add_f32_e32 v93, 1.0, v93
	v_add_f32_e32 v94, 1.0, v94
	v_add_f32_e32 v95, 1.0, v95
	v_rcp_f32_e32 v92, v92
	v_rcp_f32_e32 v93, v93
	v_rcp_f32_e32 v94, v94
	v_rcp_f32_e32 v95, v95
	v_lshlrev_b32_e32 v96, 16, v109
	v_and_b32_e32 v97, 0xffff0000, v109
	v_pk_mul_f32 v[92:93], v[92:93], v[110:111]
	v_pk_mul_f32 v[94:95], v[94:95], v[96:97]
	v_cvt_pk_bf16_f32 v92, v92, v93
	v_cvt_pk_bf16_f32 v93, v94, v95
	global_store_dwordx2 v[100:101], v[92:93], off
	global_load_dwordx4 v[92:95], v[128:129], off offset:64
	s_waitcnt vmcnt(4)
	v_lshlrev_b32_e32 v96, 16, v102
	v_and_b32_e32 v97, 0xffff0000, v102
	s_waitcnt vmcnt(0)
	v_add_f32_e32 v88, v88, v92
	v_add_f32_e32 v89, v89, v93
	v_add_f32_e32 v90, v90, v94
	v_add_f32_e32 v91, v91, v95
	v_mul_f32_e32 v88, 0xbfb8aa3b, v88
	v_mul_f32_e32 v89, 0xbfb8aa3b, v89
	v_mul_f32_e32 v90, 0xbfb8aa3b, v90
	v_mul_f32_e32 v91, 0xbfb8aa3b, v91
	v_exp_f32_e32 v88, v88
	v_exp_f32_e32 v89, v89
	v_exp_f32_e32 v90, v90
	v_exp_f32_e32 v91, v91
	v_add_f32_e32 v88, 1.0, v88
	v_add_f32_e32 v89, 1.0, v89
	v_add_f32_e32 v90, 1.0, v90
	v_add_f32_e32 v91, 1.0, v91
	v_rcp_f32_e32 v88, v88
	v_rcp_f32_e32 v89, v89
	v_rcp_f32_e32 v90, v90
	v_rcp_f32_e32 v91, v91
	v_lshlrev_b32_e32 v92, 16, v103
	v_and_b32_e32 v93, 0xffff0000, v103
	v_pk_mul_f32 v[88:89], v[88:89], v[96:97]
	v_pk_mul_f32 v[90:91], v[90:91], v[92:93]
	v_cvt_pk_bf16_f32 v88, v88, v89
	v_cvt_pk_bf16_f32 v89, v90, v91
	global_store_dwordx2 v[100:101], v[88:89], off offset:32
	global_load_dwordx4 v[88:91], v[128:129], off offset:128
	v_lshlrev_b32_e32 v92, 16, v104
	v_and_b32_e32 v93, 0xffff0000, v104
	v_lshlrev_b32_e32 v94, 16, v106
	v_and_b32_e32 v95, 0xffff0000, v106
	s_waitcnt vmcnt(0)
; template <class Epi>
; DI void gemm_tile(char* smem, const bf16_t* __restrict__ A0, int lda0, int ksplit, const bf16_t* __restrict__ A1, int lda1,
;                   const bf16_t* __restrict__ Bt, int K, int row0, int col0, const Epi& epi, int tid) {
;     ...
; #pragma unroll
;   for (int m = 0; m < 8; ++m)
; #pragma unroll
;     for (int n = 0; n < 4; ++n) epi(row0 + wr * 128 + m * 16 + fr, col0 + wc * 64 + n * 16 + fq * 4, acc[m][n]);
	v_add_f32_e32 v84, v84, v88
	v_add_f32_e32 v85, v85, v89
	v_add_f32_e32 v86, v86, v90
	v_add_f32_e32 v87, v87, v91
	v_mul_f32_e32 v84, 0xbfb8aa3b, v84
	v_mul_f32_e32 v85, 0xbfb8aa3b, v85
	v_mul_f32_e32 v86, 0xbfb8aa3b, v86
	v_mul_f32_e32 v87, 0xbfb8aa3b, v87
	v_exp_f32_e32 v84, v84
	v_exp_f32_e32 v85, v85
	v_exp_f32_e32 v86, v86
	v_exp_f32_e32 v87, v87
	v_add_f32_e32 v84, 1.0, v84
	v_add_f32_e32 v85, 1.0, v85
	v_add_f32_e32 v86, 1.0, v86
	v_add_f32_e32 v87, 1.0, v87
	v_rcp_f32_e32 v84, v84
	v_rcp_f32_e32 v85, v85
	v_rcp_f32_e32 v86, v86
	v_rcp_f32_e32 v87, v87
	v_lshlrev_b32_e32 v88, 16, v105
	v_and_b32_e32 v89, 0xffff0000, v105
	v_pk_mul_f32 v[84:85], v[84:85], v[92:93]
	v_pk_mul_f32 v[86:87], v[86:87], v[88:89]
	v_cvt_pk_bf16_f32 v84, v84, v85
	v_cvt_pk_bf16_f32 v85, v86, v87
	global_store_dwordx2 v[100:101], v[84:85], off offset:64
	global_load_dwordx4 v[84:87], v[128:129], off offset:192
	v_or_b32_e32 v88, 48, v132
	v_ashrrev_i32_e32 v89, 31, v88
	v_lshlrev_b64 v[88:89], 10, v[88:89]
	v_lshl_add_u64 v[90:91], s[2:3], 0, v[88:89]
	v_lshl_add_u64 v[90:91], v[90:91], 0, v[130:131]
	global_load_dwordx2 v[92:93], v[90:91], off
	s_waitcnt vmcnt(1)
	v_add_f32_e32 v80, v80, v84
	v_add_f32_e32 v81, v81, v85
	v_add_f32_e32 v82, v82, v86
	v_add_f32_e32 v83, v83, v87
	v_mul_f32_e32 v80, 0xbfb8aa3b, v80
	v_mul_f32_e32 v81, 0xbfb8aa3b, v81
	v_mul_f32_e32 v82, 0xbfb8aa3b, v82
	v_mul_f32_e32 v83, 0xbfb8aa3b, v83
	v_exp_f32_e32 v80, v80
	v_exp_f32_e32 v81, v81
	v_exp_f32_e32 v82, v82
	v_exp_f32_e32 v83, v83
	v_add_f32_e32 v80, 1.0, v80
	v_add_f32_e32 v81, 1.0, v81
	v_add_f32_e32 v82, 1.0, v82
	v_add_f32_e32 v83, 1.0, v83
	v_rcp_f32_e32 v80, v80
	v_rcp_f32_e32 v81, v81
	v_rcp_f32_e32 v82, v82
	v_rcp_f32_e32 v83, v83
	v_lshlrev_b32_e32 v84, 16, v107
	v_and_b32_e32 v85, 0xffff0000, v107
	v_pk_mul_f32 v[80:81], v[80:81], v[94:95]
	v_pk_mul_f32 v[82:83], v[82:83], v[84:85]
	v_cvt_pk_bf16_f32 v80, v80, v81
	v_cvt_pk_bf16_f32 v81, v82, v83
	global_store_dwordx2 v[100:101], v[80:81], off offset:96
	global_load_dwordx4 v[82:85], v[128:129], off
	v_lshl_add_u64 v[80:81], s[4:5], 0, v[88:89]
	global_load_dwordx2 v[86:87], v[90:91], off offset:32
	global_load_dwordx2 v[88:89], v[90:91], off offset:64
	global_load_dwordx2 v[94:95], v[90:91], off offset:96
	s_waitcnt vmcnt(5)
	v_lshlrev_b32_e32 v90, 16, v92
	v_and_b32_e32 v91, 0xffff0000, v92
	v_lshl_add_u64 v[80:81], v[80:81], 0, v[130:131]
	s_waitcnt vmcnt(3)
	v_add_f32_e32 v76, v76, v82
	v_add_f32_e32 v77, v77, v83
	v_add_f32_e32 v78, v78, v84
	v_add_f32_e32 v79, v79, v85
	v_mul_f32_e32 v76, 0xbfb8aa3b, v76
	v_mul_f32_e32 v77, 0xbfb8aa3b, v77
	v_mul_f32_e32 v78, 0xbfb8aa3b, v78
	v_mul_f32_e32 v79, 0xbfb8aa3b, v79
	v_exp_f32_e32 v76, v76
	v_exp_f32_e32 v77, v77
	v_exp_f32_e32 v78, v78
	v_exp_f32_e32 v79, v79
	v_add_f32_e32 v76, 1.0, v76
	v_add_f32_e32 v77, 1.0, v77
	v_add_f32_e32 v78, 1.0, v78
	v_add_f32_e32 v79, 1.0, v79
	v_rcp_f32_e32 v76, v76
	v_rcp_f32_e32 v77, v77
	v_rcp_f32_e32 v78, v78
	v_rcp_f32_e32 v79, v79
	v_lshlrev_b32_e32 v82, 16, v93
	v_and_b32_e32 v83, 0xffff0000, v93
	v_pk_mul_f32 v[76:77], v[76:77], v[90:91]
	v_pk_mul_f32 v[78:79], v[78:79], v[82:83]
	v_cvt_pk_bf16_f32 v76, v76, v77
	v_cvt_pk_bf16_f32 v77, v78, v79
	global_store_dwordx2 v[80:81], v[76:77], off
	global_load_dwordx4 v[76:79], v[128:129], off offset:64
	s_waitcnt vmcnt(4)
	v_lshlrev_b32_e32 v82, 16, v86
	v_and_b32_e32 v83, 0xffff0000, v86
	s_waitcnt vmcnt(0)
	v_add_f32_e32 v72, v72, v76
	v_add_f32_e32 v73, v73, v77
	v_add_f32_e32 v74, v74, v78
	v_add_f32_e32 v75, v75, v79
	v_mul_f32_e32 v72, 0xbfb8aa3b, v72
	v_mul_f32_e32 v73, 0xbfb8aa3b, v73
	v_mul_f32_e32 v74, 0xbfb8aa3b, v74
	v_mul_f32_e32 v75, 0xbfb8aa3b, v75
	v_exp_f32_e32 v72, v72
	v_exp_f32_e32 v73, v73
	v_exp_f32_e32 v74, v74
	v_exp_f32_e32 v75, v75
	v_add_f32_e32 v72, 1.0, v72
	v_add_f32_e32 v73, 1.0, v73
	v_add_f32_e32 v74, 1.0, v74
	v_add_f32_e32 v75, 1.0, v75
	v_rcp_f32_e32 v72, v72
	v_rcp_f32_e32 v73, v73
	v_rcp_f32_e32 v74, v74
	v_rcp_f32_e32 v75, v75
	v_lshlrev_b32_e32 v76, 16, v87
	v_and_b32_e32 v77, 0xffff0000, v87
	v_pk_mul_f32 v[72:73], v[72:73], v[82:83]
	v_pk_mul_f32 v[74:75], v[74:75], v[76:77]
	v_cvt_pk_bf16_f32 v72, v72, v73
	v_cvt_pk_bf16_f32 v73, v74, v75
	global_store_dwordx2 v[80:81], v[72:73], off offset:32
	global_load_dwordx4 v[72:75], v[128:129], off offset:128
	v_lshlrev_b32_e32 v76, 16, v88
	v_and_b32_e32 v77, 0xffff0000, v88
	v_lshlrev_b32_e32 v78, 16, v94
	v_and_b32_e32 v79, 0xffff0000, v94
	s_waitcnt vmcnt(0)
	v_add_f32_e32 v68, v68, v72
	v_add_f32_e32 v69, v69, v73
	v_add_f32_e32 v70, v70, v74
	v_add_f32_e32 v71, v71, v75
	v_mul_f32_e32 v68, 0xbfb8aa3b, v68
	v_mul_f32_e32 v69, 0xbfb8aa3b, v69
	v_mul_f32_e32 v70, 0xbfb8aa3b, v70
	v_mul_f32_e32 v71, 0xbfb8aa3b, v71
	v_exp_f32_e32 v68, v68
	v_exp_f32_e32 v69, v69
	v_exp_f32_e32 v70, v70
	v_exp_f32_e32 v71, v71
	v_add_f32_e32 v68, 1.0, v68
	v_add_f32_e32 v69, 1.0, v69
	v_add_f32_e32 v70, 1.0, v70
	v_add_f32_e32 v71, 1.0, v71
	v_rcp_f32_e32 v68, v68
	v_rcp_f32_e32 v69, v69
	v_rcp_f32_e32 v70, v70
	v_rcp_f32_e32 v71, v71
	v_lshlrev_b32_e32 v72, 16, v89
	v_and_b32_e32 v73, 0xffff0000, v89
	v_pk_mul_f32 v[68:69], v[68:69], v[76:77]
	v_pk_mul_f32 v[70:71], v[70:71], v[72:73]
	v_cvt_pk_bf16_f32 v68, v68, v69
	v_cvt_pk_bf16_f32 v69, v70, v71
	global_store_dwordx2 v[80:81], v[68:69], off offset:64
	global_load_dwordx4 v[68:71], v[128:129], off offset:192
	v_or_b32_e32 v72, 64, v132
	v_ashrrev_i32_e32 v73, 31, v72
	v_lshlrev_b64 v[72:73], 10, v[72:73]
	v_lshl_add_u64 v[74:75], s[2:3], 0, v[72:73]
	v_lshl_add_u64 v[74:75], v[74:75], 0, v[130:131]
	global_load_dwordx2 v[76:77], v[74:75], off
	s_waitcnt vmcnt(1)
; template <class Epi>
; DI void gemm_tile(char* smem, const bf16_t* __restrict__ A0, int lda0, int ksplit, const bf16_t* __restrict__ A1, int lda1,
;                   const bf16_t* __restrict__ Bt, int K, int row0, int col0, const Epi& epi, int tid) {
;     ...
; #pragma unroll
;   for (int m = 0; m < 8; ++m)
; #pragma unroll
;     for (int n = 0; n < 4; ++n) epi(row0 + wr * 128 + m * 16 + fr, col0 + wc * 64 + n * 16 + fq * 4, acc[m][n]);
	v_add_f32_e32 v64, v64, v68
	v_add_f32_e32 v65, v65, v69
	v_add_f32_e32 v66, v66, v70
	v_add_f32_e32 v67, v67, v71
	v_mul_f32_e32 v64, 0xbfb8aa3b, v64
	v_mul_f32_e32 v65, 0xbfb8aa3b, v65
	v_mul_f32_e32 v66, 0xbfb8aa3b, v66
	v_mul_f32_e32 v67, 0xbfb8aa3b, v67
	v_exp_f32_e32 v64, v64
	v_exp_f32_e32 v65, v65
	v_exp_f32_e32 v66, v66
	v_exp_f32_e32 v67, v67
	v_add_f32_e32 v64, 1.0, v64
	v_add_f32_e32 v65, 1.0, v65
	v_add_f32_e32 v66, 1.0, v66
	v_add_f32_e32 v67, 1.0, v67
	v_rcp_f32_e32 v64, v64
	v_rcp_f32_e32 v65, v65
	v_rcp_f32_e32 v66, v66
	v_rcp_f32_e32 v67, v67
	v_lshlrev_b32_e32 v68, 16, v95
	v_and_b32_e32 v69, 0xffff0000, v95
	v_pk_mul_f32 v[64:65], v[64:65], v[78:79]
	v_pk_mul_f32 v[66:67], v[66:67], v[68:69]
	v_cvt_pk_bf16_f32 v64, v64, v65
	v_cvt_pk_bf16_f32 v65, v66, v67
	global_store_dwordx2 v[80:81], v[64:65], off offset:96
	global_load_dwordx4 v[66:69], v[128:129], off
	v_lshl_add_u64 v[64:65], s[4:5], 0, v[72:73]
	global_load_dwordx2 v[70:71], v[74:75], off offset:32
	global_load_dwordx2 v[72:73], v[74:75], off offset:64
	global_load_dwordx2 v[78:79], v[74:75], off offset:96
	s_waitcnt vmcnt(5)
	v_lshlrev_b32_e32 v74, 16, v76
	v_and_b32_e32 v75, 0xffff0000, v76
	v_lshl_add_u64 v[64:65], v[64:65], 0, v[130:131]
	s_waitcnt vmcnt(3)
	v_add_f32_e32 v60, v60, v66
	v_add_f32_e32 v61, v61, v67
	v_add_f32_e32 v62, v62, v68
	v_add_f32_e32 v63, v63, v69
	v_mul_f32_e32 v60, 0xbfb8aa3b, v60
	v_mul_f32_e32 v61, 0xbfb8aa3b, v61
	v_mul_f32_e32 v62, 0xbfb8aa3b, v62
	v_mul_f32_e32 v63, 0xbfb8aa3b, v63
	v_exp_f32_e32 v60, v60
	v_exp_f32_e32 v61, v61
	v_exp_f32_e32 v62, v62
	v_exp_f32_e32 v63, v63
	v_add_f32_e32 v60, 1.0, v60
	v_add_f32_e32 v61, 1.0, v61
	v_add_f32_e32 v62, 1.0, v62
	v_add_f32_e32 v63, 1.0, v63
	v_rcp_f32_e32 v60, v60
	v_rcp_f32_e32 v61, v61
	v_rcp_f32_e32 v62, v62
	v_rcp_f32_e32 v63, v63
	v_lshlrev_b32_e32 v66, 16, v77
	v_and_b32_e32 v67, 0xffff0000, v77
	v_pk_mul_f32 v[60:61], v[60:61], v[74:75]
	v_pk_mul_f32 v[62:63], v[62:63], v[66:67]
	v_cvt_pk_bf16_f32 v60, v60, v61
	v_cvt_pk_bf16_f32 v61, v62, v63
	global_store_dwordx2 v[64:65], v[60:61], off
	global_load_dwordx4 v[60:63], v[128:129], off offset:64
	s_waitcnt vmcnt(4)
	v_lshlrev_b32_e32 v66, 16, v70
	v_and_b32_e32 v67, 0xffff0000, v70
	s_waitcnt vmcnt(0)
	v_add_f32_e32 v56, v56, v60
	v_add_f32_e32 v57, v57, v61
	v_add_f32_e32 v58, v58, v62
	v_add_f32_e32 v59, v59, v63
	v_mul_f32_e32 v56, 0xbfb8aa3b, v56
	v_mul_f32_e32 v57, 0xbfb8aa3b, v57
	v_mul_f32_e32 v58, 0xbfb8aa3b, v58
	v_mul_f32_e32 v59, 0xbfb8aa3b, v59
	v_exp_f32_e32 v56, v56
	v_exp_f32_e32 v57, v57
	v_exp_f32_e32 v58, v58
	v_exp_f32_e32 v59, v59
	v_add_f32_e32 v56, 1.0, v56
	v_add_f32_e32 v57, 1.0, v57
	v_add_f32_e32 v58, 1.0, v58
	v_add_f32_e32 v59, 1.0, v59
	v_rcp_f32_e32 v56, v56
	v_rcp_f32_e32 v57, v57
	v_rcp_f32_e32 v58, v58
	v_rcp_f32_e32 v59, v59
	v_lshlrev_b32_e32 v60, 16, v71
	v_and_b32_e32 v61, 0xffff0000, v71
	v_pk_mul_f32 v[56:57], v[56:57], v[66:67]
	v_pk_mul_f32 v[58:59], v[58:59], v[60:61]
	v_cvt_pk_bf16_f32 v56, v56, v57
	v_cvt_pk_bf16_f32 v57, v58, v59
	global_store_dwordx2 v[64:65], v[56:57], off offset:32
	global_load_dwordx4 v[56:59], v[128:129], off offset:128
	v_lshlrev_b32_e32 v60, 16, v72
	v_and_b32_e32 v61, 0xffff0000, v72
	v_lshlrev_b32_e32 v62, 16, v78
	v_and_b32_e32 v63, 0xffff0000, v78
	s_waitcnt vmcnt(0)
	v_add_f32_e32 v52, v52, v56
	v_add_f32_e32 v53, v53, v57
	v_add_f32_e32 v54, v54, v58
	v_add_f32_e32 v55, v55, v59
	v_mul_f32_e32 v52, 0xbfb8aa3b, v52
	v_mul_f32_e32 v53, 0xbfb8aa3b, v53
	v_mul_f32_e32 v54, 0xbfb8aa3b, v54
	v_mul_f32_e32 v55, 0xbfb8aa3b, v55
	v_exp_f32_e32 v52, v52
	v_exp_f32_e32 v53, v53
	v_exp_f32_e32 v54, v54
	v_exp_f32_e32 v55, v55
	v_add_f32_e32 v52, 1.0, v52
	v_add_f32_e32 v53, 1.0, v53
	v_add_f32_e32 v54, 1.0, v54
	v_add_f32_e32 v55, 1.0, v55
	v_rcp_f32_e32 v52, v52
	v_rcp_f32_e32 v53, v53
	v_rcp_f32_e32 v54, v54
	v_rcp_f32_e32 v55, v55
	v_lshlrev_b32_e32 v56, 16, v73
	v_and_b32_e32 v57, 0xffff0000, v73
	v_pk_mul_f32 v[52:53], v[52:53], v[60:61]
	v_pk_mul_f32 v[54:55], v[54:55], v[56:57]
	v_cvt_pk_bf16_f32 v52, v52, v53
	v_cvt_pk_bf16_f32 v53, v54, v55
	global_store_dwordx2 v[64:65], v[52:53], off offset:64
	global_load_dwordx4 v[52:55], v[128:129], off offset:192
	v_or_b32_e32 v56, 0x50, v132
	v_ashrrev_i32_e32 v57, 31, v56
	v_lshlrev_b64 v[56:57], 10, v[56:57]
	v_lshl_add_u64 v[58:59], s[2:3], 0, v[56:57]
	v_lshl_add_u64 v[58:59], v[58:59], 0, v[130:131]
	global_load_dwordx2 v[60:61], v[58:59], off
	s_waitcnt vmcnt(1)
	v_add_f32_e32 v48, v48, v52
	v_add_f32_e32 v49, v49, v53
	v_add_f32_e32 v50, v50, v54
	v_add_f32_e32 v51, v51, v55
	v_mul_f32_e32 v48, 0xbfb8aa3b, v48
	v_mul_f32_e32 v49, 0xbfb8aa3b, v49
	v_mul_f32_e32 v50, 0xbfb8aa3b, v50
	v_mul_f32_e32 v51, 0xbfb8aa3b, v51
	v_exp_f32_e32 v48, v48
	v_exp_f32_e32 v49, v49
	v_exp_f32_e32 v50, v50
	v_exp_f32_e32 v51, v51
	v_add_f32_e32 v48, 1.0, v48
	v_add_f32_e32 v49, 1.0, v49
	v_add_f32_e32 v50, 1.0, v50
	v_add_f32_e32 v51, 1.0, v51
	v_rcp_f32_e32 v48, v48
	v_rcp_f32_e32 v49, v49
	v_rcp_f32_e32 v50, v50
	v_rcp_f32_e32 v51, v51
	v_lshlrev_b32_e32 v52, 16, v79
	v_and_b32_e32 v53, 0xffff0000, v79
	v_pk_mul_f32 v[48:49], v[48:49], v[62:63]
	v_pk_mul_f32 v[50:51], v[50:51], v[52:53]
	v_cvt_pk_bf16_f32 v48, v48, v49
	v_cvt_pk_bf16_f32 v49, v50, v51
	global_store_dwordx2 v[64:65], v[48:49], off offset:96
	global_load_dwordx4 v[50:53], v[128:129], off
	v_lshl_add_u64 v[48:49], s[4:5], 0, v[56:57]
	global_load_dwordx2 v[54:55], v[58:59], off offset:32
	global_load_dwordx2 v[56:57], v[58:59], off offset:64
	global_load_dwordx2 v[62:63], v[58:59], off offset:96
	s_waitcnt vmcnt(5)
; template <class Epi>
; DI void gemm_tile(char* smem, const bf16_t* __restrict__ A0, int lda0, int ksplit, const bf16_t* __restrict__ A1, int lda1,
;                   const bf16_t* __restrict__ Bt, int K, int row0, int col0, const Epi& epi, int tid) {
;     ...
; #pragma unroll
;   for (int m = 0; m < 8; ++m)
; #pragma unroll
;     for (int n = 0; n < 4; ++n) epi(row0 + wr * 128 + m * 16 + fr, col0 + wc * 64 + n * 16 + fq * 4, acc[m][n]);
	v_lshlrev_b32_e32 v58, 16, v60
	v_and_b32_e32 v59, 0xffff0000, v60
	v_lshl_add_u64 v[48:49], v[48:49], 0, v[130:131]
	s_waitcnt vmcnt(3)
	v_add_f32_e32 v44, v44, v50
	v_add_f32_e32 v45, v45, v51
	v_add_f32_e32 v46, v46, v52
	v_add_f32_e32 v47, v47, v53
	v_mul_f32_e32 v44, 0xbfb8aa3b, v44
	v_mul_f32_e32 v45, 0xbfb8aa3b, v45
	v_mul_f32_e32 v46, 0xbfb8aa3b, v46
	v_mul_f32_e32 v47, 0xbfb8aa3b, v47
	v_exp_f32_e32 v44, v44
	v_exp_f32_e32 v45, v45
	v_exp_f32_e32 v46, v46
	v_exp_f32_e32 v47, v47
	v_add_f32_e32 v44, 1.0, v44
	v_add_f32_e32 v45, 1.0, v45
	v_add_f32_e32 v46, 1.0, v46
	v_add_f32_e32 v47, 1.0, v47
	v_rcp_f32_e32 v44, v44
	v_rcp_f32_e32 v45, v45
	v_rcp_f32_e32 v46, v46
	v_rcp_f32_e32 v47, v47
	v_lshlrev_b32_e32 v50, 16, v61
	v_and_b32_e32 v51, 0xffff0000, v61
	v_pk_mul_f32 v[44:45], v[44:45], v[58:59]
	v_pk_mul_f32 v[46:47], v[46:47], v[50:51]
	v_cvt_pk_bf16_f32 v44, v44, v45
	v_cvt_pk_bf16_f32 v45, v46, v47
	global_store_dwordx2 v[48:49], v[44:45], off
	global_load_dwordx4 v[44:47], v[128:129], off offset:64
	s_waitcnt vmcnt(4)
	v_lshlrev_b32_e32 v50, 16, v54
	v_and_b32_e32 v51, 0xffff0000, v54
	s_waitcnt vmcnt(0)
	v_add_f32_e32 v40, v40, v44
	v_add_f32_e32 v41, v41, v45
	v_add_f32_e32 v42, v42, v46
	v_add_f32_e32 v43, v43, v47
	v_mul_f32_e32 v40, 0xbfb8aa3b, v40
	v_mul_f32_e32 v41, 0xbfb8aa3b, v41
	v_mul_f32_e32 v42, 0xbfb8aa3b, v42
	v_mul_f32_e32 v43, 0xbfb8aa3b, v43
	v_exp_f32_e32 v40, v40
	v_exp_f32_e32 v41, v41
	v_exp_f32_e32 v42, v42
	v_exp_f32_e32 v43, v43
	v_add_f32_e32 v40, 1.0, v40
	v_add_f32_e32 v41, 1.0, v41
	v_add_f32_e32 v42, 1.0, v42
	v_add_f32_e32 v43, 1.0, v43
	v_rcp_f32_e32 v40, v40
	v_rcp_f32_e32 v41, v41
	v_rcp_f32_e32 v42, v42
	v_rcp_f32_e32 v43, v43
	v_lshlrev_b32_e32 v44, 16, v55
	v_and_b32_e32 v45, 0xffff0000, v55
	v_pk_mul_f32 v[40:41], v[40:41], v[50:51]
	v_pk_mul_f32 v[42:43], v[42:43], v[44:45]
	v_cvt_pk_bf16_f32 v40, v40, v41
	v_cvt_pk_bf16_f32 v41, v42, v43
	global_store_dwordx2 v[48:49], v[40:41], off offset:32
	global_load_dwordx4 v[40:43], v[128:129], off offset:128
	v_lshlrev_b32_e32 v44, 16, v56
	v_and_b32_e32 v45, 0xffff0000, v56
	v_lshlrev_b32_e32 v46, 16, v62
	v_and_b32_e32 v47, 0xffff0000, v62
	s_waitcnt vmcnt(0)
	v_add_f32_e32 v36, v36, v40
	v_add_f32_e32 v37, v37, v41
	v_add_f32_e32 v38, v38, v42
	v_add_f32_e32 v39, v39, v43
	v_mul_f32_e32 v36, 0xbfb8aa3b, v36
	v_mul_f32_e32 v37, 0xbfb8aa3b, v37
	v_mul_f32_e32 v38, 0xbfb8aa3b, v38
	v_mul_f32_e32 v39, 0xbfb8aa3b, v39
	v_exp_f32_e32 v36, v36
	v_exp_f32_e32 v37, v37
	v_exp_f32_e32 v38, v38
	v_exp_f32_e32 v39, v39
	v_add_f32_e32 v36, 1.0, v36
	v_add_f32_e32 v37, 1.0, v37
	v_add_f32_e32 v38, 1.0, v38
	v_add_f32_e32 v39, 1.0, v39
	v_rcp_f32_e32 v36, v36
	v_rcp_f32_e32 v37, v37
	v_rcp_f32_e32 v38, v38
	v_rcp_f32_e32 v39, v39
	v_lshlrev_b32_e32 v40, 16, v57
	v_and_b32_e32 v41, 0xffff0000, v57
	v_pk_mul_f32 v[36:37], v[36:37], v[44:45]
	v_pk_mul_f32 v[38:39], v[38:39], v[40:41]
	v_cvt_pk_bf16_f32 v36, v36, v37
	v_cvt_pk_bf16_f32 v37, v38, v39
	global_store_dwordx2 v[48:49], v[36:37], off offset:64
	global_load_dwordx4 v[36:39], v[128:129], off offset:192
	v_or_b32_e32 v40, 0x60, v132
	v_ashrrev_i32_e32 v41, 31, v40
	v_lshlrev_b64 v[40:41], 10, v[40:41]
	v_lshl_add_u64 v[42:43], s[2:3], 0, v[40:41]
	v_lshl_add_u64 v[42:43], v[42:43], 0, v[130:131]
	global_load_dwordx2 v[44:45], v[42:43], off
	s_waitcnt vmcnt(1)
	v_add_f32_e32 v32, v32, v36
	v_add_f32_e32 v33, v33, v37
	v_add_f32_e32 v34, v34, v38
	v_add_f32_e32 v35, v35, v39
	v_mul_f32_e32 v32, 0xbfb8aa3b, v32
	v_mul_f32_e32 v33, 0xbfb8aa3b, v33
	v_mul_f32_e32 v34, 0xbfb8aa3b, v34
	v_mul_f32_e32 v35, 0xbfb8aa3b, v35
	v_exp_f32_e32 v32, v32
	v_exp_f32_e32 v33, v33
	v_exp_f32_e32 v34, v34
	v_exp_f32_e32 v35, v35
	v_add_f32_e32 v32, 1.0, v32
	v_add_f32_e32 v33, 1.0, v33
	v_add_f32_e32 v34, 1.0, v34
	v_add_f32_e32 v35, 1.0, v35
	v_rcp_f32_e32 v32, v32
	v_rcp_f32_e32 v33, v33
	v_rcp_f32_e32 v34, v34
	v_rcp_f32_e32 v35, v35
	v_lshlrev_b32_e32 v36, 16, v63
	v_and_b32_e32 v37, 0xffff0000, v63
	v_pk_mul_f32 v[32:33], v[32:33], v[46:47]
	v_pk_mul_f32 v[34:35], v[34:35], v[36:37]
	v_cvt_pk_bf16_f32 v32, v32, v33
	v_cvt_pk_bf16_f32 v33, v34, v35
	global_store_dwordx2 v[48:49], v[32:33], off offset:96
	global_load_dwordx4 v[34:37], v[128:129], off
	v_lshl_add_u64 v[32:33], s[4:5], 0, v[40:41]
	global_load_dwordx2 v[38:39], v[42:43], off offset:32
	global_load_dwordx2 v[40:41], v[42:43], off offset:64
	global_load_dwordx2 v[46:47], v[42:43], off offset:96
	s_waitcnt vmcnt(5)
	v_lshlrev_b32_e32 v42, 16, v44
	v_and_b32_e32 v43, 0xffff0000, v44
	v_lshl_add_u64 v[32:33], v[32:33], 0, v[130:131]
	s_waitcnt vmcnt(3)
	v_add_f32_e32 v28, v28, v34
	v_add_f32_e32 v29, v29, v35
	v_add_f32_e32 v30, v30, v36
	v_add_f32_e32 v31, v31, v37
	v_mul_f32_e32 v28, 0xbfb8aa3b, v28
	v_mul_f32_e32 v29, 0xbfb8aa3b, v29
	v_mul_f32_e32 v30, 0xbfb8aa3b, v30
	v_mul_f32_e32 v31, 0xbfb8aa3b, v31
	v_exp_f32_e32 v28, v28
	v_exp_f32_e32 v29, v29
	v_exp_f32_e32 v30, v30
	v_exp_f32_e32 v31, v31
	v_add_f32_e32 v28, 1.0, v28
	v_add_f32_e32 v29, 1.0, v29
	v_add_f32_e32 v30, 1.0, v30
	v_add_f32_e32 v31, 1.0, v31
	v_rcp_f32_e32 v28, v28
	v_rcp_f32_e32 v29, v29
	v_rcp_f32_e32 v30, v30
	v_rcp_f32_e32 v31, v31
	v_lshlrev_b32_e32 v34, 16, v45
	v_and_b32_e32 v35, 0xffff0000, v45
	v_pk_mul_f32 v[28:29], v[28:29], v[42:43]
	v_pk_mul_f32 v[30:31], v[30:31], v[34:35]
	v_cvt_pk_bf16_f32 v28, v28, v29
	v_cvt_pk_bf16_f32 v29, v30, v31
	global_store_dwordx2 v[32:33], v[28:29], off
	global_load_dwordx4 v[28:31], v[128:129], off offset:64
	s_waitcnt vmcnt(4)
	v_lshlrev_b32_e32 v34, 16, v38
	v_and_b32_e32 v35, 0xffff0000, v38
	s_waitcnt vmcnt(0)
; template <class Epi>
; DI void gemm_tile(char* smem, const bf16_t* __restrict__ A0, int lda0, int ksplit, const bf16_t* __restrict__ A1, int lda1,
;                   const bf16_t* __restrict__ Bt, int K, int row0, int col0, const Epi& epi, int tid) {
;     ...
; #pragma unroll
;   for (int m = 0; m < 8; ++m)
; #pragma unroll
;     for (int n = 0; n < 4; ++n) epi(row0 + wr * 128 + m * 16 + fr, col0 + wc * 64 + n * 16 + fq * 4, acc[m][n]);
	v_add_f32_e32 v24, v24, v28
	v_add_f32_e32 v25, v25, v29
	v_add_f32_e32 v26, v26, v30
	v_add_f32_e32 v27, v27, v31
	v_mul_f32_e32 v24, 0xbfb8aa3b, v24
	v_mul_f32_e32 v25, 0xbfb8aa3b, v25
	v_mul_f32_e32 v26, 0xbfb8aa3b, v26
	v_mul_f32_e32 v27, 0xbfb8aa3b, v27
	v_exp_f32_e32 v24, v24
	v_exp_f32_e32 v25, v25
	v_exp_f32_e32 v26, v26
	v_exp_f32_e32 v27, v27
	v_add_f32_e32 v24, 1.0, v24
	v_add_f32_e32 v25, 1.0, v25
	v_add_f32_e32 v26, 1.0, v26
	v_add_f32_e32 v27, 1.0, v27
	v_rcp_f32_e32 v24, v24
	v_rcp_f32_e32 v25, v25
	v_rcp_f32_e32 v26, v26
	v_rcp_f32_e32 v27, v27
	v_lshlrev_b32_e32 v28, 16, v39
	v_and_b32_e32 v29, 0xffff0000, v39
	v_pk_mul_f32 v[24:25], v[24:25], v[34:35]
	v_pk_mul_f32 v[26:27], v[26:27], v[28:29]
	v_cvt_pk_bf16_f32 v24, v24, v25
	v_cvt_pk_bf16_f32 v25, v26, v27
	global_store_dwordx2 v[32:33], v[24:25], off offset:32
	global_load_dwordx4 v[24:27], v[128:129], off offset:128
	v_lshlrev_b32_e32 v28, 16, v40
	v_and_b32_e32 v29, 0xffff0000, v40
	v_lshlrev_b32_e32 v30, 16, v46
	v_and_b32_e32 v31, 0xffff0000, v46
	s_waitcnt vmcnt(0)
	v_add_f32_e32 v20, v20, v24
	v_add_f32_e32 v21, v21, v25
	v_add_f32_e32 v22, v22, v26
	v_add_f32_e32 v23, v23, v27
	v_mul_f32_e32 v20, 0xbfb8aa3b, v20
	v_mul_f32_e32 v21, 0xbfb8aa3b, v21
	v_mul_f32_e32 v22, 0xbfb8aa3b, v22
	v_mul_f32_e32 v23, 0xbfb8aa3b, v23
	v_exp_f32_e32 v20, v20
	v_exp_f32_e32 v21, v21
	v_exp_f32_e32 v22, v22
	v_exp_f32_e32 v23, v23
	v_add_f32_e32 v20, 1.0, v20
	v_add_f32_e32 v21, 1.0, v21
	v_add_f32_e32 v22, 1.0, v22
	v_add_f32_e32 v23, 1.0, v23
	v_rcp_f32_e32 v20, v20
	v_rcp_f32_e32 v21, v21
	v_rcp_f32_e32 v22, v22
	v_rcp_f32_e32 v23, v23
	v_lshlrev_b32_e32 v24, 16, v41
	v_and_b32_e32 v25, 0xffff0000, v41
	v_pk_mul_f32 v[20:21], v[20:21], v[28:29]
	v_pk_mul_f32 v[22:23], v[22:23], v[24:25]
	v_cvt_pk_bf16_f32 v20, v20, v21
	v_cvt_pk_bf16_f32 v21, v22, v23
	global_store_dwordx2 v[32:33], v[20:21], off offset:64
	global_load_dwordx4 v[20:23], v[128:129], off offset:192
	v_or_b32_e32 v24, 0x70, v132
	v_ashrrev_i32_e32 v25, 31, v24
	v_lshlrev_b64 v[24:25], 10, v[24:25]
	v_lshl_add_u64 v[26:27], s[2:3], 0, v[24:25]
	v_lshl_add_u64 v[26:27], v[26:27], 0, v[130:131]
	global_load_dwordx2 v[28:29], v[26:27], off
	s_waitcnt vmcnt(1)
	v_add_f32_e32 v16, v16, v20
	v_add_f32_e32 v17, v17, v21
	v_add_f32_e32 v18, v18, v22
	v_add_f32_e32 v19, v19, v23
	v_mul_f32_e32 v16, 0xbfb8aa3b, v16
	v_mul_f32_e32 v17, 0xbfb8aa3b, v17
	v_mul_f32_e32 v18, 0xbfb8aa3b, v18
	v_mul_f32_e32 v19, 0xbfb8aa3b, v19
	v_exp_f32_e32 v16, v16
	v_exp_f32_e32 v17, v17
	v_exp_f32_e32 v18, v18
	v_exp_f32_e32 v19, v19
	v_add_f32_e32 v16, 1.0, v16
	v_add_f32_e32 v17, 1.0, v17
	v_add_f32_e32 v18, 1.0, v18
	v_add_f32_e32 v19, 1.0, v19
	v_rcp_f32_e32 v16, v16
	v_rcp_f32_e32 v17, v17
	v_rcp_f32_e32 v18, v18
	v_rcp_f32_e32 v19, v19
	v_lshlrev_b32_e32 v20, 16, v47
	v_and_b32_e32 v21, 0xffff0000, v47
	v_pk_mul_f32 v[16:17], v[16:17], v[30:31]
	v_pk_mul_f32 v[18:19], v[18:19], v[20:21]
	v_cvt_pk_bf16_f32 v16, v16, v17
	v_cvt_pk_bf16_f32 v17, v18, v19
	global_store_dwordx2 v[32:33], v[16:17], off offset:96
	global_load_dwordx4 v[16:19], v[128:129], off
	v_lshl_add_u64 v[20:21], s[4:5], 0, v[24:25]
	global_load_dwordx2 v[22:23], v[26:27], off offset:32
	global_load_dwordx2 v[24:25], v[26:27], off offset:64
	global_load_dwordx2 v[30:31], v[26:27], off offset:96
	s_waitcnt vmcnt(5)
	v_lshlrev_b32_e32 v26, 16, v28
	v_and_b32_e32 v27, 0xffff0000, v28
	v_lshl_add_u64 v[20:21], v[20:21], 0, v[130:131]
	s_waitcnt vmcnt(3)
; template <class Epi>
; DI void gemm_tile(char* smem, const bf16_t* __restrict__ A0, int lda0, int ksplit, const bf16_t* __restrict__ A1, int lda1,
;                   const bf16_t* __restrict__ Bt, int K, int row0, int col0, const Epi& epi, int tid) {
;     ...
; #pragma unroll
;   for (int m = 0; m < 8; ++m)
; #pragma unroll
;     for (int n = 0; n < 4; ++n) epi(row0 + wr * 128 + m * 16 + fr, col0 + wc * 64 + n * 16 + fq * 4, acc[m][n]);
	v_add_f32_e32 v12, v12, v16
	v_add_f32_e32 v13, v13, v17
	v_add_f32_e32 v14, v14, v18
	v_add_f32_e32 v15, v15, v19
	v_mul_f32_e32 v12, 0xbfb8aa3b, v12
	v_mul_f32_e32 v13, 0xbfb8aa3b, v13
	v_mul_f32_e32 v14, 0xbfb8aa3b, v14
	v_mul_f32_e32 v15, 0xbfb8aa3b, v15
	v_exp_f32_e32 v12, v12
	v_exp_f32_e32 v13, v13
	v_exp_f32_e32 v14, v14
	v_exp_f32_e32 v15, v15
	v_add_f32_e32 v12, 1.0, v12
	v_add_f32_e32 v13, 1.0, v13
	v_add_f32_e32 v14, 1.0, v14
	v_add_f32_e32 v15, 1.0, v15
	v_rcp_f32_e32 v12, v12
	v_rcp_f32_e32 v13, v13
	v_rcp_f32_e32 v14, v14
	v_rcp_f32_e32 v15, v15
	v_lshlrev_b32_e32 v16, 16, v29
	v_and_b32_e32 v17, 0xffff0000, v29
	v_pk_mul_f32 v[12:13], v[12:13], v[26:27]
	v_pk_mul_f32 v[14:15], v[14:15], v[16:17]
	v_cvt_pk_bf16_f32 v12, v12, v13
	v_cvt_pk_bf16_f32 v13, v14, v15
	global_store_dwordx2 v[20:21], v[12:13], off
	global_load_dwordx4 v[12:15], v[128:129], off offset:64
	s_waitcnt vmcnt(4)
	v_lshlrev_b32_e32 v16, 16, v22
	v_and_b32_e32 v17, 0xffff0000, v22
	s_waitcnt vmcnt(0)
	v_add_f32_e32 v8, v8, v12
	v_add_f32_e32 v9, v9, v13
	v_add_f32_e32 v10, v10, v14
	v_add_f32_e32 v11, v11, v15
	v_mul_f32_e32 v8, 0xbfb8aa3b, v8
	v_mul_f32_e32 v9, 0xbfb8aa3b, v9
	v_mul_f32_e32 v10, 0xbfb8aa3b, v10
	v_mul_f32_e32 v11, 0xbfb8aa3b, v11
	v_exp_f32_e32 v8, v8
	v_exp_f32_e32 v9, v9
	v_exp_f32_e32 v10, v10
	v_exp_f32_e32 v11, v11
	v_add_f32_e32 v8, 1.0, v8
	v_add_f32_e32 v9, 1.0, v9
	v_add_f32_e32 v10, 1.0, v10
	v_add_f32_e32 v11, 1.0, v11
	v_rcp_f32_e32 v8, v8
	v_rcp_f32_e32 v9, v9
	v_rcp_f32_e32 v10, v10
	v_rcp_f32_e32 v11, v11
	v_lshlrev_b32_e32 v12, 16, v23
	v_and_b32_e32 v13, 0xffff0000, v23
	v_pk_mul_f32 v[8:9], v[8:9], v[16:17]
	v_pk_mul_f32 v[10:11], v[10:11], v[12:13]
	v_cvt_pk_bf16_f32 v8, v8, v9
	v_cvt_pk_bf16_f32 v9, v10, v11
	global_store_dwordx2 v[20:21], v[8:9], off offset:32
	global_load_dwordx4 v[8:11], v[128:129], off offset:128
	v_lshlrev_b32_e32 v12, 16, v24
	v_and_b32_e32 v13, 0xffff0000, v24
	s_waitcnt vmcnt(0)
	v_add_f32_e32 v4, v4, v8
	v_add_f32_e32 v5, v5, v9
	v_add_f32_e32 v6, v6, v10
	v_add_f32_e32 v7, v7, v11
	v_mul_f32_e32 v4, 0xbfb8aa3b, v4
	v_mul_f32_e32 v5, 0xbfb8aa3b, v5
	v_mul_f32_e32 v6, 0xbfb8aa3b, v6
	v_mul_f32_e32 v7, 0xbfb8aa3b, v7
	v_exp_f32_e32 v4, v4
	v_exp_f32_e32 v5, v5
	v_exp_f32_e32 v6, v6
	v_exp_f32_e32 v7, v7
	v_add_f32_e32 v4, 1.0, v4
	v_add_f32_e32 v5, 1.0, v5
	v_add_f32_e32 v6, 1.0, v6
	v_add_f32_e32 v7, 1.0, v7
	v_rcp_f32_e32 v4, v4
	v_rcp_f32_e32 v5, v5
	v_rcp_f32_e32 v6, v6
	v_rcp_f32_e32 v7, v7
	v_lshlrev_b32_e32 v8, 16, v25
	v_and_b32_e32 v9, 0xffff0000, v25
	v_pk_mul_f32 v[4:5], v[4:5], v[12:13]
	v_pk_mul_f32 v[6:7], v[6:7], v[8:9]
	v_cvt_pk_bf16_f32 v4, v4, v5
	v_cvt_pk_bf16_f32 v5, v6, v7
	global_store_dwordx2 v[20:21], v[4:5], off offset:64
	global_load_dwordx4 v[4:7], v[128:129], off offset:192
	v_lshlrev_b32_e32 v8, 16, v30
	v_and_b32_e32 v9, 0xffff0000, v30
	s_waitcnt vmcnt(0)
	v_add_f32_e32 v0, v0, v4
	v_add_f32_e32 v1, v1, v5
	v_add_f32_e32 v2, v2, v6
	v_add_f32_e32 v3, v3, v7
	v_mul_f32_e32 v0, 0xbfb8aa3b, v0
	v_mul_f32_e32 v1, 0xbfb8aa3b, v1
	v_mul_f32_e32 v2, 0xbfb8aa3b, v2
	v_mul_f32_e32 v3, 0xbfb8aa3b, v3
	v_exp_f32_e32 v0, v0
	v_exp_f32_e32 v1, v1
	v_exp_f32_e32 v2, v2
	v_exp_f32_e32 v3, v3
	v_add_f32_e32 v0, 1.0, v0
	v_add_f32_e32 v1, 1.0, v1
	v_add_f32_e32 v2, 1.0, v2
	v_add_f32_e32 v3, 1.0, v3
	v_rcp_f32_e32 v0, v0
	v_rcp_f32_e32 v1, v1
	v_rcp_f32_e32 v2, v2
	v_rcp_f32_e32 v3, v3
	v_lshlrev_b32_e32 v4, 16, v31
	v_and_b32_e32 v5, 0xffff0000, v31
	v_pk_mul_f32 v[0:1], v[0:1], v[8:9]
	v_pk_mul_f32 v[2:3], v[2:3], v[4:5]
	v_cvt_pk_bf16_f32 v0, v0, v1
	v_cvt_pk_bf16_f32 v1, v2, v3
	global_store_dwordx2 v[20:21], v[0:1], off offset:96
	s_cbranch_scc1 .LBB0_1820

; #define LWRITE(S, buf) do { bf16_t* sA_ = sbase + (buf) * BUF; bf16_t* sB_ = sA_ + 256 * PITCH; \
;     _Pragma("unroll") for (int i_ = 0; i_ < 4; ++i_) *(u32x4*)(sA_ + (sr + i_ * 64) * PITCH + scv * 8) = ra[S][i_]; \
;     _Pragma("unroll") for (int i_ = 0; i_ < 2; ++i_) *(u32x4*)(sB_ + (sr + i_ * 64) * PITCH + scv * 8) = rb[S][i_]; } while (0)
; template <class Epi>
; DI void gemm_tile(char* smem, const bf16_t* __restrict__ A0, int lda0, int ksplit, const bf16_t* __restrict__ A1, int lda1,
;                   const bf16_t* __restrict__ Bt, int K, int row0, int col0, const Epi& epi, int tid) {
;   constexpr int BK = 32, PITCH = 40, BUF = (256 + 128) * PITCH;
;   bf16_t* sbase = (bf16_t*)smem;
;   const int lane = tid & 63, wid = tid >> 6, wr = wid >> 1, wc = wid & 1, fr = lane & 15, fq = lane >> 4;
;   f32x4 acc[8][4];
; #pragma unroll
;   for (int m = 0; m < 8; ++m)
; #pragma unroll
;     for (int n = 0; n < 4; ++n) acc[m][n] = (f32x4){0.f, 0.f, 0.f, 0.f};
;   u32x4 ra[2][4], rb[2][2];
;   const int nk = K / BK;
;   const int sr = tid >> 2, scv = tid & 3;
;     ...
;   __syncthreads();
;   {
;     const int last = nk - 1;
;     GLOAD(0, 0);
;     __builtin_amdgcn_sched_barrier(0);
;     GLOAD(1, 1);
;     __builtin_amdgcn_sched_barrier(0);
;     LWRITE(0, 0);
;     __builtin_amdgcn_sched_barrier(0);
;     GLOAD(0, (2 < last ? 2 : last));
;     __builtin_amdgcn_sched_barrier(0);
;     __syncthreads();
; template <class Epi>
; DI void gemm_phase(char* smem, const bf16_t* A0, int lda0, int ksplit, const bf16_t* A1, int lda1, const bf16_t* Bt, int K, int nN, const Epi& epi, int tid) {
;     ...
;   if ((G & 7) == 0) {
;     const int x = blockIdx.x & 7, l = blockIdx.x >> 3, L = G >> 3, per = 8 * nN, tot = 2 * per;
;     for (int q = l; q < tot; q += L) { const int rgl = q / per, rem = q % per, ct = rem >> 3, rt = (x * 2 + rgl) * 8 + (rem & 7);
;       gemm_tile(smem, A0, lda0, ksplit, A1, lda1, Bt, K, rt * 256, ct * 128, epi, tid); }
.LBB0_1824:
.LBB0_1825:
	s_cmpk_gt_u32 s96, 0x1ff
	s_cbranch_scc1 .LBB0_1830
	v_and_b32_e32 v0, 3, v195
	v_lshlrev_b32_e32 v176, 4, v0
	v_mov_b32_e32 v177, 0
	v_ashrrev_i32_e32 v197, 2, v196
	v_lshl_add_u64 v[178:179], s[2:3], 0, v[176:177]
	v_lshl_add_u64 v[180:181], s[0:1], 0, v[176:177]
	v_add_u32_e32 v0, 0, v176
	s_movk_i32 s0, 0x40
	v_bfe_u32 v2, v195, 4, 2
	v_and_b32_e32 v3, 0x4f, v196
	v_and_b32_e32 v176, 0xffffff8f, v196
	v_or_b32_e32 v6, 0x70, v196
	s_lshl_b32 s6, s96, 1
	v_mul_lo_u32 v1, v197, s0
	v_lshl_add_u32 v4, v2, 4, 0
	v_mul_u32_u24_e32 v3, 0x40, v3
	v_mul_lo_u32 v5, v176, s0
	v_mul_lo_u32 v6, v6, s0
	v_and_b32_e32 v7, 64, v196
	s_ashr_i32 s12, s14, 3
	s_lshr_b32 s13, s96, 3
	s_and_b32 s17, s6, 14
	s_mov_b32 s1, 0
	v_lshl_or_b32 v196, v2, 2, v7
	s_mov_b64 s[6:7], 0x10000
	s_mov_b64 s[8:9], 0x20000
	s_mov_b64 s[10:11], 0x30000
	v_add_u32_e32 v198, v0, v1
	v_add_u32_e32 v199, v4, v3
	v_add_u32_e32 v200, v4, v5
	v_add_u32_e32 v201, v4, v6
	v_mbcnt_lo_u32_b32 v1, -1, 0
	v_mbcnt_hi_u32_b32 v1, -1, v1
	v_bfe_u32 v3, v1, 3, 1
	v_bfe_u32 v1, v1, 5, 1
	v_mul_u32_u24_e32 v3, 48, v3
	v_mul_u32_u24_e32 v1, 48, v1
	v_xor_b32_e32 v198, v198, v1
	v_xor_b32_e32 v199, v199, v3
	v_xor_b32_e32 v200, v200, v3
	v_xor_b32_e32 v201, v201, v3
.LBB0_1827:
	s_ashr_i32 s0, s13, 31
	s_lshr_b32 s0, s0, 27
	s_add_i32 s0, s13, s0
	s_lshr_b32 s18, s0, 5
	s_andn2_b32 s0, s0, 31
	s_sub_i32 s0, s13, s0
	s_add_i32 s18, s18, s17
	s_lshl_b32 s19, s0, 8
	s_lshl_b32 s18, s18, 11
	s_and_b32 s19, s19, 0x700
	s_or_b32 s18, s18, s19
	s_lshl_b32 s0, s0, 4
	s_and_b32 s19, s0, 0xffffff80
	v_add_u32_e32 v0, s18, v197
	v_ashrrev_i32_e32 v1, 31, v0
	v_add_u32_e32 v16, s19, v197
	v_lshlrev_b64 v[182:183], 10, v[0:1]
	v_ashrrev_i32_e32 v17, 31, v16
	v_lshl_add_u64 v[186:187], v[182:183], 0, s[8:9]
	v_lshlrev_b64 v[190:191], 10, v[16:17]
	v_lshl_add_u64 v[24:25], v[178:179], 0, v[182:183]
	v_lshl_add_u64 v[184:185], v[182:183], 0, s[6:7]
	v_lshl_add_u64 v[28:29], v[178:179], 0, v[186:187]
	v_lshl_add_u64 v[188:189], v[182:183], 0, s[10:11]
	v_lshl_add_u64 v[32:33], v[180:181], 0, v[190:191]
	v_lshl_add_u64 v[192:193], v[190:191], 0, s[6:7]
	s_barrier
	v_lshl_add_u64 v[26:27], v[178:179], 0, v[184:185]
	global_load_dwordx4 v[0:3], v[24:25], off
	global_load_dwordx4 v[4:7], v[26:27], off
	v_lshl_add_u64 v[30:31], v[178:179], 0, v[188:189]
	global_load_dwordx4 v[8:11], v[28:29], off
	global_load_dwordx4 v[12:15], v[30:31], off
	v_lshl_add_u64 v[34:35], v[180:181], 0, v[192:193]
	global_load_dwordx4 v[16:19], v[32:33], off
	global_load_dwordx4 v[20:23], v[34:35], off
	global_load_dwordx4 v[128:131], v[24:25], off offset:64
	global_load_dwordx4 v[132:135], v[26:27], off offset:64
	global_load_dwordx4 v[136:139], v[28:29], off offset:64
	global_load_dwordx4 v[140:143], v[30:31], off offset:64
	global_load_dwordx4 v[144:147], v[32:33], off offset:64
	global_load_dwordx4 v[148:151], v[34:35], off offset:64
	s_waitcnt vmcnt(11)
	ds_write_b128 v198, v[0:3]
	s_waitcnt vmcnt(10)
	ds_write_b128 v198, v[4:7] offset:4096
	s_waitcnt vmcnt(9)
	ds_write_b128 v198, v[8:11] offset:8192
	s_waitcnt vmcnt(8)
	ds_write_b128 v198, v[12:15] offset:12288
	s_waitcnt vmcnt(7)
	ds_write_b128 v198, v[16:19] offset:16384
	s_waitcnt vmcnt(6)
	ds_write_b128 v198, v[20:23] offset:20480
	global_load_dwordx4 v[152:155], v[24:25], off offset:128
	global_load_dwordx4 v[156:159], v[26:27], off offset:128
	global_load_dwordx4 v[160:163], v[28:29], off offset:128
	global_load_dwordx4 v[164:167], v[30:31], off offset:128
	global_load_dwordx4 v[168:171], v[32:33], off offset:128
	global_load_dwordx4 v[172:175], v[34:35], off offset:128
	s_mov_b32 s20, -2
	v_mov_b32_e32 v96, 0
	v_mov_b32_e32 v97, v177
	v_mov_b32_e32 v98, v177
	v_mov_b32_e32 v99, v177
	v_mov_b32_e32 v100, 0
	v_mov_b32_e32 v101, v177
	v_mov_b32_e32 v102, v177
	v_mov_b32_e32 v103, v177
	v_mov_b32_e32 v104, 0
	v_mov_b32_e32 v105, v177
	v_mov_b32_e32 v106, v177
	v_mov_b32_e32 v107, v177
	v_mov_b32_e32 v108, 0
	v_mov_b32_e32 v109, v177
	v_mov_b32_e32 v110, v177
	v_mov_b32_e32 v111, v177
	v_mov_b32_e32 v112, 0
	v_mov_b32_e32 v113, v177
	v_mov_b32_e32 v114, v177
	v_mov_b32_e32 v115, v177
	v_mov_b32_e32 v116, 0
	v_mov_b32_e32 v117, v177
	v_mov_b32_e32 v118, v177
	v_mov_b32_e32 v119, v177
	v_mov_b32_e32 v120, 0
	v_mov_b32_e32 v121, v177
	v_mov_b32_e32 v122, v177
	v_mov_b32_e32 v123, v177
	v_mov_b32_e32 v124, 0
	v_mov_b32_e32 v125, v177
	v_mov_b32_e32 v126, v177
	v_mov_b32_e32 v127, v177
	v_mov_b32_e32 v92, 0
	v_mov_b32_e32 v93, v177
	v_mov_b32_e32 v94, v177
	v_mov_b32_e32 v95, v177
	v_mov_b32_e32 v88, 0
	v_mov_b32_e32 v89, v177
	v_mov_b32_e32 v90, v177
	v_mov_b32_e32 v91, v177
	v_mov_b32_e32 v84, 0
	v_mov_b32_e32 v85, v177
	v_mov_b32_e32 v86, v177
	v_mov_b32_e32 v87, v177
	v_mov_b32_e32 v80, 0
	v_mov_b32_e32 v81, v177
	v_mov_b32_e32 v82, v177
	v_mov_b32_e32 v83, v177
	v_mov_b32_e32 v76, 0
	v_mov_b32_e32 v77, v177
	v_mov_b32_e32 v78, v177
	v_mov_b32_e32 v79, v177
	v_mov_b32_e32 v72, 0
	v_mov_b32_e32 v73, v177
	v_mov_b32_e32 v74, v177
	v_mov_b32_e32 v75, v177
	v_mov_b32_e32 v68, 0
	v_mov_b32_e32 v69, v177
	v_mov_b32_e32 v70, v177
	v_mov_b32_e32 v71, v177
	v_mov_b32_e32 v64, 0
	v_mov_b32_e32 v65, v177
	v_mov_b32_e32 v66, v177
	v_mov_b32_e32 v67, v177
	v_mov_b32_e32 v60, 0
	v_mov_b32_e32 v61, v177
	v_mov_b32_e32 v62, v177
	v_mov_b32_e32 v63, v177
	v_mov_b32_e32 v56, 0
	v_mov_b32_e32 v57, v177
	v_mov_b32_e32 v58, v177
	v_mov_b32_e32 v59, v177
	v_mov_b32_e32 v52, 0
	v_mov_b32_e32 v53, v177
	v_mov_b32_e32 v54, v177
	v_mov_b32_e32 v55, v177
	v_mov_b32_e32 v48, 0
	v_mov_b32_e32 v49, v177
	v_mov_b32_e32 v50, v177
	v_mov_b32_e32 v51, v177
	v_mov_b32_e32 v44, 0
	v_mov_b32_e32 v45, v177
	v_mov_b32_e32 v46, v177
	v_mov_b32_e32 v47, v177
	v_mov_b32_e32 v40, 0
	v_mov_b32_e32 v41, v177
	v_mov_b32_e32 v42, v177
	v_mov_b32_e32 v43, v177
	v_mov_b32_e32 v36, 0
	v_mov_b32_e32 v37, v177
	v_mov_b32_e32 v38, v177
	v_mov_b32_e32 v39, v177
	v_mov_b32_e32 v32, 0
	v_mov_b32_e32 v33, v177
	v_mov_b32_e32 v34, v177
	v_mov_b32_e32 v35, v177
	v_mov_b32_e32 v28, 0
	v_mov_b32_e32 v29, v177
	v_mov_b32_e32 v30, v177
	v_mov_b32_e32 v31, v177
	v_mov_b32_e32 v24, 0
	v_mov_b32_e32 v25, v177
	v_mov_b32_e32 v26, v177
	v_mov_b32_e32 v27, v177
	v_mov_b32_e32 v20, 0
	v_mov_b32_e32 v21, v177
	v_mov_b32_e32 v22, v177
	v_mov_b32_e32 v23, v177
	v_mov_b32_e32 v16, 0
	v_mov_b32_e32 v17, v177
	v_mov_b32_e32 v18, v177
	v_mov_b32_e32 v19, v177
	v_mov_b32_e32 v12, 0
	v_mov_b32_e32 v13, v177
	v_mov_b32_e32 v14, v177
	v_mov_b32_e32 v15, v177
	v_mov_b32_e32 v8, 0
	v_mov_b32_e32 v9, v177
	v_mov_b32_e32 v10, v177
	v_mov_b32_e32 v11, v177
	v_mov_b32_e32 v4, 0
	v_mov_b32_e32 v5, v177
	v_mov_b32_e32 v6, v177
	v_mov_b32_e32 v7, v177
	v_mov_b32_e32 v0, 0
	v_mov_b32_e32 v1, v177
	v_mov_b32_e32 v2, v177
	v_mov_b32_e32 v3, v177
	s_waitcnt lgkmcnt(0)
	s_barrier
; #define LWRITE(S, buf) do { bf16_t* sA_ = sbase + (buf) * BUF; bf16_t* sB_ = sA_ + 256 * PITCH; \
;     _Pragma("unroll") for (int i_ = 0; i_ < 4; ++i_) *(u32x4*)(sA_ + (sr + i_ * 64) * PITCH + scv * 8) = ra[S][i_]; \
;     _Pragma("unroll") for (int i_ = 0; i_ < 2; ++i_) *(u32x4*)(sB_ + (sr + i_ * 64) * PITCH + scv * 8) = rb[S][i_]; } while (0)
; template <class Epi>
; DI void gemm_tile(char* smem, const bf16_t* __restrict__ A0, int lda0, int ksplit, const bf16_t* __restrict__ A1, int lda1,
;                   const bf16_t* __restrict__ Bt, int K, int row0, int col0, const Epi& epi, int tid) {
;     ...
;     for (int kt = 0; kt < nk; kt += 2) {
;       LWRITE(1, 1);
;       __builtin_amdgcn_sched_barrier(0);
;       GLOAD(1, (kt + 3 < last ? kt + 3 : last));
;       __builtin_amdgcn_sched_barrier(0);
;       COMPUTE(0);
;       __syncthreads();
;       LWRITE(0, 0);
;       __builtin_amdgcn_sched_barrier(0);
;       GLOAD(0, (kt + 4 < last ? kt + 4 : last));
;       __builtin_amdgcn_sched_barrier(0);
;       COMPUTE(1);
.LBB0_1828:
	s_add_i32 s20, s20, 2
	s_waitcnt vmcnt(11)
	ds_write_b128 v198, v[128:131] offset:24576
	s_waitcnt vmcnt(10)
	ds_write_b128 v198, v[132:135] offset:28672
	s_waitcnt vmcnt(9)
	ds_write_b128 v198, v[136:139] offset:32768
	s_waitcnt vmcnt(8)
	ds_write_b128 v198, v[140:143] offset:36864
	s_waitcnt vmcnt(7)
	ds_write_b128 v198, v[144:147] offset:40960
	s_waitcnt vmcnt(6)
	ds_write_b128 v198, v[148:151] offset:45056
	s_min_u32 s0, s20, 12
	s_lshl_b32 s0, s0, 6
	v_lshl_add_u64 v[136:137], v[178:179], 0, s[0:1]
	v_lshl_add_u64 v[144:145], v[180:181], 0, s[0:1]
	v_lshl_add_u64 v[128:129], v[136:137], 0, v[182:183]
	v_lshl_add_u64 v[132:133], v[136:137], 0, v[184:185]
	v_lshl_add_u64 v[138:139], v[136:137], 0, v[186:187]
	v_lshl_add_u64 v[140:141], v[136:137], 0, v[188:189]
	v_lshl_add_u64 v[146:147], v[144:145], 0, v[190:191]
	v_lshl_add_u64 v[148:149], v[144:145], 0, v[192:193]
	ds_read_b128 v[202:205], v199 offset:16384
	ds_read_b128 v[206:209], v199 offset:17408
	ds_read_b128 v[210:213], v199 offset:18432
	ds_read_b128 v[214:217], v199 offset:19456
	ds_read_b128 v[218:221], v200
	ds_read_b128 v[222:225], v200 offset:1024
	ds_read_b128 v[226:229], v200 offset:2048
	ds_read_b128 v[230:233], v200 offset:3072
	ds_read_b128 v[234:237], v200 offset:4096
	ds_read_b128 v[238:241], v200 offset:5120
	ds_read_b128 v[242:245], v200 offset:6144
	ds_read_b128 v[246:249], v201
	s_setprio 1
	s_waitcnt lgkmcnt(7)
	v_mfma_f32_16x16x32_bf16 v[124:127], v[202:205], v[218:221], v[124:127]
	v_mfma_f32_16x16x32_bf16 v[120:123], v[206:209], v[218:221], v[120:123]
	v_mfma_f32_16x16x32_bf16 v[116:119], v[210:213], v[218:221], v[116:119]
	v_mfma_f32_16x16x32_bf16 v[112:115], v[214:217], v[218:221], v[112:115]
	global_load_dwordx4 v[128:131], v[128:129], off offset:192
	s_waitcnt lgkmcnt(6)
	v_mfma_f32_16x16x32_bf16 v[108:111], v[202:205], v[222:225], v[108:111]
	v_mfma_f32_16x16x32_bf16 v[104:107], v[206:209], v[222:225], v[104:107]
	v_mfma_f32_16x16x32_bf16 v[100:103], v[210:213], v[222:225], v[100:103]
	v_mfma_f32_16x16x32_bf16 v[96:99], v[214:217], v[222:225], v[96:99]
	global_load_dwordx4 v[132:135], v[132:133], off offset:192
	s_waitcnt lgkmcnt(5)
	v_mfma_f32_16x16x32_bf16 v[92:95], v[202:205], v[226:229], v[92:95]
	v_mfma_f32_16x16x32_bf16 v[88:91], v[206:209], v[226:229], v[88:91]
	v_mfma_f32_16x16x32_bf16 v[84:87], v[210:213], v[226:229], v[84:87]
	v_mfma_f32_16x16x32_bf16 v[80:83], v[214:217], v[226:229], v[80:83]
	global_load_dwordx4 v[136:139], v[138:139], off offset:192
	s_waitcnt lgkmcnt(4)
	v_mfma_f32_16x16x32_bf16 v[76:79], v[202:205], v[230:233], v[76:79]
	v_mfma_f32_16x16x32_bf16 v[72:75], v[206:209], v[230:233], v[72:75]
	v_mfma_f32_16x16x32_bf16 v[68:71], v[210:213], v[230:233], v[68:71]
	v_mfma_f32_16x16x32_bf16 v[64:67], v[214:217], v[230:233], v[64:67]
	global_load_dwordx4 v[140:143], v[140:141], off offset:192
	s_waitcnt lgkmcnt(3)
	v_mfma_f32_16x16x32_bf16 v[60:63], v[202:205], v[234:237], v[60:63]
	v_mfma_f32_16x16x32_bf16 v[56:59], v[206:209], v[234:237], v[56:59]
	v_mfma_f32_16x16x32_bf16 v[52:55], v[210:213], v[234:237], v[52:55]
	v_mfma_f32_16x16x32_bf16 v[48:51], v[214:217], v[234:237], v[48:51]
	global_load_dwordx4 v[144:147], v[146:147], off offset:192
	s_waitcnt lgkmcnt(2)
	v_mfma_f32_16x16x32_bf16 v[44:47], v[202:205], v[238:241], v[44:47]
	v_mfma_f32_16x16x32_bf16 v[40:43], v[206:209], v[238:241], v[40:43]
	v_mfma_f32_16x16x32_bf16 v[36:39], v[210:213], v[238:241], v[36:39]
	v_mfma_f32_16x16x32_bf16 v[32:35], v[214:217], v[238:241], v[32:35]
	global_load_dwordx4 v[148:151], v[148:149], off offset:192
	s_waitcnt lgkmcnt(1)
	v_mfma_f32_16x16x32_bf16 v[28:31], v[202:205], v[242:245], v[28:31]
	v_mfma_f32_16x16x32_bf16 v[24:27], v[206:209], v[242:245], v[24:27]
	v_mfma_f32_16x16x32_bf16 v[20:23], v[210:213], v[242:245], v[20:23]
	v_mfma_f32_16x16x32_bf16 v[16:19], v[214:217], v[242:245], v[16:19]
	s_waitcnt lgkmcnt(0)
	v_mfma_f32_16x16x32_bf16 v[12:15], v[202:205], v[246:249], v[12:15]
	v_mfma_f32_16x16x32_bf16 v[8:11], v[206:209], v[246:249], v[8:11]
	v_mfma_f32_16x16x32_bf16 v[4:7], v[210:213], v[246:249], v[4:7]
	v_mfma_f32_16x16x32_bf16 v[0:3], v[214:217], v[246:249], v[0:3]
	s_setprio 0
	s_barrier
	s_waitcnt vmcnt(11)
	ds_write_b128 v198, v[152:155]
	s_waitcnt vmcnt(10)
	ds_write_b128 v198, v[156:159] offset:4096
	s_waitcnt vmcnt(9)
	ds_write_b128 v198, v[160:163] offset:8192
	s_waitcnt vmcnt(8)
	ds_write_b128 v198, v[164:167] offset:12288
	s_waitcnt vmcnt(7)
	ds_write_b128 v198, v[168:171] offset:16384
	s_waitcnt vmcnt(6)
	ds_write_b128 v198, v[172:175] offset:20480
	s_min_u32 s0, s20, 11
	s_lshl_b32 s0, s0, 6
	v_lshl_add_u64 v[160:161], v[178:179], 0, s[0:1]
	v_lshl_add_u64 v[168:169], v[180:181], 0, s[0:1]
	v_lshl_add_u64 v[152:153], v[160:161], 0, v[182:183]
	v_lshl_add_u64 v[156:157], v[160:161], 0, v[184:185]
	v_lshl_add_u64 v[162:163], v[160:161], 0, v[186:187]
	v_lshl_add_u64 v[164:165], v[160:161], 0, v[188:189]
	v_lshl_add_u64 v[170:171], v[168:169], 0, v[190:191]
	v_lshl_add_u64 v[172:173], v[168:169], 0, v[192:193]
	ds_read_b128 v[202:205], v199 offset:40960
	ds_read_b128 v[206:209], v199 offset:41984
	ds_read_b128 v[210:213], v199 offset:43008
	ds_read_b128 v[214:217], v199 offset:44032
	ds_read_b128 v[218:221], v200 offset:26624
	ds_read_b128 v[222:225], v200 offset:27648
	ds_read_b128 v[226:229], v200 offset:28672
	ds_read_b128 v[230:233], v200 offset:29696
	ds_read_b128 v[234:237], v200 offset:24576
	ds_read_b128 v[238:241], v200 offset:30720
	ds_read_b128 v[242:245], v200 offset:25600
	ds_read_b128 v[246:249], v201 offset:24576
	s_setprio 1
	s_waitcnt lgkmcnt(3)
; template <class Epi>
; DI void gemm_tile(char* smem, const bf16_t* __restrict__ A0, int lda0, int ksplit, const bf16_t* __restrict__ A1, int lda1,
;                   const bf16_t* __restrict__ Bt, int K, int row0, int col0, const Epi& epi, int tid) {
;     ...
;       COMPUTE(1);
;       __syncthreads();
;     }
;   }
;     ...
; #pragma unroll
;   for (int m = 0; m < 8; ++m)
; #pragma unroll
;     for (int n = 0; n < 4; ++n) epi(row0 + wr * 128 + m * 16 + fr, col0 + wc * 64 + n * 16 + fq * 4, acc[m][n]);
	v_mfma_f32_16x16x32_bf16 v[124:127], v[202:205], v[234:237], v[124:127]
	v_mfma_f32_16x16x32_bf16 v[120:123], v[206:209], v[234:237], v[120:123]
	v_mfma_f32_16x16x32_bf16 v[116:119], v[210:213], v[234:237], v[116:119]
	v_mfma_f32_16x16x32_bf16 v[112:115], v[214:217], v[234:237], v[112:115]
	global_load_dwordx4 v[152:155], v[152:153], off offset:256
	s_waitcnt lgkmcnt(1)
	v_mfma_f32_16x16x32_bf16 v[108:111], v[202:205], v[242:245], v[108:111]
	v_mfma_f32_16x16x32_bf16 v[104:107], v[206:209], v[242:245], v[104:107]
	v_mfma_f32_16x16x32_bf16 v[100:103], v[210:213], v[242:245], v[100:103]
	v_mfma_f32_16x16x32_bf16 v[96:99], v[214:217], v[242:245], v[96:99]
	global_load_dwordx4 v[156:159], v[156:157], off offset:256
	v_mfma_f32_16x16x32_bf16 v[92:95], v[202:205], v[218:221], v[92:95]
	v_mfma_f32_16x16x32_bf16 v[88:91], v[206:209], v[218:221], v[88:91]
	v_mfma_f32_16x16x32_bf16 v[84:87], v[210:213], v[218:221], v[84:87]
	v_mfma_f32_16x16x32_bf16 v[80:83], v[214:217], v[218:221], v[80:83]
	global_load_dwordx4 v[160:163], v[162:163], off offset:256
	v_mfma_f32_16x16x32_bf16 v[76:79], v[202:205], v[222:225], v[76:79]
	v_mfma_f32_16x16x32_bf16 v[72:75], v[206:209], v[222:225], v[72:75]
	v_mfma_f32_16x16x32_bf16 v[68:71], v[210:213], v[222:225], v[68:71]
	v_mfma_f32_16x16x32_bf16 v[64:67], v[214:217], v[222:225], v[64:67]
	global_load_dwordx4 v[164:167], v[164:165], off offset:256
	v_mfma_f32_16x16x32_bf16 v[60:63], v[202:205], v[226:229], v[60:63]
	v_mfma_f32_16x16x32_bf16 v[56:59], v[206:209], v[226:229], v[56:59]
	v_mfma_f32_16x16x32_bf16 v[52:55], v[210:213], v[226:229], v[52:55]
	v_mfma_f32_16x16x32_bf16 v[48:51], v[214:217], v[226:229], v[48:51]
	global_load_dwordx4 v[168:171], v[170:171], off offset:256
	v_mfma_f32_16x16x32_bf16 v[44:47], v[202:205], v[230:233], v[44:47]
	v_mfma_f32_16x16x32_bf16 v[40:43], v[206:209], v[230:233], v[40:43]
	v_mfma_f32_16x16x32_bf16 v[36:39], v[210:213], v[230:233], v[36:39]
	v_mfma_f32_16x16x32_bf16 v[32:35], v[214:217], v[230:233], v[32:35]
	global_load_dwordx4 v[172:175], v[172:173], off offset:256
	v_mfma_f32_16x16x32_bf16 v[28:31], v[202:205], v[238:241], v[28:31]
	v_mfma_f32_16x16x32_bf16 v[24:27], v[206:209], v[238:241], v[24:27]
	v_mfma_f32_16x16x32_bf16 v[20:23], v[210:213], v[238:241], v[20:23]
	v_mfma_f32_16x16x32_bf16 v[16:19], v[214:217], v[238:241], v[16:19]
	s_waitcnt lgkmcnt(0)
	v_mfma_f32_16x16x32_bf16 v[12:15], v[202:205], v[246:249], v[12:15]
	v_mfma_f32_16x16x32_bf16 v[8:11], v[206:209], v[246:249], v[8:11]
	v_mfma_f32_16x16x32_bf16 v[4:7], v[210:213], v[246:249], v[4:7]
	v_mfma_f32_16x16x32_bf16 v[0:3], v[214:217], v[246:249], v[0:3]
	s_setprio 0
	s_cmp_lt_u32 s20, 14
	s_barrier
	s_cbranch_scc1 .LBB0_1828
	s_waitcnt vmcnt(11)
	v_or_b32_e32 v130, s19, v196
	v_ashrrev_i32_e32 v131, 31, v130
	v_lshl_add_u64 v[128:129], v[130:131], 2, s[82:83]
	global_load_dwordx4 v[134:137], v[128:129], off
	s_waitcnt vmcnt(11)
	v_add_u32_e32 v132, s18, v176
	v_ashrrev_i32_e32 v133, 31, v132
	s_waitcnt vmcnt(10)
	v_lshlrev_b64 v[138:139], 10, v[132:133]
	v_lshlrev_b64 v[130:131], 1, v[130:131]
	s_waitcnt vmcnt(9)
	v_lshl_add_u64 v[140:141], s[2:3], 0, v[138:139]
	v_lshl_add_u64 v[140:141], v[140:141], 0, v[130:131]
	global_load_dwordx2 v[142:143], v[140:141], off
	v_lshl_add_u64 v[138:139], s[4:5], 0, v[138:139]
	v_lshl_add_u64 v[138:139], v[138:139], 0, v[130:131]
	global_load_dwordx2 v[144:145], v[140:141], off offset:32
	global_load_dwordx2 v[146:147], v[140:141], off offset:64
	s_nop 0
	global_load_dwordx2 v[140:141], v[140:141], off offset:96
	s_add_i32 s13, s13, s12
	s_cmp_gt_i32 s13, 63
	s_waitcnt vmcnt(4)
	v_add_f32_e32 v124, v124, v134
	v_add_f32_e32 v125, v125, v135
	v_add_f32_e32 v126, v126, v136
	v_add_f32_e32 v127, v127, v137
	v_mul_f32_e32 v124, 0xbfb8aa3b, v124
	v_mul_f32_e32 v125, 0xbfb8aa3b, v125
	v_mul_f32_e32 v126, 0xbfb8aa3b, v126
	v_mul_f32_e32 v127, 0xbfb8aa3b, v127
	v_exp_f32_e32 v133, v124
	v_exp_f32_e32 v134, v125
	v_exp_f32_e32 v126, v126
	v_exp_f32_e32 v127, v127
	v_add_f32_e32 v133, 1.0, v133
	v_add_f32_e32 v134, 1.0, v134
	v_add_f32_e32 v135, 1.0, v126
	v_add_f32_e32 v136, 1.0, v127
	v_rcp_f32_e32 v126, v133
	v_rcp_f32_e32 v127, v134
	v_rcp_f32_e32 v134, v135
	v_rcp_f32_e32 v135, v136
	s_waitcnt vmcnt(3)
	v_lshlrev_b32_e32 v124, 16, v142
	v_and_b32_e32 v125, 0xffff0000, v142
	v_lshlrev_b32_e32 v136, 16, v143
	v_and_b32_e32 v137, 0xffff0000, v143
	v_pk_mul_f32 v[124:125], v[126:127], v[124:125]
	v_pk_mul_f32 v[126:127], v[134:135], v[136:137]
	v_cvt_pk_bf16_f32 v124, v124, v125
	v_cvt_pk_bf16_f32 v125, v126, v127
	global_store_dwordx2 v[138:139], v[124:125], off
	global_load_dwordx4 v[124:127], v[128:129], off offset:64
	s_waitcnt vmcnt(4)
	v_lshlrev_b32_e32 v134, 16, v144
	v_and_b32_e32 v135, 0xffff0000, v144
	s_waitcnt vmcnt(0)
	v_add_f32_e32 v120, v120, v124
	v_add_f32_e32 v121, v121, v125
	v_add_f32_e32 v122, v122, v126
	v_add_f32_e32 v123, v123, v127
	v_mul_f32_e32 v120, 0xbfb8aa3b, v120
	v_mul_f32_e32 v121, 0xbfb8aa3b, v121
	v_mul_f32_e32 v122, 0xbfb8aa3b, v122
	v_mul_f32_e32 v123, 0xbfb8aa3b, v123
	v_exp_f32_e32 v120, v120
	v_exp_f32_e32 v121, v121
	v_exp_f32_e32 v122, v122
	v_exp_f32_e32 v123, v123
	v_add_f32_e32 v120, 1.0, v120
	v_add_f32_e32 v121, 1.0, v121
	v_add_f32_e32 v122, 1.0, v122
	v_add_f32_e32 v123, 1.0, v123
	v_rcp_f32_e32 v120, v120
	v_rcp_f32_e32 v121, v121
	v_rcp_f32_e32 v122, v122
	v_rcp_f32_e32 v123, v123
	v_lshlrev_b32_e32 v124, 16, v145
	v_and_b32_e32 v125, 0xffff0000, v145
	v_pk_mul_f32 v[120:121], v[120:121], v[134:135]
	v_pk_mul_f32 v[122:123], v[122:123], v[124:125]
	v_cvt_pk_bf16_f32 v120, v120, v121
	v_cvt_pk_bf16_f32 v121, v122, v123
	global_store_dwordx2 v[138:139], v[120:121], off offset:32
	global_load_dwordx4 v[120:123], v[128:129], off offset:128
	v_lshlrev_b32_e32 v124, 16, v146
	v_and_b32_e32 v125, 0xffff0000, v146
	v_lshlrev_b32_e32 v126, 16, v140
	v_and_b32_e32 v127, 0xffff0000, v140
	s_waitcnt vmcnt(0)
; template <class Epi>
; DI void gemm_tile(char* smem, const bf16_t* __restrict__ A0, int lda0, int ksplit, const bf16_t* __restrict__ A1, int lda1,
;                   const bf16_t* __restrict__ Bt, int K, int row0, int col0, const Epi& epi, int tid) {
;     ...
; #pragma unroll
;   for (int m = 0; m < 8; ++m)
; #pragma unroll
;     for (int n = 0; n < 4; ++n) epi(row0 + wr * 128 + m * 16 + fr, col0 + wc * 64 + n * 16 + fq * 4, acc[m][n]);
	v_add_f32_e32 v116, v116, v120
	v_add_f32_e32 v117, v117, v121
	v_add_f32_e32 v118, v118, v122
	v_add_f32_e32 v119, v119, v123
	v_mul_f32_e32 v116, 0xbfb8aa3b, v116
	v_mul_f32_e32 v117, 0xbfb8aa3b, v117
	v_mul_f32_e32 v118, 0xbfb8aa3b, v118
	v_mul_f32_e32 v119, 0xbfb8aa3b, v119
	v_exp_f32_e32 v116, v116
	v_exp_f32_e32 v117, v117
	v_exp_f32_e32 v118, v118
	v_exp_f32_e32 v119, v119
	v_add_f32_e32 v116, 1.0, v116
	v_add_f32_e32 v117, 1.0, v117
	v_add_f32_e32 v118, 1.0, v118
	v_add_f32_e32 v119, 1.0, v119
	v_rcp_f32_e32 v116, v116
	v_rcp_f32_e32 v117, v117
	v_rcp_f32_e32 v118, v118
	v_rcp_f32_e32 v119, v119
	v_lshlrev_b32_e32 v120, 16, v147
	v_and_b32_e32 v121, 0xffff0000, v147
	v_pk_mul_f32 v[116:117], v[116:117], v[124:125]
	v_pk_mul_f32 v[118:119], v[118:119], v[120:121]
	v_cvt_pk_bf16_f32 v116, v116, v117
	v_cvt_pk_bf16_f32 v117, v118, v119
	global_store_dwordx2 v[138:139], v[116:117], off offset:64
	global_load_dwordx4 v[116:119], v[128:129], off offset:192
	v_or_b32_e32 v120, 16, v132
	v_ashrrev_i32_e32 v121, 31, v120
	v_lshlrev_b64 v[120:121], 10, v[120:121]
	v_lshl_add_u64 v[122:123], s[2:3], 0, v[120:121]
	v_lshl_add_u64 v[122:123], v[122:123], 0, v[130:131]
	global_load_dwordx2 v[124:125], v[122:123], off
	s_waitcnt vmcnt(1)
	v_add_f32_e32 v112, v112, v116
	v_add_f32_e32 v113, v113, v117
	v_add_f32_e32 v114, v114, v118
	v_add_f32_e32 v115, v115, v119
	v_mul_f32_e32 v112, 0xbfb8aa3b, v112
	v_mul_f32_e32 v113, 0xbfb8aa3b, v113
	v_mul_f32_e32 v114, 0xbfb8aa3b, v114
	v_mul_f32_e32 v115, 0xbfb8aa3b, v115
	v_exp_f32_e32 v112, v112
	v_exp_f32_e32 v113, v113
	v_exp_f32_e32 v114, v114
	v_exp_f32_e32 v115, v115
	v_add_f32_e32 v112, 1.0, v112
	v_add_f32_e32 v113, 1.0, v113
	v_add_f32_e32 v114, 1.0, v114
	v_add_f32_e32 v115, 1.0, v115
	v_rcp_f32_e32 v112, v112
	v_rcp_f32_e32 v113, v113
	v_rcp_f32_e32 v114, v114
	v_rcp_f32_e32 v115, v115
	v_lshlrev_b32_e32 v116, 16, v141
	v_and_b32_e32 v117, 0xffff0000, v141
	v_pk_mul_f32 v[112:113], v[112:113], v[126:127]
	v_pk_mul_f32 v[114:115], v[114:115], v[116:117]
	v_cvt_pk_bf16_f32 v112, v112, v113
	v_cvt_pk_bf16_f32 v113, v114, v115
	global_store_dwordx2 v[138:139], v[112:113], off offset:96
	global_load_dwordx4 v[112:115], v[128:129], off
	s_waitcnt vmcnt(2)
	v_lshlrev_b32_e32 v126, 16, v124
	v_and_b32_e32 v127, 0xffff0000, v124
	v_lshl_add_u64 v[116:117], s[4:5], 0, v[120:121]
	v_lshl_add_u64 v[116:117], v[116:117], 0, v[130:131]
	global_load_dwordx2 v[118:119], v[122:123], off offset:32
	global_load_dwordx2 v[120:121], v[122:123], off offset:64
	s_nop 0
	global_load_dwordx2 v[122:123], v[122:123], off offset:96
	s_waitcnt vmcnt(3)
	v_add_f32_e32 v108, v108, v112
	v_add_f32_e32 v109, v109, v113
	v_add_f32_e32 v110, v110, v114
	v_add_f32_e32 v111, v111, v115
	v_mul_f32_e32 v108, 0xbfb8aa3b, v108
	v_mul_f32_e32 v109, 0xbfb8aa3b, v109
	v_mul_f32_e32 v110, 0xbfb8aa3b, v110
	v_mul_f32_e32 v111, 0xbfb8aa3b, v111
	v_exp_f32_e32 v108, v108
	v_exp_f32_e32 v109, v109
	v_exp_f32_e32 v110, v110
	v_exp_f32_e32 v111, v111
	v_add_f32_e32 v108, 1.0, v108
	v_add_f32_e32 v109, 1.0, v109
	v_add_f32_e32 v110, 1.0, v110
	v_add_f32_e32 v111, 1.0, v111
	v_rcp_f32_e32 v108, v108
	v_rcp_f32_e32 v109, v109
	v_rcp_f32_e32 v110, v110
	v_rcp_f32_e32 v111, v111
	v_lshlrev_b32_e32 v112, 16, v125
	v_and_b32_e32 v113, 0xffff0000, v125
	v_pk_mul_f32 v[108:109], v[108:109], v[126:127]
	v_pk_mul_f32 v[110:111], v[110:111], v[112:113]
	v_cvt_pk_bf16_f32 v108, v108, v109
	v_cvt_pk_bf16_f32 v109, v110, v111
	global_store_dwordx2 v[116:117], v[108:109], off
	global_load_dwordx4 v[108:111], v[128:129], off offset:64
	s_waitcnt vmcnt(4)
	v_lshlrev_b32_e32 v112, 16, v118
	v_and_b32_e32 v113, 0xffff0000, v118
	s_waitcnt vmcnt(0)
	v_add_f32_e32 v104, v104, v108
	v_add_f32_e32 v105, v105, v109
	v_add_f32_e32 v106, v106, v110
	v_add_f32_e32 v107, v107, v111
	v_mul_f32_e32 v104, 0xbfb8aa3b, v104
	v_mul_f32_e32 v105, 0xbfb8aa3b, v105
	v_mul_f32_e32 v106, 0xbfb8aa3b, v106
	v_mul_f32_e32 v107, 0xbfb8aa3b, v107
	v_exp_f32_e32 v104, v104
	v_exp_f32_e32 v105, v105
	v_exp_f32_e32 v106, v106
	v_exp_f32_e32 v107, v107
	v_add_f32_e32 v104, 1.0, v104
	v_add_f32_e32 v105, 1.0, v105
	v_add_f32_e32 v106, 1.0, v106
	v_add_f32_e32 v107, 1.0, v107
	v_rcp_f32_e32 v104, v104
	v_rcp_f32_e32 v105, v105
	v_rcp_f32_e32 v106, v106
	v_rcp_f32_e32 v107, v107
	v_lshlrev_b32_e32 v108, 16, v119
	v_and_b32_e32 v109, 0xffff0000, v119
	v_pk_mul_f32 v[104:105], v[104:105], v[112:113]
	v_pk_mul_f32 v[106:107], v[106:107], v[108:109]
	v_cvt_pk_bf16_f32 v104, v104, v105
	v_cvt_pk_bf16_f32 v105, v106, v107
	global_store_dwordx2 v[116:117], v[104:105], off offset:32
	global_load_dwordx4 v[104:107], v[128:129], off offset:128
	v_lshlrev_b32_e32 v108, 16, v120
	v_and_b32_e32 v109, 0xffff0000, v120
	v_lshlrev_b32_e32 v110, 16, v122
	v_and_b32_e32 v111, 0xffff0000, v122
	s_waitcnt vmcnt(0)
	v_add_f32_e32 v100, v100, v104
	v_add_f32_e32 v101, v101, v105
	v_add_f32_e32 v102, v102, v106
	v_add_f32_e32 v103, v103, v107
	v_mul_f32_e32 v100, 0xbfb8aa3b, v100
	v_mul_f32_e32 v101, 0xbfb8aa3b, v101
	v_mul_f32_e32 v102, 0xbfb8aa3b, v102
	v_mul_f32_e32 v103, 0xbfb8aa3b, v103
	v_exp_f32_e32 v100, v100
	v_exp_f32_e32 v101, v101
	v_exp_f32_e32 v102, v102
	v_exp_f32_e32 v103, v103
	v_add_f32_e32 v100, 1.0, v100
	v_add_f32_e32 v101, 1.0, v101
	v_add_f32_e32 v102, 1.0, v102
	v_add_f32_e32 v103, 1.0, v103
	v_rcp_f32_e32 v100, v100
	v_rcp_f32_e32 v101, v101
	v_rcp_f32_e32 v102, v102
	v_rcp_f32_e32 v103, v103
	v_lshlrev_b32_e32 v104, 16, v121
	v_and_b32_e32 v105, 0xffff0000, v121
	v_pk_mul_f32 v[100:101], v[100:101], v[108:109]
	v_pk_mul_f32 v[102:103], v[102:103], v[104:105]
	v_cvt_pk_bf16_f32 v100, v100, v101
	v_cvt_pk_bf16_f32 v101, v102, v103
	global_store_dwordx2 v[116:117], v[100:101], off offset:64
	global_load_dwordx4 v[100:103], v[128:129], off offset:192
	v_or_b32_e32 v104, 32, v132
	v_ashrrev_i32_e32 v105, 31, v104
	v_lshlrev_b64 v[104:105], 10, v[104:105]
	v_lshl_add_u64 v[106:107], s[2:3], 0, v[104:105]
	v_lshl_add_u64 v[106:107], v[106:107], 0, v[130:131]
	global_load_dwordx2 v[108:109], v[106:107], off
	s_waitcnt vmcnt(1)
; template <class Epi>
; DI void gemm_tile(char* smem, const bf16_t* __restrict__ A0, int lda0, int ksplit, const bf16_t* __restrict__ A1, int lda1,
;                   const bf16_t* __restrict__ Bt, int K, int row0, int col0, const Epi& epi, int tid) {
;     ...
; #pragma unroll
;   for (int m = 0; m < 8; ++m)
; #pragma unroll
;     for (int n = 0; n < 4; ++n) epi(row0 + wr * 128 + m * 16 + fr, col0 + wc * 64 + n * 16 + fq * 4, acc[m][n]);
	v_add_f32_e32 v96, v96, v100
	v_add_f32_e32 v97, v97, v101
	v_add_f32_e32 v98, v98, v102
	v_add_f32_e32 v99, v99, v103
	v_mul_f32_e32 v96, 0xbfb8aa3b, v96
	v_mul_f32_e32 v97, 0xbfb8aa3b, v97
	v_mul_f32_e32 v98, 0xbfb8aa3b, v98
	v_mul_f32_e32 v99, 0xbfb8aa3b, v99
	v_exp_f32_e32 v96, v96
	v_exp_f32_e32 v97, v97
	v_exp_f32_e32 v98, v98
	v_exp_f32_e32 v99, v99
	v_add_f32_e32 v96, 1.0, v96
	v_add_f32_e32 v97, 1.0, v97
	v_add_f32_e32 v98, 1.0, v98
	v_add_f32_e32 v99, 1.0, v99
	v_rcp_f32_e32 v96, v96
	v_rcp_f32_e32 v97, v97
	v_rcp_f32_e32 v98, v98
	v_rcp_f32_e32 v99, v99
	v_lshlrev_b32_e32 v100, 16, v123
	v_and_b32_e32 v101, 0xffff0000, v123
	v_pk_mul_f32 v[96:97], v[96:97], v[110:111]
	v_pk_mul_f32 v[98:99], v[98:99], v[100:101]
	v_cvt_pk_bf16_f32 v96, v96, v97
	v_cvt_pk_bf16_f32 v97, v98, v99
	global_store_dwordx2 v[116:117], v[96:97], off offset:96
	global_load_dwordx4 v[96:99], v[128:129], off
	s_waitcnt vmcnt(2)
	v_lshlrev_b32_e32 v110, 16, v108
	v_and_b32_e32 v111, 0xffff0000, v108
	v_lshl_add_u64 v[100:101], s[4:5], 0, v[104:105]
	v_lshl_add_u64 v[100:101], v[100:101], 0, v[130:131]
	global_load_dwordx2 v[102:103], v[106:107], off offset:32
	global_load_dwordx2 v[104:105], v[106:107], off offset:64
	s_nop 0
	global_load_dwordx2 v[106:107], v[106:107], off offset:96
	s_waitcnt vmcnt(3)
	v_add_f32_e32 v92, v92, v96
	v_add_f32_e32 v93, v93, v97
	v_add_f32_e32 v94, v94, v98
	v_add_f32_e32 v95, v95, v99
	v_mul_f32_e32 v92, 0xbfb8aa3b, v92
	v_mul_f32_e32 v93, 0xbfb8aa3b, v93
	v_mul_f32_e32 v94, 0xbfb8aa3b, v94
	v_mul_f32_e32 v95, 0xbfb8aa3b, v95
	v_exp_f32_e32 v92, v92
	v_exp_f32_e32 v93, v93
	v_exp_f32_e32 v94, v94
	v_exp_f32_e32 v95, v95
	v_add_f32_e32 v92, 1.0, v92
	v_add_f32_e32 v93, 1.0, v93
	v_add_f32_e32 v94, 1.0, v94
	v_add_f32_e32 v95, 1.0, v95
	v_rcp_f32_e32 v92, v92
	v_rcp_f32_e32 v93, v93
	v_rcp_f32_e32 v94, v94
	v_rcp_f32_e32 v95, v95
	v_lshlrev_b32_e32 v96, 16, v109
	v_and_b32_e32 v97, 0xffff0000, v109
	v_pk_mul_f32 v[92:93], v[92:93], v[110:111]
	v_pk_mul_f32 v[94:95], v[94:95], v[96:97]
	v_cvt_pk_bf16_f32 v92, v92, v93
	v_cvt_pk_bf16_f32 v93, v94, v95
	global_store_dwordx2 v[100:101], v[92:93], off
	global_load_dwordx4 v[92:95], v[128:129], off offset:64
	s_waitcnt vmcnt(4)
	v_lshlrev_b32_e32 v96, 16, v102
	v_and_b32_e32 v97, 0xffff0000, v102
	s_waitcnt vmcnt(0)
	v_add_f32_e32 v88, v88, v92
	v_add_f32_e32 v89, v89, v93
	v_add_f32_e32 v90, v90, v94
	v_add_f32_e32 v91, v91, v95
	v_mul_f32_e32 v88, 0xbfb8aa3b, v88
	v_mul_f32_e32 v89, 0xbfb8aa3b, v89
	v_mul_f32_e32 v90, 0xbfb8aa3b, v90
	v_mul_f32_e32 v91, 0xbfb8aa3b, v91
	v_exp_f32_e32 v88, v88
	v_exp_f32_e32 v89, v89
	v_exp_f32_e32 v90, v90
	v_exp_f32_e32 v91, v91
	v_add_f32_e32 v88, 1.0, v88
	v_add_f32_e32 v89, 1.0, v89
	v_add_f32_e32 v90, 1.0, v90
	v_add_f32_e32 v91, 1.0, v91
	v_rcp_f32_e32 v88, v88
	v_rcp_f32_e32 v89, v89
	v_rcp_f32_e32 v90, v90
	v_rcp_f32_e32 v91, v91
	v_lshlrev_b32_e32 v92, 16, v103
	v_and_b32_e32 v93, 0xffff0000, v103
	v_pk_mul_f32 v[88:89], v[88:89], v[96:97]
	v_pk_mul_f32 v[90:91], v[90:91], v[92:93]
	v_cvt_pk_bf16_f32 v88, v88, v89
	v_cvt_pk_bf16_f32 v89, v90, v91
	global_store_dwordx2 v[100:101], v[88:89], off offset:32
	global_load_dwordx4 v[88:91], v[128:129], off offset:128
	v_lshlrev_b32_e32 v92, 16, v104
	v_and_b32_e32 v93, 0xffff0000, v104
	v_lshlrev_b32_e32 v94, 16, v106
	v_and_b32_e32 v95, 0xffff0000, v106
	s_waitcnt vmcnt(0)
	v_add_f32_e32 v84, v84, v88
	v_add_f32_e32 v85, v85, v89
	v_add_f32_e32 v86, v86, v90
	v_add_f32_e32 v87, v87, v91
	v_mul_f32_e32 v84, 0xbfb8aa3b, v84
	v_mul_f32_e32 v85, 0xbfb8aa3b, v85
	v_mul_f32_e32 v86, 0xbfb8aa3b, v86
	v_mul_f32_e32 v87, 0xbfb8aa3b, v87
	v_exp_f32_e32 v84, v84
	v_exp_f32_e32 v85, v85
	v_exp_f32_e32 v86, v86
	v_exp_f32_e32 v87, v87
	v_add_f32_e32 v84, 1.0, v84
	v_add_f32_e32 v85, 1.0, v85
	v_add_f32_e32 v86, 1.0, v86
	v_add_f32_e32 v87, 1.0, v87
	v_rcp_f32_e32 v84, v84
	v_rcp_f32_e32 v85, v85
	v_rcp_f32_e32 v86, v86
	v_rcp_f32_e32 v87, v87
	v_lshlrev_b32_e32 v88, 16, v105
	v_and_b32_e32 v89, 0xffff0000, v105
	v_pk_mul_f32 v[84:85], v[84:85], v[92:93]
	v_pk_mul_f32 v[86:87], v[86:87], v[88:89]
	v_cvt_pk_bf16_f32 v84, v84, v85
	v_cvt_pk_bf16_f32 v85, v86, v87
	global_store_dwordx2 v[100:101], v[84:85], off offset:64
	global_load_dwordx4 v[84:87], v[128:129], off offset:192
	v_or_b32_e32 v88, 48, v132
	v_ashrrev_i32_e32 v89, 31, v88
	v_lshlrev_b64 v[88:89], 10, v[88:89]
	v_lshl_add_u64 v[90:91], s[2:3], 0, v[88:89]
	v_lshl_add_u64 v[90:91], v[90:91], 0, v[130:131]
	global_load_dwordx2 v[92:93], v[90:91], off
	s_waitcnt vmcnt(1)
	v_add_f32_e32 v80, v80, v84
	v_add_f32_e32 v81, v81, v85
	v_add_f32_e32 v82, v82, v86
	v_add_f32_e32 v83, v83, v87
	v_mul_f32_e32 v80, 0xbfb8aa3b, v80
	v_mul_f32_e32 v81, 0xbfb8aa3b, v81
	v_mul_f32_e32 v82, 0xbfb8aa3b, v82
	v_mul_f32_e32 v83, 0xbfb8aa3b, v83
	v_exp_f32_e32 v80, v80
	v_exp_f32_e32 v81, v81
	v_exp_f32_e32 v82, v82
	v_exp_f32_e32 v83, v83
	v_add_f32_e32 v80, 1.0, v80
	v_add_f32_e32 v81, 1.0, v81
	v_add_f32_e32 v82, 1.0, v82
	v_add_f32_e32 v83, 1.0, v83
	v_rcp_f32_e32 v80, v80
	v_rcp_f32_e32 v81, v81
	v_rcp_f32_e32 v82, v82
	v_rcp_f32_e32 v83, v83
	v_lshlrev_b32_e32 v84, 16, v107
	v_and_b32_e32 v85, 0xffff0000, v107
	v_pk_mul_f32 v[80:81], v[80:81], v[94:95]
	v_pk_mul_f32 v[82:83], v[82:83], v[84:85]
	v_cvt_pk_bf16_f32 v80, v80, v81
	v_cvt_pk_bf16_f32 v81, v82, v83
	global_store_dwordx2 v[100:101], v[80:81], off offset:96
	global_load_dwordx4 v[82:85], v[128:129], off
	v_lshl_add_u64 v[80:81], s[4:5], 0, v[88:89]
	global_load_dwordx2 v[86:87], v[90:91], off offset:32
	global_load_dwordx2 v[88:89], v[90:91], off offset:64
	global_load_dwordx2 v[94:95], v[90:91], off offset:96
	s_waitcnt vmcnt(5)
; template <class Epi>
; DI void gemm_tile(char* smem, const bf16_t* __restrict__ A0, int lda0, int ksplit, const bf16_t* __restrict__ A1, int lda1,
;                   const bf16_t* __restrict__ Bt, int K, int row0, int col0, const Epi& epi, int tid) {
;     ...
; #pragma unroll
;   for (int m = 0; m < 8; ++m)
; #pragma unroll
;     for (int n = 0; n < 4; ++n) epi(row0 + wr * 128 + m * 16 + fr, col0 + wc * 64 + n * 16 + fq * 4, acc[m][n]);
	v_lshlrev_b32_e32 v90, 16, v92
	v_and_b32_e32 v91, 0xffff0000, v92
	v_lshl_add_u64 v[80:81], v[80:81], 0, v[130:131]
	s_waitcnt vmcnt(3)
	v_add_f32_e32 v76, v76, v82
	v_add_f32_e32 v77, v77, v83
	v_add_f32_e32 v78, v78, v84
	v_add_f32_e32 v79, v79, v85
	v_mul_f32_e32 v76, 0xbfb8aa3b, v76
	v_mul_f32_e32 v77, 0xbfb8aa3b, v77
	v_mul_f32_e32 v78, 0xbfb8aa3b, v78
	v_mul_f32_e32 v79, 0xbfb8aa3b, v79
	v_exp_f32_e32 v76, v76
	v_exp_f32_e32 v77, v77
	v_exp_f32_e32 v78, v78
	v_exp_f32_e32 v79, v79
	v_add_f32_e32 v76, 1.0, v76
	v_add_f32_e32 v77, 1.0, v77
	v_add_f32_e32 v78, 1.0, v78
	v_add_f32_e32 v79, 1.0, v79
	v_rcp_f32_e32 v76, v76
	v_rcp_f32_e32 v77, v77
	v_rcp_f32_e32 v78, v78
	v_rcp_f32_e32 v79, v79
	v_lshlrev_b32_e32 v82, 16, v93
	v_and_b32_e32 v83, 0xffff0000, v93
	v_pk_mul_f32 v[76:77], v[76:77], v[90:91]
	v_pk_mul_f32 v[78:79], v[78:79], v[82:83]
	v_cvt_pk_bf16_f32 v76, v76, v77
	v_cvt_pk_bf16_f32 v77, v78, v79
	global_store_dwordx2 v[80:81], v[76:77], off
	global_load_dwordx4 v[76:79], v[128:129], off offset:64
	s_waitcnt vmcnt(4)
	v_lshlrev_b32_e32 v82, 16, v86
	v_and_b32_e32 v83, 0xffff0000, v86
	s_waitcnt vmcnt(0)
	v_add_f32_e32 v72, v72, v76
	v_add_f32_e32 v73, v73, v77
	v_add_f32_e32 v74, v74, v78
	v_add_f32_e32 v75, v75, v79
	v_mul_f32_e32 v72, 0xbfb8aa3b, v72
	v_mul_f32_e32 v73, 0xbfb8aa3b, v73
	v_mul_f32_e32 v74, 0xbfb8aa3b, v74
	v_mul_f32_e32 v75, 0xbfb8aa3b, v75
	v_exp_f32_e32 v72, v72
	v_exp_f32_e32 v73, v73
	v_exp_f32_e32 v74, v74
	v_exp_f32_e32 v75, v75
	v_add_f32_e32 v72, 1.0, v72
	v_add_f32_e32 v73, 1.0, v73
	v_add_f32_e32 v74, 1.0, v74
	v_add_f32_e32 v75, 1.0, v75
	v_rcp_f32_e32 v72, v72
	v_rcp_f32_e32 v73, v73
	v_rcp_f32_e32 v74, v74
	v_rcp_f32_e32 v75, v75
	v_lshlrev_b32_e32 v76, 16, v87
	v_and_b32_e32 v77, 0xffff0000, v87
	v_pk_mul_f32 v[72:73], v[72:73], v[82:83]
	v_pk_mul_f32 v[74:75], v[74:75], v[76:77]
	v_cvt_pk_bf16_f32 v72, v72, v73
	v_cvt_pk_bf16_f32 v73, v74, v75
	global_store_dwordx2 v[80:81], v[72:73], off offset:32
	global_load_dwordx4 v[72:75], v[128:129], off offset:128
	v_lshlrev_b32_e32 v76, 16, v88
	v_and_b32_e32 v77, 0xffff0000, v88
	v_lshlrev_b32_e32 v78, 16, v94
	v_and_b32_e32 v79, 0xffff0000, v94
	s_waitcnt vmcnt(0)
	v_add_f32_e32 v68, v68, v72
	v_add_f32_e32 v69, v69, v73
	v_add_f32_e32 v70, v70, v74
	v_add_f32_e32 v71, v71, v75
	v_mul_f32_e32 v68, 0xbfb8aa3b, v68
	v_mul_f32_e32 v69, 0xbfb8aa3b, v69
	v_mul_f32_e32 v70, 0xbfb8aa3b, v70
	v_mul_f32_e32 v71, 0xbfb8aa3b, v71
	v_exp_f32_e32 v68, v68
	v_exp_f32_e32 v69, v69
	v_exp_f32_e32 v70, v70
	v_exp_f32_e32 v71, v71
	v_add_f32_e32 v68, 1.0, v68
	v_add_f32_e32 v69, 1.0, v69
	v_add_f32_e32 v70, 1.0, v70
	v_add_f32_e32 v71, 1.0, v71
	v_rcp_f32_e32 v68, v68
	v_rcp_f32_e32 v69, v69
	v_rcp_f32_e32 v70, v70
	v_rcp_f32_e32 v71, v71
	v_lshlrev_b32_e32 v72, 16, v89
	v_and_b32_e32 v73, 0xffff0000, v89
	v_pk_mul_f32 v[68:69], v[68:69], v[76:77]
	v_pk_mul_f32 v[70:71], v[70:71], v[72:73]
	v_cvt_pk_bf16_f32 v68, v68, v69
	v_cvt_pk_bf16_f32 v69, v70, v71
	global_store_dwordx2 v[80:81], v[68:69], off offset:64
	global_load_dwordx4 v[68:71], v[128:129], off offset:192
	v_or_b32_e32 v72, 64, v132
	v_ashrrev_i32_e32 v73, 31, v72
	v_lshlrev_b64 v[72:73], 10, v[72:73]
	v_lshl_add_u64 v[74:75], s[2:3], 0, v[72:73]
	v_lshl_add_u64 v[74:75], v[74:75], 0, v[130:131]
	global_load_dwordx2 v[76:77], v[74:75], off
	s_waitcnt vmcnt(1)
	v_add_f32_e32 v64, v64, v68
	v_add_f32_e32 v65, v65, v69
	v_add_f32_e32 v66, v66, v70
	v_add_f32_e32 v67, v67, v71
	v_mul_f32_e32 v64, 0xbfb8aa3b, v64
	v_mul_f32_e32 v65, 0xbfb8aa3b, v65
	v_mul_f32_e32 v66, 0xbfb8aa3b, v66
	v_mul_f32_e32 v67, 0xbfb8aa3b, v67
	v_exp_f32_e32 v64, v64
	v_exp_f32_e32 v65, v65
	v_exp_f32_e32 v66, v66
	v_exp_f32_e32 v67, v67
	v_add_f32_e32 v64, 1.0, v64
	v_add_f32_e32 v65, 1.0, v65
	v_add_f32_e32 v66, 1.0, v66
	v_add_f32_e32 v67, 1.0, v67
	v_rcp_f32_e32 v64, v64
	v_rcp_f32_e32 v65, v65
	v_rcp_f32_e32 v66, v66
	v_rcp_f32_e32 v67, v67
	v_lshlrev_b32_e32 v68, 16, v95
	v_and_b32_e32 v69, 0xffff0000, v95
	v_pk_mul_f32 v[64:65], v[64:65], v[78:79]
	v_pk_mul_f32 v[66:67], v[66:67], v[68:69]
	v_cvt_pk_bf16_f32 v64, v64, v65
	v_cvt_pk_bf16_f32 v65, v66, v67
	global_store_dwordx2 v[80:81], v[64:65], off offset:96
	global_load_dwordx4 v[66:69], v[128:129], off
	v_lshl_add_u64 v[64:65], s[4:5], 0, v[72:73]
	global_load_dwordx2 v[70:71], v[74:75], off offset:32
	global_load_dwordx2 v[72:73], v[74:75], off offset:64
	global_load_dwordx2 v[78:79], v[74:75], off offset:96
	s_waitcnt vmcnt(5)
	v_lshlrev_b32_e32 v74, 16, v76
	v_and_b32_e32 v75, 0xffff0000, v76
	v_lshl_add_u64 v[64:65], v[64:65], 0, v[130:131]
	s_waitcnt vmcnt(3)
	v_add_f32_e32 v60, v60, v66
	v_add_f32_e32 v61, v61, v67
	v_add_f32_e32 v62, v62, v68
	v_add_f32_e32 v63, v63, v69
	v_mul_f32_e32 v60, 0xbfb8aa3b, v60
	v_mul_f32_e32 v61, 0xbfb8aa3b, v61
	v_mul_f32_e32 v62, 0xbfb8aa3b, v62
	v_mul_f32_e32 v63, 0xbfb8aa3b, v63
	v_exp_f32_e32 v60, v60
	v_exp_f32_e32 v61, v61
	v_exp_f32_e32 v62, v62
	v_exp_f32_e32 v63, v63
	v_add_f32_e32 v60, 1.0, v60
	v_add_f32_e32 v61, 1.0, v61
	v_add_f32_e32 v62, 1.0, v62
	v_add_f32_e32 v63, 1.0, v63
	v_rcp_f32_e32 v60, v60
	v_rcp_f32_e32 v61, v61
	v_rcp_f32_e32 v62, v62
	v_rcp_f32_e32 v63, v63
	v_lshlrev_b32_e32 v66, 16, v77
	v_and_b32_e32 v67, 0xffff0000, v77
	v_pk_mul_f32 v[60:61], v[60:61], v[74:75]
	v_pk_mul_f32 v[62:63], v[62:63], v[66:67]
	v_cvt_pk_bf16_f32 v60, v60, v61
	v_cvt_pk_bf16_f32 v61, v62, v63
	global_store_dwordx2 v[64:65], v[60:61], off
	global_load_dwordx4 v[60:63], v[128:129], off offset:64
	s_waitcnt vmcnt(4)
	v_lshlrev_b32_e32 v66, 16, v70
	v_and_b32_e32 v67, 0xffff0000, v70
	s_waitcnt vmcnt(0)
	v_add_f32_e32 v56, v56, v60
	v_add_f32_e32 v57, v57, v61
	v_add_f32_e32 v58, v58, v62
	v_add_f32_e32 v59, v59, v63
	v_mul_f32_e32 v56, 0xbfb8aa3b, v56
	v_mul_f32_e32 v57, 0xbfb8aa3b, v57
	v_mul_f32_e32 v58, 0xbfb8aa3b, v58
	v_mul_f32_e32 v59, 0xbfb8aa3b, v59
	v_exp_f32_e32 v56, v56
	v_exp_f32_e32 v57, v57
	v_exp_f32_e32 v58, v58
	v_exp_f32_e32 v59, v59
	v_add_f32_e32 v56, 1.0, v56
	v_add_f32_e32 v57, 1.0, v57
	v_add_f32_e32 v58, 1.0, v58
	v_add_f32_e32 v59, 1.0, v59
	v_rcp_f32_e32 v56, v56
	v_rcp_f32_e32 v57, v57
	v_rcp_f32_e32 v58, v58
	v_rcp_f32_e32 v59, v59
	v_lshlrev_b32_e32 v60, 16, v71
	v_and_b32_e32 v61, 0xffff0000, v71
	v_pk_mul_f32 v[56:57], v[56:57], v[66:67]
	v_pk_mul_f32 v[58:59], v[58:59], v[60:61]
	v_cvt_pk_bf16_f32 v56, v56, v57
	v_cvt_pk_bf16_f32 v57, v58, v59
	global_store_dwordx2 v[64:65], v[56:57], off offset:32
	global_load_dwordx4 v[56:59], v[128:129], off offset:128
	v_lshlrev_b32_e32 v60, 16, v72
	v_and_b32_e32 v61, 0xffff0000, v72
	v_lshlrev_b32_e32 v62, 16, v78
	v_and_b32_e32 v63, 0xffff0000, v78
	s_waitcnt vmcnt(0)
	v_add_f32_e32 v52, v52, v56
	v_add_f32_e32 v53, v53, v57
	v_add_f32_e32 v54, v54, v58
	v_add_f32_e32 v55, v55, v59
	v_mul_f32_e32 v52, 0xbfb8aa3b, v52
	v_mul_f32_e32 v53, 0xbfb8aa3b, v53
	v_mul_f32_e32 v54, 0xbfb8aa3b, v54
	v_mul_f32_e32 v55, 0xbfb8aa3b, v55
	v_exp_f32_e32 v52, v52
	v_exp_f32_e32 v53, v53
	v_exp_f32_e32 v54, v54
	v_exp_f32_e32 v55, v55
	v_add_f32_e32 v52, 1.0, v52
	v_add_f32_e32 v53, 1.0, v53
	v_add_f32_e32 v54, 1.0, v54
	v_add_f32_e32 v55, 1.0, v55
	v_rcp_f32_e32 v52, v52
	v_rcp_f32_e32 v53, v53
	v_rcp_f32_e32 v54, v54
	v_rcp_f32_e32 v55, v55
	v_lshlrev_b32_e32 v56, 16, v73
	v_and_b32_e32 v57, 0xffff0000, v73
	v_pk_mul_f32 v[52:53], v[52:53], v[60:61]
	v_pk_mul_f32 v[54:55], v[54:55], v[56:57]
	v_cvt_pk_bf16_f32 v52, v52, v53
	v_cvt_pk_bf16_f32 v53, v54, v55
	global_store_dwordx2 v[64:65], v[52:53], off offset:64
	global_load_dwordx4 v[52:55], v[128:129], off offset:192
	v_or_b32_e32 v56, 0x50, v132
	v_ashrrev_i32_e32 v57, 31, v56
	v_lshlrev_b64 v[56:57], 10, v[56:57]
	v_lshl_add_u64 v[58:59], s[2:3], 0, v[56:57]
	v_lshl_add_u64 v[58:59], v[58:59], 0, v[130:131]
	global_load_dwordx2 v[60:61], v[58:59], off
	s_waitcnt vmcnt(1)
	v_add_f32_e32 v48, v48, v52
	v_add_f32_e32 v49, v49, v53
	v_add_f32_e32 v50, v50, v54
	v_add_f32_e32 v51, v51, v55
	v_mul_f32_e32 v48, 0xbfb8aa3b, v48
	v_mul_f32_e32 v49, 0xbfb8aa3b, v49
	v_mul_f32_e32 v50, 0xbfb8aa3b, v50
	v_mul_f32_e32 v51, 0xbfb8aa3b, v51
	v_exp_f32_e32 v48, v48
	v_exp_f32_e32 v49, v49
	v_exp_f32_e32 v50, v50
	v_exp_f32_e32 v51, v51
	v_add_f32_e32 v48, 1.0, v48
	v_add_f32_e32 v49, 1.0, v49
	v_add_f32_e32 v50, 1.0, v50
	v_add_f32_e32 v51, 1.0, v51
	v_rcp_f32_e32 v48, v48
	v_rcp_f32_e32 v49, v49
	v_rcp_f32_e32 v50, v50
	v_rcp_f32_e32 v51, v51
	v_lshlrev_b32_e32 v52, 16, v79
	v_and_b32_e32 v53, 0xffff0000, v79
	v_pk_mul_f32 v[48:49], v[48:49], v[62:63]
	v_pk_mul_f32 v[50:51], v[50:51], v[52:53]
	v_cvt_pk_bf16_f32 v48, v48, v49
	v_cvt_pk_bf16_f32 v49, v50, v51
	global_store_dwordx2 v[64:65], v[48:49], off offset:96
	global_load_dwordx4 v[50:53], v[128:129], off
	v_lshl_add_u64 v[48:49], s[4:5], 0, v[56:57]
	global_load_dwordx2 v[54:55], v[58:59], off offset:32
	global_load_dwordx2 v[56:57], v[58:59], off offset:64
	global_load_dwordx2 v[62:63], v[58:59], off offset:96
	s_waitcnt vmcnt(5)
	v_lshlrev_b32_e32 v58, 16, v60
	v_and_b32_e32 v59, 0xffff0000, v60
	v_lshl_add_u64 v[48:49], v[48:49], 0, v[130:131]
	s_waitcnt vmcnt(3)
	v_add_f32_e32 v44, v44, v50
	v_add_f32_e32 v45, v45, v51
	v_add_f32_e32 v46, v46, v52
	v_add_f32_e32 v47, v47, v53
	v_mul_f32_e32 v44, 0xbfb8aa3b, v44
	v_mul_f32_e32 v45, 0xbfb8aa3b, v45
	v_mul_f32_e32 v46, 0xbfb8aa3b, v46
	v_mul_f32_e32 v47, 0xbfb8aa3b, v47
	v_exp_f32_e32 v44, v44
	v_exp_f32_e32 v45, v45
	v_exp_f32_e32 v46, v46
	v_exp_f32_e32 v47, v47
	v_add_f32_e32 v44, 1.0, v44
	v_add_f32_e32 v45, 1.0, v45
	v_add_f32_e32 v46, 1.0, v46
	v_add_f32_e32 v47, 1.0, v47
	v_rcp_f32_e32 v44, v44
	v_rcp_f32_e32 v45, v45
	v_rcp_f32_e32 v46, v46
	v_rcp_f32_e32 v47, v47
	v_lshlrev_b32_e32 v50, 16, v61
	v_and_b32_e32 v51, 0xffff0000, v61
	v_pk_mul_f32 v[44:45], v[44:45], v[58:59]
	v_pk_mul_f32 v[46:47], v[46:47], v[50:51]
	v_cvt_pk_bf16_f32 v44, v44, v45
	v_cvt_pk_bf16_f32 v45, v46, v47
	global_store_dwordx2 v[48:49], v[44:45], off
	global_load_dwordx4 v[44:47], v[128:129], off offset:64
	s_waitcnt vmcnt(4)
	v_lshlrev_b32_e32 v50, 16, v54
	v_and_b32_e32 v51, 0xffff0000, v54
	s_waitcnt vmcnt(0)
	v_add_f32_e32 v40, v40, v44
	v_add_f32_e32 v41, v41, v45
	v_add_f32_e32 v42, v42, v46
	v_add_f32_e32 v43, v43, v47
	v_mul_f32_e32 v40, 0xbfb8aa3b, v40
	v_mul_f32_e32 v41, 0xbfb8aa3b, v41
	v_mul_f32_e32 v42, 0xbfb8aa3b, v42
	v_mul_f32_e32 v43, 0xbfb8aa3b, v43
	v_exp_f32_e32 v40, v40
	v_exp_f32_e32 v41, v41
	v_exp_f32_e32 v42, v42
	v_exp_f32_e32 v43, v43
	v_add_f32_e32 v40, 1.0, v40
	v_add_f32_e32 v41, 1.0, v41
	v_add_f32_e32 v42, 1.0, v42
	v_add_f32_e32 v43, 1.0, v43
	v_rcp_f32_e32 v40, v40
	v_rcp_f32_e32 v41, v41
	v_rcp_f32_e32 v42, v42
	v_rcp_f32_e32 v43, v43
	v_lshlrev_b32_e32 v44, 16, v55
	v_and_b32_e32 v45, 0xffff0000, v55
	v_pk_mul_f32 v[40:41], v[40:41], v[50:51]
	v_pk_mul_f32 v[42:43], v[42:43], v[44:45]
	v_cvt_pk_bf16_f32 v40, v40, v41
	v_cvt_pk_bf16_f32 v41, v42, v43
	global_store_dwordx2 v[48:49], v[40:41], off offset:32
	global_load_dwordx4 v[40:43], v[128:129], off offset:128
	v_lshlrev_b32_e32 v44, 16, v56
	v_and_b32_e32 v45, 0xffff0000, v56
	v_lshlrev_b32_e32 v46, 16, v62
	v_and_b32_e32 v47, 0xffff0000, v62
	s_waitcnt vmcnt(0)
	v_add_f32_e32 v36, v36, v40
	v_add_f32_e32 v37, v37, v41
	v_add_f32_e32 v38, v38, v42
	v_add_f32_e32 v39, v39, v43
	v_mul_f32_e32 v36, 0xbfb8aa3b, v36
	v_mul_f32_e32 v37, 0xbfb8aa3b, v37
	v_mul_f32_e32 v38, 0xbfb8aa3b, v38
	v_mul_f32_e32 v39, 0xbfb8aa3b, v39
	v_exp_f32_e32 v36, v36
	v_exp_f32_e32 v37, v37
	v_exp_f32_e32 v38, v38
	v_exp_f32_e32 v39, v39
	v_add_f32_e32 v36, 1.0, v36
	v_add_f32_e32 v37, 1.0, v37
	v_add_f32_e32 v38, 1.0, v38
	v_add_f32_e32 v39, 1.0, v39
	v_rcp_f32_e32 v36, v36
	v_rcp_f32_e32 v37, v37
	v_rcp_f32_e32 v38, v38
	v_rcp_f32_e32 v39, v39
	v_lshlrev_b32_e32 v40, 16, v57
	v_and_b32_e32 v41, 0xffff0000, v57
	v_pk_mul_f32 v[36:37], v[36:37], v[44:45]
	v_pk_mul_f32 v[38:39], v[38:39], v[40:41]
	v_cvt_pk_bf16_f32 v36, v36, v37
	v_cvt_pk_bf16_f32 v37, v38, v39
	global_store_dwordx2 v[48:49], v[36:37], off offset:64
	global_load_dwordx4 v[36:39], v[128:129], off offset:192
	v_or_b32_e32 v40, 0x60, v132
	v_ashrrev_i32_e32 v41, 31, v40
	v_lshlrev_b64 v[40:41], 10, v[40:41]
	v_lshl_add_u64 v[42:43], s[2:3], 0, v[40:41]
	v_lshl_add_u64 v[42:43], v[42:43], 0, v[130:131]
	global_load_dwordx2 v[44:45], v[42:43], off
	s_waitcnt vmcnt(1)
	v_add_f32_e32 v32, v32, v36
	v_add_f32_e32 v33, v33, v37
	v_add_f32_e32 v34, v34, v38
	v_add_f32_e32 v35, v35, v39
	v_mul_f32_e32 v32, 0xbfb8aa3b, v32
	v_mul_f32_e32 v33, 0xbfb8aa3b, v33
	v_mul_f32_e32 v34, 0xbfb8aa3b, v34
	v_mul_f32_e32 v35, 0xbfb8aa3b, v35
	v_exp_f32_e32 v32, v32
	v_exp_f32_e32 v33, v33
	v_exp_f32_e32 v34, v34
	v_exp_f32_e32 v35, v35
	v_add_f32_e32 v32, 1.0, v32
	v_add_f32_e32 v33, 1.0, v33
	v_add_f32_e32 v34, 1.0, v34
	v_add_f32_e32 v35, 1.0, v35
	v_rcp_f32_e32 v32, v32
	v_rcp_f32_e32 v33, v33
	v_rcp_f32_e32 v34, v34
	v_rcp_f32_e32 v35, v35
	v_lshlrev_b32_e32 v36, 16, v63
	v_and_b32_e32 v37, 0xffff0000, v63
	v_pk_mul_f32 v[32:33], v[32:33], v[46:47]
	v_pk_mul_f32 v[34:35], v[34:35], v[36:37]
	v_cvt_pk_bf16_f32 v32, v32, v33
	v_cvt_pk_bf16_f32 v33, v34, v35
	global_store_dwordx2 v[48:49], v[32:33], off offset:96
	global_load_dwordx4 v[34:37], v[128:129], off
	v_lshl_add_u64 v[32:33], s[4:5], 0, v[40:41]
	global_load_dwordx2 v[38:39], v[42:43], off offset:32
	global_load_dwordx2 v[40:41], v[42:43], off offset:64
	global_load_dwordx2 v[46:47], v[42:43], off offset:96
	s_waitcnt vmcnt(5)
	v_lshlrev_b32_e32 v42, 16, v44
	v_and_b32_e32 v43, 0xffff0000, v44
	v_lshl_add_u64 v[32:33], v[32:33], 0, v[130:131]
	s_waitcnt vmcnt(3)
	v_add_f32_e32 v28, v28, v34
	v_add_f32_e32 v29, v29, v35
	v_add_f32_e32 v30, v30, v36
	v_add_f32_e32 v31, v31, v37
	v_mul_f32_e32 v28, 0xbfb8aa3b, v28
	v_mul_f32_e32 v29, 0xbfb8aa3b, v29
	v_mul_f32_e32 v30, 0xbfb8aa3b, v30
	v_mul_f32_e32 v31, 0xbfb8aa3b, v31
	v_exp_f32_e32 v28, v28
	v_exp_f32_e32 v29, v29
	v_exp_f32_e32 v30, v30
	v_exp_f32_e32 v31, v31
	v_add_f32_e32 v28, 1.0, v28
	v_add_f32_e32 v29, 1.0, v29
	v_add_f32_e32 v30, 1.0, v30
	v_add_f32_e32 v31, 1.0, v31
	v_rcp_f32_e32 v28, v28
	v_rcp_f32_e32 v29, v29
	v_rcp_f32_e32 v30, v30
	v_rcp_f32_e32 v31, v31
	v_lshlrev_b32_e32 v34, 16, v45
	v_and_b32_e32 v35, 0xffff0000, v45
	v_pk_mul_f32 v[28:29], v[28:29], v[42:43]
	v_pk_mul_f32 v[30:31], v[30:31], v[34:35]
	v_cvt_pk_bf16_f32 v28, v28, v29
	v_cvt_pk_bf16_f32 v29, v30, v31
	global_store_dwordx2 v[32:33], v[28:29], off
	global_load_dwordx4 v[28:31], v[128:129], off offset:64
	s_waitcnt vmcnt(4)
	v_lshlrev_b32_e32 v34, 16, v38
	v_and_b32_e32 v35, 0xffff0000, v38
	s_waitcnt vmcnt(0)
	v_add_f32_e32 v24, v24, v28
	v_add_f32_e32 v25, v25, v29
	v_add_f32_e32 v26, v26, v30
	v_add_f32_e32 v27, v27, v31
	v_mul_f32_e32 v24, 0xbfb8aa3b, v24
	v_mul_f32_e32 v25, 0xbfb8aa3b, v25
	v_mul_f32_e32 v26, 0xbfb8aa3b, v26
	v_mul_f32_e32 v27, 0xbfb8aa3b, v27
	v_exp_f32_e32 v24, v24
	v_exp_f32_e32 v25, v25
	v_exp_f32_e32 v26, v26
	v_exp_f32_e32 v27, v27
	v_add_f32_e32 v24, 1.0, v24
	v_add_f32_e32 v25, 1.0, v25
	v_add_f32_e32 v26, 1.0, v26
	v_add_f32_e32 v27, 1.0, v27
	v_rcp_f32_e32 v24, v24
	v_rcp_f32_e32 v25, v25
	v_rcp_f32_e32 v26, v26
	v_rcp_f32_e32 v27, v27
	v_lshlrev_b32_e32 v28, 16, v39
	v_and_b32_e32 v29, 0xffff0000, v39
	v_pk_mul_f32 v[24:25], v[24:25], v[34:35]
	v_pk_mul_f32 v[26:27], v[26:27], v[28:29]
	v_cvt_pk_bf16_f32 v24, v24, v25
	v_cvt_pk_bf16_f32 v25, v26, v27
	global_store_dwordx2 v[32:33], v[24:25], off offset:32
	global_load_dwordx4 v[24:27], v[128:129], off offset:128
	v_lshlrev_b32_e32 v28, 16, v40
	v_and_b32_e32 v29, 0xffff0000, v40
	v_lshlrev_b32_e32 v30, 16, v46
	v_and_b32_e32 v31, 0xffff0000, v46
	s_waitcnt vmcnt(0)
	v_add_f32_e32 v20, v20, v24
	v_add_f32_e32 v21, v21, v25
	v_add_f32_e32 v22, v22, v26
	v_add_f32_e32 v23, v23, v27
	v_mul_f32_e32 v20, 0xbfb8aa3b, v20
	v_mul_f32_e32 v21, 0xbfb8aa3b, v21
	v_mul_f32_e32 v22, 0xbfb8aa3b, v22
	v_mul_f32_e32 v23, 0xbfb8aa3b, v23
	v_exp_f32_e32 v20, v20
	v_exp_f32_e32 v21, v21
	v_exp_f32_e32 v22, v22
	v_exp_f32_e32 v23, v23
	v_add_f32_e32 v20, 1.0, v20
	v_add_f32_e32 v21, 1.0, v21
	v_add_f32_e32 v22, 1.0, v22
	v_add_f32_e32 v23, 1.0, v23
	v_rcp_f32_e32 v20, v20
	v_rcp_f32_e32 v21, v21
	v_rcp_f32_e32 v22, v22
	v_rcp_f32_e32 v23, v23
	v_lshlrev_b32_e32 v24, 16, v41
	v_and_b32_e32 v25, 0xffff0000, v41
	v_pk_mul_f32 v[20:21], v[20:21], v[28:29]
	v_pk_mul_f32 v[22:23], v[22:23], v[24:25]
	v_cvt_pk_bf16_f32 v20, v20, v21
	v_cvt_pk_bf16_f32 v21, v22, v23
	global_store_dwordx2 v[32:33], v[20:21], off offset:64
	global_load_dwordx4 v[20:23], v[128:129], off offset:192
	v_or_b32_e32 v24, 0x70, v132
	v_ashrrev_i32_e32 v25, 31, v24
	v_lshlrev_b64 v[24:25], 10, v[24:25]
	v_lshl_add_u64 v[26:27], s[2:3], 0, v[24:25]
	v_lshl_add_u64 v[26:27], v[26:27], 0, v[130:131]
	global_load_dwordx2 v[28:29], v[26:27], off
	s_waitcnt vmcnt(1)
; template <class Epi>
; DI void gemm_tile(char* smem, const bf16_t* __restrict__ A0, int lda0, int ksplit, const bf16_t* __restrict__ A1, int lda1,
;                   const bf16_t* __restrict__ Bt, int K, int row0, int col0, const Epi& epi, int tid) {
;     ...
; #pragma unroll
;   for (int m = 0; m < 8; ++m)
; #pragma unroll
;     for (int n = 0; n < 4; ++n) epi(row0 + wr * 128 + m * 16 + fr, col0 + wc * 64 + n * 16 + fq * 4, acc[m][n]);
	v_add_f32_e32 v16, v16, v20
	v_add_f32_e32 v17, v17, v21
	v_add_f32_e32 v18, v18, v22
	v_add_f32_e32 v19, v19, v23
	v_mul_f32_e32 v16, 0xbfb8aa3b, v16
	v_mul_f32_e32 v17, 0xbfb8aa3b, v17
	v_mul_f32_e32 v18, 0xbfb8aa3b, v18
	v_mul_f32_e32 v19, 0xbfb8aa3b, v19
	v_exp_f32_e32 v16, v16
	v_exp_f32_e32 v17, v17
	v_exp_f32_e32 v18, v18
	v_exp_f32_e32 v19, v19
	v_add_f32_e32 v16, 1.0, v16
	v_add_f32_e32 v17, 1.0, v17
	v_add_f32_e32 v18, 1.0, v18
	v_add_f32_e32 v19, 1.0, v19
	v_rcp_f32_e32 v16, v16
	v_rcp_f32_e32 v17, v17
	v_rcp_f32_e32 v18, v18
	v_rcp_f32_e32 v19, v19
	v_lshlrev_b32_e32 v20, 16, v47
	v_and_b32_e32 v21, 0xffff0000, v47
	v_pk_mul_f32 v[16:17], v[16:17], v[30:31]
	v_pk_mul_f32 v[18:19], v[18:19], v[20:21]
	v_cvt_pk_bf16_f32 v16, v16, v17
	v_cvt_pk_bf16_f32 v17, v18, v19
	global_store_dwordx2 v[32:33], v[16:17], off offset:96
	global_load_dwordx4 v[16:19], v[128:129], off
	v_lshl_add_u64 v[20:21], s[4:5], 0, v[24:25]
	global_load_dwordx2 v[22:23], v[26:27], off offset:32
	global_load_dwordx2 v[24:25], v[26:27], off offset:64
	global_load_dwordx2 v[30:31], v[26:27], off offset:96
	s_waitcnt vmcnt(5)
	v_lshlrev_b32_e32 v26, 16, v28
	v_and_b32_e32 v27, 0xffff0000, v28
	v_lshl_add_u64 v[20:21], v[20:21], 0, v[130:131]
	s_waitcnt vmcnt(3)
	v_add_f32_e32 v12, v12, v16
	v_add_f32_e32 v13, v13, v17
	v_add_f32_e32 v14, v14, v18
	v_add_f32_e32 v15, v15, v19
	v_mul_f32_e32 v12, 0xbfb8aa3b, v12
	v_mul_f32_e32 v13, 0xbfb8aa3b, v13
	v_mul_f32_e32 v14, 0xbfb8aa3b, v14
	v_mul_f32_e32 v15, 0xbfb8aa3b, v15
	v_exp_f32_e32 v12, v12
	v_exp_f32_e32 v13, v13
	v_exp_f32_e32 v14, v14
	v_exp_f32_e32 v15, v15
	v_add_f32_e32 v12, 1.0, v12
	v_add_f32_e32 v13, 1.0, v13
	v_add_f32_e32 v14, 1.0, v14
	v_add_f32_e32 v15, 1.0, v15
	v_rcp_f32_e32 v12, v12
	v_rcp_f32_e32 v13, v13
	v_rcp_f32_e32 v14, v14
	v_rcp_f32_e32 v15, v15
	v_lshlrev_b32_e32 v16, 16, v29
	v_and_b32_e32 v17, 0xffff0000, v29
	v_pk_mul_f32 v[12:13], v[12:13], v[26:27]
	v_pk_mul_f32 v[14:15], v[14:15], v[16:17]
	v_cvt_pk_bf16_f32 v12, v12, v13
	v_cvt_pk_bf16_f32 v13, v14, v15
	global_store_dwordx2 v[20:21], v[12:13], off
	global_load_dwordx4 v[12:15], v[128:129], off offset:64
	s_waitcnt vmcnt(4)
	v_lshlrev_b32_e32 v16, 16, v22
	v_and_b32_e32 v17, 0xffff0000, v22
	s_waitcnt vmcnt(0)
	v_add_f32_e32 v8, v8, v12
	v_add_f32_e32 v9, v9, v13
	v_add_f32_e32 v10, v10, v14
	v_add_f32_e32 v11, v11, v15
	v_mul_f32_e32 v8, 0xbfb8aa3b, v8
	v_mul_f32_e32 v9, 0xbfb8aa3b, v9
	v_mul_f32_e32 v10, 0xbfb8aa3b, v10
	v_mul_f32_e32 v11, 0xbfb8aa3b, v11
	v_exp_f32_e32 v8, v8
	v_exp_f32_e32 v9, v9
	v_exp_f32_e32 v10, v10
	v_exp_f32_e32 v11, v11
	v_add_f32_e32 v8, 1.0, v8
	v_add_f32_e32 v9, 1.0, v9
	v_add_f32_e32 v10, 1.0, v10
	v_add_f32_e32 v11, 1.0, v11
	v_rcp_f32_e32 v8, v8
	v_rcp_f32_e32 v9, v9
	v_rcp_f32_e32 v10, v10
	v_rcp_f32_e32 v11, v11
	v_lshlrev_b32_e32 v12, 16, v23
	v_and_b32_e32 v13, 0xffff0000, v23
	v_pk_mul_f32 v[8:9], v[8:9], v[16:17]
	v_pk_mul_f32 v[10:11], v[10:11], v[12:13]
	v_cvt_pk_bf16_f32 v8, v8, v9
	v_cvt_pk_bf16_f32 v9, v10, v11
	global_store_dwordx2 v[20:21], v[8:9], off offset:32
	global_load_dwordx4 v[8:11], v[128:129], off offset:128
	v_lshlrev_b32_e32 v12, 16, v24
	v_and_b32_e32 v13, 0xffff0000, v24
	s_waitcnt vmcnt(0)
	v_add_f32_e32 v4, v4, v8
	v_add_f32_e32 v5, v5, v9
	v_add_f32_e32 v6, v6, v10
	v_add_f32_e32 v7, v7, v11
	v_mul_f32_e32 v4, 0xbfb8aa3b, v4
	v_mul_f32_e32 v5, 0xbfb8aa3b, v5
	v_mul_f32_e32 v6, 0xbfb8aa3b, v6
	v_mul_f32_e32 v7, 0xbfb8aa3b, v7
	v_exp_f32_e32 v4, v4
	v_exp_f32_e32 v5, v5
	v_exp_f32_e32 v6, v6
	v_exp_f32_e32 v7, v7
	v_add_f32_e32 v4, 1.0, v4
	v_add_f32_e32 v5, 1.0, v5
	v_add_f32_e32 v6, 1.0, v6
	v_add_f32_e32 v7, 1.0, v7
	v_rcp_f32_e32 v4, v4
	v_rcp_f32_e32 v5, v5
	v_rcp_f32_e32 v6, v6
	v_rcp_f32_e32 v7, v7
	v_lshlrev_b32_e32 v8, 16, v25
	v_and_b32_e32 v9, 0xffff0000, v25
	v_pk_mul_f32 v[4:5], v[4:5], v[12:13]
	v_pk_mul_f32 v[6:7], v[6:7], v[8:9]
	v_cvt_pk_bf16_f32 v4, v4, v5
	v_cvt_pk_bf16_f32 v5, v6, v7
	global_store_dwordx2 v[20:21], v[4:5], off offset:64
	global_load_dwordx4 v[4:7], v[128:129], off offset:192
	v_lshlrev_b32_e32 v8, 16, v30
	v_and_b32_e32 v9, 0xffff0000, v30
	s_waitcnt vmcnt(0)
	v_add_f32_e32 v0, v0, v4
	v_add_f32_e32 v1, v1, v5
	v_add_f32_e32 v2, v2, v6
	v_add_f32_e32 v3, v3, v7
	v_mul_f32_e32 v0, 0xbfb8aa3b, v0
	v_mul_f32_e32 v1, 0xbfb8aa3b, v1
	v_mul_f32_e32 v2, 0xbfb8aa3b, v2
	v_mul_f32_e32 v3, 0xbfb8aa3b, v3
	v_exp_f32_e32 v0, v0
	v_exp_f32_e32 v1, v1
	v_exp_f32_e32 v2, v2
	v_exp_f32_e32 v3, v3
	v_add_f32_e32 v0, 1.0, v0
	v_add_f32_e32 v1, 1.0, v1
	v_add_f32_e32 v2, 1.0, v2
	v_add_f32_e32 v3, 1.0, v3
	v_rcp_f32_e32 v0, v0
	v_rcp_f32_e32 v1, v1
	v_rcp_f32_e32 v2, v2
	v_rcp_f32_e32 v3, v3
	v_lshlrev_b32_e32 v4, 16, v31
	v_and_b32_e32 v5, 0xffff0000, v31
	v_pk_mul_f32 v[0:1], v[0:1], v[8:9]
	v_pk_mul_f32 v[2:3], v[2:3], v[4:5]
	v_cvt_pk_bf16_f32 v0, v0, v1
	v_cvt_pk_bf16_f32 v1, v2, v3
	global_store_dwordx2 v[20:21], v[0:1], off offset:96
	s_cbranch_scc0 .LBB0_1827

; template <class Epi>
; DI void gemm_tile(char* smem, const bf16_t* __restrict__ A0, int lda0, int ksplit, const bf16_t* __restrict__ A1, int lda1,
;                   const bf16_t* __restrict__ Bt, int K, int row0, int col0, const Epi& epi, int tid) {
;   constexpr int BK = 32, PITCH = 40, BUF = (256 + 128) * PITCH;
;   bf16_t* sbase = (bf16_t*)smem;
;   const int lane = tid & 63, wid = tid >> 6, wr = wid >> 1, wc = wid & 1, fr = lane & 15, fq = lane >> 4;
;   f32x4 acc[8][4];
; #pragma unroll
;   for (int m = 0; m < 8; ++m)
; #pragma unroll
;     for (int n = 0; n < 4; ++n) acc[m][n] = (f32x4){0.f, 0.f, 0.f, 0.f};
;   u32x4 ra[2][4], rb[2][2];
;   const int nk = K / BK;
;   const int sr = tid >> 2, scv = tid & 3;
; template <class Epi>
; DI void gemm_phase(char* smem, const bf16_t* A0, int lda0, int ksplit, const bf16_t* A1, int lda1, const bf16_t* Bt, int K, int nN, const Epi& epi, int tid) {
;   const int G = gridDim.x;
;   if ((G & 7) == 0) {
;     const int x = blockIdx.x & 7, l = blockIdx.x >> 3, L = G >> 3, per = 8 * nN, tot = 2 * per;
.LBB0_1844:
	s_cmp_gt_i32 s94, 15
	s_cselect_b64 s[0:1], -1, 0
	s_cmp_lt_i32 s95, 16
	s_cselect_b64 s[2:3], -1, 0
	s_or_b64 s[0:1], s[0:1], s[2:3]
	s_and_b64 vcc, exec, s[0:1]
	s_cbranch_vccnz .LBB0_1872
	s_add_u32 s0, s92, 0x11a00000
	s_load_dword s12, s[74:75], 0x180
	s_addc_u32 s1, s93, 0
	s_add_u32 s6, s92, 0x9800800
	s_addc_u32 s7, s93, 0
	s_add_u32 s2, s92, 0x3100000
	s_addc_u32 s3, s93, 0
	s_and_b32 s8, s72, 0xffffffc0
	v_mbcnt_hi_u32_b32 v195, -1, v194
	s_waitcnt lgkmcnt(0)
	s_and_b32 s10, s12, 7
	s_cmp_lg_u32 s10, 0
	s_waitcnt vmcnt(16)
	v_add_u32_e32 v196, s8, v195
	v_mbcnt_lo_u32_b32 v240, -1, 0
	v_mbcnt_hi_u32_b32 v240, -1, v240
	s_lshr_b32 s20, s72, 6
	s_lshl_b32 s13, s20, 10
	v_and_b32_e32 v241, 15, v240
	v_lshrrev_b32_e32 v242, 4, v240
	v_bfe_u32 v243, v240, 3, 1
	v_mul_u32_u24_e32 v243, 3, v243
	v_xor_b32_e32 v243, v242, v243
	v_lshlrev_b32_e32 v243, 4, v243
	v_lshl_add_u32 v243, v241, 6, v243
	s_lshr_b32 s19, s20, 1
	s_lshl_b32 s19, s19, 13
	v_add_u32_e32 v230, s19, v243
	s_and_b32 s19, s20, 1
	s_lshl_b32 s19, s19, 12
	s_add_u32 s19, s19, 16384
	v_add_u32_e32 v231, s19, v243
	s_lshr_b32 s19, s20, 1
	s_lshl_b32 s19, s19, 7
	v_add_u32_e32 v244, s19, v241
	s_and_b32 s19, s20, 1
	s_lshl_b32 s19, s19, 6
	v_lshl_add_u32 v245, v242, 2, s19
	s_movk_i32 s19, 0x1000
	v_mul_lo_u32 v246, v244, s19
	v_lshl_add_u32 v234, v245, 2, v246
	v_lshrrev_b32_e32 v241, 2, v240
	s_lshl_b32 s19, s20, 4
	v_add_u32_e32 v241, s19, v241
	v_bfe_u32 v242, v240, 5, 1
	v_mul_u32_u24_e32 v242, 3, v242
	v_and_b32_e32 v243, 3, v240
	v_xor_b32_e32 v243, v243, v242
	v_lshlrev_b32_e32 v243, 4, v243
	s_mov_b32 s19, 1024
	v_mad_u32_u24 v224, v241, s19, v243
	v_add_u32_e32 v225, 0x10000, v224
	v_add_u32_e32 v226, 0x20000, v224
	v_add_u32_e32 v227, 0x30000, v224
	s_mov_b32 s19, 4160
	v_mad_u32_u24 v236, v241, s19, v243
	v_add_u32_e32 v237, 0x41000, v236
	v_add_u32_e32 v238, 0x82000, v236
	v_add_u32_e32 v239, 0xc3000, v236
	v_mov_b32_e32 v248, v224
	v_mov_b32_e32 v249, v225
	v_mov_b32_e32 v250, v226
	v_mov_b32_e32 v251, v227
	s_mov_b32 s19, 3072
	v_mad_u32_u24 v228, v241, s19, v243
	v_add_u32_e32 v229, 0x30000, v228
	s_load_dwordx2 s[6:7], s[74:75], 0x168
	s_lshr_b32 s9, s96, 3
	s_and_b32 s11, s96, 7
	s_lshl_b32 s11, s11, 1
	s_waitcnt lgkmcnt(0)
; #define LWRITE(S, buf) do { bf16_t* sA_ = sbase + (buf) * BUF; bf16_t* sB_ = sA_ + 256 * PITCH; \
;     _Pragma("unroll") for (int i_ = 0; i_ < 4; ++i_) *(u32x4*)(sA_ + (sr + i_ * 64) * PITCH + scv * 8) = ra[S][i_]; \
;     _Pragma("unroll") for (int i_ = 0; i_ < 2; ++i_) *(u32x4*)(sB_ + (sr + i_ * 64) * PITCH + scv * 8) = rb[S][i_]; } while (0)
; template <class Epi>
; DI void gemm_tile(char* smem, const bf16_t* __restrict__ A0, int lda0, int ksplit, const bf16_t* __restrict__ A1, int lda1,
;                   const bf16_t* __restrict__ Bt, int K, int row0, int col0, const Epi& epi, int tid) {
;     ...
;   f32x4 acc[8][4];
; #pragma unroll
;   for (int m = 0; m < 8; ++m)
; #pragma unroll
;     for (int n = 0; n < 4; ++n) acc[m][n] = (f32x4){0.f, 0.f, 0.f, 0.f};
;   u32x4 ra[2][4], rb[2][2];
;   const int nk = K / BK;
;   const int sr = tid >> 2, scv = tid & 3;
;     ...
;   __syncthreads();
;   {
;     const int last = nk - 1;
;     GLOAD(0, 0);
;     __builtin_amdgcn_sched_barrier(0);
;     GLOAD(1, 1);
;     __builtin_amdgcn_sched_barrier(0);
;     LWRITE(0, 0);
;     __builtin_amdgcn_sched_barrier(0);
;     GLOAD(0, (2 < last ? 2 : last));
;     __builtin_amdgcn_sched_barrier(0);
;     __syncthreads();
; template <class Epi>
; DI void gemm_phase(char* smem, const bf16_t* A0, int lda0, int ksplit, const bf16_t* A1, int lda1, const bf16_t* Bt, int K, int nN, const Epi& epi, int tid) {
;     ...
;     const int x = blockIdx.x & 7, l = blockIdx.x >> 3, L = G >> 3, per = 8 * nN, tot = 2 * per;
;     for (int q = l; q < tot; q += L) { const int rgl = q / per, rem = q % per, ct = rem >> 3, rt = (x * 2 + rgl) * 8 + (rem & 7);
;       gemm_tile(smem, A0, lda0, ksplit, A1, lda1, Bt, K, rt * 256, ct * 128, epi, tid); }
.Lg15_tile:
	s_cmpk_ge_u32 s9, 128
	s_cbranch_scc1 .Lg15_done
	s_cmpk_ge_u32 s9, 64
	s_cselect_b32 s20, 1, 0
	s_cselect_b32 s19, 64, 0
	s_sub_u32 s19, s9, s19
	s_and_b32 s98, s19, 7
	s_lshl_b32 s98, s98, 3
	s_bfe_u32 s21, s19, 0x30003
	s_or_b32 s98, s98, s21
	s_andn2_b32 s19, s19, 63
	s_or_b32 s19, s19, s98
	s_add_u32 s20, s20, s11
	s_lshl_b32 s20, s20, 3
	s_and_b32 s98, s19, 7
	s_add_u32 s98, s98, s20
	s_lshl_b32 s98, s98, 8
	s_lshr_b32 s21, s19, 3
	s_lshl_b32 s21, s21, 7
	s_mul_i32 s20, s98, 1024
	s_add_u32 s20, s20, 0x11a00000
	s_add_u32 s0, s92, s20
	s_addc_u32 s1, s93, 0
	s_mul_i32 s20, s21, 3072
	s_add_u32 s20, s20, 0x3100000
	s_add_u32 s2, s92, s20
	s_addc_u32 s3, s93, 0
	v_mov_b32_e32 v224, v248
	v_mov_b32_e32 v225, v249
	v_mov_b32_e32 v226, v250
	v_mov_b32_e32 v227, v251
	s_mov_b32 s22, 0
	s_mov_b32 s99, 0
	s_add_u32 s19, s99, s13
	s_add_u32 m0, s19, 0
	s_nop 0
	global_load_lds_dwordx4 v224, s[0:1]
	s_add_u32 m0, s19, 4096
	s_nop 0
	global_load_lds_dwordx4 v225, s[0:1]
	s_add_u32 m0, s19, 8192
	s_nop 0
	global_load_lds_dwordx4 v226, s[0:1]
	s_add_u32 m0, s19, 12288
	s_nop 0
	global_load_lds_dwordx4 v227, s[0:1]
	s_add_u32 m0, s19, 16384
	s_nop 0
	global_load_lds_dwordx4 v228, s[2:3]
	s_add_u32 m0, s19, 20480
	s_nop 0
	global_load_lds_dwordx4 v229, s[2:3]
	s_add_u32 s0, s0, 64
	s_addc_u32 s1, s1, 0
	s_add_u32 s2, s2, 64
	s_addc_u32 s3, s3, 0
	s_add_u32 s22, s22, 1
	s_add_u32 s99, s99, 24576
	s_cmp_eq_u32 s99, 73728
	s_cselect_b32 s99, 0, s99
	s_add_u32 s19, s99, s13
	s_add_u32 m0, s19, 0
	s_nop 0
	global_load_lds_dwordx4 v224, s[0:1]
	s_add_u32 m0, s19, 4096
	s_nop 0
	global_load_lds_dwordx4 v225, s[0:1]
	s_add_u32 m0, s19, 8192
	s_nop 0
	global_load_lds_dwordx4 v226, s[0:1]
	s_add_u32 m0, s19, 12288
	s_nop 0
	global_load_lds_dwordx4 v227, s[0:1]
	s_add_u32 m0, s19, 16384
	s_nop 0
	global_load_lds_dwordx4 v228, s[2:3]
	s_add_u32 m0, s19, 20480
	s_nop 0
	global_load_lds_dwordx4 v229, s[2:3]
	s_add_u32 s0, s0, 64
	s_addc_u32 s1, s1, 0
	s_add_u32 s2, s2, 64
	s_addc_u32 s3, s3, 0
	s_add_u32 s22, s22, 1
	s_add_u32 s99, s99, 24576
	s_cmp_eq_u32 s99, 73728
	s_cselect_b32 s99, 0, s99
	s_add_u32 s19, s99, s13
	s_add_u32 m0, s19, 0
	s_nop 0
	global_load_lds_dwordx4 v224, s[0:1]
	s_add_u32 m0, s19, 4096
	s_nop 0
	global_load_lds_dwordx4 v225, s[0:1]
	s_add_u32 m0, s19, 8192
	s_nop 0
	global_load_lds_dwordx4 v226, s[0:1]
	s_add_u32 m0, s19, 12288
	s_nop 0
	global_load_lds_dwordx4 v227, s[0:1]
	s_add_u32 m0, s19, 16384
	s_nop 0
	global_load_lds_dwordx4 v228, s[2:3]
	s_add_u32 m0, s19, 20480
	s_nop 0
	global_load_lds_dwordx4 v229, s[2:3]
	s_add_u32 s0, s0, 64
	s_addc_u32 s1, s1, 0
	s_add_u32 s2, s2, 64
	s_addc_u32 s3, s3, 0
	s_add_u32 s22, s22, 1
	s_add_u32 s99, s99, 24576
	s_cmp_eq_u32 s99, 73728
	s_cselect_b32 s99, 0, s99
	v_mov_b32_e32 v0, 0
	v_mov_b32_e32 v1, 0
	v_mov_b32_e32 v2, 0
	v_mov_b32_e32 v3, 0
	v_mov_b32_e32 v4, 0
	v_mov_b32_e32 v5, 0
	v_mov_b32_e32 v6, 0
	v_mov_b32_e32 v7, 0
	v_mov_b32_e32 v8, 0
	v_mov_b32_e32 v9, 0
	v_mov_b32_e32 v10, 0
	v_mov_b32_e32 v11, 0
	v_mov_b32_e32 v12, 0
	v_mov_b32_e32 v13, 0
	v_mov_b32_e32 v14, 0
	v_mov_b32_e32 v15, 0
	v_mov_b32_e32 v16, 0
	v_mov_b32_e32 v17, 0
	v_mov_b32_e32 v18, 0
	v_mov_b32_e32 v19, 0
	v_mov_b32_e32 v20, 0
	v_mov_b32_e32 v21, 0
	v_mov_b32_e32 v22, 0
	v_mov_b32_e32 v23, 0
	v_mov_b32_e32 v24, 0
	v_mov_b32_e32 v25, 0
	v_mov_b32_e32 v26, 0
	v_mov_b32_e32 v27, 0
	v_mov_b32_e32 v28, 0
	v_mov_b32_e32 v29, 0
	v_mov_b32_e32 v30, 0
	v_mov_b32_e32 v31, 0
	v_mov_b32_e32 v32, 0
	v_mov_b32_e32 v33, 0
	v_mov_b32_e32 v34, 0
	v_mov_b32_e32 v35, 0
	v_mov_b32_e32 v36, 0
	v_mov_b32_e32 v37, 0
	v_mov_b32_e32 v38, 0
	v_mov_b32_e32 v39, 0
	v_mov_b32_e32 v40, 0
	v_mov_b32_e32 v41, 0
	v_mov_b32_e32 v42, 0
	v_mov_b32_e32 v43, 0
	v_mov_b32_e32 v44, 0
	v_mov_b32_e32 v45, 0
	v_mov_b32_e32 v46, 0
	v_mov_b32_e32 v47, 0
	v_mov_b32_e32 v48, 0
	v_mov_b32_e32 v49, 0
	v_mov_b32_e32 v50, 0
	v_mov_b32_e32 v51, 0
	v_mov_b32_e32 v52, 0
	v_mov_b32_e32 v53, 0
	v_mov_b32_e32 v54, 0
	v_mov_b32_e32 v55, 0
	v_mov_b32_e32 v56, 0
	v_mov_b32_e32 v57, 0
	v_mov_b32_e32 v58, 0
	v_mov_b32_e32 v59, 0
	v_mov_b32_e32 v60, 0
	v_mov_b32_e32 v61, 0
	v_mov_b32_e32 v62, 0
	v_mov_b32_e32 v63, 0
	v_mov_b32_e32 v64, 0
	v_mov_b32_e32 v65, 0
	v_mov_b32_e32 v66, 0
	v_mov_b32_e32 v67, 0
	v_mov_b32_e32 v68, 0
	v_mov_b32_e32 v69, 0
	v_mov_b32_e32 v70, 0
	v_mov_b32_e32 v71, 0
	v_mov_b32_e32 v72, 0
	v_mov_b32_e32 v73, 0
	v_mov_b32_e32 v74, 0
	v_mov_b32_e32 v75, 0
	v_mov_b32_e32 v76, 0
	v_mov_b32_e32 v77, 0
	v_mov_b32_e32 v78, 0
	v_mov_b32_e32 v79, 0
	v_mov_b32_e32 v80, 0
	v_mov_b32_e32 v81, 0
	v_mov_b32_e32 v82, 0
	v_mov_b32_e32 v83, 0
	v_mov_b32_e32 v84, 0
	v_mov_b32_e32 v85, 0
	v_mov_b32_e32 v86, 0
	v_mov_b32_e32 v87, 0
	v_mov_b32_e32 v88, 0
	v_mov_b32_e32 v89, 0
	v_mov_b32_e32 v90, 0
	v_mov_b32_e32 v91, 0
	v_mov_b32_e32 v92, 0
	v_mov_b32_e32 v93, 0
	v_mov_b32_e32 v94, 0
	v_mov_b32_e32 v95, 0
	v_mov_b32_e32 v96, 0
	v_mov_b32_e32 v97, 0
	v_mov_b32_e32 v98, 0
	v_mov_b32_e32 v99, 0
	v_mov_b32_e32 v100, 0
	v_mov_b32_e32 v101, 0
	v_mov_b32_e32 v102, 0
	v_mov_b32_e32 v103, 0
	v_mov_b32_e32 v104, 0
	v_mov_b32_e32 v105, 0
	v_mov_b32_e32 v106, 0
	v_mov_b32_e32 v107, 0
	v_mov_b32_e32 v108, 0
	v_mov_b32_e32 v109, 0
	v_mov_b32_e32 v110, 0
	v_mov_b32_e32 v111, 0
	v_mov_b32_e32 v112, 0
	v_mov_b32_e32 v113, 0
	v_mov_b32_e32 v114, 0
	v_mov_b32_e32 v115, 0
	v_mov_b32_e32 v116, 0
	v_mov_b32_e32 v117, 0
	v_mov_b32_e32 v118, 0
	v_mov_b32_e32 v119, 0
	v_mov_b32_e32 v120, 0
	v_mov_b32_e32 v121, 0
	v_mov_b32_e32 v122, 0
	v_mov_b32_e32 v123, 0
	v_mov_b32_e32 v124, 0
	v_mov_b32_e32 v125, 0
	v_mov_b32_e32 v126, 0
	v_mov_b32_e32 v127, 0
	s_mov_b32 s101, 0
	s_mov_b32 s100, 24576
	s_waitcnt vmcnt(12)
	s_barrier
	ds_read_b128 v[128:131], v231 offset:0
	ds_read_b128 v[132:135], v231 offset:1024
	ds_read_b128 v[136:139], v231 offset:2048
	ds_read_b128 v[140:143], v231 offset:3072
	ds_read_b128 v[144:147], v230 offset:0
	ds_read_b128 v[148:151], v230 offset:1024
	ds_read_b128 v[152:155], v230 offset:2048
	ds_read_b128 v[156:159], v230 offset:3072
	ds_read_b128 v[160:163], v230 offset:4096
	ds_read_b128 v[164:167], v230 offset:5120
	ds_read_b128 v[168:171], v230 offset:6144
	ds_read_b128 v[172:175], v230 offset:7168

.Lg15_sw0:
	s_mul_i32 s20, s98, 4160
	s_add_u32 s20, s20, 0x9800800
	s_add_u32 s0, s92, s20
	s_addc_u32 s1, s93, 0
	v_mov_b32_e32 v224, v236
	v_mov_b32_e32 v225, v237
	v_mov_b32_e32 v226, v238
	v_mov_b32_e32 v227, v239
	s_branch .Lg15_swb0

; template <class Epi>
; DI void gemm_tile(char* smem, const bf16_t* __restrict__ A0, int lda0, int ksplit, const bf16_t* __restrict__ A1, int lda1,
;                   const bf16_t* __restrict__ Bt, int K, int row0, int col0, const Epi& epi, int tid) {
;     ...
; #pragma unroll
;   for (int m = 0; m < 8; ++m)
; #pragma unroll
;     for (int n = 0; n < 4; ++n) epi(row0 + wr * 128 + m * 16 + fr, col0 + wc * 64 + n * 16 + fq * 4, acc[m][n]);
.Lg15_epi:
	s_nop 7
	s_nop 7
	s_lshl_b32 s20, s98, 12
	s_lshl_b32 s19, s21, 2
	s_add_u32 s20, s20, s19
	s_add_u32 s4, s6, s20
	s_addc_u32 s5, s7, 0
	global_load_dwordx4 v[128:131], v234, s[4:5] offset:0
	global_load_dwordx4 v[132:135], v234, s[4:5] offset:64
	global_load_dwordx4 v[136:139], v234, s[4:5] offset:128
	global_load_dwordx4 v[140:143], v234, s[4:5] offset:192
	s_add_u32 s4, s4, 0x10000
	s_addc_u32 s5, s5, 0
	global_load_dwordx4 v[144:147], v234, s[4:5] offset:0
	global_load_dwordx4 v[148:151], v234, s[4:5] offset:64
	global_load_dwordx4 v[152:155], v234, s[4:5] offset:128
	global_load_dwordx4 v[156:159], v234, s[4:5] offset:192
	s_add_u32 s4, s4, 0x10000
	s_addc_u32 s5, s5, 0
	global_load_dwordx4 v[160:163], v234, s[4:5] offset:0
	global_load_dwordx4 v[164:167], v234, s[4:5] offset:64
	global_load_dwordx4 v[168:171], v234, s[4:5] offset:128
	global_load_dwordx4 v[172:175], v234, s[4:5] offset:192
	s_add_u32 s4, s4, 0x10000
	s_addc_u32 s5, s5, 0
	global_load_dwordx4 v[176:179], v234, s[4:5] offset:0
	global_load_dwordx4 v[180:183], v234, s[4:5] offset:64
	global_load_dwordx4 v[184:187], v234, s[4:5] offset:128
	global_load_dwordx4 v[188:191], v234, s[4:5] offset:192
	s_add_u32 s4, s4, 0x10000
	s_addc_u32 s5, s5, 0
	s_sub_u32 s4, s4, 0x40000
	s_subb_u32 s5, s5, 0
	s_waitcnt vmcnt(15)
	v_pk_add_f32 v[128:129], v[128:129], v[0:1]
	v_pk_add_f32 v[130:131], v[130:131], v[2:3]
	global_store_dwordx4 v234, v[128:131], s[4:5] offset:0
	s_waitcnt vmcnt(15)
	v_pk_add_f32 v[132:133], v[132:133], v[4:5]
	v_pk_add_f32 v[134:135], v[134:135], v[6:7]
	global_store_dwordx4 v234, v[132:135], s[4:5] offset:64
	s_waitcnt vmcnt(15)
	v_pk_add_f32 v[136:137], v[136:137], v[8:9]
	v_pk_add_f32 v[138:139], v[138:139], v[10:11]
	global_store_dwordx4 v234, v[136:139], s[4:5] offset:128
	s_waitcnt vmcnt(15)
	v_pk_add_f32 v[140:141], v[140:141], v[12:13]
	v_pk_add_f32 v[142:143], v[142:143], v[14:15]
	global_store_dwordx4 v234, v[140:143], s[4:5] offset:192
	s_add_u32 s4, s4, 0x10000
	s_addc_u32 s5, s5, 0
	s_waitcnt vmcnt(15)
	v_pk_add_f32 v[144:145], v[144:145], v[16:17]
	v_pk_add_f32 v[146:147], v[146:147], v[18:19]
	global_store_dwordx4 v234, v[144:147], s[4:5] offset:0
	s_waitcnt vmcnt(15)
	v_pk_add_f32 v[148:149], v[148:149], v[20:21]
	v_pk_add_f32 v[150:151], v[150:151], v[22:23]
	global_store_dwordx4 v234, v[148:151], s[4:5] offset:64
	s_waitcnt vmcnt(15)
	v_pk_add_f32 v[152:153], v[152:153], v[24:25]
	v_pk_add_f32 v[154:155], v[154:155], v[26:27]
	global_store_dwordx4 v234, v[152:155], s[4:5] offset:128
	s_waitcnt vmcnt(15)
	v_pk_add_f32 v[156:157], v[156:157], v[28:29]
	v_pk_add_f32 v[158:159], v[158:159], v[30:31]
	global_store_dwordx4 v234, v[156:159], s[4:5] offset:192
	s_add_u32 s4, s4, 0x10000
	s_addc_u32 s5, s5, 0
	s_waitcnt vmcnt(15)
	v_pk_add_f32 v[160:161], v[160:161], v[32:33]
	v_pk_add_f32 v[162:163], v[162:163], v[34:35]
	global_store_dwordx4 v234, v[160:163], s[4:5] offset:0
	s_waitcnt vmcnt(15)
	v_pk_add_f32 v[164:165], v[164:165], v[36:37]
	v_pk_add_f32 v[166:167], v[166:167], v[38:39]
	global_store_dwordx4 v234, v[164:167], s[4:5] offset:64
	s_waitcnt vmcnt(15)
	v_pk_add_f32 v[168:169], v[168:169], v[40:41]
	v_pk_add_f32 v[170:171], v[170:171], v[42:43]
	global_store_dwordx4 v234, v[168:171], s[4:5] offset:128
	s_waitcnt vmcnt(15)
	v_pk_add_f32 v[172:173], v[172:173], v[44:45]
	v_pk_add_f32 v[174:175], v[174:175], v[46:47]
	global_store_dwordx4 v234, v[172:175], s[4:5] offset:192
	s_add_u32 s4, s4, 0x10000
	s_addc_u32 s5, s5, 0
	s_waitcnt vmcnt(15)
	v_pk_add_f32 v[176:177], v[176:177], v[48:49]
	v_pk_add_f32 v[178:179], v[178:179], v[50:51]
	global_store_dwordx4 v234, v[176:179], s[4:5] offset:0
	s_waitcnt vmcnt(15)
	v_pk_add_f32 v[180:181], v[180:181], v[52:53]
	v_pk_add_f32 v[182:183], v[182:183], v[54:55]
	global_store_dwordx4 v234, v[180:183], s[4:5] offset:64
	s_waitcnt vmcnt(15)
	v_pk_add_f32 v[184:185], v[184:185], v[56:57]
	v_pk_add_f32 v[186:187], v[186:187], v[58:59]
	global_store_dwordx4 v234, v[184:187], s[4:5] offset:128
	s_waitcnt vmcnt(15)
; template <class Epi>
; DI void gemm_tile(char* smem, const bf16_t* __restrict__ A0, int lda0, int ksplit, const bf16_t* __restrict__ A1, int lda1,
;                   const bf16_t* __restrict__ Bt, int K, int row0, int col0, const Epi& epi, int tid) {
;     ...
; #pragma unroll
;   for (int m = 0; m < 8; ++m)
; #pragma unroll
;     for (int n = 0; n < 4; ++n) epi(row0 + wr * 128 + m * 16 + fr, col0 + wc * 64 + n * 16 + fq * 4, acc[m][n]);
	v_pk_add_f32 v[188:189], v[188:189], v[60:61]
	v_pk_add_f32 v[190:191], v[190:191], v[62:63]
	global_store_dwordx4 v234, v[188:191], s[4:5] offset:192
	s_add_u32 s4, s4, 0x10000
	s_addc_u32 s5, s5, 0
	s_nop 1
	global_load_dwordx4 v[128:131], v234, s[4:5] offset:0
	global_load_dwordx4 v[132:135], v234, s[4:5] offset:64
	global_load_dwordx4 v[136:139], v234, s[4:5] offset:128
	global_load_dwordx4 v[140:143], v234, s[4:5] offset:192
	s_add_u32 s4, s4, 0x10000
	s_addc_u32 s5, s5, 0
	global_load_dwordx4 v[144:147], v234, s[4:5] offset:0
	global_load_dwordx4 v[148:151], v234, s[4:5] offset:64
	global_load_dwordx4 v[152:155], v234, s[4:5] offset:128
	global_load_dwordx4 v[156:159], v234, s[4:5] offset:192
	s_add_u32 s4, s4, 0x10000
	s_addc_u32 s5, s5, 0
	global_load_dwordx4 v[160:163], v234, s[4:5] offset:0
	global_load_dwordx4 v[164:167], v234, s[4:5] offset:64
	global_load_dwordx4 v[168:171], v234, s[4:5] offset:128
	global_load_dwordx4 v[172:175], v234, s[4:5] offset:192
	s_add_u32 s4, s4, 0x10000
	s_addc_u32 s5, s5, 0
	global_load_dwordx4 v[176:179], v234, s[4:5] offset:0
	global_load_dwordx4 v[180:183], v234, s[4:5] offset:64
	global_load_dwordx4 v[184:187], v234, s[4:5] offset:128
	global_load_dwordx4 v[188:191], v234, s[4:5] offset:192
	s_sub_u32 s4, s4, 0x30000
	s_subb_u32 s5, s5, 0
	s_waitcnt vmcnt(15)
	v_pk_add_f32 v[128:129], v[128:129], v[64:65]
	v_pk_add_f32 v[130:131], v[130:131], v[66:67]
	global_store_dwordx4 v234, v[128:131], s[4:5] offset:0
	s_waitcnt vmcnt(15)
	v_pk_add_f32 v[132:133], v[132:133], v[68:69]
	v_pk_add_f32 v[134:135], v[134:135], v[70:71]
	global_store_dwordx4 v234, v[132:135], s[4:5] offset:64
	s_waitcnt vmcnt(15)
	v_pk_add_f32 v[136:137], v[136:137], v[72:73]
	v_pk_add_f32 v[138:139], v[138:139], v[74:75]
	global_store_dwordx4 v234, v[136:139], s[4:5] offset:128
	s_waitcnt vmcnt(15)
	v_pk_add_f32 v[140:141], v[140:141], v[76:77]
	v_pk_add_f32 v[142:143], v[142:143], v[78:79]
	global_store_dwordx4 v234, v[140:143], s[4:5] offset:192
	s_add_u32 s4, s4, 0x10000
	s_addc_u32 s5, s5, 0
	s_waitcnt vmcnt(15)
	v_pk_add_f32 v[144:145], v[144:145], v[80:81]
	v_pk_add_f32 v[146:147], v[146:147], v[82:83]
	global_store_dwordx4 v234, v[144:147], s[4:5] offset:0
	s_waitcnt vmcnt(15)
	v_pk_add_f32 v[148:149], v[148:149], v[84:85]
	v_pk_add_f32 v[150:151], v[150:151], v[86:87]
	global_store_dwordx4 v234, v[148:151], s[4:5] offset:64
	s_waitcnt vmcnt(15)
	v_pk_add_f32 v[152:153], v[152:153], v[88:89]
	v_pk_add_f32 v[154:155], v[154:155], v[90:91]
	global_store_dwordx4 v234, v[152:155], s[4:5] offset:128
	s_waitcnt vmcnt(15)
	v_pk_add_f32 v[156:157], v[156:157], v[92:93]
	v_pk_add_f32 v[158:159], v[158:159], v[94:95]
	global_store_dwordx4 v234, v[156:159], s[4:5] offset:192
	s_add_u32 s4, s4, 0x10000
	s_addc_u32 s5, s5, 0
	s_waitcnt vmcnt(15)
	v_pk_add_f32 v[160:161], v[160:161], v[96:97]
	v_pk_add_f32 v[162:163], v[162:163], v[98:99]
	global_store_dwordx4 v234, v[160:163], s[4:5] offset:0
	s_waitcnt vmcnt(15)
	v_pk_add_f32 v[164:165], v[164:165], v[100:101]
	v_pk_add_f32 v[166:167], v[166:167], v[102:103]
	global_store_dwordx4 v234, v[164:167], s[4:5] offset:64
	s_waitcnt vmcnt(15)
	v_pk_add_f32 v[168:169], v[168:169], v[104:105]
	v_pk_add_f32 v[170:171], v[170:171], v[106:107]
	global_store_dwordx4 v234, v[168:171], s[4:5] offset:128
	s_waitcnt vmcnt(15)
	v_pk_add_f32 v[172:173], v[172:173], v[108:109]
	v_pk_add_f32 v[174:175], v[174:175], v[110:111]
	global_store_dwordx4 v234, v[172:175], s[4:5] offset:192
	s_add_u32 s4, s4, 0x10000
	s_addc_u32 s5, s5, 0
	s_waitcnt vmcnt(15)
	v_pk_add_f32 v[176:177], v[176:177], v[112:113]
	v_pk_add_f32 v[178:179], v[178:179], v[114:115]
	global_store_dwordx4 v234, v[176:179], s[4:5] offset:0
	s_waitcnt vmcnt(15)
	v_pk_add_f32 v[180:181], v[180:181], v[116:117]
	v_pk_add_f32 v[182:183], v[182:183], v[118:119]
	global_store_dwordx4 v234, v[180:183], s[4:5] offset:64
	s_waitcnt vmcnt(15)
	v_pk_add_f32 v[184:185], v[184:185], v[120:121]
	v_pk_add_f32 v[186:187], v[186:187], v[122:123]
	global_store_dwordx4 v234, v[184:187], s[4:5] offset:128
	s_waitcnt vmcnt(15)
	v_pk_add_f32 v[188:189], v[188:189], v[124:125]
	v_pk_add_f32 v[190:191], v[190:191], v[126:127]
	global_store_dwordx4 v234, v[188:191], s[4:5] offset:192
	s_add_u32 s4, s4, 0x10000
	s_addc_u32 s5, s5, 0
	s_nop 1
	s_add_u32 s9, s9, 64
	s_branch .Lg15_tile

; template <class Epi>
; DI void gemm_tile(char* smem, const bf16_t* __restrict__ A0, int lda0, int ksplit, const bf16_t* __restrict__ A1, int lda1,
;                   const bf16_t* __restrict__ Bt, int K, int row0, int col0, const Epi& epi, int tid) {
;   constexpr int BK = 32, PITCH = 40, BUF = (256 + 128) * PITCH;
;   bf16_t* sbase = (bf16_t*)smem;
;   const int lane = tid & 63, wid = tid >> 6, wr = wid >> 1, wc = wid & 1, fr = lane & 15, fq = lane >> 4;
;   f32x4 acc[8][4];
; #pragma unroll
;   for (int m = 0; m < 8; ++m)
; #pragma unroll
;     for (int n = 0; n < 4; ++n) acc[m][n] = (f32x4){0.f, 0.f, 0.f, 0.f};
;   u32x4 ra[2][4], rb[2][2];
;   const int nk = K / BK;
;   const int sr = tid >> 2, scv = tid & 3;
; template <class Epi>
; DI void gemm_phase(char* smem, const bf16_t* A0, int lda0, int ksplit, const bf16_t* A1, int lda1, const bf16_t* Bt, int K, int nN, const Epi& epi, int tid) {
;   const int G = gridDim.x;
;   if ((G & 7) == 0) {
;     const int x = blockIdx.x & 7, l = blockIdx.x >> 3, L = G >> 3, per = 8 * nN, tot = 2 * per;
.LBB0_1890:
	s_cmp_gt_i32 s94, 17
	s_cselect_b64 s[0:1], -1, 0
	s_cmp_lt_i32 s95, 18
	s_cselect_b64 s[2:3], -1, 0
	s_or_b64 s[0:1], s[0:1], s[2:3]
	s_and_b64 vcc, exec, s[0:1]
	s_cbranch_vccnz .LBB0_1918
	s_add_u32 s2, s92, 0x3800000
	s_waitcnt lgkmcnt(0)
	s_load_dword s14, s[74:75], 0x180
	s_addc_u32 s3, s93, 0
	s_add_u32 s4, s92, 0x13c0000
	s_addc_u32 s5, s93, 0
	s_add_u32 s0, s92, 0x7800000
	s_addc_u32 s1, s93, 0
	s_and_b32 s16, s72, 0xffffffc0
	v_mbcnt_hi_u32_b32 v195, -1, v194
	s_waitcnt lgkmcnt(0)
	s_and_b32 s15, s14, 7
	s_cmp_lg_u32 s15, 0
	s_waitcnt vmcnt(16)
	v_add_u32_e32 v196, s16, v195
	v_mbcnt_lo_u32_b32 v240, -1, 0
	v_mbcnt_hi_u32_b32 v240, -1, v240
	s_lshr_b32 s12, s72, 6
	s_lshl_b32 s101, s12, 10
	v_and_b32_e32 v241, 15, v240
	v_lshrrev_b32_e32 v242, 4, v240
	v_bfe_u32 v243, v240, 3, 1
	v_mul_u32_u24_e32 v243, 3, v243
	v_xor_b32_e32 v243, v242, v243
	v_lshlrev_b32_e32 v243, 4, v243
	v_lshl_add_u32 v243, v241, 6, v243
	s_lshr_b32 s11, s12, 1
	s_lshl_b32 s11, s11, 13
	v_add_u32_e32 v230, s11, v243
	s_and_b32 s11, s12, 1
	s_lshl_b32 s11, s11, 12
	s_add_u32 s11, s11, 16384
	v_add_u32_e32 v231, s11, v243
	s_lshr_b32 s11, s12, 1
	s_lshl_b32 s11, s11, 7
	v_add_u32_e32 v244, s11, v241
	s_and_b32 s11, s12, 1
	s_lshl_b32 s11, s11, 6
	v_lshl_add_u32 v245, v242, 2, s11
	s_movk_i32 s11, 0x2000
	v_mul_lo_u32 v246, v244, s11
	v_lshl_add_u32 v234, v245, 1, v246
	v_lshrrev_b32_e32 v241, 2, v240
	s_lshl_b32 s11, s12, 4
	v_add_u32_e32 v241, s11, v241
	v_bfe_u32 v242, v240, 5, 1
	v_mul_u32_u24_e32 v242, 3, v242
	v_and_b32_e32 v243, 3, v240
	v_xor_b32_e32 v243, v243, v242
	v_lshlrev_b32_e32 v243, 4, v243
	s_mov_b32 s11, 2048
	v_mad_u32_u24 v224, v241, s11, v243
	v_add_u32_e32 v225, 0x20000, v224
	v_add_u32_e32 v226, 0x40000, v224
	v_add_u32_e32 v227, 0x60000, v224
	s_mov_b32 s11, 2048
	v_mad_u32_u24 v228, v241, s11, v243
	v_add_u32_e32 v229, 0x20000, v228
	s_lshr_b32 s17, s96, 3
	s_and_b32 s20, s96, 7
	s_lshl_b32 s20, s20, 1
	s_waitcnt lgkmcnt(0)
; #define LWRITE(S, buf) do { bf16_t* sA_ = sbase + (buf) * BUF; bf16_t* sB_ = sA_ + 256 * PITCH; \
;     _Pragma("unroll") for (int i_ = 0; i_ < 4; ++i_) *(u32x4*)(sA_ + (sr + i_ * 64) * PITCH + scv * 8) = ra[S][i_]; \
;     _Pragma("unroll") for (int i_ = 0; i_ < 2; ++i_) *(u32x4*)(sB_ + (sr + i_ * 64) * PITCH + scv * 8) = rb[S][i_]; } while (0)
; template <class Epi>
; DI void gemm_tile(char* smem, const bf16_t* __restrict__ A0, int lda0, int ksplit, const bf16_t* __restrict__ A1, int lda1,
;                   const bf16_t* __restrict__ Bt, int K, int row0, int col0, const Epi& epi, int tid) {
;     ...
;   f32x4 acc[8][4];
; #pragma unroll
;   for (int m = 0; m < 8; ++m)
; #pragma unroll
;     for (int n = 0; n < 4; ++n) acc[m][n] = (f32x4){0.f, 0.f, 0.f, 0.f};
;   u32x4 ra[2][4], rb[2][2];
;   const int nk = K / BK;
;   const int sr = tid >> 2, scv = tid & 3;
;     ...
;   __syncthreads();
;   {
;     const int last = nk - 1;
;     GLOAD(0, 0);
;     __builtin_amdgcn_sched_barrier(0);
;     GLOAD(1, 1);
;     __builtin_amdgcn_sched_barrier(0);
;     LWRITE(0, 0);
;     __builtin_amdgcn_sched_barrier(0);
;     GLOAD(0, (2 < last ? 2 : last));
;     __builtin_amdgcn_sched_barrier(0);
;     __syncthreads();
; template <class Epi>
; DI void gemm_phase(char* smem, const bf16_t* A0, int lda0, int ksplit, const bf16_t* A1, int lda1, const bf16_t* Bt, int K, int nN, const Epi& epi, int tid) {
;     ...
;     const int x = blockIdx.x & 7, l = blockIdx.x >> 3, L = G >> 3, per = 8 * nN, tot = 2 * per;
;     for (int q = l; q < tot; q += L) { const int rgl = q / per, rem = q % per, ct = rem >> 3, rt = (x * 2 + rgl) * 8 + (rem & 7);
;       gemm_tile(smem, A0, lda0, ksplit, A1, lda1, Bt, K, rt * 256, ct * 128, epi, tid); }
.Lg17_tile:
	s_cmpk_ge_u32 s17, 512
	s_cbranch_scc1 .Lg17_done
	s_cmpk_ge_u32 s17, 256
	s_cselect_b32 s12, 1, 0
	s_cselect_b32 s11, 256, 0
	s_sub_u32 s11, s17, s11
	s_and_b32 s18, s11, 7
	s_lshl_b32 s18, s18, 3
	s_bfe_u32 s13, s11, 0x30003
	s_or_b32 s18, s18, s13
	s_andn2_b32 s11, s11, 63
	s_or_b32 s11, s11, s18
	s_add_u32 s12, s12, s20
	s_lshl_b32 s12, s12, 3
	s_and_b32 s18, s11, 7
	s_add_u32 s18, s18, s12
	s_lshl_b32 s18, s18, 8
	s_lshr_b32 s13, s11, 3
	s_lshl_b32 s13, s13, 7
	s_mul_i32 s12, s18, 2048
	s_add_u32 s12, s12, 0x3800000
	s_add_u32 s0, s92, s12
	s_addc_u32 s1, s93, 0
	s_mul_i32 s12, s13, 2048
	s_add_u32 s12, s12, 0x13c0000
	s_add_u32 s2, s92, s12
	s_addc_u32 s3, s93, 0
	s_mov_b32 s100, 0
	s_mov_b32 s19, 0
	s_add_u32 s11, s19, s101
	s_add_u32 m0, s11, 0
	s_nop 0
	global_load_lds_dwordx4 v224, s[0:1]
	s_add_u32 m0, s11, 4096
	s_nop 0
	global_load_lds_dwordx4 v225, s[0:1]
	s_add_u32 m0, s11, 8192
	s_nop 0
	global_load_lds_dwordx4 v226, s[0:1]
	s_add_u32 m0, s11, 12288
	s_nop 0
	global_load_lds_dwordx4 v227, s[0:1]
	s_add_u32 m0, s11, 16384
	s_nop 0
	global_load_lds_dwordx4 v228, s[2:3]
	s_add_u32 m0, s11, 20480
	s_nop 0
	global_load_lds_dwordx4 v229, s[2:3]
	s_add_u32 s0, s0, 64
	s_addc_u32 s1, s1, 0
	s_add_u32 s2, s2, 64
	s_addc_u32 s3, s3, 0
	s_add_u32 s100, s100, 1
	s_add_u32 s19, s19, 24576
	s_cmp_eq_u32 s19, 73728
	s_cselect_b32 s19, 0, s19
	s_add_u32 s11, s19, s101
	s_add_u32 m0, s11, 0
	s_nop 0
	global_load_lds_dwordx4 v224, s[0:1]
	s_add_u32 m0, s11, 4096
	s_nop 0
	global_load_lds_dwordx4 v225, s[0:1]
	s_add_u32 m0, s11, 8192
	s_nop 0
	global_load_lds_dwordx4 v226, s[0:1]
	s_add_u32 m0, s11, 12288
	s_nop 0
	global_load_lds_dwordx4 v227, s[0:1]
	s_add_u32 m0, s11, 16384
	s_nop 0
	global_load_lds_dwordx4 v228, s[2:3]
	s_add_u32 m0, s11, 20480
	s_nop 0
	global_load_lds_dwordx4 v229, s[2:3]
	s_add_u32 s0, s0, 64
	s_addc_u32 s1, s1, 0
	s_add_u32 s2, s2, 64
	s_addc_u32 s3, s3, 0
	s_add_u32 s100, s100, 1
	s_add_u32 s19, s19, 24576
	s_cmp_eq_u32 s19, 73728
	s_cselect_b32 s19, 0, s19
	s_add_u32 s11, s19, s101
	s_add_u32 m0, s11, 0
	s_nop 0
	global_load_lds_dwordx4 v224, s[0:1]
	s_add_u32 m0, s11, 4096
	s_nop 0
	global_load_lds_dwordx4 v225, s[0:1]
	s_add_u32 m0, s11, 8192
	s_nop 0
	global_load_lds_dwordx4 v226, s[0:1]
	s_add_u32 m0, s11, 12288
	s_nop 0
	global_load_lds_dwordx4 v227, s[0:1]
	s_add_u32 m0, s11, 16384
	s_nop 0
	global_load_lds_dwordx4 v228, s[2:3]
	s_add_u32 m0, s11, 20480
	s_nop 0
	global_load_lds_dwordx4 v229, s[2:3]
	s_add_u32 s0, s0, 64
	s_addc_u32 s1, s1, 0
	s_add_u32 s2, s2, 64
	s_addc_u32 s3, s3, 0
	s_add_u32 s100, s100, 1
	s_add_u32 s19, s19, 24576
	s_cmp_eq_u32 s19, 73728
	s_cselect_b32 s19, 0, s19
	v_mov_b32_e32 v0, 0
	v_mov_b32_e32 v1, 0
	v_mov_b32_e32 v2, 0
	v_mov_b32_e32 v3, 0
	v_mov_b32_e32 v4, 0
	v_mov_b32_e32 v5, 0
	v_mov_b32_e32 v6, 0
	v_mov_b32_e32 v7, 0
	v_mov_b32_e32 v8, 0
	v_mov_b32_e32 v9, 0
	v_mov_b32_e32 v10, 0
	v_mov_b32_e32 v11, 0
	v_mov_b32_e32 v12, 0
	v_mov_b32_e32 v13, 0
	v_mov_b32_e32 v14, 0
	v_mov_b32_e32 v15, 0
	v_mov_b32_e32 v16, 0
	v_mov_b32_e32 v17, 0
	v_mov_b32_e32 v18, 0
	v_mov_b32_e32 v19, 0
	v_mov_b32_e32 v20, 0
	v_mov_b32_e32 v21, 0
	v_mov_b32_e32 v22, 0
	v_mov_b32_e32 v23, 0
	v_mov_b32_e32 v24, 0
	v_mov_b32_e32 v25, 0
	v_mov_b32_e32 v26, 0
	v_mov_b32_e32 v27, 0
	v_mov_b32_e32 v28, 0
	v_mov_b32_e32 v29, 0
	v_mov_b32_e32 v30, 0
	v_mov_b32_e32 v31, 0
	v_mov_b32_e32 v32, 0
	v_mov_b32_e32 v33, 0
	v_mov_b32_e32 v34, 0
	v_mov_b32_e32 v35, 0
	v_mov_b32_e32 v36, 0
	v_mov_b32_e32 v37, 0
	v_mov_b32_e32 v38, 0
	v_mov_b32_e32 v39, 0
	v_mov_b32_e32 v40, 0
	v_mov_b32_e32 v41, 0
	v_mov_b32_e32 v42, 0
	v_mov_b32_e32 v43, 0
	v_mov_b32_e32 v44, 0
	v_mov_b32_e32 v45, 0
	v_mov_b32_e32 v46, 0
	v_mov_b32_e32 v47, 0
	v_mov_b32_e32 v48, 0
	v_mov_b32_e32 v49, 0
	v_mov_b32_e32 v50, 0
	v_mov_b32_e32 v51, 0
	v_mov_b32_e32 v52, 0
	v_mov_b32_e32 v53, 0
	v_mov_b32_e32 v54, 0
	v_mov_b32_e32 v55, 0
	v_mov_b32_e32 v56, 0
	v_mov_b32_e32 v57, 0
	v_mov_b32_e32 v58, 0
	v_mov_b32_e32 v59, 0
	v_mov_b32_e32 v60, 0
	v_mov_b32_e32 v61, 0
	v_mov_b32_e32 v62, 0
	v_mov_b32_e32 v63, 0
	v_mov_b32_e32 v64, 0
	v_mov_b32_e32 v65, 0
	v_mov_b32_e32 v66, 0
	v_mov_b32_e32 v67, 0
	v_mov_b32_e32 v68, 0
	v_mov_b32_e32 v69, 0
	v_mov_b32_e32 v70, 0
	v_mov_b32_e32 v71, 0
	v_mov_b32_e32 v72, 0
	v_mov_b32_e32 v73, 0
	v_mov_b32_e32 v74, 0
	v_mov_b32_e32 v75, 0
	v_mov_b32_e32 v76, 0
	v_mov_b32_e32 v77, 0
	v_mov_b32_e32 v78, 0
	v_mov_b32_e32 v79, 0
	v_mov_b32_e32 v80, 0
	v_mov_b32_e32 v81, 0
	v_mov_b32_e32 v82, 0
	v_mov_b32_e32 v83, 0
	v_mov_b32_e32 v84, 0
	v_mov_b32_e32 v85, 0
	v_mov_b32_e32 v86, 0
	v_mov_b32_e32 v87, 0
	v_mov_b32_e32 v88, 0
	v_mov_b32_e32 v89, 0
	v_mov_b32_e32 v90, 0
	v_mov_b32_e32 v91, 0
	v_mov_b32_e32 v92, 0
	v_mov_b32_e32 v93, 0
	v_mov_b32_e32 v94, 0
	v_mov_b32_e32 v95, 0
	v_mov_b32_e32 v96, 0
	v_mov_b32_e32 v97, 0
	v_mov_b32_e32 v98, 0
	v_mov_b32_e32 v99, 0
	v_mov_b32_e32 v100, 0
	v_mov_b32_e32 v101, 0
	v_mov_b32_e32 v102, 0
	v_mov_b32_e32 v103, 0
	v_mov_b32_e32 v104, 0
	v_mov_b32_e32 v105, 0
	v_mov_b32_e32 v106, 0
	v_mov_b32_e32 v107, 0
	v_mov_b32_e32 v108, 0
	v_mov_b32_e32 v109, 0
	v_mov_b32_e32 v110, 0
	v_mov_b32_e32 v111, 0
	v_mov_b32_e32 v112, 0
	v_mov_b32_e32 v113, 0
	v_mov_b32_e32 v114, 0
	v_mov_b32_e32 v115, 0
	v_mov_b32_e32 v116, 0
	v_mov_b32_e32 v117, 0
	v_mov_b32_e32 v118, 0
	v_mov_b32_e32 v119, 0
	v_mov_b32_e32 v120, 0
	v_mov_b32_e32 v121, 0
	v_mov_b32_e32 v122, 0
	v_mov_b32_e32 v123, 0
	v_mov_b32_e32 v124, 0
	v_mov_b32_e32 v125, 0
	v_mov_b32_e32 v126, 0
	v_mov_b32_e32 v127, 0
	s_mov_b32 s99, 0
	s_mov_b32 s98, 24576
	s_waitcnt vmcnt(12)
	s_barrier
	ds_read_b128 v[128:131], v231 offset:0
	ds_read_b128 v[132:135], v231 offset:1024
	ds_read_b128 v[136:139], v231 offset:2048
	ds_read_b128 v[140:143], v231 offset:3072
	ds_read_b128 v[144:147], v230 offset:0
	ds_read_b128 v[148:151], v230 offset:1024
	ds_read_b128 v[152:155], v230 offset:2048
	ds_read_b128 v[156:159], v230 offset:3072
	ds_read_b128 v[160:163], v230 offset:4096
	ds_read_b128 v[164:167], v230 offset:5120
	ds_read_b128 v[168:171], v230 offset:6144
	ds_read_b128 v[172:175], v230 offset:7168

; template <class Epi>
; DI void gemm_tile(char* smem, const bf16_t* __restrict__ A0, int lda0, int ksplit, const bf16_t* __restrict__ A1, int lda1,
;                   const bf16_t* __restrict__ Bt, int K, int row0, int col0, const Epi& epi, int tid) {
;   constexpr int BK = 32, PITCH = 40, BUF = (256 + 128) * PITCH;
;   bf16_t* sbase = (bf16_t*)smem;
;   const int lane = tid & 63, wid = tid >> 6, wr = wid >> 1, wc = wid & 1, fr = lane & 15, fq = lane >> 4;
;   f32x4 acc[8][4];
; #pragma unroll
;   for (int m = 0; m < 8; ++m)
; #pragma unroll
;     for (int n = 0; n < 4; ++n) acc[m][n] = (f32x4){0.f, 0.f, 0.f, 0.f};
;   u32x4 ra[2][4], rb[2][2];
;   const int nk = K / BK;
;   const int sr = tid >> 2, scv = tid & 3;
; template <class Epi>
; DI void gemm_phase(char* smem, const bf16_t* A0, int lda0, int ksplit, const bf16_t* A1, int lda1, const bf16_t* Bt, int K, int nN, const Epi& epi, int tid) {
;   const int G = gridDim.x;
;   if ((G & 7) == 0) {
;     const int x = blockIdx.x & 7, l = blockIdx.x >> 3, L = G >> 3, per = 8 * nN, tot = 2 * per;
.LBB0_1918:
	s_cmp_gt_i32 s94, 18
	s_cselect_b64 s[0:1], -1, 0
	s_cmp_lt_i32 s95, 19
	s_cselect_b64 s[2:3], -1, 0
	s_or_b64 s[0:1], s[0:1], s[2:3]
	s_and_b64 vcc, exec, s[0:1]
	s_cbranch_vccnz .LBB0_1946
	s_load_dword s12, s[74:75], 0x180
	s_add_u32 s0, s92, 0x7800000
	s_addc_u32 s1, s93, 0
	s_add_u32 s2, s92, 0x23c0000
	s_addc_u32 s3, s93, 0
	s_waitcnt lgkmcnt(0)
	s_and_b32 s14, s72, 0xffffffc0
	v_mbcnt_hi_u32_b32 v195, -1, v194
	s_and_b32 s13, s12, 7
	s_cmp_lg_u32 s13, 0
	s_waitcnt vmcnt(16)
	v_add_u32_e32 v196, s14, v195
	v_mbcnt_lo_u32_b32 v240, -1, 0
	v_mbcnt_hi_u32_b32 v240, -1, v240
	s_lshr_b32 s10, s72, 6
	s_lshl_b32 s101, s10, 10
	v_and_b32_e32 v241, 15, v240
	v_lshrrev_b32_e32 v242, 4, v240
	v_bfe_u32 v243, v240, 3, 1
	v_mul_u32_u24_e32 v243, 3, v243
	v_xor_b32_e32 v243, v242, v243
	v_lshlrev_b32_e32 v243, 4, v243
	v_lshl_add_u32 v243, v241, 6, v243
	s_lshr_b32 s9, s10, 1
	s_lshl_b32 s9, s9, 13
	v_add_u32_e32 v230, s9, v243
	s_and_b32 s9, s10, 1
	s_lshl_b32 s9, s9, 12
	s_add_u32 s9, s9, 16384
	v_add_u32_e32 v231, s9, v243
	s_lshr_b32 s9, s10, 1
	s_lshl_b32 s9, s9, 7
	v_add_u32_e32 v244, s9, v241
	s_and_b32 s9, s10, 1
	s_lshl_b32 s9, s9, 6
	v_lshl_add_u32 v245, v242, 2, s9
	s_movk_i32 s9, 0x1000
	v_mul_lo_u32 v246, v244, s9
	v_lshl_add_u32 v234, v245, 2, v246
	v_lshrrev_b32_e32 v241, 2, v240
	s_lshl_b32 s9, s10, 4
	v_add_u32_e32 v241, s9, v241
	v_bfe_u32 v242, v240, 5, 1
	v_mul_u32_u24_e32 v242, 3, v242
	v_and_b32_e32 v243, 3, v240
	v_xor_b32_e32 v243, v243, v242
	v_lshlrev_b32_e32 v243, 4, v243
	s_mov_b32 s9, 8192
	v_mad_u32_u24 v224, v241, s9, v243
	v_add_u32_e32 v225, 0x80000, v224
	v_add_u32_e32 v226, 0x100000, v224
	v_add_u32_e32 v227, 0x180000, v224
	s_mov_b32 s9, 8192
	v_mad_u32_u24 v228, v241, s9, v243
	v_add_u32_e32 v229, 0x80000, v228
	s_load_dwordx2 s[6:7], s[74:75], 0x168
	s_lshr_b32 s15, s96, 3
	s_and_b32 s18, s96, 7
	s_lshl_b32 s18, s18, 1
	s_waitcnt lgkmcnt(0)
; #define LWRITE(S, buf) do { bf16_t* sA_ = sbase + (buf) * BUF; bf16_t* sB_ = sA_ + 256 * PITCH; \
;     _Pragma("unroll") for (int i_ = 0; i_ < 4; ++i_) *(u32x4*)(sA_ + (sr + i_ * 64) * PITCH + scv * 8) = ra[S][i_]; \
;     _Pragma("unroll") for (int i_ = 0; i_ < 2; ++i_) *(u32x4*)(sB_ + (sr + i_ * 64) * PITCH + scv * 8) = rb[S][i_]; } while (0)
; template <class Epi>
; DI void gemm_tile(char* smem, const bf16_t* __restrict__ A0, int lda0, int ksplit, const bf16_t* __restrict__ A1, int lda1,
;                   const bf16_t* __restrict__ Bt, int K, int row0, int col0, const Epi& epi, int tid) {
;     ...
;   f32x4 acc[8][4];
; #pragma unroll
;   for (int m = 0; m < 8; ++m)
; #pragma unroll
;     for (int n = 0; n < 4; ++n) acc[m][n] = (f32x4){0.f, 0.f, 0.f, 0.f};
;   u32x4 ra[2][4], rb[2][2];
;   const int nk = K / BK;
;   const int sr = tid >> 2, scv = tid & 3;
;     ...
;   __syncthreads();
;   {
;     const int last = nk - 1;
;     GLOAD(0, 0);
;     __builtin_amdgcn_sched_barrier(0);
;     GLOAD(1, 1);
;     __builtin_amdgcn_sched_barrier(0);
;     LWRITE(0, 0);
;     __builtin_amdgcn_sched_barrier(0);
;     GLOAD(0, (2 < last ? 2 : last));
;     __builtin_amdgcn_sched_barrier(0);
;     __syncthreads();
; template <class Epi>
; DI void gemm_phase(char* smem, const bf16_t* A0, int lda0, int ksplit, const bf16_t* A1, int lda1, const bf16_t* Bt, int K, int nN, const Epi& epi, int tid) {
;     ...
;     const int x = blockIdx.x & 7, l = blockIdx.x >> 3, L = G >> 3, per = 8 * nN, tot = 2 * per;
;     for (int q = l; q < tot; q += L) { const int rgl = q / per, rem = q % per, ct = rem >> 3, rt = (x * 2 + rgl) * 8 + (rem & 7);
;       gemm_tile(smem, A0, lda0, ksplit, A1, lda1, Bt, K, rt * 256, ct * 128, epi, tid); }
.Lg18_tile:
	s_cmpk_ge_u32 s15, 128
	s_cbranch_scc1 .Lg18_done
	s_cmpk_ge_u32 s15, 64
	s_cselect_b32 s10, 1, 0
	s_cselect_b32 s9, 64, 0
	s_sub_u32 s9, s15, s9
	s_and_b32 s16, s9, 7
	s_lshl_b32 s16, s16, 3
	s_bfe_u32 s11, s9, 0x30003
	s_or_b32 s16, s16, s11
	s_andn2_b32 s9, s9, 63
	s_or_b32 s9, s9, s16
	s_add_u32 s10, s10, s18
	s_lshl_b32 s10, s10, 3
	s_and_b32 s16, s9, 7
	s_add_u32 s16, s16, s10
	s_lshl_b32 s16, s16, 8
	s_lshr_b32 s11, s9, 3
	s_lshl_b32 s11, s11, 7
	s_mul_i32 s10, s16, 8192
	s_add_u32 s10, s10, 0x7800000
	s_add_u32 s0, s92, s10
	s_addc_u32 s1, s93, 0
	s_mul_i32 s10, s11, 8192
	s_add_u32 s10, s10, 0x23c0000
	s_add_u32 s2, s92, s10
	s_addc_u32 s3, s93, 0
	s_mov_b32 s100, 0
	s_mov_b32 s17, 0
	s_add_u32 s9, s17, s101
	s_add_u32 m0, s9, 0
	s_nop 0
	global_load_lds_dwordx4 v224, s[0:1]
	s_add_u32 m0, s9, 4096
	s_nop 0
	global_load_lds_dwordx4 v225, s[0:1]
	s_add_u32 m0, s9, 8192
	s_nop 0
	global_load_lds_dwordx4 v226, s[0:1]
	s_add_u32 m0, s9, 12288
	s_nop 0
	global_load_lds_dwordx4 v227, s[0:1]
	s_add_u32 m0, s9, 16384
	s_nop 0
	global_load_lds_dwordx4 v228, s[2:3]
	s_add_u32 m0, s9, 20480
	s_nop 0
	global_load_lds_dwordx4 v229, s[2:3]
	s_add_u32 s0, s0, 64
	s_addc_u32 s1, s1, 0
	s_add_u32 s2, s2, 64
	s_addc_u32 s3, s3, 0
	s_add_u32 s100, s100, 1
	s_add_u32 s17, s17, 24576
	s_cmp_eq_u32 s17, 73728
	s_cselect_b32 s17, 0, s17
	s_add_u32 s9, s17, s101
	s_add_u32 m0, s9, 0
	s_nop 0
	global_load_lds_dwordx4 v224, s[0:1]
	s_add_u32 m0, s9, 4096
	s_nop 0
	global_load_lds_dwordx4 v225, s[0:1]
	s_add_u32 m0, s9, 8192
	s_nop 0
	global_load_lds_dwordx4 v226, s[0:1]
	s_add_u32 m0, s9, 12288
	s_nop 0
	global_load_lds_dwordx4 v227, s[0:1]
	s_add_u32 m0, s9, 16384
	s_nop 0
	global_load_lds_dwordx4 v228, s[2:3]
	s_add_u32 m0, s9, 20480
	s_nop 0
	global_load_lds_dwordx4 v229, s[2:3]
	s_add_u32 s0, s0, 64
	s_addc_u32 s1, s1, 0
	s_add_u32 s2, s2, 64
	s_addc_u32 s3, s3, 0
	s_add_u32 s100, s100, 1
	s_add_u32 s17, s17, 24576
	s_cmp_eq_u32 s17, 73728
	s_cselect_b32 s17, 0, s17
	s_add_u32 s9, s17, s101
	s_add_u32 m0, s9, 0
	s_nop 0
	global_load_lds_dwordx4 v224, s[0:1]
	s_add_u32 m0, s9, 4096
	s_nop 0
	global_load_lds_dwordx4 v225, s[0:1]
	s_add_u32 m0, s9, 8192
	s_nop 0
	global_load_lds_dwordx4 v226, s[0:1]
	s_add_u32 m0, s9, 12288
	s_nop 0
	global_load_lds_dwordx4 v227, s[0:1]
	s_add_u32 m0, s9, 16384
	s_nop 0
	global_load_lds_dwordx4 v228, s[2:3]
	s_add_u32 m0, s9, 20480
	s_nop 0
	global_load_lds_dwordx4 v229, s[2:3]
	s_add_u32 s0, s0, 64
	s_addc_u32 s1, s1, 0
	s_add_u32 s2, s2, 64
	s_addc_u32 s3, s3, 0
	s_add_u32 s100, s100, 1
	s_add_u32 s17, s17, 24576
	s_cmp_eq_u32 s17, 73728
	s_cselect_b32 s17, 0, s17
	v_mov_b32_e32 v0, 0
	v_mov_b32_e32 v1, 0
	v_mov_b32_e32 v2, 0
	v_mov_b32_e32 v3, 0
	v_mov_b32_e32 v4, 0
	v_mov_b32_e32 v5, 0
	v_mov_b32_e32 v6, 0
	v_mov_b32_e32 v7, 0
	v_mov_b32_e32 v8, 0
	v_mov_b32_e32 v9, 0
	v_mov_b32_e32 v10, 0
	v_mov_b32_e32 v11, 0
	v_mov_b32_e32 v12, 0
	v_mov_b32_e32 v13, 0
	v_mov_b32_e32 v14, 0
	v_mov_b32_e32 v15, 0
	v_mov_b32_e32 v16, 0
	v_mov_b32_e32 v17, 0
	v_mov_b32_e32 v18, 0
	v_mov_b32_e32 v19, 0
	v_mov_b32_e32 v20, 0
	v_mov_b32_e32 v21, 0
	v_mov_b32_e32 v22, 0
	v_mov_b32_e32 v23, 0
	v_mov_b32_e32 v24, 0
	v_mov_b32_e32 v25, 0
	v_mov_b32_e32 v26, 0
	v_mov_b32_e32 v27, 0
	v_mov_b32_e32 v28, 0
	v_mov_b32_e32 v29, 0
	v_mov_b32_e32 v30, 0
	v_mov_b32_e32 v31, 0
	v_mov_b32_e32 v32, 0
	v_mov_b32_e32 v33, 0
	v_mov_b32_e32 v34, 0
	v_mov_b32_e32 v35, 0
	v_mov_b32_e32 v36, 0
	v_mov_b32_e32 v37, 0
	v_mov_b32_e32 v38, 0
	v_mov_b32_e32 v39, 0
	v_mov_b32_e32 v40, 0
	v_mov_b32_e32 v41, 0
	v_mov_b32_e32 v42, 0
	v_mov_b32_e32 v43, 0
	v_mov_b32_e32 v44, 0
	v_mov_b32_e32 v45, 0
	v_mov_b32_e32 v46, 0
	v_mov_b32_e32 v47, 0
	v_mov_b32_e32 v48, 0
	v_mov_b32_e32 v49, 0
	v_mov_b32_e32 v50, 0
	v_mov_b32_e32 v51, 0
	v_mov_b32_e32 v52, 0
	v_mov_b32_e32 v53, 0
	v_mov_b32_e32 v54, 0
	v_mov_b32_e32 v55, 0
	v_mov_b32_e32 v56, 0
	v_mov_b32_e32 v57, 0
	v_mov_b32_e32 v58, 0
	v_mov_b32_e32 v59, 0
	v_mov_b32_e32 v60, 0
	v_mov_b32_e32 v61, 0
	v_mov_b32_e32 v62, 0
	v_mov_b32_e32 v63, 0
	v_mov_b32_e32 v64, 0
	v_mov_b32_e32 v65, 0
	v_mov_b32_e32 v66, 0
	v_mov_b32_e32 v67, 0
	v_mov_b32_e32 v68, 0
	v_mov_b32_e32 v69, 0
	v_mov_b32_e32 v70, 0
	v_mov_b32_e32 v71, 0
	v_mov_b32_e32 v72, 0
	v_mov_b32_e32 v73, 0
	v_mov_b32_e32 v74, 0
	v_mov_b32_e32 v75, 0
	v_mov_b32_e32 v76, 0
	v_mov_b32_e32 v77, 0
	v_mov_b32_e32 v78, 0
	v_mov_b32_e32 v79, 0
	v_mov_b32_e32 v80, 0
	v_mov_b32_e32 v81, 0
	v_mov_b32_e32 v82, 0
	v_mov_b32_e32 v83, 0
	v_mov_b32_e32 v84, 0
	v_mov_b32_e32 v85, 0
	v_mov_b32_e32 v86, 0
	v_mov_b32_e32 v87, 0
	v_mov_b32_e32 v88, 0
	v_mov_b32_e32 v89, 0
	v_mov_b32_e32 v90, 0
	v_mov_b32_e32 v91, 0
	v_mov_b32_e32 v92, 0
	v_mov_b32_e32 v93, 0
	v_mov_b32_e32 v94, 0
	v_mov_b32_e32 v95, 0
	v_mov_b32_e32 v96, 0
	v_mov_b32_e32 v97, 0
	v_mov_b32_e32 v98, 0
	v_mov_b32_e32 v99, 0
	v_mov_b32_e32 v100, 0
	v_mov_b32_e32 v101, 0
	v_mov_b32_e32 v102, 0
	v_mov_b32_e32 v103, 0
	v_mov_b32_e32 v104, 0
	v_mov_b32_e32 v105, 0
	v_mov_b32_e32 v106, 0
	v_mov_b32_e32 v107, 0
	v_mov_b32_e32 v108, 0
	v_mov_b32_e32 v109, 0
	v_mov_b32_e32 v110, 0
	v_mov_b32_e32 v111, 0
	v_mov_b32_e32 v112, 0
	v_mov_b32_e32 v113, 0
	v_mov_b32_e32 v114, 0
	v_mov_b32_e32 v115, 0
	v_mov_b32_e32 v116, 0
	v_mov_b32_e32 v117, 0
	v_mov_b32_e32 v118, 0
	v_mov_b32_e32 v119, 0
	v_mov_b32_e32 v120, 0
	v_mov_b32_e32 v121, 0
	v_mov_b32_e32 v122, 0
	v_mov_b32_e32 v123, 0
	v_mov_b32_e32 v124, 0
	v_mov_b32_e32 v125, 0
	v_mov_b32_e32 v126, 0
	v_mov_b32_e32 v127, 0
	s_mov_b32 s99, 0
	s_mov_b32 s98, 24576
	s_waitcnt vmcnt(12)
	s_barrier
	ds_read_b128 v[128:131], v231 offset:0
	ds_read_b128 v[132:135], v231 offset:1024
	ds_read_b128 v[136:139], v231 offset:2048
	ds_read_b128 v[140:143], v231 offset:3072
	ds_read_b128 v[144:147], v230 offset:0
	ds_read_b128 v[148:151], v230 offset:1024
	ds_read_b128 v[152:155], v230 offset:2048
	ds_read_b128 v[156:159], v230 offset:3072
	ds_read_b128 v[160:163], v230 offset:4096
	ds_read_b128 v[164:167], v230 offset:5120
	ds_read_b128 v[168:171], v230 offset:6144
	ds_read_b128 v[172:175], v230 offset:7168

; __global__ void __launch_bounds__(256, 2) mega(Params p, int ph0, int ph1) {
;   extern __shared__ __attribute__((aligned(16))) char smem[];
;   const Ctx c{p, __builtin_amdgcn_readfirstlane((int)(__builtin_amdgcn_workitem_id_x() >> 6))};
;   run_from<0>(c, smem, ph0, ph1);
; }
	.amdhsa_kernel _Z4mega6Paramsii
		.amdhsa_group_segment_fixed_size 0
		.amdhsa_private_segment_fixed_size 0
		.amdhsa_kernarg_size 640
		.amdhsa_user_sgpr_count 2
		.amdhsa_user_sgpr_dispatch_ptr 0
		.amdhsa_user_sgpr_queue_ptr 0
		.amdhsa_user_sgpr_kernarg_segment_ptr 1
		.amdhsa_user_sgpr_dispatch_id 0
		.amdhsa_user_sgpr_kernarg_preload_length 0
		.amdhsa_user_sgpr_kernarg_preload_offset 0
		.amdhsa_user_sgpr_private_segment_size 0
		.amdhsa_uses_dynamic_stack 0
		.amdhsa_enable_private_segment 0
		.amdhsa_system_sgpr_workgroup_id_x 1
		.amdhsa_system_sgpr_workgroup_id_y 0
		.amdhsa_system_sgpr_workgroup_id_z 0
		.amdhsa_system_sgpr_workgroup_info 0
		.amdhsa_system_vgpr_workitem_id 2
		.amdhsa_next_free_vgpr 254
		.amdhsa_next_free_sgpr 102
		.amdhsa_accum_offset 256
		.amdhsa_reserve_vcc 1
		.amdhsa_float_round_mode_32 0
		.amdhsa_float_round_mode_16_64 0
		.amdhsa_float_denorm_mode_32 3
		.amdhsa_float_denorm_mode_16_64 3
		.amdhsa_dx10_clamp 1
		.amdhsa_ieee_mode 1
		.amdhsa_fp16_overflow 0
		.amdhsa_tg_split 0
		.amdhsa_exception_fp_ieee_invalid_op 0
		.amdhsa_exception_fp_denorm_src 0
		.amdhsa_exception_fp_ieee_div_zero 0
		.amdhsa_exception_fp_ieee_overflow 0
		.amdhsa_exception_fp_ieee_underflow 0
		.amdhsa_exception_fp_ieee_inexact 0
		.amdhsa_exception_int_div_zero 0
	.end_amdhsa_kernel

; __global__ void __launch_bounds__(256, 2) mega(Params p, int ph0, int ph1) {
;   extern __shared__ __attribute__((aligned(16))) char smem[];
;   const Ctx c{p, __builtin_amdgcn_readfirstlane((int)(__builtin_amdgcn_workitem_id_x() >> 6))};
;   run_from<0>(c, smem, ph0, ph1);
; }
amdhsa.kernels:
  - .agpr_count:     0
    .args:
      - .offset:         0
        .size:           376
        .value_kind:     by_value
      - .offset:         376
        .size:           4
        .value_kind:     by_value
      - .offset:         380
        .size:           4
        .value_kind:     by_value
      - .offset:         384
        .size:           4
        .value_kind:     hidden_block_count_x
      - .offset:         388
        .size:           4
        .value_kind:     hidden_block_count_y
      - .offset:         392
        .size:           4
        .value_kind:     hidden_block_count_z
      - .offset:         396
        .size:           2
        .value_kind:     hidden_group_size_x
      - .offset:         398
        .size:           2
        .value_kind:     hidden_group_size_y
      - .offset:         400
        .size:           2
        .value_kind:     hidden_group_size_z
      - .offset:         402
        .size:           2
        .value_kind:     hidden_remainder_x
      - .offset:         404
        .size:           2
        .value_kind:     hidden_remainder_y
      - .offset:         406
        .size:           2
        .value_kind:     hidden_remainder_z
      - .offset:         424
        .size:           8
        .value_kind:     hidden_global_offset_x
      - .offset:         432
        .size:           8
        .value_kind:     hidden_global_offset_y
      - .offset:         440
        .size:           8
        .value_kind:     hidden_global_offset_z
      - .offset:         448
        .size:           2
        .value_kind:     hidden_grid_dims
      - .offset:         472
        .size:           8
        .value_kind:     hidden_multigrid_sync_arg
      - .offset:         504
        .size:           4
        .value_kind:     hidden_dynamic_lds_size
    .group_segment_fixed_size: 0
    .kernarg_segment_align: 8
    .kernarg_segment_size: 640
    .language:       OpenCL C
    .language_version:
      - 2
      - 0
    .max_flat_workgroup_size: 256
    .name:           _Z4mega6Paramsii
    .private_segment_fixed_size: 0
    .sgpr_count:     108
    .sgpr_spill_count: 107
    .symbol:         _Z4mega6Paramsii.kd
    .uniform_work_group_size: 1
    .uses_dynamic_stack: false
    .vgpr_count:     254
    .vgpr_spill_count: 0
    .wavefront_size: 64
